# speedup vs baseline: 1.0242x; 1.0174x over previous
; DEVFI void ln_rows4(const float* src, float* dst, bfraw* dstb, float* stats, const float* w, const float* b, int lane) {
;   float4 v[4][4];
; #pragma unroll
;   for (int r = 0; r < 4; ++r)
; #pragma unroll
;     for (int i = 0; i < 4; ++i) v[r][i] = ((const float4*)(src + r * 1024))[i * 64 + lane];
;   float4 ww[4], bb[4];
; #pragma unroll
;   for (int i = 0; i < 4; ++i) { ww[i] = ((const float4*)w)[i * 64 + lane]; bb[i] = ((const float4*)b)[i * 64 + lane]; }
; #pragma unroll
;   for (int r = 0; r < 4; ++r) {
;     float s = 0;
; #pragma unroll
;     for (int i = 0; i < 4; ++i) s += v[r][i].x + v[r][i].y + v[r][i].z + v[r][i].w;
;     const float mean = red64(s) * (1.f / 1024.f);
;     float q = 0;
; #pragma unroll
;     for (int i = 0; i < 4; ++i) { float a = v[r][i].x - mean, c1 = v[r][i].y - mean, c = v[r][i].z - mean, d = v[r][i].w - mean; q += a * a + c1 * c1 + c * c + d * d; }
;     const float rstd = 1.f / sqrtf(red64(q) * (1.f / 1024.f) + LN_EPS);
;     if (lane == 0) { stats[r * 2] = mean; stats[r * 2 + 1] = rstd; }
.LBB0_19:
	s_or_b64 exec, exec, s[6:7]
	s_mov_b64 s[6:7], s[0:1]
	s_load_dwordx2 s[8:9], s[6:7], 0xe8
	s_mov_b64 s[6:7], s[0:1]
	s_mov_b64 s[34:35], s[0:1]
	s_load_dwordx2 s[6:7], s[6:7], 0xe8
	s_mov_b64 s[36:37], s[0:1]
	v_lshl_add_u64 v[4:5], v[2:3], 0, v[110:111]
	s_load_dwordx2 s[34:35], s[34:35], 0x20
	global_load_dwordx4 v[94:97], v[4:5], off
	global_load_dwordx4 v[90:93], v[4:5], off offset:1024
	global_load_dwordx4 v[86:89], v[4:5], off offset:2048
	global_load_dwordx4 v[82:85], v[4:5], off offset:3072
	v_lshl_add_u64 v[4:5], v[2:3], 0, s[18:19]
	v_lshl_add_u64 v[6:7], v[2:3], 0, s[20:21]
	v_lshl_add_u64 v[2:3], v[2:3], 0, s[22:23]
	v_lshl_add_u64 v[8:9], v[4:5], 0, v[110:111]
	s_mov_b32 s38, -1
	v_lshl_add_u64 v[10:11], v[4:5], 0, v[112:113]
	v_lshl_add_u64 v[12:13], v[4:5], 0, v[114:115]
	v_lshl_add_u64 v[18:19], v[4:5], 0, v[116:117]
	v_lshl_add_u64 v[20:21], v[6:7], 0, v[110:111]
	v_lshl_add_u64 v[22:23], v[6:7], 0, v[112:113]
	v_lshl_add_u64 v[24:25], v[6:7], 0, v[114:115]
	v_lshl_add_u64 v[6:7], v[6:7], 0, v[116:117]
	v_lshl_add_u64 v[30:31], v[2:3], 0, v[110:111]
	v_lshl_add_u64 v[32:33], v[2:3], 0, v[112:113]
	v_lshl_add_u64 v[34:35], v[2:3], 0, v[114:115]
	v_lshl_add_u64 v[36:37], v[2:3], 0, v[116:117]
	global_load_dwordx4 v[78:81], v[8:9], off
	global_load_dwordx4 v[74:77], v[10:11], off
	global_load_dwordx4 v[70:73], v[12:13], off
	global_load_dwordx4 v[66:69], v[18:19], off
	global_load_dwordx4 v[62:65], v[20:21], off
	global_load_dwordx4 v[58:61], v[22:23], off
	global_load_dwordx4 v[54:57], v[24:25], off
	global_load_dwordx4 v[50:53], v[6:7], off
	global_load_dwordx4 v[38:41], v[30:31], off
	global_load_dwordx4 v[26:29], v[32:33], off
	global_load_dwordx4 v[14:17], v[34:35], off
	global_load_dwordx4 v[2:5], v[36:37], off
	s_load_dwordx2 s[36:37], s[36:37], 0x28
	s_waitcnt lgkmcnt(0)
	global_load_dwordx4 v[42:45], v110, s[34:35]
	global_load_dwordx4 v[30:33], v110, s[34:35] offset:1024
	global_load_dwordx4 v[18:21], v110, s[34:35] offset:2048
	global_load_dwordx4 v[6:9], v110, s[34:35] offset:3072
	global_load_dwordx4 v[46:49], v110, s[36:37]
	global_load_dwordx4 v[34:37], v110, s[36:37] offset:1024
	global_load_dwordx4 v[22:25], v110, s[36:37] offset:2048
	global_load_dwordx4 v[10:13], v110, s[36:37] offset:3072
	s_mov_b32 s34, -1
	v_mbcnt_lo_u32_b32 v107, s38, 0
	v_mbcnt_hi_u32_b32 v107, s38, v107
	v_lshlrev_b32_e32 v107, 2, v107
	v_xor_b32_e32 v120, 0x80, v107
	s_waitcnt vmcnt(23)
	v_add_f32_e32 v121, v94, v95
	s_waitcnt vmcnt(22)
	v_add_f32_e32 v122, v90, v91
	v_add_f32_e32 v121, v121, v96
	s_waitcnt vmcnt(21)
	v_add_f32_e32 v123, v86, v87
	v_add_f32_e32 v122, v122, v92
	v_add_f32_e32 v121, v121, v97
	s_waitcnt vmcnt(20)
	v_add_f32_e32 v124, v82, v83
	v_add_f32_e32 v123, v123, v88
	v_add_f32_e32 v122, v122, v93
	v_add_f32_e32 v121, 0, v121
	v_add_f32_e32 v124, v124, v84
	v_add_f32_e32 v123, v123, v89
	v_add_f32_e32 v121, v121, v122
	v_add_f32_e32 v124, v124, v85
	v_add_f32_e32 v121, v121, v123
	v_add_f32_e32 v121, v121, v124
	ds_bpermute_b32 v120, v120, v121
	v_xor_b32_e32 v122, 64, v107
	s_waitcnt lgkmcnt(0)
	v_add_f32_e32 v120, v121, v120
	ds_bpermute_b32 v121, v122, v120
	v_xor_b32_e32 v122, 32, v107
	s_waitcnt lgkmcnt(0)
	v_add_f32_e32 v120, v120, v121
	ds_bpermute_b32 v121, v122, v120
	v_xor_b32_e32 v122, 16, v107
	s_waitcnt lgkmcnt(0)
	v_add_f32_e32 v120, v120, v121
	ds_bpermute_b32 v121, v122, v120
	v_xor_b32_e32 v122, 8, v107
	v_xor_b32_e32 v107, 4, v107
	s_waitcnt lgkmcnt(0)
	v_add_f32_e32 v120, v120, v121
	ds_bpermute_b32 v121, v122, v120
	s_waitcnt lgkmcnt(0)
	v_add_f32_e32 v120, v120, v121
	ds_bpermute_b32 v107, v107, v120
	v_mbcnt_lo_u32_b32 v121, s34, 0
	v_mbcnt_hi_u32_b32 v121, s34, v121
	v_lshlrev_b32_e32 v128, 2, v121
	v_xor_b32_e32 v129, 0x80, v128
	s_waitcnt lgkmcnt(0)
	v_add_f32_e32 v127, v120, v107
	v_fmamk_f32 v125, v127, 0xba800000, v95
	v_fmamk_f32 v122, v127, 0xba800000, v91
	v_fmamk_f32 v124, v127, 0xba800000, v94
	v_fmamk_f32 v121, v127, 0xba800000, v90
	v_fmamk_f32 v123, v127, 0xba800000, v92
	v_fmamk_f32 v107, v127, 0xba800000, v87
	v_fmamk_f32 v120, v127, 0xba800000, v88
	v_fmamk_f32 v88, v127, 0xba800000, v82
	v_fmamk_f32 v92, v127, 0xba800000, v83
	v_mul_f32_e32 v82, v125, v125
	v_mul_f32_e32 v83, v122, v122
	v_fmamk_f32 v126, v127, 0xba800000, v96
	v_fmamk_f32 v96, v127, 0xba800000, v86
	v_mul_f32_e32 v86, v107, v107
	v_fmac_f32_e32 v82, v124, v124
	v_fmac_f32_e32 v83, v121, v121
	v_fmac_f32_e32 v97, 0xba800000, v127
	v_fmac_f32_e32 v93, 0xba800000, v127
	v_mul_f32_e32 v87, v92, v92
	v_fmac_f32_e32 v86, v96, v96
	v_fmac_f32_e32 v82, v126, v126
	v_fmac_f32_e32 v83, v123, v123
	v_fmac_f32_e32 v89, 0xba800000, v127
	v_fmamk_f32 v84, v127, 0xba800000, v84
	v_fmac_f32_e32 v87, v88, v88
	v_fmac_f32_e32 v86, v120, v120
	v_fmac_f32_e32 v82, v97, v97
	v_fmac_f32_e32 v83, v93, v93
	v_fmac_f32_e32 v85, 0xba800000, v127
	v_fmac_f32_e32 v87, v84, v84
	v_fmac_f32_e32 v86, v89, v89
	v_add_f32_e32 v82, v82, v83
	v_fmac_f32_e32 v87, v85, v85
	v_add_f32_e32 v82, v86, v82
	v_add_f32_e32 v82, v87, v82
	ds_bpermute_b32 v83, v129, v82
	v_xor_b32_e32 v86, 64, v128
	s_waitcnt lgkmcnt(0)
	v_add_f32_e32 v82, v82, v83
	ds_bpermute_b32 v83, v86, v82
	v_xor_b32_e32 v86, 32, v128
	s_waitcnt lgkmcnt(0)
	v_add_f32_e32 v82, v82, v83
	ds_bpermute_b32 v83, v86, v82
	v_xor_b32_e32 v86, 16, v128
	s_waitcnt lgkmcnt(0)
	v_add_f32_e32 v82, v82, v83
	ds_bpermute_b32 v83, v86, v82
	v_xor_b32_e32 v86, 8, v128
	s_waitcnt lgkmcnt(0)
	v_add_f32_e32 v82, v82, v83
	ds_bpermute_b32 v83, v86, v82
	v_xor_b32_e32 v86, 4, v128
	s_waitcnt lgkmcnt(0)
	v_add_f32_e32 v82, v82, v83
	ds_bpermute_b32 v83, v86, v82
	s_waitcnt lgkmcnt(0)
	v_add_f32_e32 v82, v82, v83
	v_fmamk_f32 v82, v82, 0x3a800000, v103
	v_mul_f32_e32 v83, 0x4f800000, v82
	v_cmp_gt_f32_e32 vcc, s30, v82
	s_nop 1
	v_cndmask_b32_e32 v86, v82, v83, vcc
	v_sqrt_f32_e32 v87, v86
	v_lshl_add_u64 v[82:83], v[118:119], 3, s[6:7]
	v_lshl_add_u64 v[82:83], v[82:83], 0, s[16:17]
	v_add_u32_e32 v90, -1, v87
	v_add_u32_e32 v91, 1, v87
	v_fma_f32 v94, -v90, v87, v86
	v_fma_f32 v95, -v91, v87, v86
	v_cmp_ge_f32_e64 s[6:7], 0, v94
	s_nop 1
	v_cndmask_b32_e64 v87, v87, v90, s[6:7]
	v_cmp_lt_f32_e64 s[6:7], 0, v95
	s_nop 1
	v_cndmask_b32_e64 v87, v87, v91, s[6:7]
	v_mul_f32_e32 v90, 0x37800000, v87
	v_cndmask_b32_e32 v87, v87, v90, vcc
	v_cmp_class_f32_e32 vcc, v86, v105
	s_nop 1
	v_cndmask_b32_e32 v86, v87, v86, vcc
	v_rcp_f32_e32 v90, v86
	s_nop 0
	v_fma_f32 v87, -v86, v90, 1.0
	v_fma_f32 v87, v87, v90, v90
	v_div_fixup_f32 v95, v87, v86, 1.0
	s_and_saveexec_b64 s[6:7], s[4:5]
	s_cbranch_execz .LBB0_21
	v_mul_f32_e32 v94, 0x3a800000, v127
	global_store_dwordx2 v[82:83], v[94:95], off
; DEVFI void ln_rows4(const float* src, float* dst, bfraw* dstb, float* stats, const float* w, const float* b, int lane) {
;     ...
;   for (int r = 0; r < 4; ++r) {
;     float s = 0;
; #pragma unroll
;     for (int i = 0; i < 4; ++i) s += v[r][i].x + v[r][i].y + v[r][i].z + v[r][i].w;
;     const float mean = red64(s) * (1.f / 1024.f);
;     float q = 0;
; #pragma unroll
;     for (int i = 0; i < 4; ++i) { float a = v[r][i].x - mean, c1 = v[r][i].y - mean, c = v[r][i].z - mean, d = v[r][i].w - mean; q += a * a + c1 * c1 + c * c + d * d; }
;     const float rstd = 1.f / sqrtf(red64(q) * (1.f / 1024.f) + LN_EPS);
;     if (lane == 0) { stats[r * 2] = mean; stats[r * 2 + 1] = rstd; }
; #pragma unroll
;     for (int i = 0; i < 4; ++i) { const int c4 = i * 64 + lane;
;       float4 y; y.x = (v[r][i].x - mean) * rstd * ww[i].x + bb[i].x; y.y = (v[r][i].y - mean) * rstd * ww[i].y + bb[i].y;
;       y.z = (v[r][i].z - mean) * rstd * ww[i].z + bb[i].z; y.w = (v[r][i].w - mean) * rstd * ww[i].w + bb[i].w;
;       if (dst) ((float4*)(dst + r * 1024))[c4] = y;
;       u32x2 pk = {cvtpk(y.x, y.y), cvtpk(y.z, y.w)}; ((u32x2*)(dstb + r * 1024))[c4] = pk; }
.LBB0_21:
	s_or_b64 exec, exec, s[6:7]
	v_lshlrev_b64 v[86:87], 11, v[118:119]
	v_lshl_add_u64 v[86:87], s[8:9], 0, v[86:87]
	v_mul_f32_e32 v90, v97, v95
	v_mul_f32_e32 v91, v126, v95
	v_lshl_add_u64 v[86:87], v[86:87], 0, s[24:25]
	s_waitcnt vmcnt(3)
	v_fma_f32 v90, v45, v90, v49
	v_fma_f32 v91, v44, v91, v48
	v_mul_f32_e32 v94, v125, v95
	v_mul_f32_e32 v97, v124, v95
	v_fma_f32 v94, v43, v94, v47
	v_fma_f32 v97, v42, v97, v46
	v_cvt_pk_bf16_f32 v118, v97, v94
	v_cvt_pk_bf16_f32 v119, v91, v90
	v_lshl_add_u64 v[90:91], v[86:87], 0, v[100:101]
	global_store_dwordx2 v[90:91], v[118:119], off
	v_mul_f32_e32 v93, v93, v95
	v_mul_f32_e32 v94, v123, v95
	v_mul_f32_e32 v118, v121, v95
	s_waitcnt vmcnt(3)
	v_fma_f32 v93, v33, v93, v37
	v_fma_f32 v94, v32, v94, v36
	v_mul_f32_e32 v97, v122, v95
	v_fma_f32 v118, v30, v118, v34
	v_mul_f32_e32 v89, v89, v95
	v_mul_f32_e32 v96, v96, v95
	v_fma_f32 v97, v31, v97, v35
	v_cvt_pk_bf16_f32 v118, v118, v97
	v_cvt_pk_bf16_f32 v119, v94, v93
	s_waitcnt vmcnt(2)
	v_fma_f32 v89, v21, v89, v25
	v_mul_f32_e32 v93, v120, v95
	v_mul_f32_e32 v94, v107, v95
	v_fma_f32 v96, v18, v96, v22
	v_mul_f32_e32 v84, v84, v95
	global_store_dwordx2 v[90:91], v[118:119], off offset:512
	v_fma_f32 v93, v20, v93, v24
	v_fma_f32 v94, v19, v94, v23
	v_cvt_pk_bf16_f32 v96, v96, v94
	v_cvt_pk_bf16_f32 v97, v93, v89
	s_waitcnt vmcnt(2)
	v_fma_f32 v89, v8, v84, v12
	v_mul_f32_e32 v84, v92, v95
	v_mul_f32_e32 v85, v85, v95
	v_fma_f32 v84, v7, v84, v11
	v_mul_f32_e32 v88, v88, v95
	global_store_dwordx2 v[90:91], v[96:97], off offset:1024
	v_fma_f32 v85, v9, v85, v13
	v_fma_f32 v88, v6, v88, v10
	v_cvt_pk_bf16_f32 v84, v88, v84
	v_cvt_pk_bf16_f32 v85, v89, v85
	global_store_dwordx2 v[90:91], v[84:85], off offset:1536
	v_add_f32_e32 v84, v78, v79
	v_add_f32_e32 v84, v84, v80
	v_add_f32_e32 v85, v74, v75
	v_add_f32_e32 v84, v84, v81
	v_add_f32_e32 v85, v85, v76
	v_add_f32_e32 v84, 0, v84
	v_add_f32_e32 v85, v85, v77
	v_add_f32_e32 v84, v84, v85
	v_add_f32_e32 v85, v70, v71
	v_add_f32_e32 v85, v85, v72
	v_add_f32_e32 v85, v85, v73
	v_add_f32_e32 v84, v84, v85
	v_add_f32_e32 v85, v66, v67
	v_add_f32_e32 v85, v85, v68
	v_add_f32_e32 v85, v85, v69
	s_mov_b32 s6, -1
	v_add_f32_e32 v84, v84, v85
	s_nop 0
	v_mbcnt_lo_u32_b32 v85, s6, 0
	v_mbcnt_hi_u32_b32 v85, s6, v85
	v_lshlrev_b32_e32 v85, 2, v85
	v_xor_b32_e32 v88, 0x80, v85
	ds_bpermute_b32 v88, v88, v84
	s_mov_b32 s6, -1
	s_waitcnt lgkmcnt(0)
	v_add_f32_e32 v84, v84, v88
	v_xor_b32_e32 v88, 64, v85
	ds_bpermute_b32 v88, v88, v84
	s_waitcnt lgkmcnt(0)
	v_add_f32_e32 v84, v84, v88
	v_xor_b32_e32 v88, 32, v85
	ds_bpermute_b32 v88, v88, v84
	s_waitcnt lgkmcnt(0)
	v_add_f32_e32 v84, v84, v88
	v_xor_b32_e32 v88, 16, v85
	ds_bpermute_b32 v88, v88, v84
	s_waitcnt lgkmcnt(0)
	v_add_f32_e32 v84, v84, v88
	v_xor_b32_e32 v88, 8, v85
	ds_bpermute_b32 v88, v88, v84
	v_xor_b32_e32 v85, 4, v85
	s_waitcnt lgkmcnt(0)
	v_add_f32_e32 v84, v84, v88
	ds_bpermute_b32 v85, v85, v84
	s_waitcnt lgkmcnt(0)
	v_add_f32_e32 v88, v84, v85
	v_fmamk_f32 v79, v88, 0xba800000, v79
	v_fmamk_f32 v75, v88, 0xba800000, v75
	v_fmamk_f32 v78, v88, 0xba800000, v78
	v_fmamk_f32 v85, v88, 0xba800000, v80
	v_mul_f32_e32 v84, v79, v79
	v_fmamk_f32 v74, v88, 0xba800000, v74
	v_fmamk_f32 v80, v88, 0xba800000, v76
	v_mul_f32_e32 v76, v75, v75
	v_fmac_f32_e32 v84, v78, v78
	v_fmac_f32_e32 v76, v74, v74
	v_fmac_f32_e32 v81, 0xba800000, v88
	v_fmac_f32_e32 v84, v85, v85
	v_fmac_f32_e32 v77, 0xba800000, v88
	v_fmac_f32_e32 v76, v80, v80
	v_fmac_f32_e32 v84, v81, v81
	v_fmac_f32_e32 v76, v77, v77
	v_add_f32_e32 v89, v84, v76
	v_fmamk_f32 v76, v88, 0xba800000, v71
	v_fmamk_f32 v70, v88, 0xba800000, v70
	v_mul_f32_e32 v71, v76, v76
	v_fmamk_f32 v84, v88, 0xba800000, v72
	v_fmac_f32_e32 v71, v70, v70
	v_fmac_f32_e32 v73, 0xba800000, v88
	v_fmac_f32_e32 v71, v84, v84
	v_fmac_f32_e32 v71, v73, v73
	v_fmamk_f32 v72, v88, 0xba800000, v67
	v_add_f32_e32 v89, v71, v89
	v_fmamk_f32 v71, v88, 0xba800000, v66
	v_mul_f32_e32 v66, v72, v72
	v_fmamk_f32 v68, v88, 0xba800000, v68
	v_fmac_f32_e32 v66, v71, v71
	v_mbcnt_lo_u32_b32 v67, s6, 0
	v_fmac_f32_e32 v69, 0xba800000, v88
	v_fmac_f32_e32 v66, v68, v68
	v_mbcnt_hi_u32_b32 v67, s6, v67
	v_fmac_f32_e32 v66, v69, v69
	v_lshlrev_b32_e32 v67, 2, v67
	v_add_f32_e32 v66, v66, v89
	v_xor_b32_e32 v89, 0x80, v67
	ds_bpermute_b32 v89, v89, v66
	s_waitcnt lgkmcnt(0)
	v_add_f32_e32 v66, v66, v89
	v_xor_b32_e32 v89, 64, v67
	ds_bpermute_b32 v89, v89, v66
	s_waitcnt lgkmcnt(0)
	v_add_f32_e32 v66, v66, v89
	v_xor_b32_e32 v89, 32, v67
	ds_bpermute_b32 v89, v89, v66
	s_waitcnt lgkmcnt(0)
	v_add_f32_e32 v66, v66, v89
	v_xor_b32_e32 v89, 16, v67
	ds_bpermute_b32 v89, v89, v66
	s_waitcnt lgkmcnt(0)
	v_add_f32_e32 v66, v66, v89
	v_xor_b32_e32 v89, 8, v67
	ds_bpermute_b32 v89, v89, v66
	v_xor_b32_e32 v67, 4, v67
	s_waitcnt lgkmcnt(0)
	v_add_f32_e32 v66, v66, v89
	ds_bpermute_b32 v67, v67, v66
	s_waitcnt lgkmcnt(0)
	v_add_f32_e32 v66, v66, v67
	v_fmamk_f32 v66, v66, 0x3a800000, v103
	v_mul_f32_e32 v67, 0x4f800000, v66
	v_cmp_gt_f32_e32 vcc, s30, v66
	s_nop 1
	v_cndmask_b32_e32 v66, v66, v67, vcc
	v_sqrt_f32_e32 v67, v66
	s_nop 0
	v_add_u32_e32 v89, -1, v67
	v_fma_f32 v92, -v89, v67, v66
	v_cmp_ge_f32_e64 s[6:7], 0, v92
	v_add_u32_e32 v92, 1, v67
	s_nop 0
	v_cndmask_b32_e64 v89, v67, v89, s[6:7]
	v_fma_f32 v67, -v92, v67, v66
	v_cmp_lt_f32_e64 s[6:7], 0, v67
	s_nop 1
	v_cndmask_b32_e64 v67, v89, v92, s[6:7]
	v_mul_f32_e32 v89, 0x37800000, v67
	v_cndmask_b32_e32 v67, v67, v89, vcc
	v_cmp_class_f32_e32 vcc, v66, v105
	s_nop 1
	v_cndmask_b32_e32 v66, v67, v66, vcc
	s_nop 0
	v_rcp_f32_e32 v89, v66
	s_nop 0
	v_fma_f32 v67, -v66, v89, 1.0
	v_fma_f32 v67, v67, v89, v89
	v_div_fixup_f32 v67, v67, v66, 1.0
	s_and_saveexec_b64 s[6:7], s[4:5]
	s_cbranch_execz .LBB0_23
	v_mul_f32_e32 v66, 0x3a800000, v88
	global_store_dwordx2 v[82:83], v[66:67], off offset:8
; DEVFI void ln_rows4(const float* src, float* dst, bfraw* dstb, float* stats, const float* w, const float* b, int lane) {
;     ...
;   for (int r = 0; r < 4; ++r) {
;     float s = 0;
; #pragma unroll
;     for (int i = 0; i < 4; ++i) s += v[r][i].x + v[r][i].y + v[r][i].z + v[r][i].w;
;     const float mean = red64(s) * (1.f / 1024.f);
;     float q = 0;
; #pragma unroll
;     for (int i = 0; i < 4; ++i) { float a = v[r][i].x - mean, c1 = v[r][i].y - mean, c = v[r][i].z - mean, d = v[r][i].w - mean; q += a * a + c1 * c1 + c * c + d * d; }
;     const float rstd = 1.f / sqrtf(red64(q) * (1.f / 1024.f) + LN_EPS);
;     if (lane == 0) { stats[r * 2] = mean; stats[r * 2 + 1] = rstd; }
; #pragma unroll
;     for (int i = 0; i < 4; ++i) { const int c4 = i * 64 + lane;
;       float4 y; y.x = (v[r][i].x - mean) * rstd * ww[i].x + bb[i].x; y.y = (v[r][i].y - mean) * rstd * ww[i].y + bb[i].y;
;       y.z = (v[r][i].z - mean) * rstd * ww[i].z + bb[i].z; y.w = (v[r][i].w - mean) * rstd * ww[i].w + bb[i].w;
;       if (dst) ((float4*)(dst + r * 1024))[c4] = y;
;       u32x2 pk = {cvtpk(y.x, y.y), cvtpk(y.z, y.w)}; ((u32x2*)(dstb + r * 1024))[c4] = pk; }
.LBB0_23:
	s_or_b64 exec, exec, s[6:7]
	v_mul_f32_e32 v66, v81, v67
	v_mul_f32_e32 v79, v79, v67
	v_mul_f32_e32 v78, v78, v67
	v_fma_f32 v66, v45, v66, v49
	v_mul_f32_e32 v81, v85, v67
	v_fma_f32 v79, v43, v79, v47
	v_fma_f32 v78, v42, v78, v46
	v_mul_f32_e32 v74, v74, v67
	v_fma_f32 v81, v44, v81, v48
	v_cvt_pk_bf16_f32 v78, v78, v79
	v_cvt_pk_bf16_f32 v79, v81, v66
	v_mul_f32_e32 v66, v77, v67
	v_mul_f32_e32 v75, v75, v67
	v_fma_f32 v74, v30, v74, v34
	global_store_dwordx2 v[90:91], v[78:79], off offset:2048
	v_fma_f32 v66, v33, v66, v37
	v_mul_f32_e32 v77, v80, v67
	v_fma_f32 v75, v31, v75, v35
	v_cvt_pk_bf16_f32 v74, v74, v75
	v_fma_f32 v77, v32, v77, v36
	v_cvt_pk_bf16_f32 v75, v77, v66
	global_store_dwordx2 v[90:91], v[74:75], off offset:2560
	v_mul_f32_e32 v66, v73, v67
	v_mul_f32_e32 v74, v76, v67
	v_fma_f32 v66, v21, v66, v25
	v_mul_f32_e32 v73, v84, v67
	v_fma_f32 v74, v19, v74, v23
	v_mul_f32_e32 v70, v70, v67
	v_fma_f32 v73, v20, v73, v24
	v_fma_f32 v70, v18, v70, v22
	v_cvt_pk_bf16_f32 v74, v70, v74
	v_cvt_pk_bf16_f32 v75, v73, v66
	v_mul_f32_e32 v66, v69, v67
	v_fma_f32 v69, v9, v66, v13
	v_mul_f32_e32 v66, v68, v67
	v_fma_f32 v68, v8, v66, v12
	v_mul_f32_e32 v66, v72, v67
	v_fma_f32 v66, v7, v66, v11
	v_mul_f32_e32 v67, v71, v67
	global_store_dwordx2 v[90:91], v[74:75], off offset:3072
	v_fma_f32 v67, v6, v67, v10
	v_cvt_pk_bf16_f32 v66, v67, v66
	v_cvt_pk_bf16_f32 v67, v68, v69
	global_store_dwordx2 v[90:91], v[66:67], off offset:3584
	v_add_f32_e32 v66, v62, v63
	v_add_f32_e32 v66, v66, v64
	v_add_f32_e32 v67, v58, v59
	v_add_f32_e32 v66, v66, v65
	v_add_f32_e32 v67, v67, v60
	v_add_f32_e32 v66, 0, v66
	v_add_f32_e32 v67, v67, v61
	v_add_f32_e32 v66, v66, v67
	v_add_f32_e32 v67, v54, v55
	v_add_f32_e32 v67, v67, v56
	v_add_f32_e32 v67, v67, v57
	v_add_f32_e32 v66, v66, v67
	v_add_f32_e32 v67, v50, v51
	v_add_f32_e32 v67, v67, v52
	v_add_f32_e32 v67, v67, v53
	s_mov_b32 s6, -1
	v_add_f32_e32 v66, v66, v67
	s_nop 0
	v_mbcnt_lo_u32_b32 v67, s6, 0
	v_mbcnt_hi_u32_b32 v67, s6, v67
	v_lshlrev_b32_e32 v67, 2, v67
	v_xor_b32_e32 v68, 0x80, v67
	ds_bpermute_b32 v68, v68, v66
	s_mov_b32 s6, -1
	s_waitcnt lgkmcnt(0)
	v_add_f32_e32 v66, v66, v68
	v_xor_b32_e32 v68, 64, v67
	ds_bpermute_b32 v68, v68, v66
	s_waitcnt lgkmcnt(0)
	v_add_f32_e32 v66, v66, v68
	v_xor_b32_e32 v68, 32, v67
	ds_bpermute_b32 v68, v68, v66
	s_waitcnt lgkmcnt(0)
	v_add_f32_e32 v66, v66, v68
	v_xor_b32_e32 v68, 16, v67
	ds_bpermute_b32 v68, v68, v66
	s_waitcnt lgkmcnt(0)
	v_add_f32_e32 v66, v66, v68
	v_xor_b32_e32 v68, 8, v67
	ds_bpermute_b32 v68, v68, v66
	v_xor_b32_e32 v67, 4, v67
	s_waitcnt lgkmcnt(0)
	v_add_f32_e32 v66, v66, v68
	ds_bpermute_b32 v67, v67, v66
	s_waitcnt lgkmcnt(0)
	v_add_f32_e32 v70, v66, v67
	v_fmamk_f32 v68, v70, 0xba800000, v63
	v_fmamk_f32 v69, v70, 0xba800000, v64
	v_fmamk_f32 v64, v70, 0xba800000, v59
	v_fmamk_f32 v66, v70, 0xba800000, v62
	v_mul_f32_e32 v63, v68, v68
	v_fmamk_f32 v62, v70, 0xba800000, v58
	v_mul_f32_e32 v58, v64, v64
	v_fmac_f32_e32 v63, v66, v66
	v_fmamk_f32 v67, v70, 0xba800000, v60
	v_fmac_f32_e32 v58, v62, v62
	v_fmac_f32_e32 v65, 0xba800000, v70
	v_fmac_f32_e32 v63, v69, v69
	v_fmac_f32_e32 v61, 0xba800000, v70
	v_fmac_f32_e32 v58, v67, v67
	v_fmac_f32_e32 v63, v65, v65
	v_fmac_f32_e32 v58, v61, v61
	v_fmamk_f32 v55, v70, 0xba800000, v55
	v_add_f32_e32 v58, v63, v58
	v_fmamk_f32 v54, v70, 0xba800000, v54
	v_fmamk_f32 v63, v70, 0xba800000, v56
	v_mul_f32_e32 v56, v55, v55
	v_fmac_f32_e32 v56, v54, v54
	v_fmac_f32_e32 v57, 0xba800000, v70
	v_fmac_f32_e32 v56, v63, v63
	v_fmac_f32_e32 v56, v57, v57
	v_fmamk_f32 v60, v70, 0xba800000, v51
	v_add_f32_e32 v58, v56, v58
	v_fmamk_f32 v56, v70, 0xba800000, v50
	v_mul_f32_e32 v50, v60, v60
	v_fmamk_f32 v52, v70, 0xba800000, v52
	v_fmac_f32_e32 v50, v56, v56
	v_mbcnt_lo_u32_b32 v51, s6, 0
	v_fmac_f32_e32 v53, 0xba800000, v70
	v_fmac_f32_e32 v50, v52, v52
	v_mbcnt_hi_u32_b32 v51, s6, v51
	v_fmac_f32_e32 v50, v53, v53
	v_lshlrev_b32_e32 v51, 2, v51
	v_add_f32_e32 v50, v50, v58
	v_xor_b32_e32 v58, 0x80, v51
	ds_bpermute_b32 v58, v58, v50
	s_waitcnt lgkmcnt(0)
	v_add_f32_e32 v50, v50, v58
	v_xor_b32_e32 v58, 64, v51
	ds_bpermute_b32 v58, v58, v50
	s_waitcnt lgkmcnt(0)
	v_add_f32_e32 v50, v50, v58
	v_xor_b32_e32 v58, 32, v51
	ds_bpermute_b32 v58, v58, v50
	s_waitcnt lgkmcnt(0)
	v_add_f32_e32 v50, v50, v58
	v_xor_b32_e32 v58, 16, v51
	ds_bpermute_b32 v58, v58, v50
	s_waitcnt lgkmcnt(0)
	v_add_f32_e32 v50, v50, v58
	v_xor_b32_e32 v58, 8, v51
	ds_bpermute_b32 v58, v58, v50
	v_xor_b32_e32 v51, 4, v51
	s_waitcnt lgkmcnt(0)
	v_add_f32_e32 v50, v50, v58
	ds_bpermute_b32 v51, v51, v50
	s_waitcnt lgkmcnt(0)
	v_add_f32_e32 v50, v50, v51
	v_fmamk_f32 v50, v50, 0x3a800000, v103
	v_mul_f32_e32 v51, 0x4f800000, v50
	v_cmp_gt_f32_e32 vcc, s30, v50
	s_nop 1
	v_cndmask_b32_e32 v50, v50, v51, vcc
	v_sqrt_f32_e32 v51, v50
	s_nop 0
	v_add_u32_e32 v58, -1, v51
	v_fma_f32 v59, -v58, v51, v50
	v_cmp_ge_f32_e64 s[6:7], 0, v59
	v_add_u32_e32 v59, 1, v51
	s_nop 0
	v_cndmask_b32_e64 v58, v51, v58, s[6:7]
	v_fma_f32 v51, -v59, v51, v50
	v_cmp_lt_f32_e64 s[6:7], 0, v51
	s_nop 1
	v_cndmask_b32_e64 v51, v58, v59, s[6:7]
	v_mul_f32_e32 v58, 0x37800000, v51
	v_cndmask_b32_e32 v51, v51, v58, vcc
	v_cmp_class_f32_e32 vcc, v50, v105
	s_nop 1
	v_cndmask_b32_e32 v50, v51, v50, vcc
	s_nop 0
	v_rcp_f32_e32 v58, v50
	s_nop 0
	v_fma_f32 v51, -v50, v58, 1.0
	v_fma_f32 v51, v51, v58, v58
	v_div_fixup_f32 v59, v51, v50, 1.0
	s_and_saveexec_b64 s[6:7], s[4:5]
	s_cbranch_execz .LBB0_25
	v_mul_f32_e32 v58, 0x3a800000, v70
	global_store_dwordx2 v[82:83], v[58:59], off offset:16
; DEVFI KP kargs() { KP k = (KP)__builtin_amdgcn_kernarg_segment_ptr(); asm volatile("" : "+s"(k)); return k; }
; #define XBF ((bfraw*)(kargs()->ws + O_XBF))
; #define STATS ((float*)(kargs()->ws + O_STATS))
; DEVFI void ln_rows4(const float* src, float* dst, bfraw* dstb, float* stats, const float* w, const float* b, int lane) {
;     ...
;   for (int r = 0; r < 4; ++r) {
;     float s = 0;
; #pragma unroll
;     for (int i = 0; i < 4; ++i) s += v[r][i].x + v[r][i].y + v[r][i].z + v[r][i].w;
;     const float mean = red64(s) * (1.f / 1024.f);
;     float q = 0;
; #pragma unroll
;     for (int i = 0; i < 4; ++i) { float a = v[r][i].x - mean, c1 = v[r][i].y - mean, c = v[r][i].z - mean, d = v[r][i].w - mean; q += a * a + c1 * c1 + c * c + d * d; }
;     const float rstd = 1.f / sqrtf(red64(q) * (1.f / 1024.f) + LN_EPS);
;     if (lane == 0) { stats[r * 2] = mean; stats[r * 2 + 1] = rstd; }
; #pragma unroll
;     for (int i = 0; i < 4; ++i) { const int c4 = i * 64 + lane;
;       float4 y; y.x = (v[r][i].x - mean) * rstd * ww[i].x + bb[i].x; y.y = (v[r][i].y - mean) * rstd * ww[i].y + bb[i].y;
;       y.z = (v[r][i].z - mean) * rstd * ww[i].z + bb[i].z; y.w = (v[r][i].w - mean) * rstd * ww[i].w + bb[i].w;
;       if (dst) ((float4*)(dst + r * 1024))[c4] = y;
;       u32x2 pk = {cvtpk(y.x, y.y), cvtpk(y.z, y.w)}; ((u32x2*)(dstb + r * 1024))[c4] = pk; }
; __global__ void __launch_bounds__(512) mega(Params p) {
;     ...
;   for (int r = (bid * 8 + wid) * 4; r < 81920; r += nb * 32) {
;     const float* src = (r < 65536) ? kargs()->in[0] + (long)r * 1024 : kargs()->in[1] + (long)(r - 65536) * 1024;
;     ln_rows4(src, nullptr, XBF + (long)r * 1024, STATS + (long)r * 2, kargs()->in[4], kargs()->in[5], lane);
.LBB0_25:
	s_or_b64 exec, exec, s[6:7]
	v_mul_f32_e32 v50, v65, v59
	v_fma_f32 v51, v45, v50, v49
	v_mul_f32_e32 v50, v69, v59
	v_fma_f32 v58, v44, v50, v48
	v_mul_f32_e32 v50, v68, v59
	v_lshl_add_u64 v[70:71], v[86:87], 0, s[18:19]
	v_fma_f32 v50, v43, v50, v47
	v_mul_f32_e32 v65, v66, v59
	v_fma_f32 v65, v42, v65, v46
	v_cvt_pk_bf16_f32 v50, v65, v50
	v_cvt_pk_bf16_f32 v51, v58, v51
	v_lshl_add_u64 v[68:69], v[70:71], 0, v[100:101]
	global_store_dwordx2 v[68:69], v[50:51], off
	v_mul_f32_e32 v50, v61, v59
	v_mul_f32_e32 v51, v67, v59
	v_fma_f32 v50, v33, v50, v37
	v_fma_f32 v51, v32, v51, v36
	v_mul_f32_e32 v58, v64, v59
	v_mul_f32_e32 v61, v62, v59
	v_fma_f32 v58, v31, v58, v35
	v_fma_f32 v61, v30, v61, v34
	v_cvt_pk_bf16_f32 v64, v61, v58
	v_cvt_pk_bf16_f32 v65, v51, v50
	v_lshlrev_b32_e32 v50, 3, v102
	v_mov_b32_e32 v51, v101
	v_mul_f32_e32 v57, v57, v59
	v_mul_f32_e32 v55, v55, v59
	v_mul_f32_e32 v54, v54, v59
	v_lshl_add_u64 v[66:67], v[70:71], 0, v[50:51]
	v_fma_f32 v57, v21, v57, v25
	v_mul_f32_e32 v58, v63, v59
	v_fma_f32 v55, v19, v55, v23
	v_fma_f32 v54, v18, v54, v22
	global_store_dwordx2 v[66:67], v[64:65], off
	v_fma_f32 v58, v20, v58, v24
	v_cvt_pk_bf16_f32 v62, v54, v55
	v_cvt_pk_bf16_f32 v63, v58, v57
	v_lshlrev_b32_e32 v54, 3, v104
	v_mov_b32_e32 v55, v101
	v_mul_f32_e32 v53, v53, v59
	v_mul_f32_e32 v52, v52, v59
	v_mul_f32_e32 v57, v60, v59
	v_mul_f32_e32 v56, v56, v59
	v_lshl_add_u64 v[64:65], v[70:71], 0, v[54:55]
	v_fma_f32 v53, v9, v53, v13
	v_fma_f32 v52, v8, v52, v12
	v_fma_f32 v57, v7, v57, v11
	v_fma_f32 v56, v6, v56, v10
	global_store_dwordx2 v[64:65], v[62:63], off
	v_cvt_pk_bf16_f32 v56, v56, v57
	v_cvt_pk_bf16_f32 v57, v52, v53
	v_lshlrev_b32_e32 v52, 3, v106
	v_mov_b32_e32 v53, v101
	v_lshl_add_u64 v[58:59], v[70:71], 0, v[52:53]
	global_store_dwordx2 v[58:59], v[56:57], off
	v_add_f32_e32 v56, v38, v39
	v_add_f32_e32 v56, v56, v40
	v_add_f32_e32 v57, v26, v27
	v_add_f32_e32 v56, v56, v41
	v_add_f32_e32 v57, v57, v28
	v_add_f32_e32 v56, 0, v56
	v_add_f32_e32 v57, v57, v29
	v_add_f32_e32 v56, v56, v57
	v_add_f32_e32 v57, v14, v15
	v_add_f32_e32 v57, v57, v16
	v_add_f32_e32 v57, v57, v17
	v_add_f32_e32 v56, v56, v57
	v_add_f32_e32 v57, v2, v3
	v_add_f32_e32 v57, v57, v4
	v_add_f32_e32 v57, v57, v5
	s_mov_b32 s6, -1
	v_add_f32_e32 v56, v56, v57
	s_nop 0
	v_mbcnt_lo_u32_b32 v57, s6, 0
	v_mbcnt_hi_u32_b32 v57, s6, v57
	v_lshlrev_b32_e32 v57, 2, v57
	v_xor_b32_e32 v58, 0x80, v57
	ds_bpermute_b32 v58, v58, v56
	s_mov_b32 s6, -1
	s_waitcnt lgkmcnt(0)
	v_add_f32_e32 v56, v56, v58
	v_xor_b32_e32 v58, 64, v57
	ds_bpermute_b32 v58, v58, v56
	s_waitcnt lgkmcnt(0)
	v_add_f32_e32 v56, v56, v58
	v_xor_b32_e32 v58, 32, v57
	ds_bpermute_b32 v58, v58, v56
	s_waitcnt lgkmcnt(0)
	v_add_f32_e32 v56, v56, v58
	v_xor_b32_e32 v58, 16, v57
	ds_bpermute_b32 v58, v58, v56
	s_waitcnt lgkmcnt(0)
	v_add_f32_e32 v56, v56, v58
	v_xor_b32_e32 v58, 8, v57
	ds_bpermute_b32 v58, v58, v56
	v_xor_b32_e32 v57, 4, v57
	s_waitcnt lgkmcnt(0)
	v_add_f32_e32 v56, v56, v58
	ds_bpermute_b32 v57, v57, v56
	s_waitcnt lgkmcnt(0)
	v_add_f32_e32 v58, v56, v57
	v_fmamk_f32 v57, v58, 0xba800000, v39
	v_fmamk_f32 v39, v58, 0xba800000, v27
	v_fmamk_f32 v56, v58, 0xba800000, v38
	v_mul_f32_e32 v59, v57, v57
	v_fmamk_f32 v38, v58, 0xba800000, v26
	v_mul_f32_e32 v26, v39, v39
	v_fmamk_f32 v40, v58, 0xba800000, v40
	v_fmac_f32_e32 v59, v56, v56
	v_fmamk_f32 v28, v58, 0xba800000, v28
	v_fmac_f32_e32 v26, v38, v38
	v_fmac_f32_e32 v41, 0xba800000, v58
	v_fmac_f32_e32 v59, v40, v40
	v_fmac_f32_e32 v29, 0xba800000, v58
	v_fmac_f32_e32 v26, v28, v28
	v_fmac_f32_e32 v59, v41, v41
	v_fmac_f32_e32 v26, v29, v29
	v_fmamk_f32 v27, v58, 0xba800000, v15
	v_add_f32_e32 v59, v59, v26
	v_fmamk_f32 v26, v58, 0xba800000, v14
	v_mul_f32_e32 v14, v27, v27
	v_fmamk_f32 v16, v58, 0xba800000, v16
	v_fmac_f32_e32 v14, v26, v26
	v_fmac_f32_e32 v17, 0xba800000, v58
	v_fmac_f32_e32 v14, v16, v16
	v_fmac_f32_e32 v14, v17, v17
	v_fmamk_f32 v15, v58, 0xba800000, v3
	v_add_f32_e32 v59, v14, v59
	v_fmamk_f32 v14, v58, 0xba800000, v2
	v_mul_f32_e32 v2, v15, v15
	v_fmamk_f32 v4, v58, 0xba800000, v4
	v_fmac_f32_e32 v2, v14, v14
	v_mbcnt_lo_u32_b32 v3, s6, 0
	v_fmac_f32_e32 v5, 0xba800000, v58
	v_fmac_f32_e32 v2, v4, v4
	v_mbcnt_hi_u32_b32 v3, s6, v3
	v_fmac_f32_e32 v2, v5, v5
	v_lshlrev_b32_e32 v3, 2, v3
	v_add_f32_e32 v2, v2, v59
	v_xor_b32_e32 v59, 0x80, v3
	ds_bpermute_b32 v59, v59, v2
	s_waitcnt lgkmcnt(0)
	v_add_f32_e32 v2, v2, v59
	v_xor_b32_e32 v59, 64, v3
	ds_bpermute_b32 v59, v59, v2
	s_waitcnt lgkmcnt(0)
	v_add_f32_e32 v2, v2, v59
	v_xor_b32_e32 v59, 32, v3
	ds_bpermute_b32 v59, v59, v2
	s_waitcnt lgkmcnt(0)
	v_add_f32_e32 v2, v2, v59
	v_xor_b32_e32 v59, 16, v3
	ds_bpermute_b32 v59, v59, v2
	s_waitcnt lgkmcnt(0)
	v_add_f32_e32 v2, v2, v59
	v_xor_b32_e32 v59, 8, v3
	ds_bpermute_b32 v59, v59, v2
	v_xor_b32_e32 v3, 4, v3
	s_waitcnt lgkmcnt(0)
	v_add_f32_e32 v2, v2, v59
	ds_bpermute_b32 v3, v3, v2
	s_waitcnt lgkmcnt(0)
	v_add_f32_e32 v2, v2, v3
	v_fmamk_f32 v2, v2, 0x3a800000, v103
	v_mul_f32_e32 v3, 0x4f800000, v2
	v_cmp_gt_f32_e32 vcc, s30, v2
	s_nop 1
	v_cndmask_b32_e32 v2, v2, v3, vcc
	v_sqrt_f32_e32 v3, v2
	s_nop 0
	v_add_u32_e32 v59, -1, v3
	v_fma_f32 v60, -v59, v3, v2
	v_cmp_ge_f32_e64 s[6:7], 0, v60
	v_add_u32_e32 v60, 1, v3
	s_nop 0
	v_cndmask_b32_e64 v59, v3, v59, s[6:7]
	v_fma_f32 v3, -v60, v3, v2
	v_cmp_lt_f32_e64 s[6:7], 0, v3
	s_nop 1
	v_cndmask_b32_e64 v3, v59, v60, s[6:7]
	v_mul_f32_e32 v59, 0x37800000, v3
	v_cndmask_b32_e32 v3, v3, v59, vcc
	v_cmp_class_f32_e32 vcc, v2, v105
	s_nop 1
	v_cndmask_b32_e32 v2, v3, v2, vcc
	s_nop 0
	v_rcp_f32_e32 v59, v2
	s_nop 0
	v_fma_f32 v3, -v2, v59, 1.0
	v_fma_f32 v3, v3, v59, v59
	v_div_fixup_f32 v3, v3, v2, 1.0
	s_and_saveexec_b64 s[6:7], s[4:5]
	s_cbranch_execz .LBB0_14
	v_mul_f32_e32 v2, 0x3a800000, v58
	global_store_dwordx2 v[82:83], v[2:3], off offset:24
	s_branch .LBB0_14

; DEVFI int opaque_tid(const int wv) { return (wv << 6) | lane_opaque(); }
; DEVFI void gbar(unsigned* bar, unsigned& gen, const unsigned nb, const unsigned bid, const int wv) {
;   __syncthreads();
;   gen += 1;
;   if (opaque_tid(wv) == 0) {
;     const unsigned groups = (nb % 8 == 0) ? 8u : 1u, gsz = nb / groups;
;     unsigned* grp = bar + (bid % groups) * 32; unsigned* glob = bar + 8 * 32;
;     __builtin_amdgcn_fence(__ATOMIC_RELEASE, "agent");
;     asm volatile("s_waitcnt vmcnt(0)" ::: "memory");
;     const unsigned old = __hip_atomic_fetch_add(grp, 1u, __ATOMIC_RELAXED, __HIP_MEMORY_SCOPE_AGENT);
;     if (old + 1 == gsz * gen) __hip_atomic_fetch_add(glob, 1u, __ATOMIC_RELAXED, __HIP_MEMORY_SCOPE_AGENT);
.LBB0_96:
	s_or_b64 exec, exec, s[2:3]
	v_readlane_b32 s2, v255, 3
	s_or_b32 s2, s2, 1
	s_mov_b64 s[4:5], s[0:1]
	s_nop 1
	v_writelane_b32 v255, s2, 14
	s_mov_b32 s2, -1
	s_barrier
	s_nop 0
	v_mbcnt_lo_u32_b32 v0, s2, 0
	v_mbcnt_hi_u32_b32 v0, s2, v0
	v_or_b32_e32 v0, s33, v0
	v_cmp_eq_u32_e32 vcc, 0, v0
	s_and_saveexec_b64 s[2:3], vcc
	s_cbranch_execz .LBB0_105
	s_load_dwordx2 s[4:5], s[4:5], 0xe8
	s_mov_b64 s[6:7], exec
	buffer_wbl2 sc1
	s_waitcnt vmcnt(0) lgkmcnt(0)
	s_waitcnt vmcnt(0)
	v_mbcnt_lo_u32_b32 v0, s6, 0
	v_mbcnt_hi_u32_b32 v0, s7, v0
	v_cmp_eq_u32_e32 vcc, 0, v0
	s_and_saveexec_b64 s[8:9], vcc
	s_cbranch_execz .LBB0_99
	v_readlane_b32 s10, v254, 11
	s_lshl_b32 s10, s10, 2
	s_add_u32 s10, s4, s10
	s_addc_u32 s11, s5, 0
	s_bcnt1_i32_b64 s6, s[6:7]
	v_mov_b32_e32 v1, s6
	v_mov_b32_e32 v2, 0x3a8c0000
	global_atomic_add v1, v2, v1, s[10:11] offset:1024 sc0

; #define GATES ((bfraw*)(kargs()->ws + O_GATES))
; DEVFI float sigmoidf_(float x) { return 1.f / (1.f + __expf(-x)); }
; __global__ void __launch_bounds__(512) mega(Params p) {
;     ...
;                   } else {
; #pragma unroll
;                     for (int n = 0; n < 8; ++n) { const float bb = hv[n];
; #pragma unroll
;                       for (int j = 0; j < 4; ++j) a[n][j] = sigmoidf_(a[n][j] + bb); }
;                     const int gt0 = bcol - 7680, tidn = ((wr0 >> 6) * 2 + (wc0 >> 7)) * 64 + fq * 16 + fr;
;                     bfraw* gt = GATES + ((long)(((brow >> 8) * 3 + (gt0 >> 10)) * 4 + ((gt0 >> 8) & 3))) * 65536 + (long)(m * 4 * 512 + tidn) * 8;
; #pragma unroll
;                     for (int q = 0; q < 4; ++q) { u32x4 w4 = {cvtpk(a[2 * q][0], a[2 * q][1]), cvtpk(a[2 * q][2], a[2 * q][3]), cvtpk(a[2 * q + 1][0], a[2 * q + 1][1]), cvtpk(a[2 * q + 1][2], a[2 * q + 1][3])};
;                       *(u32x4*)(gt + q * 512 * 8) = w4; }
.LBB0_684:
	s_or_b64 exec, exec, s[4:5]
	v_lshl_or_b32 v225, v147, 2, v128
	s_movk_i32 s2, 0x7ff
	v_add_u32_e32 v162, s76, v225
	v_cmp_lt_i32_e64 s[4:5], s2, v176
	s_and_saveexec_b64 s[2:3], s[4:5]
	s_xor_b64 s[74:75], exec, s[2:3]
	s_cbranch_execz .LBB0_1044
	s_cmpk_gt_u32 s26, 0xbff
	s_mov_b64 s[2:3], -1
	s_cbranch_scc0 .LBB0_1042
	s_cmpk_gt_u32 s26, 0xfff
	s_cbranch_scc0 .LBB0_975
	s_cmpk_gt_u32 s26, 0x17ff
	s_cbranch_scc0 .LBB0_896
	s_cmpk_gt_u32 s26, 0x1cff
	s_cbranch_scc0 .LBB0_758
	s_cmpk_lt_u32 s26, 0x1e00
	s_cbranch_scc1 .LBB0_691
	s_waitcnt vmcnt(0)
	v_add_f32_e32 v128, v124, v224
	v_mul_f32_e32 v128, 0xbfb8aa3b, v128
	v_exp_f32_e32 v128, v128
	s_add_i32 s6, s26, 0xffffe200
	s_ashr_i32 s7, s76, 8
	s_mul_i32 s7, s7, 3
	v_add_f32_e32 v128, 1.0, v128
	s_ashr_i32 s8, s6, 10
	s_add_i32 s8, s8, s7
	s_lshl_b32 s7, s8, 2
	v_rcp_f32_e32 v130, v128
	s_nop 0
	v_fma_f32 v129, -v128, v130, 1.0
	v_fma_f32 v129, v129, v130, v130
	v_div_fixup_f32 v128, v129, v128, 1.0
	v_add_f32_e32 v129, v125, v224
	v_mul_f32_e32 v129, 0xbfb8aa3b, v129
	v_exp_f32_e32 v129, v129
	s_bfe_u32 s6, s6, 0x20008
	s_or_b32 s6, s7, s6
	s_ashr_i32 s7, s6, 31
	v_add_f32_e32 v129, 1.0, v129
	s_lshl_b64 s[6:7], s[6:7], 17
	v_rcp_f32_e32 v131, v129
	s_nop 0
	v_fma_f32 v130, -v129, v131, 1.0
	v_fma_f32 v130, v130, v131, v131
	v_div_fixup_f32 v129, v130, v129, 1.0
	v_add_f32_e32 v130, v126, v224
	v_mul_f32_e32 v130, 0xbfb8aa3b, v130
	v_exp_f32_e32 v130, v130
	s_nop 0
	v_add_f32_e32 v130, 1.0, v130
	s_nop 0
	v_rcp_f32_e32 v133, v130
	s_nop 0
	v_fma_f32 v131, -v130, v133, 1.0
	v_fma_f32 v131, v131, v133, v133
	v_div_fixup_f32 v130, v131, v130, 1.0
	v_add_f32_e32 v131, v127, v224
	v_mul_f32_e32 v131, 0xbfb8aa3b, v131
	v_exp_f32_e32 v131, v131
	s_nop 0
	v_add_f32_e32 v131, 1.0, v131
	s_nop 0
	v_rcp_f32_e32 v134, v131
	s_nop 0
	v_fma_f32 v133, -v131, v134, 1.0
	v_fma_f32 v133, v133, v134, v134
	v_div_fixup_f32 v131, v133, v131, 1.0
	v_add_f32_e32 v133, v120, v223
	v_mul_f32_e32 v133, 0xbfb8aa3b, v133
	v_exp_f32_e32 v133, v133
	s_nop 0
	v_add_f32_e32 v133, 1.0, v133
	s_nop 0
	v_rcp_f32_e32 v135, v133
	s_nop 0
	v_fma_f32 v134, -v133, v135, 1.0
	v_fma_f32 v134, v134, v135, v135
	v_div_fixup_f32 v133, v134, v133, 1.0
	v_add_f32_e32 v134, v121, v223
	v_mul_f32_e32 v134, 0xbfb8aa3b, v134
	v_exp_f32_e32 v134, v134
	s_nop 0
	v_add_f32_e32 v134, 1.0, v134
	s_nop 0
	v_rcp_f32_e32 v136, v134
	s_nop 0
	v_fma_f32 v135, -v134, v136, 1.0
	v_fma_f32 v135, v135, v136, v136
	v_div_fixup_f32 v134, v135, v134, 1.0
	v_add_f32_e32 v135, v122, v223
	v_mul_f32_e32 v135, 0xbfb8aa3b, v135
	v_exp_f32_e32 v135, v135
	s_nop 0
	v_add_f32_e32 v135, 1.0, v135
	s_nop 0
	v_rcp_f32_e32 v137, v135
	s_nop 0
	v_fma_f32 v136, -v135, v137, 1.0
	v_fma_f32 v136, v136, v137, v137
	v_div_fixup_f32 v135, v136, v135, 1.0
	v_add_f32_e32 v136, v123, v223
	v_mul_f32_e32 v136, 0xbfb8aa3b, v136
	v_exp_f32_e32 v136, v136
	s_nop 0
	v_add_f32_e32 v136, 1.0, v136
	s_nop 0
	v_rcp_f32_e32 v138, v136
	s_nop 0
	v_fma_f32 v137, -v136, v138, 1.0
	v_fma_f32 v137, v137, v138, v138
	v_div_fixup_f32 v136, v137, v136, 1.0
	v_add_f32_e32 v137, v108, v212
	v_mul_f32_e32 v137, 0xbfb8aa3b, v137
	v_exp_f32_e32 v137, v137
	s_nop 0
	v_add_f32_e32 v137, 1.0, v137
	s_nop 0
	v_rcp_f32_e32 v139, v137
	s_nop 0
	v_fma_f32 v138, -v137, v139, 1.0
	v_fma_f32 v138, v138, v139, v139
	v_div_fixup_f32 v137, v138, v137, 1.0
	v_add_f32_e32 v138, v109, v212
	v_mul_f32_e32 v138, 0xbfb8aa3b, v138
	v_exp_f32_e32 v138, v138
	s_nop 0
	v_add_f32_e32 v138, 1.0, v138
	s_nop 0
	v_rcp_f32_e32 v140, v138
	s_nop 0
	v_fma_f32 v139, -v138, v140, 1.0
	v_fma_f32 v139, v139, v140, v140
	v_div_fixup_f32 v138, v139, v138, 1.0
	v_add_f32_e32 v139, v110, v212
	v_mul_f32_e32 v139, 0xbfb8aa3b, v139
	v_exp_f32_e32 v139, v139
	s_nop 0
	v_add_f32_e32 v139, 1.0, v139
	s_nop 0
	v_rcp_f32_e32 v141, v139
	s_nop 0
	v_fma_f32 v140, -v139, v141, 1.0
	v_fma_f32 v140, v140, v141, v141
	v_div_fixup_f32 v139, v140, v139, 1.0
	v_add_f32_e32 v140, v111, v212
	v_mul_f32_e32 v140, 0xbfb8aa3b, v140
	v_exp_f32_e32 v140, v140
	s_nop 0
	v_add_f32_e32 v140, 1.0, v140
	s_nop 0
	v_rcp_f32_e32 v142, v140
	s_nop 0
	v_fma_f32 v141, -v140, v142, 1.0
	v_fma_f32 v141, v141, v142, v142
	v_div_fixup_f32 v140, v141, v140, 1.0
	v_add_f32_e32 v141, v104, v211
	v_mul_f32_e32 v141, 0xbfb8aa3b, v141
	v_exp_f32_e32 v141, v141
	s_nop 0
	v_add_f32_e32 v141, 1.0, v141
	s_nop 0
	v_rcp_f32_e32 v143, v141
	s_nop 0
	v_fma_f32 v142, -v141, v143, 1.0
	v_fma_f32 v142, v142, v143, v143
	v_div_fixup_f32 v141, v142, v141, 1.0
	v_add_f32_e32 v142, v105, v211
	v_mul_f32_e32 v142, 0xbfb8aa3b, v142
	v_exp_f32_e32 v142, v142
	s_nop 0
	v_add_f32_e32 v142, 1.0, v142
	s_nop 0
	v_rcp_f32_e32 v144, v142
	s_nop 0
	v_fma_f32 v143, -v142, v144, 1.0
	v_fma_f32 v143, v143, v144, v144
	v_div_fixup_f32 v142, v143, v142, 1.0
	v_add_f32_e32 v143, v106, v211
	v_mul_f32_e32 v143, 0xbfb8aa3b, v143
	v_exp_f32_e32 v143, v143
	s_nop 0
	v_add_f32_e32 v143, 1.0, v143
	s_nop 0
	v_rcp_f32_e32 v145, v143
	s_nop 0
	v_fma_f32 v144, -v143, v145, 1.0
	v_fma_f32 v144, v144, v145, v145
	v_div_fixup_f32 v143, v144, v143, 1.0
	v_add_f32_e32 v144, v107, v211
	v_mul_f32_e32 v144, 0xbfb8aa3b, v144
	v_exp_f32_e32 v144, v144
	s_nop 0
	v_add_f32_e32 v144, 1.0, v144
	s_nop 0
	v_rcp_f32_e32 v147, v144
	s_nop 0
	v_fma_f32 v145, -v144, v147, 1.0
	v_fma_f32 v145, v145, v147, v147
	v_div_fixup_f32 v144, v145, v144, 1.0
	v_add_f32_e32 v145, v116, v210
	v_mul_f32_e32 v145, 0xbfb8aa3b, v145
	v_exp_f32_e32 v145, v145
	s_nop 0
	v_add_f32_e32 v145, 1.0, v145
	s_nop 0
	v_rcp_f32_e32 v148, v145
	s_nop 0
	v_fma_f32 v147, -v145, v148, 1.0
	v_fma_f32 v147, v147, v148, v148
	v_div_fixup_f32 v145, v147, v145, 1.0
; DEVFI float sigmoidf_(float x) { return 1.f / (1.f + __expf(-x)); }
; #define GATES ((bfraw*)(kargs()->ws + O_GATES))
; __global__ void __launch_bounds__(512) mega(Params p) {
;     ...
;                   } else {
; #pragma unroll
;                     for (int n = 0; n < 8; ++n) { const float bb = hv[n];
; #pragma unroll
;                       for (int j = 0; j < 4; ++j) a[n][j] = sigmoidf_(a[n][j] + bb); }
;                     const int gt0 = bcol - 7680, tidn = ((wr0 >> 6) * 2 + (wc0 >> 7)) * 64 + fq * 16 + fr;
;                     bfraw* gt = GATES + ((long)(((brow >> 8) * 3 + (gt0 >> 10)) * 4 + ((gt0 >> 8) & 3))) * 65536 + (long)(m * 4 * 512 + tidn) * 8;
; #pragma unroll
;                     for (int q = 0; q < 4; ++q) { u32x4 w4 = {cvtpk(a[2 * q][0], a[2 * q][1]), cvtpk(a[2 * q][2], a[2 * q][3]), cvtpk(a[2 * q + 1][0], a[2 * q + 1][1]), cvtpk(a[2 * q + 1][2], a[2 * q + 1][3])};
;                       *(u32x4*)(gt + q * 512 * 8) = w4; }
	v_add_f32_e32 v147, v117, v210
	v_mul_f32_e32 v147, 0xbfb8aa3b, v147
	v_exp_f32_e32 v147, v147
	s_nop 0
	v_add_f32_e32 v147, 1.0, v147
	s_nop 0
	v_rcp_f32_e32 v149, v147
	s_nop 0
	v_fma_f32 v148, -v147, v149, 1.0
	v_fma_f32 v148, v148, v149, v149
	v_div_fixup_f32 v147, v148, v147, 1.0
	v_add_f32_e32 v148, v118, v210
	v_mul_f32_e32 v148, 0xbfb8aa3b, v148
	v_exp_f32_e32 v148, v148
	s_nop 0
	v_add_f32_e32 v148, 1.0, v148
	s_nop 0
	v_rcp_f32_e32 v150, v148
	s_nop 0
	v_fma_f32 v149, -v148, v150, 1.0
	v_fma_f32 v149, v149, v150, v150
	v_div_fixup_f32 v148, v149, v148, 1.0
	v_add_f32_e32 v149, v119, v210
	v_mul_f32_e32 v149, 0xbfb8aa3b, v149
	v_exp_f32_e32 v149, v149
	s_nop 0
	v_add_f32_e32 v149, 1.0, v149
	s_nop 0
	v_rcp_f32_e32 v151, v149
	s_nop 0
	v_fma_f32 v150, -v149, v151, 1.0
	v_fma_f32 v150, v150, v151, v151
	v_div_fixup_f32 v149, v150, v149, 1.0
	v_add_f32_e32 v150, v112, v209
	v_mul_f32_e32 v150, 0xbfb8aa3b, v150
	v_exp_f32_e32 v150, v150
	s_nop 0
	v_add_f32_e32 v150, 1.0, v150
	s_nop 0
	v_rcp_f32_e32 v152, v150
	s_nop 0
	v_fma_f32 v151, -v150, v152, 1.0
	v_fma_f32 v151, v151, v152, v152
	v_div_fixup_f32 v150, v151, v150, 1.0
	v_add_f32_e32 v151, v113, v209
	v_mul_f32_e32 v151, 0xbfb8aa3b, v151
	v_exp_f32_e32 v151, v151
	s_nop 0
	v_add_f32_e32 v151, 1.0, v151
	s_nop 0
	v_rcp_f32_e32 v153, v151
	s_nop 0
	v_fma_f32 v152, -v151, v153, 1.0
	v_fma_f32 v152, v152, v153, v153
	v_div_fixup_f32 v151, v152, v151, 1.0
	v_add_f32_e32 v152, v114, v209
	v_mul_f32_e32 v152, 0xbfb8aa3b, v152
	v_exp_f32_e32 v152, v152
	s_nop 0
	v_add_f32_e32 v152, 1.0, v152
	s_nop 0
	v_rcp_f32_e32 v154, v152
	s_nop 0
	v_fma_f32 v153, -v152, v154, 1.0
	v_fma_f32 v153, v153, v154, v154
	v_div_fixup_f32 v152, v153, v152, 1.0
	v_add_f32_e32 v153, v115, v209
	v_mul_f32_e32 v153, 0xbfb8aa3b, v153
	v_exp_f32_e32 v153, v153
	s_nop 0
	v_add_f32_e32 v153, 1.0, v153
	s_nop 0
	v_rcp_f32_e32 v155, v153
	s_nop 0
	v_fma_f32 v154, -v153, v155, 1.0
	v_fma_f32 v154, v154, v155, v155
	v_div_fixup_f32 v153, v154, v153, 1.0
	v_add_f32_e32 v154, v100, v208
	v_mul_f32_e32 v154, 0xbfb8aa3b, v154
	v_exp_f32_e32 v154, v154
	s_nop 0
	v_add_f32_e32 v154, 1.0, v154
	s_nop 0
	v_rcp_f32_e32 v156, v154
	s_nop 0
	v_fma_f32 v155, -v154, v156, 1.0
	v_fma_f32 v155, v155, v156, v156
	v_div_fixup_f32 v156, v155, v154, 1.0
	v_add_f32_e32 v154, v101, v208
	v_mul_f32_e32 v154, 0xbfb8aa3b, v154
	v_exp_f32_e32 v154, v154
	s_nop 0
	v_add_f32_e32 v154, 1.0, v154
	s_nop 0
	v_rcp_f32_e32 v157, v154
	s_nop 0
	v_fma_f32 v155, -v154, v157, 1.0
	v_fma_f32 v155, v155, v157, v157
	v_div_fixup_f32 v157, v155, v154, 1.0
	v_add_f32_e32 v154, v102, v208
	v_mul_f32_e32 v154, 0xbfb8aa3b, v154
	v_exp_f32_e32 v154, v154
	s_nop 0
	v_add_f32_e32 v154, 1.0, v154
	s_nop 0
	v_rcp_f32_e32 v158, v154
	s_nop 0
	v_fma_f32 v155, -v154, v158, 1.0
	v_fma_f32 v155, v155, v158, v158
	v_div_fixup_f32 v158, v155, v154, 1.0
	v_add_f32_e32 v154, v103, v208
	v_mul_f32_e32 v154, 0xbfb8aa3b, v154
	v_exp_f32_e32 v154, v154
	s_nop 0
	v_add_f32_e32 v154, 1.0, v154
	s_nop 0
	v_rcp_f32_e32 v159, v154
	s_nop 0
	v_fma_f32 v155, -v154, v159, 1.0
	v_fma_f32 v155, v155, v159, v159
	v_div_fixup_f32 v159, v155, v154, 1.0
	v_add_f32_e32 v154, v96, v207
	v_mul_f32_e32 v154, 0xbfb8aa3b, v154
	v_exp_f32_e32 v154, v154
	s_nop 0
	v_add_f32_e32 v154, 1.0, v154
	s_nop 0
	v_rcp_f32_e32 v160, v154
	s_nop 0
	v_fma_f32 v155, -v154, v160, 1.0
	v_fma_f32 v155, v155, v160, v160
	v_div_fixup_f32 v160, v155, v154, 1.0
	v_add_f32_e32 v154, v97, v207
	v_mul_f32_e32 v154, 0xbfb8aa3b, v154
	v_exp_f32_e32 v154, v154
	s_nop 0
	v_add_f32_e32 v154, 1.0, v154
	s_nop 0
	v_rcp_f32_e32 v161, v154
	s_nop 0
	v_fma_f32 v155, -v154, v161, 1.0
	v_fma_f32 v155, v155, v161, v161
	v_div_fixup_f32 v161, v155, v154, 1.0
	v_add_f32_e32 v154, v98, v207
	v_mul_f32_e32 v154, 0xbfb8aa3b, v154
	v_exp_f32_e32 v154, v154
	s_nop 0
	v_add_f32_e32 v154, 1.0, v154
	s_nop 0
	v_rcp_f32_e32 v163, v154
	s_nop 0
	v_fma_f32 v155, -v154, v163, 1.0
	v_fma_f32 v155, v155, v163, v163
	v_div_fixup_f32 v163, v155, v154, 1.0
	v_add_f32_e32 v154, v99, v207
	v_mul_f32_e32 v154, 0xbfb8aa3b, v154
	v_exp_f32_e32 v154, v154
	s_nop 0
	v_add_f32_e32 v154, 1.0, v154
	s_mov_b64 s[2:3], s[0:1]
	s_load_dwordx2 s[2:3], s[2:3], 0xe8
	v_rcp_f32_e32 v164, v154
	s_nop 0
	v_fma_f32 v155, -v154, v164, 1.0
	v_fma_f32 v155, v155, v164, v164
	v_div_fixup_f32 v164, v155, v154, 1.0
	v_and_b32_e32 v154, 0xffffff80, v205
	v_lshl_or_b32 v154, v206, 6, v154
	s_waitcnt lgkmcnt(0)
	s_add_u32 s2, s2, s6
	v_or3_b32 v154, v154, v146, v202
	s_addc_u32 s3, s3, s7
	v_ashrrev_i32_e32 v155, 31, v154
	v_lshl_add_u64 v[154:155], v[154:155], 4, s[2:3]
	v_cvt_pk_bf16_f32 v128, v128, v129
	v_cvt_pk_bf16_f32 v129, v130, v131
	v_cvt_pk_bf16_f32 v130, v133, v134
	v_add_co_u32_e32 v134, vcc, s67, v154
	v_cvt_pk_bf16_f32 v131, v135, v136
	s_mov_b64 s[2:3], 0
	s_nop 0
	v_addc_co_u32_e32 v135, vcc, 0, v155, vcc
	global_store_dwordx4 v[134:135], v[128:131], off
	v_add_co_u32_e32 v134, vcc, s46, v154
	s_nop 0
	v_cvt_pk_bf16_f32 v128, v137, v138
	v_cvt_pk_bf16_f32 v129, v139, v140
	v_cvt_pk_bf16_f32 v130, v141, v142
	v_cvt_pk_bf16_f32 v131, v143, v144
	s_nop 0
	v_addc_co_u32_e32 v135, vcc, 0, v155, vcc
	global_store_dwordx4 v[134:135], v[128:131], off
	v_add_co_u32_e32 v134, vcc, 0x22724000, v154
	s_nop 0
	v_cvt_pk_bf16_f32 v128, v145, v147
	v_cvt_pk_bf16_f32 v129, v148, v149
	v_cvt_pk_bf16_f32 v130, v150, v151
	v_cvt_pk_bf16_f32 v131, v152, v153
	s_nop 0
	v_addc_co_u32_e32 v135, vcc, 0, v155, vcc
	global_store_dwordx4 v[134:135], v[128:131], off
	v_add_co_u32_e32 v134, vcc, 0x22726000, v154
	s_nop 0
	v_cvt_pk_bf16_f32 v128, v156, v157
	v_cvt_pk_bf16_f32 v129, v158, v159
	v_cvt_pk_bf16_f32 v130, v160, v161
	v_cvt_pk_bf16_f32 v131, v163, v164
	s_nop 0
	v_addc_co_u32_e32 v135, vcc, 0, v155, vcc
	global_store_dwordx4 v[134:135], v[128:131], off

; #define ATTT ((float2*)(kargs()->ws + O_ATTT))
; __global__ void __launch_bounds__(512) mega(Params p) {
;     ...
;                   } else if (c0 < 7424) {
;                     const bool isk = c0 >= 7168; const float* nw = isk ? kn_w : qn_w; const float2* attt = ATTT;
; #pragma unroll
;                     for (int j = 0; j < 4; ++j) { const int pos = (r0 + j) & (seqlen - 1);
;                       float ss = 0;
; #pragma unroll
;                       for (int n = 0; n < 8; ++n) ss += a[n][j] * a[n][j];
;                       ss = red16(ss);
;                       const float rstd = 1.f / sqrtf(ss * (1.f / 128.f) + RMS_EPS);
; #pragma unroll
;                       for (int n = 0; n < 8; ++n) a[n][j] = a[n][j] * rstd * hv[n];
;                       const float4* tb = (const float4*)(attt + pos * 64 + fr * 4);
;                       const float4 t01 = tb[0], t23 = tb[1];
;                       const float2 csv[4] = {make_float2(t01.x, t01.y), make_float2(t01.z, t01.w), make_float2(t23.x, t23.y), make_float2(t23.z, t23.w)};
; #pragma unroll
;                       for (int hh = 0; hh < 2; ++hh)
; #pragma unroll
;                         for (int n = 0; n < 2; ++n) { const float2 cs = csv[hh * 2 + n];
;                           const float x1 = a[hh * 4 + n][j], x2 = a[hh * 4 + n + 2][j];
;                           a[hh * 4 + n][j] = x1 * cs.x - x2 * cs.y; a[hh * 4 + n + 2][j] = x1 * cs.y + x2 * cs.x; } }
.LBB0_763:
	s_mov_b64 s[2:3], s[0:1]
	s_load_dwordx2 s[2:3], s[2:3], 0xe8
	v_mul_f32_e32 v128, v120, v120
	v_fmac_f32_e32 v128, v124, v124
	v_fmac_f32_e32 v128, v108, v108
	v_fmac_f32_e32 v128, v104, v104
	s_waitcnt lgkmcnt(0)
	s_add_u32 s36, s2, 0x3da0000
	s_mov_b32 s2, -1
	v_fmac_f32_e32 v128, v116, v116
	v_fmac_f32_e32 v128, v112, v112
	v_mbcnt_lo_u32_b32 v129, s2, 0
	v_mbcnt_hi_u32_b32 v129, s2, v129
	v_fmac_f32_e32 v128, v100, v100
	v_lshlrev_b32_e32 v129, 2, v129
	v_fmac_f32_e32 v128, v96, v96
	v_xor_b32_e32 v130, 4, v129
	ds_bpermute_b32 v130, v130, v128
	v_mov_b32_e32 v170, 0x358637bd
	s_addc_u32 s37, s3, 0
	s_waitcnt lgkmcnt(0)
	v_add_f32_e32 v128, v128, v130
	v_xor_b32_e32 v130, 8, v129
	ds_bpermute_b32 v130, v130, v128
	s_waitcnt lgkmcnt(0)
	v_add_f32_e32 v128, v128, v130
	v_xor_b32_e32 v130, 16, v129
	ds_bpermute_b32 v130, v130, v128
	v_xor_b32_e32 v129, 32, v129
	s_waitcnt lgkmcnt(0)
	v_add_f32_e32 v128, v128, v130
	ds_bpermute_b32 v129, v129, v128
	s_waitcnt lgkmcnt(0)
	v_add_f32_e32 v128, v128, v129
	v_fmamk_f32 v128, v128, 0x3c000000, v170
	v_cmp_gt_f32_e32 vcc, s30, v128
	v_mul_f32_e32 v129, 0x4f800000, v128
	s_nop 0
	v_cndmask_b32_e32 v128, v128, v129, vcc
	v_sqrt_f32_e32 v129, v128
	s_nop 0
	v_add_u32_e32 v130, -1, v129
	v_fma_f32 v131, -v130, v129, v128
	v_cmp_ge_f32_e64 s[6:7], 0, v131
	v_add_u32_e32 v131, 1, v129
	s_nop 0
	v_cndmask_b32_e64 v130, v129, v130, s[6:7]
	v_fma_f32 v129, -v131, v129, v128
	v_cmp_lt_f32_e64 s[6:7], 0, v129
	s_nop 1
	v_cndmask_b32_e64 v129, v130, v131, s[6:7]
	v_mul_f32_e32 v130, 0x37800000, v129
	v_cndmask_b32_e32 v129, v129, v130, vcc
	v_cmp_class_f32_e32 vcc, v128, v222
	s_nop 1
	v_cndmask_b32_e32 v128, v129, v128, vcc
	s_mov_b32 s2, -1
	v_rcp_f32_e32 v130, v128
	s_nop 0
	v_fma_f32 v129, -v128, v130, 1.0
	v_fma_f32 v129, v129, v130, v130
	v_div_fixup_f32 v128, v129, v128, 1.0
	v_mul_f32_e32 v129, v124, v128
	s_waitcnt vmcnt(0)
	v_mul_f32_e32 v133, v224, v129
	v_mul_f32_e32 v129, v120, v128
	v_mul_f32_e32 v134, v223, v129
	v_mul_f32_e32 v129, v108, v128
	v_mul_f32_e32 v135, v212, v129
	v_mul_f32_e32 v129, v104, v128
	v_mul_f32_e32 v136, v211, v129
	v_mul_f32_e32 v129, v116, v128
	v_mul_f32_e32 v141, v210, v129
	v_mul_f32_e32 v129, v112, v128
	v_mul_f32_e32 v150, v209, v129
	v_mul_f32_e32 v129, v100, v128
	v_mul_f32_e32 v128, v96, v128
	v_mul_f32_e32 v152, v207, v128
	v_and_b32_e32 v128, s14, v162
	v_mul_f32_e32 v151, v208, v129
	v_lshlrev_b32_e32 v128, 6, v128
	v_mov_b32_e32 v129, v177
	v_lshl_add_u64 v[130:131], v[128:129], 3, s[36:37]
	v_lshlrev_b32_e32 v128, 3, v132
	v_lshl_add_u64 v[130:131], v[130:131], 0, v[128:129]
	global_load_dwordx4 v[142:145], v[130:131], off offset:16
	global_load_dwordx4 v[146:149], v[130:131], off
	v_add_u32_e32 v131, 1, v162
	s_waitcnt vmcnt(0)
	v_mul_f32_e32 v130, v147, v135
	v_fma_f32 v139, v146, v133, -v130
	v_mul_f32_e32 v130, v149, v136
	v_fma_f32 v140, v148, v134, -v130
	v_mul_f32_e32 v130, v143, v151
	v_mul_f32_e32 v137, v146, v135
	v_fma_f32 v135, v142, v141, -v130
	v_mul_f32_e32 v130, v145, v152
	v_mul_f32_e32 v138, v148, v136
	v_fma_f32 v136, v144, v150, -v130
	v_mul_f32_e32 v130, v121, v121
	v_fmac_f32_e32 v130, v125, v125
	v_fmac_f32_e32 v130, v109, v109
	v_fmac_f32_e32 v137, v147, v133
	v_mul_f32_e32 v133, v142, v151
	v_fmac_f32_e32 v130, v105, v105
	v_fmac_f32_e32 v133, v143, v141
	v_fmac_f32_e32 v130, v117, v117
	v_mbcnt_lo_u32_b32 v141, s2, 0
	v_fmac_f32_e32 v130, v113, v113
	v_mbcnt_hi_u32_b32 v141, s2, v141
	v_fmac_f32_e32 v130, v101, v101
	v_lshlrev_b32_e32 v141, 2, v141
	v_fmac_f32_e32 v130, v97, v97
	v_xor_b32_e32 v142, 4, v141
	ds_bpermute_b32 v142, v142, v130
	v_fmac_f32_e32 v138, v149, v134
	v_mul_f32_e32 v134, v144, v152
	v_fmac_f32_e32 v134, v145, v150
	s_waitcnt lgkmcnt(0)
	v_add_f32_e32 v130, v130, v142
	v_xor_b32_e32 v142, 8, v141
	ds_bpermute_b32 v142, v142, v130
	s_waitcnt lgkmcnt(0)
	v_add_f32_e32 v130, v130, v142
	v_xor_b32_e32 v142, 16, v141
	ds_bpermute_b32 v142, v142, v130
	v_xor_b32_e32 v141, 32, v141
	s_waitcnt lgkmcnt(0)
	v_add_f32_e32 v130, v130, v142
	ds_bpermute_b32 v141, v141, v130
	s_waitcnt lgkmcnt(0)
	v_add_f32_e32 v130, v130, v141
	v_fmamk_f32 v130, v130, 0x3c000000, v170
	v_cmp_gt_f32_e32 vcc, s30, v130
	v_mul_f32_e32 v141, 0x4f800000, v130
	s_nop 0
	v_cndmask_b32_e32 v130, v130, v141, vcc
	v_sqrt_f32_e32 v141, v130
	s_nop 0
	v_add_u32_e32 v142, -1, v141
	v_fma_f32 v143, -v142, v141, v130
	v_cmp_ge_f32_e64 s[6:7], 0, v143
	v_add_u32_e32 v143, 1, v141
	s_nop 0
	v_cndmask_b32_e64 v142, v141, v142, s[6:7]
	v_fma_f32 v141, -v143, v141, v130
	v_cmp_lt_f32_e64 s[6:7], 0, v141
	s_nop 1
	v_cndmask_b32_e64 v141, v142, v143, s[6:7]
	v_mul_f32_e32 v142, 0x37800000, v141
	v_cndmask_b32_e32 v141, v141, v142, vcc
	v_cmp_class_f32_e32 vcc, v130, v222
	s_nop 1
	v_cndmask_b32_e32 v130, v141, v130, vcc
	s_mov_b32 s2, -1
	v_rcp_f32_e32 v142, v130
	s_nop 0
	v_fma_f32 v141, -v130, v142, 1.0
	v_fma_f32 v141, v141, v142, v142
	v_div_fixup_f32 v130, v141, v130, 1.0
	v_mul_f32_e32 v145, v117, v130
	v_mul_f32_e32 v149, v210, v145
	v_mul_f32_e32 v145, v113, v130
	v_mul_f32_e32 v141, v125, v130
	v_mul_f32_e32 v142, v121, v130
	v_mul_f32_e32 v143, v109, v130
	v_mul_f32_e32 v144, v105, v130
	v_mul_f32_e32 v158, v209, v145
	v_mul_f32_e32 v145, v101, v130
	v_mul_f32_e32 v130, v97, v130
	v_mul_f32_e32 v160, v207, v130
	v_and_b32_e32 v130, s14, v131
	v_lshlrev_b32_e32 v130, 6, v130
	v_mov_b32_e32 v131, v177
	v_lshl_add_u64 v[130:131], v[130:131], 3, s[36:37]
	v_lshl_add_u64 v[130:131], v[130:131], 0, v[128:129]
	global_load_dwordx4 v[150:153], v[130:131], off offset:16
	global_load_dwordx4 v[154:157], v[130:131], off
	v_mul_f32_e32 v143, v212, v143
	v_mul_f32_e32 v141, v224, v141
	v_mul_f32_e32 v144, v211, v144
	v_mul_f32_e32 v142, v223, v142
	v_mul_f32_e32 v159, v208, v145
	v_add_u32_e32 v131, 2, v162
	s_waitcnt vmcnt(0)
; #define ATTT ((float2*)(kargs()->ws + O_ATTT))
; #define AQ ((bfraw*)(kargs()->ws + O_AQ))
; #define AK ((bfraw*)(kargs()->ws + O_AK))
; __global__ void __launch_bounds__(512) mega(Params p) {
;     ...
;                     const bool isk = c0 >= 7168; const float* nw = isk ? kn_w : qn_w; const float2* attt = ATTT;
; #pragma unroll
;                     for (int j = 0; j < 4; ++j) { const int pos = (r0 + j) & (seqlen - 1);
;                       float ss = 0;
; #pragma unroll
;                       for (int n = 0; n < 8; ++n) ss += a[n][j] * a[n][j];
;                       ss = red16(ss);
;                       const float rstd = 1.f / sqrtf(ss * (1.f / 128.f) + RMS_EPS);
; #pragma unroll
;                       for (int n = 0; n < 8; ++n) a[n][j] = a[n][j] * rstd * hv[n];
;                       const float4* tb = (const float4*)(attt + pos * 64 + fr * 4);
;                       const float4 t01 = tb[0], t23 = tb[1];
;                       const float2 csv[4] = {make_float2(t01.x, t01.y), make_float2(t01.z, t01.w), make_float2(t23.x, t23.y), make_float2(t23.z, t23.w)};
; #pragma unroll
;                       for (int hh = 0; hh < 2; ++hh)
; #pragma unroll
;                         for (int n = 0; n < 2; ++n) { const float2 cs = csv[hh * 2 + n];
;                           const float x1 = a[hh * 4 + n][j], x2 = a[hh * 4 + n + 2][j];
;                           a[hh * 4 + n][j] = x1 * cs.x - x2 * cs.y; a[hh * 4 + n + 2][j] = x1 * cs.y + x2 * cs.x; } }
;                     if (isk) store_nat_m(AK + (long)r0 * 256 + (c0 - 7168), 256, a, fr);
;                     else store_nat_m(AQ + (long)r0 * 1024 + (c0 - 6144), 1024, a, fr);
	v_mul_f32_e32 v130, v155, v143
	v_fma_f32 v147, v154, v141, -v130
	v_mul_f32_e32 v130, v157, v144
	v_fma_f32 v148, v156, v142, -v130
	v_mul_f32_e32 v130, v151, v159
	v_mul_f32_e32 v145, v154, v143
	v_fma_f32 v143, v150, v149, -v130
	v_mul_f32_e32 v130, v153, v160
	v_mul_f32_e32 v146, v156, v144
	v_fma_f32 v144, v152, v158, -v130
	v_mul_f32_e32 v130, v122, v122
	v_fmac_f32_e32 v130, v126, v126
	v_fmac_f32_e32 v130, v110, v110
	v_fmac_f32_e32 v145, v155, v141
	v_mul_f32_e32 v141, v150, v159
	v_fmac_f32_e32 v130, v106, v106
	v_fmac_f32_e32 v141, v151, v149
	v_fmac_f32_e32 v130, v118, v118
	v_mbcnt_lo_u32_b32 v149, s2, 0
	v_fmac_f32_e32 v130, v114, v114
	v_mbcnt_hi_u32_b32 v149, s2, v149
	v_fmac_f32_e32 v130, v102, v102
	v_lshlrev_b32_e32 v149, 2, v149
	v_fmac_f32_e32 v130, v98, v98
	v_xor_b32_e32 v150, 4, v149
	ds_bpermute_b32 v150, v150, v130
	v_fmac_f32_e32 v146, v157, v142
	v_mul_f32_e32 v142, v152, v160
	v_fmac_f32_e32 v142, v153, v158
	s_waitcnt lgkmcnt(0)
	v_add_f32_e32 v130, v130, v150
	v_xor_b32_e32 v150, 8, v149
	ds_bpermute_b32 v150, v150, v130
	s_waitcnt lgkmcnt(0)
	v_add_f32_e32 v130, v130, v150
	v_xor_b32_e32 v150, 16, v149
	ds_bpermute_b32 v150, v150, v130
	v_xor_b32_e32 v149, 32, v149
	s_waitcnt lgkmcnt(0)
	v_add_f32_e32 v130, v130, v150
	ds_bpermute_b32 v149, v149, v130
	s_waitcnt lgkmcnt(0)
	v_add_f32_e32 v130, v130, v149
	v_fmamk_f32 v130, v130, 0x3c000000, v170
	v_cmp_gt_f32_e32 vcc, s30, v130
	v_mul_f32_e32 v149, 0x4f800000, v130
	s_nop 0
	v_cndmask_b32_e32 v130, v130, v149, vcc
	v_sqrt_f32_e32 v149, v130
	s_nop 0
	v_add_u32_e32 v150, -1, v149
	v_fma_f32 v151, -v150, v149, v130
	v_cmp_ge_f32_e64 s[6:7], 0, v151
	v_add_u32_e32 v151, 1, v149
	s_nop 0
	v_cndmask_b32_e64 v150, v149, v150, s[6:7]
	v_fma_f32 v149, -v151, v149, v130
	v_cmp_lt_f32_e64 s[6:7], 0, v149
	s_nop 1
	v_cndmask_b32_e64 v149, v150, v151, s[6:7]
	v_mul_f32_e32 v150, 0x37800000, v149
	v_cndmask_b32_e32 v149, v149, v150, vcc
	v_cmp_class_f32_e32 vcc, v130, v222
	s_nop 1
	v_cndmask_b32_e32 v130, v149, v130, vcc
	s_mov_b32 s2, -1
	v_rcp_f32_e32 v150, v130
	s_nop 0
	v_fma_f32 v149, -v130, v150, 1.0
	v_fma_f32 v149, v149, v150, v150
	v_div_fixup_f32 v130, v149, v130, 1.0
	v_mul_f32_e32 v153, v118, v130
	v_mul_f32_e32 v157, v210, v153
	v_mul_f32_e32 v153, v114, v130
	v_mul_f32_e32 v149, v126, v130
	v_mul_f32_e32 v150, v122, v130
	v_mul_f32_e32 v151, v110, v130
	v_mul_f32_e32 v152, v106, v130
	v_mul_f32_e32 v163, v209, v153
	v_mul_f32_e32 v153, v102, v130
	v_mul_f32_e32 v130, v98, v130
	v_mul_f32_e32 v169, v207, v130
	v_and_b32_e32 v130, s14, v131
	v_lshlrev_b32_e32 v130, 6, v130
	v_mov_b32_e32 v131, v177
	v_lshl_add_u64 v[130:131], v[130:131], 3, s[36:37]
	v_lshl_add_u64 v[130:131], v[130:131], 0, v[128:129]
	global_load_dwordx4 v[158:161], v[130:131], off offset:16
	global_load_dwordx4 v[164:167], v[130:131], off
	v_mul_f32_e32 v151, v212, v151
	v_mul_f32_e32 v149, v224, v149
	v_mul_f32_e32 v152, v211, v152
	v_mul_f32_e32 v150, v223, v150
	v_mul_f32_e32 v168, v208, v153
	v_add_u32_e32 v131, 3, v162
	s_waitcnt vmcnt(0)
	v_mul_f32_e32 v130, v165, v151
	v_fma_f32 v155, v164, v149, -v130
	v_mul_f32_e32 v130, v167, v152
	v_fma_f32 v156, v166, v150, -v130
	v_mul_f32_e32 v130, v159, v168
	v_mul_f32_e32 v153, v164, v151
	v_fma_f32 v151, v158, v157, -v130
	v_mul_f32_e32 v130, v161, v169
	v_mul_f32_e32 v154, v166, v152
	v_fma_f32 v152, v160, v163, -v130
	v_mul_f32_e32 v130, v123, v123
	v_fmac_f32_e32 v130, v127, v127
	v_fmac_f32_e32 v130, v111, v111
	v_fmac_f32_e32 v153, v165, v149
	v_mul_f32_e32 v149, v158, v168
	v_fmac_f32_e32 v130, v107, v107
	v_fmac_f32_e32 v149, v159, v157
	v_fmac_f32_e32 v130, v119, v119
	v_mbcnt_lo_u32_b32 v157, s2, 0
	v_fmac_f32_e32 v130, v115, v115
	v_mbcnt_hi_u32_b32 v157, s2, v157
	v_fmac_f32_e32 v130, v103, v103
	v_lshlrev_b32_e32 v157, 2, v157
	v_fmac_f32_e32 v130, v99, v99
	v_xor_b32_e32 v158, 4, v157
	ds_bpermute_b32 v158, v158, v130
	v_fmac_f32_e32 v154, v167, v150
	v_mul_f32_e32 v150, v160, v169
	v_fmac_f32_e32 v150, v161, v163
	s_waitcnt lgkmcnt(0)
	v_add_f32_e32 v130, v130, v158
	v_xor_b32_e32 v158, 8, v157
	ds_bpermute_b32 v158, v158, v130
	s_waitcnt lgkmcnt(0)
	v_add_f32_e32 v130, v130, v158
	v_xor_b32_e32 v158, 16, v157
	ds_bpermute_b32 v158, v158, v130
	v_xor_b32_e32 v157, 32, v157
	s_waitcnt lgkmcnt(0)
	v_add_f32_e32 v130, v130, v158
	ds_bpermute_b32 v157, v157, v130
	s_waitcnt lgkmcnt(0)
	v_add_f32_e32 v130, v130, v157
	v_fmamk_f32 v130, v130, 0x3c000000, v170
	v_cmp_gt_f32_e32 vcc, s30, v130
	v_mul_f32_e32 v157, 0x4f800000, v130
	s_nop 0
	v_cndmask_b32_e32 v130, v130, v157, vcc
	v_sqrt_f32_e32 v157, v130
	s_nop 0
	v_add_u32_e32 v158, -1, v157
	v_fma_f32 v159, -v158, v157, v130
	v_cmp_ge_f32_e64 s[6:7], 0, v159
	v_add_u32_e32 v159, 1, v157
	s_nop 0
	v_cndmask_b32_e64 v158, v157, v158, s[6:7]
	v_fma_f32 v157, -v159, v157, v130
	v_cmp_lt_f32_e64 s[6:7], 0, v157
	s_nop 1
	v_cndmask_b32_e64 v157, v158, v159, s[6:7]
	v_mul_f32_e32 v158, 0x37800000, v157
	v_cndmask_b32_e32 v157, v157, v158, vcc
	v_cmp_class_f32_e32 vcc, v130, v222
	s_nop 1
	v_cndmask_b32_e32 v130, v157, v130, vcc
	s_mov_b64 s[2:3], -1
	v_rcp_f32_e32 v158, v130
	s_nop 0
	v_fma_f32 v157, -v130, v158, 1.0
	v_fma_f32 v157, v157, v158, v158
	v_div_fixup_f32 v130, v157, v130, 1.0
	v_mul_f32_e32 v158, v123, v130
	v_mul_f32_e32 v163, v223, v158
	v_mul_f32_e32 v158, v111, v130
	v_mul_f32_e32 v160, v212, v158
	v_mul_f32_e32 v158, v107, v130
	v_mul_f32_e32 v161, v211, v158
	v_mul_f32_e32 v158, v119, v130
	v_mul_f32_e32 v170, v210, v158
	v_mul_f32_e32 v158, v115, v130
	v_mul_f32_e32 v157, v127, v130
	v_mul_f32_e32 v171, v209, v158
	v_mul_f32_e32 v158, v103, v130
	v_mul_f32_e32 v130, v99, v130
	v_mul_f32_e32 v173, v207, v130
	v_and_b32_e32 v130, s14, v131
	v_lshlrev_b32_e32 v130, 6, v130
	v_mov_b32_e32 v131, v177
	v_lshl_add_u64 v[130:131], v[130:131], 3, s[36:37]
	v_mul_f32_e32 v172, v208, v158
	v_lshl_add_u64 v[158:159], v[130:131], 0, v[128:129]
	global_load_dwordx4 v[128:131], v[158:159], off offset:16
	global_load_dwordx4 v[166:169], v[158:159], off
	v_mul_f32_e32 v157, v224, v157
	s_waitcnt vmcnt(0)
	v_mul_f32_e32 v158, v167, v160
	v_mul_f32_e32 v160, v166, v160
	v_fma_f32 v164, v166, v157, -v158
	v_fmac_f32_e32 v160, v167, v157
	v_mul_f32_e32 v157, v169, v161
	v_fma_f32 v165, v168, v163, -v157
	v_mul_f32_e32 v157, v129, v172
	v_fma_f32 v158, v128, v170, -v157
	v_mul_f32_e32 v157, v128, v172
	v_mul_f32_e32 v128, v131, v173
	v_fma_f32 v159, v130, v171, -v128
	v_and_b32_e32 v128, 1, v203
	v_mul_f32_e32 v161, v168, v161
	v_mul_f32_e32 v130, v130, v173
	v_cmp_eq_u32_e32 vcc, 0, v128
	v_cmp_eq_u32_e64 s[6:7], 1, v128
	v_add_u32_e32 v128, 15, v202
	v_fmac_f32_e32 v161, v169, v163
	v_fmac_f32_e32 v157, v129, v170
	v_fmac_f32_e32 v130, v131, v171
	v_ashrrev_i32_e32 v163, 31, v162
	v_cndmask_b32_e32 v131, v128, v202, vcc
	v_cndmask_b32_e32 v166, v139, v140, vcc
	s_and_b64 vcc, exec, s[8:9]
	s_cbranch_vccz .LBB0_829
; DEVFI float dpp_xor1(float x) { return __int_as_float(__builtin_amdgcn_update_dpp(0, __float_as_int(x), 0xB1, 0xF, 0xF, true)); }
; DEVFI void store_nat_m(bfraw* base, long ld, f32x4 (&a)[8], int fr) {
;     ...
;     for (int n0 = 0; n0 < 8; n0 += 2) { const float own0 = a[n0][j], own1 = a[n0 + 1][j];
;       const float recv = dpp_xor1(odd ? own0 : own1);
;       const unsigned pk = odd ? cvtpk(recv, own1) : cvtpk(own0, recv);
;       *reinterpret_cast<unsigned*>(p0 + (long)j * ld + n0 * 16) = pk; }
	s_mov_b64 s[2:3], s[0:1]
	s_load_dwordx2 s[2:3], s[2:3], 0xe8
	v_mov_b32_dpp v128, v166 quad_perm:[1,0,3,2] row_mask:0xf bank_mask:0xf bound_ctrl:1
	s_and_saveexec_b64 s[8:9], s[6:7]
	s_xor_b64 s[8:9], exec, s[8:9]
	s_cbranch_execz .LBB0_766
	v_cvt_pk_bf16_f32 v167, v128, v140

; DEVFI float gelu_tanh(float x) {
;   float u = 0.7978845608028654f * (x + 0.044715f * x * x * x);
;   float t = __expf(2.f * u);
;   float th = 1.f - 2.f / (t + 1.f);
;   return 0.5f * x * (1.f + th);
; __global__ void __launch_bounds__(512) mega(Params p) {
;     ...
;                   } else if (c0 < 6144) {
; #pragma unroll
;                     for (int n = 0; n < 8; ++n)
; #pragma unroll
;                       for (int j = 0; j < 4; ++j) a[n][j] = gelu_tanh(a[n][j]);
.LBB0_896:
	s_andn2_b64 vcc, exec, s[2:3]
	s_cbranch_vccnz .LBB0_974
	v_mul_f32_e32 v129, 0x3d372713, v125
	v_mul_f32_e32 v129, v125, v129
	v_fma_f32 v129, v125, v129, v125
	v_mul_f32_e32 v129, 0x3f4c422a, v129
	v_add_f32_e32 v129, v129, v129
	v_mul_f32_e32 v129, 0x3fb8aa3b, v129
	v_exp_f32_e32 v130, v129
	v_mul_f32_e32 v129, 0x3d372713, v126
	v_mul_f32_e32 v129, v126, v129
	v_fma_f32 v129, v126, v129, v126
	v_mul_f32_e32 v129, 0x3f4c422a, v129
	v_add_f32_e32 v129, v129, v129
	v_mul_f32_e32 v129, 0x3fb8aa3b, v129
	v_mul_f32_e32 v128, 0x3d372713, v124
	v_exp_f32_e32 v134, v129
	v_mul_f32_e32 v129, 0x3d372713, v120
	v_mul_f32_e32 v128, v124, v128
	v_mul_f32_e32 v129, v120, v129
	v_fma_f32 v128, v124, v128, v124
	v_fma_f32 v129, v120, v129, v120
	v_mul_f32_e32 v128, 0x3f4c422a, v128
	v_mul_f32_e32 v129, 0x3f4c422a, v129
	v_add_f32_e32 v128, v128, v128
	v_add_f32_e32 v129, v129, v129
	v_mul_f32_e32 v128, 0x3fb8aa3b, v128
	v_mul_f32_e32 v129, 0x3fb8aa3b, v129
	v_exp_f32_e32 v128, v128
	v_exp_f32_e32 v129, v129
	v_mul_f32_e32 v131, 0x3d372713, v127
	v_mul_f32_e32 v131, v127, v131
	v_fma_f32 v131, v127, v131, v127
	v_pk_add_f32 v[128:129], v[128:129], 1.0 op_sel_hi:[1,0]
	v_mul_f32_e32 v131, 0x3f4c422a, v131
	v_add_f32_e32 v131, v131, v131
	v_mul_f32_e32 v131, 0x3fb8aa3b, v131
	v_exp_f32_e32 v136, v131
	v_rcp_f32_e32 v135, v129
	s_nop 0
	v_fma_f32 v131, -v129, v135, 1.0
	v_fma_f32 v135, v131, v135, v135
	v_add_f32_e32 v131, v135, v135
	v_div_fixup_f32 v129, v131, v129, 2.0
	v_mov_b32_e32 v139, v120
	v_rcp_f32_e32 v138, v128
	s_nop 0
	v_fma_f32 v131, -v128, v138, 1.0
	v_fma_f32 v138, v131, v138, v138
	v_add_f32_e32 v131, v138, v138
	v_div_fixup_f32 v128, v131, v128, 2.0
	v_mul_f32_e32 v131, 0x3d372713, v121
	v_mul_f32_e32 v131, v121, v131
	v_fma_f32 v131, v121, v131, v121
	v_mul_f32_e32 v131, 0x3f4c422a, v131
	v_add_f32_e32 v131, v131, v131
	v_mul_f32_e32 v131, 0x3fb8aa3b, v131
	v_exp_f32_e32 v131, v131
	v_pk_add_f32 v[128:129], v[128:129], 1.0 op_sel_hi:[1,0] neg_lo:[1,0] neg_hi:[1,0]
	v_mov_b32_e32 v138, v124
	v_pk_mul_f32 v[138:139], v[138:139], 0.5 op_sel_hi:[1,0]
	v_pk_add_f32 v[130:131], v[130:131], 1.0 op_sel_hi:[1,0]
	v_pk_add_f32 v[128:129], v[128:129], 1.0 op_sel_hi:[1,0]
	v_pk_mul_f32 v[144:145], v[138:139], v[128:129]
	s_cmpk_lt_u32 s26, 0x1400
	s_mov_b64 s[8:9], -1
	v_rcp_f32_e32 v135, v131
	s_nop 0
	v_fma_f32 v128, -v131, v135, 1.0
	v_fma_f32 v135, v128, v135, v135
	v_add_f32_e32 v128, v135, v135
	v_div_fixup_f32 v129, v128, v131, 2.0
	v_rcp_f32_e32 v137, v130
	s_nop 0
	v_fma_f32 v128, -v130, v137, 1.0
	v_fma_f32 v137, v128, v137, v137
	v_add_f32_e32 v128, v137, v137
	v_div_fixup_f32 v128, v128, v130, 2.0
	v_mul_f32_e32 v130, 0x3d372713, v122
	v_mul_f32_e32 v130, v122, v130
	v_fma_f32 v130, v122, v130, v122
	v_mul_f32_e32 v130, 0x3f4c422a, v130
	v_add_f32_e32 v130, v130, v130
	v_mul_f32_e32 v130, 0x3fb8aa3b, v130
	v_exp_f32_e32 v135, v130
	v_pk_add_f32 v[128:129], v[128:129], 1.0 op_sel_hi:[1,0] neg_lo:[1,0] neg_hi:[1,0]
	v_mov_b32_e32 v130, v125
	v_mov_b32_e32 v131, v121
	v_pk_add_f32 v[134:135], v[134:135], 1.0 op_sel_hi:[1,0]
	v_pk_mul_f32 v[130:131], v[130:131], 0.5 op_sel_hi:[1,0]
	v_pk_add_f32 v[128:129], v[128:129], 1.0 op_sel_hi:[1,0]
	s_nop 0
	v_pk_mul_f32 v[140:141], v[130:131], v[128:129]
	v_rcp_f32_e32 v137, v135
	s_nop 0
	v_fma_f32 v128, -v135, v137, 1.0
	v_fma_f32 v137, v128, v137, v137
	v_add_f32_e32 v128, v137, v137
	v_div_fixup_f32 v129, v128, v135, 2.0
	v_mul_f32_e32 v130, 0x3d372713, v123
	v_mul_f32_e32 v130, v123, v130
	v_fma_f32 v130, v123, v130, v123
	v_mul_f32_e32 v130, 0x3f4c422a, v130
	v_add_f32_e32 v130, v130, v130
	v_mul_f32_e32 v130, 0x3fb8aa3b, v130
	v_exp_f32_e32 v137, v130
	v_rcp_f32_e32 v131, v134
	s_nop 0
	v_fma_f32 v128, -v134, v131, 1.0
	v_fma_f32 v131, v128, v131, v131
	v_add_f32_e32 v128, v131, v131
	v_div_fixup_f32 v128, v128, v134, 2.0
	v_pk_add_f32 v[128:129], v[128:129], 1.0 op_sel_hi:[1,0] neg_lo:[1,0] neg_hi:[1,0]
	v_pk_add_f32 v[136:137], v[136:137], 1.0 op_sel_hi:[1,0]
	v_mov_b32_e32 v130, v126
	v_mov_b32_e32 v131, v122
	v_pk_mul_f32 v[130:131], v[130:131], 0.5 op_sel_hi:[1,0]
	v_pk_add_f32 v[128:129], v[128:129], 1.0 op_sel_hi:[1,0]
	s_nop 0
	v_pk_mul_f32 v[134:135], v[130:131], v[128:129]
	v_rcp_f32_e32 v138, v137
	s_nop 0
	v_fma_f32 v128, -v137, v138, 1.0
	v_fma_f32 v138, v128, v138, v138
	v_add_f32_e32 v128, v138, v138
	v_div_fixup_f32 v129, v128, v137, 2.0
	v_mul_f32_e32 v130, 0x3d372713, v108
	v_mul_f32_e32 v130, v108, v130
	v_fma_f32 v130, v108, v130, v108
	v_mul_f32_e32 v130, 0x3f4c422a, v130
	v_add_f32_e32 v130, v130, v130
	v_mul_f32_e32 v130, 0x3fb8aa3b, v130
	v_rcp_f32_e32 v131, v136
	s_nop 0
	v_fma_f32 v128, -v136, v131, 1.0
	v_fma_f32 v131, v128, v131, v131
	v_add_f32_e32 v128, v131, v131
	v_exp_f32_e32 v133, v130
	v_div_fixup_f32 v128, v128, v136, 2.0
	v_pk_add_f32 v[128:129], v[128:129], 1.0 op_sel_hi:[1,0] neg_lo:[1,0] neg_hi:[1,0]
	v_mov_b32_e32 v130, v127
	v_add_f32_e32 v133, 1.0, v133
	v_mov_b32_e32 v131, v123
	v_pk_mul_f32 v[130:131], v[130:131], 0.5 op_sel_hi:[1,0]
	v_pk_add_f32 v[128:129], v[128:129], 1.0 op_sel_hi:[1,0]
	s_nop 0
	v_pk_mul_f32 v[128:129], v[130:131], v[128:129]
	v_mul_f32_e32 v136, 0x3d372713, v109
	v_mul_f32_e32 v136, v109, v136
	v_fma_f32 v136, v109, v136, v109
	v_mul_f32_e32 v136, 0x3f4c422a, v136
	v_add_f32_e32 v136, v136, v136
	v_mul_f32_e32 v136, 0x3fb8aa3b, v136
	v_exp_f32_e32 v136, v136
	v_rcp_f32_e32 v137, v133
	s_nop 0
	v_fma_f32 v130, -v133, v137, 1.0
	v_fma_f32 v137, v130, v137, v137
	v_add_f32_e32 v130, v137, v137
	v_div_fixup_f32 v130, v130, v133, 2.0
	v_sub_f32_e32 v130, 1.0, v130
	v_add_f32_e32 v131, 1.0, v136
	v_mul_f32_e32 v137, 0.5, v108
; DEVFI float gelu_tanh(float x) {
;   float u = 0.7978845608028654f * (x + 0.044715f * x * x * x);
;   float t = __expf(2.f * u);
;   float th = 1.f - 2.f / (t + 1.f);
;   return 0.5f * x * (1.f + th);
; __global__ void __launch_bounds__(512) mega(Params p) {
;     ...
;                   } else if (c0 < 6144) {
; #pragma unroll
;                     for (int n = 0; n < 8; ++n)
; #pragma unroll
;                       for (int j = 0; j < 4; ++j) a[n][j] = gelu_tanh(a[n][j]);
	v_add_f32_e32 v130, 1.0, v130
	v_mul_f32_e32 v156, v137, v130
	v_mul_f32_e32 v133, 0x3d372713, v110
	v_mul_f32_e32 v133, v110, v133
	v_fma_f32 v133, v110, v133, v110
	v_mul_f32_e32 v133, 0x3f4c422a, v133
	v_add_f32_e32 v133, v133, v133
	v_mul_f32_e32 v133, 0x3fb8aa3b, v133
	v_exp_f32_e32 v133, v133
	v_rcp_f32_e32 v136, v131
	s_nop 0
	v_fma_f32 v130, -v131, v136, 1.0
	v_fma_f32 v136, v130, v136, v136
	v_add_f32_e32 v130, v136, v136
	v_div_fixup_f32 v130, v130, v131, 2.0
	v_sub_f32_e32 v130, 1.0, v130
	v_add_f32_e32 v131, 1.0, v133
	v_mul_f32_e32 v137, 0.5, v109
	v_add_f32_e32 v130, 1.0, v130
	v_mul_f32_e32 v148, v137, v130
	v_mul_f32_e32 v133, 0x3d372713, v111
	v_mul_f32_e32 v133, v111, v133
	v_fma_f32 v133, v111, v133, v111
	v_mul_f32_e32 v133, 0x3f4c422a, v133
	v_add_f32_e32 v133, v133, v133
	v_mul_f32_e32 v133, 0x3fb8aa3b, v133
	v_exp_f32_e32 v133, v133
	v_rcp_f32_e32 v136, v131
	s_nop 0
	v_fma_f32 v130, -v131, v136, 1.0
	v_fma_f32 v136, v130, v136, v136
	v_add_f32_e32 v130, v136, v136
	v_div_fixup_f32 v130, v130, v131, 2.0
	v_sub_f32_e32 v130, 1.0, v130
	v_add_f32_e32 v131, 1.0, v133
	v_mul_f32_e32 v137, 0.5, v110
	v_add_f32_e32 v130, 1.0, v130
	v_mul_f32_e32 v138, v137, v130
	v_mul_f32_e32 v133, 0x3d372713, v104
	v_mul_f32_e32 v133, v104, v133
	v_fma_f32 v133, v104, v133, v104
	v_mul_f32_e32 v133, 0x3f4c422a, v133
	v_add_f32_e32 v133, v133, v133
	v_mul_f32_e32 v133, 0x3fb8aa3b, v133
	v_exp_f32_e32 v133, v133
	v_rcp_f32_e32 v136, v131
	s_nop 0
	v_fma_f32 v130, -v131, v136, 1.0
	v_fma_f32 v136, v130, v136, v136
	v_add_f32_e32 v130, v136, v136
	v_div_fixup_f32 v130, v130, v131, 2.0
	v_sub_f32_e32 v130, 1.0, v130
	v_add_f32_e32 v131, 1.0, v133
	v_mul_f32_e32 v137, 0.5, v111
	v_add_f32_e32 v130, 1.0, v130
	v_mul_f32_e32 v130, v137, v130
	v_mul_f32_e32 v137, 0x3d372713, v105
	v_mul_f32_e32 v137, v105, v137
	v_fma_f32 v137, v105, v137, v105
	v_mul_f32_e32 v137, 0x3f4c422a, v137
	v_add_f32_e32 v137, v137, v137
	v_mul_f32_e32 v137, 0x3fb8aa3b, v137
	v_exp_f32_e32 v137, v137
	v_rcp_f32_e32 v136, v131
	s_nop 0
	v_fma_f32 v133, -v131, v136, 1.0
	v_fma_f32 v136, v133, v136, v136
	v_add_f32_e32 v133, v136, v136
	v_div_fixup_f32 v131, v133, v131, 2.0
	v_sub_f32_e32 v131, 1.0, v131
	v_add_f32_e32 v133, 1.0, v137
	v_mul_f32_e32 v139, 0.5, v104
	v_add_f32_e32 v131, 1.0, v131
	v_mul_f32_e32 v170, v139, v131
	v_mul_f32_e32 v136, 0x3d372713, v106
	v_mul_f32_e32 v136, v106, v136
	v_fma_f32 v136, v106, v136, v106
	v_mul_f32_e32 v136, 0x3f4c422a, v136
	v_add_f32_e32 v136, v136, v136
	v_mul_f32_e32 v136, 0x3fb8aa3b, v136
	v_exp_f32_e32 v136, v136
	v_rcp_f32_e32 v137, v133
	s_nop 0
	v_fma_f32 v131, -v133, v137, 1.0
	v_fma_f32 v137, v131, v137, v137
	v_add_f32_e32 v131, v137, v137
	v_div_fixup_f32 v131, v131, v133, 2.0
	v_sub_f32_e32 v131, 1.0, v131
	v_add_f32_e32 v133, 1.0, v136
	v_mul_f32_e32 v139, 0.5, v105
	v_add_f32_e32 v131, 1.0, v131
	v_mul_f32_e32 v158, v139, v131
	v_mul_f32_e32 v136, 0x3d372713, v107
	v_mul_f32_e32 v136, v107, v136
	v_fma_f32 v136, v107, v136, v107
	v_mul_f32_e32 v136, 0x3f4c422a, v136
	v_add_f32_e32 v136, v136, v136
	v_mul_f32_e32 v136, 0x3fb8aa3b, v136
	v_exp_f32_e32 v136, v136
	v_rcp_f32_e32 v137, v133
	s_nop 0
	v_fma_f32 v131, -v133, v137, 1.0
	v_fma_f32 v137, v131, v137, v137
	v_add_f32_e32 v131, v137, v137
	v_div_fixup_f32 v131, v131, v133, 2.0
	v_sub_f32_e32 v131, 1.0, v131
	v_add_f32_e32 v133, 1.0, v136
	v_mul_f32_e32 v139, 0.5, v106
	v_add_f32_e32 v131, 1.0, v131
	v_mul_f32_e32 v146, v139, v131
	v_mul_f32_e32 v136, 0x3d372713, v116
	v_mul_f32_e32 v136, v116, v136
	v_fma_f32 v136, v116, v136, v116
	v_mul_f32_e32 v136, 0x3f4c422a, v136
	v_add_f32_e32 v136, v136, v136
	v_mul_f32_e32 v136, 0x3fb8aa3b, v136
	v_exp_f32_e32 v136, v136
	v_rcp_f32_e32 v137, v133
	s_nop 0
	v_fma_f32 v131, -v133, v137, 1.0
	v_fma_f32 v137, v131, v137, v137
	v_add_f32_e32 v131, v137, v137
	v_div_fixup_f32 v131, v131, v133, 2.0
	v_sub_f32_e32 v131, 1.0, v131
	v_add_f32_e32 v133, 1.0, v136
	v_mul_f32_e32 v136, 0.5, v107
	v_add_f32_e32 v131, 1.0, v131
	v_mul_f32_e32 v136, v136, v131
	v_mul_f32_e32 v137, 0x3d372713, v117
	v_mul_f32_e32 v137, v117, v137
	v_fma_f32 v137, v117, v137, v117
	v_mul_f32_e32 v137, 0x3f4c422a, v137
	v_add_f32_e32 v137, v137, v137
	v_mul_f32_e32 v137, 0x3fb8aa3b, v137
	v_exp_f32_e32 v137, v137
	v_rcp_f32_e32 v139, v133
	s_nop 0
	v_fma_f32 v131, -v133, v139, 1.0
	v_fma_f32 v139, v131, v139, v139
	v_add_f32_e32 v131, v139, v139
	v_div_fixup_f32 v131, v131, v133, 2.0
	v_sub_f32_e32 v131, 1.0, v131
	v_add_f32_e32 v133, 1.0, v137
	v_mul_f32_e32 v142, 0.5, v116
	v_add_f32_e32 v131, 1.0, v131
	v_mul_f32_e32 v172, v142, v131
	v_mul_f32_e32 v137, 0x3d372713, v118
	v_mul_f32_e32 v137, v118, v137
	v_fma_f32 v137, v118, v137, v118
	v_mul_f32_e32 v137, 0x3f4c422a, v137
	v_add_f32_e32 v137, v137, v137
	v_mul_f32_e32 v137, 0x3fb8aa3b, v137
	v_exp_f32_e32 v137, v137
	v_rcp_f32_e32 v139, v133
	s_nop 0
	v_fma_f32 v131, -v133, v139, 1.0
	v_fma_f32 v139, v131, v139, v139
	v_add_f32_e32 v131, v139, v139
	v_div_fixup_f32 v131, v131, v133, 2.0
	v_sub_f32_e32 v131, 1.0, v131
	v_add_f32_e32 v133, 1.0, v137
	v_mul_f32_e32 v142, 0.5, v117
	v_add_f32_e32 v131, 1.0, v131
	v_mul_f32_e32 v164, v142, v131
	v_mul_f32_e32 v137, 0x3d372713, v119
	v_mul_f32_e32 v137, v119, v137
	v_fma_f32 v137, v119, v137, v119
	v_mul_f32_e32 v137, 0x3f4c422a, v137
	v_add_f32_e32 v137, v137, v137
	v_mul_f32_e32 v137, 0x3fb8aa3b, v137
	v_exp_f32_e32 v137, v137
	v_rcp_f32_e32 v139, v133
	s_nop 0
	v_fma_f32 v131, -v133, v139, 1.0
	v_fma_f32 v139, v131, v139, v139
	v_add_f32_e32 v131, v139, v139
	v_div_fixup_f32 v131, v131, v133, 2.0
	v_sub_f32_e32 v131, 1.0, v131
	v_add_f32_e32 v133, 1.0, v137
; DEVFI float gelu_tanh(float x) {
;   float u = 0.7978845608028654f * (x + 0.044715f * x * x * x);
;   float t = __expf(2.f * u);
;   float th = 1.f - 2.f / (t + 1.f);
;   return 0.5f * x * (1.f + th);
; __global__ void __launch_bounds__(512) mega(Params p) {
;     ...
;                   } else if (c0 < 6144) {
; #pragma unroll
;                     for (int n = 0; n < 8; ++n)
; #pragma unroll
;                       for (int j = 0; j < 4; ++j) a[n][j] = gelu_tanh(a[n][j]);
	v_mul_f32_e32 v142, 0.5, v118
	v_add_f32_e32 v131, 1.0, v131
	v_mul_f32_e32 v152, v142, v131
	v_mul_f32_e32 v137, 0x3d372713, v112
	v_mul_f32_e32 v137, v112, v137
	v_fma_f32 v137, v112, v137, v112
	v_mul_f32_e32 v137, 0x3f4c422a, v137
	v_add_f32_e32 v137, v137, v137
	v_mul_f32_e32 v137, 0x3fb8aa3b, v137
	v_exp_f32_e32 v137, v137
	v_rcp_f32_e32 v139, v133
	s_nop 0
	v_fma_f32 v131, -v133, v139, 1.0
	v_fma_f32 v139, v131, v139, v139
	v_add_f32_e32 v131, v139, v139
	v_div_fixup_f32 v131, v131, v133, 2.0
	v_sub_f32_e32 v131, 1.0, v131
	v_add_f32_e32 v133, 1.0, v137
	v_mul_f32_e32 v142, 0.5, v119
	v_add_f32_e32 v131, 1.0, v131
	v_mul_f32_e32 v142, v142, v131
	v_mul_f32_e32 v137, 0x3d372713, v113
	v_mul_f32_e32 v137, v113, v137
	v_fma_f32 v137, v113, v137, v113
	v_mul_f32_e32 v137, 0x3f4c422a, v137
	v_add_f32_e32 v137, v137, v137
	v_mul_f32_e32 v137, 0x3fb8aa3b, v137
	v_exp_f32_e32 v137, v137
	v_rcp_f32_e32 v139, v133
	s_nop 0
	v_fma_f32 v131, -v133, v139, 1.0
	v_fma_f32 v139, v131, v139, v139
	v_add_f32_e32 v131, v139, v139
	v_div_fixup_f32 v131, v131, v133, 2.0
	v_sub_f32_e32 v131, 1.0, v131
	v_add_f32_e32 v133, 1.0, v137
	v_mul_f32_e32 v143, 0.5, v112
	v_add_f32_e32 v131, 1.0, v131
	v_mul_f32_e32 v188, v143, v131
	v_mul_f32_e32 v137, 0x3d372713, v114
	v_mul_f32_e32 v137, v114, v137
	v_fma_f32 v137, v114, v137, v114
	v_mul_f32_e32 v137, 0x3f4c422a, v137
	v_add_f32_e32 v137, v137, v137
	v_mul_f32_e32 v137, 0x3fb8aa3b, v137
	v_exp_f32_e32 v137, v137
	v_rcp_f32_e32 v139, v133
	s_nop 0
	v_fma_f32 v131, -v133, v139, 1.0
	v_fma_f32 v139, v131, v139, v139
	v_add_f32_e32 v131, v139, v139
	v_div_fixup_f32 v131, v131, v133, 2.0
	v_sub_f32_e32 v131, 1.0, v131
	v_add_f32_e32 v133, 1.0, v137
	v_mul_f32_e32 v143, 0.5, v113
	v_add_f32_e32 v131, 1.0, v131
	v_mul_f32_e32 v174, v143, v131
	v_mul_f32_e32 v137, 0x3d372713, v115
	v_mul_f32_e32 v137, v115, v137
	v_fma_f32 v137, v115, v137, v115
	v_mul_f32_e32 v137, 0x3f4c422a, v137
	v_add_f32_e32 v137, v137, v137
	v_mul_f32_e32 v137, 0x3fb8aa3b, v137
	v_exp_f32_e32 v137, v137
	v_rcp_f32_e32 v139, v133
	s_nop 0
	v_fma_f32 v131, -v133, v139, 1.0
	v_fma_f32 v139, v131, v139, v139
	v_add_f32_e32 v131, v139, v139
	v_div_fixup_f32 v131, v131, v133, 2.0
	v_sub_f32_e32 v131, 1.0, v131
	v_add_f32_e32 v133, 1.0, v137
	v_mul_f32_e32 v143, 0.5, v114
	v_add_f32_e32 v131, 1.0, v131
	v_mul_f32_e32 v160, v143, v131
	v_mul_f32_e32 v137, 0x3d372713, v100
	v_mul_f32_e32 v137, v100, v137
	v_fma_f32 v137, v100, v137, v100
	v_mul_f32_e32 v137, 0x3f4c422a, v137
	v_add_f32_e32 v137, v137, v137
	v_mul_f32_e32 v137, 0x3fb8aa3b, v137
	v_exp_f32_e32 v137, v137
	v_rcp_f32_e32 v139, v133
	s_nop 0
	v_fma_f32 v131, -v133, v139, 1.0
	v_fma_f32 v139, v131, v139, v139
	v_add_f32_e32 v131, v139, v139
	v_div_fixup_f32 v131, v131, v133, 2.0
	v_sub_f32_e32 v131, 1.0, v131
	v_add_f32_e32 v133, 1.0, v137
	v_mul_f32_e32 v143, 0.5, v115
	v_add_f32_e32 v131, 1.0, v131
	v_mul_f32_e32 v150, v143, v131
	v_mul_f32_e32 v137, 0x3d372713, v101
	v_mul_f32_e32 v137, v101, v137
	v_fma_f32 v137, v101, v137, v101
	v_mul_f32_e32 v137, 0x3f4c422a, v137
	v_add_f32_e32 v137, v137, v137
	v_mul_f32_e32 v137, 0x3fb8aa3b, v137
	v_exp_f32_e32 v137, v137
	v_rcp_f32_e32 v139, v133
	s_nop 0
	v_fma_f32 v131, -v133, v139, 1.0
	v_fma_f32 v139, v131, v139, v139
	v_add_f32_e32 v131, v139, v139
	v_div_fixup_f32 v131, v131, v133, 2.0
	v_sub_f32_e32 v131, 1.0, v131
	v_add_f32_e32 v133, 1.0, v137
	v_mul_f32_e32 v143, 0.5, v100
	v_add_f32_e32 v131, 1.0, v131
	v_mul_f32_e32 v190, v143, v131
	v_mul_f32_e32 v137, 0x3d372713, v102
	v_mul_f32_e32 v137, v102, v137
	v_fma_f32 v137, v102, v137, v102
	v_mul_f32_e32 v137, 0x3f4c422a, v137
	v_add_f32_e32 v137, v137, v137
	v_mul_f32_e32 v137, 0x3fb8aa3b, v137
	v_exp_f32_e32 v137, v137
	v_rcp_f32_e32 v139, v133
	s_nop 0
	v_fma_f32 v131, -v133, v139, 1.0
	v_fma_f32 v139, v131, v139, v139
	v_add_f32_e32 v131, v139, v139
	v_div_fixup_f32 v131, v131, v133, 2.0
	v_sub_f32_e32 v131, 1.0, v131
	v_add_f32_e32 v133, 1.0, v137
	v_mul_f32_e32 v143, 0.5, v101
	v_add_f32_e32 v131, 1.0, v131
	v_mul_f32_e32 v186, v143, v131
	v_mul_f32_e32 v137, 0x3d372713, v103
	v_mul_f32_e32 v137, v103, v137
	v_fma_f32 v137, v103, v137, v103
	v_mul_f32_e32 v137, 0x3f4c422a, v137
	v_add_f32_e32 v137, v137, v137
	v_mul_f32_e32 v137, 0x3fb8aa3b, v137
	v_exp_f32_e32 v137, v137
	v_rcp_f32_e32 v139, v133
	s_nop 0
	v_fma_f32 v131, -v133, v139, 1.0
	v_fma_f32 v139, v131, v139, v139
	v_add_f32_e32 v131, v139, v139
	v_div_fixup_f32 v131, v131, v133, 2.0
	v_sub_f32_e32 v131, 1.0, v131
	v_add_f32_e32 v133, 1.0, v137
	v_mul_f32_e32 v143, 0.5, v102
	v_add_f32_e32 v131, 1.0, v131
	v_mul_f32_e32 v168, v143, v131
	v_mul_f32_e32 v137, 0x3d372713, v96
	v_mul_f32_e32 v137, v96, v137
	v_fma_f32 v137, v96, v137, v96
	v_mul_f32_e32 v137, 0x3f4c422a, v137
	v_add_f32_e32 v137, v137, v137
; #define SU ((bfraw*)(kargs()->ws + O_SU))
; #define SV ((bfraw*)(kargs()->ws + O_SV))
; #define SVSTAT ((float*)(kargs()->ws + O_SVSTAT))
; __global__ void __launch_bounds__(512) mega(Params p) {
;     ...
;                   } else if (c0 < 6144) {
; #pragma unroll
;                     for (int n = 0; n < 8; ++n)
; #pragma unroll
;                       for (int j = 0; j < 4; ++j) a[n][j] = gelu_tanh(a[n][j]);
;                     if (c0 >= 5120) { float* stp = SVSTAT + (long)r0 * 16 + ((c0 - 5120) >> 7) * 2;
; #pragma unroll
;                       for (int j = 0; j < 4; ++j) { float s1 = 0, s2 = 0;
; #pragma unroll
;                         for (int n = 0; n < 8; ++n) { s1 += a[n][j]; s2 += a[n][j] * a[n][j]; }
;                         s1 = red16(s1); s2 = red16(s2);
;                         if (fr == 0) { stp[j * 16] = s1; stp[j * 16 + 1] = s2; } } }
;                     store_nat_m((c0 < 5120 ? SU + (c0 - 4096) : SV + (c0 - 5120)) + (long)r0 * 1024, 1024, a, fr);
	v_mul_f32_e32 v137, 0x3fb8aa3b, v137
	v_exp_f32_e32 v137, v137
	v_rcp_f32_e32 v139, v133
	s_nop 0
	v_fma_f32 v131, -v133, v139, 1.0
	v_fma_f32 v139, v131, v139, v139
	v_add_f32_e32 v131, v139, v139
	v_div_fixup_f32 v131, v131, v133, 2.0
	v_sub_f32_e32 v131, 1.0, v131
	v_add_f32_e32 v133, 1.0, v137
	v_mul_f32_e32 v143, 0.5, v103
	v_add_f32_e32 v131, 1.0, v131
	v_mul_f32_e32 v154, v143, v131
	v_mul_f32_e32 v137, 0x3d372713, v97
	v_mul_f32_e32 v137, v97, v137
	v_fma_f32 v137, v97, v137, v97
	v_mul_f32_e32 v137, 0x3f4c422a, v137
	v_add_f32_e32 v137, v137, v137
	v_mul_f32_e32 v137, 0x3fb8aa3b, v137
	v_exp_f32_e32 v137, v137
	v_rcp_f32_e32 v139, v133
	s_nop 0
	v_fma_f32 v131, -v133, v139, 1.0
	v_fma_f32 v139, v131, v139, v139
	v_add_f32_e32 v131, v139, v139
	v_div_fixup_f32 v131, v131, v133, 2.0
	v_sub_f32_e32 v131, 1.0, v131
	v_add_f32_e32 v133, 1.0, v137
	v_mul_f32_e32 v143, 0.5, v96
	v_add_f32_e32 v131, 1.0, v131
	v_mul_f32_e32 v194, v143, v131
	v_mul_f32_e32 v137, 0x3d372713, v98
	v_mul_f32_e32 v137, v98, v137
	v_fma_f32 v137, v98, v137, v98
	v_mul_f32_e32 v137, 0x3f4c422a, v137
	v_add_f32_e32 v137, v137, v137
	v_mul_f32_e32 v137, 0x3fb8aa3b, v137
	v_exp_f32_e32 v137, v137
	v_rcp_f32_e32 v139, v133
	s_nop 0
	v_fma_f32 v131, -v133, v139, 1.0
	v_fma_f32 v139, v131, v139, v139
	v_add_f32_e32 v131, v139, v139
	v_div_fixup_f32 v131, v131, v133, 2.0
	v_sub_f32_e32 v131, 1.0, v131
	v_add_f32_e32 v133, 1.0, v137
	v_mul_f32_e32 v143, 0.5, v97
	v_add_f32_e32 v131, 1.0, v131
	v_mul_f32_e32 v192, v143, v131
	v_mul_f32_e32 v137, 0x3d372713, v99
	v_mul_f32_e32 v137, v99, v137
	v_fma_f32 v137, v99, v137, v99
	v_mul_f32_e32 v137, 0x3f4c422a, v137
	v_add_f32_e32 v137, v137, v137
	v_mul_f32_e32 v137, 0x3fb8aa3b, v137
	v_exp_f32_e32 v137, v137
	v_rcp_f32_e32 v139, v133
	s_nop 0
	v_fma_f32 v131, -v133, v139, 1.0
	v_fma_f32 v139, v131, v139, v139
	v_add_f32_e32 v131, v139, v139
	v_div_fixup_f32 v131, v131, v133, 2.0
	v_sub_f32_e32 v131, 1.0, v131
	v_add_f32_e32 v133, 1.0, v137
	v_mul_f32_e32 v143, 0.5, v98
	v_add_f32_e32 v131, 1.0, v131
	v_mul_f32_e32 v184, v143, v131
	v_rcp_f32_e32 v139, v133
	s_nop 0
	v_fma_f32 v131, -v133, v139, 1.0
	v_fma_f32 v139, v131, v139, v139
	v_add_f32_e32 v131, v139, v139
	v_div_fixup_f32 v131, v131, v133, 2.0
	v_sub_f32_e32 v131, 1.0, v131
	v_mul_f32_e32 v133, 0.5, v99
	v_add_f32_e32 v131, 1.0, v131
	v_mul_f32_e32 v166, v133, v131
	s_cbranch_scc1 .LBB0_907
	s_mov_b64 s[2:3], s[0:1]
	s_load_dwordx2 s[2:3], s[2:3], 0xe8
	v_ashrrev_i32_e32 v163, 31, v162
	v_lshlrev_b64 v[178:179], 6, v[162:163]
	v_add_u32_e32 v131, 0xffffec00, v176
	v_lshrrev_b32_e32 v180, 4, v131
	s_waitcnt lgkmcnt(0)
	v_lshl_add_u64 v[178:179], s[2:3], 0, v[178:179]
	v_mov_b32_e32 v181, v177
	v_lshl_add_u64 v[178:179], v[178:179], 0, v[180:181]
	s_mov_b64 s[2:3], 0x3a720400
	v_lshl_add_u64 v[196:197], v[178:179], 0, s[2:3]
	v_mov_b32_e32 v178, v177
	v_mov_b32_e32 v179, v145
	v_pk_add_f32 v[178:179], v[144:145], v[178:179]
	v_pk_mul_f32 v[180:181], v[144:145], v[144:145]
	v_mul_f32_e32 v157, v156, v156
	v_mov_b32_e32 v179, v181
	v_pk_mov_b32 v[180:181], v[144:145], v[180:181] op_sel:[1,0]
	s_mov_b32 s2, -1
	v_pk_add_f32 v[178:179], v[178:179], v[180:181]
	v_mul_f32_e32 v171, v170, v170
	v_pk_add_f32 v[178:179], v[178:179], v[156:157]
	v_mbcnt_lo_u32_b32 v131, s2, 0
	v_mul_f32_e32 v173, v172, v172
	v_mbcnt_hi_u32_b32 v131, s2, v131
	s_mov_b32 s2, -1
	v_pk_add_f32 v[178:179], v[178:179], v[170:171]
	v_mul_f32_e32 v189, v188, v188
	v_pk_add_f32 v[178:179], v[178:179], v[172:173]
	v_mbcnt_lo_u32_b32 v143, s2, 0
	v_mul_f32_e32 v191, v190, v190
	v_mbcnt_hi_u32_b32 v143, s2, v143
	v_pk_add_f32 v[178:179], v[178:179], v[188:189]
	v_mul_f32_e32 v195, v194, v194
	v_lshlrev_b32_e32 v131, 2, v131
	v_lshlrev_b32_e32 v143, 2, v143
	v_pk_add_f32 v[178:179], v[178:179], v[190:191]
	v_xor_b32_e32 v133, 4, v131
	v_xor_b32_e32 v147, 4, v143
	v_pk_add_f32 v[178:179], v[178:179], v[194:195]
	ds_bpermute_b32 v180, v133, v178
	ds_bpermute_b32 v181, v147, v179
	v_xor_b32_e32 v137, 8, v131
	v_xor_b32_e32 v149, 8, v143
	v_xor_b32_e32 v139, 16, v131
	v_xor_b32_e32 v151, 16, v143
	s_waitcnt lgkmcnt(0)
	v_pk_add_f32 v[178:179], v[178:179], v[180:181]
	ds_bpermute_b32 v180, v137, v178
	ds_bpermute_b32 v181, v149, v179
	v_xor_b32_e32 v131, 32, v131
	v_cmp_eq_u32_e32 vcc, 0, v202
	s_waitcnt lgkmcnt(0)
	v_pk_add_f32 v[178:179], v[178:179], v[180:181]
	ds_bpermute_b32 v180, v139, v178
	ds_bpermute_b32 v181, v151, v179
	s_waitcnt lgkmcnt(0)
	v_pk_add_f32 v[198:199], v[178:179], v[180:181]
	ds_bpermute_b32 v200, v131, v198
	v_xor_b32_e32 v131, 32, v143
	ds_bpermute_b32 v201, v131, v199
	s_and_saveexec_b64 s[2:3], vcc
	s_cbranch_execz .LBB0_900
	s_waitcnt lgkmcnt(0)
	v_pk_add_f32 v[178:179], v[198:199], v[200:201]
	global_store_dwordx2 v[196:197], v[178:179], off

; DEVFI float sigmoidf_(float x) { return 1.f / (1.f + __expf(-x)); }
; #define RG ((bfraw*)(kargs()->ws + O_RG))
; __global__ void __launch_bounds__(512) mega(Params p) {
;     ...
;                   } else if (c0 < 4096) {
; #pragma unroll
;                     for (int n = 0; n < 8; ++n)
; #pragma unroll
;                       for (int j = 0; j < 4; ++j) { const float x = a[n][j]; a[n][j] = x * sigmoidf_(x); }
;                     store_nat_m(RG + (long)r0 * 1024 + (c0 - 3072), 1024, a, fr);
.LBB0_975:
	s_andn2_b64 vcc, exec, s[2:3]
	s_cbranch_vccnz .LBB0_1041
	v_mul_f32_e32 v128, 0xbfb8aa3b, v124
	v_exp_f32_e32 v128, v128
	s_nop 0
	v_add_f32_e32 v128, 1.0, v128
	s_nop 0
	v_rcp_f32_e32 v130, v128
	s_nop 0
	v_fma_f32 v129, -v128, v130, 1.0
	v_fma_f32 v129, v129, v130, v130
	v_div_fixup_f32 v128, v129, v128, 1.0
	v_mul_f32_e32 v129, 0xbfb8aa3b, v120
	v_exp_f32_e32 v129, v129
	v_mul_f32_e32 v128, v124, v128
	v_add_f32_e32 v129, 1.0, v129
	s_nop 0
	v_rcp_f32_e32 v131, v129
	s_nop 0
	v_fma_f32 v130, -v129, v131, 1.0
	v_fma_f32 v130, v130, v131, v131
	v_div_fixup_f32 v129, v130, v129, 1.0
	v_mul_f32_e32 v130, 0xbfb8aa3b, v108
	v_exp_f32_e32 v130, v130
	v_mul_f32_e32 v129, v120, v129
	v_add_f32_e32 v130, 1.0, v130
	s_nop 0
	v_rcp_f32_e32 v133, v130
	s_nop 0
	v_fma_f32 v131, -v130, v133, 1.0
	v_fma_f32 v133, v131, v133, v133
	v_mul_f32_e32 v131, 0xbfb8aa3b, v104
	v_exp_f32_e32 v131, v131
	s_nop 0
	v_add_f32_e32 v134, 1.0, v131
	s_mov_b64 s[2:3], s[0:1]
	s_load_dwordx2 s[2:3], s[2:3], 0xe8
	v_rcp_f32_e32 v135, v134
	s_nop 0
	v_fma_f32 v131, -v134, v135, 1.0
	v_fma_f32 v135, v131, v135, v135
	v_and_b32_e32 v131, 1, v203
	v_cmp_eq_u32_e64 s[8:9], 0, v131
	v_cmp_eq_u32_e64 s[6:7], 1, v131
	s_nop 0
	v_cndmask_b32_e64 v131, v128, v129, s[8:9]
	s_nop 1
	v_mov_b32_dpp v136, v131 quad_perm:[1,0,3,2] row_mask:0xf bank_mask:0xf bound_ctrl:1
	s_and_saveexec_b64 s[36:37], s[6:7]
	s_xor_b64 s[36:37], exec, s[36:37]
	s_cbranch_execz .LBB0_978
	v_cvt_pk_bf16_f32 v131, v136, v129

; DEVFI float sigmoidf_(float x) { return 1.f / (1.f + __expf(-x)); }
; DEVFI float dpp_xor1(float x) { return __int_as_float(__builtin_amdgcn_update_dpp(0, __float_as_int(x), 0xB1, 0xF, 0xF, true)); }
; #define RG ((bfraw*)(kargs()->ws + O_RG))
; DEVFI void store_nat_m(bfraw* base, long ld, f32x4 (&a)[8], int fr) {
;     ...
;     for (int n0 = 0; n0 < 8; n0 += 2) { const float own0 = a[n0][j], own1 = a[n0 + 1][j];
;       const float recv = dpp_xor1(odd ? own0 : own1);
;       const unsigned pk = odd ? cvtpk(recv, own1) : cvtpk(own0, recv);
;       *reinterpret_cast<unsigned*>(p0 + (long)j * ld + n0 * 16) = pk; }
; __global__ void __launch_bounds__(512) mega(Params p) {
;     ...
;                   } else if (c0 < 4096) {
; #pragma unroll
;                     for (int n = 0; n < 8; ++n)
; #pragma unroll
;                       for (int j = 0; j < 4; ++j) { const float x = a[n][j]; a[n][j] = x * sigmoidf_(x); }
;                     store_nat_m(RG + (long)r0 * 1024 + (c0 - 3072), 1024, a, fr);
.LBB0_980:
	s_or_b64 exec, exec, s[36:37]
	v_mul_f32_e32 v128, 0xbfb8aa3b, v116
	v_exp_f32_e32 v128, v128
	v_ashrrev_i32_e32 v163, 31, v162
	v_mov_b32_e32 v141, v177
	v_add_f32_e32 v135, 1.0, v128
	s_nop 0
	v_rcp_f32_e32 v129, v135
	s_nop 0
	v_fma_f32 v128, -v135, v129, 1.0
	v_fma_f32 v136, v128, v129, v129
	v_mul_f32_e32 v128, 0xbfb8aa3b, v112
	v_exp_f32_e32 v128, v128
	s_nop 0
	v_add_f32_e32 v137, 1.0, v128
	s_nop 0
	v_rcp_f32_e32 v129, v137
	s_nop 0
	v_fma_f32 v128, -v137, v129, 1.0
	v_fma_f32 v138, v128, v129, v129
	v_lshlrev_b64 v[128:129], 11, v[162:163]
	v_add_u32_e32 v139, 15, v202
	s_waitcnt lgkmcnt(0)
	v_lshl_add_u64 v[128:129], s[2:3], 0, v[128:129]
	v_cndmask_b32_e64 v139, v139, v202, s[8:9]
	v_lshl_add_u64 v[128:129], v[176:177], 1, v[128:129]
	v_lshlrev_b32_e32 v140, 1, v139
	v_lshl_add_u64 v[128:129], v[128:129], 0, v[140:141]
	v_add_co_u32_e32 v140, vcc, 0x1971e000, v128
	v_mov_b32_dpp v139, v134 quad_perm:[1,0,3,2] row_mask:0xf bank_mask:0xf bound_ctrl:1
	s_nop 0
	v_addc_co_u32_e32 v141, vcc, 0, v129, vcc
	global_store_dword v[140:141], v131, off offset:2048
	s_and_saveexec_b64 s[2:3], s[6:7]
	s_xor_b64 s[2:3], exec, s[2:3]
	s_cbranch_execz .LBB0_982
	v_cvt_pk_bf16_f32 v134, v139, v133

; DEVFI float sigmoidf_(float x) { return 1.f / (1.f + __expf(-x)); }
; DEVFI float dpp_xor1(float x) { return __int_as_float(__builtin_amdgcn_update_dpp(0, __float_as_int(x), 0xB1, 0xF, 0xF, true)); }
; #define RG ((bfraw*)(kargs()->ws + O_RG))
; DEVFI void store_nat_m(bfraw* base, long ld, f32x4 (&a)[8], int fr) {
;     ...
;     for (int n0 = 0; n0 < 8; n0 += 2) { const float own0 = a[n0][j], own1 = a[n0 + 1][j];
;       const float recv = dpp_xor1(odd ? own0 : own1);
;       const unsigned pk = odd ? cvtpk(recv, own1) : cvtpk(own0, recv);
;       *reinterpret_cast<unsigned*>(p0 + (long)j * ld + n0 * 16) = pk; }
; __global__ void __launch_bounds__(512) mega(Params p) {
;     ...
;                   } else if (c0 < 4096) {
; #pragma unroll
;                     for (int n = 0; n < 8; ++n)
; #pragma unroll
;                       for (int j = 0; j < 4; ++j) { const float x = a[n][j]; a[n][j] = x * sigmoidf_(x); }
;                     store_nat_m(RG + (long)r0 * 1024 + (c0 - 3072), 1024, a, fr);
.LBB0_984:
	s_or_b64 exec, exec, s[2:3]
	v_mul_f32_e32 v130, 0xbfb8aa3b, v100
	v_exp_f32_e32 v130, v130
	s_mov_b64 s[2:3], 0x1971e800
	v_lshl_add_u64 v[128:129], v[128:129], 0, s[2:3]
	global_store_dword v[128:129], v134, off offset:64
	v_add_f32_e32 v130, 1.0, v130
	s_nop 0
	v_rcp_f32_e32 v137, v130
	s_nop 0
	v_fma_f32 v136, -v130, v137, 1.0
	v_fma_f32 v136, v136, v137, v137
	v_mul_f32_e32 v137, 0xbfb8aa3b, v96
	v_exp_f32_e32 v137, v137
	s_nop 0
	v_add_f32_e32 v137, 1.0, v137
	s_nop 0
	v_rcp_f32_e32 v139, v137
	s_nop 0
	v_fma_f32 v138, -v137, v139, 1.0
	v_fma_f32 v139, v138, v139, v139
	s_nop 0
	v_mov_b32_dpp v138, v135 quad_perm:[1,0,3,2] row_mask:0xf bank_mask:0xf bound_ctrl:1
	s_and_saveexec_b64 s[2:3], s[6:7]
	s_xor_b64 s[2:3], exec, s[2:3]
	s_cbranch_execz .LBB0_986
	v_cvt_pk_bf16_f32 v134, v138, v133

; DEVFI float sigmoidf_(float x) { return 1.f / (1.f + __expf(-x)); }
; DEVFI float dpp_xor1(float x) { return __int_as_float(__builtin_amdgcn_update_dpp(0, __float_as_int(x), 0xB1, 0xF, 0xF, true)); }
; #define RG ((bfraw*)(kargs()->ws + O_RG))
; DEVFI void store_nat_m(bfraw* base, long ld, f32x4 (&a)[8], int fr) {
;     ...
;     for (int n0 = 0; n0 < 8; n0 += 2) { const float own0 = a[n0][j], own1 = a[n0 + 1][j];
;       const float recv = dpp_xor1(odd ? own0 : own1);
;       const unsigned pk = odd ? cvtpk(recv, own1) : cvtpk(own0, recv);
;       *reinterpret_cast<unsigned*>(p0 + (long)j * ld + n0 * 16) = pk; }
; __global__ void __launch_bounds__(512) mega(Params p) {
;     ...
;                   } else if (c0 < 4096) {
; #pragma unroll
;                     for (int n = 0; n < 8; ++n)
; #pragma unroll
;                       for (int j = 0; j < 4; ++j) { const float x = a[n][j]; a[n][j] = x * sigmoidf_(x); }
;                     store_nat_m(RG + (long)r0 * 1024 + (c0 - 3072), 1024, a, fr);
.LBB0_988:
	s_or_b64 exec, exec, s[2:3]
	v_mul_f32_e32 v131, 0xbfb8aa3b, v125
	v_exp_f32_e32 v131, v131
	global_store_dword v[128:129], v134, off offset:128
	v_add_f32_e32 v131, 1.0, v131
	s_nop 0
	v_rcp_f32_e32 v137, v131
	s_nop 0
	v_fma_f32 v136, -v131, v137, 1.0
	v_fma_f32 v136, v136, v137, v137
	v_mul_f32_e32 v137, 0xbfb8aa3b, v121
	v_exp_f32_e32 v137, v137
	s_nop 0
	v_add_f32_e32 v137, 1.0, v137
	s_nop 0
	v_rcp_f32_e32 v139, v137
	s_nop 0
	v_fma_f32 v138, -v137, v139, 1.0
	v_fma_f32 v139, v138, v139, v139
	s_nop 0
	v_mov_b32_dpp v138, v133 quad_perm:[1,0,3,2] row_mask:0xf bank_mask:0xf bound_ctrl:1
	s_and_saveexec_b64 s[2:3], s[6:7]
	s_xor_b64 s[2:3], exec, s[2:3]
	s_cbranch_execz .LBB0_990
	v_cvt_pk_bf16_f32 v133, v138, v135

; DEVFI float sigmoidf_(float x) { return 1.f / (1.f + __expf(-x)); }
; DEVFI float dpp_xor1(float x) { return __int_as_float(__builtin_amdgcn_update_dpp(0, __float_as_int(x), 0xB1, 0xF, 0xF, true)); }
; #define RG ((bfraw*)(kargs()->ws + O_RG))
; DEVFI void store_nat_m(bfraw* base, long ld, f32x4 (&a)[8], int fr) {
;     ...
;     for (int n0 = 0; n0 < 8; n0 += 2) { const float own0 = a[n0][j], own1 = a[n0 + 1][j];
;       const float recv = dpp_xor1(odd ? own0 : own1);
;       const unsigned pk = odd ? cvtpk(recv, own1) : cvtpk(own0, recv);
;       *reinterpret_cast<unsigned*>(p0 + (long)j * ld + n0 * 16) = pk; }
; __global__ void __launch_bounds__(512) mega(Params p) {
;     ...
;                   } else if (c0 < 4096) {
; #pragma unroll
;                     for (int n = 0; n < 8; ++n)
; #pragma unroll
;                       for (int j = 0; j < 4; ++j) { const float x = a[n][j]; a[n][j] = x * sigmoidf_(x); }
;                     store_nat_m(RG + (long)r0 * 1024 + (c0 - 3072), 1024, a, fr);
.LBB0_992:
	s_or_b64 exec, exec, s[2:3]
	v_mul_f32_e32 v130, 0xbfb8aa3b, v109
	v_exp_f32_e32 v130, v130
	global_store_dword v[128:129], v133, off offset:192
	v_add_f32_e32 v130, 1.0, v130
	s_nop 0
	v_rcp_f32_e32 v137, v130
	s_nop 0
	v_fma_f32 v135, -v130, v137, 1.0
	v_fma_f32 v135, v135, v137, v137
	v_mul_f32_e32 v137, 0xbfb8aa3b, v105
	v_exp_f32_e32 v137, v137
	s_nop 0
	v_add_f32_e32 v137, 1.0, v137
	s_nop 0
	v_rcp_f32_e32 v139, v137
	s_nop 0
	v_fma_f32 v138, -v137, v139, 1.0
	v_fma_f32 v139, v138, v139, v139
	s_nop 0
	v_mov_b32_dpp v138, v136 quad_perm:[1,0,3,2] row_mask:0xf bank_mask:0xf bound_ctrl:1
	s_and_saveexec_b64 s[2:3], s[6:7]
	s_xor_b64 s[2:3], exec, s[2:3]
	s_cbranch_execz .LBB0_994
	v_cvt_pk_bf16_f32 v133, v138, v134

; DEVFI float sigmoidf_(float x) { return 1.f / (1.f + __expf(-x)); }
; DEVFI float dpp_xor1(float x) { return __int_as_float(__builtin_amdgcn_update_dpp(0, __float_as_int(x), 0xB1, 0xF, 0xF, true)); }
; #define RG ((bfraw*)(kargs()->ws + O_RG))
; DEVFI void store_nat_m(bfraw* base, long ld, f32x4 (&a)[8], int fr) {
;     ...
;     for (int n0 = 0; n0 < 8; n0 += 2) { const float own0 = a[n0][j], own1 = a[n0 + 1][j];
;       const float recv = dpp_xor1(odd ? own0 : own1);
;       const unsigned pk = odd ? cvtpk(recv, own1) : cvtpk(own0, recv);
;       *reinterpret_cast<unsigned*>(p0 + (long)j * ld + n0 * 16) = pk; }
; __global__ void __launch_bounds__(512) mega(Params p) {
;     ...
;                   } else if (c0 < 4096) {
; #pragma unroll
;                     for (int n = 0; n < 8; ++n)
; #pragma unroll
;                       for (int j = 0; j < 4; ++j) { const float x = a[n][j]; a[n][j] = x * sigmoidf_(x); }
;                     store_nat_m(RG + (long)r0 * 1024 + (c0 - 3072), 1024, a, fr);
.LBB0_996:
	s_or_b64 exec, exec, s[2:3]
	v_mul_f32_e32 v131, 0xbfb8aa3b, v117
	v_exp_f32_e32 v131, v131
	global_store_dword v[128:129], v133, off offset:2048
	v_add_f32_e32 v131, 1.0, v131
	s_nop 0
	v_rcp_f32_e32 v137, v131
	s_nop 0
	v_fma_f32 v135, -v131, v137, 1.0
	v_fma_f32 v135, v135, v137, v137
	v_mul_f32_e32 v137, 0xbfb8aa3b, v113
	v_exp_f32_e32 v137, v137
	s_nop 0
	v_add_f32_e32 v137, 1.0, v137
	s_nop 0
	v_rcp_f32_e32 v139, v137
	s_nop 0
	v_fma_f32 v138, -v137, v139, 1.0
	v_fma_f32 v139, v138, v139, v139
	s_nop 0
	v_mov_b32_dpp v138, v136 quad_perm:[1,0,3,2] row_mask:0xf bank_mask:0xf bound_ctrl:1
	s_and_saveexec_b64 s[2:3], s[6:7]
	s_xor_b64 s[2:3], exec, s[2:3]
	s_cbranch_execz .LBB0_998
	v_cvt_pk_bf16_f32 v133, v138, v134

; DEVFI float sigmoidf_(float x) { return 1.f / (1.f + __expf(-x)); }
; DEVFI float dpp_xor1(float x) { return __int_as_float(__builtin_amdgcn_update_dpp(0, __float_as_int(x), 0xB1, 0xF, 0xF, true)); }
; #define RG ((bfraw*)(kargs()->ws + O_RG))
; DEVFI void store_nat_m(bfraw* base, long ld, f32x4 (&a)[8], int fr) {
;     ...
;     for (int n0 = 0; n0 < 8; n0 += 2) { const float own0 = a[n0][j], own1 = a[n0 + 1][j];
;       const float recv = dpp_xor1(odd ? own0 : own1);
;       const unsigned pk = odd ? cvtpk(recv, own1) : cvtpk(own0, recv);
;       *reinterpret_cast<unsigned*>(p0 + (long)j * ld + n0 * 16) = pk; }
; __global__ void __launch_bounds__(512) mega(Params p) {
;     ...
;                   } else if (c0 < 4096) {
; #pragma unroll
;                     for (int n = 0; n < 8; ++n)
; #pragma unroll
;                       for (int j = 0; j < 4; ++j) { const float x = a[n][j]; a[n][j] = x * sigmoidf_(x); }
;                     store_nat_m(RG + (long)r0 * 1024 + (c0 - 3072), 1024, a, fr);
.LBB0_1000:
	s_or_b64 exec, exec, s[2:3]
	v_mul_f32_e32 v130, 0xbfb8aa3b, v101
	v_exp_f32_e32 v130, v130
	global_store_dword v[128:129], v133, off offset:2112
	v_add_f32_e32 v130, 1.0, v130
	s_nop 0
	v_rcp_f32_e32 v137, v130
	s_nop 0
	v_fma_f32 v135, -v130, v137, 1.0
	v_fma_f32 v135, v135, v137, v137
	v_mul_f32_e32 v137, 0xbfb8aa3b, v97
	v_exp_f32_e32 v137, v137
	s_nop 0
	v_add_f32_e32 v137, 1.0, v137
	s_nop 0
	v_rcp_f32_e32 v139, v137
	s_nop 0
	v_fma_f32 v138, -v137, v139, 1.0
	v_fma_f32 v139, v138, v139, v139
	s_nop 0
	v_mov_b32_dpp v138, v136 quad_perm:[1,0,3,2] row_mask:0xf bank_mask:0xf bound_ctrl:1
	s_and_saveexec_b64 s[2:3], s[6:7]
	s_xor_b64 s[2:3], exec, s[2:3]
	s_cbranch_execz .LBB0_1002
	v_cvt_pk_bf16_f32 v133, v138, v134

; DEVFI float sigmoidf_(float x) { return 1.f / (1.f + __expf(-x)); }
; DEVFI float dpp_xor1(float x) { return __int_as_float(__builtin_amdgcn_update_dpp(0, __float_as_int(x), 0xB1, 0xF, 0xF, true)); }
; #define RG ((bfraw*)(kargs()->ws + O_RG))
; DEVFI void store_nat_m(bfraw* base, long ld, f32x4 (&a)[8], int fr) {
;     ...
;     for (int n0 = 0; n0 < 8; n0 += 2) { const float own0 = a[n0][j], own1 = a[n0 + 1][j];
;       const float recv = dpp_xor1(odd ? own0 : own1);
;       const unsigned pk = odd ? cvtpk(recv, own1) : cvtpk(own0, recv);
;       *reinterpret_cast<unsigned*>(p0 + (long)j * ld + n0 * 16) = pk; }
; __global__ void __launch_bounds__(512) mega(Params p) {
;     ...
;                   } else if (c0 < 4096) {
; #pragma unroll
;                     for (int n = 0; n < 8; ++n)
; #pragma unroll
;                       for (int j = 0; j < 4; ++j) { const float x = a[n][j]; a[n][j] = x * sigmoidf_(x); }
;                     store_nat_m(RG + (long)r0 * 1024 + (c0 - 3072), 1024, a, fr);
.LBB0_1004:
	s_or_b64 exec, exec, s[2:3]
	v_mul_f32_e32 v131, 0xbfb8aa3b, v126
	v_exp_f32_e32 v131, v131
	global_store_dword v[128:129], v133, off offset:2176
	v_add_f32_e32 v131, 1.0, v131
	s_nop 0
	v_rcp_f32_e32 v137, v131
	s_nop 0
	v_fma_f32 v135, -v131, v137, 1.0
	v_fma_f32 v135, v135, v137, v137
	v_mul_f32_e32 v137, 0xbfb8aa3b, v122
	v_exp_f32_e32 v137, v137
	s_nop 0
	v_add_f32_e32 v137, 1.0, v137
	s_nop 0
	v_rcp_f32_e32 v139, v137
	s_nop 0
	v_fma_f32 v138, -v137, v139, 1.0
	v_fma_f32 v139, v138, v139, v139
	s_nop 0
	v_mov_b32_dpp v138, v136 quad_perm:[1,0,3,2] row_mask:0xf bank_mask:0xf bound_ctrl:1
	s_and_saveexec_b64 s[2:3], s[6:7]
	s_xor_b64 s[2:3], exec, s[2:3]
	s_cbranch_execz .LBB0_1006
	v_cvt_pk_bf16_f32 v133, v138, v134

; DEVFI float sigmoidf_(float x) { return 1.f / (1.f + __expf(-x)); }
; DEVFI float dpp_xor1(float x) { return __int_as_float(__builtin_amdgcn_update_dpp(0, __float_as_int(x), 0xB1, 0xF, 0xF, true)); }
; #define RG ((bfraw*)(kargs()->ws + O_RG))
; DEVFI void store_nat_m(bfraw* base, long ld, f32x4 (&a)[8], int fr) {
;     ...
;     for (int n0 = 0; n0 < 8; n0 += 2) { const float own0 = a[n0][j], own1 = a[n0 + 1][j];
;       const float recv = dpp_xor1(odd ? own0 : own1);
;       const unsigned pk = odd ? cvtpk(recv, own1) : cvtpk(own0, recv);
;       *reinterpret_cast<unsigned*>(p0 + (long)j * ld + n0 * 16) = pk; }
; __global__ void __launch_bounds__(512) mega(Params p) {
;     ...
;                   } else if (c0 < 4096) {
; #pragma unroll
;                     for (int n = 0; n < 8; ++n)
; #pragma unroll
;                       for (int j = 0; j < 4; ++j) { const float x = a[n][j]; a[n][j] = x * sigmoidf_(x); }
;                     store_nat_m(RG + (long)r0 * 1024 + (c0 - 3072), 1024, a, fr);
.LBB0_1008:
	s_or_b64 exec, exec, s[2:3]
	v_mul_f32_e32 v130, 0xbfb8aa3b, v110
	v_exp_f32_e32 v130, v130
	global_store_dword v[128:129], v133, off offset:2240
	v_add_f32_e32 v130, 1.0, v130
	s_nop 0
	v_rcp_f32_e32 v137, v130
	s_nop 0
	v_fma_f32 v135, -v130, v137, 1.0
	v_fma_f32 v135, v135, v137, v137
	v_mul_f32_e32 v137, 0xbfb8aa3b, v106
	v_exp_f32_e32 v137, v137
	s_nop 0
	v_add_f32_e32 v137, 1.0, v137
	s_nop 0
	v_rcp_f32_e32 v139, v137
	s_nop 0
	v_fma_f32 v138, -v137, v139, 1.0
	v_fma_f32 v139, v138, v139, v139
	s_nop 0
	v_mov_b32_dpp v138, v136 quad_perm:[1,0,3,2] row_mask:0xf bank_mask:0xf bound_ctrl:1
	s_and_saveexec_b64 s[2:3], s[6:7]
	s_xor_b64 s[2:3], exec, s[2:3]
	s_cbranch_execz .LBB0_1010
	v_cvt_pk_bf16_f32 v133, v138, v134

; DEVFI float sigmoidf_(float x) { return 1.f / (1.f + __expf(-x)); }
; DEVFI float dpp_xor1(float x) { return __int_as_float(__builtin_amdgcn_update_dpp(0, __float_as_int(x), 0xB1, 0xF, 0xF, true)); }
; #define RG ((bfraw*)(kargs()->ws + O_RG))
; DEVFI void store_nat_m(bfraw* base, long ld, f32x4 (&a)[8], int fr) {
;     ...
;     for (int n0 = 0; n0 < 8; n0 += 2) { const float own0 = a[n0][j], own1 = a[n0 + 1][j];
;       const float recv = dpp_xor1(odd ? own0 : own1);
;       const unsigned pk = odd ? cvtpk(recv, own1) : cvtpk(own0, recv);
;       *reinterpret_cast<unsigned*>(p0 + (long)j * ld + n0 * 16) = pk; }
; __global__ void __launch_bounds__(512) mega(Params p) {
;     ...
;                   } else if (c0 < 4096) {
; #pragma unroll
;                     for (int n = 0; n < 8; ++n)
; #pragma unroll
;                       for (int j = 0; j < 4; ++j) { const float x = a[n][j]; a[n][j] = x * sigmoidf_(x); }
;                     store_nat_m(RG + (long)r0 * 1024 + (c0 - 3072), 1024, a, fr);
.LBB0_1012:
	s_or_b64 exec, exec, s[2:3]
	v_mul_f32_e32 v131, 0xbfb8aa3b, v118
	v_exp_f32_e32 v131, v131
	s_nop 0
	v_add_f32_e32 v131, 1.0, v131
	s_nop 0
	v_rcp_f32_e32 v137, v131
	s_nop 0
	v_fma_f32 v135, -v131, v137, 1.0
	v_fma_f32 v135, v135, v137, v137
	v_mul_f32_e32 v137, 0xbfb8aa3b, v114
	v_exp_f32_e32 v137, v137
	s_nop 0
	v_add_f32_e32 v137, 1.0, v137
	s_nop 0
	v_rcp_f32_e32 v139, v137
	s_nop 0
	v_fma_f32 v138, -v137, v139, 1.0
	v_fma_f32 v138, v138, v139, v139
	v_add_co_u32_e32 v140, vcc, 0x1000, v128
	v_mov_b32_dpp v139, v136 quad_perm:[1,0,3,2] row_mask:0xf bank_mask:0xf bound_ctrl:1
	s_nop 0
	v_addc_co_u32_e32 v141, vcc, 0, v129, vcc
	global_store_dword v[140:141], v133, off
	s_and_saveexec_b64 s[2:3], s[6:7]
	s_xor_b64 s[2:3], exec, s[2:3]
	s_cbranch_execz .LBB0_1014
	v_cvt_pk_bf16_f32 v133, v139, v134

; DEVFI float sigmoidf_(float x) { return 1.f / (1.f + __expf(-x)); }
; DEVFI float dpp_xor1(float x) { return __int_as_float(__builtin_amdgcn_update_dpp(0, __float_as_int(x), 0xB1, 0xF, 0xF, true)); }
; #define RG ((bfraw*)(kargs()->ws + O_RG))
; DEVFI void store_nat_m(bfraw* base, long ld, f32x4 (&a)[8], int fr) {
;     ...
;     for (int n0 = 0; n0 < 8; n0 += 2) { const float own0 = a[n0][j], own1 = a[n0 + 1][j];
;       const float recv = dpp_xor1(odd ? own0 : own1);
;       const unsigned pk = odd ? cvtpk(recv, own1) : cvtpk(own0, recv);
;       *reinterpret_cast<unsigned*>(p0 + (long)j * ld + n0 * 16) = pk; }
; __global__ void __launch_bounds__(512) mega(Params p) {
;     ...
;                   } else if (c0 < 4096) {
; #pragma unroll
;                     for (int n = 0; n < 8; ++n)
; #pragma unroll
;                       for (int j = 0; j < 4; ++j) { const float x = a[n][j]; a[n][j] = x * sigmoidf_(x); }
;                     store_nat_m(RG + (long)r0 * 1024 + (c0 - 3072), 1024, a, fr);
.LBB0_1016:
	s_or_b64 exec, exec, s[2:3]
	v_mul_f32_e32 v130, 0xbfb8aa3b, v102
	v_exp_f32_e32 v130, v130
	s_nop 0
	v_add_f32_e32 v130, 1.0, v130
	s_nop 0
	v_rcp_f32_e32 v137, v130
	s_nop 0
	v_fma_f32 v135, -v130, v137, 1.0
	v_fma_f32 v135, v135, v137, v137
	v_mul_f32_e32 v137, 0xbfb8aa3b, v98
	v_exp_f32_e32 v137, v137
	s_nop 0
	v_add_f32_e32 v137, 1.0, v137
	s_nop 0
	v_rcp_f32_e32 v139, v137
	s_nop 0
	v_fma_f32 v138, -v137, v139, 1.0
	v_fma_f32 v138, v138, v139, v139
	v_add_co_u32_e32 v140, vcc, 0x1000, v128
	v_mov_b32_dpp v139, v136 quad_perm:[1,0,3,2] row_mask:0xf bank_mask:0xf bound_ctrl:1
	s_nop 0
	v_addc_co_u32_e32 v141, vcc, 0, v129, vcc
	global_store_dword v[140:141], v133, off offset:64
	s_and_saveexec_b64 s[2:3], s[6:7]
	s_xor_b64 s[2:3], exec, s[2:3]
	s_cbranch_execz .LBB0_1018
	v_cvt_pk_bf16_f32 v133, v139, v134

; DEVFI float sigmoidf_(float x) { return 1.f / (1.f + __expf(-x)); }
; DEVFI float dpp_xor1(float x) { return __int_as_float(__builtin_amdgcn_update_dpp(0, __float_as_int(x), 0xB1, 0xF, 0xF, true)); }
; #define RG ((bfraw*)(kargs()->ws + O_RG))
; DEVFI void store_nat_m(bfraw* base, long ld, f32x4 (&a)[8], int fr) {
;     ...
;     for (int n0 = 0; n0 < 8; n0 += 2) { const float own0 = a[n0][j], own1 = a[n0 + 1][j];
;       const float recv = dpp_xor1(odd ? own0 : own1);
;       const unsigned pk = odd ? cvtpk(recv, own1) : cvtpk(own0, recv);
;       *reinterpret_cast<unsigned*>(p0 + (long)j * ld + n0 * 16) = pk; }
; __global__ void __launch_bounds__(512) mega(Params p) {
;     ...
;                   } else if (c0 < 4096) {
; #pragma unroll
;                     for (int n = 0; n < 8; ++n)
; #pragma unroll
;                       for (int j = 0; j < 4; ++j) { const float x = a[n][j]; a[n][j] = x * sigmoidf_(x); }
;                     store_nat_m(RG + (long)r0 * 1024 + (c0 - 3072), 1024, a, fr);
.LBB0_1020:
	s_or_b64 exec, exec, s[2:3]
	v_mul_f32_e32 v131, 0xbfb8aa3b, v127
	v_exp_f32_e32 v131, v131
	s_nop 0
	v_add_f32_e32 v131, 1.0, v131
	s_nop 0
	v_rcp_f32_e32 v137, v131
	s_nop 0
	v_fma_f32 v135, -v131, v137, 1.0
	v_fma_f32 v135, v135, v137, v137
	v_mul_f32_e32 v137, 0xbfb8aa3b, v123
	v_exp_f32_e32 v137, v137
	s_nop 0
	v_add_f32_e32 v137, 1.0, v137
	s_nop 0
	v_rcp_f32_e32 v139, v137
	s_nop 0
	v_fma_f32 v138, -v137, v139, 1.0
	v_fma_f32 v138, v138, v139, v139
	v_add_co_u32_e32 v140, vcc, 0x1000, v128
	v_mov_b32_dpp v139, v136 quad_perm:[1,0,3,2] row_mask:0xf bank_mask:0xf bound_ctrl:1
	s_nop 0
	v_addc_co_u32_e32 v141, vcc, 0, v129, vcc
	global_store_dword v[140:141], v133, off offset:128
	s_and_saveexec_b64 s[2:3], s[6:7]
	s_xor_b64 s[2:3], exec, s[2:3]
	s_cbranch_execz .LBB0_1022
	v_cvt_pk_bf16_f32 v133, v139, v134

; DEVFI float sigmoidf_(float x) { return 1.f / (1.f + __expf(-x)); }
; DEVFI float dpp_xor1(float x) { return __int_as_float(__builtin_amdgcn_update_dpp(0, __float_as_int(x), 0xB1, 0xF, 0xF, true)); }
; #define RG ((bfraw*)(kargs()->ws + O_RG))
; DEVFI void store_nat_m(bfraw* base, long ld, f32x4 (&a)[8], int fr) {
;     ...
;     for (int n0 = 0; n0 < 8; n0 += 2) { const float own0 = a[n0][j], own1 = a[n0 + 1][j];
;       const float recv = dpp_xor1(odd ? own0 : own1);
;       const unsigned pk = odd ? cvtpk(recv, own1) : cvtpk(own0, recv);
;       *reinterpret_cast<unsigned*>(p0 + (long)j * ld + n0 * 16) = pk; }
; __global__ void __launch_bounds__(512) mega(Params p) {
;     ...
;                   } else if (c0 < 4096) {
; #pragma unroll
;                     for (int n = 0; n < 8; ++n)
; #pragma unroll
;                       for (int j = 0; j < 4; ++j) { const float x = a[n][j]; a[n][j] = x * sigmoidf_(x); }
;                     store_nat_m(RG + (long)r0 * 1024 + (c0 - 3072), 1024, a, fr);
.LBB0_1024:
	s_or_b64 exec, exec, s[2:3]
	v_mul_f32_e32 v130, 0xbfb8aa3b, v111
	v_exp_f32_e32 v130, v130
	s_nop 0
	v_add_f32_e32 v130, 1.0, v130
	s_nop 0
	v_rcp_f32_e32 v137, v130
	s_nop 0
	v_fma_f32 v135, -v130, v137, 1.0
	v_fma_f32 v135, v135, v137, v137
	v_mul_f32_e32 v137, 0xbfb8aa3b, v107
	v_exp_f32_e32 v137, v137
	s_nop 0
	v_add_f32_e32 v137, 1.0, v137
	s_nop 0
	v_rcp_f32_e32 v139, v137
	s_nop 0
	v_fma_f32 v138, -v137, v139, 1.0
	v_fma_f32 v138, v138, v139, v139
	v_add_co_u32_e32 v140, vcc, 0x1000, v128
	v_mov_b32_dpp v139, v136 quad_perm:[1,0,3,2] row_mask:0xf bank_mask:0xf bound_ctrl:1
	s_nop 0
	v_addc_co_u32_e32 v141, vcc, 0, v129, vcc
	global_store_dword v[140:141], v133, off offset:192
	s_and_saveexec_b64 s[2:3], s[6:7]
	s_xor_b64 s[2:3], exec, s[2:3]
	s_cbranch_execz .LBB0_1026
	v_cvt_pk_bf16_f32 v133, v139, v134

; DEVFI float sigmoidf_(float x) { return 1.f / (1.f + __expf(-x)); }
; DEVFI float dpp_xor1(float x) { return __int_as_float(__builtin_amdgcn_update_dpp(0, __float_as_int(x), 0xB1, 0xF, 0xF, true)); }
; #define RG ((bfraw*)(kargs()->ws + O_RG))
; DEVFI void store_nat_m(bfraw* base, long ld, f32x4 (&a)[8], int fr) {
;     ...
;     for (int n0 = 0; n0 < 8; n0 += 2) { const float own0 = a[n0][j], own1 = a[n0 + 1][j];
;       const float recv = dpp_xor1(odd ? own0 : own1);
;       const unsigned pk = odd ? cvtpk(recv, own1) : cvtpk(own0, recv);
;       *reinterpret_cast<unsigned*>(p0 + (long)j * ld + n0 * 16) = pk; }
; __global__ void __launch_bounds__(512) mega(Params p) {
;     ...
;                   } else if (c0 < 4096) {
; #pragma unroll
;                     for (int n = 0; n < 8; ++n)
; #pragma unroll
;                       for (int j = 0; j < 4; ++j) { const float x = a[n][j]; a[n][j] = x * sigmoidf_(x); }
;                     store_nat_m(RG + (long)r0 * 1024 + (c0 - 3072), 1024, a, fr);
.LBB0_1028:
	s_or_b64 exec, exec, s[2:3]
	v_mul_f32_e32 v131, 0xbfb8aa3b, v119
	v_exp_f32_e32 v131, v131
	s_nop 0
	v_add_f32_e32 v131, 1.0, v131
	s_nop 0
	v_rcp_f32_e32 v137, v131
	s_nop 0
	v_fma_f32 v135, -v131, v137, 1.0
	v_fma_f32 v135, v135, v137, v137
	v_mul_f32_e32 v137, 0xbfb8aa3b, v115
	v_exp_f32_e32 v137, v137
	s_nop 0
	v_add_f32_e32 v137, 1.0, v137
	s_nop 0
	v_rcp_f32_e32 v139, v137
	s_nop 0
	v_fma_f32 v138, -v137, v139, 1.0
	v_fma_f32 v138, v138, v139, v139
	v_add_co_u32_e32 v140, vcc, 0x1000, v128
	v_mov_b32_dpp v139, v136 quad_perm:[1,0,3,2] row_mask:0xf bank_mask:0xf bound_ctrl:1
	s_nop 0
	v_addc_co_u32_e32 v141, vcc, 0, v129, vcc
	global_store_dword v[140:141], v133, off offset:2048
	s_and_saveexec_b64 s[2:3], s[6:7]
	s_xor_b64 s[2:3], exec, s[2:3]
	s_cbranch_execz .LBB0_1030
	v_cvt_pk_bf16_f32 v133, v139, v134

; DEVFI float sigmoidf_(float x) { return 1.f / (1.f + __expf(-x)); }
; DEVFI float dpp_xor1(float x) { return __int_as_float(__builtin_amdgcn_update_dpp(0, __float_as_int(x), 0xB1, 0xF, 0xF, true)); }
; #define RG ((bfraw*)(kargs()->ws + O_RG))
; DEVFI void store_nat_m(bfraw* base, long ld, f32x4 (&a)[8], int fr) {
;     ...
;     for (int n0 = 0; n0 < 8; n0 += 2) { const float own0 = a[n0][j], own1 = a[n0 + 1][j];
;       const float recv = dpp_xor1(odd ? own0 : own1);
;       const unsigned pk = odd ? cvtpk(recv, own1) : cvtpk(own0, recv);
;       *reinterpret_cast<unsigned*>(p0 + (long)j * ld + n0 * 16) = pk; }
; __global__ void __launch_bounds__(512) mega(Params p) {
;     ...
;                   } else if (c0 < 4096) {
; #pragma unroll
;                     for (int n = 0; n < 8; ++n)
; #pragma unroll
;                       for (int j = 0; j < 4; ++j) { const float x = a[n][j]; a[n][j] = x * sigmoidf_(x); }
;                     store_nat_m(RG + (long)r0 * 1024 + (c0 - 3072), 1024, a, fr);
.LBB0_1032:
	s_or_b64 exec, exec, s[2:3]
	v_mul_f32_e32 v130, 0xbfb8aa3b, v103
	v_exp_f32_e32 v130, v130
	v_mov_b32_dpp v136, v136 quad_perm:[1,0,3,2] row_mask:0xf bank_mask:0xf bound_ctrl:1
	v_add_f32_e32 v130, 1.0, v130
	s_nop 0
	v_rcp_f32_e32 v137, v130
	s_nop 0
	v_fma_f32 v135, -v130, v137, 1.0
	v_fma_f32 v135, v135, v137, v137
	v_mul_f32_e32 v137, 0xbfb8aa3b, v99
	v_exp_f32_e32 v137, v137
	s_nop 0
	v_add_f32_e32 v137, 1.0, v137
	s_nop 0
	v_rcp_f32_e32 v139, v137
	s_nop 0
	v_fma_f32 v138, -v137, v139, 1.0
	v_fma_f32 v138, v138, v139, v139
	v_add_co_u32_e32 v140, vcc, 0x1000, v128
	s_nop 1
	v_addc_co_u32_e32 v141, vcc, 0, v129, vcc
	global_store_dword v[140:141], v133, off offset:2112
	s_and_saveexec_b64 s[2:3], s[6:7]
	s_xor_b64 s[2:3], exec, s[2:3]
	s_cbranch_execz .LBB0_1034
	v_cvt_pk_bf16_f32 v133, v136, v134

; __global__ void __launch_bounds__(512) mega(Params p) {
;     ...
;                   if (c0 < 2048) {
;                     const bool isk = c0 >= 1024; const int cc = c0 & 1023, head = cc >> 7;
;                     const float2* ropet = ROPET;
; #pragma unroll
;                     for (int j = 0; j < 4; ++j) { const int pos = (r0 + j) & (seqlen - 1);
;                       const float4* tb = (const float4*)(ropet + pos * 64 + fr * 4);
;                       const float4 t01 = tb[0], t23 = tb[1];
;                       const float2 csv[4] = {make_float2(t01.x, t01.y), make_float2(t01.z, t01.w), make_float2(t23.x, t23.y), make_float2(t23.z, t23.w)};
; #pragma unroll
;                       for (int n = 0; n < 4; ++n) { const float2 cs = csv[n]; const float x1 = a[n][j], x2 = a[n + 4][j];
;                         float o1 = x1 * cs.x - x2 * cs.y, o2 = x1 * cs.y + x2 * cs.x;
;                         if (isk) { o1 *= 0.08838834764831845f; o2 *= 0.08838834764831845f; }
;                         a[n][j] = o1; a[n + 4][j] = o2; } }
;                     store_nat_m((isk ? RK : RQ) + (long)r0 * 1024 + cc, 1024, a, fr);
;                     if (isk) store_tr_m(RKT + ((long)((r0 >> 7) * 8 + head) * 128 + fr) * 128 + (r0 & 127), 128, a);
;                   } else if (c0 < 3072) {
;                     const int head = (c0 - 2048) >> 7;
;                     store_tr_m(RVT + ((long)((r0 >> 7) * 8 + head) * 128 + fr) * 128 + (r0 & 127), 128, a);
;                   } else if (c0 < 4096) {
; #pragma unroll
;                     for (int n = 0; n < 8; ++n)
; #pragma unroll
;                       for (int j = 0; j < 4; ++j) { const float x = a[n][j]; a[n][j] = x * sigmoidf_(x); }
;                     store_nat_m(RG + (long)r0 * 1024 + (c0 - 3072), 1024, a, fr);
;                   } else if (c0 < 6144) {
; #pragma unroll
;                     for (int n = 0; n < 8; ++n)
; #pragma unroll
;                       for (int j = 0; j < 4; ++j) a[n][j] = gelu_tanh(a[n][j]);
;                     if (c0 >= 5120) { float* stp = SVSTAT + (long)r0 * 16 + ((c0 - 5120) >> 7) * 2;
; #pragma unroll
;                       for (int j = 0; j < 4; ++j) { float s1 = 0, s2 = 0;
; #pragma unroll
;                         for (int n = 0; n < 8; ++n) { s1 += a[n][j]; s2 += a[n][j] * a[n][j]; }
;                         s1 = red16(s1); s2 = red16(s2);
.LBB0_1116:
	s_or_b64 exec, exec, s[36:37]
	v_add3_u32 v128, s76, v225, 16
	s_and_saveexec_b64 s[2:3], s[4:5]
	s_xor_b64 s[74:75], exec, s[2:3]
	s_cbranch_execz .LBB0_1476
	s_cmpk_gt_u32 s26, 0xbff
	s_mov_b64 s[2:3], -1
	s_cbranch_scc0 .LBB0_1474
	s_cmpk_gt_u32 s26, 0xfff
	s_cbranch_scc0 .LBB0_1407
	s_cmpk_gt_u32 s26, 0x17ff
	s_cbranch_scc0 .LBB0_1328
	s_cmpk_gt_u32 s26, 0x1cff
	s_cbranch_scc0 .LBB0_1190
	s_cmpk_lt_u32 s26, 0x1e00
	s_cbranch_scc1 .LBB0_1123
	s_waitcnt vmcnt(0)
	v_add_f32_e32 v96, v92, v224
	v_mul_f32_e32 v96, 0xbfb8aa3b, v96
	v_exp_f32_e32 v96, v96
	s_add_i32 s6, s26, 0xffffe200
	s_ashr_i32 s7, s76, 8
	s_mul_i32 s7, s7, 3
	v_add_f32_e32 v96, 1.0, v96
	s_ashr_i32 s8, s6, 10
	s_add_i32 s8, s8, s7
	s_lshl_b32 s7, s8, 2
	v_rcp_f32_e32 v98, v96
	s_nop 0
	v_fma_f32 v97, -v96, v98, 1.0
	v_fma_f32 v97, v97, v98, v98
	v_div_fixup_f32 v96, v97, v96, 1.0
	v_add_f32_e32 v97, v93, v224
	v_mul_f32_e32 v97, 0xbfb8aa3b, v97
	v_exp_f32_e32 v97, v97
	s_bfe_u32 s6, s6, 0x20008
	s_or_b32 s6, s7, s6
	s_ashr_i32 s7, s6, 31
	v_add_f32_e32 v97, 1.0, v97
	s_lshl_b64 s[6:7], s[6:7], 17
	v_rcp_f32_e32 v99, v97
	s_nop 0
	v_fma_f32 v98, -v97, v99, 1.0
	v_fma_f32 v98, v98, v99, v99
	v_div_fixup_f32 v97, v98, v97, 1.0
	v_add_f32_e32 v98, v94, v224
	v_mul_f32_e32 v98, 0xbfb8aa3b, v98
	v_exp_f32_e32 v98, v98
	s_nop 0
	v_add_f32_e32 v98, 1.0, v98
	s_nop 0
	v_rcp_f32_e32 v100, v98
	s_nop 0
	v_fma_f32 v99, -v98, v100, 1.0
	v_fma_f32 v99, v99, v100, v100
	v_div_fixup_f32 v98, v99, v98, 1.0
	v_add_f32_e32 v99, v95, v224
	v_mul_f32_e32 v99, 0xbfb8aa3b, v99
	v_exp_f32_e32 v99, v99
	s_nop 0
	v_add_f32_e32 v99, 1.0, v99
	s_nop 0
	v_rcp_f32_e32 v101, v99
	s_nop 0
	v_fma_f32 v100, -v99, v101, 1.0
	v_fma_f32 v100, v100, v101, v101
	v_div_fixup_f32 v99, v100, v99, 1.0
	v_add_f32_e32 v100, v88, v223
	v_mul_f32_e32 v100, 0xbfb8aa3b, v100
	v_exp_f32_e32 v100, v100
	s_nop 0
	v_add_f32_e32 v100, 1.0, v100
	s_nop 0
	v_rcp_f32_e32 v102, v100
	s_nop 0
	v_fma_f32 v101, -v100, v102, 1.0
	v_fma_f32 v101, v101, v102, v102
	v_div_fixup_f32 v100, v101, v100, 1.0
	v_add_f32_e32 v101, v89, v223
	v_mul_f32_e32 v101, 0xbfb8aa3b, v101
	v_exp_f32_e32 v101, v101
	s_nop 0
	v_add_f32_e32 v101, 1.0, v101
	s_nop 0
	v_rcp_f32_e32 v103, v101
	s_nop 0
	v_fma_f32 v102, -v101, v103, 1.0
	v_fma_f32 v102, v102, v103, v103
	v_div_fixup_f32 v101, v102, v101, 1.0
	v_add_f32_e32 v102, v90, v223
	v_mul_f32_e32 v102, 0xbfb8aa3b, v102
	v_exp_f32_e32 v102, v102
	s_nop 0
	v_add_f32_e32 v102, 1.0, v102
	s_nop 0
	v_rcp_f32_e32 v104, v102
	s_nop 0
	v_fma_f32 v103, -v102, v104, 1.0
	v_fma_f32 v103, v103, v104, v104
	v_div_fixup_f32 v102, v103, v102, 1.0
	v_add_f32_e32 v103, v91, v223
	v_mul_f32_e32 v103, 0xbfb8aa3b, v103
	v_exp_f32_e32 v103, v103
	s_nop 0
	v_add_f32_e32 v103, 1.0, v103
	s_nop 0
	v_rcp_f32_e32 v105, v103
	s_nop 0
	v_fma_f32 v104, -v103, v105, 1.0
	v_fma_f32 v104, v104, v105, v105
	v_div_fixup_f32 v103, v104, v103, 1.0
	v_add_f32_e32 v104, v76, v212
	v_mul_f32_e32 v104, 0xbfb8aa3b, v104
	v_exp_f32_e32 v104, v104
	s_nop 0
	v_add_f32_e32 v104, 1.0, v104
	s_nop 0
	v_rcp_f32_e32 v106, v104
	s_nop 0
	v_fma_f32 v105, -v104, v106, 1.0
	v_fma_f32 v105, v105, v106, v106
	v_div_fixup_f32 v104, v105, v104, 1.0
	v_add_f32_e32 v105, v77, v212
	v_mul_f32_e32 v105, 0xbfb8aa3b, v105
	v_exp_f32_e32 v105, v105
	s_nop 0
	v_add_f32_e32 v105, 1.0, v105
	s_nop 0
	v_rcp_f32_e32 v107, v105
	s_nop 0
	v_fma_f32 v106, -v105, v107, 1.0
	v_fma_f32 v106, v106, v107, v107
	v_div_fixup_f32 v105, v106, v105, 1.0
	v_add_f32_e32 v106, v78, v212
	v_mul_f32_e32 v106, 0xbfb8aa3b, v106
	v_exp_f32_e32 v106, v106
	s_nop 0
	v_add_f32_e32 v106, 1.0, v106
	s_nop 0
	v_rcp_f32_e32 v108, v106
	s_nop 0
	v_fma_f32 v107, -v106, v108, 1.0
	v_fma_f32 v107, v107, v108, v108
	v_div_fixup_f32 v106, v107, v106, 1.0
	v_add_f32_e32 v107, v79, v212
	v_mul_f32_e32 v107, 0xbfb8aa3b, v107
	v_exp_f32_e32 v107, v107
	s_nop 0
	v_add_f32_e32 v107, 1.0, v107
	s_nop 0
	v_rcp_f32_e32 v109, v107
	s_nop 0
	v_fma_f32 v108, -v107, v109, 1.0
	v_fma_f32 v108, v108, v109, v109
	v_div_fixup_f32 v107, v108, v107, 1.0
	v_add_f32_e32 v108, v72, v211
	v_mul_f32_e32 v108, 0xbfb8aa3b, v108
	v_exp_f32_e32 v108, v108
	s_nop 0
	v_add_f32_e32 v108, 1.0, v108
	s_nop 0
	v_rcp_f32_e32 v110, v108
	s_nop 0
	v_fma_f32 v109, -v108, v110, 1.0
	v_fma_f32 v109, v109, v110, v110
	v_div_fixup_f32 v108, v109, v108, 1.0
	v_add_f32_e32 v109, v73, v211
	v_mul_f32_e32 v109, 0xbfb8aa3b, v109
	v_exp_f32_e32 v109, v109
	s_nop 0
	v_add_f32_e32 v109, 1.0, v109
	s_nop 0
	v_rcp_f32_e32 v111, v109
	s_nop 0
	v_fma_f32 v110, -v109, v111, 1.0
	v_fma_f32 v110, v110, v111, v111
	v_div_fixup_f32 v109, v110, v109, 1.0
	v_add_f32_e32 v110, v74, v211
	v_mul_f32_e32 v110, 0xbfb8aa3b, v110
	v_exp_f32_e32 v110, v110
	s_nop 0
	v_add_f32_e32 v110, 1.0, v110
	s_nop 0
	v_rcp_f32_e32 v112, v110
	s_nop 0
	v_fma_f32 v111, -v110, v112, 1.0
	v_fma_f32 v111, v111, v112, v112
	v_div_fixup_f32 v110, v111, v110, 1.0
	v_add_f32_e32 v111, v75, v211
	v_mul_f32_e32 v111, 0xbfb8aa3b, v111
	v_exp_f32_e32 v111, v111
	s_nop 0
	v_add_f32_e32 v111, 1.0, v111
	s_nop 0
	v_rcp_f32_e32 v113, v111
	s_nop 0
	v_fma_f32 v112, -v111, v113, 1.0
	v_fma_f32 v112, v112, v113, v113
	v_div_fixup_f32 v111, v112, v111, 1.0
	v_add_f32_e32 v112, v84, v210
	v_mul_f32_e32 v112, 0xbfb8aa3b, v112
	v_exp_f32_e32 v112, v112
	s_nop 0
	v_add_f32_e32 v112, 1.0, v112
	s_nop 0
	v_rcp_f32_e32 v114, v112
	s_nop 0
	v_fma_f32 v113, -v112, v114, 1.0
	v_fma_f32 v113, v113, v114, v114
	v_div_fixup_f32 v112, v113, v112, 1.0
	v_add_f32_e32 v113, v85, v210
	v_mul_f32_e32 v113, 0xbfb8aa3b, v113
	v_exp_f32_e32 v113, v113
	s_nop 0
	v_add_f32_e32 v113, 1.0, v113
	s_nop 0
; DEVFI float sigmoidf_(float x) { return 1.f / (1.f + __expf(-x)); }
; #define GATES ((bfraw*)(kargs()->ws + O_GATES))
; __global__ void __launch_bounds__(512) mega(Params p) {
;     ...
;                   } else {
; #pragma unroll
;                     for (int n = 0; n < 8; ++n) { const float bb = hv[n];
; #pragma unroll
;                       for (int j = 0; j < 4; ++j) a[n][j] = sigmoidf_(a[n][j] + bb); }
;                     const int gt0 = bcol - 7680, tidn = ((wr0 >> 6) * 2 + (wc0 >> 7)) * 64 + fq * 16 + fr;
;                     bfraw* gt = GATES + ((long)(((brow >> 8) * 3 + (gt0 >> 10)) * 4 + ((gt0 >> 8) & 3))) * 65536 + (long)(m * 4 * 512 + tidn) * 8;
; #pragma unroll
;                     for (int q = 0; q < 4; ++q) { u32x4 w4 = {cvtpk(a[2 * q][0], a[2 * q][1]), cvtpk(a[2 * q][2], a[2 * q][3]), cvtpk(a[2 * q + 1][0], a[2 * q + 1][1]), cvtpk(a[2 * q + 1][2], a[2 * q + 1][3])};
;                       *(u32x4*)(gt + q * 512 * 8) = w4; }
	v_rcp_f32_e32 v115, v113
	s_nop 0
	v_fma_f32 v114, -v113, v115, 1.0
	v_fma_f32 v114, v114, v115, v115
	v_div_fixup_f32 v113, v114, v113, 1.0
	v_add_f32_e32 v114, v86, v210
	v_mul_f32_e32 v114, 0xbfb8aa3b, v114
	v_exp_f32_e32 v114, v114
	s_nop 0
	v_add_f32_e32 v114, 1.0, v114
	s_nop 0
	v_rcp_f32_e32 v116, v114
	s_nop 0
	v_fma_f32 v115, -v114, v116, 1.0
	v_fma_f32 v115, v115, v116, v116
	v_div_fixup_f32 v114, v115, v114, 1.0
	v_add_f32_e32 v115, v87, v210
	v_mul_f32_e32 v115, 0xbfb8aa3b, v115
	v_exp_f32_e32 v115, v115
	s_nop 0
	v_add_f32_e32 v115, 1.0, v115
	s_nop 0
	v_rcp_f32_e32 v117, v115
	s_nop 0
	v_fma_f32 v116, -v115, v117, 1.0
	v_fma_f32 v116, v116, v117, v117
	v_div_fixup_f32 v115, v116, v115, 1.0
	v_add_f32_e32 v116, v80, v209
	v_mul_f32_e32 v116, 0xbfb8aa3b, v116
	v_exp_f32_e32 v116, v116
	s_nop 0
	v_add_f32_e32 v116, 1.0, v116
	s_nop 0
	v_rcp_f32_e32 v118, v116
	s_nop 0
	v_fma_f32 v117, -v116, v118, 1.0
	v_fma_f32 v117, v117, v118, v118
	v_div_fixup_f32 v116, v117, v116, 1.0
	v_add_f32_e32 v117, v81, v209
	v_mul_f32_e32 v117, 0xbfb8aa3b, v117
	v_exp_f32_e32 v117, v117
	s_nop 0
	v_add_f32_e32 v117, 1.0, v117
	s_nop 0
	v_rcp_f32_e32 v119, v117
	s_nop 0
	v_fma_f32 v118, -v117, v119, 1.0
	v_fma_f32 v118, v118, v119, v119
	v_div_fixup_f32 v117, v118, v117, 1.0
	v_add_f32_e32 v118, v82, v209
	v_mul_f32_e32 v118, 0xbfb8aa3b, v118
	v_exp_f32_e32 v118, v118
	s_nop 0
	v_add_f32_e32 v118, 1.0, v118
	s_nop 0
	v_rcp_f32_e32 v120, v118
	s_nop 0
	v_fma_f32 v119, -v118, v120, 1.0
	v_fma_f32 v119, v119, v120, v120
	v_div_fixup_f32 v118, v119, v118, 1.0
	v_add_f32_e32 v119, v83, v209
	v_mul_f32_e32 v119, 0xbfb8aa3b, v119
	v_exp_f32_e32 v119, v119
	s_nop 0
	v_add_f32_e32 v119, 1.0, v119
	s_nop 0
	v_rcp_f32_e32 v121, v119
	s_nop 0
	v_fma_f32 v120, -v119, v121, 1.0
	v_fma_f32 v120, v120, v121, v121
	v_div_fixup_f32 v119, v120, v119, 1.0
	v_add_f32_e32 v120, v68, v208
	v_mul_f32_e32 v120, 0xbfb8aa3b, v120
	v_exp_f32_e32 v120, v120
	s_nop 0
	v_add_f32_e32 v120, 1.0, v120
	s_nop 0
	v_rcp_f32_e32 v122, v120
	s_nop 0
	v_fma_f32 v121, -v120, v122, 1.0
	v_fma_f32 v121, v121, v122, v122
	v_div_fixup_f32 v122, v121, v120, 1.0
	v_add_f32_e32 v120, v69, v208
	v_mul_f32_e32 v120, 0xbfb8aa3b, v120
	v_exp_f32_e32 v120, v120
	s_nop 0
	v_add_f32_e32 v120, 1.0, v120
	s_nop 0
	v_rcp_f32_e32 v123, v120
	s_nop 0
	v_fma_f32 v121, -v120, v123, 1.0
	v_fma_f32 v121, v121, v123, v123
	v_div_fixup_f32 v123, v121, v120, 1.0
	v_add_f32_e32 v120, v70, v208
	v_mul_f32_e32 v120, 0xbfb8aa3b, v120
	v_exp_f32_e32 v120, v120
	s_nop 0
	v_add_f32_e32 v120, 1.0, v120
	s_nop 0
	v_rcp_f32_e32 v124, v120
	s_nop 0
	v_fma_f32 v121, -v120, v124, 1.0
	v_fma_f32 v121, v121, v124, v124
	v_div_fixup_f32 v124, v121, v120, 1.0
	v_add_f32_e32 v120, v71, v208
	v_mul_f32_e32 v120, 0xbfb8aa3b, v120
	v_exp_f32_e32 v120, v120
	s_nop 0
	v_add_f32_e32 v120, 1.0, v120
	s_nop 0
	v_rcp_f32_e32 v125, v120
	s_nop 0
	v_fma_f32 v121, -v120, v125, 1.0
	v_fma_f32 v121, v121, v125, v125
	v_div_fixup_f32 v125, v121, v120, 1.0
	v_add_f32_e32 v120, v64, v207
	v_mul_f32_e32 v120, 0xbfb8aa3b, v120
	v_exp_f32_e32 v120, v120
	s_nop 0
	v_add_f32_e32 v120, 1.0, v120
	s_nop 0
	v_rcp_f32_e32 v126, v120
	s_nop 0
	v_fma_f32 v121, -v120, v126, 1.0
	v_fma_f32 v121, v121, v126, v126
	v_div_fixup_f32 v126, v121, v120, 1.0
	v_add_f32_e32 v120, v65, v207
	v_mul_f32_e32 v120, 0xbfb8aa3b, v120
	v_exp_f32_e32 v120, v120
	s_nop 0
	v_add_f32_e32 v120, 1.0, v120
	s_nop 0
	v_rcp_f32_e32 v127, v120
	s_nop 0
	v_fma_f32 v121, -v120, v127, 1.0
	v_fma_f32 v121, v121, v127, v127
	v_div_fixup_f32 v127, v121, v120, 1.0
	v_add_f32_e32 v120, v66, v207
	v_mul_f32_e32 v120, 0xbfb8aa3b, v120
	v_exp_f32_e32 v120, v120
	s_nop 0
	v_add_f32_e32 v120, 1.0, v120
	s_nop 0
	v_rcp_f32_e32 v129, v120
	s_nop 0
	v_fma_f32 v121, -v120, v129, 1.0
	v_fma_f32 v121, v121, v129, v129
	v_div_fixup_f32 v129, v121, v120, 1.0
	v_add_f32_e32 v120, v67, v207
	v_mul_f32_e32 v120, 0xbfb8aa3b, v120
	v_exp_f32_e32 v120, v120
	s_nop 0
	v_add_f32_e32 v120, 1.0, v120
	s_mov_b64 s[2:3], s[0:1]
	s_load_dwordx2 s[2:3], s[2:3], 0xe8
	v_rcp_f32_e32 v130, v120
	s_nop 0
	v_fma_f32 v121, -v120, v130, 1.0
	v_fma_f32 v121, v121, v130, v130
	v_div_fixup_f32 v130, v121, v120, 1.0
	v_and_b32_e32 v120, 0xffffff80, v205
	v_lshlrev_b32_e32 v121, 6, v206
	v_or3_b32 v120, v120, v204, v121
	s_waitcnt lgkmcnt(0)
	s_add_u32 s2, s2, s6
	v_add_u32_e32 v120, 0x800, v120
	s_addc_u32 s3, s3, s7
	v_ashrrev_i32_e32 v121, 31, v120
	v_lshl_add_u64 v[120:121], v[120:121], 4, s[2:3]
	v_cvt_pk_bf16_f32 v96, v96, v97
	v_cvt_pk_bf16_f32 v97, v98, v99
	v_cvt_pk_bf16_f32 v98, v100, v101
	v_add_co_u32_e32 v100, vcc, s67, v120
	v_cvt_pk_bf16_f32 v99, v102, v103
	s_mov_b64 s[2:3], 0
	s_nop 0
	v_addc_co_u32_e32 v101, vcc, 0, v121, vcc
	global_store_dwordx4 v[100:101], v[96:99], off
	v_add_co_u32_e32 v100, vcc, s46, v120
	s_nop 0
	v_cvt_pk_bf16_f32 v96, v104, v105
	v_cvt_pk_bf16_f32 v97, v106, v107
	v_cvt_pk_bf16_f32 v98, v108, v109
	v_cvt_pk_bf16_f32 v99, v110, v111
	s_nop 0
	v_addc_co_u32_e32 v101, vcc, 0, v121, vcc
	global_store_dwordx4 v[100:101], v[96:99], off
	v_add_co_u32_e32 v100, vcc, 0x22724000, v120
	s_nop 0
	v_cvt_pk_bf16_f32 v96, v112, v113
	v_cvt_pk_bf16_f32 v97, v114, v115
	v_cvt_pk_bf16_f32 v98, v116, v117
	v_cvt_pk_bf16_f32 v99, v118, v119
	s_nop 0
	v_addc_co_u32_e32 v101, vcc, 0, v121, vcc
	global_store_dwordx4 v[100:101], v[96:99], off
	v_add_co_u32_e32 v100, vcc, 0x22726000, v120
	s_nop 0
	v_cvt_pk_bf16_f32 v96, v122, v123
	v_cvt_pk_bf16_f32 v97, v124, v125
	v_cvt_pk_bf16_f32 v98, v126, v127
	v_cvt_pk_bf16_f32 v99, v129, v130
	s_nop 0
	v_addc_co_u32_e32 v101, vcc, 0, v121, vcc
	global_store_dwordx4 v[100:101], v[96:99], off

; #define ATTT ((float2*)(kargs()->ws + O_ATTT))
; __global__ void __launch_bounds__(512) mega(Params p) {
;     ...
;                   } else if (c0 < 7424) {
;                     const bool isk = c0 >= 7168; const float* nw = isk ? kn_w : qn_w; const float2* attt = ATTT;
; #pragma unroll
;                     for (int j = 0; j < 4; ++j) { const int pos = (r0 + j) & (seqlen - 1);
;                       float ss = 0;
; #pragma unroll
;                       for (int n = 0; n < 8; ++n) ss += a[n][j] * a[n][j];
;                       ss = red16(ss);
;                       const float rstd = 1.f / sqrtf(ss * (1.f / 128.f) + RMS_EPS);
; #pragma unroll
;                       for (int n = 0; n < 8; ++n) a[n][j] = a[n][j] * rstd * hv[n];
;                       const float4* tb = (const float4*)(attt + pos * 64 + fr * 4);
;                       const float4 t01 = tb[0], t23 = tb[1];
;                       const float2 csv[4] = {make_float2(t01.x, t01.y), make_float2(t01.z, t01.w), make_float2(t23.x, t23.y), make_float2(t23.z, t23.w)};
; #pragma unroll
;                       for (int hh = 0; hh < 2; ++hh)
; #pragma unroll
;                         for (int n = 0; n < 2; ++n) { const float2 cs = csv[hh * 2 + n];
;                           const float x1 = a[hh * 4 + n][j], x2 = a[hh * 4 + n + 2][j];
;                           a[hh * 4 + n][j] = x1 * cs.x - x2 * cs.y; a[hh * 4 + n + 2][j] = x1 * cs.y + x2 * cs.x; } }
.LBB0_1195:
	s_mov_b64 s[2:3], s[0:1]
	s_load_dwordx2 s[2:3], s[2:3], 0xe8
	v_mul_f32_e32 v96, v88, v88
	v_fmac_f32_e32 v96, v92, v92
	v_fmac_f32_e32 v96, v76, v76
	v_fmac_f32_e32 v96, v72, v72
	s_waitcnt lgkmcnt(0)
	s_add_u32 s36, s2, 0x3da0000
	s_mov_b32 s2, -1
	v_fmac_f32_e32 v96, v84, v84
	v_fmac_f32_e32 v96, v80, v80
	v_mbcnt_lo_u32_b32 v97, s2, 0
	v_mbcnt_hi_u32_b32 v97, s2, v97
	v_fmac_f32_e32 v96, v68, v68
	v_lshlrev_b32_e32 v97, 2, v97
	v_fmac_f32_e32 v96, v64, v64
	v_xor_b32_e32 v98, 4, v97
	ds_bpermute_b32 v98, v98, v96
	v_mov_b32_e32 v131, 0x358637bd
	s_addc_u32 s37, s3, 0
	v_mov_b32_e32 v161, v177
	s_waitcnt lgkmcnt(0)
	v_add_f32_e32 v96, v96, v98
	v_xor_b32_e32 v98, 8, v97
	ds_bpermute_b32 v98, v98, v96
	s_waitcnt lgkmcnt(0)
	v_add_f32_e32 v96, v96, v98
	v_xor_b32_e32 v98, 16, v97
	ds_bpermute_b32 v98, v98, v96
	v_xor_b32_e32 v97, 32, v97
	s_waitcnt lgkmcnt(0)
	v_add_f32_e32 v96, v96, v98
	ds_bpermute_b32 v97, v97, v96
	s_waitcnt lgkmcnt(0)
	v_add_f32_e32 v96, v96, v97
	v_fmamk_f32 v96, v96, 0x3c000000, v131
	v_cmp_gt_f32_e32 vcc, s30, v96
	v_mul_f32_e32 v97, 0x4f800000, v96
	s_nop 0
	v_cndmask_b32_e32 v96, v96, v97, vcc
	v_sqrt_f32_e32 v97, v96
	s_nop 0
	v_add_u32_e32 v98, -1, v97
	v_fma_f32 v99, -v98, v97, v96
	v_cmp_ge_f32_e64 s[6:7], 0, v99
	v_add_u32_e32 v99, 1, v97
	s_nop 0
	v_cndmask_b32_e64 v98, v97, v98, s[6:7]
	v_fma_f32 v97, -v99, v97, v96
	v_cmp_lt_f32_e64 s[6:7], 0, v97
	s_nop 1
	v_cndmask_b32_e64 v97, v98, v99, s[6:7]
	v_mul_f32_e32 v98, 0x37800000, v97
	v_cndmask_b32_e32 v97, v97, v98, vcc
	v_cmp_class_f32_e32 vcc, v96, v222
	s_nop 1
	v_cndmask_b32_e32 v96, v97, v96, vcc
	s_mov_b32 s2, -1
	v_rcp_f32_e32 v98, v96
	s_nop 0
	v_fma_f32 v97, -v96, v98, 1.0
	v_fma_f32 v97, v97, v98, v98
	v_div_fixup_f32 v96, v97, v96, 1.0
	v_mul_f32_e32 v97, v92, v96
	s_waitcnt vmcnt(0)
	v_mul_f32_e32 v105, v224, v97
	v_mul_f32_e32 v97, v88, v96
	v_mul_f32_e32 v108, v223, v97
	v_mul_f32_e32 v97, v76, v96
	v_mul_f32_e32 v104, v212, v97
	v_mul_f32_e32 v97, v72, v96
	v_mul_f32_e32 v109, v211, v97
	v_mul_f32_e32 v97, v84, v96
	v_mul_f32_e32 v110, v210, v97
	v_mul_f32_e32 v97, v80, v96
	v_mul_f32_e32 v111, v209, v97
	v_mul_f32_e32 v97, v68, v96
	v_mul_f32_e32 v96, v64, v96
	v_mul_f32_e32 v113, v207, v96
	v_and_b32_e32 v96, s14, v128
	v_mul_f32_e32 v112, v208, v97
	v_lshlrev_b32_e32 v96, 6, v96
	v_mov_b32_e32 v97, v177
	v_lshl_add_u64 v[96:97], v[96:97], 3, s[36:37]
	v_lshl_add_u64 v[100:101], v[96:97], 0, v[160:161]
	global_load_dwordx4 v[96:99], v[100:101], off offset:16
	s_nop 0
	global_load_dwordx4 v[100:103], v[100:101], off
	s_waitcnt vmcnt(0)
	v_mul_f32_e32 v106, v101, v104
	v_fma_f32 v106, v100, v105, -v106
	v_mul_f32_e32 v104, v100, v104
	v_mul_f32_e32 v100, v103, v109
	v_fma_f32 v107, v102, v108, -v100
	v_mul_f32_e32 v100, v97, v112
	v_fmac_f32_e32 v104, v101, v105
	v_mul_f32_e32 v105, v102, v109
	v_fma_f32 v102, v96, v110, -v100
	v_mul_f32_e32 v100, v96, v112
	v_mul_f32_e32 v96, v99, v113
	v_fmac_f32_e32 v105, v103, v108
	v_fma_f32 v103, v98, v111, -v96
	v_mul_f32_e32 v96, v89, v89
	v_fmac_f32_e32 v96, v93, v93
	v_fmac_f32_e32 v96, v77, v77
	v_fmac_f32_e32 v96, v73, v73
	v_mul_f32_e32 v101, v98, v113
	v_fmac_f32_e32 v96, v85, v85
	v_mbcnt_lo_u32_b32 v98, s2, 0
	v_fmac_f32_e32 v96, v81, v81
	v_mbcnt_hi_u32_b32 v98, s2, v98
	v_fmac_f32_e32 v96, v69, v69
	v_lshlrev_b32_e32 v98, 2, v98
	v_fmac_f32_e32 v101, v99, v111
	v_fmac_f32_e32 v96, v65, v65
	v_xor_b32_e32 v99, 4, v98
	ds_bpermute_b32 v99, v99, v96
	v_fmac_f32_e32 v100, v97, v110
	v_add_u32_e32 v97, 1, v128
	s_waitcnt lgkmcnt(0)
	v_add_f32_e32 v96, v96, v99
	v_xor_b32_e32 v99, 8, v98
	ds_bpermute_b32 v99, v99, v96
	s_waitcnt lgkmcnt(0)
	v_add_f32_e32 v96, v96, v99
	v_xor_b32_e32 v99, 16, v98
	ds_bpermute_b32 v99, v99, v96
	v_xor_b32_e32 v98, 32, v98
	s_waitcnt lgkmcnt(0)
	v_add_f32_e32 v96, v96, v99
	ds_bpermute_b32 v98, v98, v96
	s_waitcnt lgkmcnt(0)
	v_add_f32_e32 v96, v96, v98
	v_fmamk_f32 v96, v96, 0x3c000000, v131
	v_cmp_gt_f32_e32 vcc, s30, v96
	v_mul_f32_e32 v98, 0x4f800000, v96
	s_nop 0
	v_cndmask_b32_e32 v96, v96, v98, vcc
	v_sqrt_f32_e32 v98, v96
	s_nop 0
	v_add_u32_e32 v99, -1, v98
	v_fma_f32 v108, -v99, v98, v96
	v_cmp_ge_f32_e64 s[6:7], 0, v108
	v_add_u32_e32 v108, 1, v98
	s_nop 0
	v_cndmask_b32_e64 v99, v98, v99, s[6:7]
	v_fma_f32 v98, -v108, v98, v96
	v_cmp_lt_f32_e64 s[6:7], 0, v98
	s_nop 1
	v_cndmask_b32_e64 v98, v99, v108, s[6:7]
	v_mul_f32_e32 v99, 0x37800000, v98
	v_cndmask_b32_e32 v98, v98, v99, vcc
	v_cmp_class_f32_e32 vcc, v96, v222
	s_nop 1
	v_cndmask_b32_e32 v96, v98, v96, vcc
	s_mov_b32 s2, -1
	v_rcp_f32_e32 v99, v96
	s_nop 0
	v_fma_f32 v98, -v96, v99, 1.0
	v_fma_f32 v98, v98, v99, v99
	v_div_fixup_f32 v96, v98, v96, 1.0
	v_mul_f32_e32 v98, v93, v96
	v_mul_f32_e32 v113, v224, v98
	v_mul_f32_e32 v98, v89, v96
	v_mul_f32_e32 v116, v223, v98
	v_mul_f32_e32 v98, v77, v96
	v_mul_f32_e32 v112, v212, v98
	v_mul_f32_e32 v98, v73, v96
	v_mul_f32_e32 v117, v211, v98
	v_mul_f32_e32 v98, v85, v96
	v_mul_f32_e32 v118, v210, v98
	v_mul_f32_e32 v98, v81, v96
	v_mul_f32_e32 v119, v209, v98
	v_mul_f32_e32 v98, v69, v96
	v_mul_f32_e32 v96, v65, v96
	v_mul_f32_e32 v121, v207, v96
	v_and_b32_e32 v96, s14, v97
	v_lshlrev_b32_e32 v96, 6, v96
	v_mov_b32_e32 v97, v177
	v_lshl_add_u64 v[96:97], v[96:97], 3, s[36:37]
	v_lshl_add_u64 v[108:109], v[96:97], 0, v[160:161]
	v_mul_f32_e32 v120, v208, v98
	global_load_dwordx4 v[96:99], v[108:109], off offset:16
	s_nop 0
	global_load_dwordx4 v[108:111], v[108:109], off
	s_waitcnt vmcnt(0)
; #define ATTT ((float2*)(kargs()->ws + O_ATTT))
; #define AQ ((bfraw*)(kargs()->ws + O_AQ))
; #define AK ((bfraw*)(kargs()->ws + O_AK))
; __global__ void __launch_bounds__(512) mega(Params p) {
;     ...
;                     const bool isk = c0 >= 7168; const float* nw = isk ? kn_w : qn_w; const float2* attt = ATTT;
; #pragma unroll
;                     for (int j = 0; j < 4; ++j) { const int pos = (r0 + j) & (seqlen - 1);
;                       float ss = 0;
; #pragma unroll
;                       for (int n = 0; n < 8; ++n) ss += a[n][j] * a[n][j];
;                       ss = red16(ss);
;                       const float rstd = 1.f / sqrtf(ss * (1.f / 128.f) + RMS_EPS);
; #pragma unroll
;                       for (int n = 0; n < 8; ++n) a[n][j] = a[n][j] * rstd * hv[n];
;                       const float4* tb = (const float4*)(attt + pos * 64 + fr * 4);
;                       const float4 t01 = tb[0], t23 = tb[1];
;                       const float2 csv[4] = {make_float2(t01.x, t01.y), make_float2(t01.z, t01.w), make_float2(t23.x, t23.y), make_float2(t23.z, t23.w)};
; #pragma unroll
;                       for (int hh = 0; hh < 2; ++hh)
; #pragma unroll
;                         for (int n = 0; n < 2; ++n) { const float2 cs = csv[hh * 2 + n];
;                           const float x1 = a[hh * 4 + n][j], x2 = a[hh * 4 + n + 2][j];
;                           a[hh * 4 + n][j] = x1 * cs.x - x2 * cs.y; a[hh * 4 + n + 2][j] = x1 * cs.y + x2 * cs.x; } }
;                     if (isk) store_nat_m(AK + (long)r0 * 256 + (c0 - 7168), 256, a, fr);
;                     else store_nat_m(AQ + (long)r0 * 1024 + (c0 - 6144), 1024, a, fr);
	v_mul_f32_e32 v114, v109, v112
	v_fma_f32 v114, v108, v113, -v114
	v_mul_f32_e32 v112, v108, v112
	v_mul_f32_e32 v108, v111, v117
	v_fma_f32 v115, v110, v116, -v108
	v_mul_f32_e32 v108, v97, v120
	v_fmac_f32_e32 v112, v109, v113
	v_mul_f32_e32 v113, v110, v117
	v_fma_f32 v110, v96, v118, -v108
	v_mul_f32_e32 v108, v96, v120
	v_mul_f32_e32 v96, v99, v121
	v_fmac_f32_e32 v113, v111, v116
	v_fma_f32 v111, v98, v119, -v96
	v_mul_f32_e32 v96, v90, v90
	v_fmac_f32_e32 v96, v94, v94
	v_fmac_f32_e32 v96, v78, v78
	v_fmac_f32_e32 v96, v74, v74
	v_mul_f32_e32 v109, v98, v121
	v_fmac_f32_e32 v96, v86, v86
	v_mbcnt_lo_u32_b32 v98, s2, 0
	v_fmac_f32_e32 v96, v82, v82
	v_mbcnt_hi_u32_b32 v98, s2, v98
	v_fmac_f32_e32 v96, v70, v70
	v_lshlrev_b32_e32 v98, 2, v98
	v_fmac_f32_e32 v109, v99, v119
	v_fmac_f32_e32 v96, v66, v66
	v_xor_b32_e32 v99, 4, v98
	ds_bpermute_b32 v99, v99, v96
	v_fmac_f32_e32 v108, v97, v118
	v_add_u32_e32 v97, 2, v128
	s_waitcnt lgkmcnt(0)
	v_add_f32_e32 v96, v96, v99
	v_xor_b32_e32 v99, 8, v98
	ds_bpermute_b32 v99, v99, v96
	s_waitcnt lgkmcnt(0)
	v_add_f32_e32 v96, v96, v99
	v_xor_b32_e32 v99, 16, v98
	ds_bpermute_b32 v99, v99, v96
	v_xor_b32_e32 v98, 32, v98
	s_waitcnt lgkmcnt(0)
	v_add_f32_e32 v96, v96, v99
	ds_bpermute_b32 v98, v98, v96
	s_waitcnt lgkmcnt(0)
	v_add_f32_e32 v96, v96, v98
	v_fmamk_f32 v96, v96, 0x3c000000, v131
	v_cmp_gt_f32_e32 vcc, s30, v96
	v_mul_f32_e32 v98, 0x4f800000, v96
	s_nop 0
	v_cndmask_b32_e32 v96, v96, v98, vcc
	v_sqrt_f32_e32 v98, v96
	s_nop 0
	v_add_u32_e32 v99, -1, v98
	v_fma_f32 v116, -v99, v98, v96
	v_cmp_ge_f32_e64 s[6:7], 0, v116
	v_add_u32_e32 v116, 1, v98
	s_nop 0
	v_cndmask_b32_e64 v99, v98, v99, s[6:7]
	v_fma_f32 v98, -v116, v98, v96
	v_cmp_lt_f32_e64 s[6:7], 0, v98
	s_nop 1
	v_cndmask_b32_e64 v98, v99, v116, s[6:7]
	v_mul_f32_e32 v99, 0x37800000, v98
	v_cndmask_b32_e32 v98, v98, v99, vcc
	v_cmp_class_f32_e32 vcc, v96, v222
	s_nop 1
	v_cndmask_b32_e32 v96, v98, v96, vcc
	s_mov_b32 s2, -1
	v_rcp_f32_e32 v99, v96
	s_nop 0
	v_fma_f32 v98, -v96, v99, 1.0
	v_fma_f32 v98, v98, v99, v99
	v_div_fixup_f32 v96, v98, v96, 1.0
	v_mul_f32_e32 v98, v94, v96
	v_mul_f32_e32 v121, v224, v98
	v_mul_f32_e32 v98, v90, v96
	v_mul_f32_e32 v124, v223, v98
	v_mul_f32_e32 v98, v78, v96
	v_mul_f32_e32 v120, v212, v98
	v_mul_f32_e32 v98, v74, v96
	v_mul_f32_e32 v125, v211, v98
	v_mul_f32_e32 v98, v86, v96
	v_mul_f32_e32 v126, v210, v98
	v_mul_f32_e32 v98, v82, v96
	v_mul_f32_e32 v127, v209, v98
	v_mul_f32_e32 v98, v70, v96
	v_mul_f32_e32 v96, v66, v96
	v_mul_f32_e32 v130, v207, v96
	v_and_b32_e32 v96, s14, v97
	v_lshlrev_b32_e32 v96, 6, v96
	v_mov_b32_e32 v97, v177
	v_lshl_add_u64 v[96:97], v[96:97], 3, s[36:37]
	v_lshl_add_u64 v[116:117], v[96:97], 0, v[160:161]
	v_mul_f32_e32 v129, v208, v98
	global_load_dwordx4 v[96:99], v[116:117], off offset:16
	s_nop 0
	global_load_dwordx4 v[116:119], v[116:117], off
	s_waitcnt vmcnt(0)
	v_mul_f32_e32 v122, v117, v120
	v_fma_f32 v122, v116, v121, -v122
	v_mul_f32_e32 v120, v116, v120
	v_mul_f32_e32 v116, v119, v125
	v_fma_f32 v123, v118, v124, -v116
	v_mul_f32_e32 v116, v97, v129
	v_fmac_f32_e32 v120, v117, v121
	v_mul_f32_e32 v121, v118, v125
	v_fma_f32 v118, v96, v126, -v116
	v_mul_f32_e32 v116, v96, v129
	v_mul_f32_e32 v96, v99, v130
	v_fmac_f32_e32 v121, v119, v124
	v_fma_f32 v119, v98, v127, -v96
	v_mul_f32_e32 v96, v91, v91
	v_fmac_f32_e32 v96, v95, v95
	v_fmac_f32_e32 v96, v79, v79
	v_fmac_f32_e32 v96, v75, v75
	v_mul_f32_e32 v117, v98, v130
	v_fmac_f32_e32 v96, v87, v87
	v_mbcnt_lo_u32_b32 v98, s2, 0
	v_fmac_f32_e32 v96, v83, v83
	v_mbcnt_hi_u32_b32 v98, s2, v98
	v_fmac_f32_e32 v96, v71, v71
	v_lshlrev_b32_e32 v98, 2, v98
	v_fmac_f32_e32 v117, v99, v127
	v_fmac_f32_e32 v96, v67, v67
	v_xor_b32_e32 v99, 4, v98
	ds_bpermute_b32 v99, v99, v96
	v_fmac_f32_e32 v116, v97, v126
	v_add_u32_e32 v97, 3, v128
	s_waitcnt lgkmcnt(0)
	v_add_f32_e32 v96, v96, v99
	v_xor_b32_e32 v99, 8, v98
	ds_bpermute_b32 v99, v99, v96
	s_waitcnt lgkmcnt(0)
	v_add_f32_e32 v96, v96, v99
	v_xor_b32_e32 v99, 16, v98
	ds_bpermute_b32 v99, v99, v96
	v_xor_b32_e32 v98, 32, v98
	s_waitcnt lgkmcnt(0)
	v_add_f32_e32 v96, v96, v99
	ds_bpermute_b32 v98, v98, v96
	s_waitcnt lgkmcnt(0)
	v_add_f32_e32 v96, v96, v98
	v_fmamk_f32 v96, v96, 0x3c000000, v131
	v_cmp_gt_f32_e32 vcc, s30, v96
	v_mul_f32_e32 v98, 0x4f800000, v96
	s_nop 0
	v_cndmask_b32_e32 v96, v96, v98, vcc
	v_sqrt_f32_e32 v98, v96
	s_nop 0
	v_add_u32_e32 v99, -1, v98
	v_fma_f32 v124, -v99, v98, v96
	v_cmp_ge_f32_e64 s[6:7], 0, v124
	v_add_u32_e32 v124, 1, v98
	s_nop 0
	v_cndmask_b32_e64 v99, v98, v99, s[6:7]
	v_fma_f32 v98, -v124, v98, v96
	v_cmp_lt_f32_e64 s[6:7], 0, v98
	s_nop 1
	v_cndmask_b32_e64 v98, v99, v124, s[6:7]
	v_mul_f32_e32 v99, 0x37800000, v98
	v_cndmask_b32_e32 v98, v98, v99, vcc
	v_cmp_class_f32_e32 vcc, v96, v222
	s_nop 1
	v_cndmask_b32_e32 v96, v98, v96, vcc
	s_mov_b64 s[2:3], -1
	v_rcp_f32_e32 v99, v96
	s_nop 0
	v_fma_f32 v98, -v96, v99, 1.0
	v_fma_f32 v98, v98, v99, v99
	v_div_fixup_f32 v96, v98, v96, 1.0
	v_mul_f32_e32 v98, v95, v96
	v_mul_f32_e32 v126, v224, v98
	v_mul_f32_e32 v98, v91, v96
	v_mul_f32_e32 v129, v223, v98
	v_mul_f32_e32 v98, v79, v96
	v_mul_f32_e32 v127, v212, v98
	v_mul_f32_e32 v98, v75, v96
	v_mul_f32_e32 v130, v211, v98
	v_mul_f32_e32 v98, v87, v96
	v_mul_f32_e32 v136, v210, v98
	v_mul_f32_e32 v98, v83, v96
	v_mul_f32_e32 v137, v209, v98
	v_mul_f32_e32 v98, v71, v96
	v_mul_f32_e32 v96, v67, v96
	v_mul_f32_e32 v139, v207, v96
	v_and_b32_e32 v96, s14, v97
	v_lshlrev_b32_e32 v96, 6, v96
	v_mov_b32_e32 v97, v177
	v_lshl_add_u64 v[96:97], v[96:97], 3, s[36:37]
	v_lshl_add_u64 v[124:125], v[96:97], 0, v[160:161]
	v_mul_f32_e32 v138, v208, v98
	global_load_dwordx4 v[96:99], v[124:125], off offset:16
	global_load_dwordx4 v[132:135], v[124:125], off
	s_waitcnt vmcnt(0)
	v_mul_f32_e32 v124, v133, v127
	v_fma_f32 v131, v132, v126, -v124
	v_mul_f32_e32 v124, v135, v130
	v_mul_f32_e32 v127, v132, v127
	v_fma_f32 v132, v134, v129, -v124
	v_mul_f32_e32 v124, v97, v138
	v_fma_f32 v125, v96, v136, -v124
	v_mul_f32_e32 v124, v96, v138
	v_mul_f32_e32 v96, v99, v139
	v_fmac_f32_e32 v127, v133, v126
	v_fma_f32 v126, v98, v137, -v96
	v_and_b32_e32 v96, 1, v203
	v_mul_f32_e32 v130, v134, v130
	v_mul_f32_e32 v98, v98, v139
	v_cmp_eq_u32_e32 vcc, 0, v96
	v_cmp_eq_u32_e64 s[6:7], 1, v96
	v_add_u32_e32 v96, 15, v202
	v_fmac_f32_e32 v130, v135, v129
	v_fmac_f32_e32 v124, v97, v136
	v_fmac_f32_e32 v98, v99, v137
	v_ashrrev_i32_e32 v129, 31, v128
	v_cndmask_b32_e32 v99, v96, v202, vcc
	v_cndmask_b32_e32 v133, v106, v107, vcc
	s_and_b64 vcc, exec, s[8:9]
	s_cbranch_vccz .LBB0_1261
	s_mov_b64 s[2:3], s[0:1]
	s_load_dwordx2 s[2:3], s[2:3], 0xe8
	v_mov_b32_dpp v96, v133 quad_perm:[1,0,3,2] row_mask:0xf bank_mask:0xf bound_ctrl:1
	s_and_saveexec_b64 s[8:9], s[6:7]
	s_xor_b64 s[8:9], exec, s[8:9]
	s_cbranch_execz .LBB0_1198
	v_cvt_pk_bf16_f32 v134, v96, v107

; DEVFI float gelu_tanh(float x) {
;   float u = 0.7978845608028654f * (x + 0.044715f * x * x * x);
;   float t = __expf(2.f * u);
;   float th = 1.f - 2.f / (t + 1.f);
;   return 0.5f * x * (1.f + th);
; __global__ void __launch_bounds__(512) mega(Params p) {
;     ...
;                   } else if (c0 < 6144) {
; #pragma unroll
;                     for (int n = 0; n < 8; ++n)
; #pragma unroll
;                       for (int j = 0; j < 4; ++j) a[n][j] = gelu_tanh(a[n][j]);
.LBB0_1328:
	s_andn2_b64 vcc, exec, s[2:3]
	s_cbranch_vccnz .LBB0_1406
	v_mul_f32_e32 v97, 0x3d372713, v93
	v_mul_f32_e32 v97, v93, v97
	v_fma_f32 v97, v93, v97, v93
	v_mul_f32_e32 v97, 0x3f4c422a, v97
	v_add_f32_e32 v97, v97, v97
	v_mul_f32_e32 v97, 0x3fb8aa3b, v97
	v_exp_f32_e32 v98, v97
	v_mul_f32_e32 v97, 0x3d372713, v94
	v_mul_f32_e32 v97, v94, v97
	v_fma_f32 v97, v94, v97, v94
	v_mul_f32_e32 v97, 0x3f4c422a, v97
	v_add_f32_e32 v97, v97, v97
	v_mul_f32_e32 v97, 0x3fb8aa3b, v97
	v_mul_f32_e32 v96, 0x3d372713, v92
	v_exp_f32_e32 v100, v97
	v_mul_f32_e32 v97, 0x3d372713, v88
	v_mul_f32_e32 v96, v92, v96
	v_mul_f32_e32 v97, v88, v97
	v_fma_f32 v96, v92, v96, v92
	v_fma_f32 v97, v88, v97, v88
	v_mul_f32_e32 v96, 0x3f4c422a, v96
	v_mul_f32_e32 v97, 0x3f4c422a, v97
	v_add_f32_e32 v96, v96, v96
	v_add_f32_e32 v97, v97, v97
	v_mul_f32_e32 v96, 0x3fb8aa3b, v96
	v_mul_f32_e32 v97, 0x3fb8aa3b, v97
	v_exp_f32_e32 v96, v96
	v_exp_f32_e32 v97, v97
	v_mul_f32_e32 v99, 0x3d372713, v95
	v_mul_f32_e32 v99, v95, v99
	v_fma_f32 v99, v95, v99, v95
	v_pk_add_f32 v[96:97], v[96:97], 1.0 op_sel_hi:[1,0]
	v_mul_f32_e32 v99, 0x3f4c422a, v99
	v_add_f32_e32 v99, v99, v99
	v_mul_f32_e32 v99, 0x3fb8aa3b, v99
	v_exp_f32_e32 v102, v99
	v_rcp_f32_e32 v103, v97
	s_nop 0
	v_fma_f32 v99, -v97, v103, 1.0
	v_fma_f32 v103, v99, v103, v103
	v_add_f32_e32 v99, v103, v103
	v_div_fixup_f32 v97, v99, v97, 2.0
	s_cmpk_lt_u32 s26, 0x1400
	v_rcp_f32_e32 v105, v96
	s_nop 0
	v_fma_f32 v99, -v96, v105, 1.0
	v_fma_f32 v105, v99, v105, v105
	v_add_f32_e32 v99, v105, v105
	v_div_fixup_f32 v96, v99, v96, 2.0
	v_mul_f32_e32 v99, 0x3d372713, v89
	v_mul_f32_e32 v99, v89, v99
	v_fma_f32 v99, v89, v99, v89
	v_mul_f32_e32 v99, 0x3f4c422a, v99
	v_add_f32_e32 v99, v99, v99
	v_mul_f32_e32 v99, 0x3fb8aa3b, v99
	v_exp_f32_e32 v99, v99
	v_pk_add_f32 v[96:97], v[96:97], 1.0 op_sel_hi:[1,0] neg_lo:[1,0] neg_hi:[1,0]
	v_mov_b32_e32 v104, v92
	v_mov_b32_e32 v105, v88
	v_pk_add_f32 v[98:99], v[98:99], 1.0 op_sel_hi:[1,0]
	v_pk_mul_f32 v[104:105], v[104:105], 0.5 op_sel_hi:[1,0]
	v_pk_add_f32 v[96:97], v[96:97], 1.0 op_sel_hi:[1,0]
	s_mov_b64 s[8:9], -1
	v_pk_mul_f32 v[110:111], v[104:105], v[96:97]
	v_rcp_f32_e32 v103, v99
	s_nop 0
	v_fma_f32 v96, -v99, v103, 1.0
	v_fma_f32 v103, v96, v103, v103
	v_add_f32_e32 v96, v103, v103
	v_div_fixup_f32 v97, v96, v99, 2.0
	v_rcp_f32_e32 v104, v98
	s_nop 0
	v_fma_f32 v96, -v98, v104, 1.0
	v_fma_f32 v104, v96, v104, v104
	v_add_f32_e32 v96, v104, v104
	v_div_fixup_f32 v96, v96, v98, 2.0
	v_mul_f32_e32 v98, 0x3d372713, v90
	v_mul_f32_e32 v98, v90, v98
	v_fma_f32 v98, v90, v98, v90
	v_mul_f32_e32 v98, 0x3f4c422a, v98
	v_add_f32_e32 v98, v98, v98
	v_mul_f32_e32 v98, 0x3fb8aa3b, v98
	v_exp_f32_e32 v101, v98
	v_pk_add_f32 v[96:97], v[96:97], 1.0 op_sel_hi:[1,0] neg_lo:[1,0] neg_hi:[1,0]
	v_mov_b32_e32 v98, v93
	v_mov_b32_e32 v99, v89
	v_pk_add_f32 v[100:101], v[100:101], 1.0 op_sel_hi:[1,0]
	v_pk_mul_f32 v[98:99], v[98:99], 0.5 op_sel_hi:[1,0]
	v_pk_add_f32 v[96:97], v[96:97], 1.0 op_sel_hi:[1,0]
	s_nop 0
	v_pk_mul_f32 v[106:107], v[98:99], v[96:97]
	v_rcp_f32_e32 v104, v101
	s_nop 0
	v_fma_f32 v96, -v101, v104, 1.0
	v_fma_f32 v104, v96, v104, v104
	v_add_f32_e32 v96, v104, v104
	v_div_fixup_f32 v97, v96, v101, 2.0
	v_mul_f32_e32 v98, 0x3d372713, v91
	v_mul_f32_e32 v98, v91, v98
	v_fma_f32 v98, v91, v98, v91
	v_mul_f32_e32 v98, 0x3f4c422a, v98
	v_add_f32_e32 v98, v98, v98
	v_mul_f32_e32 v98, 0x3fb8aa3b, v98
	v_exp_f32_e32 v103, v98
	v_rcp_f32_e32 v99, v100
	s_nop 0
	v_fma_f32 v96, -v100, v99, 1.0
	v_fma_f32 v99, v96, v99, v99
	v_add_f32_e32 v96, v99, v99
	v_div_fixup_f32 v96, v96, v100, 2.0
	v_pk_add_f32 v[96:97], v[96:97], 1.0 op_sel_hi:[1,0] neg_lo:[1,0] neg_hi:[1,0]
	v_pk_add_f32 v[102:103], v[102:103], 1.0 op_sel_hi:[1,0]
	v_mov_b32_e32 v98, v94
	v_mov_b32_e32 v99, v90
	v_pk_mul_f32 v[98:99], v[98:99], 0.5 op_sel_hi:[1,0]
	v_pk_add_f32 v[96:97], v[96:97], 1.0 op_sel_hi:[1,0]
	s_nop 0
	v_pk_mul_f32 v[100:101], v[98:99], v[96:97]
	v_rcp_f32_e32 v105, v103
	s_nop 0
	v_fma_f32 v96, -v103, v105, 1.0
	v_fma_f32 v105, v96, v105, v105
	v_add_f32_e32 v96, v105, v105
	v_div_fixup_f32 v97, v96, v103, 2.0
	v_mul_f32_e32 v98, 0x3d372713, v76
	v_mul_f32_e32 v98, v76, v98
	v_fma_f32 v98, v76, v98, v76
	v_mul_f32_e32 v98, 0x3f4c422a, v98
	v_add_f32_e32 v98, v98, v98
	v_rcp_f32_e32 v99, v102
	s_nop 0
	v_fma_f32 v96, -v102, v99, 1.0
	v_fma_f32 v99, v96, v99, v99
	v_add_f32_e32 v96, v99, v99
	v_mul_f32_e32 v98, 0x3fb8aa3b, v98
	v_div_fixup_f32 v96, v96, v102, 2.0
	v_exp_f32_e32 v102, v98
	v_pk_add_f32 v[96:97], v[96:97], 1.0 op_sel_hi:[1,0] neg_lo:[1,0] neg_hi:[1,0]
	v_mov_b32_e32 v98, v95
	v_mov_b32_e32 v99, v91
	v_add_f32_e32 v102, 1.0, v102
	v_pk_mul_f32 v[98:99], v[98:99], 0.5 op_sel_hi:[1,0]
	v_pk_add_f32 v[96:97], v[96:97], 1.0 op_sel_hi:[1,0]
	s_nop 0
	v_pk_mul_f32 v[96:97], v[98:99], v[96:97]
	v_mul_f32_e32 v103, 0x3d372713, v77
	v_mul_f32_e32 v103, v77, v103
	v_fma_f32 v103, v77, v103, v77
	v_mul_f32_e32 v103, 0x3f4c422a, v103
	v_add_f32_e32 v103, v103, v103
	v_mul_f32_e32 v103, 0x3fb8aa3b, v103
	v_exp_f32_e32 v103, v103
	v_rcp_f32_e32 v104, v102
	s_nop 0
	v_fma_f32 v98, -v102, v104, 1.0
	v_fma_f32 v104, v98, v104, v104
	v_add_f32_e32 v98, v104, v104
	v_div_fixup_f32 v98, v98, v102, 2.0
	v_sub_f32_e32 v98, 1.0, v98
	v_add_f32_e32 v99, 1.0, v103
	v_mul_f32_e32 v104, 0.5, v76
	v_add_f32_e32 v98, 1.0, v98
	v_mul_f32_e32 v122, v104, v98
	v_mul_f32_e32 v102, 0x3d372713, v78
	v_mul_f32_e32 v102, v78, v102
	v_fma_f32 v102, v78, v102, v78
	v_mul_f32_e32 v102, 0x3f4c422a, v102
	v_add_f32_e32 v102, v102, v102
	v_mul_f32_e32 v102, 0x3fb8aa3b, v102
	v_exp_f32_e32 v102, v102
; DEVFI float gelu_tanh(float x) {
;   float u = 0.7978845608028654f * (x + 0.044715f * x * x * x);
;   float t = __expf(2.f * u);
;   float th = 1.f - 2.f / (t + 1.f);
;   return 0.5f * x * (1.f + th);
; __global__ void __launch_bounds__(512) mega(Params p) {
;     ...
;                   } else if (c0 < 6144) {
; #pragma unroll
;                     for (int n = 0; n < 8; ++n)
; #pragma unroll
;                       for (int j = 0; j < 4; ++j) a[n][j] = gelu_tanh(a[n][j]);
	v_rcp_f32_e32 v103, v99
	s_nop 0
	v_fma_f32 v98, -v99, v103, 1.0
	v_fma_f32 v103, v98, v103, v103
	v_add_f32_e32 v98, v103, v103
	v_div_fixup_f32 v98, v98, v99, 2.0
	v_sub_f32_e32 v98, 1.0, v98
	v_add_f32_e32 v99, 1.0, v102
	v_mul_f32_e32 v104, 0.5, v77
	v_add_f32_e32 v98, 1.0, v98
	v_mul_f32_e32 v114, v104, v98
	v_mul_f32_e32 v102, 0x3d372713, v79
	v_mul_f32_e32 v102, v79, v102
	v_fma_f32 v102, v79, v102, v79
	v_mul_f32_e32 v102, 0x3f4c422a, v102
	v_add_f32_e32 v102, v102, v102
	v_mul_f32_e32 v102, 0x3fb8aa3b, v102
	v_exp_f32_e32 v102, v102
	v_rcp_f32_e32 v103, v99
	s_nop 0
	v_fma_f32 v98, -v99, v103, 1.0
	v_fma_f32 v103, v98, v103, v103
	v_add_f32_e32 v98, v103, v103
	v_div_fixup_f32 v98, v98, v99, 2.0
	v_sub_f32_e32 v98, 1.0, v98
	v_add_f32_e32 v99, 1.0, v102
	v_mul_f32_e32 v104, 0.5, v78
	v_add_f32_e32 v98, 1.0, v98
	v_mul_f32_e32 v104, v104, v98
	v_mul_f32_e32 v102, 0x3d372713, v72
	v_mul_f32_e32 v102, v72, v102
	v_fma_f32 v102, v72, v102, v72
	v_mul_f32_e32 v102, 0x3f4c422a, v102
	v_add_f32_e32 v102, v102, v102
	v_mul_f32_e32 v102, 0x3fb8aa3b, v102
	v_exp_f32_e32 v102, v102
	v_rcp_f32_e32 v103, v99
	s_nop 0
	v_fma_f32 v98, -v99, v103, 1.0
	v_fma_f32 v103, v98, v103, v103
	v_add_f32_e32 v98, v103, v103
	v_div_fixup_f32 v98, v98, v99, 2.0
	v_sub_f32_e32 v98, 1.0, v98
	v_add_f32_e32 v99, 1.0, v102
	v_mul_f32_e32 v105, 0.5, v79
	v_add_f32_e32 v98, 1.0, v98
	v_mul_f32_e32 v98, v105, v98
	v_mul_f32_e32 v105, 0x3d372713, v73
	v_mul_f32_e32 v105, v73, v105
	v_fma_f32 v105, v73, v105, v73
	v_mul_f32_e32 v105, 0x3f4c422a, v105
	v_add_f32_e32 v105, v105, v105
	v_mul_f32_e32 v105, 0x3fb8aa3b, v105
	v_exp_f32_e32 v105, v105
	v_rcp_f32_e32 v103, v99
	s_nop 0
	v_fma_f32 v102, -v99, v103, 1.0
	v_fma_f32 v103, v102, v103, v103
	v_add_f32_e32 v102, v103, v103
	v_div_fixup_f32 v99, v102, v99, 2.0
	v_sub_f32_e32 v99, 1.0, v99
	v_add_f32_e32 v102, 1.0, v105
	v_mul_f32_e32 v108, 0.5, v72
	v_add_f32_e32 v99, 1.0, v99
	v_mul_f32_e32 v136, v108, v99
	v_mul_f32_e32 v103, 0x3d372713, v74
	v_mul_f32_e32 v103, v74, v103
	v_fma_f32 v103, v74, v103, v74
	v_mul_f32_e32 v103, 0x3f4c422a, v103
	v_add_f32_e32 v103, v103, v103
	v_mul_f32_e32 v103, 0x3fb8aa3b, v103
	v_exp_f32_e32 v103, v103
	v_rcp_f32_e32 v105, v102
	s_nop 0
	v_fma_f32 v99, -v102, v105, 1.0
	v_fma_f32 v105, v99, v105, v105
	v_add_f32_e32 v99, v105, v105
	v_div_fixup_f32 v99, v99, v102, 2.0
	v_sub_f32_e32 v99, 1.0, v99
	v_add_f32_e32 v102, 1.0, v103
	v_mul_f32_e32 v108, 0.5, v73
	v_add_f32_e32 v99, 1.0, v99
	v_mul_f32_e32 v124, v108, v99
	v_mul_f32_e32 v103, 0x3d372713, v75
	v_mul_f32_e32 v103, v75, v103
	v_fma_f32 v103, v75, v103, v75
	v_mul_f32_e32 v103, 0x3f4c422a, v103
	v_add_f32_e32 v103, v103, v103
	v_mul_f32_e32 v103, 0x3fb8aa3b, v103
	v_exp_f32_e32 v103, v103
	v_rcp_f32_e32 v105, v102
	s_nop 0
	v_fma_f32 v99, -v102, v105, 1.0
	v_fma_f32 v105, v99, v105, v105
	v_add_f32_e32 v99, v105, v105
	v_div_fixup_f32 v99, v99, v102, 2.0
	v_sub_f32_e32 v99, 1.0, v99
	v_add_f32_e32 v102, 1.0, v103
	v_mul_f32_e32 v108, 0.5, v74
	v_add_f32_e32 v99, 1.0, v99
	v_mul_f32_e32 v112, v108, v99
	v_mul_f32_e32 v103, 0x3d372713, v84
	v_mul_f32_e32 v103, v84, v103
	v_fma_f32 v103, v84, v103, v84
	v_mul_f32_e32 v103, 0x3f4c422a, v103
	v_add_f32_e32 v103, v103, v103
	v_mul_f32_e32 v103, 0x3fb8aa3b, v103
	v_exp_f32_e32 v103, v103
	v_rcp_f32_e32 v105, v102
	s_nop 0
	v_fma_f32 v99, -v102, v105, 1.0
	v_fma_f32 v105, v99, v105, v105
	v_add_f32_e32 v99, v105, v105
	v_div_fixup_f32 v99, v99, v102, 2.0
	v_sub_f32_e32 v99, 1.0, v99
	v_add_f32_e32 v103, 1.0, v103
	v_mul_f32_e32 v102, 0.5, v75
	v_add_f32_e32 v99, 1.0, v99
	v_mul_f32_e32 v102, v102, v99
	v_mul_f32_e32 v105, 0x3d372713, v85
	v_mul_f32_e32 v105, v85, v105
	v_fma_f32 v105, v85, v105, v85
	v_mul_f32_e32 v105, 0x3f4c422a, v105
	v_add_f32_e32 v105, v105, v105
	v_mul_f32_e32 v105, 0x3fb8aa3b, v105
	v_exp_f32_e32 v105, v105
	v_rcp_f32_e32 v108, v103
	s_nop 0
	v_fma_f32 v99, -v103, v108, 1.0
	v_fma_f32 v108, v99, v108, v108
	v_add_f32_e32 v99, v108, v108
	v_div_fixup_f32 v99, v99, v103, 2.0
	v_sub_f32_e32 v99, 1.0, v99
	v_add_f32_e32 v103, 1.0, v105
	v_mul_f32_e32 v109, 0.5, v84
	v_add_f32_e32 v99, 1.0, v99
	v_mul_f32_e32 v138, v109, v99
	v_mul_f32_e32 v105, 0x3d372713, v86
	v_mul_f32_e32 v105, v86, v105
	v_fma_f32 v105, v86, v105, v86
	v_mul_f32_e32 v105, 0x3f4c422a, v105
	v_add_f32_e32 v105, v105, v105
	v_mul_f32_e32 v105, 0x3fb8aa3b, v105
	v_exp_f32_e32 v105, v105
	v_rcp_f32_e32 v108, v103
	s_nop 0
	v_fma_f32 v99, -v103, v108, 1.0
	v_fma_f32 v108, v99, v108, v108
	v_add_f32_e32 v99, v108, v108
	v_div_fixup_f32 v99, v99, v103, 2.0
	v_sub_f32_e32 v99, 1.0, v99
	v_add_f32_e32 v103, 1.0, v105
	v_mul_f32_e32 v109, 0.5, v85
	v_add_f32_e32 v99, 1.0, v99
	v_mul_f32_e32 v130, v109, v99
	v_mul_f32_e32 v105, 0x3d372713, v87
	v_mul_f32_e32 v105, v87, v105
	v_fma_f32 v105, v87, v105, v87
	v_mul_f32_e32 v105, 0x3f4c422a, v105
	v_add_f32_e32 v105, v105, v105
	v_mul_f32_e32 v105, 0x3fb8aa3b, v105
	v_exp_f32_e32 v105, v105
	v_rcp_f32_e32 v108, v103
	s_nop 0
	v_fma_f32 v99, -v103, v108, 1.0
	v_fma_f32 v108, v99, v108, v108
	v_add_f32_e32 v99, v108, v108
	v_div_fixup_f32 v99, v99, v103, 2.0
	v_sub_f32_e32 v99, 1.0, v99
	v_add_f32_e32 v103, 1.0, v105
	v_mul_f32_e32 v109, 0.5, v86
	v_add_f32_e32 v99, 1.0, v99
	v_mul_f32_e32 v118, v109, v99
	v_mul_f32_e32 v105, 0x3d372713, v80
	v_mul_f32_e32 v105, v80, v105
	v_fma_f32 v105, v80, v105, v80
	v_mul_f32_e32 v105, 0x3f4c422a, v105
	v_add_f32_e32 v105, v105, v105
	v_mul_f32_e32 v105, 0x3fb8aa3b, v105
	v_exp_f32_e32 v105, v105
	v_rcp_f32_e32 v108, v103
	s_nop 0
	v_fma_f32 v99, -v103, v108, 1.0
	v_fma_f32 v108, v99, v108, v108
	v_add_f32_e32 v99, v108, v108
; #define SVSTAT ((float*)(kargs()->ws + O_SVSTAT))
; DEVFI float gelu_tanh(float x) {
;   float u = 0.7978845608028654f * (x + 0.044715f * x * x * x);
;   float t = __expf(2.f * u);
;   float th = 1.f - 2.f / (t + 1.f);
;   return 0.5f * x * (1.f + th);
; __global__ void __launch_bounds__(512) mega(Params p) {
;     ...
;                   } else if (c0 < 6144) {
; #pragma unroll
;                     for (int n = 0; n < 8; ++n)
; #pragma unroll
;                       for (int j = 0; j < 4; ++j) a[n][j] = gelu_tanh(a[n][j]);
;                     if (c0 >= 5120) { float* stp = SVSTAT + (long)r0 * 16 + ((c0 - 5120) >> 7) * 2;
	v_div_fixup_f32 v99, v99, v103, 2.0
	v_sub_f32_e32 v99, 1.0, v99
	v_add_f32_e32 v103, 1.0, v105
	v_mul_f32_e32 v108, 0.5, v87
	v_add_f32_e32 v99, 1.0, v99
	v_mul_f32_e32 v108, v108, v99
	v_mul_f32_e32 v105, 0x3d372713, v81
	v_mul_f32_e32 v105, v81, v105
	v_fma_f32 v105, v81, v105, v81
	v_mul_f32_e32 v105, 0x3f4c422a, v105
	v_add_f32_e32 v105, v105, v105
	v_mul_f32_e32 v105, 0x3fb8aa3b, v105
	v_exp_f32_e32 v105, v105
	v_rcp_f32_e32 v109, v103
	s_nop 0
	v_fma_f32 v99, -v103, v109, 1.0
	v_fma_f32 v109, v99, v109, v109
	v_add_f32_e32 v99, v109, v109
	v_div_fixup_f32 v99, v99, v103, 2.0
	v_sub_f32_e32 v99, 1.0, v99
	v_add_f32_e32 v103, 1.0, v105
	v_mul_f32_e32 v113, 0.5, v80
	v_add_f32_e32 v99, 1.0, v99
	v_mul_f32_e32 v146, v113, v99
	v_mul_f32_e32 v105, 0x3d372713, v82
	v_mul_f32_e32 v105, v82, v105
	v_fma_f32 v105, v82, v105, v82
	v_mul_f32_e32 v105, 0x3f4c422a, v105
	v_add_f32_e32 v105, v105, v105
	v_mul_f32_e32 v105, 0x3fb8aa3b, v105
	v_exp_f32_e32 v105, v105
	v_rcp_f32_e32 v109, v103
	s_nop 0
	v_fma_f32 v99, -v103, v109, 1.0
	v_fma_f32 v109, v99, v109, v109
	v_add_f32_e32 v99, v109, v109
	v_div_fixup_f32 v99, v99, v103, 2.0
	v_sub_f32_e32 v99, 1.0, v99
	v_add_f32_e32 v103, 1.0, v105
	v_mul_f32_e32 v113, 0.5, v81
	v_add_f32_e32 v99, 1.0, v99
	v_mul_f32_e32 v140, v113, v99
	v_mul_f32_e32 v105, 0x3d372713, v83
	v_mul_f32_e32 v105, v83, v105
	v_fma_f32 v105, v83, v105, v83
	v_mul_f32_e32 v105, 0x3f4c422a, v105
	v_add_f32_e32 v105, v105, v105
	v_mul_f32_e32 v105, 0x3fb8aa3b, v105
	v_exp_f32_e32 v105, v105
	v_rcp_f32_e32 v109, v103
	s_nop 0
	v_fma_f32 v99, -v103, v109, 1.0
	v_fma_f32 v109, v99, v109, v109
	v_add_f32_e32 v99, v109, v109
	v_div_fixup_f32 v99, v99, v103, 2.0
	v_sub_f32_e32 v99, 1.0, v99
	v_add_f32_e32 v103, 1.0, v105
	v_mul_f32_e32 v113, 0.5, v82
	v_add_f32_e32 v99, 1.0, v99
	v_mul_f32_e32 v126, v113, v99
	v_mul_f32_e32 v105, 0x3d372713, v68
	v_mul_f32_e32 v105, v68, v105
	v_fma_f32 v105, v68, v105, v68
	v_mul_f32_e32 v105, 0x3f4c422a, v105
	v_add_f32_e32 v105, v105, v105
	v_mul_f32_e32 v105, 0x3fb8aa3b, v105
	v_exp_f32_e32 v105, v105
	v_rcp_f32_e32 v109, v103
	s_nop 0
	v_fma_f32 v99, -v103, v109, 1.0
	v_fma_f32 v109, v99, v109, v109
	v_add_f32_e32 v99, v109, v109
	v_div_fixup_f32 v99, v99, v103, 2.0
	v_sub_f32_e32 v99, 1.0, v99
	v_add_f32_e32 v103, 1.0, v105
	v_mul_f32_e32 v113, 0.5, v83
	v_add_f32_e32 v99, 1.0, v99
	v_mul_f32_e32 v116, v113, v99
	v_mul_f32_e32 v105, 0x3d372713, v69
	v_mul_f32_e32 v105, v69, v105
	v_fma_f32 v105, v69, v105, v69
	v_mul_f32_e32 v105, 0x3f4c422a, v105
	v_add_f32_e32 v105, v105, v105
	v_mul_f32_e32 v105, 0x3fb8aa3b, v105
	v_exp_f32_e32 v105, v105
	v_rcp_f32_e32 v109, v103
	s_nop 0
	v_fma_f32 v99, -v103, v109, 1.0
	v_fma_f32 v109, v99, v109, v109
	v_add_f32_e32 v99, v109, v109
	v_div_fixup_f32 v99, v99, v103, 2.0
	v_sub_f32_e32 v99, 1.0, v99
	v_add_f32_e32 v103, 1.0, v105
	v_mul_f32_e32 v113, 0.5, v68
	v_add_f32_e32 v99, 1.0, v99
	v_mul_f32_e32 v148, v113, v99
	v_mul_f32_e32 v105, 0x3d372713, v70
	v_mul_f32_e32 v105, v70, v105
	v_fma_f32 v105, v70, v105, v70
	v_mul_f32_e32 v105, 0x3f4c422a, v105
	v_add_f32_e32 v105, v105, v105
	v_mul_f32_e32 v105, 0x3fb8aa3b, v105
	v_exp_f32_e32 v105, v105
	v_rcp_f32_e32 v109, v103
	s_nop 0
	v_fma_f32 v99, -v103, v109, 1.0
	v_fma_f32 v109, v99, v109, v109
	v_add_f32_e32 v99, v109, v109
	v_div_fixup_f32 v99, v99, v103, 2.0
	v_sub_f32_e32 v99, 1.0, v99
	v_add_f32_e32 v103, 1.0, v105
	v_mul_f32_e32 v113, 0.5, v69
	v_add_f32_e32 v99, 1.0, v99
	v_mul_f32_e32 v144, v113, v99
	v_mul_f32_e32 v105, 0x3d372713, v71
	v_mul_f32_e32 v105, v71, v105
	v_fma_f32 v105, v71, v105, v71
	v_mul_f32_e32 v105, 0x3f4c422a, v105
	v_add_f32_e32 v105, v105, v105
	v_mul_f32_e32 v105, 0x3fb8aa3b, v105
	v_exp_f32_e32 v105, v105
	v_rcp_f32_e32 v109, v103
	s_nop 0
	v_fma_f32 v99, -v103, v109, 1.0
	v_fma_f32 v109, v99, v109, v109
	v_add_f32_e32 v99, v109, v109
	v_div_fixup_f32 v99, v99, v103, 2.0
	v_sub_f32_e32 v99, 1.0, v99
	v_add_f32_e32 v103, 1.0, v105
	v_mul_f32_e32 v113, 0.5, v70
	v_add_f32_e32 v99, 1.0, v99
	v_mul_f32_e32 v134, v113, v99
	v_mul_f32_e32 v105, 0x3d372713, v64
	v_mul_f32_e32 v105, v64, v105
	v_fma_f32 v105, v64, v105, v64
	v_mul_f32_e32 v105, 0x3f4c422a, v105
	v_add_f32_e32 v105, v105, v105
	v_mul_f32_e32 v105, 0x3fb8aa3b, v105
	v_exp_f32_e32 v105, v105
	v_rcp_f32_e32 v109, v103
	s_nop 0
	v_fma_f32 v99, -v103, v109, 1.0
	v_fma_f32 v109, v99, v109, v109
	v_add_f32_e32 v99, v109, v109
	v_div_fixup_f32 v99, v99, v103, 2.0
	v_sub_f32_e32 v99, 1.0, v99
	v_add_f32_e32 v103, 1.0, v105
	v_mul_f32_e32 v113, 0.5, v71
	v_add_f32_e32 v99, 1.0, v99
	v_mul_f32_e32 v120, v113, v99
	v_mul_f32_e32 v105, 0x3d372713, v65
	v_mul_f32_e32 v105, v65, v105
	v_fma_f32 v105, v65, v105, v65
	v_mul_f32_e32 v105, 0x3f4c422a, v105
	v_add_f32_e32 v105, v105, v105
	v_mul_f32_e32 v105, 0x3fb8aa3b, v105
	v_exp_f32_e32 v105, v105
	v_rcp_f32_e32 v109, v103
	s_nop 0
	v_fma_f32 v99, -v103, v109, 1.0
	v_fma_f32 v109, v99, v109, v109
	v_add_f32_e32 v99, v109, v109
	v_div_fixup_f32 v99, v99, v103, 2.0
	v_sub_f32_e32 v99, 1.0, v99
	v_add_f32_e32 v103, 1.0, v105
	v_mul_f32_e32 v113, 0.5, v64
	v_add_f32_e32 v99, 1.0, v99
	v_mul_f32_e32 v152, v113, v99
	v_mul_f32_e32 v105, 0x3d372713, v66
	v_mul_f32_e32 v105, v66, v105
	v_fma_f32 v105, v66, v105, v66
	v_mul_f32_e32 v105, 0x3f4c422a, v105
	v_add_f32_e32 v105, v105, v105
	v_mul_f32_e32 v105, 0x3fb8aa3b, v105
	v_exp_f32_e32 v105, v105
	v_rcp_f32_e32 v109, v103
	s_nop 0
	v_fma_f32 v99, -v103, v109, 1.0
	v_fma_f32 v109, v99, v109, v109
	v_add_f32_e32 v99, v109, v109
	v_div_fixup_f32 v99, v99, v103, 2.0
	v_sub_f32_e32 v99, 1.0, v99
	v_add_f32_e32 v103, 1.0, v105
	v_mul_f32_e32 v113, 0.5, v65
	v_add_f32_e32 v99, 1.0, v99
	v_mul_f32_e32 v150, v113, v99
	v_mul_f32_e32 v105, 0x3d372713, v67
	v_mul_f32_e32 v105, v67, v105
	v_fma_f32 v105, v67, v105, v67
	v_mul_f32_e32 v105, 0x3f4c422a, v105
	v_add_f32_e32 v105, v105, v105
	v_mul_f32_e32 v105, 0x3fb8aa3b, v105
	v_exp_f32_e32 v105, v105
	v_rcp_f32_e32 v109, v103
	s_nop 0
	v_fma_f32 v99, -v103, v109, 1.0
	v_fma_f32 v109, v99, v109, v109
	v_add_f32_e32 v99, v109, v109
	v_div_fixup_f32 v99, v99, v103, 2.0
	v_sub_f32_e32 v99, 1.0, v99
	v_add_f32_e32 v103, 1.0, v105
	v_mul_f32_e32 v113, 0.5, v66
	v_add_f32_e32 v99, 1.0, v99
	v_mul_f32_e32 v142, v113, v99
	v_rcp_f32_e32 v109, v103
	s_nop 0
	v_fma_f32 v99, -v103, v109, 1.0
	v_fma_f32 v109, v99, v109, v109
	v_add_f32_e32 v99, v109, v109
	v_div_fixup_f32 v99, v99, v103, 2.0
	v_sub_f32_e32 v99, 1.0, v99
	v_mul_f32_e32 v103, 0.5, v67
	v_add_f32_e32 v99, 1.0, v99
	v_mul_f32_e32 v132, v103, v99
	s_cbranch_scc1 .LBB0_1339
; DEVFI int lane_opaque() { unsigned m = ~0u; asm volatile("" : "+s"(m)); return (int)__builtin_amdgcn_mbcnt_hi(m, __builtin_amdgcn_mbcnt_lo(m, 0u)); }
; DEVFI float shx(float v, int mask, int lane) { return __int_as_float(__builtin_amdgcn_ds_bpermute((lane ^ mask) << 2, __float_as_int(v))); }
; #define SVSTAT ((float*)(kargs()->ws + O_SVSTAT))
; DEVFI float red16(float v) {
;   const int ln = lane_opaque();
;   v += shx(v, 1, ln); v += shx(v, 2, ln); v += shx(v, 4, ln); v += shx(v, 8, ln); return v;
; }
; __global__ void __launch_bounds__(512) mega(Params p) {
;     ...
;                     if (c0 >= 5120) { float* stp = SVSTAT + (long)r0 * 16 + ((c0 - 5120) >> 7) * 2;
; #pragma unroll
;                       for (int j = 0; j < 4; ++j) { float s1 = 0, s2 = 0;
; #pragma unroll
;                         for (int n = 0; n < 8; ++n) { s1 += a[n][j]; s2 += a[n][j] * a[n][j]; }
;                         s1 = red16(s1); s2 = red16(s2);
;                         if (fr == 0) { stp[j * 16] = s1; stp[j * 16 + 1] = s2; } } }
	s_mov_b64 s[2:3], s[0:1]
	s_load_dwordx2 s[2:3], s[2:3], 0xe8
	v_ashrrev_i32_e32 v129, 31, v128
	v_lshlrev_b64 v[154:155], 6, v[128:129]
	v_add_u32_e32 v99, 0xffffec00, v176
	v_lshrrev_b32_e32 v156, 4, v99
	s_waitcnt lgkmcnt(0)
	v_lshl_add_u64 v[154:155], s[2:3], 0, v[154:155]
	v_mov_b32_e32 v157, v177
	v_lshl_add_u64 v[154:155], v[154:155], 0, v[156:157]
	v_mov_b32_e32 v156, v177
	v_mov_b32_e32 v157, v111
	v_pk_add_f32 v[156:157], v[110:111], v[156:157]
	v_pk_mul_f32 v[158:159], v[110:111], v[110:111]
	s_mov_b64 s[2:3], 0x3a720400
	v_mov_b32_e32 v157, v159
	v_pk_mov_b32 v[158:159], v[110:111], v[158:159] op_sel:[1,0]
	v_lshl_add_u64 v[154:155], v[154:155], 0, s[2:3]
	v_mul_f32_e32 v123, v122, v122
	s_mov_b32 s2, -1
	v_pk_add_f32 v[156:157], v[156:157], v[158:159]
	v_mul_f32_e32 v137, v136, v136
	v_pk_add_f32 v[156:157], v[156:157], v[122:123]
	v_mbcnt_lo_u32_b32 v99, s2, 0
	v_mul_f32_e32 v139, v138, v138
	v_mbcnt_hi_u32_b32 v99, s2, v99
	s_mov_b32 s2, -1
	v_pk_add_f32 v[156:157], v[156:157], v[136:137]
	v_mul_f32_e32 v147, v146, v146
	v_pk_add_f32 v[156:157], v[156:157], v[138:139]
	v_mbcnt_lo_u32_b32 v113, s2, 0
	v_mul_f32_e32 v149, v148, v148
	v_mbcnt_hi_u32_b32 v113, s2, v113
	v_pk_add_f32 v[156:157], v[156:157], v[146:147]
	v_mul_f32_e32 v153, v152, v152
	v_lshlrev_b32_e32 v99, 2, v99
	v_lshlrev_b32_e32 v113, 2, v113
	v_pk_add_f32 v[156:157], v[156:157], v[148:149]
	v_xor_b32_e32 v103, 4, v99
	v_xor_b32_e32 v115, 4, v113
	v_pk_add_f32 v[156:157], v[156:157], v[152:153]
	ds_bpermute_b32 v158, v103, v156
	ds_bpermute_b32 v159, v115, v157
	v_xor_b32_e32 v105, 8, v99
	v_xor_b32_e32 v117, 8, v113
	v_xor_b32_e32 v109, 16, v99
	v_xor_b32_e32 v119, 16, v113
	s_waitcnt lgkmcnt(0)
	v_pk_add_f32 v[156:157], v[156:157], v[158:159]
	ds_bpermute_b32 v158, v105, v156
	ds_bpermute_b32 v159, v117, v157
	v_xor_b32_e32 v99, 32, v99
	v_cmp_eq_u32_e32 vcc, 0, v202
	s_waitcnt lgkmcnt(0)
	v_pk_add_f32 v[156:157], v[156:157], v[158:159]
	ds_bpermute_b32 v158, v109, v156
	ds_bpermute_b32 v159, v119, v157
	s_waitcnt lgkmcnt(0)
	v_pk_add_f32 v[156:157], v[156:157], v[158:159]
	ds_bpermute_b32 v158, v99, v156
	v_xor_b32_e32 v99, 32, v113
	ds_bpermute_b32 v159, v99, v157
	s_and_saveexec_b64 s[2:3], vcc
	s_cbranch_execz .LBB0_1332
	s_waitcnt lgkmcnt(0)
	v_pk_add_f32 v[156:157], v[156:157], v[158:159]
	global_store_dwordx2 v[154:155], v[156:157], off

; DEVFI float sigmoidf_(float x) { return 1.f / (1.f + __expf(-x)); }
; DEVFI float dpp_xor1(float x) { return __int_as_float(__builtin_amdgcn_update_dpp(0, __float_as_int(x), 0xB1, 0xF, 0xF, true)); }
; #define RG ((bfraw*)(kargs()->ws + O_RG))
; DEVFI void store_nat_m(bfraw* base, long ld, f32x4 (&a)[8], int fr) {
;   const bool odd = fr & 1;
;   bfraw* p0 = base + (odd ? 15 + fr : fr);
; #pragma unroll
;   for (int j = 0; j < 4; ++j)
; #pragma unroll
;     for (int n0 = 0; n0 < 8; n0 += 2) { const float own0 = a[n0][j], own1 = a[n0 + 1][j];
;       const float recv = dpp_xor1(odd ? own0 : own1);
;       const unsigned pk = odd ? cvtpk(recv, own1) : cvtpk(own0, recv);
;       *reinterpret_cast<unsigned*>(p0 + (long)j * ld + n0 * 16) = pk; }
; __global__ void __launch_bounds__(512) mega(Params p) {
;     ...
;                   } else if (c0 < 4096) {
; #pragma unroll
;                     for (int n = 0; n < 8; ++n)
; #pragma unroll
;                       for (int j = 0; j < 4; ++j) { const float x = a[n][j]; a[n][j] = x * sigmoidf_(x); }
;                     store_nat_m(RG + (long)r0 * 1024 + (c0 - 3072), 1024, a, fr);
.LBB0_1407:
	s_andn2_b64 vcc, exec, s[2:3]
	s_cbranch_vccnz .LBB0_1473
	v_mul_f32_e32 v96, 0xbfb8aa3b, v92
	v_exp_f32_e32 v96, v96
	s_nop 0
	v_add_f32_e32 v96, 1.0, v96
	s_nop 0
	v_rcp_f32_e32 v98, v96
	s_nop 0
	v_fma_f32 v97, -v96, v98, 1.0
	v_fma_f32 v97, v97, v98, v98
	v_div_fixup_f32 v96, v97, v96, 1.0
	v_mul_f32_e32 v97, 0xbfb8aa3b, v88
	v_exp_f32_e32 v97, v97
	v_mul_f32_e32 v96, v92, v96
	v_add_f32_e32 v97, 1.0, v97
	s_nop 0
	v_rcp_f32_e32 v99, v97
	s_nop 0
	v_fma_f32 v98, -v97, v99, 1.0
	v_fma_f32 v98, v98, v99, v99
	v_div_fixup_f32 v97, v98, v97, 1.0
	v_mul_f32_e32 v98, 0xbfb8aa3b, v76
	v_exp_f32_e32 v98, v98
	v_mul_f32_e32 v97, v88, v97
	v_add_f32_e32 v98, 1.0, v98
	s_nop 0
	v_rcp_f32_e32 v100, v98
	s_nop 0
	v_fma_f32 v99, -v98, v100, 1.0
	v_fma_f32 v100, v99, v100, v100
	v_mul_f32_e32 v99, 0xbfb8aa3b, v72
	v_exp_f32_e32 v99, v99
	s_nop 0
	v_add_f32_e32 v101, 1.0, v99
	s_mov_b64 s[2:3], s[0:1]
	s_load_dwordx2 s[2:3], s[2:3], 0xe8
	v_rcp_f32_e32 v102, v101
	s_nop 0
	v_fma_f32 v99, -v101, v102, 1.0
	v_fma_f32 v102, v99, v102, v102
	v_and_b32_e32 v99, 1, v203
	v_cmp_eq_u32_e64 s[8:9], 0, v99
	v_cmp_eq_u32_e64 s[6:7], 1, v99
	s_nop 0
	v_cndmask_b32_e64 v99, v96, v97, s[8:9]
	s_nop 1
	v_mov_b32_dpp v103, v99 quad_perm:[1,0,3,2] row_mask:0xf bank_mask:0xf bound_ctrl:1
	s_and_saveexec_b64 s[36:37], s[6:7]
	s_xor_b64 s[36:37], exec, s[36:37]
	s_cbranch_execz .LBB0_1410
	v_cvt_pk_bf16_f32 v99, v103, v97

; DEVFI float sigmoidf_(float x) { return 1.f / (1.f + __expf(-x)); }
; DEVFI float dpp_xor1(float x) { return __int_as_float(__builtin_amdgcn_update_dpp(0, __float_as_int(x), 0xB1, 0xF, 0xF, true)); }
; #define RG ((bfraw*)(kargs()->ws + O_RG))
; DEVFI void store_nat_m(bfraw* base, long ld, f32x4 (&a)[8], int fr) {
;   const bool odd = fr & 1;
;   bfraw* p0 = base + (odd ? 15 + fr : fr);
; #pragma unroll
;   for (int j = 0; j < 4; ++j)
; #pragma unroll
;     for (int n0 = 0; n0 < 8; n0 += 2) { const float own0 = a[n0][j], own1 = a[n0 + 1][j];
;       const float recv = dpp_xor1(odd ? own0 : own1);
;       const unsigned pk = odd ? cvtpk(recv, own1) : cvtpk(own0, recv);
;       *reinterpret_cast<unsigned*>(p0 + (long)j * ld + n0 * 16) = pk; }
; __global__ void __launch_bounds__(512) mega(Params p) {
;     ...
;                   } else if (c0 < 4096) {
; #pragma unroll
;                     for (int n = 0; n < 8; ++n)
; #pragma unroll
;                       for (int j = 0; j < 4; ++j) { const float x = a[n][j]; a[n][j] = x * sigmoidf_(x); }
;                     store_nat_m(RG + (long)r0 * 1024 + (c0 - 3072), 1024, a, fr);
.LBB0_1412:
	s_or_b64 exec, exec, s[36:37]
	v_mul_f32_e32 v96, 0xbfb8aa3b, v84
	v_exp_f32_e32 v96, v96
	v_ashrrev_i32_e32 v129, 31, v128
	v_add_f32_e32 v102, 1.0, v96
	s_nop 0
	v_rcp_f32_e32 v97, v102
	s_nop 0
	v_fma_f32 v96, -v102, v97, 1.0
	v_fma_f32 v103, v96, v97, v97
	v_mul_f32_e32 v96, 0xbfb8aa3b, v80
	v_exp_f32_e32 v96, v96
	s_nop 0
	v_add_f32_e32 v104, 1.0, v96
	s_nop 0
	v_rcp_f32_e32 v97, v104
	s_nop 0
	v_fma_f32 v96, -v104, v97, 1.0
	v_fma_f32 v105, v96, v97, v97
	v_lshlrev_b64 v[96:97], 11, v[128:129]
	v_add_u32_e32 v106, 15, v202
	s_waitcnt lgkmcnt(0)
	v_lshl_add_u64 v[96:97], s[2:3], 0, v[96:97]
	v_cndmask_b32_e64 v106, v106, v202, s[8:9]
	v_lshl_add_u64 v[96:97], v[176:177], 1, v[96:97]
	v_lshlrev_b32_e32 v106, 1, v106
	v_mov_b32_e32 v107, v177
	v_lshl_add_u64 v[96:97], v[96:97], 0, v[106:107]
	v_add_co_u32_e32 v106, vcc, 0x1971e000, v96
	s_nop 1
	v_addc_co_u32_e32 v107, vcc, 0, v97, vcc
	global_store_dword v[106:107], v99, off offset:2048
	v_mov_b32_dpp v106, v101 quad_perm:[1,0,3,2] row_mask:0xf bank_mask:0xf bound_ctrl:1
	s_and_saveexec_b64 s[2:3], s[6:7]
	s_xor_b64 s[2:3], exec, s[2:3]
	s_cbranch_execz .LBB0_1414
	v_cvt_pk_bf16_f32 v101, v106, v100

; DEVFI float sigmoidf_(float x) { return 1.f / (1.f + __expf(-x)); }
; DEVFI float dpp_xor1(float x) { return __int_as_float(__builtin_amdgcn_update_dpp(0, __float_as_int(x), 0xB1, 0xF, 0xF, true)); }
; #define RG ((bfraw*)(kargs()->ws + O_RG))
; DEVFI void store_nat_m(bfraw* base, long ld, f32x4 (&a)[8], int fr) {
;   const bool odd = fr & 1;
;   bfraw* p0 = base + (odd ? 15 + fr : fr);
; #pragma unroll
;   for (int j = 0; j < 4; ++j)
; #pragma unroll
;     for (int n0 = 0; n0 < 8; n0 += 2) { const float own0 = a[n0][j], own1 = a[n0 + 1][j];
;       const float recv = dpp_xor1(odd ? own0 : own1);
;       const unsigned pk = odd ? cvtpk(recv, own1) : cvtpk(own0, recv);
;       *reinterpret_cast<unsigned*>(p0 + (long)j * ld + n0 * 16) = pk; }
; __global__ void __launch_bounds__(512) mega(Params p) {
;     ...
;                   } else if (c0 < 4096) {
; #pragma unroll
;                     for (int n = 0; n < 8; ++n)
; #pragma unroll
;                       for (int j = 0; j < 4; ++j) { const float x = a[n][j]; a[n][j] = x * sigmoidf_(x); }
;                     store_nat_m(RG + (long)r0 * 1024 + (c0 - 3072), 1024, a, fr);
.LBB0_1416:
	s_or_b64 exec, exec, s[2:3]
	v_mul_f32_e32 v98, 0xbfb8aa3b, v68
	v_exp_f32_e32 v98, v98
	s_mov_b64 s[2:3], 0x1971e800
	v_lshl_add_u64 v[96:97], v[96:97], 0, s[2:3]
	global_store_dword v[96:97], v101, off offset:64
	v_add_f32_e32 v98, 1.0, v98
	s_nop 0
	v_rcp_f32_e32 v104, v98
	s_nop 0
	v_fma_f32 v103, -v98, v104, 1.0
	v_fma_f32 v103, v103, v104, v104
	v_mul_f32_e32 v104, 0xbfb8aa3b, v64
	v_exp_f32_e32 v104, v104
	s_nop 0
	v_add_f32_e32 v104, 1.0, v104
	s_nop 0
	v_rcp_f32_e32 v106, v104
	s_nop 0
	v_fma_f32 v105, -v104, v106, 1.0
	v_fma_f32 v106, v105, v106, v106
	s_nop 0
	v_mov_b32_dpp v105, v102 quad_perm:[1,0,3,2] row_mask:0xf bank_mask:0xf bound_ctrl:1
	s_and_saveexec_b64 s[2:3], s[6:7]
	s_xor_b64 s[2:3], exec, s[2:3]
	s_cbranch_execz .LBB0_1418
	v_cvt_pk_bf16_f32 v101, v105, v100

; DEVFI float sigmoidf_(float x) { return 1.f / (1.f + __expf(-x)); }
; DEVFI float dpp_xor1(float x) { return __int_as_float(__builtin_amdgcn_update_dpp(0, __float_as_int(x), 0xB1, 0xF, 0xF, true)); }
; #define RG ((bfraw*)(kargs()->ws + O_RG))
; DEVFI void store_nat_m(bfraw* base, long ld, f32x4 (&a)[8], int fr) {
;   const bool odd = fr & 1;
;   bfraw* p0 = base + (odd ? 15 + fr : fr);
; #pragma unroll
;   for (int j = 0; j < 4; ++j)
; #pragma unroll
;     for (int n0 = 0; n0 < 8; n0 += 2) { const float own0 = a[n0][j], own1 = a[n0 + 1][j];
;       const float recv = dpp_xor1(odd ? own0 : own1);
;       const unsigned pk = odd ? cvtpk(recv, own1) : cvtpk(own0, recv);
;       *reinterpret_cast<unsigned*>(p0 + (long)j * ld + n0 * 16) = pk; }
; __global__ void __launch_bounds__(512) mega(Params p) {
;     ...
;                   } else if (c0 < 4096) {
; #pragma unroll
;                     for (int n = 0; n < 8; ++n)
; #pragma unroll
;                       for (int j = 0; j < 4; ++j) { const float x = a[n][j]; a[n][j] = x * sigmoidf_(x); }
;                     store_nat_m(RG + (long)r0 * 1024 + (c0 - 3072), 1024, a, fr);
.LBB0_1420:
	s_or_b64 exec, exec, s[2:3]
	v_mul_f32_e32 v99, 0xbfb8aa3b, v93
	v_exp_f32_e32 v99, v99
	global_store_dword v[96:97], v101, off offset:128
	v_add_f32_e32 v99, 1.0, v99
	s_nop 0
	v_rcp_f32_e32 v104, v99
	s_nop 0
	v_fma_f32 v103, -v99, v104, 1.0
	v_fma_f32 v103, v103, v104, v104
	v_mul_f32_e32 v104, 0xbfb8aa3b, v89
	v_exp_f32_e32 v104, v104
	s_nop 0
	v_add_f32_e32 v104, 1.0, v104
	s_nop 0
	v_rcp_f32_e32 v106, v104
	s_nop 0
	v_fma_f32 v105, -v104, v106, 1.0
	v_fma_f32 v106, v105, v106, v106
	s_nop 0
	v_mov_b32_dpp v105, v100 quad_perm:[1,0,3,2] row_mask:0xf bank_mask:0xf bound_ctrl:1
	s_and_saveexec_b64 s[2:3], s[6:7]
	s_xor_b64 s[2:3], exec, s[2:3]
	s_cbranch_execz .LBB0_1422
	v_cvt_pk_bf16_f32 v100, v105, v102

; DEVFI float sigmoidf_(float x) { return 1.f / (1.f + __expf(-x)); }
; DEVFI float dpp_xor1(float x) { return __int_as_float(__builtin_amdgcn_update_dpp(0, __float_as_int(x), 0xB1, 0xF, 0xF, true)); }
; #define RG ((bfraw*)(kargs()->ws + O_RG))
; DEVFI void store_nat_m(bfraw* base, long ld, f32x4 (&a)[8], int fr) {
;   const bool odd = fr & 1;
;   bfraw* p0 = base + (odd ? 15 + fr : fr);
; #pragma unroll
;   for (int j = 0; j < 4; ++j)
; #pragma unroll
;     for (int n0 = 0; n0 < 8; n0 += 2) { const float own0 = a[n0][j], own1 = a[n0 + 1][j];
;       const float recv = dpp_xor1(odd ? own0 : own1);
;       const unsigned pk = odd ? cvtpk(recv, own1) : cvtpk(own0, recv);
;       *reinterpret_cast<unsigned*>(p0 + (long)j * ld + n0 * 16) = pk; }
; __global__ void __launch_bounds__(512) mega(Params p) {
;     ...
;                   } else if (c0 < 4096) {
; #pragma unroll
;                     for (int n = 0; n < 8; ++n)
; #pragma unroll
;                       for (int j = 0; j < 4; ++j) { const float x = a[n][j]; a[n][j] = x * sigmoidf_(x); }
;                     store_nat_m(RG + (long)r0 * 1024 + (c0 - 3072), 1024, a, fr);
.LBB0_1424:
	s_or_b64 exec, exec, s[2:3]
	v_mul_f32_e32 v98, 0xbfb8aa3b, v77
	v_exp_f32_e32 v98, v98
	global_store_dword v[96:97], v100, off offset:192
	v_add_f32_e32 v98, 1.0, v98
	s_nop 0
	v_rcp_f32_e32 v104, v98
	s_nop 0
	v_fma_f32 v102, -v98, v104, 1.0
	v_fma_f32 v102, v102, v104, v104
	v_mul_f32_e32 v104, 0xbfb8aa3b, v73
	v_exp_f32_e32 v104, v104
	s_nop 0
	v_add_f32_e32 v104, 1.0, v104
	s_nop 0
	v_rcp_f32_e32 v106, v104
	s_nop 0
	v_fma_f32 v105, -v104, v106, 1.0
	v_fma_f32 v106, v105, v106, v106
	s_nop 0
	v_mov_b32_dpp v105, v103 quad_perm:[1,0,3,2] row_mask:0xf bank_mask:0xf bound_ctrl:1
	s_and_saveexec_b64 s[2:3], s[6:7]
	s_xor_b64 s[2:3], exec, s[2:3]
	s_cbranch_execz .LBB0_1426
	v_cvt_pk_bf16_f32 v100, v105, v101

; DEVFI float sigmoidf_(float x) { return 1.f / (1.f + __expf(-x)); }
; DEVFI float dpp_xor1(float x) { return __int_as_float(__builtin_amdgcn_update_dpp(0, __float_as_int(x), 0xB1, 0xF, 0xF, true)); }
; #define RG ((bfraw*)(kargs()->ws + O_RG))
; DEVFI void store_nat_m(bfraw* base, long ld, f32x4 (&a)[8], int fr) {
;   const bool odd = fr & 1;
;   bfraw* p0 = base + (odd ? 15 + fr : fr);
; #pragma unroll
;   for (int j = 0; j < 4; ++j)
; #pragma unroll
;     for (int n0 = 0; n0 < 8; n0 += 2) { const float own0 = a[n0][j], own1 = a[n0 + 1][j];
;       const float recv = dpp_xor1(odd ? own0 : own1);
;       const unsigned pk = odd ? cvtpk(recv, own1) : cvtpk(own0, recv);
;       *reinterpret_cast<unsigned*>(p0 + (long)j * ld + n0 * 16) = pk; }
; __global__ void __launch_bounds__(512) mega(Params p) {
;     ...
;                   } else if (c0 < 4096) {
; #pragma unroll
;                     for (int n = 0; n < 8; ++n)
; #pragma unroll
;                       for (int j = 0; j < 4; ++j) { const float x = a[n][j]; a[n][j] = x * sigmoidf_(x); }
;                     store_nat_m(RG + (long)r0 * 1024 + (c0 - 3072), 1024, a, fr);
.LBB0_1428:
	s_or_b64 exec, exec, s[2:3]
	v_mul_f32_e32 v99, 0xbfb8aa3b, v85
	v_exp_f32_e32 v99, v99
	global_store_dword v[96:97], v100, off offset:2048
	v_add_f32_e32 v99, 1.0, v99
	s_nop 0
	v_rcp_f32_e32 v104, v99
	s_nop 0
	v_fma_f32 v102, -v99, v104, 1.0
	v_fma_f32 v102, v102, v104, v104
	v_mul_f32_e32 v104, 0xbfb8aa3b, v81
	v_exp_f32_e32 v104, v104
	s_nop 0
	v_add_f32_e32 v104, 1.0, v104
	s_nop 0
	v_rcp_f32_e32 v106, v104
	s_nop 0
	v_fma_f32 v105, -v104, v106, 1.0
	v_fma_f32 v106, v105, v106, v106
	s_nop 0
	v_mov_b32_dpp v105, v103 quad_perm:[1,0,3,2] row_mask:0xf bank_mask:0xf bound_ctrl:1
	s_and_saveexec_b64 s[2:3], s[6:7]
	s_xor_b64 s[2:3], exec, s[2:3]
	s_cbranch_execz .LBB0_1430
	v_cvt_pk_bf16_f32 v100, v105, v101

; DEVFI float sigmoidf_(float x) { return 1.f / (1.f + __expf(-x)); }
; DEVFI float dpp_xor1(float x) { return __int_as_float(__builtin_amdgcn_update_dpp(0, __float_as_int(x), 0xB1, 0xF, 0xF, true)); }
; #define RG ((bfraw*)(kargs()->ws + O_RG))
; DEVFI void store_nat_m(bfraw* base, long ld, f32x4 (&a)[8], int fr) {
;   const bool odd = fr & 1;
;   bfraw* p0 = base + (odd ? 15 + fr : fr);
; #pragma unroll
;   for (int j = 0; j < 4; ++j)
; #pragma unroll
;     for (int n0 = 0; n0 < 8; n0 += 2) { const float own0 = a[n0][j], own1 = a[n0 + 1][j];
;       const float recv = dpp_xor1(odd ? own0 : own1);
;       const unsigned pk = odd ? cvtpk(recv, own1) : cvtpk(own0, recv);
;       *reinterpret_cast<unsigned*>(p0 + (long)j * ld + n0 * 16) = pk; }
; __global__ void __launch_bounds__(512) mega(Params p) {
;     ...
;                   } else if (c0 < 4096) {
; #pragma unroll
;                     for (int n = 0; n < 8; ++n)
; #pragma unroll
;                       for (int j = 0; j < 4; ++j) { const float x = a[n][j]; a[n][j] = x * sigmoidf_(x); }
;                     store_nat_m(RG + (long)r0 * 1024 + (c0 - 3072), 1024, a, fr);
.LBB0_1432:
	s_or_b64 exec, exec, s[2:3]
	v_mul_f32_e32 v98, 0xbfb8aa3b, v69
	v_exp_f32_e32 v98, v98
	global_store_dword v[96:97], v100, off offset:2112
	v_add_f32_e32 v98, 1.0, v98
	s_nop 0
	v_rcp_f32_e32 v104, v98
	s_nop 0
	v_fma_f32 v102, -v98, v104, 1.0
	v_fma_f32 v102, v102, v104, v104
	v_mul_f32_e32 v104, 0xbfb8aa3b, v65
	v_exp_f32_e32 v104, v104
	s_nop 0
	v_add_f32_e32 v104, 1.0, v104
	s_nop 0
	v_rcp_f32_e32 v106, v104
	s_nop 0
	v_fma_f32 v105, -v104, v106, 1.0
	v_fma_f32 v106, v105, v106, v106
	s_nop 0
	v_mov_b32_dpp v105, v103 quad_perm:[1,0,3,2] row_mask:0xf bank_mask:0xf bound_ctrl:1
	s_and_saveexec_b64 s[2:3], s[6:7]
	s_xor_b64 s[2:3], exec, s[2:3]
	s_cbranch_execz .LBB0_1434
	v_cvt_pk_bf16_f32 v100, v105, v101

; DEVFI float sigmoidf_(float x) { return 1.f / (1.f + __expf(-x)); }
; DEVFI float dpp_xor1(float x) { return __int_as_float(__builtin_amdgcn_update_dpp(0, __float_as_int(x), 0xB1, 0xF, 0xF, true)); }
; #define RG ((bfraw*)(kargs()->ws + O_RG))
; DEVFI void store_nat_m(bfraw* base, long ld, f32x4 (&a)[8], int fr) {
;   const bool odd = fr & 1;
;   bfraw* p0 = base + (odd ? 15 + fr : fr);
; #pragma unroll
;   for (int j = 0; j < 4; ++j)
; #pragma unroll
;     for (int n0 = 0; n0 < 8; n0 += 2) { const float own0 = a[n0][j], own1 = a[n0 + 1][j];
;       const float recv = dpp_xor1(odd ? own0 : own1);
;       const unsigned pk = odd ? cvtpk(recv, own1) : cvtpk(own0, recv);
;       *reinterpret_cast<unsigned*>(p0 + (long)j * ld + n0 * 16) = pk; }
; __global__ void __launch_bounds__(512) mega(Params p) {
;     ...
;                   } else if (c0 < 4096) {
; #pragma unroll
;                     for (int n = 0; n < 8; ++n)
; #pragma unroll
;                       for (int j = 0; j < 4; ++j) { const float x = a[n][j]; a[n][j] = x * sigmoidf_(x); }
;                     store_nat_m(RG + (long)r0 * 1024 + (c0 - 3072), 1024, a, fr);
.LBB0_1436:
	s_or_b64 exec, exec, s[2:3]
	v_mul_f32_e32 v99, 0xbfb8aa3b, v94
	v_exp_f32_e32 v99, v99
	global_store_dword v[96:97], v100, off offset:2176
	v_add_f32_e32 v99, 1.0, v99
	s_nop 0
	v_rcp_f32_e32 v104, v99
	s_nop 0
	v_fma_f32 v102, -v99, v104, 1.0
	v_fma_f32 v102, v102, v104, v104
	v_mul_f32_e32 v104, 0xbfb8aa3b, v90
	v_exp_f32_e32 v104, v104
	s_nop 0
	v_add_f32_e32 v104, 1.0, v104
	s_nop 0
	v_rcp_f32_e32 v106, v104
	s_nop 0
	v_fma_f32 v105, -v104, v106, 1.0
	v_fma_f32 v106, v105, v106, v106
	s_nop 0
	v_mov_b32_dpp v105, v103 quad_perm:[1,0,3,2] row_mask:0xf bank_mask:0xf bound_ctrl:1
	s_and_saveexec_b64 s[2:3], s[6:7]
	s_xor_b64 s[2:3], exec, s[2:3]
	s_cbranch_execz .LBB0_1438
	v_cvt_pk_bf16_f32 v100, v105, v101

; DEVFI float sigmoidf_(float x) { return 1.f / (1.f + __expf(-x)); }
; DEVFI float dpp_xor1(float x) { return __int_as_float(__builtin_amdgcn_update_dpp(0, __float_as_int(x), 0xB1, 0xF, 0xF, true)); }
; #define RG ((bfraw*)(kargs()->ws + O_RG))
; DEVFI void store_nat_m(bfraw* base, long ld, f32x4 (&a)[8], int fr) {
;   const bool odd = fr & 1;
;   bfraw* p0 = base + (odd ? 15 + fr : fr);
; #pragma unroll
;   for (int j = 0; j < 4; ++j)
; #pragma unroll
;     for (int n0 = 0; n0 < 8; n0 += 2) { const float own0 = a[n0][j], own1 = a[n0 + 1][j];
;       const float recv = dpp_xor1(odd ? own0 : own1);
;       const unsigned pk = odd ? cvtpk(recv, own1) : cvtpk(own0, recv);
;       *reinterpret_cast<unsigned*>(p0 + (long)j * ld + n0 * 16) = pk; }
; __global__ void __launch_bounds__(512) mega(Params p) {
;     ...
;                   } else if (c0 < 4096) {
; #pragma unroll
;                     for (int n = 0; n < 8; ++n)
; #pragma unroll
;                       for (int j = 0; j < 4; ++j) { const float x = a[n][j]; a[n][j] = x * sigmoidf_(x); }
;                     store_nat_m(RG + (long)r0 * 1024 + (c0 - 3072), 1024, a, fr);
.LBB0_1440:
	s_or_b64 exec, exec, s[2:3]
	v_mul_f32_e32 v98, 0xbfb8aa3b, v78
	v_exp_f32_e32 v98, v98
	global_store_dword v[96:97], v100, off offset:2240
	v_add_f32_e32 v98, 1.0, v98
	s_nop 0
	v_rcp_f32_e32 v104, v98
	s_nop 0
	v_fma_f32 v102, -v98, v104, 1.0
	v_fma_f32 v102, v102, v104, v104
	v_mul_f32_e32 v104, 0xbfb8aa3b, v74
	v_exp_f32_e32 v104, v104
	s_nop 0
	v_add_f32_e32 v104, 1.0, v104
	s_nop 0
	v_rcp_f32_e32 v106, v104
	s_nop 0
	v_fma_f32 v105, -v104, v106, 1.0
	v_fma_f32 v106, v105, v106, v106
	s_nop 0
	v_mov_b32_dpp v105, v103 quad_perm:[1,0,3,2] row_mask:0xf bank_mask:0xf bound_ctrl:1
	s_and_saveexec_b64 s[2:3], s[6:7]
	s_xor_b64 s[2:3], exec, s[2:3]
	s_cbranch_execz .LBB0_1442
	v_cvt_pk_bf16_f32 v100, v105, v101

; DEVFI float sigmoidf_(float x) { return 1.f / (1.f + __expf(-x)); }
; DEVFI float dpp_xor1(float x) { return __int_as_float(__builtin_amdgcn_update_dpp(0, __float_as_int(x), 0xB1, 0xF, 0xF, true)); }
; #define RG ((bfraw*)(kargs()->ws + O_RG))
; DEVFI void store_nat_m(bfraw* base, long ld, f32x4 (&a)[8], int fr) {
;   const bool odd = fr & 1;
;   bfraw* p0 = base + (odd ? 15 + fr : fr);
; #pragma unroll
;   for (int j = 0; j < 4; ++j)
; #pragma unroll
;     for (int n0 = 0; n0 < 8; n0 += 2) { const float own0 = a[n0][j], own1 = a[n0 + 1][j];
;       const float recv = dpp_xor1(odd ? own0 : own1);
;       const unsigned pk = odd ? cvtpk(recv, own1) : cvtpk(own0, recv);
;       *reinterpret_cast<unsigned*>(p0 + (long)j * ld + n0 * 16) = pk; }
; __global__ void __launch_bounds__(512) mega(Params p) {
;     ...
;                   } else if (c0 < 4096) {
; #pragma unroll
;                     for (int n = 0; n < 8; ++n)
; #pragma unroll
;                       for (int j = 0; j < 4; ++j) { const float x = a[n][j]; a[n][j] = x * sigmoidf_(x); }
;                     store_nat_m(RG + (long)r0 * 1024 + (c0 - 3072), 1024, a, fr);
.LBB0_1444:
	s_or_b64 exec, exec, s[2:3]
	v_mul_f32_e32 v99, 0xbfb8aa3b, v86
	v_exp_f32_e32 v99, v99
	s_nop 0
	v_add_f32_e32 v99, 1.0, v99
	s_nop 0
	v_rcp_f32_e32 v104, v99
	s_nop 0
	v_fma_f32 v102, -v99, v104, 1.0
	v_fma_f32 v102, v102, v104, v104
	v_mul_f32_e32 v104, 0xbfb8aa3b, v82
	v_exp_f32_e32 v104, v104
	s_nop 0
	v_add_f32_e32 v104, 1.0, v104
	s_nop 0
	v_rcp_f32_e32 v106, v104
	s_nop 0
	v_fma_f32 v105, -v104, v106, 1.0
	v_fma_f32 v105, v105, v106, v106
	v_add_co_u32_e32 v106, vcc, 0x1000, v96
	s_nop 1
	v_addc_co_u32_e32 v107, vcc, 0, v97, vcc
	global_store_dword v[106:107], v100, off
	v_mov_b32_dpp v106, v103 quad_perm:[1,0,3,2] row_mask:0xf bank_mask:0xf bound_ctrl:1
	s_and_saveexec_b64 s[2:3], s[6:7]
	s_xor_b64 s[2:3], exec, s[2:3]
	s_cbranch_execz .LBB0_1446
	v_cvt_pk_bf16_f32 v100, v106, v101

; DEVFI float sigmoidf_(float x) { return 1.f / (1.f + __expf(-x)); }
; DEVFI float dpp_xor1(float x) { return __int_as_float(__builtin_amdgcn_update_dpp(0, __float_as_int(x), 0xB1, 0xF, 0xF, true)); }
; #define RG ((bfraw*)(kargs()->ws + O_RG))
; DEVFI void store_nat_m(bfraw* base, long ld, f32x4 (&a)[8], int fr) {
;   const bool odd = fr & 1;
;   bfraw* p0 = base + (odd ? 15 + fr : fr);
; #pragma unroll
;   for (int j = 0; j < 4; ++j)
; #pragma unroll
;     for (int n0 = 0; n0 < 8; n0 += 2) { const float own0 = a[n0][j], own1 = a[n0 + 1][j];
;       const float recv = dpp_xor1(odd ? own0 : own1);
;       const unsigned pk = odd ? cvtpk(recv, own1) : cvtpk(own0, recv);
;       *reinterpret_cast<unsigned*>(p0 + (long)j * ld + n0 * 16) = pk; }
; __global__ void __launch_bounds__(512) mega(Params p) {
;     ...
;                   } else if (c0 < 4096) {
; #pragma unroll
;                     for (int n = 0; n < 8; ++n)
; #pragma unroll
;                       for (int j = 0; j < 4; ++j) { const float x = a[n][j]; a[n][j] = x * sigmoidf_(x); }
;                     store_nat_m(RG + (long)r0 * 1024 + (c0 - 3072), 1024, a, fr);
.LBB0_1448:
	s_or_b64 exec, exec, s[2:3]
	v_mul_f32_e32 v98, 0xbfb8aa3b, v70
	v_exp_f32_e32 v98, v98
	s_nop 0
	v_add_f32_e32 v98, 1.0, v98
	s_nop 0
	v_rcp_f32_e32 v104, v98
	s_nop 0
	v_fma_f32 v102, -v98, v104, 1.0
	v_fma_f32 v102, v102, v104, v104
	v_mul_f32_e32 v104, 0xbfb8aa3b, v66
	v_exp_f32_e32 v104, v104
	s_nop 0
	v_add_f32_e32 v104, 1.0, v104
	s_nop 0
	v_rcp_f32_e32 v106, v104
	s_nop 0
	v_fma_f32 v105, -v104, v106, 1.0
	v_fma_f32 v105, v105, v106, v106
	v_add_co_u32_e32 v106, vcc, 0x1000, v96
	s_nop 1
	v_addc_co_u32_e32 v107, vcc, 0, v97, vcc
	global_store_dword v[106:107], v100, off offset:64
	v_mov_b32_dpp v106, v103 quad_perm:[1,0,3,2] row_mask:0xf bank_mask:0xf bound_ctrl:1
	s_and_saveexec_b64 s[2:3], s[6:7]
	s_xor_b64 s[2:3], exec, s[2:3]
	s_cbranch_execz .LBB0_1450
	v_cvt_pk_bf16_f32 v100, v106, v101

; DEVFI float sigmoidf_(float x) { return 1.f / (1.f + __expf(-x)); }
; DEVFI float dpp_xor1(float x) { return __int_as_float(__builtin_amdgcn_update_dpp(0, __float_as_int(x), 0xB1, 0xF, 0xF, true)); }
; #define RG ((bfraw*)(kargs()->ws + O_RG))
; DEVFI void store_nat_m(bfraw* base, long ld, f32x4 (&a)[8], int fr) {
;   const bool odd = fr & 1;
;   bfraw* p0 = base + (odd ? 15 + fr : fr);
; #pragma unroll
;   for (int j = 0; j < 4; ++j)
; #pragma unroll
;     for (int n0 = 0; n0 < 8; n0 += 2) { const float own0 = a[n0][j], own1 = a[n0 + 1][j];
;       const float recv = dpp_xor1(odd ? own0 : own1);
;       const unsigned pk = odd ? cvtpk(recv, own1) : cvtpk(own0, recv);
;       *reinterpret_cast<unsigned*>(p0 + (long)j * ld + n0 * 16) = pk; }
; __global__ void __launch_bounds__(512) mega(Params p) {
;     ...
;                   } else if (c0 < 4096) {
; #pragma unroll
;                     for (int n = 0; n < 8; ++n)
; #pragma unroll
;                       for (int j = 0; j < 4; ++j) { const float x = a[n][j]; a[n][j] = x * sigmoidf_(x); }
;                     store_nat_m(RG + (long)r0 * 1024 + (c0 - 3072), 1024, a, fr);
.LBB0_1452:
	s_or_b64 exec, exec, s[2:3]
	v_mul_f32_e32 v99, 0xbfb8aa3b, v95
	v_exp_f32_e32 v99, v99
	s_nop 0
	v_add_f32_e32 v99, 1.0, v99
	s_nop 0
	v_rcp_f32_e32 v104, v99
	s_nop 0
	v_fma_f32 v102, -v99, v104, 1.0
	v_fma_f32 v102, v102, v104, v104
	v_mul_f32_e32 v104, 0xbfb8aa3b, v91
	v_exp_f32_e32 v104, v104
	s_nop 0
	v_add_f32_e32 v104, 1.0, v104
	s_nop 0
	v_rcp_f32_e32 v106, v104
	s_nop 0
	v_fma_f32 v105, -v104, v106, 1.0
	v_fma_f32 v105, v105, v106, v106
	v_add_co_u32_e32 v106, vcc, 0x1000, v96
	s_nop 1
	v_addc_co_u32_e32 v107, vcc, 0, v97, vcc
	global_store_dword v[106:107], v100, off offset:128
	v_mov_b32_dpp v106, v103 quad_perm:[1,0,3,2] row_mask:0xf bank_mask:0xf bound_ctrl:1
	s_and_saveexec_b64 s[2:3], s[6:7]
	s_xor_b64 s[2:3], exec, s[2:3]
	s_cbranch_execz .LBB0_1454
	v_cvt_pk_bf16_f32 v100, v106, v101

; DEVFI float sigmoidf_(float x) { return 1.f / (1.f + __expf(-x)); }
; DEVFI float dpp_xor1(float x) { return __int_as_float(__builtin_amdgcn_update_dpp(0, __float_as_int(x), 0xB1, 0xF, 0xF, true)); }
; #define RG ((bfraw*)(kargs()->ws + O_RG))
; DEVFI void store_nat_m(bfraw* base, long ld, f32x4 (&a)[8], int fr) {
;   const bool odd = fr & 1;
;   bfraw* p0 = base + (odd ? 15 + fr : fr);
; #pragma unroll
;   for (int j = 0; j < 4; ++j)
; #pragma unroll
;     for (int n0 = 0; n0 < 8; n0 += 2) { const float own0 = a[n0][j], own1 = a[n0 + 1][j];
;       const float recv = dpp_xor1(odd ? own0 : own1);
;       const unsigned pk = odd ? cvtpk(recv, own1) : cvtpk(own0, recv);
;       *reinterpret_cast<unsigned*>(p0 + (long)j * ld + n0 * 16) = pk; }
; __global__ void __launch_bounds__(512) mega(Params p) {
;     ...
;                   } else if (c0 < 4096) {
; #pragma unroll
;                     for (int n = 0; n < 8; ++n)
; #pragma unroll
;                       for (int j = 0; j < 4; ++j) { const float x = a[n][j]; a[n][j] = x * sigmoidf_(x); }
;                     store_nat_m(RG + (long)r0 * 1024 + (c0 - 3072), 1024, a, fr);
.LBB0_1456:
	s_or_b64 exec, exec, s[2:3]
	v_mul_f32_e32 v98, 0xbfb8aa3b, v79
	v_exp_f32_e32 v98, v98
	s_nop 0
	v_add_f32_e32 v98, 1.0, v98
	s_nop 0
	v_rcp_f32_e32 v104, v98
	s_nop 0
	v_fma_f32 v102, -v98, v104, 1.0
	v_fma_f32 v102, v102, v104, v104
	v_mul_f32_e32 v104, 0xbfb8aa3b, v75
	v_exp_f32_e32 v104, v104
	s_nop 0
	v_add_f32_e32 v104, 1.0, v104
	s_nop 0
	v_rcp_f32_e32 v106, v104
	s_nop 0
	v_fma_f32 v105, -v104, v106, 1.0
	v_fma_f32 v105, v105, v106, v106
	v_add_co_u32_e32 v106, vcc, 0x1000, v96
	s_nop 1
	v_addc_co_u32_e32 v107, vcc, 0, v97, vcc
	global_store_dword v[106:107], v100, off offset:192
	v_mov_b32_dpp v106, v103 quad_perm:[1,0,3,2] row_mask:0xf bank_mask:0xf bound_ctrl:1
	s_and_saveexec_b64 s[2:3], s[6:7]
	s_xor_b64 s[2:3], exec, s[2:3]
	s_cbranch_execz .LBB0_1458
	v_cvt_pk_bf16_f32 v100, v106, v101

; DEVFI float sigmoidf_(float x) { return 1.f / (1.f + __expf(-x)); }
; DEVFI float dpp_xor1(float x) { return __int_as_float(__builtin_amdgcn_update_dpp(0, __float_as_int(x), 0xB1, 0xF, 0xF, true)); }
; #define RG ((bfraw*)(kargs()->ws + O_RG))
; DEVFI void store_nat_m(bfraw* base, long ld, f32x4 (&a)[8], int fr) {
;   const bool odd = fr & 1;
;   bfraw* p0 = base + (odd ? 15 + fr : fr);
; #pragma unroll
;   for (int j = 0; j < 4; ++j)
; #pragma unroll
;     for (int n0 = 0; n0 < 8; n0 += 2) { const float own0 = a[n0][j], own1 = a[n0 + 1][j];
;       const float recv = dpp_xor1(odd ? own0 : own1);
;       const unsigned pk = odd ? cvtpk(recv, own1) : cvtpk(own0, recv);
;       *reinterpret_cast<unsigned*>(p0 + (long)j * ld + n0 * 16) = pk; }
; __global__ void __launch_bounds__(512) mega(Params p) {
;     ...
;                   } else if (c0 < 4096) {
; #pragma unroll
;                     for (int n = 0; n < 8; ++n)
; #pragma unroll
;                       for (int j = 0; j < 4; ++j) { const float x = a[n][j]; a[n][j] = x * sigmoidf_(x); }
;                     store_nat_m(RG + (long)r0 * 1024 + (c0 - 3072), 1024, a, fr);
.LBB0_1460:
	s_or_b64 exec, exec, s[2:3]
	v_mul_f32_e32 v99, 0xbfb8aa3b, v87
	v_exp_f32_e32 v99, v99
	s_nop 0
	v_add_f32_e32 v99, 1.0, v99
	s_nop 0
	v_rcp_f32_e32 v104, v99
	s_nop 0
	v_fma_f32 v102, -v99, v104, 1.0
	v_fma_f32 v102, v102, v104, v104
	v_mul_f32_e32 v104, 0xbfb8aa3b, v83
	v_exp_f32_e32 v104, v104
	s_nop 0
	v_add_f32_e32 v104, 1.0, v104
	s_nop 0
	v_rcp_f32_e32 v106, v104
	s_nop 0
	v_fma_f32 v105, -v104, v106, 1.0
	v_fma_f32 v105, v105, v106, v106
	v_add_co_u32_e32 v106, vcc, 0x1000, v96
	s_nop 1
	v_addc_co_u32_e32 v107, vcc, 0, v97, vcc
	global_store_dword v[106:107], v100, off offset:2048
	v_mov_b32_dpp v106, v103 quad_perm:[1,0,3,2] row_mask:0xf bank_mask:0xf bound_ctrl:1
	s_and_saveexec_b64 s[2:3], s[6:7]
	s_xor_b64 s[2:3], exec, s[2:3]
	s_cbranch_execz .LBB0_1462
	v_cvt_pk_bf16_f32 v100, v106, v101

; DEVFI float sigmoidf_(float x) { return 1.f / (1.f + __expf(-x)); }
; DEVFI float dpp_xor1(float x) { return __int_as_float(__builtin_amdgcn_update_dpp(0, __float_as_int(x), 0xB1, 0xF, 0xF, true)); }
; #define RG ((bfraw*)(kargs()->ws + O_RG))
; DEVFI void store_nat_m(bfraw* base, long ld, f32x4 (&a)[8], int fr) {
;   const bool odd = fr & 1;
;   bfraw* p0 = base + (odd ? 15 + fr : fr);
; #pragma unroll
;   for (int j = 0; j < 4; ++j)
; #pragma unroll
;     for (int n0 = 0; n0 < 8; n0 += 2) { const float own0 = a[n0][j], own1 = a[n0 + 1][j];
;       const float recv = dpp_xor1(odd ? own0 : own1);
;       const unsigned pk = odd ? cvtpk(recv, own1) : cvtpk(own0, recv);
;       *reinterpret_cast<unsigned*>(p0 + (long)j * ld + n0 * 16) = pk; }
; __global__ void __launch_bounds__(512) mega(Params p) {
;     ...
;                   } else if (c0 < 4096) {
; #pragma unroll
;                     for (int n = 0; n < 8; ++n)
; #pragma unroll
;                       for (int j = 0; j < 4; ++j) { const float x = a[n][j]; a[n][j] = x * sigmoidf_(x); }
;                     store_nat_m(RG + (long)r0 * 1024 + (c0 - 3072), 1024, a, fr);
.LBB0_1464:
	s_or_b64 exec, exec, s[2:3]
	v_mul_f32_e32 v98, 0xbfb8aa3b, v71
	v_exp_f32_e32 v98, v98
	v_mov_b32_dpp v103, v103 quad_perm:[1,0,3,2] row_mask:0xf bank_mask:0xf bound_ctrl:1
	v_add_f32_e32 v98, 1.0, v98
	s_nop 0
	v_rcp_f32_e32 v104, v98
	s_nop 0
	v_fma_f32 v102, -v98, v104, 1.0
	v_fma_f32 v102, v102, v104, v104
	v_mul_f32_e32 v104, 0xbfb8aa3b, v67
	v_exp_f32_e32 v104, v104
	s_nop 0
	v_add_f32_e32 v104, 1.0, v104
	s_nop 0
	v_rcp_f32_e32 v106, v104
	s_nop 0
	v_fma_f32 v105, -v104, v106, 1.0
	v_fma_f32 v105, v105, v106, v106
	v_add_co_u32_e32 v106, vcc, 0x1000, v96
	s_nop 1
	v_addc_co_u32_e32 v107, vcc, 0, v97, vcc
	global_store_dword v[106:107], v100, off offset:2112
	s_and_saveexec_b64 s[2:3], s[6:7]
	s_xor_b64 s[2:3], exec, s[2:3]
	s_cbranch_execz .LBB0_1466
	v_cvt_pk_bf16_f32 v100, v103, v101

; DEVFI float sigmoidf_(float x) { return 1.f / (1.f + __expf(-x)); }
; #define GATES ((bfraw*)(kargs()->ws + O_GATES))
; __global__ void __launch_bounds__(512) mega(Params p) {
;     ...
;                   } else {
; #pragma unroll
;                     for (int n = 0; n < 8; ++n) { const float bb = hv[n];
; #pragma unroll
;                       for (int j = 0; j < 4; ++j) a[n][j] = sigmoidf_(a[n][j] + bb); }
;                     const int gt0 = bcol - 7680, tidn = ((wr0 >> 6) * 2 + (wc0 >> 7)) * 64 + fq * 16 + fr;
;                     bfraw* gt = GATES + ((long)(((brow >> 8) * 3 + (gt0 >> 10)) * 4 + ((gt0 >> 8) & 3))) * 65536 + (long)(m * 4 * 512 + tidn) * 8;
; #pragma unroll
;                     for (int q = 0; q < 4; ++q) { u32x4 w4 = {cvtpk(a[2 * q][0], a[2 * q][1]), cvtpk(a[2 * q][2], a[2 * q][3]), cvtpk(a[2 * q + 1][0], a[2 * q + 1][1]), cvtpk(a[2 * q + 1][2], a[2 * q + 1][3])};
;                       *(u32x4*)(gt + q * 512 * 8) = w4; }
.LBB0_1548:
	s_or_b64 exec, exec, s[36:37]
	v_add3_u32 v96, s76, v225, 32
	s_and_saveexec_b64 s[2:3], s[4:5]
	s_xor_b64 s[74:75], exec, s[2:3]
	s_cbranch_execz .LBB0_1908
	s_cmpk_gt_u32 s26, 0xbff
	s_mov_b64 s[2:3], -1
	s_cbranch_scc0 .LBB0_1906
	s_cmpk_gt_u32 s26, 0xfff
	s_cbranch_scc0 .LBB0_1839
	s_cmpk_gt_u32 s26, 0x17ff
	s_cbranch_scc0 .LBB0_1760
	s_cmpk_gt_u32 s26, 0x1cff
	s_cbranch_scc0 .LBB0_1622
	s_cmpk_lt_u32 s26, 0x1e00
	s_cbranch_scc1 .LBB0_1555
	s_waitcnt vmcnt(0)
	v_add_f32_e32 v64, v60, v224
	v_mul_f32_e32 v64, 0xbfb8aa3b, v64
	v_exp_f32_e32 v64, v64
	s_add_i32 s6, s26, 0xffffe200
	s_ashr_i32 s7, s76, 8
	s_mul_i32 s7, s7, 3
	v_add_f32_e32 v64, 1.0, v64
	s_ashr_i32 s8, s6, 10
	s_add_i32 s8, s8, s7
	s_lshl_b32 s7, s8, 2
	v_rcp_f32_e32 v66, v64
	s_nop 0
	v_fma_f32 v65, -v64, v66, 1.0
	v_fma_f32 v65, v65, v66, v66
	v_div_fixup_f32 v64, v65, v64, 1.0
	v_add_f32_e32 v65, v61, v224
	v_mul_f32_e32 v65, 0xbfb8aa3b, v65
	v_exp_f32_e32 v65, v65
	s_bfe_u32 s6, s6, 0x20008
	s_or_b32 s6, s7, s6
	s_ashr_i32 s7, s6, 31
	v_add_f32_e32 v65, 1.0, v65
	s_lshl_b64 s[6:7], s[6:7], 17
	v_rcp_f32_e32 v67, v65
	s_nop 0
	v_fma_f32 v66, -v65, v67, 1.0
	v_fma_f32 v66, v66, v67, v67
	v_div_fixup_f32 v65, v66, v65, 1.0
	v_add_f32_e32 v66, v62, v224
	v_mul_f32_e32 v66, 0xbfb8aa3b, v66
	v_exp_f32_e32 v66, v66
	s_nop 0
	v_add_f32_e32 v66, 1.0, v66
	s_nop 0
	v_rcp_f32_e32 v68, v66
	s_nop 0
	v_fma_f32 v67, -v66, v68, 1.0
	v_fma_f32 v67, v67, v68, v68
	v_div_fixup_f32 v66, v67, v66, 1.0
	v_add_f32_e32 v67, v63, v224
	v_mul_f32_e32 v67, 0xbfb8aa3b, v67
	v_exp_f32_e32 v67, v67
	s_nop 0
	v_add_f32_e32 v67, 1.0, v67
	s_nop 0
	v_rcp_f32_e32 v69, v67
	s_nop 0
	v_fma_f32 v68, -v67, v69, 1.0
	v_fma_f32 v68, v68, v69, v69
	v_div_fixup_f32 v67, v68, v67, 1.0
	v_add_f32_e32 v68, v56, v223
	v_mul_f32_e32 v68, 0xbfb8aa3b, v68
	v_exp_f32_e32 v68, v68
	s_nop 0
	v_add_f32_e32 v68, 1.0, v68
	s_nop 0
	v_rcp_f32_e32 v70, v68
	s_nop 0
	v_fma_f32 v69, -v68, v70, 1.0
	v_fma_f32 v69, v69, v70, v70
	v_div_fixup_f32 v68, v69, v68, 1.0
	v_add_f32_e32 v69, v57, v223
	v_mul_f32_e32 v69, 0xbfb8aa3b, v69
	v_exp_f32_e32 v69, v69
	s_nop 0
	v_add_f32_e32 v69, 1.0, v69
	s_nop 0
	v_rcp_f32_e32 v71, v69
	s_nop 0
	v_fma_f32 v70, -v69, v71, 1.0
	v_fma_f32 v70, v70, v71, v71
	v_div_fixup_f32 v69, v70, v69, 1.0
	v_add_f32_e32 v70, v58, v223
	v_mul_f32_e32 v70, 0xbfb8aa3b, v70
	v_exp_f32_e32 v70, v70
	s_nop 0
	v_add_f32_e32 v70, 1.0, v70
	s_nop 0
	v_rcp_f32_e32 v72, v70
	s_nop 0
	v_fma_f32 v71, -v70, v72, 1.0
	v_fma_f32 v71, v71, v72, v72
	v_div_fixup_f32 v70, v71, v70, 1.0
	v_add_f32_e32 v71, v59, v223
	v_mul_f32_e32 v71, 0xbfb8aa3b, v71
	v_exp_f32_e32 v71, v71
	s_nop 0
	v_add_f32_e32 v71, 1.0, v71
	s_nop 0
	v_rcp_f32_e32 v73, v71
	s_nop 0
	v_fma_f32 v72, -v71, v73, 1.0
	v_fma_f32 v72, v72, v73, v73
	v_div_fixup_f32 v71, v72, v71, 1.0
	v_add_f32_e32 v72, v44, v212
	v_mul_f32_e32 v72, 0xbfb8aa3b, v72
	v_exp_f32_e32 v72, v72
	s_nop 0
	v_add_f32_e32 v72, 1.0, v72
	s_nop 0
	v_rcp_f32_e32 v74, v72
	s_nop 0
	v_fma_f32 v73, -v72, v74, 1.0
	v_fma_f32 v73, v73, v74, v74
	v_div_fixup_f32 v72, v73, v72, 1.0
	v_add_f32_e32 v73, v45, v212
	v_mul_f32_e32 v73, 0xbfb8aa3b, v73
	v_exp_f32_e32 v73, v73
	s_nop 0
	v_add_f32_e32 v73, 1.0, v73
	s_nop 0
	v_rcp_f32_e32 v75, v73
	s_nop 0
	v_fma_f32 v74, -v73, v75, 1.0
	v_fma_f32 v74, v74, v75, v75
	v_div_fixup_f32 v73, v74, v73, 1.0
	v_add_f32_e32 v74, v46, v212
	v_mul_f32_e32 v74, 0xbfb8aa3b, v74
	v_exp_f32_e32 v74, v74
	s_nop 0
	v_add_f32_e32 v74, 1.0, v74
	s_nop 0
	v_rcp_f32_e32 v76, v74
	s_nop 0
	v_fma_f32 v75, -v74, v76, 1.0
	v_fma_f32 v75, v75, v76, v76
	v_div_fixup_f32 v74, v75, v74, 1.0
	v_add_f32_e32 v75, v47, v212
	v_mul_f32_e32 v75, 0xbfb8aa3b, v75
	v_exp_f32_e32 v75, v75
	s_nop 0
	v_add_f32_e32 v75, 1.0, v75
	s_nop 0
	v_rcp_f32_e32 v77, v75
	s_nop 0
	v_fma_f32 v76, -v75, v77, 1.0
	v_fma_f32 v76, v76, v77, v77
	v_div_fixup_f32 v75, v76, v75, 1.0
	v_add_f32_e32 v76, v40, v211
	v_mul_f32_e32 v76, 0xbfb8aa3b, v76
	v_exp_f32_e32 v76, v76
	s_nop 0
	v_add_f32_e32 v76, 1.0, v76
	s_nop 0
	v_rcp_f32_e32 v78, v76
	s_nop 0
	v_fma_f32 v77, -v76, v78, 1.0
	v_fma_f32 v77, v77, v78, v78
	v_div_fixup_f32 v76, v77, v76, 1.0
	v_add_f32_e32 v77, v41, v211
	v_mul_f32_e32 v77, 0xbfb8aa3b, v77
	v_exp_f32_e32 v77, v77
	s_nop 0
	v_add_f32_e32 v77, 1.0, v77
	s_nop 0
	v_rcp_f32_e32 v79, v77
	s_nop 0
	v_fma_f32 v78, -v77, v79, 1.0
	v_fma_f32 v78, v78, v79, v79
	v_div_fixup_f32 v77, v78, v77, 1.0
	v_add_f32_e32 v78, v42, v211
	v_mul_f32_e32 v78, 0xbfb8aa3b, v78
	v_exp_f32_e32 v78, v78
	s_nop 0
	v_add_f32_e32 v78, 1.0, v78
	s_nop 0
	v_rcp_f32_e32 v80, v78
	s_nop 0
	v_fma_f32 v79, -v78, v80, 1.0
	v_fma_f32 v79, v79, v80, v80
	v_div_fixup_f32 v78, v79, v78, 1.0
	v_add_f32_e32 v79, v43, v211
	v_mul_f32_e32 v79, 0xbfb8aa3b, v79
	v_exp_f32_e32 v79, v79
	s_nop 0
	v_add_f32_e32 v79, 1.0, v79
	s_nop 0
	v_rcp_f32_e32 v81, v79
	s_nop 0
	v_fma_f32 v80, -v79, v81, 1.0
	v_fma_f32 v80, v80, v81, v81
	v_div_fixup_f32 v79, v80, v79, 1.0
	v_add_f32_e32 v80, v52, v210
	v_mul_f32_e32 v80, 0xbfb8aa3b, v80
	v_exp_f32_e32 v80, v80
	s_nop 0
	v_add_f32_e32 v80, 1.0, v80
	s_nop 0
	v_rcp_f32_e32 v82, v80
	s_nop 0
	v_fma_f32 v81, -v80, v82, 1.0
	v_fma_f32 v81, v81, v82, v82
	v_div_fixup_f32 v80, v81, v80, 1.0
	v_add_f32_e32 v81, v53, v210
	v_mul_f32_e32 v81, 0xbfb8aa3b, v81
	v_exp_f32_e32 v81, v81
	s_nop 0
	v_add_f32_e32 v81, 1.0, v81
; DEVFI float sigmoidf_(float x) { return 1.f / (1.f + __expf(-x)); }
; #define GATES ((bfraw*)(kargs()->ws + O_GATES))
; __global__ void __launch_bounds__(512) mega(Params p) {
;     ...
;                   } else {
; #pragma unroll
;                     for (int n = 0; n < 8; ++n) { const float bb = hv[n];
; #pragma unroll
;                       for (int j = 0; j < 4; ++j) a[n][j] = sigmoidf_(a[n][j] + bb); }
;                     const int gt0 = bcol - 7680, tidn = ((wr0 >> 6) * 2 + (wc0 >> 7)) * 64 + fq * 16 + fr;
;                     bfraw* gt = GATES + ((long)(((brow >> 8) * 3 + (gt0 >> 10)) * 4 + ((gt0 >> 8) & 3))) * 65536 + (long)(m * 4 * 512 + tidn) * 8;
; #pragma unroll
;                     for (int q = 0; q < 4; ++q) { u32x4 w4 = {cvtpk(a[2 * q][0], a[2 * q][1]), cvtpk(a[2 * q][2], a[2 * q][3]), cvtpk(a[2 * q + 1][0], a[2 * q + 1][1]), cvtpk(a[2 * q + 1][2], a[2 * q + 1][3])};
;                       *(u32x4*)(gt + q * 512 * 8) = w4; }
	s_nop 0
	v_rcp_f32_e32 v83, v81
	s_nop 0
	v_fma_f32 v82, -v81, v83, 1.0
	v_fma_f32 v82, v82, v83, v83
	v_div_fixup_f32 v81, v82, v81, 1.0
	v_add_f32_e32 v82, v54, v210
	v_mul_f32_e32 v82, 0xbfb8aa3b, v82
	v_exp_f32_e32 v82, v82
	s_nop 0
	v_add_f32_e32 v82, 1.0, v82
	s_nop 0
	v_rcp_f32_e32 v84, v82
	s_nop 0
	v_fma_f32 v83, -v82, v84, 1.0
	v_fma_f32 v83, v83, v84, v84
	v_div_fixup_f32 v82, v83, v82, 1.0
	v_add_f32_e32 v83, v55, v210
	v_mul_f32_e32 v83, 0xbfb8aa3b, v83
	v_exp_f32_e32 v83, v83
	s_nop 0
	v_add_f32_e32 v83, 1.0, v83
	s_nop 0
	v_rcp_f32_e32 v85, v83
	s_nop 0
	v_fma_f32 v84, -v83, v85, 1.0
	v_fma_f32 v84, v84, v85, v85
	v_div_fixup_f32 v83, v84, v83, 1.0
	v_add_f32_e32 v84, v48, v209
	v_mul_f32_e32 v84, 0xbfb8aa3b, v84
	v_exp_f32_e32 v84, v84
	s_nop 0
	v_add_f32_e32 v84, 1.0, v84
	s_nop 0
	v_rcp_f32_e32 v86, v84
	s_nop 0
	v_fma_f32 v85, -v84, v86, 1.0
	v_fma_f32 v85, v85, v86, v86
	v_div_fixup_f32 v84, v85, v84, 1.0
	v_add_f32_e32 v85, v49, v209
	v_mul_f32_e32 v85, 0xbfb8aa3b, v85
	v_exp_f32_e32 v85, v85
	s_nop 0
	v_add_f32_e32 v85, 1.0, v85
	s_nop 0
	v_rcp_f32_e32 v87, v85
	s_nop 0
	v_fma_f32 v86, -v85, v87, 1.0
	v_fma_f32 v86, v86, v87, v87
	v_div_fixup_f32 v85, v86, v85, 1.0
	v_add_f32_e32 v86, v50, v209
	v_mul_f32_e32 v86, 0xbfb8aa3b, v86
	v_exp_f32_e32 v86, v86
	s_nop 0
	v_add_f32_e32 v86, 1.0, v86
	s_nop 0
	v_rcp_f32_e32 v88, v86
	s_nop 0
	v_fma_f32 v87, -v86, v88, 1.0
	v_fma_f32 v87, v87, v88, v88
	v_div_fixup_f32 v86, v87, v86, 1.0
	v_add_f32_e32 v87, v51, v209
	v_mul_f32_e32 v87, 0xbfb8aa3b, v87
	v_exp_f32_e32 v87, v87
	s_nop 0
	v_add_f32_e32 v87, 1.0, v87
	s_nop 0
	v_rcp_f32_e32 v89, v87
	s_nop 0
	v_fma_f32 v88, -v87, v89, 1.0
	v_fma_f32 v88, v88, v89, v89
	v_div_fixup_f32 v87, v88, v87, 1.0
	v_add_f32_e32 v88, v36, v208
	v_mul_f32_e32 v88, 0xbfb8aa3b, v88
	v_exp_f32_e32 v88, v88
	s_nop 0
	v_add_f32_e32 v88, 1.0, v88
	s_nop 0
	v_rcp_f32_e32 v90, v88
	s_nop 0
	v_fma_f32 v89, -v88, v90, 1.0
	v_fma_f32 v89, v89, v90, v90
	v_div_fixup_f32 v90, v89, v88, 1.0
	v_add_f32_e32 v88, v37, v208
	v_mul_f32_e32 v88, 0xbfb8aa3b, v88
	v_exp_f32_e32 v88, v88
	s_nop 0
	v_add_f32_e32 v88, 1.0, v88
	s_nop 0
	v_rcp_f32_e32 v91, v88
	s_nop 0
	v_fma_f32 v89, -v88, v91, 1.0
	v_fma_f32 v89, v89, v91, v91
	v_div_fixup_f32 v91, v89, v88, 1.0
	v_add_f32_e32 v88, v38, v208
	v_mul_f32_e32 v88, 0xbfb8aa3b, v88
	v_exp_f32_e32 v88, v88
	s_nop 0
	v_add_f32_e32 v88, 1.0, v88
	s_nop 0
	v_rcp_f32_e32 v92, v88
	s_nop 0
	v_fma_f32 v89, -v88, v92, 1.0
	v_fma_f32 v89, v89, v92, v92
	v_div_fixup_f32 v92, v89, v88, 1.0
	v_add_f32_e32 v88, v39, v208
	v_mul_f32_e32 v88, 0xbfb8aa3b, v88
	v_exp_f32_e32 v88, v88
	s_nop 0
	v_add_f32_e32 v88, 1.0, v88
	s_nop 0
	v_rcp_f32_e32 v93, v88
	s_nop 0
	v_fma_f32 v89, -v88, v93, 1.0
	v_fma_f32 v89, v89, v93, v93
	v_div_fixup_f32 v93, v89, v88, 1.0
	v_add_f32_e32 v88, v32, v207
	v_mul_f32_e32 v88, 0xbfb8aa3b, v88
	v_exp_f32_e32 v88, v88
	s_nop 0
	v_add_f32_e32 v88, 1.0, v88
	s_nop 0
	v_rcp_f32_e32 v94, v88
	s_nop 0
	v_fma_f32 v89, -v88, v94, 1.0
	v_fma_f32 v89, v89, v94, v94
	v_div_fixup_f32 v94, v89, v88, 1.0
	v_add_f32_e32 v88, v33, v207
	v_mul_f32_e32 v88, 0xbfb8aa3b, v88
	v_exp_f32_e32 v88, v88
	s_nop 0
	v_add_f32_e32 v88, 1.0, v88
	s_nop 0
	v_rcp_f32_e32 v95, v88
	s_nop 0
	v_fma_f32 v89, -v88, v95, 1.0
	v_fma_f32 v89, v89, v95, v95
	v_div_fixup_f32 v95, v89, v88, 1.0
	v_add_f32_e32 v88, v34, v207
	v_mul_f32_e32 v88, 0xbfb8aa3b, v88
	v_exp_f32_e32 v88, v88
	s_nop 0
	v_add_f32_e32 v88, 1.0, v88
	s_nop 0
	v_rcp_f32_e32 v97, v88
	s_nop 0
	v_fma_f32 v89, -v88, v97, 1.0
	v_fma_f32 v89, v89, v97, v97
	v_div_fixup_f32 v97, v89, v88, 1.0
	v_add_f32_e32 v88, v35, v207
	v_mul_f32_e32 v88, 0xbfb8aa3b, v88
	v_exp_f32_e32 v88, v88
	s_nop 0
	v_add_f32_e32 v88, 1.0, v88
	s_mov_b64 s[2:3], s[0:1]
	s_load_dwordx2 s[2:3], s[2:3], 0xe8
	v_rcp_f32_e32 v98, v88
	s_nop 0
	v_fma_f32 v89, -v88, v98, 1.0
	v_fma_f32 v89, v89, v98, v98
	v_div_fixup_f32 v98, v89, v88, 1.0
	v_and_b32_e32 v88, 0xffffff80, v205
	v_lshlrev_b32_e32 v89, 6, v206
	v_or3_b32 v88, v88, v204, v89
	s_waitcnt lgkmcnt(0)
	s_add_u32 s2, s2, s6
	v_add_u32_e32 v88, 0x1000, v88
	s_addc_u32 s3, s3, s7
	v_ashrrev_i32_e32 v89, 31, v88
	v_lshl_add_u64 v[88:89], v[88:89], 4, s[2:3]
	v_cvt_pk_bf16_f32 v64, v64, v65
	v_cvt_pk_bf16_f32 v65, v66, v67
	v_cvt_pk_bf16_f32 v66, v68, v69
	v_add_co_u32_e32 v68, vcc, s67, v88
	v_cvt_pk_bf16_f32 v67, v70, v71
	s_mov_b64 s[2:3], 0
	s_nop 0
	v_addc_co_u32_e32 v69, vcc, 0, v89, vcc
	global_store_dwordx4 v[68:69], v[64:67], off
	v_add_co_u32_e32 v68, vcc, s46, v88
	s_nop 0
	v_cvt_pk_bf16_f32 v64, v72, v73
	v_cvt_pk_bf16_f32 v65, v74, v75
	v_cvt_pk_bf16_f32 v66, v76, v77
	v_cvt_pk_bf16_f32 v67, v78, v79
	s_nop 0
	v_addc_co_u32_e32 v69, vcc, 0, v89, vcc
	global_store_dwordx4 v[68:69], v[64:67], off
	v_add_co_u32_e32 v68, vcc, 0x22724000, v88
	s_nop 0
	v_cvt_pk_bf16_f32 v64, v80, v81
	v_cvt_pk_bf16_f32 v65, v82, v83
	v_cvt_pk_bf16_f32 v66, v84, v85
	v_cvt_pk_bf16_f32 v67, v86, v87
	s_nop 0
	v_addc_co_u32_e32 v69, vcc, 0, v89, vcc
	global_store_dwordx4 v[68:69], v[64:67], off
	v_add_co_u32_e32 v68, vcc, 0x22726000, v88
	s_nop 0
	v_cvt_pk_bf16_f32 v64, v90, v91
	v_cvt_pk_bf16_f32 v65, v92, v93
	v_cvt_pk_bf16_f32 v66, v94, v95
	v_cvt_pk_bf16_f32 v67, v97, v98
	s_nop 0
	v_addc_co_u32_e32 v69, vcc, 0, v89, vcc
	global_store_dwordx4 v[68:69], v[64:67], off

; #define ATTT ((float2*)(kargs()->ws + O_ATTT))
; __global__ void __launch_bounds__(512) mega(Params p) {
;     ...
;                   } else if (c0 < 7424) {
;                     const bool isk = c0 >= 7168; const float* nw = isk ? kn_w : qn_w; const float2* attt = ATTT;
; #pragma unroll
;                     for (int j = 0; j < 4; ++j) { const int pos = (r0 + j) & (seqlen - 1);
;                       float ss = 0;
; #pragma unroll
;                       for (int n = 0; n < 8; ++n) ss += a[n][j] * a[n][j];
;                       ss = red16(ss);
;                       const float rstd = 1.f / sqrtf(ss * (1.f / 128.f) + RMS_EPS);
; #pragma unroll
;                       for (int n = 0; n < 8; ++n) a[n][j] = a[n][j] * rstd * hv[n];
;                       const float4* tb = (const float4*)(attt + pos * 64 + fr * 4);
;                       const float4 t01 = tb[0], t23 = tb[1];
;                       const float2 csv[4] = {make_float2(t01.x, t01.y), make_float2(t01.z, t01.w), make_float2(t23.x, t23.y), make_float2(t23.z, t23.w)};
.LBB0_1627:
	s_mov_b64 s[2:3], s[0:1]
	s_load_dwordx2 s[2:3], s[2:3], 0xe8
	v_mul_f32_e32 v64, v56, v56
	v_fmac_f32_e32 v64, v60, v60
	v_fmac_f32_e32 v64, v44, v44
	v_fmac_f32_e32 v64, v40, v40
	s_waitcnt lgkmcnt(0)
	s_add_u32 s36, s2, 0x3da0000
	s_mov_b32 s2, -1
	v_fmac_f32_e32 v64, v52, v52
	v_fmac_f32_e32 v64, v48, v48
	v_mbcnt_lo_u32_b32 v65, s2, 0
	v_mbcnt_hi_u32_b32 v65, s2, v65
	v_fmac_f32_e32 v64, v36, v36
	v_lshlrev_b32_e32 v65, 2, v65
	v_fmac_f32_e32 v64, v32, v32
	v_xor_b32_e32 v66, 4, v65
	ds_bpermute_b32 v66, v66, v64
	v_mov_b32_e32 v99, 0x358637bd
	s_addc_u32 s37, s3, 0
	v_mov_b32_e32 v161, v177
	s_waitcnt lgkmcnt(0)
	v_add_f32_e32 v64, v64, v66
	v_xor_b32_e32 v66, 8, v65
	ds_bpermute_b32 v66, v66, v64
	s_waitcnt lgkmcnt(0)
	v_add_f32_e32 v64, v64, v66
	v_xor_b32_e32 v66, 16, v65
	ds_bpermute_b32 v66, v66, v64
	v_xor_b32_e32 v65, 32, v65
	s_waitcnt lgkmcnt(0)
	v_add_f32_e32 v64, v64, v66
	ds_bpermute_b32 v65, v65, v64
	s_waitcnt lgkmcnt(0)
	v_add_f32_e32 v64, v64, v65
	v_fmamk_f32 v64, v64, 0x3c000000, v99
	v_cmp_gt_f32_e32 vcc, s30, v64
	v_mul_f32_e32 v65, 0x4f800000, v64
	s_nop 0
	v_cndmask_b32_e32 v64, v64, v65, vcc
	v_sqrt_f32_e32 v65, v64
	s_nop 0
	v_add_u32_e32 v66, -1, v65
	v_fma_f32 v67, -v66, v65, v64
	v_cmp_ge_f32_e64 s[6:7], 0, v67
	v_add_u32_e32 v67, 1, v65
	s_nop 0
	v_cndmask_b32_e64 v66, v65, v66, s[6:7]
	v_fma_f32 v65, -v67, v65, v64
	v_cmp_lt_f32_e64 s[6:7], 0, v65
	s_nop 1
	v_cndmask_b32_e64 v65, v66, v67, s[6:7]
	v_mul_f32_e32 v66, 0x37800000, v65
	v_cndmask_b32_e32 v65, v65, v66, vcc
	v_cmp_class_f32_e32 vcc, v64, v222
	s_nop 1
	v_cndmask_b32_e32 v64, v65, v64, vcc
	s_mov_b32 s2, -1
	v_rcp_f32_e32 v66, v64
	s_nop 0
	v_fma_f32 v65, -v64, v66, 1.0
	v_fma_f32 v65, v65, v66, v66
	v_div_fixup_f32 v64, v65, v64, 1.0
	v_mul_f32_e32 v65, v60, v64
	s_waitcnt vmcnt(0)
	v_mul_f32_e32 v73, v224, v65
	v_mul_f32_e32 v65, v56, v64
	v_mul_f32_e32 v76, v223, v65
	v_mul_f32_e32 v65, v44, v64
	v_mul_f32_e32 v72, v212, v65
	v_mul_f32_e32 v65, v40, v64
	v_mul_f32_e32 v77, v211, v65
	v_mul_f32_e32 v65, v52, v64
	v_mul_f32_e32 v78, v210, v65
	v_mul_f32_e32 v65, v48, v64
	v_mul_f32_e32 v79, v209, v65
	v_mul_f32_e32 v65, v36, v64
	v_mul_f32_e32 v64, v32, v64
	v_mul_f32_e32 v81, v207, v64
	v_and_b32_e32 v64, s14, v96
	v_mul_f32_e32 v80, v208, v65
	v_lshlrev_b32_e32 v64, 6, v64
	v_mov_b32_e32 v65, v177
	v_lshl_add_u64 v[64:65], v[64:65], 3, s[36:37]
	v_lshl_add_u64 v[68:69], v[64:65], 0, v[160:161]
	global_load_dwordx4 v[64:67], v[68:69], off offset:16
	s_nop 0
	global_load_dwordx4 v[68:71], v[68:69], off
	s_waitcnt vmcnt(0)
	v_mul_f32_e32 v74, v69, v72
	v_fma_f32 v74, v68, v73, -v74
	v_mul_f32_e32 v72, v68, v72
	v_mul_f32_e32 v68, v71, v77
	v_fma_f32 v75, v70, v76, -v68
	v_mul_f32_e32 v68, v65, v80
	v_fmac_f32_e32 v72, v69, v73
	v_mul_f32_e32 v73, v70, v77
	v_fma_f32 v70, v64, v78, -v68
	v_mul_f32_e32 v68, v64, v80
	v_mul_f32_e32 v64, v67, v81
	v_fmac_f32_e32 v73, v71, v76
	v_fma_f32 v71, v66, v79, -v64
	v_mul_f32_e32 v64, v57, v57
	v_fmac_f32_e32 v64, v61, v61
	v_fmac_f32_e32 v64, v45, v45
	v_fmac_f32_e32 v64, v41, v41
	v_mul_f32_e32 v69, v66, v81
	v_fmac_f32_e32 v64, v53, v53
	v_mbcnt_lo_u32_b32 v66, s2, 0
	v_fmac_f32_e32 v64, v49, v49
	v_mbcnt_hi_u32_b32 v66, s2, v66
	v_fmac_f32_e32 v64, v37, v37
	v_lshlrev_b32_e32 v66, 2, v66
	v_fmac_f32_e32 v69, v67, v79
	v_fmac_f32_e32 v64, v33, v33
	v_xor_b32_e32 v67, 4, v66
	ds_bpermute_b32 v67, v67, v64
	v_fmac_f32_e32 v68, v65, v78
	v_add_u32_e32 v65, 1, v96
	s_waitcnt lgkmcnt(0)
	v_add_f32_e32 v64, v64, v67
	v_xor_b32_e32 v67, 8, v66
	ds_bpermute_b32 v67, v67, v64
	s_waitcnt lgkmcnt(0)
	v_add_f32_e32 v64, v64, v67
	v_xor_b32_e32 v67, 16, v66
	ds_bpermute_b32 v67, v67, v64
	v_xor_b32_e32 v66, 32, v66
	s_waitcnt lgkmcnt(0)
	v_add_f32_e32 v64, v64, v67
	ds_bpermute_b32 v66, v66, v64
	s_waitcnt lgkmcnt(0)
	v_add_f32_e32 v64, v64, v66
	v_fmamk_f32 v64, v64, 0x3c000000, v99
	v_cmp_gt_f32_e32 vcc, s30, v64
	v_mul_f32_e32 v66, 0x4f800000, v64
	s_nop 0
	v_cndmask_b32_e32 v64, v64, v66, vcc
	v_sqrt_f32_e32 v66, v64
	s_nop 0
	v_add_u32_e32 v67, -1, v66
	v_fma_f32 v76, -v67, v66, v64
	v_cmp_ge_f32_e64 s[6:7], 0, v76
	v_add_u32_e32 v76, 1, v66
	s_nop 0
	v_cndmask_b32_e64 v67, v66, v67, s[6:7]
	v_fma_f32 v66, -v76, v66, v64
	v_cmp_lt_f32_e64 s[6:7], 0, v66
	s_nop 1
	v_cndmask_b32_e64 v66, v67, v76, s[6:7]
	v_mul_f32_e32 v67, 0x37800000, v66
	v_cndmask_b32_e32 v66, v66, v67, vcc
	v_cmp_class_f32_e32 vcc, v64, v222
	s_nop 1
	v_cndmask_b32_e32 v64, v66, v64, vcc
	s_mov_b32 s2, -1
	v_rcp_f32_e32 v67, v64
	s_nop 0
	v_fma_f32 v66, -v64, v67, 1.0
	v_fma_f32 v66, v66, v67, v67
	v_div_fixup_f32 v64, v66, v64, 1.0
	v_mul_f32_e32 v66, v61, v64
	v_mul_f32_e32 v81, v224, v66
	v_mul_f32_e32 v66, v57, v64
	v_mul_f32_e32 v84, v223, v66
	v_mul_f32_e32 v66, v45, v64
	v_mul_f32_e32 v80, v212, v66
	v_mul_f32_e32 v66, v41, v64
	v_mul_f32_e32 v85, v211, v66
	v_mul_f32_e32 v66, v53, v64
	v_mul_f32_e32 v86, v210, v66
	v_mul_f32_e32 v66, v49, v64
	v_mul_f32_e32 v87, v209, v66
	v_mul_f32_e32 v66, v37, v64
	v_mul_f32_e32 v64, v33, v64
	v_mul_f32_e32 v89, v207, v64
	v_and_b32_e32 v64, s14, v65
	v_lshlrev_b32_e32 v64, 6, v64
	v_mov_b32_e32 v65, v177
	v_lshl_add_u64 v[64:65], v[64:65], 3, s[36:37]
	v_lshl_add_u64 v[76:77], v[64:65], 0, v[160:161]
	v_mul_f32_e32 v88, v208, v66
	global_load_dwordx4 v[64:67], v[76:77], off offset:16
	s_nop 0
	global_load_dwordx4 v[76:79], v[76:77], off
	s_waitcnt vmcnt(0)
; __global__ void __launch_bounds__(512) mega(Params p) {
;     ...
;                     for (int j = 0; j < 4; ++j) { const int pos = (r0 + j) & (seqlen - 1);
;                       float ss = 0;
; #pragma unroll
;                       for (int n = 0; n < 8; ++n) ss += a[n][j] * a[n][j];
;                       ss = red16(ss);
;                       const float rstd = 1.f / sqrtf(ss * (1.f / 128.f) + RMS_EPS);
; #pragma unroll
;                       for (int n = 0; n < 8; ++n) a[n][j] = a[n][j] * rstd * hv[n];
;                       const float4* tb = (const float4*)(attt + pos * 64 + fr * 4);
;                       const float4 t01 = tb[0], t23 = tb[1];
;                       const float2 csv[4] = {make_float2(t01.x, t01.y), make_float2(t01.z, t01.w), make_float2(t23.x, t23.y), make_float2(t23.z, t23.w)};
; #pragma unroll
;                       for (int hh = 0; hh < 2; ++hh)
; #pragma unroll
;                         for (int n = 0; n < 2; ++n) { const float2 cs = csv[hh * 2 + n];
;                           const float x1 = a[hh * 4 + n][j], x2 = a[hh * 4 + n + 2][j];
;                           a[hh * 4 + n][j] = x1 * cs.x - x2 * cs.y; a[hh * 4 + n + 2][j] = x1 * cs.y + x2 * cs.x; } }
	v_mul_f32_e32 v82, v77, v80
	v_fma_f32 v82, v76, v81, -v82
	v_mul_f32_e32 v80, v76, v80
	v_mul_f32_e32 v76, v79, v85
	v_fma_f32 v83, v78, v84, -v76
	v_mul_f32_e32 v76, v65, v88
	v_fmac_f32_e32 v80, v77, v81
	v_mul_f32_e32 v81, v78, v85
	v_fma_f32 v78, v64, v86, -v76
	v_mul_f32_e32 v76, v64, v88
	v_mul_f32_e32 v64, v67, v89
	v_fmac_f32_e32 v81, v79, v84
	v_fma_f32 v79, v66, v87, -v64
	v_mul_f32_e32 v64, v58, v58
	v_fmac_f32_e32 v64, v62, v62
	v_fmac_f32_e32 v64, v46, v46
	v_fmac_f32_e32 v64, v42, v42
	v_mul_f32_e32 v77, v66, v89
	v_fmac_f32_e32 v64, v54, v54
	v_mbcnt_lo_u32_b32 v66, s2, 0
	v_fmac_f32_e32 v64, v50, v50
	v_mbcnt_hi_u32_b32 v66, s2, v66
	v_fmac_f32_e32 v64, v38, v38
	v_lshlrev_b32_e32 v66, 2, v66
	v_fmac_f32_e32 v77, v67, v87
	v_fmac_f32_e32 v64, v34, v34
	v_xor_b32_e32 v67, 4, v66
	ds_bpermute_b32 v67, v67, v64
	v_fmac_f32_e32 v76, v65, v86
	v_add_u32_e32 v65, 2, v96
	s_waitcnt lgkmcnt(0)
	v_add_f32_e32 v64, v64, v67
	v_xor_b32_e32 v67, 8, v66
	ds_bpermute_b32 v67, v67, v64
	s_waitcnt lgkmcnt(0)
	v_add_f32_e32 v64, v64, v67
	v_xor_b32_e32 v67, 16, v66
	ds_bpermute_b32 v67, v67, v64
	v_xor_b32_e32 v66, 32, v66
	s_waitcnt lgkmcnt(0)
	v_add_f32_e32 v64, v64, v67
	ds_bpermute_b32 v66, v66, v64
	s_waitcnt lgkmcnt(0)
	v_add_f32_e32 v64, v64, v66
	v_fmamk_f32 v64, v64, 0x3c000000, v99
	v_cmp_gt_f32_e32 vcc, s30, v64
	v_mul_f32_e32 v66, 0x4f800000, v64
	s_nop 0
	v_cndmask_b32_e32 v64, v64, v66, vcc
	v_sqrt_f32_e32 v66, v64
	s_nop 0
	v_add_u32_e32 v67, -1, v66
	v_fma_f32 v84, -v67, v66, v64
	v_cmp_ge_f32_e64 s[6:7], 0, v84
	v_add_u32_e32 v84, 1, v66
	s_nop 0
	v_cndmask_b32_e64 v67, v66, v67, s[6:7]
	v_fma_f32 v66, -v84, v66, v64
	v_cmp_lt_f32_e64 s[6:7], 0, v66
	s_nop 1
	v_cndmask_b32_e64 v66, v67, v84, s[6:7]
	v_mul_f32_e32 v67, 0x37800000, v66
	v_cndmask_b32_e32 v66, v66, v67, vcc
	v_cmp_class_f32_e32 vcc, v64, v222
	s_nop 1
	v_cndmask_b32_e32 v64, v66, v64, vcc
	s_mov_b32 s2, -1
	v_rcp_f32_e32 v67, v64
	s_nop 0
	v_fma_f32 v66, -v64, v67, 1.0
	v_fma_f32 v66, v66, v67, v67
	v_div_fixup_f32 v64, v66, v64, 1.0
	v_mul_f32_e32 v66, v62, v64
	v_mul_f32_e32 v89, v224, v66
	v_mul_f32_e32 v66, v58, v64
	v_mul_f32_e32 v92, v223, v66
	v_mul_f32_e32 v66, v46, v64
	v_mul_f32_e32 v88, v212, v66
	v_mul_f32_e32 v66, v42, v64
	v_mul_f32_e32 v93, v211, v66
	v_mul_f32_e32 v66, v54, v64
	v_mul_f32_e32 v94, v210, v66
	v_mul_f32_e32 v66, v50, v64
	v_mul_f32_e32 v95, v209, v66
	v_mul_f32_e32 v66, v38, v64
	v_mul_f32_e32 v64, v34, v64
	v_mul_f32_e32 v98, v207, v64
	v_and_b32_e32 v64, s14, v65
	v_lshlrev_b32_e32 v64, 6, v64
	v_mov_b32_e32 v65, v177
	v_lshl_add_u64 v[64:65], v[64:65], 3, s[36:37]
	v_lshl_add_u64 v[84:85], v[64:65], 0, v[160:161]
	v_mul_f32_e32 v97, v208, v66
	global_load_dwordx4 v[64:67], v[84:85], off offset:16
	s_nop 0
	global_load_dwordx4 v[84:87], v[84:85], off
	s_waitcnt vmcnt(0)
	v_mul_f32_e32 v90, v85, v88
	v_fma_f32 v90, v84, v89, -v90
	v_mul_f32_e32 v88, v84, v88
	v_mul_f32_e32 v84, v87, v93
	v_fma_f32 v91, v86, v92, -v84
	v_mul_f32_e32 v84, v65, v97
	v_fmac_f32_e32 v88, v85, v89
	v_mul_f32_e32 v89, v86, v93
	v_fma_f32 v86, v64, v94, -v84
	v_mul_f32_e32 v84, v64, v97
	v_mul_f32_e32 v64, v67, v98
	v_fmac_f32_e32 v89, v87, v92
	v_fma_f32 v87, v66, v95, -v64
	v_mul_f32_e32 v64, v59, v59
	v_fmac_f32_e32 v64, v63, v63
	v_fmac_f32_e32 v64, v47, v47
	v_fmac_f32_e32 v64, v43, v43
	v_mul_f32_e32 v85, v66, v98
	v_fmac_f32_e32 v64, v55, v55
	v_mbcnt_lo_u32_b32 v66, s2, 0
	v_fmac_f32_e32 v64, v51, v51
	v_mbcnt_hi_u32_b32 v66, s2, v66
	v_fmac_f32_e32 v64, v39, v39
	v_lshlrev_b32_e32 v66, 2, v66
	v_fmac_f32_e32 v85, v67, v95
	v_fmac_f32_e32 v64, v35, v35
	v_xor_b32_e32 v67, 4, v66
	ds_bpermute_b32 v67, v67, v64
	v_fmac_f32_e32 v84, v65, v94
	v_add_u32_e32 v65, 3, v96
	s_waitcnt lgkmcnt(0)
	v_add_f32_e32 v64, v64, v67
	v_xor_b32_e32 v67, 8, v66
	ds_bpermute_b32 v67, v67, v64
	s_waitcnt lgkmcnt(0)
	v_add_f32_e32 v64, v64, v67
	v_xor_b32_e32 v67, 16, v66
	ds_bpermute_b32 v67, v67, v64
	v_xor_b32_e32 v66, 32, v66
	s_waitcnt lgkmcnt(0)
	v_add_f32_e32 v64, v64, v67
	ds_bpermute_b32 v66, v66, v64
	s_waitcnt lgkmcnt(0)
	v_add_f32_e32 v64, v64, v66
	v_fmamk_f32 v64, v64, 0x3c000000, v99
	v_cmp_gt_f32_e32 vcc, s30, v64
	v_mul_f32_e32 v66, 0x4f800000, v64
	s_nop 0
	v_cndmask_b32_e32 v64, v64, v66, vcc
	v_sqrt_f32_e32 v66, v64
	s_nop 0
	v_add_u32_e32 v67, -1, v66
	v_fma_f32 v92, -v67, v66, v64
	v_cmp_ge_f32_e64 s[6:7], 0, v92
	v_add_u32_e32 v92, 1, v66
	s_nop 0
	v_cndmask_b32_e64 v67, v66, v67, s[6:7]
	v_fma_f32 v66, -v92, v66, v64
	v_cmp_lt_f32_e64 s[6:7], 0, v66
	s_nop 1
	v_cndmask_b32_e64 v66, v67, v92, s[6:7]
	v_mul_f32_e32 v67, 0x37800000, v66
	v_cndmask_b32_e32 v66, v66, v67, vcc
	v_cmp_class_f32_e32 vcc, v64, v222
	s_nop 1
	v_cndmask_b32_e32 v64, v66, v64, vcc
	s_mov_b64 s[2:3], -1
	v_rcp_f32_e32 v67, v64
	s_nop 0
	v_fma_f32 v66, -v64, v67, 1.0
	v_fma_f32 v66, v66, v67, v67
	v_div_fixup_f32 v64, v66, v64, 1.0
	v_mul_f32_e32 v66, v63, v64
	v_mul_f32_e32 v94, v224, v66
	v_mul_f32_e32 v66, v59, v64
	v_mul_f32_e32 v97, v223, v66
	v_mul_f32_e32 v66, v47, v64
	v_mul_f32_e32 v95, v212, v66
	v_mul_f32_e32 v66, v43, v64
	v_mul_f32_e32 v98, v211, v66
	v_mul_f32_e32 v66, v55, v64
	v_mul_f32_e32 v104, v210, v66
	v_mul_f32_e32 v66, v51, v64
	v_mul_f32_e32 v105, v209, v66
	v_mul_f32_e32 v66, v39, v64
	v_mul_f32_e32 v64, v35, v64
	v_mul_f32_e32 v107, v207, v64
	v_and_b32_e32 v64, s14, v65
	v_lshlrev_b32_e32 v64, 6, v64
	v_mov_b32_e32 v65, v177
	v_lshl_add_u64 v[64:65], v[64:65], 3, s[36:37]
	v_lshl_add_u64 v[92:93], v[64:65], 0, v[160:161]
	v_mul_f32_e32 v106, v208, v66
	global_load_dwordx4 v[64:67], v[92:93], off offset:16
	global_load_dwordx4 v[100:103], v[92:93], off
	s_waitcnt vmcnt(0)
	v_mul_f32_e32 v92, v101, v95
	v_fma_f32 v99, v100, v94, -v92
	v_mul_f32_e32 v92, v103, v98
	v_mul_f32_e32 v95, v100, v95
	v_fma_f32 v100, v102, v97, -v92
	v_mul_f32_e32 v92, v65, v106
	v_fma_f32 v93, v64, v104, -v92
	v_mul_f32_e32 v92, v64, v106
	v_mul_f32_e32 v64, v67, v107
	v_fmac_f32_e32 v95, v101, v94
	v_fma_f32 v94, v66, v105, -v64
	v_and_b32_e32 v64, 1, v203
	v_mul_f32_e32 v98, v102, v98
	v_mul_f32_e32 v66, v66, v107
	v_cmp_eq_u32_e32 vcc, 0, v64
	v_cmp_eq_u32_e64 s[6:7], 1, v64
	v_add_u32_e32 v64, 15, v202
	v_fmac_f32_e32 v98, v103, v97
	v_fmac_f32_e32 v92, v65, v104
	v_fmac_f32_e32 v66, v67, v105
	v_ashrrev_i32_e32 v97, 31, v96
	v_cndmask_b32_e32 v67, v64, v202, vcc
	v_cndmask_b32_e32 v101, v74, v75, vcc
	s_and_b64 vcc, exec, s[8:9]
	s_cbranch_vccz .LBB0_1693
	s_mov_b64 s[2:3], s[0:1]
	s_load_dwordx2 s[2:3], s[2:3], 0xe8
	v_mov_b32_dpp v64, v101 quad_perm:[1,0,3,2] row_mask:0xf bank_mask:0xf bound_ctrl:1
	s_and_saveexec_b64 s[8:9], s[6:7]
	s_xor_b64 s[8:9], exec, s[8:9]
	s_cbranch_execz .LBB0_1630
	v_cvt_pk_bf16_f32 v102, v64, v75

; DEVFI float gelu_tanh(float x) {
;   float u = 0.7978845608028654f * (x + 0.044715f * x * x * x);
;   float t = __expf(2.f * u);
;   float th = 1.f - 2.f / (t + 1.f);
;   return 0.5f * x * (1.f + th);
; __global__ void __launch_bounds__(512) mega(Params p) {
;     ...
;                   } else if (c0 < 6144) {
; #pragma unroll
;                     for (int n = 0; n < 8; ++n)
; #pragma unroll
;                       for (int j = 0; j < 4; ++j) a[n][j] = gelu_tanh(a[n][j]);
.LBB0_1760:
	s_andn2_b64 vcc, exec, s[2:3]
	s_cbranch_vccnz .LBB0_1838
	v_mul_f32_e32 v65, 0x3d372713, v61
	v_mul_f32_e32 v65, v61, v65
	v_fma_f32 v65, v61, v65, v61
	v_mul_f32_e32 v65, 0x3f4c422a, v65
	v_add_f32_e32 v65, v65, v65
	v_mul_f32_e32 v65, 0x3fb8aa3b, v65
	v_exp_f32_e32 v66, v65
	v_mul_f32_e32 v65, 0x3d372713, v62
	v_mul_f32_e32 v65, v62, v65
	v_fma_f32 v65, v62, v65, v62
	v_mul_f32_e32 v65, 0x3f4c422a, v65
	v_add_f32_e32 v65, v65, v65
	v_mul_f32_e32 v65, 0x3fb8aa3b, v65
	v_mul_f32_e32 v64, 0x3d372713, v60
	v_exp_f32_e32 v68, v65
	v_mul_f32_e32 v65, 0x3d372713, v56
	v_mul_f32_e32 v64, v60, v64
	v_mul_f32_e32 v65, v56, v65
	v_fma_f32 v64, v60, v64, v60
	v_fma_f32 v65, v56, v65, v56
	v_mul_f32_e32 v64, 0x3f4c422a, v64
	v_mul_f32_e32 v65, 0x3f4c422a, v65
	v_add_f32_e32 v64, v64, v64
	v_add_f32_e32 v65, v65, v65
	v_mul_f32_e32 v64, 0x3fb8aa3b, v64
	v_mul_f32_e32 v65, 0x3fb8aa3b, v65
	v_exp_f32_e32 v64, v64
	v_exp_f32_e32 v65, v65
	v_mul_f32_e32 v67, 0x3d372713, v63
	v_mul_f32_e32 v67, v63, v67
	v_fma_f32 v67, v63, v67, v63
	v_pk_add_f32 v[64:65], v[64:65], 1.0 op_sel_hi:[1,0]
	v_mul_f32_e32 v67, 0x3f4c422a, v67
	v_add_f32_e32 v67, v67, v67
	v_mul_f32_e32 v67, 0x3fb8aa3b, v67
	v_exp_f32_e32 v70, v67
	v_rcp_f32_e32 v71, v65
	s_nop 0
	v_fma_f32 v67, -v65, v71, 1.0
	v_fma_f32 v71, v67, v71, v71
	v_add_f32_e32 v67, v71, v71
	v_div_fixup_f32 v65, v67, v65, 2.0
	s_cmpk_lt_u32 s26, 0x1400
	v_rcp_f32_e32 v73, v64
	s_nop 0
	v_fma_f32 v67, -v64, v73, 1.0
	v_fma_f32 v73, v67, v73, v73
	v_add_f32_e32 v67, v73, v73
	v_div_fixup_f32 v64, v67, v64, 2.0
	v_mul_f32_e32 v67, 0x3d372713, v57
	v_mul_f32_e32 v67, v57, v67
	v_fma_f32 v67, v57, v67, v57
	v_mul_f32_e32 v67, 0x3f4c422a, v67
	v_add_f32_e32 v67, v67, v67
	v_mul_f32_e32 v67, 0x3fb8aa3b, v67
	v_exp_f32_e32 v67, v67
	v_pk_add_f32 v[64:65], v[64:65], 1.0 op_sel_hi:[1,0] neg_lo:[1,0] neg_hi:[1,0]
	v_mov_b32_e32 v72, v60
	v_mov_b32_e32 v73, v56
	v_pk_add_f32 v[66:67], v[66:67], 1.0 op_sel_hi:[1,0]
	v_pk_mul_f32 v[72:73], v[72:73], 0.5 op_sel_hi:[1,0]
	v_pk_add_f32 v[64:65], v[64:65], 1.0 op_sel_hi:[1,0]
	s_mov_b64 s[8:9], -1
	v_pk_mul_f32 v[78:79], v[72:73], v[64:65]
	v_rcp_f32_e32 v71, v67
	s_nop 0
	v_fma_f32 v64, -v67, v71, 1.0
	v_fma_f32 v71, v64, v71, v71
	v_add_f32_e32 v64, v71, v71
	v_div_fixup_f32 v65, v64, v67, 2.0
	v_rcp_f32_e32 v72, v66
	s_nop 0
	v_fma_f32 v64, -v66, v72, 1.0
	v_fma_f32 v72, v64, v72, v72
	v_add_f32_e32 v64, v72, v72
	v_div_fixup_f32 v64, v64, v66, 2.0
	v_mul_f32_e32 v66, 0x3d372713, v58
	v_mul_f32_e32 v66, v58, v66
	v_fma_f32 v66, v58, v66, v58
	v_mul_f32_e32 v66, 0x3f4c422a, v66
	v_add_f32_e32 v66, v66, v66
	v_mul_f32_e32 v66, 0x3fb8aa3b, v66
	v_exp_f32_e32 v69, v66
	v_pk_add_f32 v[64:65], v[64:65], 1.0 op_sel_hi:[1,0] neg_lo:[1,0] neg_hi:[1,0]
	v_mov_b32_e32 v66, v61
	v_mov_b32_e32 v67, v57
	v_pk_add_f32 v[68:69], v[68:69], 1.0 op_sel_hi:[1,0]
	v_pk_mul_f32 v[66:67], v[66:67], 0.5 op_sel_hi:[1,0]
	v_pk_add_f32 v[64:65], v[64:65], 1.0 op_sel_hi:[1,0]
	s_nop 0
	v_pk_mul_f32 v[74:75], v[66:67], v[64:65]
	v_rcp_f32_e32 v72, v69
	s_nop 0
	v_fma_f32 v64, -v69, v72, 1.0
	v_fma_f32 v72, v64, v72, v72
	v_add_f32_e32 v64, v72, v72
	v_div_fixup_f32 v65, v64, v69, 2.0
	v_mul_f32_e32 v66, 0x3d372713, v59
	v_mul_f32_e32 v66, v59, v66
	v_fma_f32 v66, v59, v66, v59
	v_mul_f32_e32 v66, 0x3f4c422a, v66
	v_add_f32_e32 v66, v66, v66
	v_mul_f32_e32 v66, 0x3fb8aa3b, v66
	v_exp_f32_e32 v71, v66
	v_rcp_f32_e32 v67, v68
	s_nop 0
	v_fma_f32 v64, -v68, v67, 1.0
	v_fma_f32 v67, v64, v67, v67
	v_add_f32_e32 v64, v67, v67
	v_div_fixup_f32 v64, v64, v68, 2.0
	v_pk_add_f32 v[64:65], v[64:65], 1.0 op_sel_hi:[1,0] neg_lo:[1,0] neg_hi:[1,0]
	v_pk_add_f32 v[70:71], v[70:71], 1.0 op_sel_hi:[1,0]
	v_mov_b32_e32 v66, v62
	v_mov_b32_e32 v67, v58
	v_pk_mul_f32 v[66:67], v[66:67], 0.5 op_sel_hi:[1,0]
	v_pk_add_f32 v[64:65], v[64:65], 1.0 op_sel_hi:[1,0]
	s_nop 0
	v_pk_mul_f32 v[68:69], v[66:67], v[64:65]
	v_rcp_f32_e32 v73, v71
	s_nop 0
	v_fma_f32 v64, -v71, v73, 1.0
	v_fma_f32 v73, v64, v73, v73
	v_add_f32_e32 v64, v73, v73
	v_div_fixup_f32 v65, v64, v71, 2.0
	v_mul_f32_e32 v66, 0x3d372713, v44
	v_mul_f32_e32 v66, v44, v66
	v_fma_f32 v66, v44, v66, v44
	v_mul_f32_e32 v66, 0x3f4c422a, v66
	v_add_f32_e32 v66, v66, v66
	v_rcp_f32_e32 v67, v70
	s_nop 0
	v_fma_f32 v64, -v70, v67, 1.0
	v_fma_f32 v67, v64, v67, v67
	v_add_f32_e32 v64, v67, v67
	v_mul_f32_e32 v66, 0x3fb8aa3b, v66
	v_div_fixup_f32 v64, v64, v70, 2.0
	v_exp_f32_e32 v70, v66
	v_pk_add_f32 v[64:65], v[64:65], 1.0 op_sel_hi:[1,0] neg_lo:[1,0] neg_hi:[1,0]
	v_mov_b32_e32 v66, v63
	v_mov_b32_e32 v67, v59
	v_add_f32_e32 v70, 1.0, v70
	v_pk_mul_f32 v[66:67], v[66:67], 0.5 op_sel_hi:[1,0]
	v_pk_add_f32 v[64:65], v[64:65], 1.0 op_sel_hi:[1,0]
	s_nop 0
	v_pk_mul_f32 v[64:65], v[66:67], v[64:65]
	v_mul_f32_e32 v71, 0x3d372713, v45
	v_mul_f32_e32 v71, v45, v71
	v_fma_f32 v71, v45, v71, v45
	v_mul_f32_e32 v71, 0x3f4c422a, v71
	v_add_f32_e32 v71, v71, v71
	v_mul_f32_e32 v71, 0x3fb8aa3b, v71
	v_exp_f32_e32 v71, v71
	v_rcp_f32_e32 v72, v70
	s_nop 0
	v_fma_f32 v66, -v70, v72, 1.0
	v_fma_f32 v72, v66, v72, v72
	v_add_f32_e32 v66, v72, v72
	v_div_fixup_f32 v66, v66, v70, 2.0
	v_sub_f32_e32 v66, 1.0, v66
	v_add_f32_e32 v67, 1.0, v71
	v_mul_f32_e32 v72, 0.5, v44
	v_add_f32_e32 v66, 1.0, v66
	v_mul_f32_e32 v90, v72, v66
	v_mul_f32_e32 v70, 0x3d372713, v46
	v_mul_f32_e32 v70, v46, v70
	v_fma_f32 v70, v46, v70, v46
	v_mul_f32_e32 v70, 0x3f4c422a, v70
	v_add_f32_e32 v70, v70, v70
	v_mul_f32_e32 v70, 0x3fb8aa3b, v70
	v_exp_f32_e32 v70, v70
	v_rcp_f32_e32 v71, v67
	s_nop 0
	v_fma_f32 v66, -v67, v71, 1.0
	v_fma_f32 v71, v66, v71, v71
	v_add_f32_e32 v66, v71, v71
; DEVFI float gelu_tanh(float x) {
;   float u = 0.7978845608028654f * (x + 0.044715f * x * x * x);
;   float t = __expf(2.f * u);
;   float th = 1.f - 2.f / (t + 1.f);
;   return 0.5f * x * (1.f + th);
; __global__ void __launch_bounds__(512) mega(Params p) {
;     ...
;                   } else if (c0 < 6144) {
; #pragma unroll
;                     for (int n = 0; n < 8; ++n)
; #pragma unroll
;                       for (int j = 0; j < 4; ++j) a[n][j] = gelu_tanh(a[n][j]);
	v_div_fixup_f32 v66, v66, v67, 2.0
	v_sub_f32_e32 v66, 1.0, v66
	v_add_f32_e32 v67, 1.0, v70
	v_mul_f32_e32 v72, 0.5, v45
	v_add_f32_e32 v66, 1.0, v66
	v_mul_f32_e32 v82, v72, v66
	v_mul_f32_e32 v70, 0x3d372713, v47
	v_mul_f32_e32 v70, v47, v70
	v_fma_f32 v70, v47, v70, v47
	v_mul_f32_e32 v70, 0x3f4c422a, v70
	v_add_f32_e32 v70, v70, v70
	v_mul_f32_e32 v70, 0x3fb8aa3b, v70
	v_exp_f32_e32 v70, v70
	v_rcp_f32_e32 v71, v67
	s_nop 0
	v_fma_f32 v66, -v67, v71, 1.0
	v_fma_f32 v71, v66, v71, v71
	v_add_f32_e32 v66, v71, v71
	v_div_fixup_f32 v66, v66, v67, 2.0
	v_sub_f32_e32 v66, 1.0, v66
	v_add_f32_e32 v67, 1.0, v70
	v_mul_f32_e32 v72, 0.5, v46
	v_add_f32_e32 v66, 1.0, v66
	v_mul_f32_e32 v72, v72, v66
	v_mul_f32_e32 v70, 0x3d372713, v40
	v_mul_f32_e32 v70, v40, v70
	v_fma_f32 v70, v40, v70, v40
	v_mul_f32_e32 v70, 0x3f4c422a, v70
	v_add_f32_e32 v70, v70, v70
	v_mul_f32_e32 v70, 0x3fb8aa3b, v70
	v_exp_f32_e32 v70, v70
	v_rcp_f32_e32 v71, v67
	s_nop 0
	v_fma_f32 v66, -v67, v71, 1.0
	v_fma_f32 v71, v66, v71, v71
	v_add_f32_e32 v66, v71, v71
	v_div_fixup_f32 v66, v66, v67, 2.0
	v_sub_f32_e32 v66, 1.0, v66
	v_add_f32_e32 v67, 1.0, v70
	v_mul_f32_e32 v73, 0.5, v47
	v_add_f32_e32 v66, 1.0, v66
	v_mul_f32_e32 v66, v73, v66
	v_mul_f32_e32 v73, 0x3d372713, v41
	v_mul_f32_e32 v73, v41, v73
	v_fma_f32 v73, v41, v73, v41
	v_mul_f32_e32 v73, 0x3f4c422a, v73
	v_add_f32_e32 v73, v73, v73
	v_mul_f32_e32 v73, 0x3fb8aa3b, v73
	v_exp_f32_e32 v73, v73
	v_rcp_f32_e32 v71, v67
	s_nop 0
	v_fma_f32 v70, -v67, v71, 1.0
	v_fma_f32 v71, v70, v71, v71
	v_add_f32_e32 v70, v71, v71
	v_div_fixup_f32 v67, v70, v67, 2.0
	v_sub_f32_e32 v67, 1.0, v67
	v_add_f32_e32 v70, 1.0, v73
	v_mul_f32_e32 v76, 0.5, v40
	v_add_f32_e32 v67, 1.0, v67
	v_mul_f32_e32 v104, v76, v67
	v_mul_f32_e32 v71, 0x3d372713, v42
	v_mul_f32_e32 v71, v42, v71
	v_fma_f32 v71, v42, v71, v42
	v_mul_f32_e32 v71, 0x3f4c422a, v71
	v_add_f32_e32 v71, v71, v71
	v_mul_f32_e32 v71, 0x3fb8aa3b, v71
	v_exp_f32_e32 v71, v71
	v_rcp_f32_e32 v73, v70
	s_nop 0
	v_fma_f32 v67, -v70, v73, 1.0
	v_fma_f32 v73, v67, v73, v73
	v_add_f32_e32 v67, v73, v73
	v_div_fixup_f32 v67, v67, v70, 2.0
	v_sub_f32_e32 v67, 1.0, v67
	v_add_f32_e32 v70, 1.0, v71
	v_mul_f32_e32 v76, 0.5, v41
	v_add_f32_e32 v67, 1.0, v67
	v_mul_f32_e32 v92, v76, v67
	v_mul_f32_e32 v71, 0x3d372713, v43
	v_mul_f32_e32 v71, v43, v71
	v_fma_f32 v71, v43, v71, v43
	v_mul_f32_e32 v71, 0x3f4c422a, v71
	v_add_f32_e32 v71, v71, v71
	v_mul_f32_e32 v71, 0x3fb8aa3b, v71
	v_exp_f32_e32 v71, v71
	v_rcp_f32_e32 v73, v70
	s_nop 0
	v_fma_f32 v67, -v70, v73, 1.0
	v_fma_f32 v73, v67, v73, v73
	v_add_f32_e32 v67, v73, v73
	v_div_fixup_f32 v67, v67, v70, 2.0
	v_sub_f32_e32 v67, 1.0, v67
	v_add_f32_e32 v70, 1.0, v71
	v_mul_f32_e32 v76, 0.5, v42
	v_add_f32_e32 v67, 1.0, v67
	v_mul_f32_e32 v80, v76, v67
	v_mul_f32_e32 v71, 0x3d372713, v52
	v_mul_f32_e32 v71, v52, v71
	v_fma_f32 v71, v52, v71, v52
	v_mul_f32_e32 v71, 0x3f4c422a, v71
	v_add_f32_e32 v71, v71, v71
	v_mul_f32_e32 v71, 0x3fb8aa3b, v71
	v_exp_f32_e32 v71, v71
	v_rcp_f32_e32 v73, v70
	s_nop 0
	v_fma_f32 v67, -v70, v73, 1.0
	v_fma_f32 v73, v67, v73, v73
	v_add_f32_e32 v67, v73, v73
	v_div_fixup_f32 v67, v67, v70, 2.0
	v_sub_f32_e32 v67, 1.0, v67
	v_add_f32_e32 v71, 1.0, v71
	v_mul_f32_e32 v70, 0.5, v43
	v_add_f32_e32 v67, 1.0, v67
	v_mul_f32_e32 v70, v70, v67
	v_mul_f32_e32 v73, 0x3d372713, v53
	v_mul_f32_e32 v73, v53, v73
	v_fma_f32 v73, v53, v73, v53
	v_mul_f32_e32 v73, 0x3f4c422a, v73
	v_add_f32_e32 v73, v73, v73
	v_mul_f32_e32 v73, 0x3fb8aa3b, v73
	v_exp_f32_e32 v73, v73
	v_rcp_f32_e32 v76, v71
	s_nop 0
	v_fma_f32 v67, -v71, v76, 1.0
	v_fma_f32 v76, v67, v76, v76
	v_add_f32_e32 v67, v76, v76
	v_div_fixup_f32 v67, v67, v71, 2.0
	v_sub_f32_e32 v67, 1.0, v67
	v_add_f32_e32 v71, 1.0, v73
	v_mul_f32_e32 v77, 0.5, v52
	v_add_f32_e32 v67, 1.0, v67
	v_mul_f32_e32 v106, v77, v67
	v_mul_f32_e32 v73, 0x3d372713, v54
	v_mul_f32_e32 v73, v54, v73
	v_fma_f32 v73, v54, v73, v54
	v_mul_f32_e32 v73, 0x3f4c422a, v73
	v_add_f32_e32 v73, v73, v73
	v_mul_f32_e32 v73, 0x3fb8aa3b, v73
	v_exp_f32_e32 v73, v73
	v_rcp_f32_e32 v76, v71
	s_nop 0
	v_fma_f32 v67, -v71, v76, 1.0
	v_fma_f32 v76, v67, v76, v76
	v_add_f32_e32 v67, v76, v76
	v_div_fixup_f32 v67, v67, v71, 2.0
	v_sub_f32_e32 v67, 1.0, v67
	v_add_f32_e32 v71, 1.0, v73
	v_mul_f32_e32 v77, 0.5, v53
	v_add_f32_e32 v67, 1.0, v67
	v_mul_f32_e32 v98, v77, v67
	v_mul_f32_e32 v73, 0x3d372713, v55
	v_mul_f32_e32 v73, v55, v73
	v_fma_f32 v73, v55, v73, v55
	v_mul_f32_e32 v73, 0x3f4c422a, v73
	v_add_f32_e32 v73, v73, v73
	v_mul_f32_e32 v73, 0x3fb8aa3b, v73
	v_exp_f32_e32 v73, v73
	v_rcp_f32_e32 v76, v71
	s_nop 0
	v_fma_f32 v67, -v71, v76, 1.0
	v_fma_f32 v76, v67, v76, v76
	v_add_f32_e32 v67, v76, v76
	v_div_fixup_f32 v67, v67, v71, 2.0
	v_sub_f32_e32 v67, 1.0, v67
	v_add_f32_e32 v71, 1.0, v73
	v_mul_f32_e32 v77, 0.5, v54
	v_add_f32_e32 v67, 1.0, v67
	v_mul_f32_e32 v86, v77, v67
	v_mul_f32_e32 v73, 0x3d372713, v48
	v_mul_f32_e32 v73, v48, v73
	v_fma_f32 v73, v48, v73, v48
	v_mul_f32_e32 v73, 0x3f4c422a, v73
	v_add_f32_e32 v73, v73, v73
	v_mul_f32_e32 v73, 0x3fb8aa3b, v73
	v_exp_f32_e32 v73, v73
	v_rcp_f32_e32 v76, v71
	s_nop 0
	v_fma_f32 v67, -v71, v76, 1.0
	v_fma_f32 v76, v67, v76, v76
	v_add_f32_e32 v67, v76, v76
	v_div_fixup_f32 v67, v67, v71, 2.0
	v_sub_f32_e32 v67, 1.0, v67
	v_add_f32_e32 v71, 1.0, v73
	v_mul_f32_e32 v76, 0.5, v55
	v_add_f32_e32 v67, 1.0, v67
	v_mul_f32_e32 v76, v76, v67
	v_mul_f32_e32 v73, 0x3d372713, v49
	v_mul_f32_e32 v73, v49, v73
	v_fma_f32 v73, v49, v73, v49
	v_mul_f32_e32 v73, 0x3f4c422a, v73
	v_add_f32_e32 v73, v73, v73
	v_mul_f32_e32 v73, 0x3fb8aa3b, v73
	v_exp_f32_e32 v73, v73
; #define SVSTAT ((float*)(kargs()->ws + O_SVSTAT))
; DEVFI float gelu_tanh(float x) {
;   float u = 0.7978845608028654f * (x + 0.044715f * x * x * x);
;   float t = __expf(2.f * u);
;   float th = 1.f - 2.f / (t + 1.f);
;   return 0.5f * x * (1.f + th);
; __global__ void __launch_bounds__(512) mega(Params p) {
;     ...
;                   } else if (c0 < 6144) {
; #pragma unroll
;                     for (int n = 0; n < 8; ++n)
; #pragma unroll
;                       for (int j = 0; j < 4; ++j) a[n][j] = gelu_tanh(a[n][j]);
;                     if (c0 >= 5120) { float* stp = SVSTAT + (long)r0 * 16 + ((c0 - 5120) >> 7) * 2;
	v_rcp_f32_e32 v77, v71
	s_nop 0
	v_fma_f32 v67, -v71, v77, 1.0
	v_fma_f32 v77, v67, v77, v77
	v_add_f32_e32 v67, v77, v77
	v_div_fixup_f32 v67, v67, v71, 2.0
	v_sub_f32_e32 v67, 1.0, v67
	v_add_f32_e32 v71, 1.0, v73
	v_mul_f32_e32 v81, 0.5, v48
	v_add_f32_e32 v67, 1.0, v67
	v_mul_f32_e32 v114, v81, v67
	v_mul_f32_e32 v73, 0x3d372713, v50
	v_mul_f32_e32 v73, v50, v73
	v_fma_f32 v73, v50, v73, v50
	v_mul_f32_e32 v73, 0x3f4c422a, v73
	v_add_f32_e32 v73, v73, v73
	v_mul_f32_e32 v73, 0x3fb8aa3b, v73
	v_exp_f32_e32 v73, v73
	v_rcp_f32_e32 v77, v71
	s_nop 0
	v_fma_f32 v67, -v71, v77, 1.0
	v_fma_f32 v77, v67, v77, v77
	v_add_f32_e32 v67, v77, v77
	v_div_fixup_f32 v67, v67, v71, 2.0
	v_sub_f32_e32 v67, 1.0, v67
	v_add_f32_e32 v71, 1.0, v73
	v_mul_f32_e32 v81, 0.5, v49
	v_add_f32_e32 v67, 1.0, v67
	v_mul_f32_e32 v108, v81, v67
	v_mul_f32_e32 v73, 0x3d372713, v51
	v_mul_f32_e32 v73, v51, v73
	v_fma_f32 v73, v51, v73, v51
	v_mul_f32_e32 v73, 0x3f4c422a, v73
	v_add_f32_e32 v73, v73, v73
	v_mul_f32_e32 v73, 0x3fb8aa3b, v73
	v_exp_f32_e32 v73, v73
	v_rcp_f32_e32 v77, v71
	s_nop 0
	v_fma_f32 v67, -v71, v77, 1.0
	v_fma_f32 v77, v67, v77, v77
	v_add_f32_e32 v67, v77, v77
	v_div_fixup_f32 v67, v67, v71, 2.0
	v_sub_f32_e32 v67, 1.0, v67
	v_add_f32_e32 v71, 1.0, v73
	v_mul_f32_e32 v81, 0.5, v50
	v_add_f32_e32 v67, 1.0, v67
	v_mul_f32_e32 v94, v81, v67
	v_mul_f32_e32 v73, 0x3d372713, v36
	v_mul_f32_e32 v73, v36, v73
	v_fma_f32 v73, v36, v73, v36
	v_mul_f32_e32 v73, 0x3f4c422a, v73
	v_add_f32_e32 v73, v73, v73
	v_mul_f32_e32 v73, 0x3fb8aa3b, v73
	v_exp_f32_e32 v73, v73
	v_rcp_f32_e32 v77, v71
	s_nop 0
	v_fma_f32 v67, -v71, v77, 1.0
	v_fma_f32 v77, v67, v77, v77
	v_add_f32_e32 v67, v77, v77
	v_div_fixup_f32 v67, v67, v71, 2.0
	v_sub_f32_e32 v67, 1.0, v67
	v_add_f32_e32 v71, 1.0, v73
	v_mul_f32_e32 v81, 0.5, v51
	v_add_f32_e32 v67, 1.0, v67
	v_mul_f32_e32 v84, v81, v67
	v_mul_f32_e32 v73, 0x3d372713, v37
	v_mul_f32_e32 v73, v37, v73
	v_fma_f32 v73, v37, v73, v37
	v_mul_f32_e32 v73, 0x3f4c422a, v73
	v_add_f32_e32 v73, v73, v73
	v_mul_f32_e32 v73, 0x3fb8aa3b, v73
	v_exp_f32_e32 v73, v73
	v_rcp_f32_e32 v77, v71
	s_nop 0
	v_fma_f32 v67, -v71, v77, 1.0
	v_fma_f32 v77, v67, v77, v77
	v_add_f32_e32 v67, v77, v77
	v_div_fixup_f32 v67, v67, v71, 2.0
	v_sub_f32_e32 v67, 1.0, v67
	v_add_f32_e32 v71, 1.0, v73
	v_mul_f32_e32 v81, 0.5, v36
	v_add_f32_e32 v67, 1.0, v67
	v_mul_f32_e32 v116, v81, v67
	v_mul_f32_e32 v73, 0x3d372713, v38
	v_mul_f32_e32 v73, v38, v73
	v_fma_f32 v73, v38, v73, v38
	v_mul_f32_e32 v73, 0x3f4c422a, v73
	v_add_f32_e32 v73, v73, v73
	v_mul_f32_e32 v73, 0x3fb8aa3b, v73
	v_exp_f32_e32 v73, v73
	v_rcp_f32_e32 v77, v71
	s_nop 0
	v_fma_f32 v67, -v71, v77, 1.0
	v_fma_f32 v77, v67, v77, v77
	v_add_f32_e32 v67, v77, v77
	v_div_fixup_f32 v67, v67, v71, 2.0
	v_sub_f32_e32 v67, 1.0, v67
	v_add_f32_e32 v71, 1.0, v73
	v_mul_f32_e32 v81, 0.5, v37
	v_add_f32_e32 v67, 1.0, v67
	v_mul_f32_e32 v112, v81, v67
	v_mul_f32_e32 v73, 0x3d372713, v39
	v_mul_f32_e32 v73, v39, v73
	v_fma_f32 v73, v39, v73, v39
	v_mul_f32_e32 v73, 0x3f4c422a, v73
	v_add_f32_e32 v73, v73, v73
	v_mul_f32_e32 v73, 0x3fb8aa3b, v73
	v_exp_f32_e32 v73, v73
	v_rcp_f32_e32 v77, v71
	s_nop 0
	v_fma_f32 v67, -v71, v77, 1.0
	v_fma_f32 v77, v67, v77, v77
	v_add_f32_e32 v67, v77, v77
	v_div_fixup_f32 v67, v67, v71, 2.0
	v_sub_f32_e32 v67, 1.0, v67
	v_add_f32_e32 v71, 1.0, v73
	v_mul_f32_e32 v81, 0.5, v38
	v_add_f32_e32 v67, 1.0, v67
	v_mul_f32_e32 v102, v81, v67
	v_mul_f32_e32 v73, 0x3d372713, v32
	v_mul_f32_e32 v73, v32, v73
	v_fma_f32 v73, v32, v73, v32
	v_mul_f32_e32 v73, 0x3f4c422a, v73
	v_add_f32_e32 v73, v73, v73
	v_mul_f32_e32 v73, 0x3fb8aa3b, v73
	v_exp_f32_e32 v73, v73
	v_rcp_f32_e32 v77, v71
	s_nop 0
	v_fma_f32 v67, -v71, v77, 1.0
	v_fma_f32 v77, v67, v77, v77
	v_add_f32_e32 v67, v77, v77
	v_div_fixup_f32 v67, v67, v71, 2.0
	v_sub_f32_e32 v67, 1.0, v67
	v_add_f32_e32 v71, 1.0, v73
	v_mul_f32_e32 v81, 0.5, v39
	v_add_f32_e32 v67, 1.0, v67
	v_mul_f32_e32 v88, v81, v67
	v_mul_f32_e32 v73, 0x3d372713, v33
	v_mul_f32_e32 v73, v33, v73
	v_fma_f32 v73, v33, v73, v33
	v_mul_f32_e32 v73, 0x3f4c422a, v73
	v_add_f32_e32 v73, v73, v73
	v_mul_f32_e32 v73, 0x3fb8aa3b, v73
	v_exp_f32_e32 v73, v73
	v_rcp_f32_e32 v77, v71
	s_nop 0
	v_fma_f32 v67, -v71, v77, 1.0
	v_fma_f32 v77, v67, v77, v77
	v_add_f32_e32 v67, v77, v77
	v_div_fixup_f32 v67, v67, v71, 2.0
	v_sub_f32_e32 v67, 1.0, v67
	v_add_f32_e32 v71, 1.0, v73
	v_mul_f32_e32 v81, 0.5, v32
	v_add_f32_e32 v67, 1.0, v67
	v_mul_f32_e32 v120, v81, v67
	v_mul_f32_e32 v73, 0x3d372713, v34
	v_mul_f32_e32 v73, v34, v73
	v_fma_f32 v73, v34, v73, v34
	v_mul_f32_e32 v73, 0x3f4c422a, v73
	v_add_f32_e32 v73, v73, v73
	v_mul_f32_e32 v73, 0x3fb8aa3b, v73
	v_exp_f32_e32 v73, v73
	v_rcp_f32_e32 v77, v71
	s_nop 0
	v_fma_f32 v67, -v71, v77, 1.0
	v_fma_f32 v77, v67, v77, v77
	v_add_f32_e32 v67, v77, v77
	v_div_fixup_f32 v67, v67, v71, 2.0
	v_sub_f32_e32 v67, 1.0, v67
	v_add_f32_e32 v71, 1.0, v73
	v_mul_f32_e32 v81, 0.5, v33
	v_add_f32_e32 v67, 1.0, v67
	v_mul_f32_e32 v118, v81, v67
	v_mul_f32_e32 v73, 0x3d372713, v35
	v_mul_f32_e32 v73, v35, v73
	v_fma_f32 v73, v35, v73, v35
	v_mul_f32_e32 v73, 0x3f4c422a, v73
	v_add_f32_e32 v73, v73, v73
	v_mul_f32_e32 v73, 0x3fb8aa3b, v73
	v_exp_f32_e32 v73, v73
	v_rcp_f32_e32 v77, v71
	s_nop 0
	v_fma_f32 v67, -v71, v77, 1.0
	v_fma_f32 v77, v67, v77, v77
	v_add_f32_e32 v67, v77, v77
	v_div_fixup_f32 v67, v67, v71, 2.0
	v_sub_f32_e32 v67, 1.0, v67
	v_add_f32_e32 v71, 1.0, v73
	v_mul_f32_e32 v81, 0.5, v34
	v_add_f32_e32 v67, 1.0, v67
	v_mul_f32_e32 v110, v81, v67
	v_rcp_f32_e32 v77, v71
	s_nop 0
	v_fma_f32 v67, -v71, v77, 1.0
	v_fma_f32 v77, v67, v77, v77
	v_add_f32_e32 v67, v77, v77
	v_div_fixup_f32 v67, v67, v71, 2.0
	v_sub_f32_e32 v67, 1.0, v67
	v_mul_f32_e32 v71, 0.5, v35
	v_add_f32_e32 v67, 1.0, v67
	v_mul_f32_e32 v100, v71, v67
	s_cbranch_scc1 .LBB0_1771
; DEVFI int lane_opaque() { unsigned m = ~0u; asm volatile("" : "+s"(m)); return (int)__builtin_amdgcn_mbcnt_hi(m, __builtin_amdgcn_mbcnt_lo(m, 0u)); }
; DEVFI float shx(float v, int mask, int lane) { return __int_as_float(__builtin_amdgcn_ds_bpermute((lane ^ mask) << 2, __float_as_int(v))); }
; #define SVSTAT ((float*)(kargs()->ws + O_SVSTAT))
; DEVFI float red16(float v) {
;   const int ln = lane_opaque();
;   v += shx(v, 1, ln); v += shx(v, 2, ln); v += shx(v, 4, ln); v += shx(v, 8, ln); return v;
; }
; __global__ void __launch_bounds__(512) mega(Params p) {
;     ...
;                     if (c0 >= 5120) { float* stp = SVSTAT + (long)r0 * 16 + ((c0 - 5120) >> 7) * 2;
; #pragma unroll
;                       for (int j = 0; j < 4; ++j) { float s1 = 0, s2 = 0;
; #pragma unroll
;                         for (int n = 0; n < 8; ++n) { s1 += a[n][j]; s2 += a[n][j] * a[n][j]; }
;                         s1 = red16(s1); s2 = red16(s2);
;                         if (fr == 0) { stp[j * 16] = s1; stp[j * 16 + 1] = s2; } } }
	s_mov_b64 s[2:3], s[0:1]
	s_load_dwordx2 s[2:3], s[2:3], 0xe8
	v_ashrrev_i32_e32 v97, 31, v96
	v_lshlrev_b64 v[122:123], 6, v[96:97]
	v_add_u32_e32 v67, 0xffffec00, v176
	v_lshrrev_b32_e32 v124, 4, v67
	s_waitcnt lgkmcnt(0)
	v_lshl_add_u64 v[122:123], s[2:3], 0, v[122:123]
	v_mov_b32_e32 v125, v177
	v_lshl_add_u64 v[122:123], v[122:123], 0, v[124:125]
	v_mov_b32_e32 v124, v177
	v_mov_b32_e32 v125, v79
	v_pk_add_f32 v[124:125], v[78:79], v[124:125]
	v_pk_mul_f32 v[126:127], v[78:79], v[78:79]
	s_mov_b64 s[2:3], 0x3a720400
	v_mov_b32_e32 v125, v127
	v_pk_mov_b32 v[126:127], v[78:79], v[126:127] op_sel:[1,0]
	v_lshl_add_u64 v[122:123], v[122:123], 0, s[2:3]
	v_mul_f32_e32 v91, v90, v90
	s_mov_b32 s2, -1
	v_pk_add_f32 v[124:125], v[124:125], v[126:127]
	v_mul_f32_e32 v105, v104, v104
	v_pk_add_f32 v[124:125], v[124:125], v[90:91]
	v_mbcnt_lo_u32_b32 v67, s2, 0
	v_mul_f32_e32 v107, v106, v106
	v_mbcnt_hi_u32_b32 v67, s2, v67
	s_mov_b32 s2, -1
	v_pk_add_f32 v[124:125], v[124:125], v[104:105]
	v_mul_f32_e32 v115, v114, v114
	v_pk_add_f32 v[124:125], v[124:125], v[106:107]
	v_mbcnt_lo_u32_b32 v81, s2, 0
	v_mul_f32_e32 v117, v116, v116
	v_mbcnt_hi_u32_b32 v81, s2, v81
	v_pk_add_f32 v[124:125], v[124:125], v[114:115]
	v_mul_f32_e32 v121, v120, v120
	v_lshlrev_b32_e32 v67, 2, v67
	v_lshlrev_b32_e32 v81, 2, v81
	v_pk_add_f32 v[124:125], v[124:125], v[116:117]
	v_xor_b32_e32 v71, 4, v67
	v_xor_b32_e32 v83, 4, v81
	v_pk_add_f32 v[124:125], v[124:125], v[120:121]
	ds_bpermute_b32 v126, v71, v124
	ds_bpermute_b32 v127, v83, v125
	v_xor_b32_e32 v73, 8, v67
	v_xor_b32_e32 v85, 8, v81
	v_xor_b32_e32 v77, 16, v67
	v_xor_b32_e32 v87, 16, v81
	s_waitcnt lgkmcnt(0)
	v_pk_add_f32 v[124:125], v[124:125], v[126:127]
	ds_bpermute_b32 v126, v73, v124
	ds_bpermute_b32 v127, v85, v125
	v_xor_b32_e32 v67, 32, v67
	v_cmp_eq_u32_e32 vcc, 0, v202
	s_waitcnt lgkmcnt(0)
	v_pk_add_f32 v[124:125], v[124:125], v[126:127]
	ds_bpermute_b32 v126, v77, v124
	ds_bpermute_b32 v127, v87, v125
	s_waitcnt lgkmcnt(0)
	v_pk_add_f32 v[124:125], v[124:125], v[126:127]
	ds_bpermute_b32 v126, v67, v124
	v_xor_b32_e32 v67, 32, v81
	ds_bpermute_b32 v127, v67, v125
	s_and_saveexec_b64 s[2:3], vcc
	s_cbranch_execz .LBB0_1764
	s_waitcnt lgkmcnt(0)
	v_pk_add_f32 v[124:125], v[124:125], v[126:127]
	global_store_dwordx2 v[122:123], v[124:125], off

; DEVFI float sigmoidf_(float x) { return 1.f / (1.f + __expf(-x)); }
; DEVFI float dpp_xor1(float x) { return __int_as_float(__builtin_amdgcn_update_dpp(0, __float_as_int(x), 0xB1, 0xF, 0xF, true)); }
; #define RG ((bfraw*)(kargs()->ws + O_RG))
; DEVFI void store_nat_m(bfraw* base, long ld, f32x4 (&a)[8], int fr) {
;   const bool odd = fr & 1;
;   bfraw* p0 = base + (odd ? 15 + fr : fr);
; #pragma unroll
;   for (int j = 0; j < 4; ++j)
; #pragma unroll
;     for (int n0 = 0; n0 < 8; n0 += 2) { const float own0 = a[n0][j], own1 = a[n0 + 1][j];
;       const float recv = dpp_xor1(odd ? own0 : own1);
;       const unsigned pk = odd ? cvtpk(recv, own1) : cvtpk(own0, recv);
;       *reinterpret_cast<unsigned*>(p0 + (long)j * ld + n0 * 16) = pk; }
; __global__ void __launch_bounds__(512) mega(Params p) {
;     ...
;                   } else if (c0 < 4096) {
; #pragma unroll
;                     for (int n = 0; n < 8; ++n)
; #pragma unroll
;                       for (int j = 0; j < 4; ++j) { const float x = a[n][j]; a[n][j] = x * sigmoidf_(x); }
;                     store_nat_m(RG + (long)r0 * 1024 + (c0 - 3072), 1024, a, fr);
.LBB0_1839:
	s_andn2_b64 vcc, exec, s[2:3]
	s_cbranch_vccnz .LBB0_1905
	v_mul_f32_e32 v64, 0xbfb8aa3b, v60
	v_exp_f32_e32 v64, v64
	s_nop 0
	v_add_f32_e32 v64, 1.0, v64
	s_nop 0
	v_rcp_f32_e32 v66, v64
	s_nop 0
	v_fma_f32 v65, -v64, v66, 1.0
	v_fma_f32 v65, v65, v66, v66
	v_div_fixup_f32 v64, v65, v64, 1.0
	v_mul_f32_e32 v65, 0xbfb8aa3b, v56
	v_exp_f32_e32 v65, v65
	v_mul_f32_e32 v64, v60, v64
	v_add_f32_e32 v65, 1.0, v65
	s_nop 0
	v_rcp_f32_e32 v67, v65
	s_nop 0
	v_fma_f32 v66, -v65, v67, 1.0
	v_fma_f32 v66, v66, v67, v67
	v_div_fixup_f32 v65, v66, v65, 1.0
	v_mul_f32_e32 v66, 0xbfb8aa3b, v44
	v_exp_f32_e32 v66, v66
	v_mul_f32_e32 v65, v56, v65
	v_add_f32_e32 v66, 1.0, v66
	s_nop 0
	v_rcp_f32_e32 v68, v66
	s_nop 0
	v_fma_f32 v67, -v66, v68, 1.0
	v_fma_f32 v68, v67, v68, v68
	v_mul_f32_e32 v67, 0xbfb8aa3b, v40
	v_exp_f32_e32 v67, v67
	s_nop 0
	v_add_f32_e32 v69, 1.0, v67
	s_mov_b64 s[2:3], s[0:1]
	s_load_dwordx2 s[2:3], s[2:3], 0xe8
	v_rcp_f32_e32 v70, v69
	s_nop 0
	v_fma_f32 v67, -v69, v70, 1.0
	v_fma_f32 v70, v67, v70, v70
	v_and_b32_e32 v67, 1, v203
	v_cmp_eq_u32_e64 s[8:9], 0, v67
	v_cmp_eq_u32_e64 s[6:7], 1, v67
	s_nop 0
	v_cndmask_b32_e64 v67, v64, v65, s[8:9]
	s_nop 1
	v_mov_b32_dpp v71, v67 quad_perm:[1,0,3,2] row_mask:0xf bank_mask:0xf bound_ctrl:1
	s_and_saveexec_b64 s[36:37], s[6:7]
	s_xor_b64 s[36:37], exec, s[36:37]
	s_cbranch_execz .LBB0_1842
	v_cvt_pk_bf16_f32 v67, v71, v65

; DEVFI float sigmoidf_(float x) { return 1.f / (1.f + __expf(-x)); }
; DEVFI float dpp_xor1(float x) { return __int_as_float(__builtin_amdgcn_update_dpp(0, __float_as_int(x), 0xB1, 0xF, 0xF, true)); }
; #define RG ((bfraw*)(kargs()->ws + O_RG))
; DEVFI void store_nat_m(bfraw* base, long ld, f32x4 (&a)[8], int fr) {
;   const bool odd = fr & 1;
;   bfraw* p0 = base + (odd ? 15 + fr : fr);
; #pragma unroll
;   for (int j = 0; j < 4; ++j)
; #pragma unroll
;     for (int n0 = 0; n0 < 8; n0 += 2) { const float own0 = a[n0][j], own1 = a[n0 + 1][j];
;       const float recv = dpp_xor1(odd ? own0 : own1);
;       const unsigned pk = odd ? cvtpk(recv, own1) : cvtpk(own0, recv);
;       *reinterpret_cast<unsigned*>(p0 + (long)j * ld + n0 * 16) = pk; }
; }
; __global__ void __launch_bounds__(512) mega(Params p) {
;     ...
;                   } else if (c0 < 4096) {
; #pragma unroll
;                     for (int n = 0; n < 8; ++n)
; #pragma unroll
;                       for (int j = 0; j < 4; ++j) { const float x = a[n][j]; a[n][j] = x * sigmoidf_(x); }
;                     store_nat_m(RG + (long)r0 * 1024 + (c0 - 3072), 1024, a, fr);
.LBB0_1844:
	s_or_b64 exec, exec, s[36:37]
	v_mul_f32_e32 v64, 0xbfb8aa3b, v52
	v_exp_f32_e32 v64, v64
	v_ashrrev_i32_e32 v97, 31, v96
	v_add_f32_e32 v70, 1.0, v64
	s_nop 0
	v_rcp_f32_e32 v65, v70
	s_nop 0
	v_fma_f32 v64, -v70, v65, 1.0
	v_fma_f32 v71, v64, v65, v65
	v_mul_f32_e32 v64, 0xbfb8aa3b, v48
	v_exp_f32_e32 v64, v64
	s_nop 0
	v_add_f32_e32 v72, 1.0, v64
	s_nop 0
	v_rcp_f32_e32 v65, v72
	s_nop 0
	v_fma_f32 v64, -v72, v65, 1.0
	v_fma_f32 v73, v64, v65, v65
	v_lshlrev_b64 v[64:65], 11, v[96:97]
	v_add_u32_e32 v74, 15, v202
	s_waitcnt lgkmcnt(0)
	v_lshl_add_u64 v[64:65], s[2:3], 0, v[64:65]
	v_cndmask_b32_e64 v74, v74, v202, s[8:9]
	v_lshl_add_u64 v[64:65], v[176:177], 1, v[64:65]
	v_lshlrev_b32_e32 v74, 1, v74
	v_mov_b32_e32 v75, v177
	v_lshl_add_u64 v[64:65], v[64:65], 0, v[74:75]
	v_add_co_u32_e32 v74, vcc, 0x1971e000, v64
	s_nop 1
	v_addc_co_u32_e32 v75, vcc, 0, v65, vcc
	global_store_dword v[74:75], v67, off offset:2048
	v_mov_b32_dpp v74, v69 quad_perm:[1,0,3,2] row_mask:0xf bank_mask:0xf bound_ctrl:1
	s_and_saveexec_b64 s[2:3], s[6:7]
	s_xor_b64 s[2:3], exec, s[2:3]
	s_cbranch_execz .LBB0_1846
	v_cvt_pk_bf16_f32 v69, v74, v68

; DEVFI float sigmoidf_(float x) { return 1.f / (1.f + __expf(-x)); }
; DEVFI float dpp_xor1(float x) { return __int_as_float(__builtin_amdgcn_update_dpp(0, __float_as_int(x), 0xB1, 0xF, 0xF, true)); }
; #define RG ((bfraw*)(kargs()->ws + O_RG))
; DEVFI void store_nat_m(bfraw* base, long ld, f32x4 (&a)[8], int fr) {
;   const bool odd = fr & 1;
;   bfraw* p0 = base + (odd ? 15 + fr : fr);
; #pragma unroll
;   for (int j = 0; j < 4; ++j)
; #pragma unroll
;     for (int n0 = 0; n0 < 8; n0 += 2) { const float own0 = a[n0][j], own1 = a[n0 + 1][j];
;       const float recv = dpp_xor1(odd ? own0 : own1);
;       const unsigned pk = odd ? cvtpk(recv, own1) : cvtpk(own0, recv);
;       *reinterpret_cast<unsigned*>(p0 + (long)j * ld + n0 * 16) = pk; }
; }
; __global__ void __launch_bounds__(512) mega(Params p) {
;     ...
;                   } else if (c0 < 4096) {
; #pragma unroll
;                     for (int n = 0; n < 8; ++n)
; #pragma unroll
;                       for (int j = 0; j < 4; ++j) { const float x = a[n][j]; a[n][j] = x * sigmoidf_(x); }
;                     store_nat_m(RG + (long)r0 * 1024 + (c0 - 3072), 1024, a, fr);
.LBB0_1848:
	s_or_b64 exec, exec, s[2:3]
	v_mul_f32_e32 v66, 0xbfb8aa3b, v36
	v_exp_f32_e32 v66, v66
	s_mov_b64 s[2:3], 0x1971e800
	v_lshl_add_u64 v[64:65], v[64:65], 0, s[2:3]
	global_store_dword v[64:65], v69, off offset:64
	v_add_f32_e32 v66, 1.0, v66
	s_nop 0
	v_rcp_f32_e32 v72, v66
	s_nop 0
	v_fma_f32 v71, -v66, v72, 1.0
	v_fma_f32 v71, v71, v72, v72
	v_mul_f32_e32 v72, 0xbfb8aa3b, v32
	v_exp_f32_e32 v72, v72
	s_nop 0
	v_add_f32_e32 v72, 1.0, v72
	s_nop 0
	v_rcp_f32_e32 v74, v72
	s_nop 0
	v_fma_f32 v73, -v72, v74, 1.0
	v_fma_f32 v74, v73, v74, v74
	s_nop 0
	v_mov_b32_dpp v73, v70 quad_perm:[1,0,3,2] row_mask:0xf bank_mask:0xf bound_ctrl:1
	s_and_saveexec_b64 s[2:3], s[6:7]
	s_xor_b64 s[2:3], exec, s[2:3]
	s_cbranch_execz .LBB0_1850
	v_cvt_pk_bf16_f32 v69, v73, v68

; DEVFI float sigmoidf_(float x) { return 1.f / (1.f + __expf(-x)); }
; DEVFI float dpp_xor1(float x) { return __int_as_float(__builtin_amdgcn_update_dpp(0, __float_as_int(x), 0xB1, 0xF, 0xF, true)); }
; #define RG ((bfraw*)(kargs()->ws + O_RG))
; DEVFI void store_nat_m(bfraw* base, long ld, f32x4 (&a)[8], int fr) {
;   const bool odd = fr & 1;
;   bfraw* p0 = base + (odd ? 15 + fr : fr);
; #pragma unroll
;   for (int j = 0; j < 4; ++j)
; #pragma unroll
;     for (int n0 = 0; n0 < 8; n0 += 2) { const float own0 = a[n0][j], own1 = a[n0 + 1][j];
;       const float recv = dpp_xor1(odd ? own0 : own1);
;       const unsigned pk = odd ? cvtpk(recv, own1) : cvtpk(own0, recv);
;       *reinterpret_cast<unsigned*>(p0 + (long)j * ld + n0 * 16) = pk; }
; }
; __global__ void __launch_bounds__(512) mega(Params p) {
;     ...
;                   } else if (c0 < 4096) {
; #pragma unroll
;                     for (int n = 0; n < 8; ++n)
; #pragma unroll
;                       for (int j = 0; j < 4; ++j) { const float x = a[n][j]; a[n][j] = x * sigmoidf_(x); }
;                     store_nat_m(RG + (long)r0 * 1024 + (c0 - 3072), 1024, a, fr);
.LBB0_1852:
	s_or_b64 exec, exec, s[2:3]
	v_mul_f32_e32 v67, 0xbfb8aa3b, v61
	v_exp_f32_e32 v67, v67
	global_store_dword v[64:65], v69, off offset:128
	v_add_f32_e32 v67, 1.0, v67
	s_nop 0
	v_rcp_f32_e32 v72, v67
	s_nop 0
	v_fma_f32 v71, -v67, v72, 1.0
	v_fma_f32 v71, v71, v72, v72
	v_mul_f32_e32 v72, 0xbfb8aa3b, v57
	v_exp_f32_e32 v72, v72
	s_nop 0
	v_add_f32_e32 v72, 1.0, v72
	s_nop 0
	v_rcp_f32_e32 v74, v72
	s_nop 0
	v_fma_f32 v73, -v72, v74, 1.0
	v_fma_f32 v74, v73, v74, v74
	s_nop 0
	v_mov_b32_dpp v73, v68 quad_perm:[1,0,3,2] row_mask:0xf bank_mask:0xf bound_ctrl:1
	s_and_saveexec_b64 s[2:3], s[6:7]
	s_xor_b64 s[2:3], exec, s[2:3]
	s_cbranch_execz .LBB0_1854
	v_cvt_pk_bf16_f32 v68, v73, v70

; DEVFI float sigmoidf_(float x) { return 1.f / (1.f + __expf(-x)); }
; DEVFI float dpp_xor1(float x) { return __int_as_float(__builtin_amdgcn_update_dpp(0, __float_as_int(x), 0xB1, 0xF, 0xF, true)); }
; #define RG ((bfraw*)(kargs()->ws + O_RG))
; DEVFI void store_nat_m(bfraw* base, long ld, f32x4 (&a)[8], int fr) {
;   const bool odd = fr & 1;
;   bfraw* p0 = base + (odd ? 15 + fr : fr);
; #pragma unroll
;   for (int j = 0; j < 4; ++j)
; #pragma unroll
;     for (int n0 = 0; n0 < 8; n0 += 2) { const float own0 = a[n0][j], own1 = a[n0 + 1][j];
;       const float recv = dpp_xor1(odd ? own0 : own1);
;       const unsigned pk = odd ? cvtpk(recv, own1) : cvtpk(own0, recv);
;       *reinterpret_cast<unsigned*>(p0 + (long)j * ld + n0 * 16) = pk; }
; }
; __global__ void __launch_bounds__(512) mega(Params p) {
;     ...
;                   } else if (c0 < 4096) {
; #pragma unroll
;                     for (int n = 0; n < 8; ++n)
; #pragma unroll
;                       for (int j = 0; j < 4; ++j) { const float x = a[n][j]; a[n][j] = x * sigmoidf_(x); }
;                     store_nat_m(RG + (long)r0 * 1024 + (c0 - 3072), 1024, a, fr);
.LBB0_1856:
	s_or_b64 exec, exec, s[2:3]
	v_mul_f32_e32 v66, 0xbfb8aa3b, v45
	v_exp_f32_e32 v66, v66
	global_store_dword v[64:65], v68, off offset:192
	v_add_f32_e32 v66, 1.0, v66
	s_nop 0
	v_rcp_f32_e32 v72, v66
	s_nop 0
	v_fma_f32 v70, -v66, v72, 1.0
	v_fma_f32 v70, v70, v72, v72
	v_mul_f32_e32 v72, 0xbfb8aa3b, v41
	v_exp_f32_e32 v72, v72
	s_nop 0
	v_add_f32_e32 v72, 1.0, v72
	s_nop 0
	v_rcp_f32_e32 v74, v72
	s_nop 0
	v_fma_f32 v73, -v72, v74, 1.0
	v_fma_f32 v74, v73, v74, v74
	s_nop 0
	v_mov_b32_dpp v73, v71 quad_perm:[1,0,3,2] row_mask:0xf bank_mask:0xf bound_ctrl:1
	s_and_saveexec_b64 s[2:3], s[6:7]
	s_xor_b64 s[2:3], exec, s[2:3]
	s_cbranch_execz .LBB0_1858
	v_cvt_pk_bf16_f32 v68, v73, v69

; DEVFI float sigmoidf_(float x) { return 1.f / (1.f + __expf(-x)); }
; DEVFI float dpp_xor1(float x) { return __int_as_float(__builtin_amdgcn_update_dpp(0, __float_as_int(x), 0xB1, 0xF, 0xF, true)); }
; #define RG ((bfraw*)(kargs()->ws + O_RG))
; DEVFI void store_nat_m(bfraw* base, long ld, f32x4 (&a)[8], int fr) {
;   const bool odd = fr & 1;
;   bfraw* p0 = base + (odd ? 15 + fr : fr);
; #pragma unroll
;   for (int j = 0; j < 4; ++j)
; #pragma unroll
;     for (int n0 = 0; n0 < 8; n0 += 2) { const float own0 = a[n0][j], own1 = a[n0 + 1][j];
;       const float recv = dpp_xor1(odd ? own0 : own1);
;       const unsigned pk = odd ? cvtpk(recv, own1) : cvtpk(own0, recv);
;       *reinterpret_cast<unsigned*>(p0 + (long)j * ld + n0 * 16) = pk; }
; }
; __global__ void __launch_bounds__(512) mega(Params p) {
;     ...
;                   } else if (c0 < 4096) {
; #pragma unroll
;                     for (int n = 0; n < 8; ++n)
; #pragma unroll
;                       for (int j = 0; j < 4; ++j) { const float x = a[n][j]; a[n][j] = x * sigmoidf_(x); }
;                     store_nat_m(RG + (long)r0 * 1024 + (c0 - 3072), 1024, a, fr);
.LBB0_1860:
	s_or_b64 exec, exec, s[2:3]
	v_mul_f32_e32 v67, 0xbfb8aa3b, v53
	v_exp_f32_e32 v67, v67
	global_store_dword v[64:65], v68, off offset:2048
	v_add_f32_e32 v67, 1.0, v67
	s_nop 0
	v_rcp_f32_e32 v72, v67
	s_nop 0
	v_fma_f32 v70, -v67, v72, 1.0
	v_fma_f32 v70, v70, v72, v72
	v_mul_f32_e32 v72, 0xbfb8aa3b, v49
	v_exp_f32_e32 v72, v72
	s_nop 0
	v_add_f32_e32 v72, 1.0, v72
	s_nop 0
	v_rcp_f32_e32 v74, v72
	s_nop 0
	v_fma_f32 v73, -v72, v74, 1.0
	v_fma_f32 v74, v73, v74, v74
	s_nop 0
	v_mov_b32_dpp v73, v71 quad_perm:[1,0,3,2] row_mask:0xf bank_mask:0xf bound_ctrl:1
	s_and_saveexec_b64 s[2:3], s[6:7]
	s_xor_b64 s[2:3], exec, s[2:3]
	s_cbranch_execz .LBB0_1862
	v_cvt_pk_bf16_f32 v68, v73, v69

; DEVFI float sigmoidf_(float x) { return 1.f / (1.f + __expf(-x)); }
; DEVFI float dpp_xor1(float x) { return __int_as_float(__builtin_amdgcn_update_dpp(0, __float_as_int(x), 0xB1, 0xF, 0xF, true)); }
; #define RG ((bfraw*)(kargs()->ws + O_RG))
; DEVFI void store_nat_m(bfraw* base, long ld, f32x4 (&a)[8], int fr) {
;   const bool odd = fr & 1;
;   bfraw* p0 = base + (odd ? 15 + fr : fr);
; #pragma unroll
;   for (int j = 0; j < 4; ++j)
; #pragma unroll
;     for (int n0 = 0; n0 < 8; n0 += 2) { const float own0 = a[n0][j], own1 = a[n0 + 1][j];
;       const float recv = dpp_xor1(odd ? own0 : own1);
;       const unsigned pk = odd ? cvtpk(recv, own1) : cvtpk(own0, recv);
;       *reinterpret_cast<unsigned*>(p0 + (long)j * ld + n0 * 16) = pk; }
; }
; __global__ void __launch_bounds__(512) mega(Params p) {
;     ...
;                   } else if (c0 < 4096) {
; #pragma unroll
;                     for (int n = 0; n < 8; ++n)
; #pragma unroll
;                       for (int j = 0; j < 4; ++j) { const float x = a[n][j]; a[n][j] = x * sigmoidf_(x); }
;                     store_nat_m(RG + (long)r0 * 1024 + (c0 - 3072), 1024, a, fr);
.LBB0_1864:
	s_or_b64 exec, exec, s[2:3]
	v_mul_f32_e32 v66, 0xbfb8aa3b, v37
	v_exp_f32_e32 v66, v66
	global_store_dword v[64:65], v68, off offset:2112
	v_add_f32_e32 v66, 1.0, v66
	s_nop 0
	v_rcp_f32_e32 v72, v66
	s_nop 0
	v_fma_f32 v70, -v66, v72, 1.0
	v_fma_f32 v70, v70, v72, v72
	v_mul_f32_e32 v72, 0xbfb8aa3b, v33
	v_exp_f32_e32 v72, v72
	s_nop 0
	v_add_f32_e32 v72, 1.0, v72
	s_nop 0
	v_rcp_f32_e32 v74, v72
	s_nop 0
	v_fma_f32 v73, -v72, v74, 1.0
	v_fma_f32 v74, v73, v74, v74
	s_nop 0
	v_mov_b32_dpp v73, v71 quad_perm:[1,0,3,2] row_mask:0xf bank_mask:0xf bound_ctrl:1
	s_and_saveexec_b64 s[2:3], s[6:7]
	s_xor_b64 s[2:3], exec, s[2:3]
	s_cbranch_execz .LBB0_1866
	v_cvt_pk_bf16_f32 v68, v73, v69

; DEVFI float sigmoidf_(float x) { return 1.f / (1.f + __expf(-x)); }
; DEVFI float dpp_xor1(float x) { return __int_as_float(__builtin_amdgcn_update_dpp(0, __float_as_int(x), 0xB1, 0xF, 0xF, true)); }
; #define RG ((bfraw*)(kargs()->ws + O_RG))
; DEVFI void store_nat_m(bfraw* base, long ld, f32x4 (&a)[8], int fr) {
;   const bool odd = fr & 1;
;   bfraw* p0 = base + (odd ? 15 + fr : fr);
; #pragma unroll
;   for (int j = 0; j < 4; ++j)
; #pragma unroll
;     for (int n0 = 0; n0 < 8; n0 += 2) { const float own0 = a[n0][j], own1 = a[n0 + 1][j];
;       const float recv = dpp_xor1(odd ? own0 : own1);
;       const unsigned pk = odd ? cvtpk(recv, own1) : cvtpk(own0, recv);
;       *reinterpret_cast<unsigned*>(p0 + (long)j * ld + n0 * 16) = pk; }
; }
; __global__ void __launch_bounds__(512) mega(Params p) {
;     ...
;                   } else if (c0 < 4096) {
; #pragma unroll
;                     for (int n = 0; n < 8; ++n)
; #pragma unroll
;                       for (int j = 0; j < 4; ++j) { const float x = a[n][j]; a[n][j] = x * sigmoidf_(x); }
;                     store_nat_m(RG + (long)r0 * 1024 + (c0 - 3072), 1024, a, fr);
.LBB0_1868:
	s_or_b64 exec, exec, s[2:3]
	v_mul_f32_e32 v67, 0xbfb8aa3b, v62
	v_exp_f32_e32 v67, v67
	global_store_dword v[64:65], v68, off offset:2176
	v_add_f32_e32 v67, 1.0, v67
	s_nop 0
	v_rcp_f32_e32 v72, v67
	s_nop 0
	v_fma_f32 v70, -v67, v72, 1.0
	v_fma_f32 v70, v70, v72, v72
	v_mul_f32_e32 v72, 0xbfb8aa3b, v58
	v_exp_f32_e32 v72, v72
	s_nop 0
	v_add_f32_e32 v72, 1.0, v72
	s_nop 0
	v_rcp_f32_e32 v74, v72
	s_nop 0
	v_fma_f32 v73, -v72, v74, 1.0
	v_fma_f32 v74, v73, v74, v74
	s_nop 0
	v_mov_b32_dpp v73, v71 quad_perm:[1,0,3,2] row_mask:0xf bank_mask:0xf bound_ctrl:1
	s_and_saveexec_b64 s[2:3], s[6:7]
	s_xor_b64 s[2:3], exec, s[2:3]
	s_cbranch_execz .LBB0_1870
	v_cvt_pk_bf16_f32 v68, v73, v69

; DEVFI float sigmoidf_(float x) { return 1.f / (1.f + __expf(-x)); }
; DEVFI float dpp_xor1(float x) { return __int_as_float(__builtin_amdgcn_update_dpp(0, __float_as_int(x), 0xB1, 0xF, 0xF, true)); }
; #define RG ((bfraw*)(kargs()->ws + O_RG))
; DEVFI void store_nat_m(bfraw* base, long ld, f32x4 (&a)[8], int fr) {
;   const bool odd = fr & 1;
;   bfraw* p0 = base + (odd ? 15 + fr : fr);
; #pragma unroll
;   for (int j = 0; j < 4; ++j)
; #pragma unroll
;     for (int n0 = 0; n0 < 8; n0 += 2) { const float own0 = a[n0][j], own1 = a[n0 + 1][j];
;       const float recv = dpp_xor1(odd ? own0 : own1);
;       const unsigned pk = odd ? cvtpk(recv, own1) : cvtpk(own0, recv);
;       *reinterpret_cast<unsigned*>(p0 + (long)j * ld + n0 * 16) = pk; }
; }
; __global__ void __launch_bounds__(512) mega(Params p) {
;     ...
;                   } else if (c0 < 4096) {
; #pragma unroll
;                     for (int n = 0; n < 8; ++n)
; #pragma unroll
;                       for (int j = 0; j < 4; ++j) { const float x = a[n][j]; a[n][j] = x * sigmoidf_(x); }
;                     store_nat_m(RG + (long)r0 * 1024 + (c0 - 3072), 1024, a, fr);
.LBB0_1872:
	s_or_b64 exec, exec, s[2:3]
	v_mul_f32_e32 v66, 0xbfb8aa3b, v46
	v_exp_f32_e32 v66, v66
	global_store_dword v[64:65], v68, off offset:2240
	v_add_f32_e32 v66, 1.0, v66
	s_nop 0
	v_rcp_f32_e32 v72, v66
	s_nop 0
	v_fma_f32 v70, -v66, v72, 1.0
	v_fma_f32 v70, v70, v72, v72
	v_mul_f32_e32 v72, 0xbfb8aa3b, v42
	v_exp_f32_e32 v72, v72
	s_nop 0
	v_add_f32_e32 v72, 1.0, v72
	s_nop 0
	v_rcp_f32_e32 v74, v72
	s_nop 0
	v_fma_f32 v73, -v72, v74, 1.0
	v_fma_f32 v74, v73, v74, v74
	s_nop 0
	v_mov_b32_dpp v73, v71 quad_perm:[1,0,3,2] row_mask:0xf bank_mask:0xf bound_ctrl:1
	s_and_saveexec_b64 s[2:3], s[6:7]
	s_xor_b64 s[2:3], exec, s[2:3]
	s_cbranch_execz .LBB0_1874
	v_cvt_pk_bf16_f32 v68, v73, v69

; DEVFI float sigmoidf_(float x) { return 1.f / (1.f + __expf(-x)); }
; DEVFI float dpp_xor1(float x) { return __int_as_float(__builtin_amdgcn_update_dpp(0, __float_as_int(x), 0xB1, 0xF, 0xF, true)); }
; #define RG ((bfraw*)(kargs()->ws + O_RG))
; DEVFI void store_nat_m(bfraw* base, long ld, f32x4 (&a)[8], int fr) {
;   const bool odd = fr & 1;
;   bfraw* p0 = base + (odd ? 15 + fr : fr);
; #pragma unroll
;   for (int j = 0; j < 4; ++j)
; #pragma unroll
;     for (int n0 = 0; n0 < 8; n0 += 2) { const float own0 = a[n0][j], own1 = a[n0 + 1][j];
;       const float recv = dpp_xor1(odd ? own0 : own1);
;       const unsigned pk = odd ? cvtpk(recv, own1) : cvtpk(own0, recv);
;       *reinterpret_cast<unsigned*>(p0 + (long)j * ld + n0 * 16) = pk; }
; }
; __global__ void __launch_bounds__(512) mega(Params p) {
;     ...
;                   } else if (c0 < 4096) {
; #pragma unroll
;                     for (int n = 0; n < 8; ++n)
; #pragma unroll
;                       for (int j = 0; j < 4; ++j) { const float x = a[n][j]; a[n][j] = x * sigmoidf_(x); }
;                     store_nat_m(RG + (long)r0 * 1024 + (c0 - 3072), 1024, a, fr);
.LBB0_1876:
	s_or_b64 exec, exec, s[2:3]
	v_mul_f32_e32 v67, 0xbfb8aa3b, v54
	v_exp_f32_e32 v67, v67
	s_nop 0
	v_add_f32_e32 v67, 1.0, v67
	s_nop 0
	v_rcp_f32_e32 v72, v67
	s_nop 0
	v_fma_f32 v70, -v67, v72, 1.0
	v_fma_f32 v70, v70, v72, v72
	v_mul_f32_e32 v72, 0xbfb8aa3b, v50
	v_exp_f32_e32 v72, v72
	s_nop 0
	v_add_f32_e32 v72, 1.0, v72
	s_nop 0
	v_rcp_f32_e32 v74, v72
	s_nop 0
	v_fma_f32 v73, -v72, v74, 1.0
	v_fma_f32 v73, v73, v74, v74
	v_add_co_u32_e32 v74, vcc, 0x1000, v64
	s_nop 1
	v_addc_co_u32_e32 v75, vcc, 0, v65, vcc
	global_store_dword v[74:75], v68, off
	v_mov_b32_dpp v74, v71 quad_perm:[1,0,3,2] row_mask:0xf bank_mask:0xf bound_ctrl:1
	s_and_saveexec_b64 s[2:3], s[6:7]
	s_xor_b64 s[2:3], exec, s[2:3]
	s_cbranch_execz .LBB0_1878
	v_cvt_pk_bf16_f32 v68, v74, v69

; DEVFI float sigmoidf_(float x) { return 1.f / (1.f + __expf(-x)); }
; DEVFI float dpp_xor1(float x) { return __int_as_float(__builtin_amdgcn_update_dpp(0, __float_as_int(x), 0xB1, 0xF, 0xF, true)); }
; #define RG ((bfraw*)(kargs()->ws + O_RG))
; DEVFI void store_nat_m(bfraw* base, long ld, f32x4 (&a)[8], int fr) {
;   const bool odd = fr & 1;
;   bfraw* p0 = base + (odd ? 15 + fr : fr);
; #pragma unroll
;   for (int j = 0; j < 4; ++j)
; #pragma unroll
;     for (int n0 = 0; n0 < 8; n0 += 2) { const float own0 = a[n0][j], own1 = a[n0 + 1][j];
;       const float recv = dpp_xor1(odd ? own0 : own1);
;       const unsigned pk = odd ? cvtpk(recv, own1) : cvtpk(own0, recv);
;       *reinterpret_cast<unsigned*>(p0 + (long)j * ld + n0 * 16) = pk; }
; }
; __global__ void __launch_bounds__(512) mega(Params p) {
;     ...
;                   } else if (c0 < 4096) {
; #pragma unroll
;                     for (int n = 0; n < 8; ++n)
; #pragma unroll
;                       for (int j = 0; j < 4; ++j) { const float x = a[n][j]; a[n][j] = x * sigmoidf_(x); }
;                     store_nat_m(RG + (long)r0 * 1024 + (c0 - 3072), 1024, a, fr);
.LBB0_1880:
	s_or_b64 exec, exec, s[2:3]
	v_mul_f32_e32 v66, 0xbfb8aa3b, v38
	v_exp_f32_e32 v66, v66
	s_nop 0
	v_add_f32_e32 v66, 1.0, v66
	s_nop 0
	v_rcp_f32_e32 v72, v66
	s_nop 0
	v_fma_f32 v70, -v66, v72, 1.0
	v_fma_f32 v70, v70, v72, v72
	v_mul_f32_e32 v72, 0xbfb8aa3b, v34
	v_exp_f32_e32 v72, v72
	s_nop 0
	v_add_f32_e32 v72, 1.0, v72
	s_nop 0
	v_rcp_f32_e32 v74, v72
	s_nop 0
	v_fma_f32 v73, -v72, v74, 1.0
	v_fma_f32 v73, v73, v74, v74
	v_add_co_u32_e32 v74, vcc, 0x1000, v64
	s_nop 1
	v_addc_co_u32_e32 v75, vcc, 0, v65, vcc
	global_store_dword v[74:75], v68, off offset:64
	v_mov_b32_dpp v74, v71 quad_perm:[1,0,3,2] row_mask:0xf bank_mask:0xf bound_ctrl:1
	s_and_saveexec_b64 s[2:3], s[6:7]
	s_xor_b64 s[2:3], exec, s[2:3]
	s_cbranch_execz .LBB0_1882
	v_cvt_pk_bf16_f32 v68, v74, v69

; DEVFI float sigmoidf_(float x) { return 1.f / (1.f + __expf(-x)); }
; DEVFI float dpp_xor1(float x) { return __int_as_float(__builtin_amdgcn_update_dpp(0, __float_as_int(x), 0xB1, 0xF, 0xF, true)); }
; #define RG ((bfraw*)(kargs()->ws + O_RG))
; DEVFI void store_nat_m(bfraw* base, long ld, f32x4 (&a)[8], int fr) {
;   const bool odd = fr & 1;
;   bfraw* p0 = base + (odd ? 15 + fr : fr);
; #pragma unroll
;   for (int j = 0; j < 4; ++j)
; #pragma unroll
;     for (int n0 = 0; n0 < 8; n0 += 2) { const float own0 = a[n0][j], own1 = a[n0 + 1][j];
;       const float recv = dpp_xor1(odd ? own0 : own1);
;       const unsigned pk = odd ? cvtpk(recv, own1) : cvtpk(own0, recv);
;       *reinterpret_cast<unsigned*>(p0 + (long)j * ld + n0 * 16) = pk; }
; }
; __global__ void __launch_bounds__(512) mega(Params p) {
;     ...
;                   } else if (c0 < 4096) {
; #pragma unroll
;                     for (int n = 0; n < 8; ++n)
; #pragma unroll
;                       for (int j = 0; j < 4; ++j) { const float x = a[n][j]; a[n][j] = x * sigmoidf_(x); }
;                     store_nat_m(RG + (long)r0 * 1024 + (c0 - 3072), 1024, a, fr);
.LBB0_1884:
	s_or_b64 exec, exec, s[2:3]
	v_mul_f32_e32 v67, 0xbfb8aa3b, v63
	v_exp_f32_e32 v67, v67
	s_nop 0
	v_add_f32_e32 v67, 1.0, v67
	s_nop 0
	v_rcp_f32_e32 v72, v67
	s_nop 0
	v_fma_f32 v70, -v67, v72, 1.0
	v_fma_f32 v70, v70, v72, v72
	v_mul_f32_e32 v72, 0xbfb8aa3b, v59
	v_exp_f32_e32 v72, v72
	s_nop 0
	v_add_f32_e32 v72, 1.0, v72
	s_nop 0
	v_rcp_f32_e32 v74, v72
	s_nop 0
	v_fma_f32 v73, -v72, v74, 1.0
	v_fma_f32 v73, v73, v74, v74
	v_add_co_u32_e32 v74, vcc, 0x1000, v64
	s_nop 1
	v_addc_co_u32_e32 v75, vcc, 0, v65, vcc
	global_store_dword v[74:75], v68, off offset:128
	v_mov_b32_dpp v74, v71 quad_perm:[1,0,3,2] row_mask:0xf bank_mask:0xf bound_ctrl:1
	s_and_saveexec_b64 s[2:3], s[6:7]
	s_xor_b64 s[2:3], exec, s[2:3]
	s_cbranch_execz .LBB0_1886
	v_cvt_pk_bf16_f32 v68, v74, v69

; DEVFI float sigmoidf_(float x) { return 1.f / (1.f + __expf(-x)); }
; DEVFI float dpp_xor1(float x) { return __int_as_float(__builtin_amdgcn_update_dpp(0, __float_as_int(x), 0xB1, 0xF, 0xF, true)); }
; #define RG ((bfraw*)(kargs()->ws + O_RG))
; DEVFI void store_nat_m(bfraw* base, long ld, f32x4 (&a)[8], int fr) {
;   const bool odd = fr & 1;
;   bfraw* p0 = base + (odd ? 15 + fr : fr);
; #pragma unroll
;   for (int j = 0; j < 4; ++j)
; #pragma unroll
;     for (int n0 = 0; n0 < 8; n0 += 2) { const float own0 = a[n0][j], own1 = a[n0 + 1][j];
;       const float recv = dpp_xor1(odd ? own0 : own1);
;       const unsigned pk = odd ? cvtpk(recv, own1) : cvtpk(own0, recv);
;       *reinterpret_cast<unsigned*>(p0 + (long)j * ld + n0 * 16) = pk; }
; }
; __global__ void __launch_bounds__(512) mega(Params p) {
;     ...
;                   } else if (c0 < 4096) {
; #pragma unroll
;                     for (int n = 0; n < 8; ++n)
; #pragma unroll
;                       for (int j = 0; j < 4; ++j) { const float x = a[n][j]; a[n][j] = x * sigmoidf_(x); }
;                     store_nat_m(RG + (long)r0 * 1024 + (c0 - 3072), 1024, a, fr);
.LBB0_1888:
	s_or_b64 exec, exec, s[2:3]
	v_mul_f32_e32 v66, 0xbfb8aa3b, v47
	v_exp_f32_e32 v66, v66
	s_nop 0
	v_add_f32_e32 v66, 1.0, v66
	s_nop 0
	v_rcp_f32_e32 v72, v66
	s_nop 0
	v_fma_f32 v70, -v66, v72, 1.0
	v_fma_f32 v70, v70, v72, v72
	v_mul_f32_e32 v72, 0xbfb8aa3b, v43
	v_exp_f32_e32 v72, v72
	s_nop 0
	v_add_f32_e32 v72, 1.0, v72
	s_nop 0
	v_rcp_f32_e32 v74, v72
	s_nop 0
	v_fma_f32 v73, -v72, v74, 1.0
	v_fma_f32 v73, v73, v74, v74
	v_add_co_u32_e32 v74, vcc, 0x1000, v64
	s_nop 1
	v_addc_co_u32_e32 v75, vcc, 0, v65, vcc
	global_store_dword v[74:75], v68, off offset:192
	v_mov_b32_dpp v74, v71 quad_perm:[1,0,3,2] row_mask:0xf bank_mask:0xf bound_ctrl:1
	s_and_saveexec_b64 s[2:3], s[6:7]
	s_xor_b64 s[2:3], exec, s[2:3]
	s_cbranch_execz .LBB0_1890
	v_cvt_pk_bf16_f32 v68, v74, v69

; DEVFI float sigmoidf_(float x) { return 1.f / (1.f + __expf(-x)); }
; DEVFI float dpp_xor1(float x) { return __int_as_float(__builtin_amdgcn_update_dpp(0, __float_as_int(x), 0xB1, 0xF, 0xF, true)); }
; #define RG ((bfraw*)(kargs()->ws + O_RG))
; DEVFI void store_nat_m(bfraw* base, long ld, f32x4 (&a)[8], int fr) {
;   const bool odd = fr & 1;
;   bfraw* p0 = base + (odd ? 15 + fr : fr);
; #pragma unroll
;   for (int j = 0; j < 4; ++j)
; #pragma unroll
;     for (int n0 = 0; n0 < 8; n0 += 2) { const float own0 = a[n0][j], own1 = a[n0 + 1][j];
;       const float recv = dpp_xor1(odd ? own0 : own1);
;       const unsigned pk = odd ? cvtpk(recv, own1) : cvtpk(own0, recv);
;       *reinterpret_cast<unsigned*>(p0 + (long)j * ld + n0 * 16) = pk; }
; }
; __global__ void __launch_bounds__(512) mega(Params p) {
;     ...
;                   } else if (c0 < 4096) {
; #pragma unroll
;                     for (int n = 0; n < 8; ++n)
; #pragma unroll
;                       for (int j = 0; j < 4; ++j) { const float x = a[n][j]; a[n][j] = x * sigmoidf_(x); }
;                     store_nat_m(RG + (long)r0 * 1024 + (c0 - 3072), 1024, a, fr);
.LBB0_1892:
	s_or_b64 exec, exec, s[2:3]
	v_mul_f32_e32 v67, 0xbfb8aa3b, v55
	v_exp_f32_e32 v67, v67
	s_nop 0
	v_add_f32_e32 v67, 1.0, v67
	s_nop 0
	v_rcp_f32_e32 v72, v67
	s_nop 0
	v_fma_f32 v70, -v67, v72, 1.0
	v_fma_f32 v70, v70, v72, v72
	v_mul_f32_e32 v72, 0xbfb8aa3b, v51
	v_exp_f32_e32 v72, v72
	s_nop 0
	v_add_f32_e32 v72, 1.0, v72
	s_nop 0
	v_rcp_f32_e32 v74, v72
	s_nop 0
	v_fma_f32 v73, -v72, v74, 1.0
	v_fma_f32 v73, v73, v74, v74
	v_add_co_u32_e32 v74, vcc, 0x1000, v64
	s_nop 1
	v_addc_co_u32_e32 v75, vcc, 0, v65, vcc
	global_store_dword v[74:75], v68, off offset:2048
	v_mov_b32_dpp v74, v71 quad_perm:[1,0,3,2] row_mask:0xf bank_mask:0xf bound_ctrl:1
	s_and_saveexec_b64 s[2:3], s[6:7]
	s_xor_b64 s[2:3], exec, s[2:3]
	s_cbranch_execz .LBB0_1894
	v_cvt_pk_bf16_f32 v68, v74, v69

; DEVFI float sigmoidf_(float x) { return 1.f / (1.f + __expf(-x)); }
; DEVFI float dpp_xor1(float x) { return __int_as_float(__builtin_amdgcn_update_dpp(0, __float_as_int(x), 0xB1, 0xF, 0xF, true)); }
; #define RG ((bfraw*)(kargs()->ws + O_RG))
; DEVFI void store_nat_m(bfraw* base, long ld, f32x4 (&a)[8], int fr) {
;   const bool odd = fr & 1;
;   bfraw* p0 = base + (odd ? 15 + fr : fr);
; #pragma unroll
;   for (int j = 0; j < 4; ++j)
; #pragma unroll
;     for (int n0 = 0; n0 < 8; n0 += 2) { const float own0 = a[n0][j], own1 = a[n0 + 1][j];
;       const float recv = dpp_xor1(odd ? own0 : own1);
;       const unsigned pk = odd ? cvtpk(recv, own1) : cvtpk(own0, recv);
;       *reinterpret_cast<unsigned*>(p0 + (long)j * ld + n0 * 16) = pk; }
; }
; __global__ void __launch_bounds__(512) mega(Params p) {
;     ...
;                   } else if (c0 < 4096) {
; #pragma unroll
;                     for (int n = 0; n < 8; ++n)
; #pragma unroll
;                       for (int j = 0; j < 4; ++j) { const float x = a[n][j]; a[n][j] = x * sigmoidf_(x); }
;                     store_nat_m(RG + (long)r0 * 1024 + (c0 - 3072), 1024, a, fr);
.LBB0_1896:
	s_or_b64 exec, exec, s[2:3]
	v_mul_f32_e32 v66, 0xbfb8aa3b, v39
	v_exp_f32_e32 v66, v66
	v_mov_b32_dpp v71, v71 quad_perm:[1,0,3,2] row_mask:0xf bank_mask:0xf bound_ctrl:1
	v_add_f32_e32 v66, 1.0, v66
	s_nop 0
	v_rcp_f32_e32 v72, v66
	s_nop 0
	v_fma_f32 v70, -v66, v72, 1.0
	v_fma_f32 v70, v70, v72, v72
	v_mul_f32_e32 v72, 0xbfb8aa3b, v35
	v_exp_f32_e32 v72, v72
	s_nop 0
	v_add_f32_e32 v72, 1.0, v72
	s_nop 0
	v_rcp_f32_e32 v74, v72
	s_nop 0
	v_fma_f32 v73, -v72, v74, 1.0
	v_fma_f32 v73, v73, v74, v74
	v_add_co_u32_e32 v74, vcc, 0x1000, v64
	s_nop 1
	v_addc_co_u32_e32 v75, vcc, 0, v65, vcc
	global_store_dword v[74:75], v68, off offset:2112
	s_and_saveexec_b64 s[2:3], s[6:7]
	s_xor_b64 s[2:3], exec, s[2:3]
	s_cbranch_execz .LBB0_1898
	v_cvt_pk_bf16_f32 v68, v71, v69

; DEVFI float sigmoidf_(float x) { return 1.f / (1.f + __expf(-x)); }
; #define GATES ((bfraw*)(kargs()->ws + O_GATES))
; __global__ void __launch_bounds__(512) mega(Params p) {
;     ...
;                   } else {
; #pragma unroll
;                     for (int n = 0; n < 8; ++n) { const float bb = hv[n];
; #pragma unroll
;                       for (int j = 0; j < 4; ++j) a[n][j] = sigmoidf_(a[n][j] + bb); }
;                     const int gt0 = bcol - 7680, tidn = ((wr0 >> 6) * 2 + (wc0 >> 7)) * 64 + fq * 16 + fr;
;                     bfraw* gt = GATES + ((long)(((brow >> 8) * 3 + (gt0 >> 10)) * 4 + ((gt0 >> 8) & 3))) * 65536 + (long)(m * 4 * 512 + tidn) * 8;
; #pragma unroll
;                     for (int q = 0; q < 4; ++q) { u32x4 w4 = {cvtpk(a[2 * q][0], a[2 * q][1]), cvtpk(a[2 * q][2], a[2 * q][3]), cvtpk(a[2 * q + 1][0], a[2 * q + 1][1]), cvtpk(a[2 * q + 1][2], a[2 * q + 1][3])};
;                       *(u32x4*)(gt + q * 512 * 8) = w4; }
;                   }
.LBB0_1980:
	s_or_b64 exec, exec, s[36:37]
	v_add3_u32 v64, s76, v225, 48
	s_and_saveexec_b64 s[2:3], s[4:5]
	s_xor_b64 s[8:9], exec, s[2:3]
	s_cbranch_execz .LBB0_2340
	s_cmpk_gt_u32 s26, 0xbff
	s_mov_b64 s[2:3], -1
	s_cbranch_scc0 .LBB0_2338
	s_cmpk_gt_u32 s26, 0xfff
	s_cbranch_scc0 .LBB0_2271
	s_cmpk_gt_u32 s26, 0x17ff
	s_cbranch_scc0 .LBB0_2192
	s_cmpk_gt_u32 s26, 0x1cff
	s_cbranch_scc0 .LBB0_2054
	s_cmpk_lt_u32 s26, 0x1e00
	s_cbranch_scc1 .LBB0_1987
	s_waitcnt vmcnt(0)
	v_add_f32_e32 v32, v28, v224
	v_mul_f32_e32 v32, 0xbfb8aa3b, v32
	v_exp_f32_e32 v32, v32
	s_add_i32 s4, s26, 0xffffe200
	s_ashr_i32 s5, s76, 8
	s_mul_i32 s5, s5, 3
	v_add_f32_e32 v32, 1.0, v32
	s_ashr_i32 s6, s4, 10
	s_add_i32 s6, s6, s5
	s_lshl_b32 s5, s6, 2
	v_rcp_f32_e32 v34, v32
	s_nop 0
	v_fma_f32 v33, -v32, v34, 1.0
	v_fma_f32 v33, v33, v34, v34
	v_div_fixup_f32 v32, v33, v32, 1.0
	v_add_f32_e32 v33, v29, v224
	v_mul_f32_e32 v33, 0xbfb8aa3b, v33
	v_exp_f32_e32 v33, v33
	s_bfe_u32 s4, s4, 0x20008
	s_or_b32 s4, s5, s4
	s_ashr_i32 s5, s4, 31
	v_add_f32_e32 v33, 1.0, v33
	s_lshl_b64 s[4:5], s[4:5], 17
	v_rcp_f32_e32 v35, v33
	s_nop 0
	v_fma_f32 v34, -v33, v35, 1.0
	v_fma_f32 v34, v34, v35, v35
	v_div_fixup_f32 v33, v34, v33, 1.0
	v_add_f32_e32 v34, v30, v224
	v_mul_f32_e32 v34, 0xbfb8aa3b, v34
	v_exp_f32_e32 v34, v34
	s_nop 0
	v_add_f32_e32 v34, 1.0, v34
	s_nop 0
	v_rcp_f32_e32 v36, v34
	s_nop 0
	v_fma_f32 v35, -v34, v36, 1.0
	v_fma_f32 v35, v35, v36, v36
	v_div_fixup_f32 v34, v35, v34, 1.0
	v_add_f32_e32 v35, v31, v224
	v_mul_f32_e32 v35, 0xbfb8aa3b, v35
	v_exp_f32_e32 v35, v35
	s_nop 0
	v_add_f32_e32 v35, 1.0, v35
	s_nop 0
	v_rcp_f32_e32 v37, v35
	s_nop 0
	v_fma_f32 v36, -v35, v37, 1.0
	v_fma_f32 v36, v36, v37, v37
	v_div_fixup_f32 v35, v36, v35, 1.0
	v_add_f32_e32 v36, v24, v223
	v_mul_f32_e32 v36, 0xbfb8aa3b, v36
	v_exp_f32_e32 v36, v36
	s_nop 0
	v_add_f32_e32 v36, 1.0, v36
	s_nop 0
	v_rcp_f32_e32 v38, v36
	s_nop 0
	v_fma_f32 v37, -v36, v38, 1.0
	v_fma_f32 v37, v37, v38, v38
	v_div_fixup_f32 v36, v37, v36, 1.0
	v_add_f32_e32 v37, v25, v223
	v_mul_f32_e32 v37, 0xbfb8aa3b, v37
	v_exp_f32_e32 v37, v37
	s_nop 0
	v_add_f32_e32 v37, 1.0, v37
	s_nop 0
	v_rcp_f32_e32 v39, v37
	s_nop 0
	v_fma_f32 v38, -v37, v39, 1.0
	v_fma_f32 v38, v38, v39, v39
	v_div_fixup_f32 v37, v38, v37, 1.0
	v_add_f32_e32 v38, v26, v223
	v_mul_f32_e32 v38, 0xbfb8aa3b, v38
	v_exp_f32_e32 v38, v38
	s_nop 0
	v_add_f32_e32 v38, 1.0, v38
	s_nop 0
	v_rcp_f32_e32 v40, v38
	s_nop 0
	v_fma_f32 v39, -v38, v40, 1.0
	v_fma_f32 v39, v39, v40, v40
	v_div_fixup_f32 v38, v39, v38, 1.0
	v_add_f32_e32 v39, v27, v223
	v_mul_f32_e32 v39, 0xbfb8aa3b, v39
	v_exp_f32_e32 v39, v39
	s_nop 0
	v_add_f32_e32 v39, 1.0, v39
	s_nop 0
	v_rcp_f32_e32 v41, v39
	s_nop 0
	v_fma_f32 v40, -v39, v41, 1.0
	v_fma_f32 v40, v40, v41, v41
	v_div_fixup_f32 v39, v40, v39, 1.0
	v_add_f32_e32 v40, v12, v212
	v_mul_f32_e32 v40, 0xbfb8aa3b, v40
	v_exp_f32_e32 v40, v40
	s_nop 0
	v_add_f32_e32 v40, 1.0, v40
	s_nop 0
	v_rcp_f32_e32 v42, v40
	s_nop 0
	v_fma_f32 v41, -v40, v42, 1.0
	v_fma_f32 v41, v41, v42, v42
	v_div_fixup_f32 v40, v41, v40, 1.0
	v_add_f32_e32 v41, v13, v212
	v_mul_f32_e32 v41, 0xbfb8aa3b, v41
	v_exp_f32_e32 v41, v41
	s_nop 0
	v_add_f32_e32 v41, 1.0, v41
	s_nop 0
	v_rcp_f32_e32 v43, v41
	s_nop 0
	v_fma_f32 v42, -v41, v43, 1.0
	v_fma_f32 v42, v42, v43, v43
	v_div_fixup_f32 v41, v42, v41, 1.0
	v_add_f32_e32 v42, v14, v212
	v_mul_f32_e32 v42, 0xbfb8aa3b, v42
	v_exp_f32_e32 v42, v42
	s_nop 0
	v_add_f32_e32 v42, 1.0, v42
	s_nop 0
	v_rcp_f32_e32 v44, v42
	s_nop 0
	v_fma_f32 v43, -v42, v44, 1.0
	v_fma_f32 v43, v43, v44, v44
	v_div_fixup_f32 v42, v43, v42, 1.0
	v_add_f32_e32 v43, v15, v212
	v_mul_f32_e32 v43, 0xbfb8aa3b, v43
	v_exp_f32_e32 v43, v43
	s_nop 0
	v_add_f32_e32 v43, 1.0, v43
	s_nop 0
	v_rcp_f32_e32 v45, v43
	s_nop 0
	v_fma_f32 v44, -v43, v45, 1.0
	v_fma_f32 v44, v44, v45, v45
	v_div_fixup_f32 v43, v44, v43, 1.0
	v_add_f32_e32 v44, v8, v211
	v_mul_f32_e32 v44, 0xbfb8aa3b, v44
	v_exp_f32_e32 v44, v44
	s_nop 0
	v_add_f32_e32 v44, 1.0, v44
	s_nop 0
	v_rcp_f32_e32 v46, v44
	s_nop 0
	v_fma_f32 v45, -v44, v46, 1.0
	v_fma_f32 v45, v45, v46, v46
	v_div_fixup_f32 v44, v45, v44, 1.0
	v_add_f32_e32 v45, v9, v211
	v_mul_f32_e32 v45, 0xbfb8aa3b, v45
	v_exp_f32_e32 v45, v45
	s_nop 0
	v_add_f32_e32 v45, 1.0, v45
	s_nop 0
	v_rcp_f32_e32 v47, v45
	s_nop 0
	v_fma_f32 v46, -v45, v47, 1.0
	v_fma_f32 v46, v46, v47, v47
	v_div_fixup_f32 v45, v46, v45, 1.0
	v_add_f32_e32 v46, v10, v211
	v_mul_f32_e32 v46, 0xbfb8aa3b, v46
	v_exp_f32_e32 v46, v46
	s_nop 0
	v_add_f32_e32 v46, 1.0, v46
	s_nop 0
	v_rcp_f32_e32 v48, v46
	s_nop 0
	v_fma_f32 v47, -v46, v48, 1.0
	v_fma_f32 v47, v47, v48, v48
	v_div_fixup_f32 v46, v47, v46, 1.0
	v_add_f32_e32 v47, v11, v211
	v_mul_f32_e32 v47, 0xbfb8aa3b, v47
	v_exp_f32_e32 v47, v47
	s_nop 0
	v_add_f32_e32 v47, 1.0, v47
	s_nop 0
	v_rcp_f32_e32 v49, v47
	s_nop 0
	v_fma_f32 v48, -v47, v49, 1.0
	v_fma_f32 v48, v48, v49, v49
	v_div_fixup_f32 v47, v48, v47, 1.0
	v_add_f32_e32 v48, v20, v210
	v_mul_f32_e32 v48, 0xbfb8aa3b, v48
	v_exp_f32_e32 v48, v48
	s_nop 0
	v_add_f32_e32 v48, 1.0, v48
	s_nop 0
	v_rcp_f32_e32 v50, v48
	s_nop 0
	v_fma_f32 v49, -v48, v50, 1.0
	v_fma_f32 v49, v49, v50, v50
	v_div_fixup_f32 v48, v49, v48, 1.0
	v_add_f32_e32 v49, v21, v210
	v_mul_f32_e32 v49, 0xbfb8aa3b, v49
	v_exp_f32_e32 v49, v49
	s_nop 0
; DEVFI float sigmoidf_(float x) { return 1.f / (1.f + __expf(-x)); }
; #define GATES ((bfraw*)(kargs()->ws + O_GATES))
; __global__ void __launch_bounds__(512) mega(Params p) {
;     ...
;                   } else {
; #pragma unroll
;                     for (int n = 0; n < 8; ++n) { const float bb = hv[n];
; #pragma unroll
;                       for (int j = 0; j < 4; ++j) a[n][j] = sigmoidf_(a[n][j] + bb); }
;                     const int gt0 = bcol - 7680, tidn = ((wr0 >> 6) * 2 + (wc0 >> 7)) * 64 + fq * 16 + fr;
;                     bfraw* gt = GATES + ((long)(((brow >> 8) * 3 + (gt0 >> 10)) * 4 + ((gt0 >> 8) & 3))) * 65536 + (long)(m * 4 * 512 + tidn) * 8;
; #pragma unroll
;                     for (int q = 0; q < 4; ++q) { u32x4 w4 = {cvtpk(a[2 * q][0], a[2 * q][1]), cvtpk(a[2 * q][2], a[2 * q][3]), cvtpk(a[2 * q + 1][0], a[2 * q + 1][1]), cvtpk(a[2 * q + 1][2], a[2 * q + 1][3])};
;                       *(u32x4*)(gt + q * 512 * 8) = w4; }
;                   }
	v_add_f32_e32 v49, 1.0, v49
	s_nop 0
	v_rcp_f32_e32 v51, v49
	s_nop 0
	v_fma_f32 v50, -v49, v51, 1.0
	v_fma_f32 v50, v50, v51, v51
	v_div_fixup_f32 v49, v50, v49, 1.0
	v_add_f32_e32 v50, v22, v210
	v_mul_f32_e32 v50, 0xbfb8aa3b, v50
	v_exp_f32_e32 v50, v50
	s_nop 0
	v_add_f32_e32 v50, 1.0, v50
	s_nop 0
	v_rcp_f32_e32 v52, v50
	s_nop 0
	v_fma_f32 v51, -v50, v52, 1.0
	v_fma_f32 v51, v51, v52, v52
	v_div_fixup_f32 v50, v51, v50, 1.0
	v_add_f32_e32 v51, v23, v210
	v_mul_f32_e32 v51, 0xbfb8aa3b, v51
	v_exp_f32_e32 v51, v51
	s_nop 0
	v_add_f32_e32 v51, 1.0, v51
	s_nop 0
	v_rcp_f32_e32 v53, v51
	s_nop 0
	v_fma_f32 v52, -v51, v53, 1.0
	v_fma_f32 v52, v52, v53, v53
	v_div_fixup_f32 v51, v52, v51, 1.0
	v_add_f32_e32 v52, v16, v209
	v_mul_f32_e32 v52, 0xbfb8aa3b, v52
	v_exp_f32_e32 v52, v52
	s_nop 0
	v_add_f32_e32 v52, 1.0, v52
	s_nop 0
	v_rcp_f32_e32 v54, v52
	s_nop 0
	v_fma_f32 v53, -v52, v54, 1.0
	v_fma_f32 v53, v53, v54, v54
	v_div_fixup_f32 v52, v53, v52, 1.0
	v_add_f32_e32 v53, v17, v209
	v_mul_f32_e32 v53, 0xbfb8aa3b, v53
	v_exp_f32_e32 v53, v53
	s_nop 0
	v_add_f32_e32 v53, 1.0, v53
	s_nop 0
	v_rcp_f32_e32 v55, v53
	s_nop 0
	v_fma_f32 v54, -v53, v55, 1.0
	v_fma_f32 v54, v54, v55, v55
	v_div_fixup_f32 v53, v54, v53, 1.0
	v_add_f32_e32 v54, v18, v209
	v_mul_f32_e32 v54, 0xbfb8aa3b, v54
	v_exp_f32_e32 v54, v54
	s_nop 0
	v_add_f32_e32 v54, 1.0, v54
	s_nop 0
	v_rcp_f32_e32 v56, v54
	s_nop 0
	v_fma_f32 v55, -v54, v56, 1.0
	v_fma_f32 v55, v55, v56, v56
	v_div_fixup_f32 v54, v55, v54, 1.0
	v_add_f32_e32 v55, v19, v209
	v_mul_f32_e32 v55, 0xbfb8aa3b, v55
	v_exp_f32_e32 v55, v55
	s_nop 0
	v_add_f32_e32 v55, 1.0, v55
	s_nop 0
	v_rcp_f32_e32 v57, v55
	s_nop 0
	v_fma_f32 v56, -v55, v57, 1.0
	v_fma_f32 v56, v56, v57, v57
	v_div_fixup_f32 v55, v56, v55, 1.0
	v_add_f32_e32 v56, v4, v208
	v_mul_f32_e32 v56, 0xbfb8aa3b, v56
	v_exp_f32_e32 v56, v56
	s_nop 0
	v_add_f32_e32 v56, 1.0, v56
	s_nop 0
	v_rcp_f32_e32 v58, v56
	s_nop 0
	v_fma_f32 v57, -v56, v58, 1.0
	v_fma_f32 v57, v57, v58, v58
	v_div_fixup_f32 v58, v57, v56, 1.0
	v_add_f32_e32 v56, v5, v208
	v_mul_f32_e32 v56, 0xbfb8aa3b, v56
	v_exp_f32_e32 v56, v56
	s_nop 0
	v_add_f32_e32 v56, 1.0, v56
	s_nop 0
	v_rcp_f32_e32 v59, v56
	s_nop 0
	v_fma_f32 v57, -v56, v59, 1.0
	v_fma_f32 v57, v57, v59, v59
	v_div_fixup_f32 v59, v57, v56, 1.0
	v_add_f32_e32 v56, v6, v208
	v_mul_f32_e32 v56, 0xbfb8aa3b, v56
	v_exp_f32_e32 v56, v56
	s_nop 0
	v_add_f32_e32 v56, 1.0, v56
	s_nop 0
	v_rcp_f32_e32 v60, v56
	s_nop 0
	v_fma_f32 v57, -v56, v60, 1.0
	v_fma_f32 v57, v57, v60, v60
	v_div_fixup_f32 v60, v57, v56, 1.0
	v_add_f32_e32 v56, v7, v208
	v_mul_f32_e32 v56, 0xbfb8aa3b, v56
	v_exp_f32_e32 v56, v56
	s_nop 0
	v_add_f32_e32 v56, 1.0, v56
	s_nop 0
	v_rcp_f32_e32 v61, v56
	s_nop 0
	v_fma_f32 v57, -v56, v61, 1.0
	v_fma_f32 v57, v57, v61, v61
	v_div_fixup_f32 v61, v57, v56, 1.0
	v_add_f32_e32 v56, v0, v207
	v_mul_f32_e32 v56, 0xbfb8aa3b, v56
	v_exp_f32_e32 v56, v56
	s_nop 0
	v_add_f32_e32 v56, 1.0, v56
	s_nop 0
	v_rcp_f32_e32 v62, v56
	s_nop 0
	v_fma_f32 v57, -v56, v62, 1.0
	v_fma_f32 v57, v57, v62, v62
	v_div_fixup_f32 v62, v57, v56, 1.0
	v_add_f32_e32 v56, v1, v207
	v_mul_f32_e32 v56, 0xbfb8aa3b, v56
	v_exp_f32_e32 v56, v56
	s_nop 0
	v_add_f32_e32 v56, 1.0, v56
	s_nop 0
	v_rcp_f32_e32 v63, v56
	s_nop 0
	v_fma_f32 v57, -v56, v63, 1.0
	v_fma_f32 v57, v57, v63, v63
	v_div_fixup_f32 v63, v57, v56, 1.0
	v_add_f32_e32 v56, v2, v207
	v_mul_f32_e32 v56, 0xbfb8aa3b, v56
	v_exp_f32_e32 v56, v56
	s_nop 0
	v_add_f32_e32 v56, 1.0, v56
	s_nop 0
	v_rcp_f32_e32 v65, v56
	s_nop 0
	v_fma_f32 v57, -v56, v65, 1.0
	v_fma_f32 v57, v57, v65, v65
	v_div_fixup_f32 v65, v57, v56, 1.0
	v_add_f32_e32 v56, v3, v207
	v_mul_f32_e32 v56, 0xbfb8aa3b, v56
	v_exp_f32_e32 v56, v56
	s_nop 0
	v_add_f32_e32 v56, 1.0, v56
	s_mov_b64 s[2:3], s[0:1]
	s_load_dwordx2 s[2:3], s[2:3], 0xe8
	v_rcp_f32_e32 v66, v56
	s_nop 0
	v_fma_f32 v57, -v56, v66, 1.0
	v_fma_f32 v57, v57, v66, v66
	v_div_fixup_f32 v66, v57, v56, 1.0
	v_and_b32_e32 v56, 0xffffff80, v205
	v_lshlrev_b32_e32 v57, 6, v206
	v_or3_b32 v56, v56, v204, v57
	s_waitcnt lgkmcnt(0)
	s_add_u32 s2, s2, s4
	v_add_u32_e32 v56, 0x1800, v56
	s_addc_u32 s3, s3, s5
	v_ashrrev_i32_e32 v57, 31, v56
	v_lshl_add_u64 v[56:57], v[56:57], 4, s[2:3]
	v_cvt_pk_bf16_f32 v32, v32, v33
	v_cvt_pk_bf16_f32 v33, v34, v35
	v_cvt_pk_bf16_f32 v34, v36, v37
	v_add_co_u32_e32 v36, vcc, s67, v56
	v_cvt_pk_bf16_f32 v35, v38, v39
	s_mov_b64 s[2:3], 0
	s_nop 0
	v_addc_co_u32_e32 v37, vcc, 0, v57, vcc
	global_store_dwordx4 v[36:37], v[32:35], off
	v_add_co_u32_e32 v36, vcc, s46, v56
	s_nop 0
	v_cvt_pk_bf16_f32 v32, v40, v41
	v_cvt_pk_bf16_f32 v33, v42, v43
	v_cvt_pk_bf16_f32 v34, v44, v45
	v_cvt_pk_bf16_f32 v35, v46, v47
	s_nop 0
	v_addc_co_u32_e32 v37, vcc, 0, v57, vcc
	global_store_dwordx4 v[36:37], v[32:35], off
	v_add_co_u32_e32 v36, vcc, 0x22724000, v56
	s_nop 0
	v_cvt_pk_bf16_f32 v32, v48, v49
	v_cvt_pk_bf16_f32 v33, v50, v51
	v_cvt_pk_bf16_f32 v34, v52, v53
	v_cvt_pk_bf16_f32 v35, v54, v55
	s_nop 0
	v_addc_co_u32_e32 v37, vcc, 0, v57, vcc
	global_store_dwordx4 v[36:37], v[32:35], off
	v_add_co_u32_e32 v36, vcc, 0x22726000, v56
	s_nop 0
	v_cvt_pk_bf16_f32 v32, v58, v59
	v_cvt_pk_bf16_f32 v33, v60, v61
	v_cvt_pk_bf16_f32 v34, v62, v63
	v_cvt_pk_bf16_f32 v35, v65, v66
	s_nop 0
	v_addc_co_u32_e32 v37, vcc, 0, v57, vcc
	global_store_dwordx4 v[36:37], v[32:35], off

; #define ATTT ((float2*)(kargs()->ws + O_ATTT))
; __global__ void __launch_bounds__(512) mega(Params p) {
;     ...
;                   } else if (c0 < 7424) {
;                     const bool isk = c0 >= 7168; const float* nw = isk ? kn_w : qn_w; const float2* attt = ATTT;
; #pragma unroll
;                     for (int j = 0; j < 4; ++j) { const int pos = (r0 + j) & (seqlen - 1);
;                       float ss = 0;
; #pragma unroll
;                       for (int n = 0; n < 8; ++n) ss += a[n][j] * a[n][j];
;                       ss = red16(ss);
;                       const float rstd = 1.f / sqrtf(ss * (1.f / 128.f) + RMS_EPS);
; #pragma unroll
;                       for (int n = 0; n < 8; ++n) a[n][j] = a[n][j] * rstd * hv[n];
;                       const float4* tb = (const float4*)(attt + pos * 64 + fr * 4);
;                       const float4 t01 = tb[0], t23 = tb[1];
;                       const float2 csv[4] = {make_float2(t01.x, t01.y), make_float2(t01.z, t01.w), make_float2(t23.x, t23.y), make_float2(t23.z, t23.w)};
; #pragma unroll
;                       for (int hh = 0; hh < 2; ++hh)
; #pragma unroll
;                         for (int n = 0; n < 2; ++n) { const float2 cs = csv[hh * 2 + n];
;                           const float x1 = a[hh * 4 + n][j], x2 = a[hh * 4 + n + 2][j];
;                           a[hh * 4 + n][j] = x1 * cs.x - x2 * cs.y; a[hh * 4 + n + 2][j] = x1 * cs.y + x2 * cs.x; } }
.LBB0_2059:
	s_mov_b64 s[2:3], s[0:1]
	s_load_dwordx2 s[2:3], s[2:3], 0xe8
	v_mul_f32_e32 v32, v24, v24
	v_fmac_f32_e32 v32, v28, v28
	v_fmac_f32_e32 v32, v12, v12
	v_fmac_f32_e32 v32, v8, v8
	s_waitcnt lgkmcnt(0)
	s_add_u32 s36, s2, 0x3da0000
	s_mov_b32 s2, -1
	v_fmac_f32_e32 v32, v20, v20
	v_fmac_f32_e32 v32, v16, v16
	v_mbcnt_lo_u32_b32 v33, s2, 0
	v_mbcnt_hi_u32_b32 v33, s2, v33
	v_fmac_f32_e32 v32, v4, v4
	v_lshlrev_b32_e32 v33, 2, v33
	v_fmac_f32_e32 v32, v0, v0
	v_xor_b32_e32 v34, 4, v33
	ds_bpermute_b32 v34, v34, v32
	v_mov_b32_e32 v67, 0x358637bd
	s_addc_u32 s37, s3, 0
	v_mov_b32_e32 v161, v177
	s_waitcnt lgkmcnt(0)
	v_add_f32_e32 v32, v32, v34
	v_xor_b32_e32 v34, 8, v33
	ds_bpermute_b32 v34, v34, v32
	s_waitcnt lgkmcnt(0)
	v_add_f32_e32 v32, v32, v34
	v_xor_b32_e32 v34, 16, v33
	ds_bpermute_b32 v34, v34, v32
	v_xor_b32_e32 v33, 32, v33
	s_waitcnt lgkmcnt(0)
	v_add_f32_e32 v32, v32, v34
	ds_bpermute_b32 v33, v33, v32
	s_waitcnt lgkmcnt(0)
	v_add_f32_e32 v32, v32, v33
	v_fmamk_f32 v32, v32, 0x3c000000, v67
	v_cmp_gt_f32_e32 vcc, s30, v32
	v_mul_f32_e32 v33, 0x4f800000, v32
	s_nop 0
	v_cndmask_b32_e32 v32, v32, v33, vcc
	v_sqrt_f32_e32 v33, v32
	s_nop 0
	v_add_u32_e32 v34, -1, v33
	v_fma_f32 v35, -v34, v33, v32
	v_cmp_ge_f32_e64 s[4:5], 0, v35
	v_add_u32_e32 v35, 1, v33
	s_nop 0
	v_cndmask_b32_e64 v34, v33, v34, s[4:5]
	v_fma_f32 v33, -v35, v33, v32
	v_cmp_lt_f32_e64 s[4:5], 0, v33
	s_nop 1
	v_cndmask_b32_e64 v33, v34, v35, s[4:5]
	v_mul_f32_e32 v34, 0x37800000, v33
	v_cndmask_b32_e32 v33, v33, v34, vcc
	v_cmp_class_f32_e32 vcc, v32, v222
	s_nop 1
	v_cndmask_b32_e32 v32, v33, v32, vcc
	s_mov_b32 s2, -1
	v_rcp_f32_e32 v34, v32
	s_nop 0
	v_fma_f32 v33, -v32, v34, 1.0
	v_fma_f32 v33, v33, v34, v34
	v_div_fixup_f32 v32, v33, v32, 1.0
	v_mul_f32_e32 v33, v28, v32
	s_waitcnt vmcnt(0)
	v_mul_f32_e32 v41, v224, v33
	v_mul_f32_e32 v33, v24, v32
	v_mul_f32_e32 v44, v223, v33
	v_mul_f32_e32 v33, v12, v32
	v_mul_f32_e32 v40, v212, v33
	v_mul_f32_e32 v33, v8, v32
	v_mul_f32_e32 v45, v211, v33
	v_mul_f32_e32 v33, v20, v32
	v_mul_f32_e32 v46, v210, v33
	v_mul_f32_e32 v33, v16, v32
	v_mul_f32_e32 v47, v209, v33
	v_mul_f32_e32 v33, v4, v32
	v_mul_f32_e32 v32, v0, v32
	v_mul_f32_e32 v49, v207, v32
	v_and_b32_e32 v32, s14, v64
	v_mul_f32_e32 v48, v208, v33
	v_lshlrev_b32_e32 v32, 6, v32
	v_mov_b32_e32 v33, v177
	v_lshl_add_u64 v[32:33], v[32:33], 3, s[36:37]
	v_lshl_add_u64 v[36:37], v[32:33], 0, v[160:161]
	global_load_dwordx4 v[32:35], v[36:37], off offset:16
	s_nop 0
	global_load_dwordx4 v[36:39], v[36:37], off
	s_waitcnt vmcnt(0)
	v_mul_f32_e32 v42, v37, v40
	v_fma_f32 v42, v36, v41, -v42
	v_mul_f32_e32 v40, v36, v40
	v_mul_f32_e32 v36, v39, v45
	v_fma_f32 v43, v38, v44, -v36
	v_mul_f32_e32 v36, v33, v48
	v_fmac_f32_e32 v40, v37, v41
	v_mul_f32_e32 v41, v38, v45
	v_fma_f32 v38, v32, v46, -v36
	v_mul_f32_e32 v36, v32, v48
	v_mul_f32_e32 v32, v35, v49
	v_fmac_f32_e32 v41, v39, v44
	v_fma_f32 v39, v34, v47, -v32
	v_mul_f32_e32 v32, v25, v25
	v_fmac_f32_e32 v32, v29, v29
	v_fmac_f32_e32 v32, v13, v13
	v_fmac_f32_e32 v32, v9, v9
	v_mul_f32_e32 v37, v34, v49
	v_fmac_f32_e32 v32, v21, v21
	v_mbcnt_lo_u32_b32 v34, s2, 0
	v_fmac_f32_e32 v32, v17, v17
	v_mbcnt_hi_u32_b32 v34, s2, v34
	v_fmac_f32_e32 v32, v5, v5
	v_lshlrev_b32_e32 v34, 2, v34
	v_fmac_f32_e32 v37, v35, v47
	v_fmac_f32_e32 v32, v1, v1
	v_xor_b32_e32 v35, 4, v34
	ds_bpermute_b32 v35, v35, v32
	v_fmac_f32_e32 v36, v33, v46
	v_add_u32_e32 v33, 1, v64
	s_waitcnt lgkmcnt(0)
	v_add_f32_e32 v32, v32, v35
	v_xor_b32_e32 v35, 8, v34
	ds_bpermute_b32 v35, v35, v32
	s_waitcnt lgkmcnt(0)
	v_add_f32_e32 v32, v32, v35
	v_xor_b32_e32 v35, 16, v34
	ds_bpermute_b32 v35, v35, v32
	v_xor_b32_e32 v34, 32, v34
	s_waitcnt lgkmcnt(0)
	v_add_f32_e32 v32, v32, v35
	ds_bpermute_b32 v34, v34, v32
	s_waitcnt lgkmcnt(0)
	v_add_f32_e32 v32, v32, v34
	v_fmamk_f32 v32, v32, 0x3c000000, v67
	v_cmp_gt_f32_e32 vcc, s30, v32
	v_mul_f32_e32 v34, 0x4f800000, v32
	s_nop 0
	v_cndmask_b32_e32 v32, v32, v34, vcc
	v_sqrt_f32_e32 v34, v32
	s_nop 0
	v_add_u32_e32 v35, -1, v34
	v_fma_f32 v44, -v35, v34, v32
	v_cmp_ge_f32_e64 s[4:5], 0, v44
	v_add_u32_e32 v44, 1, v34
	s_nop 0
	v_cndmask_b32_e64 v35, v34, v35, s[4:5]
	v_fma_f32 v34, -v44, v34, v32
	v_cmp_lt_f32_e64 s[4:5], 0, v34
	s_nop 1
	v_cndmask_b32_e64 v34, v35, v44, s[4:5]
	v_mul_f32_e32 v35, 0x37800000, v34
	v_cndmask_b32_e32 v34, v34, v35, vcc
	v_cmp_class_f32_e32 vcc, v32, v222
	s_nop 1
	v_cndmask_b32_e32 v32, v34, v32, vcc
	s_mov_b32 s2, -1
	v_rcp_f32_e32 v35, v32
	s_nop 0
	v_fma_f32 v34, -v32, v35, 1.0
	v_fma_f32 v34, v34, v35, v35
	v_div_fixup_f32 v32, v34, v32, 1.0
	v_mul_f32_e32 v34, v29, v32
	v_mul_f32_e32 v49, v224, v34
	v_mul_f32_e32 v34, v25, v32
	v_mul_f32_e32 v52, v223, v34
	v_mul_f32_e32 v34, v13, v32
	v_mul_f32_e32 v48, v212, v34
	v_mul_f32_e32 v34, v9, v32
	v_mul_f32_e32 v53, v211, v34
	v_mul_f32_e32 v34, v21, v32
	v_mul_f32_e32 v54, v210, v34
	v_mul_f32_e32 v34, v17, v32
	v_mul_f32_e32 v55, v209, v34
	v_mul_f32_e32 v34, v5, v32
	v_mul_f32_e32 v32, v1, v32
	v_mul_f32_e32 v57, v207, v32
	v_and_b32_e32 v32, s14, v33
	v_lshlrev_b32_e32 v32, 6, v32
	v_mov_b32_e32 v33, v177
	v_lshl_add_u64 v[32:33], v[32:33], 3, s[36:37]
	v_lshl_add_u64 v[44:45], v[32:33], 0, v[160:161]
	v_mul_f32_e32 v56, v208, v34
	global_load_dwordx4 v[32:35], v[44:45], off offset:16
	s_nop 0
	global_load_dwordx4 v[44:47], v[44:45], off
	s_waitcnt vmcnt(0)
; #define ATTT ((float2*)(kargs()->ws + O_ATTT))
; __global__ void __launch_bounds__(512) mega(Params p) {
;     ...
;                   } else if (c0 < 7424) {
;                     const bool isk = c0 >= 7168; const float* nw = isk ? kn_w : qn_w; const float2* attt = ATTT;
; #pragma unroll
;                     for (int j = 0; j < 4; ++j) { const int pos = (r0 + j) & (seqlen - 1);
;                       float ss = 0;
; #pragma unroll
;                       for (int n = 0; n < 8; ++n) ss += a[n][j] * a[n][j];
;                       ss = red16(ss);
;                       const float rstd = 1.f / sqrtf(ss * (1.f / 128.f) + RMS_EPS);
; #pragma unroll
;                       for (int n = 0; n < 8; ++n) a[n][j] = a[n][j] * rstd * hv[n];
;                       const float4* tb = (const float4*)(attt + pos * 64 + fr * 4);
;                       const float4 t01 = tb[0], t23 = tb[1];
;                       const float2 csv[4] = {make_float2(t01.x, t01.y), make_float2(t01.z, t01.w), make_float2(t23.x, t23.y), make_float2(t23.z, t23.w)};
; #pragma unroll
;                       for (int hh = 0; hh < 2; ++hh)
; #pragma unroll
;                         for (int n = 0; n < 2; ++n) { const float2 cs = csv[hh * 2 + n];
;                           const float x1 = a[hh * 4 + n][j], x2 = a[hh * 4 + n + 2][j];
;                           a[hh * 4 + n][j] = x1 * cs.x - x2 * cs.y; a[hh * 4 + n + 2][j] = x1 * cs.y + x2 * cs.x; } }
	v_mul_f32_e32 v50, v45, v48
	v_fma_f32 v50, v44, v49, -v50
	v_mul_f32_e32 v48, v44, v48
	v_mul_f32_e32 v44, v47, v53
	v_fma_f32 v51, v46, v52, -v44
	v_mul_f32_e32 v44, v33, v56
	v_fmac_f32_e32 v48, v45, v49
	v_mul_f32_e32 v49, v46, v53
	v_fma_f32 v46, v32, v54, -v44
	v_mul_f32_e32 v44, v32, v56
	v_mul_f32_e32 v32, v35, v57
	v_fmac_f32_e32 v49, v47, v52
	v_fma_f32 v47, v34, v55, -v32
	v_mul_f32_e32 v32, v26, v26
	v_fmac_f32_e32 v32, v30, v30
	v_fmac_f32_e32 v32, v14, v14
	v_fmac_f32_e32 v32, v10, v10
	v_mul_f32_e32 v45, v34, v57
	v_fmac_f32_e32 v32, v22, v22
	v_mbcnt_lo_u32_b32 v34, s2, 0
	v_fmac_f32_e32 v32, v18, v18
	v_mbcnt_hi_u32_b32 v34, s2, v34
	v_fmac_f32_e32 v32, v6, v6
	v_lshlrev_b32_e32 v34, 2, v34
	v_fmac_f32_e32 v45, v35, v55
	v_fmac_f32_e32 v32, v2, v2
	v_xor_b32_e32 v35, 4, v34
	ds_bpermute_b32 v35, v35, v32
	v_fmac_f32_e32 v44, v33, v54
	v_add_u32_e32 v33, 2, v64
	s_waitcnt lgkmcnt(0)
	v_add_f32_e32 v32, v32, v35
	v_xor_b32_e32 v35, 8, v34
	ds_bpermute_b32 v35, v35, v32
	s_waitcnt lgkmcnt(0)
	v_add_f32_e32 v32, v32, v35
	v_xor_b32_e32 v35, 16, v34
	ds_bpermute_b32 v35, v35, v32
	v_xor_b32_e32 v34, 32, v34
	s_waitcnt lgkmcnt(0)
	v_add_f32_e32 v32, v32, v35
	ds_bpermute_b32 v34, v34, v32
	s_waitcnt lgkmcnt(0)
	v_add_f32_e32 v32, v32, v34
	v_fmamk_f32 v32, v32, 0x3c000000, v67
	v_cmp_gt_f32_e32 vcc, s30, v32
	v_mul_f32_e32 v34, 0x4f800000, v32
	s_nop 0
	v_cndmask_b32_e32 v32, v32, v34, vcc
	v_sqrt_f32_e32 v34, v32
	s_nop 0
	v_add_u32_e32 v35, -1, v34
	v_fma_f32 v52, -v35, v34, v32
	v_cmp_ge_f32_e64 s[4:5], 0, v52
	v_add_u32_e32 v52, 1, v34
	s_nop 0
	v_cndmask_b32_e64 v35, v34, v35, s[4:5]
	v_fma_f32 v34, -v52, v34, v32
	v_cmp_lt_f32_e64 s[4:5], 0, v34
	s_nop 1
	v_cndmask_b32_e64 v34, v35, v52, s[4:5]
	v_mul_f32_e32 v35, 0x37800000, v34
	v_cndmask_b32_e32 v34, v34, v35, vcc
	v_cmp_class_f32_e32 vcc, v32, v222
	s_nop 1
	v_cndmask_b32_e32 v32, v34, v32, vcc
	s_mov_b32 s2, -1
	v_rcp_f32_e32 v35, v32
	s_nop 0
	v_fma_f32 v34, -v32, v35, 1.0
	v_fma_f32 v34, v34, v35, v35
	v_div_fixup_f32 v32, v34, v32, 1.0
	v_mul_f32_e32 v34, v30, v32
	v_mul_f32_e32 v57, v224, v34
	v_mul_f32_e32 v34, v26, v32
	v_mul_f32_e32 v60, v223, v34
	v_mul_f32_e32 v34, v14, v32
	v_mul_f32_e32 v56, v212, v34
	v_mul_f32_e32 v34, v10, v32
	v_mul_f32_e32 v61, v211, v34
	v_mul_f32_e32 v34, v22, v32
	v_mul_f32_e32 v62, v210, v34
	v_mul_f32_e32 v34, v18, v32
	v_mul_f32_e32 v63, v209, v34
	v_mul_f32_e32 v34, v6, v32
	v_mul_f32_e32 v32, v2, v32
	v_mul_f32_e32 v66, v207, v32
	v_and_b32_e32 v32, s14, v33
	v_lshlrev_b32_e32 v32, 6, v32
	v_mov_b32_e32 v33, v177
	v_lshl_add_u64 v[32:33], v[32:33], 3, s[36:37]
	v_lshl_add_u64 v[52:53], v[32:33], 0, v[160:161]
	v_mul_f32_e32 v65, v208, v34
	global_load_dwordx4 v[32:35], v[52:53], off offset:16
	s_nop 0
	global_load_dwordx4 v[52:55], v[52:53], off
	s_waitcnt vmcnt(0)
	v_mul_f32_e32 v58, v53, v56
	v_fma_f32 v58, v52, v57, -v58
	v_mul_f32_e32 v56, v52, v56
	v_mul_f32_e32 v52, v55, v61
	v_fma_f32 v59, v54, v60, -v52
	v_mul_f32_e32 v52, v33, v65
	v_fmac_f32_e32 v56, v53, v57
	v_mul_f32_e32 v57, v54, v61
	v_fma_f32 v54, v32, v62, -v52
	v_mul_f32_e32 v52, v32, v65
	v_mul_f32_e32 v32, v35, v66
	v_fmac_f32_e32 v57, v55, v60
	v_fma_f32 v55, v34, v63, -v32
	v_mul_f32_e32 v32, v27, v27
	v_fmac_f32_e32 v32, v31, v31
	v_fmac_f32_e32 v32, v15, v15
	v_fmac_f32_e32 v32, v11, v11
	v_mul_f32_e32 v53, v34, v66
	v_fmac_f32_e32 v32, v23, v23
	v_mbcnt_lo_u32_b32 v34, s2, 0
	v_fmac_f32_e32 v32, v19, v19
	v_mbcnt_hi_u32_b32 v34, s2, v34
	v_fmac_f32_e32 v32, v7, v7
	v_lshlrev_b32_e32 v34, 2, v34
	v_fmac_f32_e32 v53, v35, v63
	v_fmac_f32_e32 v32, v3, v3
	v_xor_b32_e32 v35, 4, v34
	ds_bpermute_b32 v35, v35, v32
	v_fmac_f32_e32 v52, v33, v62
	v_add_u32_e32 v33, 3, v64
	s_waitcnt lgkmcnt(0)
	v_add_f32_e32 v32, v32, v35
	v_xor_b32_e32 v35, 8, v34
	ds_bpermute_b32 v35, v35, v32
	s_waitcnt lgkmcnt(0)
	v_add_f32_e32 v32, v32, v35
	v_xor_b32_e32 v35, 16, v34
	ds_bpermute_b32 v35, v35, v32
	v_xor_b32_e32 v34, 32, v34
	s_waitcnt lgkmcnt(0)
	v_add_f32_e32 v32, v32, v35
	ds_bpermute_b32 v34, v34, v32
	s_waitcnt lgkmcnt(0)
	v_add_f32_e32 v32, v32, v34
	v_fmamk_f32 v32, v32, 0x3c000000, v67
	v_cmp_gt_f32_e32 vcc, s30, v32
	v_mul_f32_e32 v34, 0x4f800000, v32
	s_nop 0
	v_cndmask_b32_e32 v32, v32, v34, vcc
	v_sqrt_f32_e32 v34, v32
	s_nop 0
	v_add_u32_e32 v35, -1, v34
	v_fma_f32 v60, -v35, v34, v32
	v_cmp_ge_f32_e64 s[4:5], 0, v60
	v_add_u32_e32 v60, 1, v34
	s_nop 0
	v_cndmask_b32_e64 v35, v34, v35, s[4:5]
	v_fma_f32 v34, -v60, v34, v32
	v_cmp_lt_f32_e64 s[4:5], 0, v34
	s_nop 1
	v_cndmask_b32_e64 v34, v35, v60, s[4:5]
	v_mul_f32_e32 v35, 0x37800000, v34
	v_cndmask_b32_e32 v34, v34, v35, vcc
	v_cmp_class_f32_e32 vcc, v32, v222
	s_nop 1
	v_cndmask_b32_e32 v32, v34, v32, vcc
	s_mov_b64 s[2:3], -1
	v_rcp_f32_e32 v35, v32
	s_nop 0
	v_fma_f32 v34, -v32, v35, 1.0
	v_fma_f32 v34, v34, v35, v35
	v_div_fixup_f32 v32, v34, v32, 1.0
	v_mul_f32_e32 v34, v31, v32
	v_mul_f32_e32 v62, v224, v34
	v_mul_f32_e32 v34, v27, v32
	v_mul_f32_e32 v65, v223, v34
	v_mul_f32_e32 v34, v15, v32
	v_mul_f32_e32 v63, v212, v34
	v_mul_f32_e32 v34, v11, v32
	v_mul_f32_e32 v66, v211, v34
	v_mul_f32_e32 v34, v23, v32
	v_mul_f32_e32 v72, v210, v34
	v_mul_f32_e32 v34, v19, v32
	v_mul_f32_e32 v73, v209, v34
	v_mul_f32_e32 v34, v7, v32
	v_mul_f32_e32 v32, v3, v32
	v_mul_f32_e32 v75, v207, v32
	v_and_b32_e32 v32, s14, v33
	v_lshlrev_b32_e32 v32, 6, v32
	v_mov_b32_e32 v33, v177
	v_lshl_add_u64 v[32:33], v[32:33], 3, s[36:37]
	v_lshl_add_u64 v[60:61], v[32:33], 0, v[160:161]
	v_mul_f32_e32 v74, v208, v34
	global_load_dwordx4 v[32:35], v[60:61], off offset:16
	global_load_dwordx4 v[68:71], v[60:61], off
	s_waitcnt vmcnt(0)
	v_mul_f32_e32 v60, v69, v63
	v_fma_f32 v67, v68, v62, -v60
	v_mul_f32_e32 v60, v71, v66
	v_mul_f32_e32 v63, v68, v63
	v_fma_f32 v68, v70, v65, -v60
	v_mul_f32_e32 v60, v33, v74
	v_fma_f32 v61, v32, v72, -v60
	v_mul_f32_e32 v60, v32, v74
	v_mul_f32_e32 v32, v35, v75
	v_fmac_f32_e32 v63, v69, v62
	v_fma_f32 v62, v34, v73, -v32
	v_and_b32_e32 v32, 1, v203
	v_mul_f32_e32 v66, v70, v66
	v_mul_f32_e32 v34, v34, v75
	v_cmp_eq_u32_e32 vcc, 0, v32
	v_cmp_eq_u32_e64 s[4:5], 1, v32
	v_add_u32_e32 v32, 15, v202
	v_fmac_f32_e32 v66, v71, v65
	v_fmac_f32_e32 v60, v33, v72
	v_fmac_f32_e32 v34, v35, v73
	v_ashrrev_i32_e32 v65, 31, v64
	v_cndmask_b32_e32 v35, v32, v202, vcc
	v_cndmask_b32_e32 v69, v42, v43, vcc
	s_and_b64 vcc, exec, s[6:7]
	s_cbranch_vccz .LBB0_2125
	s_mov_b64 s[2:3], s[0:1]
	s_load_dwordx2 s[2:3], s[2:3], 0xe8
	v_mov_b32_dpp v32, v69 quad_perm:[1,0,3,2] row_mask:0xf bank_mask:0xf bound_ctrl:1
	s_and_saveexec_b64 s[6:7], s[4:5]
	s_xor_b64 s[6:7], exec, s[6:7]
	s_cbranch_execz .LBB0_2062
	v_cvt_pk_bf16_f32 v70, v32, v43

; DEVFI float gelu_tanh(float x) {
;   float u = 0.7978845608028654f * (x + 0.044715f * x * x * x);
;   float t = __expf(2.f * u);
;   float th = 1.f - 2.f / (t + 1.f);
;   return 0.5f * x * (1.f + th);
; }
; __global__ void __launch_bounds__(512) mega(Params p) {
;     ...
;                   } else if (c0 < 6144) {
; #pragma unroll
;                     for (int n = 0; n < 8; ++n)
; #pragma unroll
;                       for (int j = 0; j < 4; ++j) a[n][j] = gelu_tanh(a[n][j]);
.LBB0_2192:
	s_andn2_b64 vcc, exec, s[2:3]
	s_cbranch_vccnz .LBB0_2270
	v_mul_f32_e32 v32, 0x3d372713, v28
	v_mul_f32_e32 v33, 0x3d372713, v24
	v_mul_f32_e32 v32, v28, v32
	v_mul_f32_e32 v33, v24, v33
	v_fma_f32 v32, v28, v32, v28
	v_fma_f32 v33, v24, v33, v24
	v_mul_f32_e32 v32, 0x3f4c422a, v32
	v_mul_f32_e32 v33, 0x3f4c422a, v33
	v_add_f32_e32 v32, v32, v32
	v_add_f32_e32 v33, v33, v33
	v_mul_f32_e32 v32, 0x3fb8aa3b, v32
	v_mul_f32_e32 v33, 0x3fb8aa3b, v33
	v_exp_f32_e32 v34, v32
	v_exp_f32_e32 v35, v33
	v_mul_f32_e32 v32, 0x3d372713, v29
	v_mul_f32_e32 v32, v29, v32
	v_fma_f32 v32, v29, v32, v29
	v_pk_add_f32 v[34:35], v[34:35], 1.0 op_sel_hi:[1,0]
	v_mul_f32_e32 v32, 0x3f4c422a, v32
	v_add_f32_e32 v32, v32, v32
	v_mul_f32_e32 v32, 0x3fb8aa3b, v32
	v_exp_f32_e32 v36, v32
	v_rcp_f32_e32 v37, v35
	s_nop 0
	v_fma_f32 v33, -v35, v37, 1.0
	v_fma_f32 v37, v33, v37, v37
	v_add_f32_e32 v33, v37, v37
	v_div_fixup_f32 v35, v33, v35, 2.0
	v_mul_f32_e32 v32, 0x3d372713, v30
	v_mul_f32_e32 v32, v30, v32
	v_fma_f32 v32, v30, v32, v30
	v_rcp_f32_e32 v37, v34
	s_nop 0
	v_fma_f32 v33, -v34, v37, 1.0
	v_fma_f32 v37, v33, v37, v37
	v_add_f32_e32 v33, v37, v37
	v_div_fixup_f32 v34, v33, v34, 2.0
	v_mul_f32_e32 v33, 0x3d372713, v25
	v_mul_f32_e32 v33, v25, v33
	v_fma_f32 v33, v25, v33, v25
	v_mul_f32_e32 v33, 0x3f4c422a, v33
	v_add_f32_e32 v33, v33, v33
	v_mul_f32_e32 v33, 0x3fb8aa3b, v33
	v_exp_f32_e32 v37, v33
	v_pk_add_f32 v[34:35], v[34:35], 1.0 op_sel_hi:[1,0] neg_lo:[1,0] neg_hi:[1,0]
	v_mov_b32_e32 v40, v28
	v_mov_b32_e32 v41, v24
	v_pk_mul_f32 v[40:41], v[40:41], 0.5 op_sel_hi:[1,0]
	v_pk_add_f32 v[34:35], v[34:35], 1.0 op_sel_hi:[1,0]
	v_mul_f32_e32 v32, 0x3f4c422a, v32
	v_pk_mul_f32 v[40:41], v[40:41], v[34:35]
	v_pk_add_f32 v[34:35], v[36:37], 1.0 op_sel_hi:[1,0]
	v_add_f32_e32 v32, v32, v32
	v_mul_f32_e32 v32, 0x3fb8aa3b, v32
	v_exp_f32_e32 v38, v32
	v_mul_f32_e32 v32, 0x3d372713, v31
	v_rcp_f32_e32 v36, v35
	s_nop 0
	v_fma_f32 v33, -v35, v36, 1.0
	v_fma_f32 v36, v33, v36, v36
	v_add_f32_e32 v33, v36, v36
	v_div_fixup_f32 v35, v33, v35, 2.0
	v_mul_f32_e32 v32, v31, v32
	v_fma_f32 v32, v31, v32, v31
	v_mul_f32_e32 v32, 0x3f4c422a, v32
	v_rcp_f32_e32 v36, v34
	s_nop 0
	v_fma_f32 v33, -v34, v36, 1.0
	v_fma_f32 v36, v33, v36, v36
	v_add_f32_e32 v33, v36, v36
	v_div_fixup_f32 v34, v33, v34, 2.0
	v_mul_f32_e32 v33, 0x3d372713, v26
	v_mul_f32_e32 v33, v26, v33
	v_fma_f32 v33, v26, v33, v26
	v_mul_f32_e32 v33, 0x3f4c422a, v33
	v_add_f32_e32 v33, v33, v33
	v_mul_f32_e32 v33, 0x3fb8aa3b, v33
	v_exp_f32_e32 v39, v33
	v_pk_add_f32 v[34:35], v[34:35], 1.0 op_sel_hi:[1,0] neg_lo:[1,0] neg_hi:[1,0]
	v_mov_b32_e32 v36, v29
	v_mov_b32_e32 v37, v25
	v_pk_mul_f32 v[36:37], v[36:37], 0.5 op_sel_hi:[1,0]
	v_pk_add_f32 v[34:35], v[34:35], 1.0 op_sel_hi:[1,0]
	v_add_f32_e32 v32, v32, v32
	v_pk_mul_f32 v[36:37], v[36:37], v[34:35]
	v_pk_add_f32 v[34:35], v[38:39], 1.0 op_sel_hi:[1,0]
	v_mul_f32_e32 v32, 0x3fb8aa3b, v32
	v_exp_f32_e32 v32, v32
	s_mov_b64 s[6:7], -1
	s_cmpk_lt_u32 s26, 0x1400
	v_rcp_f32_e32 v38, v35
	s_nop 0
	v_fma_f32 v33, -v35, v38, 1.0
	v_fma_f32 v38, v33, v38, v38
	v_add_f32_e32 v33, v38, v38
	v_div_fixup_f32 v35, v33, v35, 2.0
	s_nop 0
	v_rcp_f32_e32 v38, v34
	s_nop 0
	v_fma_f32 v33, -v34, v38, 1.0
	v_fma_f32 v38, v33, v38, v38
	v_add_f32_e32 v33, v38, v38
	v_div_fixup_f32 v34, v33, v34, 2.0
	v_mul_f32_e32 v33, 0x3d372713, v27
	v_mul_f32_e32 v33, v27, v33
	v_fma_f32 v33, v27, v33, v27
	v_mul_f32_e32 v33, 0x3f4c422a, v33
	v_add_f32_e32 v33, v33, v33
	v_mul_f32_e32 v33, 0x3fb8aa3b, v33
	v_exp_f32_e32 v33, v33
	v_pk_add_f32 v[34:35], v[34:35], 1.0 op_sel_hi:[1,0] neg_lo:[1,0] neg_hi:[1,0]
	v_mov_b32_e32 v38, v30
	v_mov_b32_e32 v39, v26
	v_pk_mul_f32 v[38:39], v[38:39], 0.5 op_sel_hi:[1,0]
	v_pk_add_f32 v[34:35], v[34:35], 1.0 op_sel_hi:[1,0]
	v_pk_add_f32 v[32:33], v[32:33], 1.0 op_sel_hi:[1,0]
	v_pk_mul_f32 v[34:35], v[38:39], v[34:35]
	s_nop 0
	v_rcp_f32_e32 v39, v33
	s_nop 0
	v_fma_f32 v38, -v33, v39, 1.0
	v_fma_f32 v39, v38, v39, v39
	v_add_f32_e32 v38, v39, v39
	v_div_fixup_f32 v33, v38, v33, 2.0
	s_nop 0
	v_rcp_f32_e32 v39, v32
	s_nop 0
	v_fma_f32 v38, -v32, v39, 1.0
	v_fma_f32 v39, v38, v39, v39
	v_add_f32_e32 v38, v39, v39
	v_div_fixup_f32 v32, v38, v32, 2.0
	v_pk_add_f32 v[32:33], v[32:33], 1.0 op_sel_hi:[1,0] neg_lo:[1,0] neg_hi:[1,0]
	v_mov_b32_e32 v38, v31
	v_mov_b32_e32 v39, v27
	v_pk_mul_f32 v[38:39], v[38:39], 0.5 op_sel_hi:[1,0]
	v_pk_add_f32 v[32:33], v[32:33], 1.0 op_sel_hi:[1,0]
	s_nop 0
	v_pk_mul_f32 v[32:33], v[38:39], v[32:33]
	v_mul_f32_e32 v38, 0x3d372713, v12
	v_mul_f32_e32 v38, v12, v38
	v_fma_f32 v38, v12, v38, v12
	v_mul_f32_e32 v38, 0x3f4c422a, v38
	v_add_f32_e32 v38, v38, v38
	v_mul_f32_e32 v38, 0x3fb8aa3b, v38
	v_exp_f32_e32 v38, v38
	s_nop 0
	v_add_f32_e32 v38, 1.0, v38
	s_nop 0
	v_rcp_f32_e32 v42, v38
	s_nop 0
	v_fma_f32 v39, -v38, v42, 1.0
	v_fma_f32 v42, v39, v42, v42
	v_add_f32_e32 v39, v42, v42
	v_div_fixup_f32 v38, v39, v38, 2.0
	v_sub_f32_e32 v38, 1.0, v38
	v_mul_f32_e32 v39, 0.5, v12
	v_add_f32_e32 v38, 1.0, v38
	v_mul_f32_e32 v48, v39, v38
	v_mul_f32_e32 v38, 0x3d372713, v13
	v_mul_f32_e32 v38, v13, v38
	v_fma_f32 v38, v13, v38, v13
	v_mul_f32_e32 v38, 0x3f4c422a, v38
	v_add_f32_e32 v38, v38, v38
	v_mul_f32_e32 v38, 0x3fb8aa3b, v38
	v_exp_f32_e32 v38, v38
	s_nop 0
	v_add_f32_e32 v38, 1.0, v38
	s_nop 0
	v_rcp_f32_e32 v42, v38
	s_nop 0
	v_fma_f32 v39, -v38, v42, 1.0
	v_fma_f32 v42, v39, v42, v42
	v_add_f32_e32 v39, v42, v42
	v_div_fixup_f32 v38, v39, v38, 2.0
	v_sub_f32_e32 v38, 1.0, v38
	v_mul_f32_e32 v39, 0.5, v13
	v_add_f32_e32 v38, 1.0, v38
	v_mul_f32_e32 v44, v39, v38
	v_mul_f32_e32 v38, 0x3d372713, v14
; DEVFI float gelu_tanh(float x) {
;   float u = 0.7978845608028654f * (x + 0.044715f * x * x * x);
;   float t = __expf(2.f * u);
;   float th = 1.f - 2.f / (t + 1.f);
;   return 0.5f * x * (1.f + th);
; }
; __global__ void __launch_bounds__(512) mega(Params p) {
;     ...
;                   } else if (c0 < 6144) {
; #pragma unroll
;                     for (int n = 0; n < 8; ++n)
; #pragma unroll
;                       for (int j = 0; j < 4; ++j) a[n][j] = gelu_tanh(a[n][j]);
	v_mul_f32_e32 v38, v14, v38
	v_fma_f32 v38, v14, v38, v14
	v_mul_f32_e32 v38, 0x3f4c422a, v38
	v_add_f32_e32 v38, v38, v38
	v_mul_f32_e32 v38, 0x3fb8aa3b, v38
	v_exp_f32_e32 v38, v38
	s_nop 0
	v_add_f32_e32 v38, 1.0, v38
	s_nop 0
	v_rcp_f32_e32 v42, v38
	s_nop 0
	v_fma_f32 v39, -v38, v42, 1.0
	v_fma_f32 v42, v39, v42, v42
	v_add_f32_e32 v39, v42, v42
	v_div_fixup_f32 v38, v39, v38, 2.0
	v_sub_f32_e32 v38, 1.0, v38
	v_mul_f32_e32 v39, 0.5, v14
	v_add_f32_e32 v38, 1.0, v38
	v_mul_f32_e32 v42, v39, v38
	v_mul_f32_e32 v38, 0x3d372713, v15
	v_mul_f32_e32 v38, v15, v38
	v_fma_f32 v38, v15, v38, v15
	v_mul_f32_e32 v38, 0x3f4c422a, v38
	v_add_f32_e32 v38, v38, v38
	v_mul_f32_e32 v38, 0x3fb8aa3b, v38
	v_exp_f32_e32 v38, v38
	s_nop 0
	v_add_f32_e32 v38, 1.0, v38
	s_nop 0
	v_rcp_f32_e32 v43, v38
	s_nop 0
	v_fma_f32 v39, -v38, v43, 1.0
	v_fma_f32 v43, v39, v43, v43
	v_add_f32_e32 v39, v43, v43
	v_div_fixup_f32 v38, v39, v38, 2.0
	v_sub_f32_e32 v38, 1.0, v38
	v_mul_f32_e32 v39, 0.5, v15
	v_add_f32_e32 v38, 1.0, v38
	v_mul_f32_e32 v38, v39, v38
	v_mul_f32_e32 v39, 0x3d372713, v8
	v_mul_f32_e32 v39, v8, v39
	v_fma_f32 v39, v8, v39, v8
	v_mul_f32_e32 v39, 0x3f4c422a, v39
	v_add_f32_e32 v39, v39, v39
	v_mul_f32_e32 v39, 0x3fb8aa3b, v39
	v_exp_f32_e32 v39, v39
	s_nop 0
	v_add_f32_e32 v39, 1.0, v39
	s_nop 0
	v_rcp_f32_e32 v45, v39
	s_nop 0
	v_fma_f32 v43, -v39, v45, 1.0
	v_fma_f32 v45, v43, v45, v45
	v_add_f32_e32 v43, v45, v45
	v_div_fixup_f32 v39, v43, v39, 2.0
	v_sub_f32_e32 v39, 1.0, v39
	v_mul_f32_e32 v43, 0.5, v8
	v_add_f32_e32 v39, 1.0, v39
	v_mul_f32_e32 v58, v43, v39
	v_mul_f32_e32 v39, 0x3d372713, v9
	v_mul_f32_e32 v39, v9, v39
	v_fma_f32 v39, v9, v39, v9
	v_mul_f32_e32 v39, 0x3f4c422a, v39
	v_add_f32_e32 v39, v39, v39
	v_mul_f32_e32 v39, 0x3fb8aa3b, v39
	v_exp_f32_e32 v39, v39
	s_nop 0
	v_add_f32_e32 v39, 1.0, v39
	s_nop 0
	v_rcp_f32_e32 v45, v39
	s_nop 0
	v_fma_f32 v43, -v39, v45, 1.0
	v_fma_f32 v45, v43, v45, v45
	v_add_f32_e32 v43, v45, v45
	v_div_fixup_f32 v39, v43, v39, 2.0
	v_sub_f32_e32 v39, 1.0, v39
	v_mul_f32_e32 v43, 0.5, v9
	v_add_f32_e32 v39, 1.0, v39
	v_mul_f32_e32 v54, v43, v39
	v_mul_f32_e32 v39, 0x3d372713, v10
	v_mul_f32_e32 v39, v10, v39
	v_fma_f32 v39, v10, v39, v10
	v_mul_f32_e32 v39, 0x3f4c422a, v39
	v_add_f32_e32 v39, v39, v39
	v_mul_f32_e32 v39, 0x3fb8aa3b, v39
	v_exp_f32_e32 v39, v39
	s_nop 0
	v_add_f32_e32 v39, 1.0, v39
	s_nop 0
	v_rcp_f32_e32 v45, v39
	s_nop 0
	v_fma_f32 v43, -v39, v45, 1.0
	v_fma_f32 v45, v43, v45, v45
	v_add_f32_e32 v43, v45, v45
	v_div_fixup_f32 v39, v43, v39, 2.0
	v_sub_f32_e32 v39, 1.0, v39
	v_mul_f32_e32 v43, 0.5, v10
	v_add_f32_e32 v39, 1.0, v39
	v_mul_f32_e32 v50, v43, v39
	v_mul_f32_e32 v39, 0x3d372713, v11
	v_mul_f32_e32 v39, v11, v39
	v_fma_f32 v39, v11, v39, v11
	v_mul_f32_e32 v39, 0x3f4c422a, v39
	v_add_f32_e32 v39, v39, v39
	v_mul_f32_e32 v39, 0x3fb8aa3b, v39
	v_exp_f32_e32 v39, v39
	s_nop 0
	v_add_f32_e32 v39, 1.0, v39
	s_nop 0
	v_rcp_f32_e32 v45, v39
	s_nop 0
	v_fma_f32 v43, -v39, v45, 1.0
	v_fma_f32 v45, v43, v45, v45
	v_add_f32_e32 v43, v45, v45
	v_div_fixup_f32 v39, v43, v39, 2.0
	v_sub_f32_e32 v39, 1.0, v39
	v_mul_f32_e32 v43, 0.5, v11
	v_add_f32_e32 v39, 1.0, v39
	v_mul_f32_e32 v46, v43, v39
	v_mul_f32_e32 v39, 0x3d372713, v20
	v_mul_f32_e32 v39, v20, v39
	v_fma_f32 v39, v20, v39, v20
	v_mul_f32_e32 v39, 0x3f4c422a, v39
	v_add_f32_e32 v39, v39, v39
	v_mul_f32_e32 v39, 0x3fb8aa3b, v39
	v_exp_f32_e32 v39, v39
	s_nop 0
	v_add_f32_e32 v39, 1.0, v39
	s_nop 0
	v_rcp_f32_e32 v45, v39
	s_nop 0
	v_fma_f32 v43, -v39, v45, 1.0
	v_fma_f32 v45, v43, v45, v45
	v_add_f32_e32 v43, v45, v45
	v_div_fixup_f32 v39, v43, v39, 2.0
	v_sub_f32_e32 v39, 1.0, v39
	v_mul_f32_e32 v43, 0.5, v20
	v_add_f32_e32 v39, 1.0, v39
	v_mul_f32_e32 v66, v43, v39
	v_mul_f32_e32 v39, 0x3d372713, v21
	v_mul_f32_e32 v39, v21, v39
	v_fma_f32 v39, v21, v39, v21
	v_mul_f32_e32 v39, 0x3f4c422a, v39
	v_add_f32_e32 v39, v39, v39
	v_mul_f32_e32 v39, 0x3fb8aa3b, v39
	v_exp_f32_e32 v39, v39
	s_nop 0
	v_add_f32_e32 v39, 1.0, v39
	s_nop 0
	v_rcp_f32_e32 v45, v39
	s_nop 0
	v_fma_f32 v43, -v39, v45, 1.0
	v_fma_f32 v45, v43, v45, v45
	v_add_f32_e32 v43, v45, v45
	v_div_fixup_f32 v39, v43, v39, 2.0
	v_sub_f32_e32 v39, 1.0, v39
	v_mul_f32_e32 v43, 0.5, v21
	v_add_f32_e32 v39, 1.0, v39
	v_mul_f32_e32 v60, v43, v39
	v_mul_f32_e32 v39, 0x3d372713, v22
	v_mul_f32_e32 v39, v22, v39
	v_fma_f32 v39, v22, v39, v22
	v_mul_f32_e32 v39, 0x3f4c422a, v39
	v_add_f32_e32 v39, v39, v39
	v_mul_f32_e32 v39, 0x3fb8aa3b, v39
	v_exp_f32_e32 v39, v39
	s_nop 0
	v_add_f32_e32 v39, 1.0, v39
	s_nop 0
	v_rcp_f32_e32 v45, v39
	s_nop 0
	v_fma_f32 v43, -v39, v45, 1.0
	v_fma_f32 v45, v43, v45, v45
	v_add_f32_e32 v43, v45, v45
	v_div_fixup_f32 v39, v43, v39, 2.0
	v_sub_f32_e32 v39, 1.0, v39
	v_mul_f32_e32 v43, 0.5, v22
	v_add_f32_e32 v39, 1.0, v39
	v_mul_f32_e32 v56, v43, v39
	v_mul_f32_e32 v39, 0x3d372713, v23
	v_mul_f32_e32 v39, v23, v39
	v_fma_f32 v39, v23, v39, v23
	v_mul_f32_e32 v39, 0x3f4c422a, v39
	v_add_f32_e32 v39, v39, v39
	v_mul_f32_e32 v39, 0x3fb8aa3b, v39
	v_exp_f32_e32 v39, v39
	s_nop 0
	v_add_f32_e32 v39, 1.0, v39
	s_nop 0
	v_rcp_f32_e32 v45, v39
	s_nop 0
	v_fma_f32 v43, -v39, v45, 1.0
	v_fma_f32 v45, v43, v45, v45
	v_add_f32_e32 v43, v45, v45
	v_div_fixup_f32 v39, v43, v39, 2.0
	v_sub_f32_e32 v39, 1.0, v39
	v_mul_f32_e32 v43, 0.5, v23
	v_add_f32_e32 v39, 1.0, v39
	v_mul_f32_e32 v52, v43, v39
	v_mul_f32_e32 v39, 0x3d372713, v16
	v_mul_f32_e32 v39, v16, v39
	v_fma_f32 v39, v16, v39, v16
	v_mul_f32_e32 v39, 0x3f4c422a, v39
	v_add_f32_e32 v39, v39, v39
	v_mul_f32_e32 v39, 0x3fb8aa3b, v39
	v_exp_f32_e32 v39, v39
	s_nop 0
	v_add_f32_e32 v39, 1.0, v39
	s_nop 0
; DEVFI float gelu_tanh(float x) {
;   float u = 0.7978845608028654f * (x + 0.044715f * x * x * x);
;   float t = __expf(2.f * u);
;   float th = 1.f - 2.f / (t + 1.f);
;   return 0.5f * x * (1.f + th);
; }
; __global__ void __launch_bounds__(512) mega(Params p) {
;     ...
;                   } else if (c0 < 6144) {
; #pragma unroll
;                     for (int n = 0; n < 8; ++n)
; #pragma unroll
;                       for (int j = 0; j < 4; ++j) a[n][j] = gelu_tanh(a[n][j]);
	v_rcp_f32_e32 v45, v39
	s_nop 0
	v_fma_f32 v43, -v39, v45, 1.0
	v_fma_f32 v45, v43, v45, v45
	v_add_f32_e32 v43, v45, v45
	v_div_fixup_f32 v39, v43, v39, 2.0
	v_sub_f32_e32 v39, 1.0, v39
	v_mul_f32_e32 v43, 0.5, v16
	v_add_f32_e32 v39, 1.0, v39
	v_mul_f32_e32 v76, v43, v39
	v_mul_f32_e32 v39, 0x3d372713, v17
	v_mul_f32_e32 v39, v17, v39
	v_fma_f32 v39, v17, v39, v17
	v_mul_f32_e32 v39, 0x3f4c422a, v39
	v_add_f32_e32 v39, v39, v39
	v_mul_f32_e32 v39, 0x3fb8aa3b, v39
	v_exp_f32_e32 v39, v39
	s_nop 0
	v_add_f32_e32 v39, 1.0, v39
	s_nop 0
	v_rcp_f32_e32 v45, v39
	s_nop 0
	v_fma_f32 v43, -v39, v45, 1.0
	v_fma_f32 v45, v43, v45, v45
	v_add_f32_e32 v43, v45, v45
	v_div_fixup_f32 v39, v43, v39, 2.0
	v_sub_f32_e32 v39, 1.0, v39
	v_mul_f32_e32 v43, 0.5, v17
	v_add_f32_e32 v39, 1.0, v39
	v_mul_f32_e32 v72, v43, v39
	v_mul_f32_e32 v39, 0x3d372713, v18
	v_mul_f32_e32 v39, v18, v39
	v_fma_f32 v39, v18, v39, v18
	v_mul_f32_e32 v39, 0x3f4c422a, v39
	v_add_f32_e32 v39, v39, v39
	v_mul_f32_e32 v39, 0x3fb8aa3b, v39
	v_exp_f32_e32 v39, v39
	s_nop 0
	v_add_f32_e32 v39, 1.0, v39
	s_nop 0
	v_rcp_f32_e32 v45, v39
	s_nop 0
	v_fma_f32 v43, -v39, v45, 1.0
	v_fma_f32 v45, v43, v45, v45
	v_add_f32_e32 v43, v45, v45
	v_div_fixup_f32 v39, v43, v39, 2.0
	v_sub_f32_e32 v39, 1.0, v39
	v_mul_f32_e32 v43, 0.5, v18
	v_add_f32_e32 v39, 1.0, v39
	v_mul_f32_e32 v68, v43, v39
	v_mul_f32_e32 v39, 0x3d372713, v19
	v_mul_f32_e32 v39, v19, v39
	v_fma_f32 v39, v19, v39, v19
	v_mul_f32_e32 v39, 0x3f4c422a, v39
	v_add_f32_e32 v39, v39, v39
	v_mul_f32_e32 v39, 0x3fb8aa3b, v39
	v_exp_f32_e32 v39, v39
	s_nop 0
	v_add_f32_e32 v39, 1.0, v39
	s_nop 0
	v_rcp_f32_e32 v45, v39
	s_nop 0
	v_fma_f32 v43, -v39, v45, 1.0
	v_fma_f32 v45, v43, v45, v45
	v_add_f32_e32 v43, v45, v45
	v_div_fixup_f32 v39, v43, v39, 2.0
	v_sub_f32_e32 v39, 1.0, v39
	v_mul_f32_e32 v43, 0.5, v19
	v_add_f32_e32 v39, 1.0, v39
	v_mul_f32_e32 v62, v43, v39
	v_mul_f32_e32 v39, 0x3d372713, v4
	v_mul_f32_e32 v39, v4, v39
	v_fma_f32 v39, v4, v39, v4
	v_mul_f32_e32 v39, 0x3f4c422a, v39
	v_add_f32_e32 v39, v39, v39
	v_mul_f32_e32 v39, 0x3fb8aa3b, v39
	v_exp_f32_e32 v39, v39
	s_nop 0
	v_add_f32_e32 v39, 1.0, v39
	s_nop 0
	v_rcp_f32_e32 v45, v39
	s_nop 0
	v_fma_f32 v43, -v39, v45, 1.0
	v_fma_f32 v45, v43, v45, v45
	v_add_f32_e32 v43, v45, v45
	v_div_fixup_f32 v39, v43, v39, 2.0
	v_sub_f32_e32 v39, 1.0, v39
	v_mul_f32_e32 v43, 0.5, v4
	v_add_f32_e32 v39, 1.0, v39
	v_mul_f32_e32 v82, v43, v39
	v_mul_f32_e32 v39, 0x3d372713, v5
	v_mul_f32_e32 v39, v5, v39
	v_fma_f32 v39, v5, v39, v5
	v_mul_f32_e32 v39, 0x3f4c422a, v39
	v_add_f32_e32 v39, v39, v39
	v_mul_f32_e32 v39, 0x3fb8aa3b, v39
	v_exp_f32_e32 v39, v39
	s_nop 0
	v_add_f32_e32 v39, 1.0, v39
	s_nop 0
	v_rcp_f32_e32 v45, v39
	s_nop 0
	v_fma_f32 v43, -v39, v45, 1.0
	v_fma_f32 v45, v43, v45, v45
	v_add_f32_e32 v43, v45, v45
	v_div_fixup_f32 v39, v43, v39, 2.0
	v_sub_f32_e32 v39, 1.0, v39
	v_mul_f32_e32 v43, 0.5, v5
	v_add_f32_e32 v39, 1.0, v39
	v_mul_f32_e32 v78, v43, v39
	v_mul_f32_e32 v39, 0x3d372713, v6
	v_mul_f32_e32 v39, v6, v39
	v_fma_f32 v39, v6, v39, v6
	v_mul_f32_e32 v39, 0x3f4c422a, v39
	v_add_f32_e32 v39, v39, v39
	v_mul_f32_e32 v39, 0x3fb8aa3b, v39
	v_exp_f32_e32 v39, v39
	s_nop 0
	v_add_f32_e32 v39, 1.0, v39
	s_nop 0
	v_rcp_f32_e32 v45, v39
	s_nop 0
	v_fma_f32 v43, -v39, v45, 1.0
	v_fma_f32 v45, v43, v45, v45
	v_add_f32_e32 v43, v45, v45
	v_div_fixup_f32 v39, v43, v39, 2.0
	v_sub_f32_e32 v39, 1.0, v39
	v_mul_f32_e32 v43, 0.5, v6
	v_add_f32_e32 v39, 1.0, v39
	v_mul_f32_e32 v74, v43, v39
	v_mul_f32_e32 v39, 0x3d372713, v7
	v_mul_f32_e32 v39, v7, v39
	v_fma_f32 v39, v7, v39, v7
	v_mul_f32_e32 v39, 0x3f4c422a, v39
	v_add_f32_e32 v39, v39, v39
	v_mul_f32_e32 v39, 0x3fb8aa3b, v39
	v_exp_f32_e32 v39, v39
	s_nop 0
	v_add_f32_e32 v39, 1.0, v39
	s_nop 0
	v_rcp_f32_e32 v45, v39
	s_nop 0
	v_fma_f32 v43, -v39, v45, 1.0
	v_fma_f32 v45, v43, v45, v45
	v_add_f32_e32 v43, v45, v45
	v_div_fixup_f32 v39, v43, v39, 2.0
	v_sub_f32_e32 v39, 1.0, v39
	v_mul_f32_e32 v43, 0.5, v7
	v_add_f32_e32 v39, 1.0, v39
	v_mul_f32_e32 v70, v43, v39
	v_mul_f32_e32 v39, 0x3d372713, v0
	v_mul_f32_e32 v39, v0, v39
	v_fma_f32 v39, v0, v39, v0
	v_mul_f32_e32 v39, 0x3f4c422a, v39
	v_add_f32_e32 v39, v39, v39
	v_mul_f32_e32 v39, 0x3fb8aa3b, v39
	v_exp_f32_e32 v39, v39
	s_nop 0
	v_add_f32_e32 v39, 1.0, v39
	s_nop 0
	v_rcp_f32_e32 v45, v39
	s_nop 0
	v_fma_f32 v43, -v39, v45, 1.0
	v_fma_f32 v45, v43, v45, v45
	v_add_f32_e32 v43, v45, v45
	v_div_fixup_f32 v39, v43, v39, 2.0
	v_sub_f32_e32 v39, 1.0, v39
	v_mul_f32_e32 v43, 0.5, v0
	v_add_f32_e32 v39, 1.0, v39
	v_mul_f32_e32 v88, v43, v39
	v_mul_f32_e32 v39, 0x3d372713, v1
	v_mul_f32_e32 v39, v1, v39
	v_fma_f32 v39, v1, v39, v1
	v_mul_f32_e32 v39, 0x3f4c422a, v39
	v_add_f32_e32 v39, v39, v39
	v_mul_f32_e32 v39, 0x3fb8aa3b, v39
	v_exp_f32_e32 v39, v39
	s_nop 0
	v_add_f32_e32 v39, 1.0, v39
	s_nop 0
	v_rcp_f32_e32 v45, v39
	s_nop 0
	v_fma_f32 v43, -v39, v45, 1.0
	v_fma_f32 v45, v43, v45, v45
	v_add_f32_e32 v43, v45, v45
	v_div_fixup_f32 v39, v43, v39, 2.0
	v_sub_f32_e32 v39, 1.0, v39
	v_mul_f32_e32 v43, 0.5, v1
	v_add_f32_e32 v39, 1.0, v39
	v_mul_f32_e32 v86, v43, v39
	v_mul_f32_e32 v39, 0x3d372713, v2
	v_mul_f32_e32 v39, v2, v39
	v_fma_f32 v39, v2, v39, v2
	v_mul_f32_e32 v39, 0x3f4c422a, v39
	v_add_f32_e32 v39, v39, v39
	v_mul_f32_e32 v39, 0x3fb8aa3b, v39
	v_exp_f32_e32 v39, v39
	s_nop 0
	v_add_f32_e32 v39, 1.0, v39
	s_nop 0
	v_rcp_f32_e32 v45, v39
	s_nop 0
	v_fma_f32 v43, -v39, v45, 1.0
	v_fma_f32 v45, v43, v45, v45
	v_add_f32_e32 v43, v45, v45
	v_div_fixup_f32 v39, v43, v39, 2.0
	v_sub_f32_e32 v39, 1.0, v39
	v_mul_f32_e32 v43, 0.5, v2
	v_add_f32_e32 v39, 1.0, v39
	v_mul_f32_e32 v84, v43, v39
	v_mul_f32_e32 v39, 0x3d372713, v3
	v_mul_f32_e32 v39, v3, v39
	v_fma_f32 v39, v3, v39, v3
	v_mul_f32_e32 v39, 0x3f4c422a, v39
	v_add_f32_e32 v39, v39, v39
	v_mul_f32_e32 v39, 0x3fb8aa3b, v39
	v_exp_f32_e32 v39, v39
	s_nop 0
	v_add_f32_e32 v39, 1.0, v39
	s_nop 0
	v_rcp_f32_e32 v45, v39
	s_nop 0
	v_fma_f32 v43, -v39, v45, 1.0
	v_fma_f32 v45, v43, v45, v45
	v_add_f32_e32 v43, v45, v45
	v_div_fixup_f32 v39, v43, v39, 2.0
	v_sub_f32_e32 v39, 1.0, v39
	v_mul_f32_e32 v43, 0.5, v3
	v_add_f32_e32 v39, 1.0, v39
	v_mul_f32_e32 v80, v43, v39
	s_cbranch_scc1 .LBB0_2203
; #define SVSTAT ((float*)(kargs()->ws + O_SVSTAT))
; __global__ void __launch_bounds__(512) mega(Params p) {
;     ...
;                     if (c0 >= 5120) { float* stp = SVSTAT + (long)r0 * 16 + ((c0 - 5120) >> 7) * 2;
; #pragma unroll
;                       for (int j = 0; j < 4; ++j) { float s1 = 0, s2 = 0;
; #pragma unroll
;                         for (int n = 0; n < 8; ++n) { s1 += a[n][j]; s2 += a[n][j] * a[n][j]; }
;                         s1 = red16(s1); s2 = red16(s2);
;                         if (fr == 0) { stp[j * 16] = s1; stp[j * 16 + 1] = s2; } } }
	s_mov_b64 s[2:3], s[0:1]
	s_load_dwordx2 s[2:3], s[2:3], 0xe8
	v_ashrrev_i32_e32 v65, 31, v64
	v_lshlrev_b64 v[90:91], 6, v[64:65]
	v_add_u32_e32 v39, 0xffffec00, v176
	v_lshrrev_b32_e32 v92, 4, v39
	s_waitcnt lgkmcnt(0)
	v_lshl_add_u64 v[90:91], s[2:3], 0, v[90:91]
	v_mov_b32_e32 v93, v177
	v_lshl_add_u64 v[90:91], v[90:91], 0, v[92:93]
	v_mov_b32_e32 v92, v177
	v_mov_b32_e32 v93, v41
	v_pk_add_f32 v[92:93], v[40:41], v[92:93]
	v_pk_mul_f32 v[94:95], v[40:41], v[40:41]
	s_mov_b64 s[2:3], 0x3a720400
	v_mov_b32_e32 v93, v95
	v_pk_mov_b32 v[94:95], v[40:41], v[94:95] op_sel:[1,0]
	v_lshl_add_u64 v[90:91], v[90:91], 0, s[2:3]
	v_mul_f32_e32 v49, v48, v48
	s_mov_b32 s2, -1
	v_pk_add_f32 v[92:93], v[92:93], v[94:95]
	v_mul_f32_e32 v59, v58, v58
	v_pk_add_f32 v[92:93], v[92:93], v[48:49]
	v_mbcnt_lo_u32_b32 v39, s2, 0
	v_mul_f32_e32 v67, v66, v66
	v_mbcnt_hi_u32_b32 v39, s2, v39
	s_mov_b32 s2, -1
	v_pk_add_f32 v[92:93], v[92:93], v[58:59]
	v_mul_f32_e32 v77, v76, v76
	v_pk_add_f32 v[92:93], v[92:93], v[66:67]
	v_mbcnt_lo_u32_b32 v51, s2, 0
	v_mul_f32_e32 v83, v82, v82
	v_mbcnt_hi_u32_b32 v51, s2, v51
	v_pk_add_f32 v[92:93], v[92:93], v[76:77]
	v_mul_f32_e32 v89, v88, v88
	v_lshlrev_b32_e32 v39, 2, v39
	v_lshlrev_b32_e32 v51, 2, v51
	v_pk_add_f32 v[92:93], v[92:93], v[82:83]
	v_xor_b32_e32 v43, 4, v39
	v_xor_b32_e32 v53, 4, v51
	v_pk_add_f32 v[92:93], v[92:93], v[88:89]
	ds_bpermute_b32 v94, v43, v92
	ds_bpermute_b32 v95, v53, v93
	v_xor_b32_e32 v45, 8, v39
	v_xor_b32_e32 v55, 8, v51
	v_xor_b32_e32 v47, 16, v39
	v_xor_b32_e32 v57, 16, v51
	s_waitcnt lgkmcnt(0)
	v_pk_add_f32 v[92:93], v[92:93], v[94:95]
	ds_bpermute_b32 v94, v45, v92
	ds_bpermute_b32 v95, v55, v93
	v_xor_b32_e32 v39, 32, v39
	v_cmp_eq_u32_e32 vcc, 0, v202
	s_waitcnt lgkmcnt(0)
	v_pk_add_f32 v[92:93], v[92:93], v[94:95]
	ds_bpermute_b32 v94, v47, v92
	ds_bpermute_b32 v95, v57, v93
	s_waitcnt lgkmcnt(0)
	v_pk_add_f32 v[92:93], v[92:93], v[94:95]
	ds_bpermute_b32 v94, v39, v92
	v_xor_b32_e32 v39, 32, v51
	ds_bpermute_b32 v95, v39, v93
	s_and_saveexec_b64 s[2:3], vcc
	s_cbranch_execz .LBB0_2196
	s_waitcnt lgkmcnt(0)
	v_pk_add_f32 v[92:93], v[92:93], v[94:95]
	global_store_dwordx2 v[90:91], v[92:93], off

; DEVFI float sigmoidf_(float x) { return 1.f / (1.f + __expf(-x)); }
; DEVFI float dpp_xor1(float x) { return __int_as_float(__builtin_amdgcn_update_dpp(0, __float_as_int(x), 0xB1, 0xF, 0xF, true)); }
; #define RG ((bfraw*)(kargs()->ws + O_RG))
; DEVFI void store_nat_m(bfraw* base, long ld, f32x4 (&a)[8], int fr) {
;   const bool odd = fr & 1;
;   bfraw* p0 = base + (odd ? 15 + fr : fr);
; #pragma unroll
;   for (int j = 0; j < 4; ++j)
; #pragma unroll
;     for (int n0 = 0; n0 < 8; n0 += 2) { const float own0 = a[n0][j], own1 = a[n0 + 1][j];
;       const float recv = dpp_xor1(odd ? own0 : own1);
;       const unsigned pk = odd ? cvtpk(recv, own1) : cvtpk(own0, recv);
;       *reinterpret_cast<unsigned*>(p0 + (long)j * ld + n0 * 16) = pk; }
; }
; __global__ void __launch_bounds__(512) mega(Params p) {
;     ...
;                   } else if (c0 < 4096) {
; #pragma unroll
;                     for (int n = 0; n < 8; ++n)
; #pragma unroll
;                       for (int j = 0; j < 4; ++j) { const float x = a[n][j]; a[n][j] = x * sigmoidf_(x); }
;                     store_nat_m(RG + (long)r0 * 1024 + (c0 - 3072), 1024, a, fr);
.LBB0_2271:
	s_andn2_b64 vcc, exec, s[2:3]
	s_cbranch_vccnz .LBB0_2337
	v_mul_f32_e32 v32, 0xbfb8aa3b, v28
	v_exp_f32_e32 v32, v32
	s_nop 0
	v_add_f32_e32 v32, 1.0, v32
	s_nop 0
	v_rcp_f32_e32 v34, v32
	s_nop 0
	v_fma_f32 v33, -v32, v34, 1.0
	v_fma_f32 v33, v33, v34, v34
	v_div_fixup_f32 v32, v33, v32, 1.0
	v_mul_f32_e32 v33, 0xbfb8aa3b, v24
	v_exp_f32_e32 v33, v33
	v_mul_f32_e32 v32, v28, v32
	v_add_f32_e32 v33, 1.0, v33
	s_nop 0
	v_rcp_f32_e32 v35, v33
	s_nop 0
	v_fma_f32 v34, -v33, v35, 1.0
	v_fma_f32 v34, v34, v35, v35
	v_div_fixup_f32 v33, v34, v33, 1.0
	v_mul_f32_e32 v34, 0xbfb8aa3b, v12
	v_exp_f32_e32 v34, v34
	v_mul_f32_e32 v33, v24, v33
	v_add_f32_e32 v34, 1.0, v34
	s_nop 0
	v_rcp_f32_e32 v36, v34
	s_nop 0
	v_fma_f32 v35, -v34, v36, 1.0
	v_fma_f32 v36, v35, v36, v36
	v_mul_f32_e32 v35, 0xbfb8aa3b, v8
	v_exp_f32_e32 v35, v35
	s_nop 0
	v_add_f32_e32 v37, 1.0, v35
	s_mov_b64 s[2:3], s[0:1]
	s_load_dwordx2 s[2:3], s[2:3], 0xe8
	v_rcp_f32_e32 v38, v37
	s_nop 0
	v_fma_f32 v35, -v37, v38, 1.0
	v_fma_f32 v38, v35, v38, v38
	v_and_b32_e32 v35, 1, v203
	v_cmp_eq_u32_e64 s[6:7], 0, v35
	v_cmp_eq_u32_e64 s[4:5], 1, v35
	s_nop 0
	v_cndmask_b32_e64 v35, v32, v33, s[6:7]
	s_nop 1
	v_mov_b32_dpp v39, v35 quad_perm:[1,0,3,2] row_mask:0xf bank_mask:0xf bound_ctrl:1
	s_and_saveexec_b64 s[26:27], s[4:5]
	s_xor_b64 s[26:27], exec, s[26:27]
	s_cbranch_execz .LBB0_2274
	v_cvt_pk_bf16_f32 v35, v39, v33

; DEVFI float sigmoidf_(float x) { return 1.f / (1.f + __expf(-x)); }
; DEVFI float dpp_xor1(float x) { return __int_as_float(__builtin_amdgcn_update_dpp(0, __float_as_int(x), 0xB1, 0xF, 0xF, true)); }
; #define RG ((bfraw*)(kargs()->ws + O_RG))
; DEVFI void store_nat_m(bfraw* base, long ld, f32x4 (&a)[8], int fr) {
;   const bool odd = fr & 1;
;   bfraw* p0 = base + (odd ? 15 + fr : fr);
; #pragma unroll
;   for (int j = 0; j < 4; ++j)
; #pragma unroll
;     for (int n0 = 0; n0 < 8; n0 += 2) { const float own0 = a[n0][j], own1 = a[n0 + 1][j];
;       const float recv = dpp_xor1(odd ? own0 : own1);
;       const unsigned pk = odd ? cvtpk(recv, own1) : cvtpk(own0, recv);
;       *reinterpret_cast<unsigned*>(p0 + (long)j * ld + n0 * 16) = pk; }
; }
; __global__ void __launch_bounds__(512) mega(Params p) {
;     ...
;                   } else if (c0 < 4096) {
; #pragma unroll
;                     for (int n = 0; n < 8; ++n)
; #pragma unroll
;                       for (int j = 0; j < 4; ++j) { const float x = a[n][j]; a[n][j] = x * sigmoidf_(x); }
;                     store_nat_m(RG + (long)r0 * 1024 + (c0 - 3072), 1024, a, fr);
.LBB0_2276:
	s_or_b64 exec, exec, s[26:27]
	v_mul_f32_e32 v32, 0xbfb8aa3b, v20
	v_exp_f32_e32 v32, v32
	v_ashrrev_i32_e32 v65, 31, v64
	v_add_f32_e32 v38, 1.0, v32
	s_nop 0
	v_rcp_f32_e32 v33, v38
	s_nop 0
	v_fma_f32 v32, -v38, v33, 1.0
	v_fma_f32 v39, v32, v33, v33
	v_mul_f32_e32 v32, 0xbfb8aa3b, v16
	v_exp_f32_e32 v32, v32
	s_nop 0
	v_add_f32_e32 v40, 1.0, v32
	s_nop 0
	v_rcp_f32_e32 v33, v40
	s_nop 0
	v_fma_f32 v32, -v40, v33, 1.0
	v_fma_f32 v41, v32, v33, v33
	v_lshlrev_b64 v[32:33], 11, v[64:65]
	v_add_u32_e32 v42, 15, v202
	s_waitcnt lgkmcnt(0)
	v_lshl_add_u64 v[32:33], s[2:3], 0, v[32:33]
	v_cndmask_b32_e64 v42, v42, v202, s[6:7]
	v_lshl_add_u64 v[32:33], v[176:177], 1, v[32:33]
	v_lshlrev_b32_e32 v42, 1, v42
	v_mov_b32_e32 v43, v177
	v_lshl_add_u64 v[32:33], v[32:33], 0, v[42:43]
	v_add_co_u32_e32 v42, vcc, 0x1971e000, v32
	s_nop 1
	v_addc_co_u32_e32 v43, vcc, 0, v33, vcc
	global_store_dword v[42:43], v35, off offset:2048
	v_mov_b32_dpp v42, v37 quad_perm:[1,0,3,2] row_mask:0xf bank_mask:0xf bound_ctrl:1
	s_and_saveexec_b64 s[2:3], s[4:5]
	s_xor_b64 s[2:3], exec, s[2:3]
	s_cbranch_execz .LBB0_2278
	v_cvt_pk_bf16_f32 v37, v42, v36

; DEVFI float sigmoidf_(float x) { return 1.f / (1.f + __expf(-x)); }
; DEVFI float dpp_xor1(float x) { return __int_as_float(__builtin_amdgcn_update_dpp(0, __float_as_int(x), 0xB1, 0xF, 0xF, true)); }
; #define RG ((bfraw*)(kargs()->ws + O_RG))
; DEVFI void store_nat_m(bfraw* base, long ld, f32x4 (&a)[8], int fr) {
;   const bool odd = fr & 1;
;   bfraw* p0 = base + (odd ? 15 + fr : fr);
; #pragma unroll
;   for (int j = 0; j < 4; ++j)
; #pragma unroll
;     for (int n0 = 0; n0 < 8; n0 += 2) { const float own0 = a[n0][j], own1 = a[n0 + 1][j];
;       const float recv = dpp_xor1(odd ? own0 : own1);
;       const unsigned pk = odd ? cvtpk(recv, own1) : cvtpk(own0, recv);
;       *reinterpret_cast<unsigned*>(p0 + (long)j * ld + n0 * 16) = pk; }
; }
; __global__ void __launch_bounds__(512) mega(Params p) {
;     ...
;                   } else if (c0 < 4096) {
; #pragma unroll
;                     for (int n = 0; n < 8; ++n)
; #pragma unroll
;                       for (int j = 0; j < 4; ++j) { const float x = a[n][j]; a[n][j] = x * sigmoidf_(x); }
;                     store_nat_m(RG + (long)r0 * 1024 + (c0 - 3072), 1024, a, fr);
.LBB0_2280:
	s_or_b64 exec, exec, s[2:3]
	v_mul_f32_e32 v34, 0xbfb8aa3b, v4
	v_exp_f32_e32 v34, v34
	s_mov_b64 s[2:3], 0x1971e800
	v_lshl_add_u64 v[32:33], v[32:33], 0, s[2:3]
	global_store_dword v[32:33], v37, off offset:64
	v_add_f32_e32 v34, 1.0, v34
	s_nop 0
	v_rcp_f32_e32 v40, v34
	s_nop 0
	v_fma_f32 v39, -v34, v40, 1.0
	v_fma_f32 v39, v39, v40, v40
	v_mul_f32_e32 v40, 0xbfb8aa3b, v0
	v_exp_f32_e32 v40, v40
	s_nop 0
	v_add_f32_e32 v40, 1.0, v40
	s_nop 0
	v_rcp_f32_e32 v42, v40
	s_nop 0
	v_fma_f32 v41, -v40, v42, 1.0
	v_fma_f32 v42, v41, v42, v42
	s_nop 0
	v_mov_b32_dpp v41, v38 quad_perm:[1,0,3,2] row_mask:0xf bank_mask:0xf bound_ctrl:1
	s_and_saveexec_b64 s[2:3], s[4:5]
	s_xor_b64 s[2:3], exec, s[2:3]
	s_cbranch_execz .LBB0_2282
	v_cvt_pk_bf16_f32 v37, v41, v36

; DEVFI float sigmoidf_(float x) { return 1.f / (1.f + __expf(-x)); }
; DEVFI float dpp_xor1(float x) { return __int_as_float(__builtin_amdgcn_update_dpp(0, __float_as_int(x), 0xB1, 0xF, 0xF, true)); }
; #define RG ((bfraw*)(kargs()->ws + O_RG))
; DEVFI void store_nat_m(bfraw* base, long ld, f32x4 (&a)[8], int fr) {
;   const bool odd = fr & 1;
;   bfraw* p0 = base + (odd ? 15 + fr : fr);
; #pragma unroll
;   for (int j = 0; j < 4; ++j)
; #pragma unroll
;     for (int n0 = 0; n0 < 8; n0 += 2) { const float own0 = a[n0][j], own1 = a[n0 + 1][j];
;       const float recv = dpp_xor1(odd ? own0 : own1);
;       const unsigned pk = odd ? cvtpk(recv, own1) : cvtpk(own0, recv);
;       *reinterpret_cast<unsigned*>(p0 + (long)j * ld + n0 * 16) = pk; }
; }
; __global__ void __launch_bounds__(512) mega(Params p) {
;     ...
;                   } else if (c0 < 4096) {
; #pragma unroll
;                     for (int n = 0; n < 8; ++n)
; #pragma unroll
;                       for (int j = 0; j < 4; ++j) { const float x = a[n][j]; a[n][j] = x * sigmoidf_(x); }
;                     store_nat_m(RG + (long)r0 * 1024 + (c0 - 3072), 1024, a, fr);
.LBB0_2284:
	s_or_b64 exec, exec, s[2:3]
	v_mul_f32_e32 v35, 0xbfb8aa3b, v29
	v_exp_f32_e32 v35, v35
	global_store_dword v[32:33], v37, off offset:128
	v_add_f32_e32 v35, 1.0, v35
	s_nop 0
	v_rcp_f32_e32 v40, v35
	s_nop 0
	v_fma_f32 v39, -v35, v40, 1.0
	v_fma_f32 v39, v39, v40, v40
	v_mul_f32_e32 v40, 0xbfb8aa3b, v25
	v_exp_f32_e32 v40, v40
	s_nop 0
	v_add_f32_e32 v40, 1.0, v40
	s_nop 0
	v_rcp_f32_e32 v42, v40
	s_nop 0
	v_fma_f32 v41, -v40, v42, 1.0
	v_fma_f32 v42, v41, v42, v42
	s_nop 0
	v_mov_b32_dpp v41, v36 quad_perm:[1,0,3,2] row_mask:0xf bank_mask:0xf bound_ctrl:1
	s_and_saveexec_b64 s[2:3], s[4:5]
	s_xor_b64 s[2:3], exec, s[2:3]
	s_cbranch_execz .LBB0_2286
	v_cvt_pk_bf16_f32 v36, v41, v38

; DEVFI float sigmoidf_(float x) { return 1.f / (1.f + __expf(-x)); }
; DEVFI float dpp_xor1(float x) { return __int_as_float(__builtin_amdgcn_update_dpp(0, __float_as_int(x), 0xB1, 0xF, 0xF, true)); }
; #define RG ((bfraw*)(kargs()->ws + O_RG))
; DEVFI void store_nat_m(bfraw* base, long ld, f32x4 (&a)[8], int fr) {
;   const bool odd = fr & 1;
;   bfraw* p0 = base + (odd ? 15 + fr : fr);
; #pragma unroll
;   for (int j = 0; j < 4; ++j)
; #pragma unroll
;     for (int n0 = 0; n0 < 8; n0 += 2) { const float own0 = a[n0][j], own1 = a[n0 + 1][j];
;       const float recv = dpp_xor1(odd ? own0 : own1);
;       const unsigned pk = odd ? cvtpk(recv, own1) : cvtpk(own0, recv);
;       *reinterpret_cast<unsigned*>(p0 + (long)j * ld + n0 * 16) = pk; }
; }
; __global__ void __launch_bounds__(512) mega(Params p) {
;     ...
;                   } else if (c0 < 4096) {
; #pragma unroll
;                     for (int n = 0; n < 8; ++n)
; #pragma unroll
;                       for (int j = 0; j < 4; ++j) { const float x = a[n][j]; a[n][j] = x * sigmoidf_(x); }
;                     store_nat_m(RG + (long)r0 * 1024 + (c0 - 3072), 1024, a, fr);
.LBB0_2288:
	s_or_b64 exec, exec, s[2:3]
	v_mul_f32_e32 v34, 0xbfb8aa3b, v13
	v_exp_f32_e32 v34, v34
	global_store_dword v[32:33], v36, off offset:192
	v_add_f32_e32 v34, 1.0, v34
	s_nop 0
	v_rcp_f32_e32 v40, v34
	s_nop 0
	v_fma_f32 v38, -v34, v40, 1.0
	v_fma_f32 v38, v38, v40, v40
	v_mul_f32_e32 v40, 0xbfb8aa3b, v9
	v_exp_f32_e32 v40, v40
	s_nop 0
	v_add_f32_e32 v40, 1.0, v40
	s_nop 0
	v_rcp_f32_e32 v42, v40
	s_nop 0
	v_fma_f32 v41, -v40, v42, 1.0
	v_fma_f32 v42, v41, v42, v42
	s_nop 0
	v_mov_b32_dpp v41, v39 quad_perm:[1,0,3,2] row_mask:0xf bank_mask:0xf bound_ctrl:1
	s_and_saveexec_b64 s[2:3], s[4:5]
	s_xor_b64 s[2:3], exec, s[2:3]
	s_cbranch_execz .LBB0_2290
	v_cvt_pk_bf16_f32 v36, v41, v37

; DEVFI float sigmoidf_(float x) { return 1.f / (1.f + __expf(-x)); }
; DEVFI float dpp_xor1(float x) { return __int_as_float(__builtin_amdgcn_update_dpp(0, __float_as_int(x), 0xB1, 0xF, 0xF, true)); }
; #define RG ((bfraw*)(kargs()->ws + O_RG))
; DEVFI void store_nat_m(bfraw* base, long ld, f32x4 (&a)[8], int fr) {
;   const bool odd = fr & 1;
;   bfraw* p0 = base + (odd ? 15 + fr : fr);
; #pragma unroll
;   for (int j = 0; j < 4; ++j)
; #pragma unroll
;     for (int n0 = 0; n0 < 8; n0 += 2) { const float own0 = a[n0][j], own1 = a[n0 + 1][j];
;       const float recv = dpp_xor1(odd ? own0 : own1);
;       const unsigned pk = odd ? cvtpk(recv, own1) : cvtpk(own0, recv);
;       *reinterpret_cast<unsigned*>(p0 + (long)j * ld + n0 * 16) = pk; }
; }
; __global__ void __launch_bounds__(512) mega(Params p) {
;     ...
;                   } else if (c0 < 4096) {
; #pragma unroll
;                     for (int n = 0; n < 8; ++n)
; #pragma unroll
;                       for (int j = 0; j < 4; ++j) { const float x = a[n][j]; a[n][j] = x * sigmoidf_(x); }
;                     store_nat_m(RG + (long)r0 * 1024 + (c0 - 3072), 1024, a, fr);
.LBB0_2292:
	s_or_b64 exec, exec, s[2:3]
	v_mul_f32_e32 v35, 0xbfb8aa3b, v21
	v_exp_f32_e32 v35, v35
	global_store_dword v[32:33], v36, off offset:2048
	v_add_f32_e32 v35, 1.0, v35
	s_nop 0
	v_rcp_f32_e32 v40, v35
	s_nop 0
	v_fma_f32 v38, -v35, v40, 1.0
	v_fma_f32 v38, v38, v40, v40
	v_mul_f32_e32 v40, 0xbfb8aa3b, v17
	v_exp_f32_e32 v40, v40
	s_nop 0
	v_add_f32_e32 v40, 1.0, v40
	s_nop 0
	v_rcp_f32_e32 v42, v40
	s_nop 0
	v_fma_f32 v41, -v40, v42, 1.0
	v_fma_f32 v42, v41, v42, v42
	s_nop 0
	v_mov_b32_dpp v41, v39 quad_perm:[1,0,3,2] row_mask:0xf bank_mask:0xf bound_ctrl:1
	s_and_saveexec_b64 s[2:3], s[4:5]
	s_xor_b64 s[2:3], exec, s[2:3]
	s_cbranch_execz .LBB0_2294
	v_cvt_pk_bf16_f32 v36, v41, v37

; DEVFI float sigmoidf_(float x) { return 1.f / (1.f + __expf(-x)); }
; DEVFI float dpp_xor1(float x) { return __int_as_float(__builtin_amdgcn_update_dpp(0, __float_as_int(x), 0xB1, 0xF, 0xF, true)); }
; #define RG ((bfraw*)(kargs()->ws + O_RG))
; DEVFI void store_nat_m(bfraw* base, long ld, f32x4 (&a)[8], int fr) {
;   const bool odd = fr & 1;
;   bfraw* p0 = base + (odd ? 15 + fr : fr);
; #pragma unroll
;   for (int j = 0; j < 4; ++j)
; #pragma unroll
;     for (int n0 = 0; n0 < 8; n0 += 2) { const float own0 = a[n0][j], own1 = a[n0 + 1][j];
;       const float recv = dpp_xor1(odd ? own0 : own1);
;       const unsigned pk = odd ? cvtpk(recv, own1) : cvtpk(own0, recv);
;       *reinterpret_cast<unsigned*>(p0 + (long)j * ld + n0 * 16) = pk; }
; }
; __global__ void __launch_bounds__(512) mega(Params p) {
;     ...
;                   } else if (c0 < 4096) {
; #pragma unroll
;                     for (int n = 0; n < 8; ++n)
; #pragma unroll
;                       for (int j = 0; j < 4; ++j) { const float x = a[n][j]; a[n][j] = x * sigmoidf_(x); }
;                     store_nat_m(RG + (long)r0 * 1024 + (c0 - 3072), 1024, a, fr);
.LBB0_2296:
	s_or_b64 exec, exec, s[2:3]
	v_mul_f32_e32 v34, 0xbfb8aa3b, v5
	v_exp_f32_e32 v34, v34
	global_store_dword v[32:33], v36, off offset:2112
	v_add_f32_e32 v34, 1.0, v34
	s_nop 0
	v_rcp_f32_e32 v40, v34
	s_nop 0
	v_fma_f32 v38, -v34, v40, 1.0
	v_fma_f32 v38, v38, v40, v40
	v_mul_f32_e32 v40, 0xbfb8aa3b, v1
	v_exp_f32_e32 v40, v40
	s_nop 0
	v_add_f32_e32 v40, 1.0, v40
	s_nop 0
	v_rcp_f32_e32 v42, v40
	s_nop 0
	v_fma_f32 v41, -v40, v42, 1.0
	v_fma_f32 v42, v41, v42, v42
	s_nop 0
	v_mov_b32_dpp v41, v39 quad_perm:[1,0,3,2] row_mask:0xf bank_mask:0xf bound_ctrl:1
	s_and_saveexec_b64 s[2:3], s[4:5]
	s_xor_b64 s[2:3], exec, s[2:3]
	s_cbranch_execz .LBB0_2298
	v_cvt_pk_bf16_f32 v36, v41, v37

; DEVFI float sigmoidf_(float x) { return 1.f / (1.f + __expf(-x)); }
; DEVFI float dpp_xor1(float x) { return __int_as_float(__builtin_amdgcn_update_dpp(0, __float_as_int(x), 0xB1, 0xF, 0xF, true)); }
; #define RG ((bfraw*)(kargs()->ws + O_RG))
; DEVFI void store_nat_m(bfraw* base, long ld, f32x4 (&a)[8], int fr) {
;   const bool odd = fr & 1;
;   bfraw* p0 = base + (odd ? 15 + fr : fr);
; #pragma unroll
;   for (int j = 0; j < 4; ++j)
; #pragma unroll
;     for (int n0 = 0; n0 < 8; n0 += 2) { const float own0 = a[n0][j], own1 = a[n0 + 1][j];
;       const float recv = dpp_xor1(odd ? own0 : own1);
;       const unsigned pk = odd ? cvtpk(recv, own1) : cvtpk(own0, recv);
;       *reinterpret_cast<unsigned*>(p0 + (long)j * ld + n0 * 16) = pk; }
; }
; __global__ void __launch_bounds__(512) mega(Params p) {
;     ...
;                   } else if (c0 < 4096) {
; #pragma unroll
;                     for (int n = 0; n < 8; ++n)
; #pragma unroll
;                       for (int j = 0; j < 4; ++j) { const float x = a[n][j]; a[n][j] = x * sigmoidf_(x); }
;                     store_nat_m(RG + (long)r0 * 1024 + (c0 - 3072), 1024, a, fr);
.LBB0_2300:
	s_or_b64 exec, exec, s[2:3]
	v_mul_f32_e32 v35, 0xbfb8aa3b, v30
	v_exp_f32_e32 v35, v35
	global_store_dword v[32:33], v36, off offset:2176
	v_add_f32_e32 v35, 1.0, v35
	s_nop 0
	v_rcp_f32_e32 v40, v35
	s_nop 0
	v_fma_f32 v38, -v35, v40, 1.0
	v_fma_f32 v38, v38, v40, v40
	v_mul_f32_e32 v40, 0xbfb8aa3b, v26
	v_exp_f32_e32 v40, v40
	s_nop 0
	v_add_f32_e32 v40, 1.0, v40
	s_nop 0
	v_rcp_f32_e32 v42, v40
	s_nop 0
	v_fma_f32 v41, -v40, v42, 1.0
	v_fma_f32 v42, v41, v42, v42
	s_nop 0
	v_mov_b32_dpp v41, v39 quad_perm:[1,0,3,2] row_mask:0xf bank_mask:0xf bound_ctrl:1
	s_and_saveexec_b64 s[2:3], s[4:5]
	s_xor_b64 s[2:3], exec, s[2:3]
	s_cbranch_execz .LBB0_2302
	v_cvt_pk_bf16_f32 v36, v41, v37

; DEVFI float sigmoidf_(float x) { return 1.f / (1.f + __expf(-x)); }
; DEVFI float dpp_xor1(float x) { return __int_as_float(__builtin_amdgcn_update_dpp(0, __float_as_int(x), 0xB1, 0xF, 0xF, true)); }
; #define RG ((bfraw*)(kargs()->ws + O_RG))
; DEVFI void store_nat_m(bfraw* base, long ld, f32x4 (&a)[8], int fr) {
;   const bool odd = fr & 1;
;   bfraw* p0 = base + (odd ? 15 + fr : fr);
; #pragma unroll
;   for (int j = 0; j < 4; ++j)
; #pragma unroll
;     for (int n0 = 0; n0 < 8; n0 += 2) { const float own0 = a[n0][j], own1 = a[n0 + 1][j];
;       const float recv = dpp_xor1(odd ? own0 : own1);
;       const unsigned pk = odd ? cvtpk(recv, own1) : cvtpk(own0, recv);
;       *reinterpret_cast<unsigned*>(p0 + (long)j * ld + n0 * 16) = pk; }
; }
; __global__ void __launch_bounds__(512) mega(Params p) {
;     ...
;                   } else if (c0 < 4096) {
; #pragma unroll
;                     for (int n = 0; n < 8; ++n)
; #pragma unroll
;                       for (int j = 0; j < 4; ++j) { const float x = a[n][j]; a[n][j] = x * sigmoidf_(x); }
;                     store_nat_m(RG + (long)r0 * 1024 + (c0 - 3072), 1024, a, fr);
.LBB0_2304:
	s_or_b64 exec, exec, s[2:3]
	v_mul_f32_e32 v34, 0xbfb8aa3b, v14
	v_exp_f32_e32 v34, v34
	global_store_dword v[32:33], v36, off offset:2240
	v_add_f32_e32 v34, 1.0, v34
	s_nop 0
	v_rcp_f32_e32 v40, v34
	s_nop 0
	v_fma_f32 v38, -v34, v40, 1.0
	v_fma_f32 v38, v38, v40, v40
	v_mul_f32_e32 v40, 0xbfb8aa3b, v10
	v_exp_f32_e32 v40, v40
	s_nop 0
	v_add_f32_e32 v40, 1.0, v40
	s_nop 0
	v_rcp_f32_e32 v42, v40
	s_nop 0
	v_fma_f32 v41, -v40, v42, 1.0
	v_fma_f32 v42, v41, v42, v42
	s_nop 0
	v_mov_b32_dpp v41, v39 quad_perm:[1,0,3,2] row_mask:0xf bank_mask:0xf bound_ctrl:1
	s_and_saveexec_b64 s[2:3], s[4:5]
	s_xor_b64 s[2:3], exec, s[2:3]
	s_cbranch_execz .LBB0_2306
	v_cvt_pk_bf16_f32 v36, v41, v37

; DEVFI float sigmoidf_(float x) { return 1.f / (1.f + __expf(-x)); }
; DEVFI float dpp_xor1(float x) { return __int_as_float(__builtin_amdgcn_update_dpp(0, __float_as_int(x), 0xB1, 0xF, 0xF, true)); }
; #define RG ((bfraw*)(kargs()->ws + O_RG))
; DEVFI void store_nat_m(bfraw* base, long ld, f32x4 (&a)[8], int fr) {
;   const bool odd = fr & 1;
;   bfraw* p0 = base + (odd ? 15 + fr : fr);
; #pragma unroll
;   for (int j = 0; j < 4; ++j)
; #pragma unroll
;     for (int n0 = 0; n0 < 8; n0 += 2) { const float own0 = a[n0][j], own1 = a[n0 + 1][j];
;       const float recv = dpp_xor1(odd ? own0 : own1);
;       const unsigned pk = odd ? cvtpk(recv, own1) : cvtpk(own0, recv);
;       *reinterpret_cast<unsigned*>(p0 + (long)j * ld + n0 * 16) = pk; }
; }
; __global__ void __launch_bounds__(512) mega(Params p) {
;     ...
;                   } else if (c0 < 4096) {
; #pragma unroll
;                     for (int n = 0; n < 8; ++n)
; #pragma unroll
;                       for (int j = 0; j < 4; ++j) { const float x = a[n][j]; a[n][j] = x * sigmoidf_(x); }
;                     store_nat_m(RG + (long)r0 * 1024 + (c0 - 3072), 1024, a, fr);
.LBB0_2308:
	s_or_b64 exec, exec, s[2:3]
	v_mul_f32_e32 v35, 0xbfb8aa3b, v22
	v_exp_f32_e32 v35, v35
	s_nop 0
	v_add_f32_e32 v35, 1.0, v35
	s_nop 0
	v_rcp_f32_e32 v40, v35
	s_nop 0
	v_fma_f32 v38, -v35, v40, 1.0
	v_fma_f32 v38, v38, v40, v40
	v_mul_f32_e32 v40, 0xbfb8aa3b, v18
	v_exp_f32_e32 v40, v40
	s_nop 0
	v_add_f32_e32 v40, 1.0, v40
	s_nop 0
	v_rcp_f32_e32 v42, v40
	s_nop 0
	v_fma_f32 v41, -v40, v42, 1.0
	v_fma_f32 v41, v41, v42, v42
	v_add_co_u32_e32 v42, vcc, 0x1000, v32
	s_nop 1
	v_addc_co_u32_e32 v43, vcc, 0, v33, vcc
	global_store_dword v[42:43], v36, off
	v_mov_b32_dpp v42, v39 quad_perm:[1,0,3,2] row_mask:0xf bank_mask:0xf bound_ctrl:1
	s_and_saveexec_b64 s[2:3], s[4:5]
	s_xor_b64 s[2:3], exec, s[2:3]
	s_cbranch_execz .LBB0_2310
	v_cvt_pk_bf16_f32 v36, v42, v37

; DEVFI float sigmoidf_(float x) { return 1.f / (1.f + __expf(-x)); }
; DEVFI float dpp_xor1(float x) { return __int_as_float(__builtin_amdgcn_update_dpp(0, __float_as_int(x), 0xB1, 0xF, 0xF, true)); }
; #define RG ((bfraw*)(kargs()->ws + O_RG))
; DEVFI void store_nat_m(bfraw* base, long ld, f32x4 (&a)[8], int fr) {
;   const bool odd = fr & 1;
;   bfraw* p0 = base + (odd ? 15 + fr : fr);
; #pragma unroll
;   for (int j = 0; j < 4; ++j)
; #pragma unroll
;     for (int n0 = 0; n0 < 8; n0 += 2) { const float own0 = a[n0][j], own1 = a[n0 + 1][j];
;       const float recv = dpp_xor1(odd ? own0 : own1);
;       const unsigned pk = odd ? cvtpk(recv, own1) : cvtpk(own0, recv);
;       *reinterpret_cast<unsigned*>(p0 + (long)j * ld + n0 * 16) = pk; }
; }
; __global__ void __launch_bounds__(512) mega(Params p) {
;     ...
;                   } else if (c0 < 4096) {
; #pragma unroll
;                     for (int n = 0; n < 8; ++n)
; #pragma unroll
;                       for (int j = 0; j < 4; ++j) { const float x = a[n][j]; a[n][j] = x * sigmoidf_(x); }
;                     store_nat_m(RG + (long)r0 * 1024 + (c0 - 3072), 1024, a, fr);
.LBB0_2312:
	s_or_b64 exec, exec, s[2:3]
	v_mul_f32_e32 v34, 0xbfb8aa3b, v6
	v_exp_f32_e32 v34, v34
	s_nop 0
	v_add_f32_e32 v34, 1.0, v34
	s_nop 0
	v_rcp_f32_e32 v40, v34
	s_nop 0
	v_fma_f32 v38, -v34, v40, 1.0
	v_fma_f32 v38, v38, v40, v40
	v_mul_f32_e32 v40, 0xbfb8aa3b, v2
	v_exp_f32_e32 v40, v40
	s_nop 0
	v_add_f32_e32 v40, 1.0, v40
	s_nop 0
	v_rcp_f32_e32 v42, v40
	s_nop 0
	v_fma_f32 v41, -v40, v42, 1.0
	v_fma_f32 v41, v41, v42, v42
	v_add_co_u32_e32 v42, vcc, 0x1000, v32
	s_nop 1
	v_addc_co_u32_e32 v43, vcc, 0, v33, vcc
	global_store_dword v[42:43], v36, off offset:64
	v_mov_b32_dpp v42, v39 quad_perm:[1,0,3,2] row_mask:0xf bank_mask:0xf bound_ctrl:1
	s_and_saveexec_b64 s[2:3], s[4:5]
	s_xor_b64 s[2:3], exec, s[2:3]
	s_cbranch_execz .LBB0_2314
	v_cvt_pk_bf16_f32 v36, v42, v37

; DEVFI float sigmoidf_(float x) { return 1.f / (1.f + __expf(-x)); }
; DEVFI float dpp_xor1(float x) { return __int_as_float(__builtin_amdgcn_update_dpp(0, __float_as_int(x), 0xB1, 0xF, 0xF, true)); }
; #define RG ((bfraw*)(kargs()->ws + O_RG))
; DEVFI void store_nat_m(bfraw* base, long ld, f32x4 (&a)[8], int fr) {
;   const bool odd = fr & 1;
;   bfraw* p0 = base + (odd ? 15 + fr : fr);
; #pragma unroll
;   for (int j = 0; j < 4; ++j)
; #pragma unroll
;     for (int n0 = 0; n0 < 8; n0 += 2) { const float own0 = a[n0][j], own1 = a[n0 + 1][j];
;       const float recv = dpp_xor1(odd ? own0 : own1);
;       const unsigned pk = odd ? cvtpk(recv, own1) : cvtpk(own0, recv);
;       *reinterpret_cast<unsigned*>(p0 + (long)j * ld + n0 * 16) = pk; }
; }
; __global__ void __launch_bounds__(512) mega(Params p) {
;     ...
;                   } else if (c0 < 4096) {
; #pragma unroll
;                     for (int n = 0; n < 8; ++n)
; #pragma unroll
;                       for (int j = 0; j < 4; ++j) { const float x = a[n][j]; a[n][j] = x * sigmoidf_(x); }
;                     store_nat_m(RG + (long)r0 * 1024 + (c0 - 3072), 1024, a, fr);
.LBB0_2316:
	s_or_b64 exec, exec, s[2:3]
	v_mul_f32_e32 v35, 0xbfb8aa3b, v31
	v_exp_f32_e32 v35, v35
	s_nop 0
	v_add_f32_e32 v35, 1.0, v35
	s_nop 0
	v_rcp_f32_e32 v40, v35
	s_nop 0
	v_fma_f32 v38, -v35, v40, 1.0
	v_fma_f32 v38, v38, v40, v40
	v_mul_f32_e32 v40, 0xbfb8aa3b, v27
	v_exp_f32_e32 v40, v40
	s_nop 0
	v_add_f32_e32 v40, 1.0, v40
	s_nop 0
	v_rcp_f32_e32 v42, v40
	s_nop 0
	v_fma_f32 v41, -v40, v42, 1.0
	v_fma_f32 v41, v41, v42, v42
	v_add_co_u32_e32 v42, vcc, 0x1000, v32
	s_nop 1
	v_addc_co_u32_e32 v43, vcc, 0, v33, vcc
	global_store_dword v[42:43], v36, off offset:128
	v_mov_b32_dpp v42, v39 quad_perm:[1,0,3,2] row_mask:0xf bank_mask:0xf bound_ctrl:1
	s_and_saveexec_b64 s[2:3], s[4:5]
	s_xor_b64 s[2:3], exec, s[2:3]
	s_cbranch_execz .LBB0_2318
	v_cvt_pk_bf16_f32 v36, v42, v37

; DEVFI float sigmoidf_(float x) { return 1.f / (1.f + __expf(-x)); }
; DEVFI float dpp_xor1(float x) { return __int_as_float(__builtin_amdgcn_update_dpp(0, __float_as_int(x), 0xB1, 0xF, 0xF, true)); }
; #define RG ((bfraw*)(kargs()->ws + O_RG))
; DEVFI void store_nat_m(bfraw* base, long ld, f32x4 (&a)[8], int fr) {
;   const bool odd = fr & 1;
;   bfraw* p0 = base + (odd ? 15 + fr : fr);
; #pragma unroll
;   for (int j = 0; j < 4; ++j)
; #pragma unroll
;     for (int n0 = 0; n0 < 8; n0 += 2) { const float own0 = a[n0][j], own1 = a[n0 + 1][j];
;       const float recv = dpp_xor1(odd ? own0 : own1);
;       const unsigned pk = odd ? cvtpk(recv, own1) : cvtpk(own0, recv);
;       *reinterpret_cast<unsigned*>(p0 + (long)j * ld + n0 * 16) = pk; }
; }
; __global__ void __launch_bounds__(512) mega(Params p) {
;     ...
;                   } else if (c0 < 4096) {
; #pragma unroll
;                     for (int n = 0; n < 8; ++n)
; #pragma unroll
;                       for (int j = 0; j < 4; ++j) { const float x = a[n][j]; a[n][j] = x * sigmoidf_(x); }
;                     store_nat_m(RG + (long)r0 * 1024 + (c0 - 3072), 1024, a, fr);
.LBB0_2320:
	s_or_b64 exec, exec, s[2:3]
	v_mul_f32_e32 v34, 0xbfb8aa3b, v15
	v_exp_f32_e32 v34, v34
	s_nop 0
	v_add_f32_e32 v34, 1.0, v34
	s_nop 0
	v_rcp_f32_e32 v40, v34
	s_nop 0
	v_fma_f32 v38, -v34, v40, 1.0
	v_fma_f32 v38, v38, v40, v40
	v_mul_f32_e32 v40, 0xbfb8aa3b, v11
	v_exp_f32_e32 v40, v40
	s_nop 0
	v_add_f32_e32 v40, 1.0, v40
	s_nop 0
	v_rcp_f32_e32 v42, v40
	s_nop 0
	v_fma_f32 v41, -v40, v42, 1.0
	v_fma_f32 v41, v41, v42, v42
	v_add_co_u32_e32 v42, vcc, 0x1000, v32
	s_nop 1
	v_addc_co_u32_e32 v43, vcc, 0, v33, vcc
	global_store_dword v[42:43], v36, off offset:192
	v_mov_b32_dpp v42, v39 quad_perm:[1,0,3,2] row_mask:0xf bank_mask:0xf bound_ctrl:1
	s_and_saveexec_b64 s[2:3], s[4:5]
	s_xor_b64 s[2:3], exec, s[2:3]
	s_cbranch_execz .LBB0_2322
	v_cvt_pk_bf16_f32 v36, v42, v37

; DEVFI float sigmoidf_(float x) { return 1.f / (1.f + __expf(-x)); }
; DEVFI float dpp_xor1(float x) { return __int_as_float(__builtin_amdgcn_update_dpp(0, __float_as_int(x), 0xB1, 0xF, 0xF, true)); }
; #define RG ((bfraw*)(kargs()->ws + O_RG))
; DEVFI void store_nat_m(bfraw* base, long ld, f32x4 (&a)[8], int fr) {
;   const bool odd = fr & 1;
;   bfraw* p0 = base + (odd ? 15 + fr : fr);
; #pragma unroll
;   for (int j = 0; j < 4; ++j)
; #pragma unroll
;     for (int n0 = 0; n0 < 8; n0 += 2) { const float own0 = a[n0][j], own1 = a[n0 + 1][j];
;       const float recv = dpp_xor1(odd ? own0 : own1);
;       const unsigned pk = odd ? cvtpk(recv, own1) : cvtpk(own0, recv);
;       *reinterpret_cast<unsigned*>(p0 + (long)j * ld + n0 * 16) = pk; }
; }
; __global__ void __launch_bounds__(512) mega(Params p) {
;     ...
;                   } else if (c0 < 4096) {
; #pragma unroll
;                     for (int n = 0; n < 8; ++n)
; #pragma unroll
;                       for (int j = 0; j < 4; ++j) { const float x = a[n][j]; a[n][j] = x * sigmoidf_(x); }
;                     store_nat_m(RG + (long)r0 * 1024 + (c0 - 3072), 1024, a, fr);
.LBB0_2324:
	s_or_b64 exec, exec, s[2:3]
	v_mul_f32_e32 v35, 0xbfb8aa3b, v23
	v_exp_f32_e32 v35, v35
	s_nop 0
	v_add_f32_e32 v35, 1.0, v35
	s_nop 0
	v_rcp_f32_e32 v40, v35
	s_nop 0
	v_fma_f32 v38, -v35, v40, 1.0
	v_fma_f32 v38, v38, v40, v40
	v_mul_f32_e32 v40, 0xbfb8aa3b, v19
	v_exp_f32_e32 v40, v40
	s_nop 0
	v_add_f32_e32 v40, 1.0, v40
	s_nop 0
	v_rcp_f32_e32 v42, v40
	s_nop 0
	v_fma_f32 v41, -v40, v42, 1.0
	v_fma_f32 v41, v41, v42, v42
	v_add_co_u32_e32 v42, vcc, 0x1000, v32
	s_nop 1
	v_addc_co_u32_e32 v43, vcc, 0, v33, vcc
	global_store_dword v[42:43], v36, off offset:2048
	v_mov_b32_dpp v42, v39 quad_perm:[1,0,3,2] row_mask:0xf bank_mask:0xf bound_ctrl:1
	s_and_saveexec_b64 s[2:3], s[4:5]
	s_xor_b64 s[2:3], exec, s[2:3]
	s_cbranch_execz .LBB0_2326
	v_cvt_pk_bf16_f32 v36, v42, v37

; DEVFI float sigmoidf_(float x) { return 1.f / (1.f + __expf(-x)); }
; DEVFI float dpp_xor1(float x) { return __int_as_float(__builtin_amdgcn_update_dpp(0, __float_as_int(x), 0xB1, 0xF, 0xF, true)); }
; #define RG ((bfraw*)(kargs()->ws + O_RG))
; DEVFI void store_nat_m(bfraw* base, long ld, f32x4 (&a)[8], int fr) {
;   const bool odd = fr & 1;
;   bfraw* p0 = base + (odd ? 15 + fr : fr);
; #pragma unroll
;   for (int j = 0; j < 4; ++j)
; #pragma unroll
;     for (int n0 = 0; n0 < 8; n0 += 2) { const float own0 = a[n0][j], own1 = a[n0 + 1][j];
;       const float recv = dpp_xor1(odd ? own0 : own1);
;       const unsigned pk = odd ? cvtpk(recv, own1) : cvtpk(own0, recv);
;       *reinterpret_cast<unsigned*>(p0 + (long)j * ld + n0 * 16) = pk; }
; }
; __global__ void __launch_bounds__(512) mega(Params p) {
;     ...
;                   } else if (c0 < 4096) {
; #pragma unroll
;                     for (int n = 0; n < 8; ++n)
; #pragma unroll
;                       for (int j = 0; j < 4; ++j) { const float x = a[n][j]; a[n][j] = x * sigmoidf_(x); }
;                     store_nat_m(RG + (long)r0 * 1024 + (c0 - 3072), 1024, a, fr);
.LBB0_2328:
	s_or_b64 exec, exec, s[2:3]
	v_mul_f32_e32 v34, 0xbfb8aa3b, v7
	v_exp_f32_e32 v34, v34
	v_mov_b32_dpp v39, v39 quad_perm:[1,0,3,2] row_mask:0xf bank_mask:0xf bound_ctrl:1
	v_add_f32_e32 v34, 1.0, v34
	s_nop 0
	v_rcp_f32_e32 v40, v34
	s_nop 0
	v_fma_f32 v38, -v34, v40, 1.0
	v_fma_f32 v38, v38, v40, v40
	v_mul_f32_e32 v40, 0xbfb8aa3b, v3
	v_exp_f32_e32 v40, v40
	s_nop 0
	v_add_f32_e32 v40, 1.0, v40
	s_nop 0
	v_rcp_f32_e32 v42, v40
	s_nop 0
	v_fma_f32 v41, -v40, v42, 1.0
	v_fma_f32 v41, v41, v42, v42
	v_add_co_u32_e32 v42, vcc, 0x1000, v32
	s_nop 1
	v_addc_co_u32_e32 v43, vcc, 0, v33, vcc
	global_store_dword v[42:43], v36, off offset:2112
	s_and_saveexec_b64 s[2:3], s[4:5]
	s_xor_b64 s[2:3], exec, s[2:3]
	s_cbranch_execz .LBB0_2330
	v_cvt_pk_bf16_f32 v36, v39, v37

; __global__ void __launch_bounds__(512) mega(Params p) {
;     ...
;           if (tid < 128) { const float4* sp = (const float4*)(svstat_ + (long)(chunk * 128 + tid) * 16);
;             const float4 a = sp[0], b = sp[1], c = sp[2], d = sp[3];
;             const float s1 = a.x + a.z + b.x + b.z + c.x + c.z + d.x + d.z, s2 = a.y + a.w + b.y + b.w + c.y + c.w + d.y + d.w;
;             const float mean = s1 * (1.f / 1024.f); const float var = fmaxf(s2 * (1.f / 1024.f) - mean * mean, 0.f);
;             st_mu[tid] = mean; st_rs[tid] = 1.f / sqrtf(var + LN_EPS); }
.LBB0_2427:
	s_and_b32 s24, s14, 0xffffff80
	s_barrier
	s_and_saveexec_b64 s[2:3], s[6:7]
	s_cbranch_execz .LBB0_2426
	v_add_u32_e32 v0, s24, v96
	v_ashrrev_i32_e32 v1, 31, v0
	v_lshlrev_b64 v[0:1], 6, v[0:1]
	v_lshl_add_u64 v[12:13], s[16:17], 0, v[0:1]
	global_load_dwordx4 v[0:3], v[12:13], off
	global_load_dwordx4 v[4:7], v[12:13], off offset:16
	global_load_dwordx4 v[8:11], v[12:13], off offset:32
	s_nop 0
	global_load_dwordx4 v[12:15], v[12:13], off offset:48
	s_mov_b32 s8, 0x3a800000
	s_waitcnt vmcnt(3)
	v_add_f32_e32 v0, v0, v2
	s_waitcnt vmcnt(2)
	v_add_f32_e32 v0, v0, v4
	v_add_f32_e32 v1, v1, v3
	v_add_f32_e32 v0, v0, v6
	v_add_f32_e32 v1, v1, v5
	s_waitcnt vmcnt(1)
	v_add_f32_e32 v0, v0, v8
	v_add_f32_e32 v1, v1, v7
	v_add_f32_e32 v0, v0, v10
	v_add_f32_e32 v1, v1, v9
	s_waitcnt vmcnt(0)
	v_add_f32_e32 v0, v0, v12
	v_add_f32_e32 v1, v1, v11
	v_add_f32_e32 v0, v0, v14
	v_add_f32_e32 v1, v1, v13
	v_mul_f32_e32 v0, 0x3a800000, v0
	v_add_f32_e32 v1, v1, v15
	v_mul_f32_e32 v2, v0, v0
	v_fma_f32 v1, v1, s8, -v2
	v_max_f32_e32 v1, 0, v1
	v_add_f32_e32 v1, 0x3727c5ac, v1
	v_mul_f32_e32 v2, 0x4f800000, v1
	v_cmp_gt_f32_e32 vcc, s30, v1
	s_nop 1
	v_cndmask_b32_e32 v1, v1, v2, vcc
	v_sqrt_f32_e32 v2, v1
	s_nop 0
	v_add_u32_e32 v3, -1, v2
	v_add_u32_e32 v4, 1, v2
	v_fma_f32 v5, -v3, v2, v1
	v_fma_f32 v6, -v4, v2, v1
	v_cmp_ge_f32_e64 s[8:9], 0, v5
	s_nop 1
	v_cndmask_b32_e64 v2, v2, v3, s[8:9]
	v_cmp_lt_f32_e64 s[8:9], 0, v6
	s_nop 1
	v_cndmask_b32_e64 v2, v2, v4, s[8:9]
	v_mul_f32_e32 v3, 0x37800000, v2
	v_cndmask_b32_e32 v2, v2, v3, vcc
	v_cmp_class_f32_e32 vcc, v1, v222
	s_nop 1
	v_cndmask_b32_e32 v1, v2, v1, vcc
	v_rcp_f32_e32 v3, v1
	s_nop 0
	v_fma_f32 v2, -v1, v3, 1.0
	v_fma_f32 v2, v2, v3, v3
	v_div_fixup_f32 v1, v2, v1, 1.0
	ds_write2st64_b32 v98, v0, v1 offset1:2
	s_branch .LBB0_2426

; #define WAIT_V0() asm volatile("s_waitcnt vmcnt(0)" ::: "memory")
; #define RQ ((bfraw*)(kargs()->ws + O_RQ))
; #define RK ((bfraw*)(kargs()->ws + O_RK))
; #define RVT ((bfraw*)(kargs()->ws + O_RVT))
; #define ST ((bfraw*)(kargs()->ws + O_ST))
; #define LGT ((float*)(kargs()->ws + O_LGT))
; __global__ void __launch_bounds__(512) mega(Params p) {
;     ...
;         for (int bi = bid; bi < 128 * 8; bi += nb) {
;           int tz = tid; asm volatile("" : "+v"(tz));
;           const int w = __builtin_amdgcn_readfirstlane(tz >> 6), lz = tz & 63, fr = tz & 15, fq = (tz >> 4) & 3;
;           const int head = bi & 7, chunk = bi >> 3;
;           const float lgf = LGT[l * 16 + head], lgb = LGT[l * 16 + 8 + head];
;           const long tok0 = (long)chunk * 128;
;           __syncthreads();
;           { const bfraw* kb = RK + tok0 * 1024 + head * 128; const bfraw* vb = RVT + ((long)(chunk * 8 + head) * 128) * 128;
;             const bfraw* sfb = ST + ((long)((chunk * 8 + head) * 2)) * 16384;
;             const int wz = w;
; #pragma unroll
;             for (int g = 0; g < 16; ++g) { const int blk = g * 8 + wz, row = (blk & 31) * 4 + (lz >> 4), c = (lz ^ row) & 15;
;               const bfraw* sp = (g < 4) ? kb + (long)row * 1024 + c * 8 : (g < 8) ? vb + row * 128 + c * 8 : sfb + (g < 12 ? 0 : 16384) + row * 128 + c * 8;
;               __builtin_amdgcn_global_load_lds((const unsigned*)sp, (unsigned*)(shm + blk * 1024), 16, 0, 0); } }
;           bf16x8 qf[4];
;           { const bfraw* qp = RQ + (tok0 + w * 16 + fr) * 1024 + head * 128 + fq * 8;
; #pragma unroll
;             for (int sx = 0; sx < 4; ++sx) qf[sx] = *(const bf16x8*)(qp + sx * 32); }
;           WAIT_V0(); __syncthreads();
.LBB0_2481:
	v_mov_b32_e32 v116, v114
	s_and_b32 s17, s16, 7
	v_readfirstlane_b32 s2, v116
	s_ashr_i32 s18, s2, 6
	s_mov_b64 s[2:3], s[0:1]
	s_load_dwordx2 s[4:5], s[2:3], 0xe8
	s_or_b32 s12, s17, s10
	s_ashr_i32 s2, s16, 3
	s_lshl_b64 s[14:15], s[12:13], 2
	v_bfe_u32 v68, v116, 4, 2
	s_waitcnt lgkmcnt(0)
	s_add_u32 s4, s4, s14
	s_addc_u32 s5, s5, s15
	global_load_dword v117, v252, s[4:5]
	s_mov_b64 s[4:5], s[0:1]
	s_load_dwordx2 s[4:5], s[4:5], 0xe8
	v_and_b32_e32 v115, 15, v116
	v_lshrrev_b32_e32 v119, 4, v116
	v_lshlrev_b32_e32 v120, 8, v115
	v_bitop3_b32 v8, v68, v115, 4 bitop3:0x36
	s_waitcnt lgkmcnt(0)
	s_add_u32 s4, s4, s14
	s_addc_u32 s5, s5, s15
	global_load_dword v118, v252, s[4:5] offset:32
	s_mov_b64 s[4:5], s[0:1]
	s_waitcnt vmcnt(63) expcnt(7) lgkmcnt(15)
	s_barrier
	s_load_dwordx2 s[4:5], s[4:5], 0xe8
	s_ashr_i32 s3, s2, 31
	s_lshl_b64 s[14:15], s[2:3], 18
	v_bitop3_b32 v16, v68, v115, 8 bitop3:0x36
	v_bitop3_b32 v26, v68, v115, 12 bitop3:0x36
	s_waitcnt lgkmcnt(0)
	s_add_u32 s4, s4, s14
	s_addc_u32 s5, s5, s15
	s_lshl_b32 s12, s17, 8
	s_add_u32 s7, s4, s12
	s_addc_u32 s19, s5, 0
	s_mov_b64 s[4:5], s[0:1]
	s_load_dwordx2 s[14:15], s[4:5], 0xe8
	s_mov_b64 s[4:5], s[0:1]
	s_load_dwordx2 s[4:5], s[4:5], 0xe8
	s_add_u32 s20, s7, 0x13720000
	s_addc_u32 s21, s19, 0
	s_ashr_i32 s7, s6, 31
	s_lshl_b64 s[22:23], s[6:7], 15
	s_waitcnt lgkmcnt(0)
	s_add_u32 s7, s4, s22
	s_addc_u32 s19, s5, s23
	s_add_u32 s4, s7, 0x30720000
	s_addc_u32 s5, s19, 0
	s_lshl_b32 s22, s18, 2
	s_and_b32 s22, s22, 0x7c
	v_or_b32_e32 v0, s22, v68
	v_bitop3_b32 v2, s22, v116, v68 bitop3:0x36
	v_lshlrev_b32_e32 v176, 11, v0
	v_lshlrev_b32_e32 v2, 4, v2
	s_add_i32 s22, s18, 8
	v_lshl_add_u64 v[0:1], s[20:21], 0, v[176:177]
	v_and_b32_e32 v176, 0xf0, v2
	s_lshl_b32 s23, s22, 2
	v_lshl_add_u64 v[0:1], v[0:1], 0, v[176:177]
	s_lshl_b32 m0, s18, 10
	s_and_b32 s23, s23, 0x7c
	global_load_lds_dwordx4 v[0:1], off
	v_or_b32_e32 v0, s23, v68
	v_bitop3_b32 v2, s23, v116, v68 bitop3:0x36
	v_lshlrev_b32_e32 v176, 11, v0
	v_lshlrev_b32_e32 v2, 4, v2
	s_lshl_b32 m0, s22, 10
	s_add_i32 s22, s18, 16
	v_lshl_add_u64 v[0:1], s[20:21], 0, v[176:177]
	v_and_b32_e32 v176, 0xf0, v2
	s_lshl_b32 s23, s22, 2
	v_lshl_add_u64 v[0:1], v[0:1], 0, v[176:177]
	s_and_b32 s23, s23, 0x7c
	global_load_lds_dwordx4 v[0:1], off
	v_or_b32_e32 v0, s23, v68
	v_bitop3_b32 v2, s23, v116, v68 bitop3:0x36
	v_lshlrev_b32_e32 v176, 11, v0
	v_lshlrev_b32_e32 v2, 4, v2
	s_lshl_b32 m0, s22, 10
	s_add_i32 s22, s18, 24
	v_lshl_add_u64 v[0:1], s[20:21], 0, v[176:177]
	v_and_b32_e32 v176, 0xf0, v2
	s_lshl_b32 s23, s22, 2
	v_lshl_add_u64 v[0:1], v[0:1], 0, v[176:177]
	s_and_b32 s23, s23, 0x7c
	global_load_lds_dwordx4 v[0:1], off
	v_or_b32_e32 v0, s23, v68
	v_bitop3_b32 v2, s23, v116, v68 bitop3:0x36
	v_lshlrev_b32_e32 v176, 11, v0
	v_lshlrev_b32_e32 v2, 4, v2
	v_lshl_add_u64 v[0:1], s[20:21], 0, v[176:177]
	v_and_b32_e32 v176, 0xf0, v2
	v_lshl_add_u64 v[0:1], v[0:1], 0, v[176:177]
	s_lshl_b32 m0, s22, 10
	s_add_i32 s20, s18, 32
	global_load_lds_dwordx4 v[0:1], off
	v_lshl_or_b32 v0, s20, 2, v68
	s_and_b32 s21, s20, 31
	v_lshlrev_b32_e32 v2, 8, v68
	v_bitop3_b32 v0, v0, 15, v116 bitop3:0x48
	v_lshl_or_b32 v1, s21, 10, v2
	v_lshl_or_b32 v176, v0, 4, v1
	v_lshl_add_u64 v[0:1], s[14:15], 0, v[176:177]
	v_lshl_add_u64 v[0:1], v[0:1], 0, s[8:9]
	s_lshl_b32 m0, s20, 10
	s_add_i32 s20, s18, 40
	global_load_lds_dwordx4 v[0:1], off
	v_lshl_or_b32 v0, s20, 2, v68
	s_and_b32 s21, s20, 31
	v_bitop3_b32 v0, v0, 15, v116 bitop3:0x48
	v_lshl_or_b32 v1, s21, 10, v2
	v_lshl_or_b32 v176, v0, 4, v1
	v_lshl_add_u64 v[0:1], s[14:15], 0, v[176:177]
	v_lshl_add_u64 v[0:1], v[0:1], 0, s[8:9]
	s_lshl_b32 m0, s20, 10
	s_add_i32 s20, s18, 48
	global_load_lds_dwordx4 v[0:1], off
	v_lshl_or_b32 v0, s20, 2, v68
	s_and_b32 s21, s20, 31
	v_bitop3_b32 v0, v0, 15, v116 bitop3:0x48
	v_lshl_or_b32 v1, s21, 10, v2
	v_lshl_or_b32 v176, v0, 4, v1
	v_lshl_add_u64 v[0:1], s[14:15], 0, v[176:177]
	v_lshl_add_u64 v[0:1], v[0:1], 0, s[8:9]
	s_lshl_b32 m0, s20, 10
	s_add_i32 s20, s18, 56
	global_load_lds_dwordx4 v[0:1], off
	v_lshl_or_b32 v0, s20, 2, v68
	s_and_b32 s21, s20, 31
	v_bitop3_b32 v0, v0, 15, v116 bitop3:0x48
	v_lshl_or_b32 v1, s21, 10, v2
	v_lshl_or_b32 v176, v0, 4, v1
	v_lshl_add_u64 v[0:1], s[14:15], 0, v[176:177]
	s_add_i32 s14, s18, 64
	s_lshl_b32 s15, s14, 2
	v_lshl_add_u64 v[0:1], v[0:1], 0, s[8:9]
	s_lshl_b32 m0, s20, 10
	s_and_b32 s15, s15, 0x7c
	global_load_lds_dwordx4 v[0:1], off
	v_or_b32_e32 v0, s15, v68
	v_bitop3_b32 v2, s15, v116, v68 bitop3:0x36
	v_lshlrev_b32_e32 v176, 8, v0
	v_lshlrev_b32_e32 v2, 4, v2
	s_lshl_b32 m0, s14, 10
	s_add_i32 s14, s18, 0x48
	v_lshl_add_u64 v[0:1], s[4:5], 0, v[176:177]
	v_and_b32_e32 v176, 0xf0, v2
	s_lshl_b32 s15, s14, 2
	v_lshl_add_u64 v[0:1], v[0:1], 0, v[176:177]
	s_and_b32 s15, s15, 0x7c
	global_load_lds_dwordx4 v[0:1], off
	v_or_b32_e32 v0, s15, v68
	v_bitop3_b32 v2, s15, v116, v68 bitop3:0x36
	v_lshlrev_b32_e32 v176, 8, v0
	v_lshlrev_b32_e32 v2, 4, v2
	s_lshl_b32 m0, s14, 10
	s_add_i32 s14, s18, 0x50
	v_lshl_add_u64 v[0:1], s[4:5], 0, v[176:177]
	v_and_b32_e32 v176, 0xf0, v2
	s_lshl_b32 s15, s14, 2
	v_lshl_add_u64 v[0:1], v[0:1], 0, v[176:177]
	s_and_b32 s15, s15, 0x7c
	global_load_lds_dwordx4 v[0:1], off
	v_or_b32_e32 v0, s15, v68
	v_bitop3_b32 v2, s15, v116, v68 bitop3:0x36
	v_lshlrev_b32_e32 v176, 8, v0
	v_lshlrev_b32_e32 v2, 4, v2
	s_lshl_b32 m0, s14, 10
	s_add_i32 s14, s18, 0x58
	v_lshl_add_u64 v[0:1], s[4:5], 0, v[176:177]
	v_and_b32_e32 v176, 0xf0, v2
	s_lshl_b32 s15, s14, 2
	v_lshl_add_u64 v[0:1], v[0:1], 0, v[176:177]
	s_and_b32 s15, s15, 0x7c
	global_load_lds_dwordx4 v[0:1], off
; #define SBAR() __builtin_amdgcn_sched_barrier(0)
; #define WAIT_V0() asm volatile("s_waitcnt vmcnt(0)" ::: "memory")
; #define RQ ((bfraw*)(kargs()->ws + O_RQ))
; #define RK ((bfraw*)(kargs()->ws + O_RK))
; #define RVT ((bfraw*)(kargs()->ws + O_RVT))
; #define ST ((bfraw*)(kargs()->ws + O_ST))
; __global__ void __launch_bounds__(512) mega(Params p) {
;     ...
;           { const bfraw* kb = RK + tok0 * 1024 + head * 128; const bfraw* vb = RVT + ((long)(chunk * 8 + head) * 128) * 128;
;             const bfraw* sfb = ST + ((long)((chunk * 8 + head) * 2)) * 16384;
;             const int wz = w;
; #pragma unroll
;             for (int g = 0; g < 16; ++g) { const int blk = g * 8 + wz, row = (blk & 31) * 4 + (lz >> 4), c = (lz ^ row) & 15;
;               const bfraw* sp = (g < 4) ? kb + (long)row * 1024 + c * 8 : (g < 8) ? vb + row * 128 + c * 8 : sfb + (g < 12 ? 0 : 16384) + row * 128 + c * 8;
;               __builtin_amdgcn_global_load_lds((const unsigned*)sp, (unsigned*)(shm + blk * 1024), 16, 0, 0); } }
;           bf16x8 qf[4];
;           { const bfraw* qp = RQ + (tok0 + w * 16 + fr) * 1024 + head * 128 + fq * 8;
; #pragma unroll
;             for (int sx = 0; sx < 4; ++sx) qf[sx] = *(const bf16x8*)(qp + sx * 32); }
;           WAIT_V0(); __syncthreads();
;           f32x4 o[8];
;           { f32x4 af[8] = {}, ab[8] = {};
; #pragma unroll
;             for (int ne = 0; ne < 8; ++ne) { bf16x8 Bf[4], Bb[4];
; #pragma unroll
;               for (int sx = 0; sx < 4; ++sx) { Bf[sx] = RLD16(2, ne * 16 + fr, sx * 4 + fq); Bb[sx] = RLD16(3, ne * 16 + fr, sx * 4 + fq); }
;               SBAR();
; #pragma unroll
;               for (int sx = 0; sx < 4; ++sx) { af[ne] = __builtin_amdgcn_mfma_f32_16x16x32_bf16(qf[sx], Bf[sx], af[ne], 0, 0, 0);
;                 ab[ne] = __builtin_amdgcn_mfma_f32_16x16x32_bf16(qf[sx], Bb[sx], ab[ne], 0, 0, 0); }
;               SBAR(); }
	v_or_b32_e32 v0, s15, v68
	v_bitop3_b32 v2, s15, v116, v68 bitop3:0x36
	v_lshlrev_b32_e32 v176, 8, v0
	v_lshlrev_b32_e32 v2, 4, v2
	s_lshl_b32 m0, s14, 10
	s_add_i32 s14, s18, 0x60
	v_lshl_add_u64 v[0:1], s[4:5], 0, v[176:177]
	v_and_b32_e32 v176, 0xf0, v2
	s_lshl_b32 s4, s14, 2
	v_lshl_add_u64 v[0:1], v[0:1], 0, v[176:177]
	s_and_b32 s4, s4, 0x7c
	global_load_lds_dwordx4 v[0:1], off
	v_or_b32_e32 v0, s4, v68
	v_bitop3_b32 v2, s4, v116, v68 bitop3:0x36
	s_add_u32 s4, s7, 0x30728000
	s_addc_u32 s5, s19, 0
	v_lshlrev_b32_e32 v176, 8, v0
	v_lshlrev_b32_e32 v2, 4, v2
	s_add_i32 s7, s18, 0x68
	v_lshl_add_u64 v[0:1], s[4:5], 0, v[176:177]
	v_and_b32_e32 v176, 0xf0, v2
	s_lshl_b32 m0, s14, 10
	s_lshl_b32 s14, s7, 2
	v_lshl_add_u64 v[0:1], v[0:1], 0, v[176:177]
	s_and_b32 s14, s14, 0x7c
	global_load_lds_dwordx4 v[0:1], off
	v_or_b32_e32 v0, s14, v68
	v_bitop3_b32 v2, s14, v116, v68 bitop3:0x36
	v_lshlrev_b32_e32 v176, 8, v0
	v_lshlrev_b32_e32 v2, 4, v2
	s_lshl_b32 m0, s7, 10
	s_add_i32 s7, s18, 0x70
	v_lshl_add_u64 v[0:1], s[4:5], 0, v[176:177]
	v_and_b32_e32 v176, 0xf0, v2
	s_lshl_b32 s14, s7, 2
	v_lshl_add_u64 v[0:1], v[0:1], 0, v[176:177]
	s_and_b32 s14, s14, 0x7c
	global_load_lds_dwordx4 v[0:1], off
	v_or_b32_e32 v0, s14, v68
	v_bitop3_b32 v2, s14, v116, v68 bitop3:0x36
	v_lshlrev_b32_e32 v176, 8, v0
	v_lshlrev_b32_e32 v2, 4, v2
	s_lshl_b32 m0, s7, 10
	s_add_i32 s7, s18, 0x78
	v_lshl_add_u64 v[0:1], s[4:5], 0, v[176:177]
	v_and_b32_e32 v176, 0xf0, v2
	s_lshl_b32 s14, s7, 2
	v_lshl_add_u64 v[0:1], v[0:1], 0, v[176:177]
	s_and_b32 s14, s14, 0x7c
	global_load_lds_dwordx4 v[0:1], off
	v_or_b32_e32 v0, s14, v68
	v_bitop3_b32 v2, s14, v116, v68 bitop3:0x36
	v_lshlrev_b32_e32 v176, 8, v0
	v_lshlrev_b32_e32 v2, 4, v2
	v_lshl_add_u64 v[0:1], s[4:5], 0, v[176:177]
	v_and_b32_e32 v176, 0xf0, v2
	v_lshl_add_u64 v[0:1], v[0:1], 0, v[176:177]
	s_lshl_b32 m0, s7, 10
	s_lshl_b64 s[4:5], s[2:3], 7
	s_mov_b64 s[2:3], s[0:1]
	global_load_lds_dwordx4 v[0:1], off
	s_load_dwordx2 s[14:15], s[2:3], 0xe8
	s_lshl_b32 s2, s18, 4
	s_ashr_i32 s3, s2, 31
	s_add_u32 s7, s4, s2
	s_addc_u32 s3, s5, s3
	v_or_b32_e32 v104, s7, v115
	v_mov_b32_e32 v105, s3
	v_lshlrev_b64 v[0:1], 11, v[104:105]
	s_waitcnt lgkmcnt(0)
	v_lshl_add_u64 v[0:1], s[14:15], 0, v[0:1]
	v_lshl_add_u64 v[0:1], v[0:1], 0, s[12:13]
	v_lshlrev_b32_e32 v176, 4, v68
	v_lshl_add_u64 v[0:1], v[0:1], 0, v[176:177]
	v_lshl_add_u64 v[2:3], v[0:1], 0, s[24:25]
	v_add_co_u32_e32 v0, vcc, s84, v0
	v_or_b32_e32 v24, 0x10000, v120
	s_nop 0
	v_addc_co_u32_e32 v1, vcc, 0, v1, vcc
	global_load_dwordx4 v[64:67], v[2:3], off offset:64
	global_load_dwordx4 v[84:87], v[2:3], off offset:128
	global_load_dwordx4 v[92:95], v[0:1], off
	global_load_dwordx4 v[88:91], v[2:3], off offset:192
	v_bitop3_b32 v0, v119, v115, 3 bitop3:0x6c
	v_or_b32_e32 v25, 0x18000, v120
	v_lshlrev_b32_e32 v69, 4, v0
	v_lshlrev_b32_e32 v82, 4, v8
	v_lshlrev_b32_e32 v83, 4, v16
	v_lshlrev_b32_e32 v121, 4, v26
	v_or_b32_e32 v0, v24, v69
	v_or_b32_e32 v4, v25, v69
	v_or_b32_e32 v8, v24, v82
	v_or_b32_e32 v12, v25, v82
	v_or_b32_e32 v16, v24, v83
	v_or_b32_e32 v20, v25, v83
	v_or_b32_e32 v24, v24, v121
	s_waitcnt vmcnt(0)
	s_waitcnt vmcnt(0)
	s_barrier
	ds_read_b128 v[0:3], v0
	ds_read_b128 v[4:7], v4
	ds_read_b128 v[8:11], v8
	ds_read_b128 v[12:15], v12
	ds_read_b128 v[16:19], v16
	ds_read_b128 v[20:23], v20
	v_or_b32_e32 v28, v25, v121
	ds_read_b128 v[24:27], v24
	ds_read_b128 v[32:35], v28
	s_waitcnt lgkmcnt(7)
	v_mfma_f32_16x16x32_bf16 v[0:3], v[92:95], v[0:3], 0
	s_waitcnt lgkmcnt(6)
	v_mfma_f32_16x16x32_bf16 v[4:7], v[92:95], v[4:7], 0
	s_waitcnt lgkmcnt(5)
	v_mfma_f32_16x16x32_bf16 v[0:3], v[64:67], v[8:11], v[0:3]
	s_waitcnt lgkmcnt(4)
	v_mfma_f32_16x16x32_bf16 v[4:7], v[64:67], v[12:15], v[4:7]
	s_waitcnt lgkmcnt(3)
	v_mfma_f32_16x16x32_bf16 v[0:3], v[84:87], v[16:19], v[0:3]
	s_waitcnt lgkmcnt(2)
	v_mfma_f32_16x16x32_bf16 v[4:7], v[84:87], v[20:23], v[4:7]
	s_waitcnt lgkmcnt(1)
	v_mfma_f32_16x16x32_bf16 v[28:31], v[88:91], v[24:27], v[0:3]
	s_waitcnt lgkmcnt(0)
	v_mfma_f32_16x16x32_bf16 v[60:63], v[88:91], v[32:35], v[4:7]
	v_or_b32_e32 v24, 0x1000, v120
	v_or_b32_e32 v100, 0x10000, v69
	v_or_b32_e32 v101, 0x18000, v69
	v_or_b32_e32 v102, 0x10000, v82
	v_or_b32_e32 v103, 0x18000, v82
	v_or_b32_e32 v104, 0x10000, v83
	v_or_b32_e32 v106, 0x18000, v83
	v_or_b32_e32 v107, 0x10000, v121
	v_or_b32_e32 v108, 0x18000, v121
	v_or_b32_e32 v0, v100, v24
	v_or_b32_e32 v4, v101, v24
	v_or_b32_e32 v8, v102, v24
	v_or_b32_e32 v12, v103, v24
	v_or_b32_e32 v16, v104, v24
	v_or_b32_e32 v20, v106, v24
	v_or_b32_e32 v25, v107, v24
	v_or_b32_e32 v32, v108, v24
	ds_read_b128 v[0:3], v0
	ds_read_b128 v[4:7], v4
	ds_read_b128 v[8:11], v8
	ds_read_b128 v[12:15], v12
	ds_read_b128 v[16:19], v16
	ds_read_b128 v[20:23], v20
	ds_read_b128 v[24:27], v25
	ds_read_b128 v[32:35], v32
	s_waitcnt lgkmcnt(7)
	v_mfma_f32_16x16x32_bf16 v[0:3], v[92:95], v[0:3], 0
	s_waitcnt lgkmcnt(6)
	v_mfma_f32_16x16x32_bf16 v[4:7], v[92:95], v[4:7], 0
	s_waitcnt lgkmcnt(5)
	v_mfma_f32_16x16x32_bf16 v[0:3], v[64:67], v[8:11], v[0:3]
	s_waitcnt lgkmcnt(4)
	v_mfma_f32_16x16x32_bf16 v[4:7], v[64:67], v[12:15], v[4:7]
	s_waitcnt lgkmcnt(3)
	v_mfma_f32_16x16x32_bf16 v[0:3], v[84:87], v[16:19], v[0:3]
	s_waitcnt lgkmcnt(2)
	v_mfma_f32_16x16x32_bf16 v[4:7], v[84:87], v[20:23], v[4:7]
	s_waitcnt lgkmcnt(1)
	v_mfma_f32_16x16x32_bf16 v[0:3], v[88:91], v[24:27], v[0:3]
	s_waitcnt lgkmcnt(0)
; #define SBAR() __builtin_amdgcn_sched_barrier(0)
; __global__ void __launch_bounds__(512) mega(Params p) {
;     ...
;             for (int ne = 0; ne < 8; ++ne) { bf16x8 Bf[4], Bb[4];
; #pragma unroll
;               for (int sx = 0; sx < 4; ++sx) { Bf[sx] = RLD16(2, ne * 16 + fr, sx * 4 + fq); Bb[sx] = RLD16(3, ne * 16 + fr, sx * 4 + fq); }
;               SBAR();
; #pragma unroll
;               for (int sx = 0; sx < 4; ++sx) { af[ne] = __builtin_amdgcn_mfma_f32_16x16x32_bf16(qf[sx], Bf[sx], af[ne], 0, 0, 0);
;                 ab[ne] = __builtin_amdgcn_mfma_f32_16x16x32_bf16(qf[sx], Bb[sx], ab[ne], 0, 0, 0); }
;               SBAR(); }
	v_mfma_f32_16x16x32_bf16 v[56:59], v[88:91], v[32:35], v[4:7]
	v_or_b32_e32 v32, 0x2000, v120
	s_nop 2
	v_or_b32_e32 v4, v100, v32
	v_or_b32_e32 v8, v101, v32
	v_or_b32_e32 v12, v102, v32
	v_or_b32_e32 v16, v103, v32
	v_or_b32_e32 v20, v104, v32
	v_or_b32_e32 v24, v106, v32
	v_or_b32_e32 v33, v107, v32
	v_or_b32_e32 v36, v108, v32
	ds_read_b128 v[4:7], v4
	ds_read_b128 v[8:11], v8
	ds_read_b128 v[12:15], v12
	ds_read_b128 v[16:19], v16
	ds_read_b128 v[20:23], v20
	ds_read_b128 v[24:27], v24
	ds_read_b128 v[32:35], v33
	ds_read_b128 v[36:39], v36
	s_waitcnt lgkmcnt(7)
	v_mfma_f32_16x16x32_bf16 v[4:7], v[92:95], v[4:7], 0
	s_waitcnt lgkmcnt(6)
	v_mfma_f32_16x16x32_bf16 v[8:11], v[92:95], v[8:11], 0
	s_waitcnt lgkmcnt(5)
	v_mfma_f32_16x16x32_bf16 v[4:7], v[64:67], v[12:15], v[4:7]
	s_waitcnt lgkmcnt(4)
	v_mfma_f32_16x16x32_bf16 v[8:11], v[64:67], v[16:19], v[8:11]
	s_waitcnt lgkmcnt(3)
	v_mfma_f32_16x16x32_bf16 v[4:7], v[84:87], v[20:23], v[4:7]
	s_waitcnt lgkmcnt(2)
	v_mfma_f32_16x16x32_bf16 v[8:11], v[84:87], v[24:27], v[8:11]
	s_waitcnt lgkmcnt(1)
	v_mfma_f32_16x16x32_bf16 v[4:7], v[88:91], v[32:35], v[4:7]
	s_waitcnt lgkmcnt(0)
	v_mfma_f32_16x16x32_bf16 v[52:55], v[88:91], v[36:39], v[8:11]
	v_or_b32_e32 v36, 0x3000, v120
	s_nop 2
	v_or_b32_e32 v8, v100, v36
	v_or_b32_e32 v12, v101, v36
	v_or_b32_e32 v16, v102, v36
	v_or_b32_e32 v20, v103, v36
	v_or_b32_e32 v24, v104, v36
	v_or_b32_e32 v32, v106, v36
	v_or_b32_e32 v37, v107, v36
	v_or_b32_e32 v40, v108, v36
	ds_read_b128 v[8:11], v8
	ds_read_b128 v[12:15], v12
	ds_read_b128 v[16:19], v16
	ds_read_b128 v[20:23], v20
	ds_read_b128 v[24:27], v24
	ds_read_b128 v[32:35], v32
	ds_read_b128 v[36:39], v37
	ds_read_b128 v[40:43], v40
	s_waitcnt lgkmcnt(7)
	v_mfma_f32_16x16x32_bf16 v[8:11], v[92:95], v[8:11], 0
	s_waitcnt lgkmcnt(6)
	v_mfma_f32_16x16x32_bf16 v[12:15], v[92:95], v[12:15], 0
	s_waitcnt lgkmcnt(5)
	v_mfma_f32_16x16x32_bf16 v[8:11], v[64:67], v[16:19], v[8:11]
	s_waitcnt lgkmcnt(4)
	v_mfma_f32_16x16x32_bf16 v[12:15], v[64:67], v[20:23], v[12:15]
	s_waitcnt lgkmcnt(3)
	v_mfma_f32_16x16x32_bf16 v[8:11], v[84:87], v[24:27], v[8:11]
	s_waitcnt lgkmcnt(2)
	v_mfma_f32_16x16x32_bf16 v[12:15], v[84:87], v[32:35], v[12:15]
	s_waitcnt lgkmcnt(1)
	v_mfma_f32_16x16x32_bf16 v[8:11], v[88:91], v[36:39], v[8:11]
	s_waitcnt lgkmcnt(0)
	v_mfma_f32_16x16x32_bf16 v[48:51], v[88:91], v[40:43], v[12:15]
	v_or_b32_e32 v40, 0x4000, v120
	s_nop 2
	v_or_b32_e32 v12, v100, v40
	v_or_b32_e32 v16, v101, v40
	v_or_b32_e32 v20, v102, v40
	v_or_b32_e32 v24, v103, v40
	v_or_b32_e32 v32, v104, v40
	v_or_b32_e32 v36, v106, v40
	v_or_b32_e32 v41, v107, v40
	v_or_b32_e32 v44, v108, v40
	ds_read_b128 v[12:15], v12
	ds_read_b128 v[16:19], v16
	ds_read_b128 v[20:23], v20
	ds_read_b128 v[24:27], v24
	ds_read_b128 v[32:35], v32
	ds_read_b128 v[36:39], v36
	ds_read_b128 v[40:43], v41
	ds_read_b128 v[44:47], v44
	s_waitcnt lgkmcnt(7)
	v_mfma_f32_16x16x32_bf16 v[12:15], v[92:95], v[12:15], 0
	s_waitcnt lgkmcnt(6)
	v_mfma_f32_16x16x32_bf16 v[16:19], v[92:95], v[16:19], 0
	s_waitcnt lgkmcnt(5)
	v_mfma_f32_16x16x32_bf16 v[12:15], v[64:67], v[20:23], v[12:15]
	s_waitcnt lgkmcnt(4)
	v_mfma_f32_16x16x32_bf16 v[16:19], v[64:67], v[24:27], v[16:19]
	s_waitcnt lgkmcnt(3)
	v_mfma_f32_16x16x32_bf16 v[12:15], v[84:87], v[32:35], v[12:15]
	s_waitcnt lgkmcnt(2)
	v_mfma_f32_16x16x32_bf16 v[16:19], v[84:87], v[36:39], v[16:19]
	s_waitcnt lgkmcnt(1)
	v_mfma_f32_16x16x32_bf16 v[12:15], v[88:91], v[40:43], v[12:15]
	s_waitcnt lgkmcnt(0)
	v_mfma_f32_16x16x32_bf16 v[44:47], v[88:91], v[44:47], v[16:19]
	v_or_b32_e32 v70, 0x5000, v120
	s_nop 2
	v_or_b32_e32 v16, v100, v70
	v_or_b32_e32 v20, v101, v70
	v_or_b32_e32 v24, v102, v70
	v_or_b32_e32 v32, v103, v70
	v_or_b32_e32 v36, v104, v70
	v_or_b32_e32 v40, v106, v70
	v_or_b32_e32 v71, v107, v70
	v_or_b32_e32 v74, v108, v70
	ds_read_b128 v[16:19], v16
	ds_read_b128 v[20:23], v20
	ds_read_b128 v[24:27], v24
	ds_read_b128 v[32:35], v32
	ds_read_b128 v[36:39], v36
	ds_read_b128 v[40:43], v40
	ds_read_b128 v[70:73], v71
	ds_read_b128 v[74:77], v74
	s_waitcnt lgkmcnt(7)
	v_mfma_f32_16x16x32_bf16 v[16:19], v[92:95], v[16:19], 0
	s_waitcnt lgkmcnt(6)
	v_mfma_f32_16x16x32_bf16 v[20:23], v[92:95], v[20:23], 0
	s_waitcnt lgkmcnt(5)
	v_mfma_f32_16x16x32_bf16 v[16:19], v[64:67], v[24:27], v[16:19]
	s_waitcnt lgkmcnt(4)
	v_mfma_f32_16x16x32_bf16 v[20:23], v[64:67], v[32:35], v[20:23]
	s_waitcnt lgkmcnt(3)
	v_mfma_f32_16x16x32_bf16 v[16:19], v[84:87], v[36:39], v[16:19]
	s_waitcnt lgkmcnt(2)
	v_mfma_f32_16x16x32_bf16 v[20:23], v[84:87], v[40:43], v[20:23]
	s_waitcnt lgkmcnt(1)
	v_mfma_f32_16x16x32_bf16 v[16:19], v[88:91], v[70:73], v[16:19]
	s_waitcnt lgkmcnt(0)
	v_mfma_f32_16x16x32_bf16 v[40:43], v[88:91], v[74:77], v[20:23]
	v_or_b32_e32 v78, 0x6000, v120
	s_nop 2
	v_or_b32_e32 v20, v100, v78
	v_or_b32_e32 v24, v101, v78
	v_or_b32_e32 v32, v102, v78
	v_or_b32_e32 v36, v103, v78
	v_or_b32_e32 v70, v104, v78
	v_or_b32_e32 v74, v106, v78
	v_or_b32_e32 v79, v107, v78
	v_or_b32_e32 v96, v108, v78
	ds_read_b128 v[20:23], v20
	ds_read_b128 v[24:27], v24
	ds_read_b128 v[32:35], v32
	ds_read_b128 v[36:39], v36
	ds_read_b128 v[70:73], v70
	ds_read_b128 v[74:77], v74
	ds_read_b128 v[78:81], v79
	ds_read_b128 v[96:99], v96
	s_waitcnt lgkmcnt(7)
	v_mfma_f32_16x16x32_bf16 v[20:23], v[92:95], v[20:23], 0
	s_waitcnt lgkmcnt(6)
	v_mfma_f32_16x16x32_bf16 v[24:27], v[92:95], v[24:27], 0
	s_waitcnt lgkmcnt(5)
	v_mfma_f32_16x16x32_bf16 v[20:23], v[64:67], v[32:35], v[20:23]
	s_waitcnt lgkmcnt(4)
	v_mfma_f32_16x16x32_bf16 v[24:27], v[64:67], v[36:39], v[24:27]
	s_waitcnt lgkmcnt(3)
	v_mfma_f32_16x16x32_bf16 v[20:23], v[84:87], v[70:73], v[20:23]
	s_waitcnt lgkmcnt(2)
; #define SBAR() __builtin_amdgcn_sched_barrier(0)
; __global__ void __launch_bounds__(512) mega(Params p) {
;     ...
;             for (int ne = 0; ne < 8; ++ne) { bf16x8 Bf[4], Bb[4];
; #pragma unroll
;               for (int sx = 0; sx < 4; ++sx) { Bf[sx] = RLD16(2, ne * 16 + fr, sx * 4 + fq); Bb[sx] = RLD16(3, ne * 16 + fr, sx * 4 + fq); }
;               SBAR();
; #pragma unroll
;               for (int sx = 0; sx < 4; ++sx) { af[ne] = __builtin_amdgcn_mfma_f32_16x16x32_bf16(qf[sx], Bf[sx], af[ne], 0, 0, 0);
;                 ab[ne] = __builtin_amdgcn_mfma_f32_16x16x32_bf16(qf[sx], Bb[sx], ab[ne], 0, 0, 0); }
;               SBAR(); }
; #pragma unroll
;             for (int j = 0; j < 4; ++j) { const int c = w * 16 + fq * 4 + j; const float xf = __expf(lgf * (float)(c + 1)), xb = __expf(lgb * (float)(128 - c));
; #pragma unroll
;               for (int ne = 0; ne < 8; ++ne) o[ne][j] = xf * af[ne][j] + xb * ab[ne][j]; } }
;           bf16x8 pf[4];
;           { f32x4 sc[8] = {};
; #pragma unroll
;             for (int n2 = 0; n2 < 4; ++n2) { bf16x8 A[2][4];
; #pragma unroll
;               for (int q2 = 0; q2 < 2; ++q2)
; #pragma unroll
;                 for (int sx = 0; sx < 4; ++sx) A[q2][sx] = RLD16(0, (n2 * 2 + q2) * 16 + fr, sx * 4 + fq);
;               SBAR();
; #pragma unroll
;               for (int q2 = 0; q2 < 2; ++q2)
; #pragma unroll
;                 for (int sx = 0; sx < 4; ++sx) sc[n2 * 2 + q2] = __builtin_amdgcn_mfma_f32_16x16x32_bf16(A[q2][sx], qf[sx], sc[n2 * 2 + q2], 0, 0, 0);
;               SBAR(); }
	v_mfma_f32_16x16x32_bf16 v[24:27], v[84:87], v[74:77], v[24:27]
	s_waitcnt lgkmcnt(1)
	v_mfma_f32_16x16x32_bf16 v[20:23], v[88:91], v[78:81], v[20:23]
	s_waitcnt lgkmcnt(0)
	v_mfma_f32_16x16x32_bf16 v[36:39], v[88:91], v[96:99], v[24:27]
	v_or_b32_e32 v109, 0x7000, v120
	s_nop 2
	v_or_b32_e32 v24, v100, v109
	v_or_b32_e32 v32, v101, v109
	v_or_b32_e32 v70, v102, v109
	v_or_b32_e32 v74, v103, v109
	v_or_b32_e32 v78, v104, v109
	v_or_b32_e32 v96, v106, v109
	v_or_b32_e32 v100, v107, v109
	ds_read_b128 v[24:27], v24
	ds_read_b128 v[32:35], v32
	ds_read_b128 v[70:73], v70
	ds_read_b128 v[74:77], v74
	ds_read_b128 v[78:81], v78
	ds_read_b128 v[96:99], v96
	v_or_b32_e32 v104, v108, v109
	ds_read_b128 v[100:103], v100
	ds_read_b128 v[106:109], v104
	s_waitcnt lgkmcnt(7)
	v_mfma_f32_16x16x32_bf16 v[24:27], v[92:95], v[24:27], 0
	s_waitcnt lgkmcnt(6)
	v_mfma_f32_16x16x32_bf16 v[32:35], v[92:95], v[32:35], 0
	s_waitcnt lgkmcnt(5)
	v_mfma_f32_16x16x32_bf16 v[24:27], v[64:67], v[70:73], v[24:27]
	s_waitcnt lgkmcnt(4)
	v_mfma_f32_16x16x32_bf16 v[32:35], v[64:67], v[74:77], v[32:35]
	s_waitcnt lgkmcnt(3)
	v_mfma_f32_16x16x32_bf16 v[24:27], v[84:87], v[78:81], v[24:27]
	s_waitcnt lgkmcnt(2)
	v_mfma_f32_16x16x32_bf16 v[32:35], v[84:87], v[96:99], v[32:35]
	s_waitcnt lgkmcnt(1)
	v_mfma_f32_16x16x32_bf16 v[24:27], v[88:91], v[100:103], v[24:27]
	s_waitcnt lgkmcnt(0)
	v_mfma_f32_16x16x32_bf16 v[32:35], v[88:91], v[106:109], v[32:35]
	v_lshlrev_b32_e32 v104, 2, v68
	v_or_b32_e32 v68, s2, v104
	v_or_b32_e32 v70, 1, v68
	v_cvt_f32_i32_e32 v71, v70
	v_sub_u32_e32 v70, 0x80, v70
	v_cvt_f32_i32_e32 v70, v70
	v_or_b32_e32 v146, v120, v69
	v_mul_f32_e32 v71, v117, v71
	v_mul_f32_e32 v71, 0x3fb8aa3b, v71
	v_exp_f32_e32 v106, v71
	v_sub_u32_e32 v71, 0x80, v68
	v_cvt_f32_i32_e32 v71, v71
	v_mul_f32_e32 v70, v118, v70
	v_mul_f32_e32 v70, 0x3fb8aa3b, v70
	v_exp_f32_e32 v109, v70
	v_mul_f32_e32 v71, v118, v71
	v_mul_f32_e32 v71, 0x3fb8aa3b, v71
	v_exp_f32_e32 v108, v71
	v_or_b32_e32 v71, 2, v68
	v_or_b32_e32 v70, 3, v68
	v_add_u32_e32 v68, 4, v68
	v_cvt_f32_i32_e32 v68, v68
	v_cvt_f32_i32_e32 v72, v71
	v_sub_u32_e32 v71, 0x80, v71
	v_cvt_f32_i32_e32 v71, v71
	v_mul_f32_e32 v68, v117, v68
	v_mul_f32_e32 v72, v117, v72
	v_mul_f32_e32 v68, 0x3fb8aa3b, v68
	v_mul_f32_e32 v72, 0x3fb8aa3b, v72
	v_exp_f32_e32 v111, v68
	v_sub_u32_e32 v68, 0x80, v70
	v_exp_f32_e32 v107, v72
	v_cvt_f32_i32_e32 v72, v70
	v_cvt_f32_i32_e32 v68, v68
	v_mul_f32_e32 v71, v118, v71
	v_mul_f32_e32 v71, 0x3fb8aa3b, v71
	v_mul_f32_e32 v72, v117, v72
	v_mul_f32_e32 v68, v118, v68
	v_mul_f32_e32 v72, 0x3fb8aa3b, v72
	v_mul_f32_e32 v68, 0x3fb8aa3b, v68
	v_or_b32_e32 v147, v120, v82
	v_or_b32_e32 v148, v120, v83
	v_or_b32_e32 v121, v120, v121
	v_exp_f32_e32 v110, v72
	v_exp_f32_e32 v112, v71
	v_exp_f32_e32 v113, v68
	ds_read_b128 v[68:71], v146
	ds_read_b128 v[72:75], v147
	ds_read_b128 v[76:79], v148
	ds_read_b128 v[80:83], v121
	ds_read_b128 v[96:99], v146 offset:4096
	ds_read_b128 v[100:103], v147 offset:4096
	ds_read_b128 v[122:125], v148 offset:4096
	ds_read_b128 v[126:129], v121 offset:4096
	s_waitcnt lgkmcnt(7)
	v_mfma_f32_16x16x32_bf16 v[68:71], v[68:71], v[92:95], 0
	s_waitcnt lgkmcnt(6)
	v_mfma_f32_16x16x32_bf16 v[68:71], v[72:75], v[64:67], v[68:71]
	s_waitcnt lgkmcnt(5)
	v_mfma_f32_16x16x32_bf16 v[68:71], v[76:79], v[84:87], v[68:71]
	s_waitcnt lgkmcnt(4)
	v_mfma_f32_16x16x32_bf16 v[130:133], v[80:83], v[88:91], v[68:71]
	s_waitcnt lgkmcnt(3)
	v_mfma_f32_16x16x32_bf16 v[68:71], v[96:99], v[92:95], 0
	s_waitcnt lgkmcnt(2)
	v_mfma_f32_16x16x32_bf16 v[68:71], v[100:103], v[64:67], v[68:71]
	s_waitcnt lgkmcnt(1)
	v_mfma_f32_16x16x32_bf16 v[68:71], v[122:125], v[84:87], v[68:71]
	s_waitcnt lgkmcnt(0)
	v_mfma_f32_16x16x32_bf16 v[100:103], v[126:129], v[88:91], v[68:71]
	s_nop 5
	ds_read_b128 v[68:71], v146 offset:8192
	ds_read_b128 v[72:75], v146 offset:12288
	ds_read_b128 v[76:79], v147 offset:8192
	ds_read_b128 v[80:83], v147 offset:12288
	ds_read_b128 v[96:99], v148 offset:8192
	ds_read_b128 v[122:125], v148 offset:12288
	ds_read_b128 v[126:129], v121 offset:8192
	ds_read_b128 v[134:137], v121 offset:12288
	s_waitcnt lgkmcnt(7)
	v_mfma_f32_16x16x32_bf16 v[68:71], v[68:71], v[92:95], 0
	s_waitcnt lgkmcnt(5)
	v_mfma_f32_16x16x32_bf16 v[68:71], v[76:79], v[64:67], v[68:71]
	s_waitcnt lgkmcnt(3)
	v_mfma_f32_16x16x32_bf16 v[68:71], v[96:99], v[84:87], v[68:71]
	s_waitcnt lgkmcnt(1)
	v_mfma_f32_16x16x32_bf16 v[96:99], v[126:129], v[88:91], v[68:71]
	v_mfma_f32_16x16x32_bf16 v[68:71], v[72:75], v[92:95], 0
	v_mfma_f32_16x16x32_bf16 v[68:71], v[80:83], v[64:67], v[68:71]
	v_mfma_f32_16x16x32_bf16 v[68:71], v[122:125], v[84:87], v[68:71]
	s_waitcnt lgkmcnt(0)
	v_mfma_f32_16x16x32_bf16 v[80:83], v[134:137], v[88:91], v[68:71]
	s_nop 5
	ds_read_b128 v[68:71], v146 offset:16384
	ds_read_b128 v[72:75], v146 offset:20480
	ds_read_b128 v[76:79], v147 offset:16384
	ds_read_b128 v[122:125], v147 offset:20480
	ds_read_b128 v[126:129], v148 offset:16384
	ds_read_b128 v[134:137], v148 offset:20480
	ds_read_b128 v[138:141], v121 offset:16384
	ds_read_b128 v[142:145], v121 offset:20480
	s_waitcnt lgkmcnt(7)
	v_mfma_f32_16x16x32_bf16 v[68:71], v[68:71], v[92:95], 0
	s_waitcnt lgkmcnt(5)
	v_mfma_f32_16x16x32_bf16 v[68:71], v[76:79], v[64:67], v[68:71]
	s_waitcnt lgkmcnt(3)
	v_mfma_f32_16x16x32_bf16 v[68:71], v[126:129], v[84:87], v[68:71]
	s_waitcnt lgkmcnt(1)
	v_mfma_f32_16x16x32_bf16 v[76:79], v[138:141], v[88:91], v[68:71]
	v_mfma_f32_16x16x32_bf16 v[68:71], v[72:75], v[92:95], 0
	v_mfma_f32_16x16x32_bf16 v[68:71], v[122:125], v[64:67], v[68:71]
	v_mfma_f32_16x16x32_bf16 v[68:71], v[134:137], v[84:87], v[68:71]
	s_waitcnt lgkmcnt(0)
; DEVFI bfraw f2bf(float x) { unsigned u = __float_as_uint(x); u += 0x7fffu + ((u >> 16) & 1u); return (bfraw)(u >> 16); }
; #define SBAR() __builtin_amdgcn_sched_barrier(0)
; __global__ void __launch_bounds__(512) mega(Params p) {
;     ...
;             for (int n2 = 0; n2 < 4; ++n2) { bf16x8 A[2][4];
; #pragma unroll
;               for (int q2 = 0; q2 < 2; ++q2)
; #pragma unroll
;                 for (int sx = 0; sx < 4; ++sx) A[q2][sx] = RLD16(0, (n2 * 2 + q2) * 16 + fr, sx * 4 + fq);
;               SBAR();
; #pragma unroll
;               for (int q2 = 0; q2 < 2; ++q2)
; #pragma unroll
;                 for (int sx = 0; sx < 4; ++sx) sc[n2 * 2 + q2] = __builtin_amdgcn_mfma_f32_16x16x32_bf16(A[q2][sx], qf[sx], sc[n2 * 2 + q2], 0, 0, 0);
;               SBAR(); }
;             const int cc = w * 16 + fr;
; #pragma unroll
;             for (int sx = 0; sx < 4; ++sx)
; #pragma unroll
;               for (int hf = 0; hf < 2; ++hf)
; #pragma unroll
;                 for (int j = 0; j < 4; ++j) { const int n = 2 * sx + hf, mm = n * 16 + fq * 4 + j, diff = cc - mm;
;                   const float Dm = (diff >= 0) ? __expf(lgf * (float)diff) : __expf(lgb * (float)(-diff));
;                   pf[sx][hf * 4 + j] = (short)f2bf(sc[n][j] * Dm); } }
	v_mfma_f32_16x16x32_bf16 v[72:75], v[142:145], v[88:91], v[68:71]
	s_nop 5
	ds_read_b128 v[68:71], v146 offset:24576
	ds_read_b128 v[122:125], v146 offset:28672
	ds_read_b128 v[126:129], v147 offset:24576
	ds_read_b128 v[134:137], v147 offset:28672
	ds_read_b128 v[138:141], v148 offset:24576
	ds_read_b128 v[142:145], v148 offset:28672
	ds_read_b128 v[146:149], v121 offset:24576
	ds_read_b128 v[150:153], v121 offset:28672
	s_waitcnt lgkmcnt(7)
	v_mfma_f32_16x16x32_bf16 v[68:71], v[68:71], v[92:95], 0
	s_waitcnt lgkmcnt(6)
	v_mfma_f32_16x16x32_bf16 v[92:95], v[122:125], v[92:95], 0
	s_waitcnt lgkmcnt(5)
	v_mfma_f32_16x16x32_bf16 v[68:71], v[126:129], v[64:67], v[68:71]
	s_waitcnt lgkmcnt(4)
	v_mfma_f32_16x16x32_bf16 v[64:67], v[134:137], v[64:67], v[92:95]
	s_waitcnt lgkmcnt(3)
	v_mfma_f32_16x16x32_bf16 v[68:71], v[138:141], v[84:87], v[68:71]
	s_waitcnt lgkmcnt(2)
	v_mfma_f32_16x16x32_bf16 v[64:67], v[142:145], v[84:87], v[64:67]
	s_waitcnt lgkmcnt(1)
	v_mfma_f32_16x16x32_bf16 v[68:71], v[146:149], v[88:91], v[68:71]
	s_waitcnt lgkmcnt(0)
	v_mfma_f32_16x16x32_bf16 v[64:67], v[150:153], v[88:91], v[64:67]
	v_or_b32_e32 v87, s2, v115
	v_sub_u32_e32 v84, v87, v104
	v_sub_u32_e32 v85, 0, v84
	v_max_i32_e32 v85, v84, v85
	v_cvt_f32_u32_e32 v85, v85
	v_cmp_gt_i32_e32 vcc, 0, v84
	v_or_b32_e32 v86, 1, v104
	s_nop 0
	v_cndmask_b32_e32 v84, v117, v118, vcc
	v_mul_f32_e32 v84, v84, v85
	v_sub_u32_e32 v85, v87, v86
	v_sub_u32_e32 v88, 0, v85
	v_max_i32_e32 v88, v85, v88
	v_cvt_f32_u32_e32 v88, v88
	v_cmp_gt_i32_e32 vcc, 0, v85
	v_mul_f32_e32 v84, 0x3fb8aa3b, v84
	v_exp_f32_e32 v84, v84
	v_cndmask_b32_e32 v85, v117, v118, vcc
	v_mul_f32_e32 v85, v85, v88
	v_mul_f32_e32 v85, 0x3fb8aa3b, v85
	v_exp_f32_e32 v85, v85
	s_nop 0
	v_pk_mul_f32 v[94:95], v[84:85], v[130:131]
	v_or_b32_e32 v85, 2, v104
	v_sub_u32_e32 v84, v87, v85
	v_sub_u32_e32 v88, 0, v84
	v_max_i32_e32 v88, v84, v88
	v_cvt_f32_u32_e32 v88, v88
	v_cmp_gt_i32_e32 vcc, 0, v84
	v_bfe_u32 v124, v94, 16, 1
	v_bfe_u32 v123, v95, 16, 1
	v_cndmask_b32_e32 v84, v117, v118, vcc
	v_mul_f32_e32 v84, v84, v88
	v_mul_f32_e32 v84, 0x3fb8aa3b, v84
	v_exp_f32_e32 v88, v84
	v_or_b32_e32 v84, 3, v104
	v_sub_u32_e32 v89, v87, v84
	v_sub_u32_e32 v90, 0, v89
	v_max_i32_e32 v90, v89, v90
	v_cvt_f32_u32_e32 v90, v90
	v_cmp_gt_i32_e32 vcc, 0, v89
	s_nop 1
	v_cndmask_b32_e32 v89, v117, v118, vcc
	v_mul_f32_e32 v89, v89, v90
	v_or_b32_e32 v90, 16, v104
	v_sub_u32_e32 v90, v87, v90
	v_sub_u32_e32 v91, 0, v90
	v_max_i32_e32 v91, v90, v91
	v_cvt_f32_u32_e32 v91, v91
	v_cmp_gt_i32_e32 vcc, 0, v90
	v_mul_f32_e32 v89, 0x3fb8aa3b, v89
	v_exp_f32_e32 v89, v89
	v_cndmask_b32_e32 v90, v117, v118, vcc
	v_mul_f32_e32 v90, v90, v91
	v_or_b32_e32 v91, 17, v104
	v_sub_u32_e32 v91, v87, v91
	v_sub_u32_e32 v92, 0, v91
	v_max_i32_e32 v92, v91, v92
	v_cvt_f32_u32_e32 v92, v92
	v_cmp_gt_i32_e32 vcc, 0, v91
	v_mul_f32_e32 v90, 0x3fb8aa3b, v90
	v_exp_f32_e32 v90, v90
	v_cndmask_b32_e32 v91, v117, v118, vcc
	v_mul_f32_e32 v91, v91, v92
	v_mul_f32_e32 v91, 0x3fb8aa3b, v91
	v_exp_f32_e32 v91, v91
	v_pk_mul_f32 v[88:89], v[88:89], v[132:133]
	v_pk_mul_f32 v[100:101], v[90:91], v[100:101]
	v_or_b32_e32 v90, 18, v104
	v_sub_u32_e32 v90, v87, v90
	v_sub_u32_e32 v91, 0, v90
	v_max_i32_e32 v91, v90, v91
	v_cvt_f32_u32_e32 v91, v91
	v_cmp_gt_i32_e32 vcc, 0, v90
	v_bfe_u32 v122, v100, 16, 1
	v_bfe_u32 v121, v101, 16, 1
	v_cndmask_b32_e32 v90, v117, v118, vcc
	v_mul_f32_e32 v90, v90, v91
	v_or_b32_e32 v91, 19, v104
	v_sub_u32_e32 v91, v87, v91
	v_sub_u32_e32 v92, 0, v91
	v_max_i32_e32 v92, v91, v92
	v_cvt_f32_u32_e32 v92, v92
	v_cmp_gt_i32_e32 vcc, 0, v91
	v_mul_f32_e32 v90, 0x3fb8aa3b, v90
	v_exp_f32_e32 v90, v90
	v_cndmask_b32_e32 v91, v117, v118, vcc
	v_mul_f32_e32 v91, v91, v92
	v_mul_f32_e32 v91, 0x3fb8aa3b, v91
	v_exp_f32_e32 v91, v91
	s_nop 0
	v_pk_mul_f32 v[92:93], v[90:91], v[102:103]
	s_nop 0
	v_bfe_u32 v90, v93, 16, 1
	v_add3_u32 v93, v93, v90, s82
	v_add3_u32 v90, v94, v124, s82
	v_add3_u32 v94, v100, v122, s82
	v_or_b32_e32 v100, 32, v104
	v_bfe_u32 v91, v92, 16, 1
	v_sub_u32_e32 v100, v87, v100
	v_add3_u32 v91, v92, v91, s82
	v_add3_u32 v92, v95, v123, s82
	v_add3_u32 v95, v101, v121, s82
	v_sub_u32_e32 v101, 0, v100
	v_max_i32_e32 v101, v100, v101
	v_cvt_f32_u32_e32 v101, v101
	v_cmp_gt_i32_e32 vcc, 0, v100
	v_bfe_u32 v102, v89, 16, 1
	v_add3_u32 v89, v89, v102, s82
	v_cndmask_b32_e32 v100, v117, v118, vcc
	v_mul_f32_e32 v100, v100, v101
	v_or_b32_e32 v101, 33, v104
	v_sub_u32_e32 v101, v87, v101
	v_sub_u32_e32 v102, 0, v101
	v_max_i32_e32 v102, v101, v102
	v_cvt_f32_u32_e32 v102, v102
	v_cmp_gt_i32_e32 vcc, 0, v101
	v_mul_f32_e32 v100, 0x3fb8aa3b, v100
	v_exp_f32_e32 v100, v100
	v_cndmask_b32_e32 v101, v117, v118, vcc
	v_mul_f32_e32 v101, v101, v102
	v_mul_f32_e32 v101, 0x3fb8aa3b, v101
	v_exp_f32_e32 v101, v101
	v_bfe_u32 v103, v88, 16, 1
	v_add3_u32 v88, v88, v103, s82
	v_pk_mul_f32 v[100:101], v[100:101], v[96:97]
	v_or_b32_e32 v96, 34, v104
	v_sub_u32_e32 v96, v87, v96
	v_sub_u32_e32 v97, 0, v96
	v_max_i32_e32 v97, v96, v97
	v_cvt_f32_u32_e32 v97, v97
	v_cmp_gt_i32_e32 vcc, 0, v96
	v_bfe_u32 v124, v100, 16, 1
	v_bfe_u32 v123, v101, 16, 1
	v_cndmask_b32_e32 v96, v117, v118, vcc
	v_mul_f32_e32 v96, v96, v97
	v_or_b32_e32 v97, 35, v104
	v_sub_u32_e32 v97, v87, v97
	v_sub_u32_e32 v102, 0, v97
	v_max_i32_e32 v102, v97, v102
	v_cvt_f32_u32_e32 v102, v102
	v_cmp_gt_i32_e32 vcc, 0, v97
	v_mul_f32_e32 v96, 0x3fb8aa3b, v96
	v_exp_f32_e32 v96, v96
	v_cndmask_b32_e32 v97, v117, v118, vcc
	v_mul_f32_e32 v97, v97, v102
	v_mul_f32_e32 v97, 0x3fb8aa3b, v97
	v_exp_f32_e32 v97, v97
	s_nop 0
	v_pk_mul_f32 v[96:97], v[96:97], v[98:99]
; DEVFI bfraw f2bf(float x) { unsigned u = __float_as_uint(x); u += 0x7fffu + ((u >> 16) & 1u); return (bfraw)(u >> 16); }
; __global__ void __launch_bounds__(512) mega(Params p) {
;     ...
;             const int cc = w * 16 + fr;
; #pragma unroll
;             for (int sx = 0; sx < 4; ++sx)
; #pragma unroll
;               for (int hf = 0; hf < 2; ++hf)
; #pragma unroll
;                 for (int j = 0; j < 4; ++j) { const int n = 2 * sx + hf, mm = n * 16 + fq * 4 + j, diff = cc - mm;
;                   const float Dm = (diff >= 0) ? __expf(lgf * (float)diff) : __expf(lgb * (float)(-diff));
;                   pf[sx][hf * 4 + j] = (short)f2bf(sc[n][j] * Dm); } }
	v_or_b32_e32 v98, 48, v104
	v_sub_u32_e32 v98, v87, v98
	v_sub_u32_e32 v99, 0, v98
	v_max_i32_e32 v99, v98, v99
	v_cvt_f32_u32_e32 v99, v99
	v_cmp_gt_i32_e32 vcc, 0, v98
	s_nop 1
	v_cndmask_b32_e32 v98, v117, v118, vcc
	v_mul_f32_e32 v98, v98, v99
	v_or_b32_e32 v99, 49, v104
	v_sub_u32_e32 v99, v87, v99
	v_sub_u32_e32 v102, 0, v99
	v_max_i32_e32 v102, v99, v102
	v_cvt_f32_u32_e32 v102, v102
	v_cmp_gt_i32_e32 vcc, 0, v99
	v_mul_f32_e32 v98, 0x3fb8aa3b, v98
	v_exp_f32_e32 v98, v98
	v_cndmask_b32_e32 v99, v117, v118, vcc
	v_mul_f32_e32 v99, v99, v102
	v_mul_f32_e32 v99, 0x3fb8aa3b, v99
	v_exp_f32_e32 v99, v99
	s_nop 0
	v_pk_mul_f32 v[98:99], v[98:99], v[80:81]
	v_or_b32_e32 v80, 50, v104
	v_sub_u32_e32 v80, v87, v80
	v_sub_u32_e32 v81, 0, v80
	v_max_i32_e32 v81, v80, v81
	v_cvt_f32_u32_e32 v81, v81
	v_cmp_gt_i32_e32 vcc, 0, v80
	v_bfe_u32 v122, v98, 16, 1
	v_add3_u32 v98, v98, v122, s82
	v_cndmask_b32_e32 v80, v117, v118, vcc
	v_mul_f32_e32 v80, v80, v81
	v_or_b32_e32 v81, 51, v104
	v_sub_u32_e32 v81, v87, v81
	v_sub_u32_e32 v102, 0, v81
	v_max_i32_e32 v102, v81, v102
	v_cvt_f32_u32_e32 v102, v102
	v_cmp_gt_i32_e32 vcc, 0, v81
	v_mul_f32_e32 v80, 0x3fb8aa3b, v80
	v_exp_f32_e32 v80, v80
	v_cndmask_b32_e32 v81, v117, v118, vcc
	v_mul_f32_e32 v81, v81, v102
	v_mul_f32_e32 v81, 0x3fb8aa3b, v81
	v_exp_f32_e32 v81, v81
	v_bfe_u32 v121, v99, 16, 1
	v_add3_u32 v99, v99, v121, s82
	v_pk_mul_f32 v[102:103], v[80:81], v[82:83]
	s_nop 0
	v_bfe_u32 v82, v103, 16, 1
	v_bfe_u32 v81, v97, 16, 1
	v_add3_u32 v81, v97, v81, s82
	v_add3_u32 v97, v103, v82, s82
	v_add3_u32 v82, v100, v124, s82
	v_or_b32_e32 v100, 64, v104
	v_bfe_u32 v80, v96, 16, 1
	v_sub_u32_e32 v100, v87, v100
	v_add3_u32 v80, v96, v80, s82
	v_add3_u32 v96, v101, v123, s82
	v_sub_u32_e32 v101, 0, v100
	v_max_i32_e32 v101, v100, v101
	v_cvt_f32_u32_e32 v101, v101
	v_cmp_gt_i32_e32 vcc, 0, v100
	v_bfe_u32 v83, v102, 16, 1
	v_add3_u32 v83, v102, v83, s82
	v_cndmask_b32_e32 v100, v117, v118, vcc
	v_mul_f32_e32 v100, v100, v101
	v_or_b32_e32 v101, 0x41, v104
	v_sub_u32_e32 v101, v87, v101
	v_sub_u32_e32 v102, 0, v101
	v_max_i32_e32 v102, v101, v102
	v_cvt_f32_u32_e32 v102, v102
	v_cmp_gt_i32_e32 vcc, 0, v101
	v_mul_f32_e32 v100, 0x3fb8aa3b, v100
	v_exp_f32_e32 v100, v100
	v_cndmask_b32_e32 v101, v117, v118, vcc
	v_mul_f32_e32 v101, v101, v102
	v_mul_f32_e32 v101, 0x3fb8aa3b, v101
	v_exp_f32_e32 v101, v101
	s_nop 0
	v_pk_mul_f32 v[76:77], v[100:101], v[76:77]
	v_or_b32_e32 v100, 0x42, v104
	v_sub_u32_e32 v100, v87, v100
	v_sub_u32_e32 v101, 0, v100
	v_max_i32_e32 v101, v100, v101
	v_cvt_f32_u32_e32 v101, v101
	v_cmp_gt_i32_e32 vcc, 0, v100
	v_bfe_u32 v123, v77, 16, 1
	v_bfe_u32 v124, v76, 16, 1
	v_cndmask_b32_e32 v100, v117, v118, vcc
	v_mul_f32_e32 v100, v100, v101
	v_or_b32_e32 v101, 0x43, v104
	v_sub_u32_e32 v101, v87, v101
	v_sub_u32_e32 v102, 0, v101
	v_max_i32_e32 v102, v101, v102
	v_cvt_f32_u32_e32 v102, v102
	v_cmp_gt_i32_e32 vcc, 0, v101
	v_mul_f32_e32 v100, 0x3fb8aa3b, v100
	v_exp_f32_e32 v100, v100
	v_cndmask_b32_e32 v101, v117, v118, vcc
	v_mul_f32_e32 v101, v101, v102
	v_mul_f32_e32 v101, 0x3fb8aa3b, v101
	v_exp_f32_e32 v101, v101
	v_add3_u32 v142, v76, v124, s82
	v_add3_u32 v143, v77, v123, s82
	v_pk_mul_f32 v[78:79], v[100:101], v[78:79]
	v_or_b32_e32 v100, 0x50, v104
	v_sub_u32_e32 v100, v87, v100
	v_sub_u32_e32 v101, 0, v100
	v_max_i32_e32 v101, v100, v101
	v_cvt_f32_u32_e32 v101, v101
	v_cmp_gt_i32_e32 vcc, 0, v100
	v_bfe_u32 v103, v78, 16, 1
	v_add3_u32 v78, v78, v103, s82
	v_cndmask_b32_e32 v100, v117, v118, vcc
	v_mul_f32_e32 v100, v100, v101
	v_or_b32_e32 v101, 0x51, v104
	v_sub_u32_e32 v101, v87, v101
	v_sub_u32_e32 v102, 0, v101
	v_max_i32_e32 v102, v101, v102
	v_cvt_f32_u32_e32 v102, v102
	v_cmp_gt_i32_e32 vcc, 0, v101
	v_mul_f32_e32 v100, 0x3fb8aa3b, v100
	v_exp_f32_e32 v100, v100
	v_cndmask_b32_e32 v101, v117, v118, vcc
	v_mul_f32_e32 v101, v101, v102
	v_mul_f32_e32 v101, 0x3fb8aa3b, v101
	v_exp_f32_e32 v101, v101
	s_nop 0
	v_pk_mul_f32 v[72:73], v[100:101], v[72:73]
	v_or_b32_e32 v100, 0x52, v104
	v_sub_u32_e32 v100, v87, v100
	v_sub_u32_e32 v101, 0, v100
	v_max_i32_e32 v101, v100, v101
	v_cvt_f32_u32_e32 v101, v101
	v_cmp_gt_i32_e32 vcc, 0, v100
	v_bfe_u32 v122, v72, 16, 1
	v_add3_u32 v144, v72, v122, s82
	v_cndmask_b32_e32 v100, v117, v118, vcc
	v_mul_f32_e32 v100, v100, v101
	v_or_b32_e32 v101, 0x53, v104
	v_sub_u32_e32 v101, v87, v101
	v_sub_u32_e32 v102, 0, v101
	v_max_i32_e32 v102, v101, v102
	v_cvt_f32_u32_e32 v102, v102
	v_cmp_gt_i32_e32 vcc, 0, v101
	v_or_b32_e32 v72, 0x60, v104
	v_bfe_u32 v121, v73, 16, 1
	v_cndmask_b32_e32 v101, v117, v118, vcc
	v_sub_u32_e32 v72, v87, v72
	v_mul_f32_e32 v101, v101, v102
	v_add3_u32 v145, v73, v121, s82
	v_sub_u32_e32 v73, 0, v72
	v_mul_f32_e32 v100, 0x3fb8aa3b, v100
	v_mul_f32_e32 v101, 0x3fb8aa3b, v101
	v_max_i32_e32 v73, v72, v73
	v_exp_f32_e32 v100, v100
	v_exp_f32_e32 v101, v101
	v_cvt_f32_u32_e32 v73, v73
	v_cmp_gt_i32_e32 vcc, 0, v72
	v_bfe_u32 v102, v79, 16, 1
	v_pk_mul_f32 v[74:75], v[100:101], v[74:75]
	v_cndmask_b32_e32 v72, v117, v118, vcc
	v_mul_f32_e32 v72, v72, v73
	v_or_b32_e32 v73, 0x61, v104
	v_bfe_u32 v101, v74, 16, 1
	v_sub_u32_e32 v73, v87, v73
	v_add3_u32 v140, v74, v101, s82
	v_sub_u32_e32 v74, 0, v73
	v_max_i32_e32 v74, v73, v74
	v_cvt_f32_u32_e32 v74, v74
	v_cmp_gt_i32_e32 vcc, 0, v73
	v_mul_f32_e32 v72, 0x3fb8aa3b, v72
	v_exp_f32_e32 v72, v72
	v_cndmask_b32_e32 v73, v117, v118, vcc
	v_mul_f32_e32 v73, v73, v74
	v_mul_f32_e32 v73, 0x3fb8aa3b, v73
	v_exp_f32_e32 v73, v73
	v_bfe_u32 v100, v75, 16, 1
	v_add3_u32 v141, v75, v100, s82
	v_add3_u32 v79, v79, v102, s82
	v_pk_mul_f32 v[68:69], v[72:73], v[68:69]
; DEVFI bfraw f2bf(float x) { unsigned u = __float_as_uint(x); u += 0x7fffu + ((u >> 16) & 1u); return (bfraw)(u >> 16); }
; #define SBAR() __builtin_amdgcn_sched_barrier(0)
; __global__ void __launch_bounds__(512) mega(Params p) {
;     ...
;             const int cc = w * 16 + fr;
; #pragma unroll
;             for (int sx = 0; sx < 4; ++sx)
; #pragma unroll
;               for (int hf = 0; hf < 2; ++hf)
; #pragma unroll
;                 for (int j = 0; j < 4; ++j) { const int n = 2 * sx + hf, mm = n * 16 + fq * 4 + j, diff = cc - mm;
;                   const float Dm = (diff >= 0) ? __expf(lgf * (float)diff) : __expf(lgb * (float)(-diff));
;                   pf[sx][hf * 4 + j] = (short)f2bf(sc[n][j] * Dm); } }
;           { const char* vl = shm + 32768 + fr * 256 + (fq & 1) * 8;
; #pragma unroll
;             for (int n2 = 0; n2 < 4; ++n2) { s16x4 lo[2][4], hi[2][4];
; #pragma unroll
;               for (int q2 = 0; q2 < 2; ++q2)
; #pragma unroll
;                 for (int sx = 0; sx < 4; ++sx) { lo[q2][sx] = *(const s16x4*)(vl + (n2 * 2 + q2) * 4096 + ((((sx * 4 + (fq >> 1)) ^ fr) & 15) << 4));
;                   hi[q2][sx] = *(const s16x4*)(vl + (n2 * 2 + q2) * 4096 + ((((sx * 4 + 2 + (fq >> 1)) ^ fr) & 15) << 4)); }
;               SBAR();
; #pragma unroll
;               for (int q2 = 0; q2 < 2; ++q2)
; #pragma unroll
;                 for (int sx = 0; sx < 4; ++sx) { const bf16x8 B = {lo[q2][sx][0], lo[q2][sx][1], lo[q2][sx][2], lo[q2][sx][3], hi[q2][sx][0], hi[q2][sx][1], hi[q2][sx][2], hi[q2][sx][3]};
;                   o[n2 * 2 + q2] = __builtin_amdgcn_mfma_f32_16x16x32_bf16(pf[sx], B, o[n2 * 2 + q2], 0, 0, 0); }
;               SBAR(); } }
	v_or_b32_e32 v72, 0x62, v104
	v_sub_u32_e32 v72, v87, v72
	v_sub_u32_e32 v73, 0, v72
	v_max_i32_e32 v73, v72, v73
	v_cvt_f32_u32_e32 v73, v73
	v_cmp_gt_i32_e32 vcc, 0, v72
	v_bfe_u32 v100, v68, 16, 1
	v_add3_u32 v150, v68, v100, s82
	v_cndmask_b32_e32 v72, v117, v118, vcc
	v_mul_f32_e32 v72, v72, v73
	v_or_b32_e32 v73, 0x63, v104
	v_sub_u32_e32 v73, v87, v73
	v_sub_u32_e32 v74, 0, v73
	v_max_i32_e32 v74, v73, v74
	v_cvt_f32_u32_e32 v74, v74
	v_cmp_gt_i32_e32 vcc, 0, v73
	v_mul_f32_e32 v72, 0x3fb8aa3b, v72
	v_exp_f32_e32 v72, v72
	v_cndmask_b32_e32 v73, v117, v118, vcc
	v_mul_f32_e32 v73, v73, v74
	v_mul_f32_e32 v73, 0x3fb8aa3b, v73
	v_exp_f32_e32 v73, v73
	s_nop 0
	v_pk_mul_f32 v[70:71], v[72:73], v[70:71]
	v_or_b32_e32 v72, 0x70, v104
	v_sub_u32_e32 v72, v87, v72
	v_sub_u32_e32 v73, 0, v72
	v_max_i32_e32 v73, v72, v73
	v_cvt_f32_u32_e32 v73, v73
	v_cmp_gt_i32_e32 vcc, 0, v72
	v_bfe_u32 v75, v70, 16, 1
	v_add3_u32 v146, v70, v75, s82
	v_cndmask_b32_e32 v72, v117, v118, vcc
	v_mul_f32_e32 v72, v72, v73
	v_or_b32_e32 v73, 0x71, v104
	v_sub_u32_e32 v73, v87, v73
	v_sub_u32_e32 v74, 0, v73
	v_max_i32_e32 v74, v73, v74
	v_cvt_f32_u32_e32 v74, v74
	v_cmp_gt_i32_e32 vcc, 0, v73
	v_mul_f32_e32 v72, 0x3fb8aa3b, v72
	v_exp_f32_e32 v72, v72
	v_cndmask_b32_e32 v73, v117, v118, vcc
	v_mul_f32_e32 v73, v73, v74
	v_mul_f32_e32 v73, 0x3fb8aa3b, v73
	v_exp_f32_e32 v73, v73
	s_nop 0
	v_pk_mul_f32 v[64:65], v[72:73], v[64:65]
	v_or_b32_e32 v72, 0x72, v104
	v_sub_u32_e32 v72, v87, v72
	v_sub_u32_e32 v73, 0, v72
	v_max_i32_e32 v73, v72, v73
	v_cvt_f32_u32_e32 v73, v73
	v_cmp_gt_i32_e32 vcc, 0, v72
	v_bfe_u32 v76, v65, 16, 1
	v_bfe_u32 v77, v64, 16, 1
	v_cndmask_b32_e32 v72, v117, v118, vcc
	v_mul_f32_e32 v72, v72, v73
	v_or_b32_e32 v73, 0x73, v104
	v_sub_u32_e32 v73, v87, v73
	v_sub_u32_e32 v74, 0, v73
	v_max_i32_e32 v74, v73, v74
	v_cvt_f32_u32_e32 v74, v74
	v_cmp_gt_i32_e32 vcc, 0, v73
	v_mul_f32_e32 v72, 0x3fb8aa3b, v72
	v_exp_f32_e32 v72, v72
	v_cndmask_b32_e32 v73, v117, v118, vcc
	v_mul_f32_e32 v73, v73, v74
	v_mul_f32_e32 v73, 0x3fb8aa3b, v73
	v_exp_f32_e32 v73, v73
	v_add3_u32 v151, v64, v77, s82
	v_add3_u32 v152, v65, v76, s82
	v_lshrrev_b32_e32 v64, 1, v116
	v_pk_mul_f32 v[66:67], v[72:73], v[66:67]
	v_bfe_u32 v65, v119, 1, 1
	v_bfe_u32 v73, v66, 16, 1
	v_add3_u32 v148, v66, v73, s82
	v_and_or_b32 v64, v64, 8, v120
	v_bitop3_b32 v66, v65, v116, 15 bitop3:0x78
	v_lshl_or_b32 v153, v66, 4, v64
	v_bitop3_b32 v66, v65, v115, 2 bitop3:0x36
	v_lshl_or_b32 v154, v66, 4, v64
	v_bitop3_b32 v66, v65, v115, 4 bitop3:0x36
	v_lshl_or_b32 v155, v66, 4, v64
	v_bitop3_b32 v66, v65, v115, 6 bitop3:0x36
	v_lshl_or_b32 v156, v66, 4, v64
	v_bitop3_b32 v66, v65, v115, 8 bitop3:0x36
	v_lshl_or_b32 v157, v66, 4, v64
	v_bitop3_b32 v66, v65, v115, 10 bitop3:0x36
	v_lshl_or_b32 v158, v66, 4, v64
	v_bitop3_b32 v66, v65, v115, 12 bitop3:0x36
	v_bitop3_b32 v65, v65, v115, 14 bitop3:0x36
	v_bfe_u32 v74, v71, 16, 1
	v_lshl_or_b32 v159, v66, 4, v64
	v_lshl_or_b32 v160, v65, 4, v64
	v_add3_u32 v147, v71, v74, s82
	ds_read2st64_b64 v[74:77], v153 offset0:64 offset1:72
	ds_read2st64_b64 v[100:103], v154 offset0:64 offset1:72
	ds_read2st64_b64 v[116:119], v155 offset0:64 offset1:72
	ds_read2st64_b64 v[120:123], v156 offset0:64 offset1:72
	ds_read2st64_b64 v[124:127], v157 offset0:64 offset1:72
	ds_read2st64_b64 v[128:131], v158 offset0:64 offset1:72
	ds_read2st64_b64 v[132:135], v159 offset0:64 offset1:72
	ds_read2st64_b64 v[136:139], v160 offset0:64 offset1:72
	v_bfe_u32 v72, v67, 16, 1
	v_bfe_u32 v87, v69, 16, 1
	v_add3_u32 v149, v67, v72, s82
	v_add3_u32 v87, v69, v87, s82
	v_perm_b32 v67, v93, v91, s58
	v_perm_b32 v65, v89, v88, s58
	v_perm_b32 v66, v95, v94, s58
	v_perm_b32 v64, v92, v90, s58
	v_pk_mul_f32 v[62:63], v[112:113], v[62:63]
	v_pk_mul_f32 v[60:61], v[108:109], v[60:61]
	s_waitcnt lgkmcnt(7)
	v_mov_b32_e32 v68, v74
	v_mov_b32_e32 v69, v75
	s_waitcnt lgkmcnt(6)
	v_mov_b32_e32 v70, v100
	v_mov_b32_e32 v71, v101
	v_pk_fma_f32 v[30:31], v[110:111], v[30:31], v[62:63]
	v_pk_fma_f32 v[28:29], v[106:107], v[28:29], v[60:61]
	v_perm_b32 v63, v97, v83, s58
	v_perm_b32 v61, v81, v80, s58
	v_perm_b32 v62, v99, v98, s58
	v_perm_b32 v60, v96, v82, s58
	v_mfma_f32_16x16x32_bf16 v[28:31], v[64:67], v[68:71], v[28:31]
	v_mul_f32_e64 v58, v112, v58
	v_mul_f32_e64 v59, v113, v59
	v_pk_mul_f32 v[56:57], v[108:109], v[56:57]
	v_mov_b32_e32 v100, v76
	v_mov_b32_e32 v101, v77
	v_pk_fma_f32 v[2:3], v[110:111], v[2:3], v[58:59]
	v_pk_fma_f32 v[0:1], v[106:107], v[0:1], v[56:57]
	s_waitcnt lgkmcnt(5)
	v_mov_b32_e32 v68, v116
	v_mov_b32_e32 v69, v117
	v_mfma_f32_16x16x32_bf16 v[0:3], v[64:67], v[100:103], v[0:3]
	s_waitcnt lgkmcnt(4)
	v_mov_b32_e32 v70, v120
	v_mov_b32_e32 v71, v121
	v_mov_b32_e32 v120, v118
	v_mov_b32_e32 v121, v119
	v_mfma_f32_16x16x32_bf16 v[28:31], v[60:63], v[68:71], v[28:31]
	v_perm_b32 v71, v141, v140, s58
	v_perm_b32 v69, v79, v78, s58
	v_perm_b32 v70, v145, v144, s58
	v_perm_b32 v68, v143, v142, s58
	v_mfma_f32_16x16x32_bf16 v[0:3], v[60:63], v[120:123], v[0:3]
	s_waitcnt lgkmcnt(3)
	v_mov_b32_e32 v72, v124
	v_mov_b32_e32 v73, v125
	s_waitcnt lgkmcnt(2)
	v_mov_b32_e32 v74, v128
	v_mov_b32_e32 v75, v129
	v_mov_b32_e32 v128, v126
	v_mov_b32_e32 v129, v127
	v_mfma_f32_16x16x32_bf16 v[28:31], v[68:71], v[72:75], v[28:31]
	v_perm_b32 v75, v149, v148, s58
	v_perm_b32 v73, v147, v146, s58
	v_perm_b32 v74, v152, v151, s58
	v_perm_b32 v72, v87, v150, s58
	v_mfma_f32_16x16x32_bf16 v[0:3], v[68:71], v[128:131], v[0:3]
	s_waitcnt lgkmcnt(1)
	v_mov_b32_e32 v78, v132
	v_mov_b32_e32 v79, v133
	s_waitcnt lgkmcnt(0)
; #define SBAR() __builtin_amdgcn_sched_barrier(0)
; __global__ void __launch_bounds__(512) mega(Params p) {
;     ...
;           { const char* vl = shm + 32768 + fr * 256 + (fq & 1) * 8;
; #pragma unroll
;             for (int n2 = 0; n2 < 4; ++n2) { s16x4 lo[2][4], hi[2][4];
; #pragma unroll
;               for (int q2 = 0; q2 < 2; ++q2)
; #pragma unroll
;                 for (int sx = 0; sx < 4; ++sx) { lo[q2][sx] = *(const s16x4*)(vl + (n2 * 2 + q2) * 4096 + ((((sx * 4 + (fq >> 1)) ^ fr) & 15) << 4));
;                   hi[q2][sx] = *(const s16x4*)(vl + (n2 * 2 + q2) * 4096 + ((((sx * 4 + 2 + (fq >> 1)) ^ fr) & 15) << 4)); }
;               SBAR();
; #pragma unroll
;               for (int q2 = 0; q2 < 2; ++q2)
; #pragma unroll
;                 for (int sx = 0; sx < 4; ++sx) { const bf16x8 B = {lo[q2][sx][0], lo[q2][sx][1], lo[q2][sx][2], lo[q2][sx][3], hi[q2][sx][0], hi[q2][sx][1], hi[q2][sx][2], hi[q2][sx][3]};
;                   o[n2 * 2 + q2] = __builtin_amdgcn_mfma_f32_16x16x32_bf16(pf[sx], B, o[n2 * 2 + q2], 0, 0, 0); }
;               SBAR(); } }
	v_mov_b32_e32 v80, v136
	v_mov_b32_e32 v81, v137
	v_mov_b32_e32 v136, v134
	v_mov_b32_e32 v137, v135
	v_mfma_f32_16x16x32_bf16 v[28:31], v[72:75], v[78:81], v[28:31]
	s_nop 0
	v_mfma_f32_16x16x32_bf16 v[0:3], v[72:75], v[136:139], v[0:3]
	ds_read2st64_b64 v[56:59], v153 offset0:80 offset1:88
	ds_read2st64_b64 v[76:79], v154 offset0:80 offset1:88
	ds_read2st64_b64 v[80:83], v155 offset0:80 offset1:88
	ds_read2st64_b64 v[88:91], v156 offset0:80 offset1:88
	ds_read2st64_b64 v[92:95], v157 offset0:80 offset1:88
	ds_read2st64_b64 v[96:99], v158 offset0:80 offset1:88
	ds_read2st64_b64 v[100:103], v159 offset0:80 offset1:88
	ds_read2st64_b64 v[116:119], v160 offset0:80 offset1:88
	v_pk_mul_f32 v[54:55], v[112:113], v[54:55]
	v_pk_mul_f32 v[52:53], v[108:109], v[52:53]
	v_pk_mul_f32 v[50:51], v[112:113], v[50:51]
	v_pk_mul_f32 v[48:49], v[108:109], v[48:49]
	s_waitcnt lgkmcnt(7)
	v_mov_b32_e32 v120, v56
	v_mov_b32_e32 v121, v57
	s_waitcnt lgkmcnt(6)
	v_mov_b32_e32 v122, v76
	v_mov_b32_e32 v123, v77
	v_pk_fma_f32 v[6:7], v[110:111], v[6:7], v[54:55]
	v_pk_fma_f32 v[4:5], v[106:107], v[4:5], v[52:53]
	v_mov_b32_e32 v76, v58
	v_mov_b32_e32 v77, v59
	v_pk_fma_f32 v[10:11], v[110:111], v[10:11], v[50:51]
	v_pk_fma_f32 v[8:9], v[106:107], v[8:9], v[48:49]
	v_mfma_f32_16x16x32_bf16 v[4:7], v[64:67], v[120:123], v[4:7]
	s_waitcnt lgkmcnt(5)
	v_mov_b32_e32 v52, v80
	v_mov_b32_e32 v53, v81
	s_waitcnt lgkmcnt(4)
	v_mov_b32_e32 v54, v88
	v_mfma_f32_16x16x32_bf16 v[8:11], v[64:67], v[76:79], v[8:11]
	v_mov_b32_e32 v55, v89
	v_mov_b32_e32 v88, v82
	v_mov_b32_e32 v89, v83
	v_mfma_f32_16x16x32_bf16 v[4:7], v[60:63], v[52:55], v[4:7]
	s_waitcnt lgkmcnt(3)
	v_mov_b32_e32 v52, v92
	v_mov_b32_e32 v53, v93
	s_waitcnt lgkmcnt(2)
	v_mov_b32_e32 v54, v96
	v_mfma_f32_16x16x32_bf16 v[8:11], v[60:63], v[88:91], v[8:11]
	v_mov_b32_e32 v55, v97
	v_mov_b32_e32 v96, v94
	v_mov_b32_e32 v97, v95
	v_mfma_f32_16x16x32_bf16 v[4:7], v[68:71], v[52:55], v[4:7]
	s_waitcnt lgkmcnt(1)
	v_mov_b32_e32 v52, v100
	v_mov_b32_e32 v53, v101
	s_waitcnt lgkmcnt(0)
	v_mov_b32_e32 v54, v116
	v_mfma_f32_16x16x32_bf16 v[8:11], v[68:71], v[96:99], v[8:11]
	v_mov_b32_e32 v55, v117
	v_mov_b32_e32 v116, v102
	v_mov_b32_e32 v117, v103
	v_mfma_f32_16x16x32_bf16 v[4:7], v[72:75], v[52:55], v[4:7]
	s_nop 0
	v_mfma_f32_16x16x32_bf16 v[8:11], v[72:75], v[116:119], v[8:11]
	ds_read2st64_b64 v[48:51], v153 offset0:96 offset1:104
	ds_read2st64_b64 v[52:55], v154 offset0:96 offset1:104
	ds_read2st64_b64 v[56:59], v155 offset0:96 offset1:104
	ds_read2st64_b64 v[76:79], v156 offset0:96 offset1:104
	ds_read2st64_b64 v[80:83], v157 offset0:96 offset1:104
	ds_read2st64_b64 v[88:91], v158 offset0:96 offset1:104
	ds_read2st64_b64 v[92:95], v159 offset0:96 offset1:104
	ds_read2st64_b64 v[96:99], v160 offset0:96 offset1:104
	v_pk_mul_f32 v[46:47], v[112:113], v[46:47]
	v_pk_mul_f32 v[44:45], v[108:109], v[44:45]
	v_pk_mul_f32 v[42:43], v[112:113], v[42:43]
	v_pk_mul_f32 v[40:41], v[108:109], v[40:41]
	s_waitcnt lgkmcnt(7)
	v_mov_b32_e32 v100, v48
	v_mov_b32_e32 v101, v49
	s_waitcnt lgkmcnt(6)
	v_mov_b32_e32 v102, v52
	v_mov_b32_e32 v103, v53
	v_pk_fma_f32 v[14:15], v[110:111], v[14:15], v[46:47]
	v_pk_fma_f32 v[12:13], v[106:107], v[12:13], v[44:45]
	v_mov_b32_e32 v52, v50
	v_mov_b32_e32 v53, v51
	v_pk_fma_f32 v[18:19], v[110:111], v[18:19], v[42:43]
	v_pk_fma_f32 v[16:17], v[106:107], v[16:17], v[40:41]
	v_mfma_f32_16x16x32_bf16 v[12:15], v[64:67], v[100:103], v[12:15]
	s_waitcnt lgkmcnt(5)
	v_mov_b32_e32 v44, v56
	v_mov_b32_e32 v45, v57
	s_waitcnt lgkmcnt(4)
	v_mov_b32_e32 v46, v76
	v_mfma_f32_16x16x32_bf16 v[16:19], v[64:67], v[52:55], v[16:19]
	v_mov_b32_e32 v47, v77
	v_mov_b32_e32 v76, v58
	v_mov_b32_e32 v77, v59
	v_mfma_f32_16x16x32_bf16 v[12:15], v[60:63], v[44:47], v[12:15]
	s_waitcnt lgkmcnt(3)
	v_mov_b32_e32 v44, v80
	v_mov_b32_e32 v45, v81
	s_waitcnt lgkmcnt(2)
	v_mov_b32_e32 v46, v88
	v_mfma_f32_16x16x32_bf16 v[16:19], v[60:63], v[76:79], v[16:19]
	v_mov_b32_e32 v47, v89
	v_mov_b32_e32 v88, v82
	v_mov_b32_e32 v89, v83
	v_mfma_f32_16x16x32_bf16 v[12:15], v[68:71], v[44:47], v[12:15]
	s_waitcnt lgkmcnt(1)
	v_mov_b32_e32 v44, v92
	v_mov_b32_e32 v45, v93
	s_waitcnt lgkmcnt(0)
	v_mov_b32_e32 v46, v96
	v_mfma_f32_16x16x32_bf16 v[16:19], v[68:71], v[88:91], v[16:19]
	v_mov_b32_e32 v47, v97
	v_mov_b32_e32 v96, v94
	v_mov_b32_e32 v97, v95
	v_mfma_f32_16x16x32_bf16 v[12:15], v[72:75], v[44:47], v[12:15]
	s_nop 0
	v_mfma_f32_16x16x32_bf16 v[16:19], v[72:75], v[96:99], v[16:19]
	ds_read2st64_b64 v[40:43], v153 offset0:112 offset1:120
	ds_read2st64_b64 v[44:47], v154 offset0:112 offset1:120
	ds_read2st64_b64 v[48:51], v155 offset0:112 offset1:120
	ds_read2st64_b64 v[52:55], v156 offset0:112 offset1:120
	ds_read2st64_b64 v[56:59], v157 offset0:112 offset1:120
	ds_read2st64_b64 v[76:79], v158 offset0:112 offset1:120
	ds_read2st64_b64 v[80:83], v159 offset0:112 offset1:120
	ds_read2st64_b64 v[88:91], v160 offset0:112 offset1:120
	v_pk_mul_f32 v[38:39], v[112:113], v[38:39]
	v_pk_mul_f32 v[36:37], v[108:109], v[36:37]
	v_pk_mul_f32 v[34:35], v[112:113], v[34:35]
	v_pk_mul_f32 v[32:33], v[108:109], v[32:33]
	s_waitcnt lgkmcnt(7)
	v_mov_b32_e32 v92, v40
	v_mov_b32_e32 v93, v41
	s_waitcnt lgkmcnt(6)
	v_mov_b32_e32 v94, v44
	v_mov_b32_e32 v95, v45
	v_pk_fma_f32 v[22:23], v[110:111], v[22:23], v[38:39]
	v_pk_fma_f32 v[20:21], v[106:107], v[20:21], v[36:37]
	v_mov_b32_e32 v44, v42
	v_mov_b32_e32 v45, v43
	v_pk_fma_f32 v[26:27], v[110:111], v[26:27], v[34:35]
	v_pk_fma_f32 v[24:25], v[106:107], v[24:25], v[32:33]
	v_mfma_f32_16x16x32_bf16 v[20:23], v[64:67], v[92:95], v[20:23]
	s_waitcnt lgkmcnt(5)
; DEVFI float bf2f(bfraw h) { return __uint_as_float(((unsigned)h) << 16); }
; DEVFI bfraw f2bf(float x) { unsigned u = __float_as_uint(x); u += 0x7fffu + ((u >> 16) & 1u); return (bfraw)(u >> 16); }
; #define RG ((bfraw*)(kargs()->ws + O_RG))
; #define RO ((bfraw*)(kargs()->ws + O_RO))
; __global__ void __launch_bounds__(512) mega(Params p) {
;     ...
;           float gw[8];
; #pragma unroll
;           for (int ne = 0; ne < 8; ++ne) gw[ne] = gn_w[head * 128 + ne * 16 + fr];
; #pragma unroll
;           for (int j = 0; j < 4; ++j) { float s1 = 0;
; #pragma unroll
;             for (int ne = 0; ne < 8; ++ne) s1 += o[ne][j];
;             const float mean = red16(s1) * (1.f / 128.f); float s2 = 0;
; #pragma unroll
;             for (int ne = 0; ne < 8; ++ne) { const float dd = o[ne][j] - mean; s2 += dd * dd; }
;             const float rstd = 1.f / sqrtf(red16(s2) * (1.f / 128.f) + LN_EPS);
;             const long tok = tok0 + w * 16 + fq * 4 + j;
;             const bfraw* gp = RG + tok * 1024 + head * 128 + fr; bfraw* op = RO + tok * 1024 + head * 128 + fr;
; #pragma unroll
;             for (int ne = 0; ne < 8; ++ne) op[ne * 16] = f2bf((o[ne][j] - mean) * rstd * gw[ne] * bf2f(gp[ne * 16])); }
	v_mov_b32_e32 v36, v48
	v_mov_b32_e32 v37, v49
	s_waitcnt lgkmcnt(4)
	v_mov_b32_e32 v38, v52
	v_mfma_f32_16x16x32_bf16 v[24:27], v[64:67], v[44:47], v[24:27]
	v_mov_b32_e32 v39, v53
	v_mov_b32_e32 v52, v50
	v_mov_b32_e32 v53, v51
	v_mfma_f32_16x16x32_bf16 v[20:23], v[60:63], v[36:39], v[20:23]
	s_waitcnt lgkmcnt(3)
	v_mov_b32_e32 v36, v56
	v_mov_b32_e32 v37, v57
	s_waitcnt lgkmcnt(2)
	v_mov_b32_e32 v38, v76
	v_mfma_f32_16x16x32_bf16 v[24:27], v[60:63], v[52:55], v[24:27]
	v_mov_b32_e32 v39, v77
	v_mov_b32_e32 v76, v58
	v_mov_b32_e32 v77, v59
	v_mfma_f32_16x16x32_bf16 v[20:23], v[68:71], v[36:39], v[20:23]
	s_waitcnt lgkmcnt(1)
	v_mov_b32_e32 v36, v80
	v_mov_b32_e32 v37, v81
	s_waitcnt lgkmcnt(0)
	v_mov_b32_e32 v38, v88
	v_mfma_f32_16x16x32_bf16 v[24:27], v[68:71], v[76:79], v[24:27]
	v_mov_b32_e32 v39, v89
	v_mov_b32_e32 v88, v82
	v_mov_b32_e32 v89, v83
	v_mfma_f32_16x16x32_bf16 v[20:23], v[72:75], v[36:39], v[20:23]
	s_nop 0
	v_mfma_f32_16x16x32_bf16 v[24:27], v[72:75], v[88:91], v[24:27]
	s_mov_b64 s[2:3], s[0:1]
	s_load_dwordx2 s[4:5], s[2:3], 0x50
	s_lshl_b64 s[2:3], s[54:55], 2
	v_lshlrev_b32_e32 v32, 2, v115
	v_lshl_or_b32 v32, s17, 9, v32
	v_or_b32_e32 v104, s7, v104
	s_waitcnt lgkmcnt(0)
	s_add_u32 s4, s4, s2
	s_addc_u32 s5, s5, s3
	global_load_dword v43, v32, s[4:5]
	s_mov_b64 s[4:5], s[0:1]
	s_load_dwordx2 s[4:5], s[4:5], 0x50
	v_lshlrev_b32_e32 v176, 1, v115
	s_waitcnt lgkmcnt(0)
	s_add_u32 s4, s4, s2
	s_addc_u32 s5, s5, s3
	global_load_dword v36, v32, s[4:5] offset:64
	s_mov_b64 s[4:5], s[0:1]
	s_load_dwordx2 s[4:5], s[4:5], 0x50
	s_waitcnt lgkmcnt(0)
	s_add_u32 s4, s4, s2
	s_addc_u32 s5, s5, s3
	global_load_dword v37, v32, s[4:5] offset:128
	s_mov_b64 s[4:5], s[0:1]
	s_load_dwordx2 s[4:5], s[4:5], 0x50
	s_waitcnt lgkmcnt(0)
	s_add_u32 s4, s4, s2
	s_addc_u32 s5, s5, s3
	global_load_dword v38, v32, s[4:5] offset:192
	s_mov_b64 s[4:5], s[0:1]
	s_load_dwordx2 s[4:5], s[4:5], 0x50
	s_waitcnt lgkmcnt(0)
	s_add_u32 s4, s4, s2
	s_addc_u32 s5, s5, s3
	global_load_dword v39, v32, s[4:5] offset:256
	s_mov_b64 s[4:5], s[0:1]
	s_load_dwordx2 s[4:5], s[4:5], 0x50
	s_waitcnt lgkmcnt(0)
	s_add_u32 s4, s4, s2
	s_addc_u32 s5, s5, s3
	global_load_dword v41, v32, s[4:5] offset:320
	s_mov_b64 s[4:5], s[0:1]
	s_load_dwordx2 s[4:5], s[4:5], 0x50
	s_waitcnt lgkmcnt(0)
	s_add_u32 s4, s4, s2
	s_addc_u32 s5, s5, s3
	global_load_dword v40, v32, s[4:5] offset:384
	s_mov_b64 s[4:5], s[0:1]
	s_load_dwordx2 s[4:5], s[4:5], 0x50
	s_waitcnt lgkmcnt(0)
	s_add_u32 s2, s4, s2
	s_addc_u32 s3, s5, s3
	global_load_dword v42, v32, s[2:3] offset:448
	v_add_f32_e32 v32, 0, v28
	v_add_f32_e32 v32, v32, v0
	v_add_f32_e32 v32, v32, v4
	v_add_f32_e32 v32, v32, v8
	s_mov_b32 s2, -1
	v_add_f32_e32 v32, v32, v12
	v_add_f32_e32 v32, v32, v16
	v_mbcnt_lo_u32_b32 v33, s2, 0
	v_mbcnt_hi_u32_b32 v33, s2, v33
	v_add_f32_e32 v32, v32, v20
	v_lshlrev_b32_e32 v33, 2, v33
	v_add_f32_e32 v32, v32, v24
	v_xor_b32_e32 v34, 4, v33
	ds_bpermute_b32 v34, v34, v32
	s_mov_b32 s2, -1
	s_add_i32 s16, s16, s28
	s_add_u32 s8, s8, s72
	s_waitcnt lgkmcnt(0)
	v_add_f32_e32 v32, v32, v34
	v_xor_b32_e32 v34, 8, v33
	ds_bpermute_b32 v34, v34, v32
	s_addc_u32 s9, s9, s73
	s_add_i32 s6, s6, s59
	s_cmpk_gt_i32 s16, 0x3ff
	s_waitcnt lgkmcnt(0)
	v_add_f32_e32 v32, v32, v34
	v_xor_b32_e32 v34, 16, v33
	ds_bpermute_b32 v34, v34, v32
	v_xor_b32_e32 v33, 32, v33
	s_waitcnt lgkmcnt(0)
	v_add_f32_e32 v32, v32, v34
	ds_bpermute_b32 v33, v33, v32
	s_waitcnt lgkmcnt(0)
	v_add_f32_e32 v32, v32, v33
	v_fmamk_f32 v45, v32, 0xbc000000, v0
	v_fmamk_f32 v50, v32, 0xbc000000, v28
	v_mul_f32_e32 v33, v45, v45
	v_fmac_f32_e32 v33, v50, v50
	v_fmamk_f32 v44, v32, 0xbc000000, v4
	v_fmac_f32_e32 v33, v44, v44
	v_fmamk_f32 v28, v32, 0xbc000000, v8
	v_fmac_f32_e32 v33, v28, v28
	v_fmamk_f32 v12, v32, 0xbc000000, v12
	v_fmac_f32_e32 v33, v12, v12
	v_fmamk_f32 v8, v32, 0xbc000000, v16
	v_mbcnt_lo_u32_b32 v16, s2, 0
	v_fmac_f32_e32 v33, v8, v8
	v_fmamk_f32 v4, v32, 0xbc000000, v20
	v_mbcnt_hi_u32_b32 v16, s2, v16
	v_fmac_f32_e32 v33, v4, v4
	v_fmamk_f32 v0, v32, 0xbc000000, v24
	v_lshlrev_b32_e32 v16, 2, v16
	v_fmac_f32_e32 v33, v0, v0
	v_xor_b32_e32 v20, 4, v16
	ds_bpermute_b32 v20, v20, v33
	v_xor_b32_e32 v24, 8, v16
	s_waitcnt lgkmcnt(0)
	v_add_f32_e32 v20, v33, v20
	ds_bpermute_b32 v24, v24, v20
	s_waitcnt lgkmcnt(0)
	v_add_f32_e32 v20, v20, v24
	v_xor_b32_e32 v24, 16, v16
	ds_bpermute_b32 v24, v24, v20
	v_xor_b32_e32 v16, 32, v16
	s_waitcnt lgkmcnt(0)
	v_add_f32_e32 v20, v20, v24
	ds_bpermute_b32 v16, v16, v20
	s_waitcnt lgkmcnt(0)
	v_add_f32_e32 v16, v20, v16
	v_fmamk_f32 v16, v16, 0x3c000000, v183
	v_cmp_gt_f32_e32 vcc, s30, v16
	v_mul_f32_e32 v20, 0x4f800000, v16
	s_nop 0
	v_cndmask_b32_e32 v16, v16, v20, vcc
	v_sqrt_f32_e32 v20, v16
	s_nop 0
	v_add_u32_e32 v24, -1, v20
	v_fma_f32 v32, -v24, v20, v16
	v_cmp_ge_f32_e64 s[4:5], 0, v32
	v_add_u32_e32 v32, 1, v20
	s_nop 0
	v_cndmask_b32_e64 v24, v20, v24, s[4:5]
	v_fma_f32 v20, -v32, v20, v16
	v_cmp_lt_f32_e64 s[4:5], 0, v20
	s_nop 1
	v_cndmask_b32_e64 v20, v24, v32, s[4:5]
	v_mul_f32_e32 v24, 0x37800000, v20
	v_cndmask_b32_e32 v20, v20, v24, vcc
	v_cmp_class_f32_e32 vcc, v16, v222
	s_nop 1
	v_cndmask_b32_e32 v16, v20, v16, vcc
	s_mov_b64 s[2:3], s[0:1]
	s_load_dwordx2 s[2:3], s[2:3], 0xe8
	v_lshlrev_b64 v[34:35], 11, v[104:105]
	v_rcp_f32_e32 v24, v16
	s_nop 0
	v_fma_f32 v20, -v16, v24, 1.0
	v_fma_f32 v20, v20, v24, v24
	s_waitcnt lgkmcnt(0)
	v_lshl_add_u64 v[32:33], s[2:3], 0, v[34:35]
	v_lshl_add_u64 v[32:33], v[32:33], 0, s[12:13]
	v_lshl_add_u64 v[46:47], v[32:33], 0, v[176:177]
	v_lshl_add_u64 v[32:33], v[46:47], 0, s[42:43]
	v_add_co_u32_e32 v46, vcc, s68, v46
	s_mov_b64 s[2:3], s[0:1]
	s_nop 0
	v_addc_co_u32_e32 v47, vcc, 0, v47, vcc
	global_load_ushort v24, v[46:47], off
	s_load_dwordx2 s[2:3], s[2:3], 0xe8
	v_div_fixup_f32 v16, v20, v16, 1.0
	v_mul_f32_e32 v20, v16, v50
	s_waitcnt vmcnt(8)
; DEVFI float bf2f(bfraw h) { return __uint_as_float(((unsigned)h) << 16); }
; DEVFI bfraw f2bf(float x) { unsigned u = __float_as_uint(x); u += 0x7fffu + ((u >> 16) & 1u); return (bfraw)(u >> 16); }
; #define RG ((bfraw*)(kargs()->ws + O_RG))
; #define RO ((bfraw*)(kargs()->ws + O_RO))
; __global__ void __launch_bounds__(512) mega(Params p) {
;     ...
;           for (int j = 0; j < 4; ++j) { float s1 = 0;
; #pragma unroll
;             for (int ne = 0; ne < 8; ++ne) s1 += o[ne][j];
;             const float mean = red16(s1) * (1.f / 128.f); float s2 = 0;
; #pragma unroll
;             for (int ne = 0; ne < 8; ++ne) { const float dd = o[ne][j] - mean; s2 += dd * dd; }
;             const float rstd = 1.f / sqrtf(red16(s2) * (1.f / 128.f) + LN_EPS);
;             const long tok = tok0 + w * 16 + fq * 4 + j;
;             const bfraw* gp = RG + tok * 1024 + head * 128 + fr; bfraw* op = RO + tok * 1024 + head * 128 + fr;
; #pragma unroll
;             for (int ne = 0; ne < 8; ++ne) op[ne * 16] = f2bf((o[ne][j] - mean) * rstd * gw[ne] * bf2f(gp[ne * 16])); }
	v_mul_f32_e32 v20, v20, v43
	v_mul_f32_e32 v12, v16, v12
	s_waitcnt lgkmcnt(0)
	v_lshl_add_u64 v[34:35], s[2:3], 0, v[34:35]
	v_lshl_add_u64 v[34:35], v[34:35], 0, s[12:13]
	v_lshl_add_u64 v[48:49], v[34:35], 0, v[176:177]
	v_add_co_u32_e32 v46, vcc, s69, v48
	v_lshl_add_u64 v[34:35], v[48:49], 0, s[50:51]
	s_nop 0
	v_addc_co_u32_e32 v47, vcc, 0, v49, vcc
	s_waitcnt vmcnt(4)
	v_mul_f32_e32 v12, v12, v39
	v_mul_f32_e32 v8, v16, v8
	s_waitcnt vmcnt(3)
	v_mul_f32_e32 v8, v8, v41
	v_mul_f32_e32 v4, v16, v4
	s_waitcnt vmcnt(2)
	v_mul_f32_e32 v4, v4, v40
	v_mul_f32_e32 v0, v16, v0
	s_waitcnt vmcnt(1)
	v_mul_f32_e32 v0, v0, v42
	s_mov_b32 s2, -1
	v_or_b32_e32 v104, s7, v86
	s_waitcnt vmcnt(0)
	v_lshlrev_b32_e32 v24, 16, v24
	v_mul_f32_e32 v20, v20, v24
	v_bfe_u32 v24, v20, 16, 1
	v_add3_u32 v20, v20, v24, s82
	global_store_short_d16_hi v[46:47], v20, off
	global_load_ushort v24, v[32:33], off offset:32
	v_mul_f32_e32 v20, v16, v45
	v_mul_f32_e32 v20, v20, v36
	s_waitcnt vmcnt(0)
	v_lshlrev_b32_e32 v24, 16, v24
	v_mul_f32_e32 v20, v20, v24
	v_bfe_u32 v24, v20, 16, 1
	v_add3_u32 v20, v20, v24, s82
	global_store_short_d16_hi v[34:35], v20, off offset:32
	global_load_ushort v24, v[32:33], off offset:64
	v_mul_f32_e32 v20, v16, v44
	v_mul_f32_e32 v20, v20, v37
	s_waitcnt vmcnt(0)
	v_lshlrev_b32_e32 v24, 16, v24
	v_mul_f32_e32 v20, v20, v24
	v_bfe_u32 v24, v20, 16, 1
	v_add3_u32 v20, v20, v24, s82
	global_store_short_d16_hi v[34:35], v20, off offset:64
	global_load_ushort v24, v[32:33], off offset:96
	v_mul_f32_e32 v20, v16, v28
	v_mul_f32_e32 v20, v20, v38
	s_waitcnt vmcnt(0)
	v_lshlrev_b32_e32 v24, 16, v24
	v_mul_f32_e32 v20, v20, v24
	v_bfe_u32 v24, v20, 16, 1
	v_add3_u32 v20, v20, v24, s82
	global_store_short_d16_hi v[34:35], v20, off offset:96
	global_load_ushort v20, v[32:33], off offset:128
	s_waitcnt vmcnt(0)
	v_lshlrev_b32_e32 v20, 16, v20
	v_mul_f32_e32 v12, v12, v20
	v_bfe_u32 v20, v12, 16, 1
	v_add3_u32 v12, v12, v20, s82
	global_store_short_d16_hi v[34:35], v12, off offset:128
	global_load_ushort v12, v[32:33], off offset:160
	s_waitcnt vmcnt(0)
	v_lshlrev_b32_e32 v12, 16, v12
	v_mul_f32_e32 v8, v8, v12
	v_bfe_u32 v12, v8, 16, 1
	v_add3_u32 v8, v8, v12, s82
	global_store_short_d16_hi v[34:35], v8, off offset:160
	global_load_ushort v8, v[32:33], off offset:192
	s_waitcnt vmcnt(0)
	v_lshlrev_b32_e32 v8, 16, v8
	v_mul_f32_e32 v4, v4, v8
	v_bfe_u32 v8, v4, 16, 1
	v_add3_u32 v4, v4, v8, s82
	global_store_short_d16_hi v[34:35], v4, off offset:192
	global_load_ushort v4, v[32:33], off offset:224
	s_waitcnt vmcnt(0)
	v_lshlrev_b32_e32 v4, 16, v4
	v_mul_f32_e32 v0, v0, v4
	v_bfe_u32 v4, v0, 16, 1
	v_add3_u32 v0, v0, v4, s82
	global_store_short_d16_hi v[34:35], v0, off offset:224
	v_add_f32_e32 v0, 0, v29
	v_add_f32_e32 v0, v0, v1
	v_add_f32_e32 v0, v0, v5
	v_add_f32_e32 v0, v0, v9
	v_add_f32_e32 v0, v0, v13
	v_add_f32_e32 v0, v0, v17
	v_mbcnt_lo_u32_b32 v4, s2, 0
	v_mbcnt_hi_u32_b32 v4, s2, v4
	v_add_f32_e32 v0, v0, v21
	v_lshlrev_b32_e32 v4, 2, v4
	v_add_f32_e32 v0, v0, v25
	v_xor_b32_e32 v8, 4, v4
	ds_bpermute_b32 v8, v8, v0
	s_mov_b32 s2, -1
	s_waitcnt lgkmcnt(0)
	v_add_f32_e32 v0, v0, v8
	v_xor_b32_e32 v8, 8, v4
	ds_bpermute_b32 v8, v8, v0
	s_waitcnt lgkmcnt(0)
	v_add_f32_e32 v0, v0, v8
	v_xor_b32_e32 v8, 16, v4
	ds_bpermute_b32 v8, v8, v0
	v_xor_b32_e32 v4, 32, v4
	s_waitcnt lgkmcnt(0)
	v_add_f32_e32 v0, v0, v8
	ds_bpermute_b32 v4, v4, v0
	s_waitcnt lgkmcnt(0)
	v_add_f32_e32 v0, v0, v4
	v_fmamk_f32 v24, v0, 0xbc000000, v1
	v_fmamk_f32 v34, v0, 0xbc000000, v29
	v_mul_f32_e32 v1, v24, v24
	v_fmac_f32_e32 v1, v34, v34
	v_fmamk_f32 v20, v0, 0xbc000000, v5
	v_fmac_f32_e32 v1, v20, v20
	v_fmamk_f32 v16, v0, 0xbc000000, v9
	v_fmac_f32_e32 v1, v16, v16
	v_fmamk_f32 v13, v0, 0xbc000000, v13
	v_fmac_f32_e32 v1, v13, v13
	v_fmamk_f32 v12, v0, 0xbc000000, v17
	v_fmamk_f32 v9, v0, 0xbc000000, v21
	v_fmamk_f32 v8, v0, 0xbc000000, v25
	v_mbcnt_lo_u32_b32 v0, s2, 0
	v_fmac_f32_e32 v1, v12, v12
	v_mbcnt_hi_u32_b32 v0, s2, v0
	v_fmac_f32_e32 v1, v9, v9
	v_lshlrev_b32_e32 v0, 2, v0
	v_fmac_f32_e32 v1, v8, v8
	v_xor_b32_e32 v4, 4, v0
	ds_bpermute_b32 v4, v4, v1
	s_waitcnt lgkmcnt(0)
	v_add_f32_e32 v1, v1, v4
	v_xor_b32_e32 v4, 8, v0
	ds_bpermute_b32 v4, v4, v1
	s_waitcnt lgkmcnt(0)
	v_add_f32_e32 v1, v1, v4
	v_xor_b32_e32 v4, 16, v0
	ds_bpermute_b32 v4, v4, v1
	v_xor_b32_e32 v0, 32, v0
	s_waitcnt lgkmcnt(0)
	v_add_f32_e32 v1, v1, v4
	ds_bpermute_b32 v0, v0, v1
	s_waitcnt lgkmcnt(0)
	v_add_f32_e32 v0, v1, v0
	v_fmamk_f32 v0, v0, 0x3c000000, v183
	v_cmp_gt_f32_e32 vcc, s30, v0
	v_mul_f32_e32 v1, 0x4f800000, v0
	s_nop 0
	v_cndmask_b32_e32 v0, v0, v1, vcc
	v_sqrt_f32_e32 v1, v0
	s_nop 0
	v_add_u32_e32 v4, -1, v1
	v_fma_f32 v5, -v4, v1, v0
	v_cmp_ge_f32_e64 s[4:5], 0, v5
	v_add_u32_e32 v5, 1, v1
	s_nop 0
	v_cndmask_b32_e64 v4, v1, v4, s[4:5]
	v_fma_f32 v1, -v5, v1, v0
	v_cmp_lt_f32_e64 s[4:5], 0, v1
	s_nop 1
	v_cndmask_b32_e64 v1, v4, v5, s[4:5]
	v_mul_f32_e32 v4, 0x37800000, v1
	v_cndmask_b32_e32 v1, v1, v4, vcc
	v_cmp_class_f32_e32 vcc, v0, v222
	s_nop 1
	v_cndmask_b32_e32 v0, v1, v0, vcc
	s_mov_b64 s[2:3], s[0:1]
	s_load_dwordx2 s[2:3], s[2:3], 0xe8
	v_rcp_f32_e32 v4, v0
	s_nop 0
	v_fma_f32 v1, -v0, v4, 1.0
	v_fma_f32 v1, v1, v4, v4
	v_lshlrev_b64 v[4:5], 11, v[104:105]
	v_div_fixup_f32 v17, v1, v0, 1.0
	s_waitcnt lgkmcnt(0)
	v_lshl_add_u64 v[0:1], s[2:3], 0, v[4:5]
	v_lshl_add_u64 v[0:1], v[0:1], 0, s[12:13]
	v_lshl_add_u64 v[28:29], v[0:1], 0, v[176:177]
	v_lshl_add_u64 v[0:1], v[28:29], 0, s[42:43]
	v_add_co_u32_e32 v28, vcc, s68, v28
	s_mov_b64 s[2:3], s[0:1]
	s_nop 0
	v_addc_co_u32_e32 v29, vcc, 0, v29, vcc
	global_load_ushort v25, v[28:29], off
	s_load_dwordx2 s[2:3], s[2:3], 0xe8
	v_mul_f32_e32 v21, v17, v34
	v_mul_f32_e32 v21, v21, v43
	v_mul_f32_e32 v20, v17, v20
	v_mul_f32_e32 v20, v20, v37
	s_waitcnt lgkmcnt(0)
; DEVFI float bf2f(bfraw h) { return __uint_as_float(((unsigned)h) << 16); }
; DEVFI bfraw f2bf(float x) { unsigned u = __float_as_uint(x); u += 0x7fffu + ((u >> 16) & 1u); return (bfraw)(u >> 16); }
; #define RG ((bfraw*)(kargs()->ws + O_RG))
; #define RO ((bfraw*)(kargs()->ws + O_RO))
; __global__ void __launch_bounds__(512) mega(Params p) {
;     ...
;           for (int j = 0; j < 4; ++j) { float s1 = 0;
; #pragma unroll
;             for (int ne = 0; ne < 8; ++ne) s1 += o[ne][j];
;             const float mean = red16(s1) * (1.f / 128.f); float s2 = 0;
; #pragma unroll
;             for (int ne = 0; ne < 8; ++ne) { const float dd = o[ne][j] - mean; s2 += dd * dd; }
;             const float rstd = 1.f / sqrtf(red16(s2) * (1.f / 128.f) + LN_EPS);
;             const long tok = tok0 + w * 16 + fq * 4 + j;
;             const bfraw* gp = RG + tok * 1024 + head * 128 + fr; bfraw* op = RO + tok * 1024 + head * 128 + fr;
; #pragma unroll
;             for (int ne = 0; ne < 8; ++ne) op[ne * 16] = f2bf((o[ne][j] - mean) * rstd * gw[ne] * bf2f(gp[ne * 16])); }
	v_lshl_add_u64 v[4:5], s[2:3], 0, v[4:5]
	v_lshl_add_u64 v[4:5], v[4:5], 0, s[12:13]
	v_lshl_add_u64 v[32:33], v[4:5], 0, v[176:177]
	v_add_co_u32_e32 v28, vcc, s69, v32
	v_lshl_add_u64 v[4:5], v[32:33], 0, s[50:51]
	s_nop 0
	v_addc_co_u32_e32 v29, vcc, 0, v33, vcc
	v_mul_f32_e32 v16, v17, v16
	v_mul_f32_e32 v16, v16, v38
	v_mul_f32_e32 v13, v17, v13
	v_mul_f32_e32 v13, v13, v39
	v_mul_f32_e32 v12, v17, v12
	v_mul_f32_e32 v12, v12, v41
	v_mul_f32_e32 v9, v17, v9
	v_mul_f32_e32 v9, v9, v40
	v_mul_f32_e32 v8, v17, v8
	v_mul_f32_e32 v8, v8, v42
	s_mov_b32 s2, -1
	v_or_b32_e32 v104, s7, v85
	s_waitcnt vmcnt(0)
	v_lshlrev_b32_e32 v25, 16, v25
	v_mul_f32_e32 v21, v21, v25
	v_bfe_u32 v25, v21, 16, 1
	v_add3_u32 v21, v21, v25, s82
	global_store_short_d16_hi v[28:29], v21, off
	v_mul_f32_e32 v21, v17, v24
	global_load_ushort v24, v[0:1], off offset:32
	v_mul_f32_e32 v21, v21, v36
	s_waitcnt vmcnt(0)
	v_lshlrev_b32_e32 v24, 16, v24
	v_mul_f32_e32 v21, v21, v24
	v_bfe_u32 v24, v21, 16, 1
	v_add3_u32 v21, v21, v24, s82
	global_store_short_d16_hi v[4:5], v21, off offset:32
	global_load_ushort v21, v[0:1], off offset:64
	s_waitcnt vmcnt(0)
	v_lshlrev_b32_e32 v21, 16, v21
	v_mul_f32_e32 v20, v20, v21
	v_bfe_u32 v21, v20, 16, 1
	v_add3_u32 v20, v20, v21, s82
	global_store_short_d16_hi v[4:5], v20, off offset:64
	global_load_ushort v20, v[0:1], off offset:96
	s_waitcnt vmcnt(0)
	v_lshlrev_b32_e32 v20, 16, v20
	v_mul_f32_e32 v16, v16, v20
	v_bfe_u32 v20, v16, 16, 1
	v_add3_u32 v16, v16, v20, s82
	global_store_short_d16_hi v[4:5], v16, off offset:96
	global_load_ushort v16, v[0:1], off offset:128
	s_waitcnt vmcnt(0)
	v_lshlrev_b32_e32 v16, 16, v16
	v_mul_f32_e32 v13, v13, v16
	v_bfe_u32 v16, v13, 16, 1
	v_add3_u32 v13, v13, v16, s82
	global_store_short_d16_hi v[4:5], v13, off offset:128
	global_load_ushort v13, v[0:1], off offset:160
	s_waitcnt vmcnt(0)
	v_lshlrev_b32_e32 v13, 16, v13
	v_mul_f32_e32 v12, v12, v13
	v_bfe_u32 v13, v12, 16, 1
	v_add3_u32 v12, v12, v13, s82
	global_store_short_d16_hi v[4:5], v12, off offset:160
	global_load_ushort v12, v[0:1], off offset:192
	s_waitcnt vmcnt(0)
	v_lshlrev_b32_e32 v12, 16, v12
	v_mul_f32_e32 v9, v9, v12
	v_bfe_u32 v12, v9, 16, 1
	v_add3_u32 v9, v9, v12, s82
	global_store_short_d16_hi v[4:5], v9, off offset:192
	global_load_ushort v0, v[0:1], off offset:224
	s_waitcnt vmcnt(0)
	v_lshlrev_b32_e32 v0, 16, v0
	v_mul_f32_e32 v0, v8, v0
	v_bfe_u32 v1, v0, 16, 1
	v_add3_u32 v0, v0, v1, s82
	global_store_short_d16_hi v[4:5], v0, off offset:224
	v_add_f32_e32 v0, 0, v30
	v_add_f32_e32 v0, v0, v2
	v_add_f32_e32 v0, v0, v6
	v_add_f32_e32 v0, v0, v10
	v_add_f32_e32 v0, v0, v14
	v_add_f32_e32 v0, v0, v18
	v_mbcnt_lo_u32_b32 v1, s2, 0
	v_mbcnt_hi_u32_b32 v1, s2, v1
	v_add_f32_e32 v0, v0, v22
	v_lshlrev_b32_e32 v1, 2, v1
	v_add_f32_e32 v0, v0, v26
	v_xor_b32_e32 v4, 4, v1
	ds_bpermute_b32 v4, v4, v0
	s_mov_b32 s2, -1
	s_waitcnt lgkmcnt(0)
	v_add_f32_e32 v0, v0, v4
	v_xor_b32_e32 v4, 8, v1
	ds_bpermute_b32 v4, v4, v0
	s_waitcnt lgkmcnt(0)
	v_add_f32_e32 v0, v0, v4
	v_xor_b32_e32 v4, 16, v1
	ds_bpermute_b32 v4, v4, v0
	v_xor_b32_e32 v1, 32, v1
	s_waitcnt lgkmcnt(0)
	v_add_f32_e32 v0, v0, v4
	ds_bpermute_b32 v1, v1, v0
	s_waitcnt lgkmcnt(0)
	v_add_f32_e32 v0, v0, v1
	v_fmamk_f32 v13, v0, 0xbc000000, v2
	v_fmamk_f32 v24, v0, 0xbc000000, v30
	v_mul_f32_e32 v1, v13, v13
	v_fmac_f32_e32 v1, v24, v24
	v_fmamk_f32 v12, v0, 0xbc000000, v6
	v_fmac_f32_e32 v1, v12, v12
	v_fmamk_f32 v10, v0, 0xbc000000, v10
	v_fmac_f32_e32 v1, v10, v10
	v_fmamk_f32 v9, v0, 0xbc000000, v14
	v_fmac_f32_e32 v1, v9, v9
	v_fmamk_f32 v8, v0, 0xbc000000, v18
	v_fmamk_f32 v6, v0, 0xbc000000, v22
	v_fmamk_f32 v2, v0, 0xbc000000, v26
	v_mbcnt_lo_u32_b32 v0, s2, 0
	v_fmac_f32_e32 v1, v8, v8
	v_mbcnt_hi_u32_b32 v0, s2, v0
	v_fmac_f32_e32 v1, v6, v6
	v_lshlrev_b32_e32 v0, 2, v0
	v_fmac_f32_e32 v1, v2, v2
	v_xor_b32_e32 v4, 4, v0
	ds_bpermute_b32 v4, v4, v1
	s_waitcnt lgkmcnt(0)
	v_add_f32_e32 v1, v1, v4
	v_xor_b32_e32 v4, 8, v0
	ds_bpermute_b32 v4, v4, v1
	s_waitcnt lgkmcnt(0)
	v_add_f32_e32 v1, v1, v4
	v_xor_b32_e32 v4, 16, v0
	ds_bpermute_b32 v4, v4, v1
	v_xor_b32_e32 v0, 32, v0
	s_waitcnt lgkmcnt(0)
	v_add_f32_e32 v1, v1, v4
	ds_bpermute_b32 v0, v0, v1
	s_waitcnt lgkmcnt(0)
	v_add_f32_e32 v0, v1, v0
	v_fmamk_f32 v0, v0, 0x3c000000, v183
	v_cmp_gt_f32_e32 vcc, s30, v0
	v_mul_f32_e32 v1, 0x4f800000, v0
	s_nop 0
	v_cndmask_b32_e32 v0, v0, v1, vcc
	v_sqrt_f32_e32 v1, v0
	s_nop 0
	v_add_u32_e32 v4, -1, v1
	v_fma_f32 v5, -v4, v1, v0
	v_cmp_ge_f32_e64 s[4:5], 0, v5
	v_add_u32_e32 v5, 1, v1
	s_nop 0
	v_cndmask_b32_e64 v4, v1, v4, s[4:5]
	v_fma_f32 v1, -v5, v1, v0
	v_cmp_lt_f32_e64 s[4:5], 0, v1
	s_nop 1
	v_cndmask_b32_e64 v1, v4, v5, s[4:5]
	v_mul_f32_e32 v4, 0x37800000, v1
	v_cndmask_b32_e32 v1, v1, v4, vcc
	v_cmp_class_f32_e32 vcc, v0, v222
	s_nop 1
	v_cndmask_b32_e32 v0, v1, v0, vcc
	s_mov_b64 s[2:3], s[0:1]
	s_load_dwordx2 s[2:3], s[2:3], 0xe8
	v_rcp_f32_e32 v4, v0
	s_nop 0
	v_fma_f32 v1, -v0, v4, 1.0
	v_fma_f32 v1, v1, v4, v4
	v_lshlrev_b64 v[4:5], 11, v[104:105]
	v_div_fixup_f32 v14, v1, v0, 1.0
	s_waitcnt lgkmcnt(0)
	v_lshl_add_u64 v[0:1], s[2:3], 0, v[4:5]
	v_lshl_add_u64 v[0:1], v[0:1], 0, s[12:13]
	v_lshl_add_u64 v[16:17], v[0:1], 0, v[176:177]
	v_lshl_add_u64 v[0:1], v[16:17], 0, s[42:43]
	v_add_co_u32_e32 v16, vcc, s68, v16
	s_mov_b64 s[2:3], s[0:1]
	s_nop 0
	v_addc_co_u32_e32 v17, vcc, 0, v17, vcc
	global_load_ushort v16, v[16:17], off
	s_load_dwordx2 s[2:3], s[2:3], 0xe8
	v_mul_f32_e32 v18, v14, v24
	v_mul_f32_e32 v18, v18, v43
	v_mul_f32_e32 v13, v14, v13
	v_mul_f32_e32 v13, v13, v36
	s_waitcnt lgkmcnt(0)
; DEVFI float bf2f(bfraw h) { return __uint_as_float(((unsigned)h) << 16); }
; DEVFI bfraw f2bf(float x) { unsigned u = __float_as_uint(x); u += 0x7fffu + ((u >> 16) & 1u); return (bfraw)(u >> 16); }
; #define RG ((bfraw*)(kargs()->ws + O_RG))
; #define RO ((bfraw*)(kargs()->ws + O_RO))
; __global__ void __launch_bounds__(512) mega(Params p) {
;     ...
;           for (int j = 0; j < 4; ++j) { float s1 = 0;
; #pragma unroll
;             for (int ne = 0; ne < 8; ++ne) s1 += o[ne][j];
;             const float mean = red16(s1) * (1.f / 128.f); float s2 = 0;
; #pragma unroll
;             for (int ne = 0; ne < 8; ++ne) { const float dd = o[ne][j] - mean; s2 += dd * dd; }
;             const float rstd = 1.f / sqrtf(red16(s2) * (1.f / 128.f) + LN_EPS);
;             const long tok = tok0 + w * 16 + fq * 4 + j;
;             const bfraw* gp = RG + tok * 1024 + head * 128 + fr; bfraw* op = RO + tok * 1024 + head * 128 + fr;
; #pragma unroll
;             for (int ne = 0; ne < 8; ++ne) op[ne * 16] = f2bf((o[ne][j] - mean) * rstd * gw[ne] * bf2f(gp[ne * 16])); }
	v_lshl_add_u64 v[4:5], s[2:3], 0, v[4:5]
	v_lshl_add_u64 v[4:5], v[4:5], 0, s[12:13]
	v_lshl_add_u64 v[20:21], v[4:5], 0, v[176:177]
	v_lshl_add_u64 v[4:5], v[20:21], 0, s[50:51]
	v_mul_f32_e32 v12, v14, v12
	v_mul_f32_e32 v12, v12, v37
	v_mul_f32_e32 v10, v14, v10
	v_mul_f32_e32 v10, v10, v38
	v_mul_f32_e32 v9, v14, v9
	v_mul_f32_e32 v9, v9, v39
	v_mul_f32_e32 v8, v14, v8
	v_mul_f32_e32 v8, v8, v41
	v_mul_f32_e32 v6, v14, v6
	v_mul_f32_e32 v6, v6, v40
	v_mul_f32_e32 v2, v14, v2
	v_mul_f32_e32 v2, v2, v42
	s_mov_b32 s2, -1
	v_or_b32_e32 v104, s7, v84
	s_waitcnt vmcnt(0)
	v_lshlrev_b32_e32 v16, 16, v16
	v_mul_f32_e32 v16, v18, v16
	v_bfe_u32 v17, v16, 16, 1
	v_add3_u32 v18, v16, v17, s82
	v_add_co_u32_e32 v16, vcc, s69, v20
	s_nop 1
	v_addc_co_u32_e32 v17, vcc, 0, v21, vcc
	global_store_short_d16_hi v[16:17], v18, off
	global_load_ushort v16, v[0:1], off offset:32
	s_waitcnt vmcnt(0)
	v_lshlrev_b32_e32 v16, 16, v16
	v_mul_f32_e32 v13, v13, v16
	v_bfe_u32 v16, v13, 16, 1
	v_add3_u32 v13, v13, v16, s82
	global_store_short_d16_hi v[4:5], v13, off offset:32
	global_load_ushort v13, v[0:1], off offset:64
	s_waitcnt vmcnt(0)
	v_lshlrev_b32_e32 v13, 16, v13
	v_mul_f32_e32 v12, v12, v13
	v_bfe_u32 v13, v12, 16, 1
	v_add3_u32 v12, v12, v13, s82
	global_store_short_d16_hi v[4:5], v12, off offset:64
	global_load_ushort v12, v[0:1], off offset:96
	s_waitcnt vmcnt(0)
	v_lshlrev_b32_e32 v12, 16, v12
	v_mul_f32_e32 v10, v10, v12
	v_bfe_u32 v12, v10, 16, 1
	v_add3_u32 v10, v10, v12, s82
	global_store_short_d16_hi v[4:5], v10, off offset:96
	global_load_ushort v10, v[0:1], off offset:128
	s_waitcnt vmcnt(0)
	v_lshlrev_b32_e32 v10, 16, v10
	v_mul_f32_e32 v9, v9, v10
	v_bfe_u32 v10, v9, 16, 1
	v_add3_u32 v9, v9, v10, s82
	global_store_short_d16_hi v[4:5], v9, off offset:128
	global_load_ushort v9, v[0:1], off offset:160
	s_waitcnt vmcnt(0)
	v_lshlrev_b32_e32 v9, 16, v9
	v_mul_f32_e32 v8, v8, v9
	v_bfe_u32 v9, v8, 16, 1
	v_add3_u32 v8, v8, v9, s82
	global_store_short_d16_hi v[4:5], v8, off offset:160
	global_load_ushort v8, v[0:1], off offset:192
	s_waitcnt vmcnt(0)
	v_lshlrev_b32_e32 v8, 16, v8
	v_mul_f32_e32 v6, v6, v8
	v_bfe_u32 v8, v6, 16, 1
	v_add3_u32 v6, v6, v8, s82
	global_store_short_d16_hi v[4:5], v6, off offset:192
	global_load_ushort v0, v[0:1], off offset:224
	s_waitcnt vmcnt(0)
	v_lshlrev_b32_e32 v0, 16, v0
	v_mul_f32_e32 v0, v2, v0
	v_bfe_u32 v1, v0, 16, 1
	v_add3_u32 v0, v0, v1, s82
	global_store_short_d16_hi v[4:5], v0, off offset:224
	v_add_f32_e32 v0, 0, v31
	v_add_f32_e32 v0, v0, v3
	v_add_f32_e32 v0, v0, v7
	v_add_f32_e32 v0, v0, v11
	v_add_f32_e32 v0, v0, v15
	v_add_f32_e32 v0, v0, v19
	v_mbcnt_lo_u32_b32 v1, s2, 0
	v_mbcnt_hi_u32_b32 v1, s2, v1
	v_add_f32_e32 v0, v0, v23
	v_lshlrev_b32_e32 v1, 2, v1
	v_add_f32_e32 v0, v0, v27
	v_xor_b32_e32 v2, 4, v1
	ds_bpermute_b32 v2, v2, v0
	s_mov_b32 s2, -1
	s_waitcnt lgkmcnt(0)
	v_add_f32_e32 v0, v0, v2
	v_xor_b32_e32 v2, 8, v1
	ds_bpermute_b32 v2, v2, v0
	s_waitcnt lgkmcnt(0)
	v_add_f32_e32 v0, v0, v2
	v_xor_b32_e32 v2, 16, v1
	ds_bpermute_b32 v2, v2, v0
	v_xor_b32_e32 v1, 32, v1
	s_waitcnt lgkmcnt(0)
	v_add_f32_e32 v0, v0, v2
	ds_bpermute_b32 v1, v1, v0
	s_waitcnt lgkmcnt(0)
	v_add_f32_e32 v0, v0, v1
	v_fmac_f32_e32 v3, 0xbc000000, v0
	v_fmac_f32_e32 v31, 0xbc000000, v0
	v_mul_f32_e32 v1, v3, v3
	v_fmac_f32_e32 v1, v31, v31
	v_fmac_f32_e32 v7, 0xbc000000, v0
	v_fmac_f32_e32 v1, v7, v7
	v_fmac_f32_e32 v11, 0xbc000000, v0
	v_fmac_f32_e32 v1, v11, v11
	v_fmac_f32_e32 v15, 0xbc000000, v0
	v_fmac_f32_e32 v1, v15, v15
	v_fmac_f32_e32 v19, 0xbc000000, v0
	v_fmac_f32_e32 v23, 0xbc000000, v0
	v_fmac_f32_e32 v27, 0xbc000000, v0
	v_mbcnt_lo_u32_b32 v0, s2, 0
	v_fmac_f32_e32 v1, v19, v19
	v_mbcnt_hi_u32_b32 v0, s2, v0
	v_fmac_f32_e32 v1, v23, v23
	v_lshlrev_b32_e32 v0, 2, v0
	v_fmac_f32_e32 v1, v27, v27
	v_xor_b32_e32 v2, 4, v0
	ds_bpermute_b32 v2, v2, v1
	s_waitcnt lgkmcnt(0)
	v_add_f32_e32 v1, v1, v2
	v_xor_b32_e32 v2, 8, v0
	ds_bpermute_b32 v2, v2, v1
	s_waitcnt lgkmcnt(0)
; DEVFI float bf2f(bfraw h) { return __uint_as_float(((unsigned)h) << 16); }
; DEVFI bfraw f2bf(float x) { unsigned u = __float_as_uint(x); u += 0x7fffu + ((u >> 16) & 1u); return (bfraw)(u >> 16); }
; #define RG ((bfraw*)(kargs()->ws + O_RG))
; #define RO ((bfraw*)(kargs()->ws + O_RO))
; __global__ void __launch_bounds__(512) mega(Params p) {
;     ...
;           for (int j = 0; j < 4; ++j) { float s1 = 0;
; #pragma unroll
;             for (int ne = 0; ne < 8; ++ne) s1 += o[ne][j];
;             const float mean = red16(s1) * (1.f / 128.f); float s2 = 0;
; #pragma unroll
;             for (int ne = 0; ne < 8; ++ne) { const float dd = o[ne][j] - mean; s2 += dd * dd; }
;             const float rstd = 1.f / sqrtf(red16(s2) * (1.f / 128.f) + LN_EPS);
;             const long tok = tok0 + w * 16 + fq * 4 + j;
;             const bfraw* gp = RG + tok * 1024 + head * 128 + fr; bfraw* op = RO + tok * 1024 + head * 128 + fr;
; #pragma unroll
;             for (int ne = 0; ne < 8; ++ne) op[ne * 16] = f2bf((o[ne][j] - mean) * rstd * gw[ne] * bf2f(gp[ne * 16])); }
;         }
	v_add_f32_e32 v1, v1, v2
	v_xor_b32_e32 v2, 16, v0
	ds_bpermute_b32 v2, v2, v1
	v_xor_b32_e32 v0, 32, v0
	s_waitcnt lgkmcnt(0)
	v_add_f32_e32 v1, v1, v2
	ds_bpermute_b32 v0, v0, v1
	s_waitcnt lgkmcnt(0)
	v_add_f32_e32 v0, v1, v0
	v_fmamk_f32 v0, v0, 0x3c000000, v183
	v_cmp_gt_f32_e32 vcc, s30, v0
	v_mul_f32_e32 v1, 0x4f800000, v0
	s_nop 0
	v_cndmask_b32_e32 v0, v0, v1, vcc
	v_sqrt_f32_e32 v1, v0
	s_nop 0
	v_add_u32_e32 v2, -1, v1
	v_fma_f32 v4, -v2, v1, v0
	v_cmp_ge_f32_e64 s[4:5], 0, v4
	v_add_u32_e32 v4, 1, v1
	s_nop 0
	v_cndmask_b32_e64 v2, v1, v2, s[4:5]
	v_fma_f32 v1, -v4, v1, v0
	v_cmp_lt_f32_e64 s[4:5], 0, v1
	s_nop 1
	v_cndmask_b32_e64 v1, v2, v4, s[4:5]
	v_mul_f32_e32 v2, 0x37800000, v1
	v_cndmask_b32_e32 v1, v1, v2, vcc
	v_cmp_class_f32_e32 vcc, v0, v222
	s_nop 1
	v_cndmask_b32_e32 v0, v1, v0, vcc
	s_mov_b64 s[2:3], s[0:1]
	s_load_dwordx2 s[2:3], s[2:3], 0xe8
	v_rcp_f32_e32 v2, v0
	s_nop 0
	v_fma_f32 v1, -v0, v2, 1.0
	v_fma_f32 v1, v1, v2, v2
	v_lshlrev_b64 v[4:5], 11, v[104:105]
	v_div_fixup_f32 v2, v1, v0, 1.0
	s_waitcnt lgkmcnt(0)
	v_lshl_add_u64 v[0:1], s[2:3], 0, v[4:5]
	v_lshl_add_u64 v[0:1], v[0:1], 0, s[12:13]
	v_lshl_add_u64 v[8:9], v[0:1], 0, v[176:177]
	v_lshl_add_u64 v[0:1], v[8:9], 0, s[42:43]
	v_add_co_u32_e32 v8, vcc, s68, v8
	s_mov_b64 s[2:3], s[0:1]
	s_nop 0
	v_addc_co_u32_e32 v9, vcc, 0, v9, vcc
	global_load_ushort v8, v[8:9], off
	s_load_dwordx2 s[2:3], s[2:3], 0xe8
	v_mul_f32_e32 v6, v2, v31
	v_mul_f32_e32 v6, v6, v43
	v_mul_f32_e32 v3, v2, v3
	v_mul_f32_e32 v3, v3, v36
	s_waitcnt lgkmcnt(0)
	v_lshl_add_u64 v[4:5], s[2:3], 0, v[4:5]
	v_lshl_add_u64 v[4:5], v[4:5], 0, s[12:13]
	v_lshl_add_u64 v[12:13], v[4:5], 0, v[176:177]
	v_lshl_add_u64 v[4:5], v[12:13], 0, s[50:51]
	s_waitcnt vmcnt(0)
	v_lshlrev_b32_e32 v8, 16, v8
	v_mul_f32_e32 v6, v6, v8
	v_bfe_u32 v8, v6, 16, 1
	v_add3_u32 v6, v6, v8, s82
	v_add_co_u32_e32 v8, vcc, s69, v12
	s_nop 1
	v_addc_co_u32_e32 v9, vcc, 0, v13, vcc
	global_store_short_d16_hi v[8:9], v6, off
	global_load_ushort v6, v[0:1], off offset:32
	s_waitcnt vmcnt(0)
	v_lshlrev_b32_e32 v6, 16, v6
	v_mul_f32_e32 v3, v3, v6
	v_bfe_u32 v6, v3, 16, 1
	v_add3_u32 v3, v3, v6, s82
	global_store_short_d16_hi v[4:5], v3, off offset:32
	global_load_ushort v6, v[0:1], off offset:64
	v_mul_f32_e32 v3, v2, v7
	v_mul_f32_e32 v3, v3, v37
	s_waitcnt vmcnt(0)
	v_lshlrev_b32_e32 v6, 16, v6
	v_mul_f32_e32 v3, v3, v6
	v_bfe_u32 v6, v3, 16, 1
	v_add3_u32 v3, v3, v6, s82
	global_store_short_d16_hi v[4:5], v3, off offset:64
	global_load_ushort v6, v[0:1], off offset:96
	v_mul_f32_e32 v3, v2, v11
	v_mul_f32_e32 v3, v3, v38
	s_waitcnt vmcnt(0)
	v_lshlrev_b32_e32 v6, 16, v6
	v_mul_f32_e32 v3, v3, v6
	v_bfe_u32 v6, v3, 16, 1
	v_add3_u32 v3, v3, v6, s82
	global_store_short_d16_hi v[4:5], v3, off offset:96
	global_load_ushort v6, v[0:1], off offset:128
	v_mul_f32_e32 v3, v2, v15
	v_mul_f32_e32 v3, v3, v39
	s_waitcnt vmcnt(0)
	v_lshlrev_b32_e32 v6, 16, v6
	v_mul_f32_e32 v3, v3, v6
	v_bfe_u32 v6, v3, 16, 1
	v_add3_u32 v3, v3, v6, s82
	global_store_short_d16_hi v[4:5], v3, off offset:128
	global_load_ushort v6, v[0:1], off offset:160
	v_mul_f32_e32 v3, v2, v19
	v_mul_f32_e32 v3, v3, v41
	s_waitcnt vmcnt(0)
	v_lshlrev_b32_e32 v6, 16, v6
	v_mul_f32_e32 v3, v3, v6
	v_bfe_u32 v6, v3, 16, 1
	v_add3_u32 v3, v3, v6, s82
	global_store_short_d16_hi v[4:5], v3, off offset:160
	global_load_ushort v6, v[0:1], off offset:192
	v_mul_f32_e32 v3, v2, v23
	v_mul_f32_e32 v3, v3, v40
	v_mul_f32_e32 v2, v2, v27
	v_mul_f32_e32 v2, v2, v42
	s_waitcnt vmcnt(0)
	v_lshlrev_b32_e32 v6, 16, v6
	v_mul_f32_e32 v3, v3, v6
	v_bfe_u32 v6, v3, 16, 1
	v_add3_u32 v3, v3, v6, s82
	global_store_short_d16_hi v[4:5], v3, off offset:192
	global_load_ushort v0, v[0:1], off offset:224
	s_waitcnt vmcnt(0)
	v_lshlrev_b32_e32 v0, 16, v0
	v_mul_f32_e32 v0, v2, v0
	v_bfe_u32 v1, v0, 16, 1
	v_add3_u32 v0, v0, v1, s82
	global_store_short_d16_hi v[4:5], v0, off offset:224
	s_cbranch_scc0 .LBB0_2481

; DEVFI int opaque_tid(const int wv) { return (wv << 6) | lane_opaque(); }
; DEVFI void gbar(unsigned* bar, unsigned& gen, const unsigned nb, const unsigned bid, const int wv) {
;   __syncthreads();
;   gen += 1;
;   if (opaque_tid(wv) == 0) {
.LBB0_2863:
	v_readlane_b32 s2, v255, 14
	s_add_i32 s2, s2, 5
	s_mov_b64 s[4:5], s[0:1]
	s_nop 1
	v_writelane_b32 v255, s2, 14
	s_mov_b32 s2, -1
	s_barrier
	s_nop 0
	v_mbcnt_lo_u32_b32 v0, s2, 0
	v_mbcnt_hi_u32_b32 v0, s2, v0
	v_or_b32_e32 v0, s33, v0
	v_cmp_eq_u32_e32 vcc, 0, v0
	s_and_saveexec_b64 s[2:3], vcc
	s_cbranch_execnz .LBB0_2864
	s_getpc_b64 s[98:99]

; DEVFI void ln_resid4(const float* ysrc, float* ydst, bfraw* fb, float* stats, const float* pw, const float* pb,
;                      const float* w, const float* b, int lane, bool fin) {
;   f32x4 v[4][4];
; #pragma unroll
;   for (int r = 0; r < 4; ++r)
; #pragma unroll
;     for (int i = 0; i < 4; ++i) v[r][i] = __builtin_nontemporal_load((const f32x4*)(ysrc + r * 1024) + i * 64 + lane);
;   u32x2 fv[4][4];
; #pragma unroll
;   for (int r = 0; r < 4; ++r)
; #pragma unroll
;     for (int i = 0; i < 4; ++i) fv[r][i] = __builtin_nontemporal_load((const u32x2*)(fb + r * 1024) + i * 64 + lane);
;   f32x4 pwv[4], pbv[4], ww[4], bb[4];
; #pragma unroll
;   for (int i = 0; i < 4; ++i) { pwv[i] = ((const f32x4*)pw)[i * 64 + lane]; pbv[i] = ((const f32x4*)pb)[i * 64 + lane];
;     ww[i] = ((const f32x4*)w)[i * 64 + lane]; bb[i] = ((const f32x4*)b)[i * 64 + lane]; }
; #pragma unroll
;   for (int r = 0; r < 4; ++r) {
;     const float pmu = stats[r * 2], prs = stats[r * 2 + 1];
;     f32x4 y[4];
; #pragma unroll
;     for (int i = 0; i < 4; ++i) { const unsigned f0 = fv[r][i][0], f1 = fv[r][i][1];
;       const f32x4 f4 = {__uint_as_float(f0 << 16), __uint_as_float(f0 & 0xffff0000u), __uint_as_float(f1 << 16), __uint_as_float(f1 & 0xffff0000u)};
;       y[i] = ALPHA * ((v[r][i] - pmu) * prs * pwv[i] + pbv[i]) + f4; }
;     float s = 0;
; #pragma unroll
;     for (int i = 0; i < 4; ++i) s += y[i][0] + y[i][1] + y[i][2] + y[i][3];
.LBB0_3162:
	v_lshlrev_b32_e32 v176, 4, v130
	v_lshl_add_u64 v[64:65], v[0:1], 0, v[176:177]
	v_lshlrev_b64 v[2:3], 11, v[168:169]
	v_lshl_add_u64 v[156:157], v[168:169], 3, s[18:19]
	global_load_dwordx4 v[112:115], v[64:65], off nt
	global_load_dwordx2 v[178:179], v[156:157], off
	v_lshl_add_u64 v[154:155], s[16:17], 0, v[2:3]
	v_lshlrev_b32_e32 v158, 3, v130
	v_mov_b32_e32 v159, v177
	v_lshl_add_u64 v[172:173], v[154:155], 0, v[158:159]
	global_load_dwordx2 v[180:181], v[172:173], off nt
	global_load_dwordx4 v[40:43], v[132:133], off
	global_load_dwordx4 v[44:47], v[134:135], off
	global_load_dwordx2 v[196:197], v[172:173], off offset:512 nt
	global_load_dwordx4 v[116:119], v[64:65], off offset:1024 nt
	global_load_dwordx4 v[48:51], v[132:133], off offset:1024
	global_load_dwordx4 v[52:55], v[134:135], off offset:1024
	global_load_dwordx4 v[24:27], v[136:137], off
	global_load_dwordx4 v[16:19], v[136:137], off offset:1024
	global_load_dwordx4 v[28:31], v[138:139], off
	global_load_dwordx4 v[20:23], v[138:139], off offset:1024
	global_load_dwordx4 v[56:59], v[132:133], off offset:2048
	global_load_dwordx4 v[32:35], v[132:133], off offset:3072
	global_load_dwordx2 v[198:199], v[172:173], off offset:1024 nt
	global_load_dwordx4 v[60:63], v[134:135], off offset:2048
	global_load_dwordx4 v[36:39], v[134:135], off offset:3072
	global_load_dwordx4 v[8:11], v[136:137], off offset:2048
	global_load_dwordx4 v[0:3], v[136:137], off offset:3072
	global_load_dwordx4 v[120:123], v[64:65], off offset:2048 nt
	global_load_dwordx4 v[12:15], v[138:139], off offset:2048
	global_load_dwordx4 v[4:7], v[138:139], off offset:3072
	global_load_dwordx4 v[124:127], v[64:65], off offset:3072 nt
	global_load_dwordx2 v[200:201], v[172:173], off offset:1536 nt
	v_add_co_u32_e32 v66, vcc, 0x1000, v64
	s_movk_i32 s2, 0x3000
	s_nop 0
	v_addc_co_u32_e32 v67, vcc, 0, v65, vcc
	v_add_co_u32_e32 v68, vcc, s53, v64
	v_add_co_u32_e64 v70, s[6:7], s56, v172
	s_nop 0
	v_addc_co_u32_e32 v69, vcc, 0, v65, vcc
	v_add_co_u32_e32 v64, vcc, s2, v64
	v_addc_co_u32_e64 v71, s[6:7], 0, v173, s[6:7]
	s_nop 0
	v_addc_co_u32_e32 v65, vcc, 0, v65, vcc
	s_mov_b32 s2, -1
	global_load_dwordx2 v[194:195], v[172:173], off offset:2048 nt
	global_load_dwordx2 v[192:193], v[172:173], off offset:2560 nt
	global_load_dwordx2 v[190:191], v[172:173], off offset:3072 nt
	global_load_dwordx2 v[188:189], v[172:173], off offset:3584 nt
	global_load_dwordx4 v[108:111], v[66:67], off nt
	global_load_dwordx4 v[104:107], v[66:67], off offset:1024 nt
	global_load_dwordx4 v[100:103], v[66:67], off offset:2048 nt
	global_load_dwordx4 v[96:99], v[66:67], off offset:3072 nt
	global_load_dwordx2 v[186:187], v[70:71], off nt
	global_load_dwordx2 v[184:185], v[70:71], off offset:512 nt
	global_load_dwordx2 v[174:175], v[70:71], off offset:1024 nt
	global_load_dwordx2 v[170:171], v[70:71], off offset:1536 nt
	global_load_dwordx2 v[166:167], v[70:71], off offset:2048 nt
	global_load_dwordx2 v[164:165], v[70:71], off offset:2560 nt
	global_load_dwordx2 v[162:163], v[70:71], off offset:3072 nt
	global_load_dwordx2 v[160:161], v[70:71], off offset:3584 nt
	global_load_dwordx4 v[88:91], v[68:69], off offset:1024 nt
	global_load_dwordx4 v[84:87], v[68:69], off offset:2048 nt
	global_load_dwordx4 v[80:83], v[68:69], off offset:3072 nt
	global_load_dwordx4 v[92:95], v[64:65], off offset:-4096 nt
	global_load_dwordx4 v[76:79], v[64:65], off nt
	global_load_dwordx4 v[72:75], v[64:65], off offset:1024 nt
	s_nop 0
	global_load_dwordx4 v[68:71], v[64:65], off offset:2048 nt
	s_nop 0
	global_load_dwordx4 v[64:67], v[64:65], off offset:3072 nt
	s_waitcnt vmcnt(46)
	v_lshlrev_b32_e32 v202, 16, v180
	v_and_b32_e32 v203, 0xffff0000, v180
	v_lshlrev_b32_e32 v180, 16, v181
	v_and_b32_e32 v181, 0xffff0000, v181
	v_mbcnt_lo_u32_b32 v141, s2, 0
	v_mbcnt_hi_u32_b32 v141, s2, v141
	v_lshlrev_b32_e32 v141, 2, v141
	v_xor_b32_e32 v143, 0x80, v141
	s_mov_b32 s2, -1
	v_sub_f32_e32 v115, v115, v178
	v_sub_f32_e32 v114, v114, v178
	v_pk_mul_f32 v[114:115], v[178:179], v[114:115] op_sel:[1,0]
	s_waitcnt vmcnt(42)
	v_sub_f32_e32 v117, v117, v178
	v_sub_f32_e32 v116, v116, v178
	v_sub_f32_e32 v113, v113, v178
	v_sub_f32_e32 v112, v112, v178
	v_pk_fma_f32 v[114:115], v[42:43], v[114:115], v[46:47]
	v_pk_mul_f32 v[116:117], v[178:179], v[116:117] op_sel:[1,0]
	s_waitcnt vmcnt(28)
	v_sub_f32_e32 v121, v121, v178
	v_sub_f32_e32 v120, v120, v178
	v_pk_mul_f32 v[112:113], v[178:179], v[112:113] op_sel:[1,0]
	v_pk_fma_f32 v[114:115], v[114:115], s[52:53], v[180:181] op_sel_hi:[1,0,1]
	v_lshlrev_b32_e32 v180, 16, v196
	v_and_b32_e32 v181, 0xffff0000, v196
	v_sub_f32_e32 v119, v119, v178
	v_sub_f32_e32 v118, v118, v178
	v_pk_fma_f32 v[116:117], v[48:49], v[116:117], v[52:53]
	v_pk_mul_f32 v[120:121], v[178:179], v[120:121] op_sel:[1,0]
	s_waitcnt vmcnt(25)
	v_sub_f32_e32 v125, v125, v178
	v_sub_f32_e32 v124, v124, v178
	v_pk_fma_f32 v[112:113], v[40:41], v[112:113], v[44:45]
	v_pk_mul_f32 v[118:119], v[178:179], v[118:119] op_sel:[1,0]
	v_pk_fma_f32 v[116:117], v[116:117], s[52:53], v[180:181] op_sel_hi:[1,0,1]
	v_lshlrev_b32_e32 v180, 16, v198
	v_and_b32_e32 v181, 0xffff0000, v198
	v_pk_fma_f32 v[120:121], v[56:57], v[120:121], v[60:61]
	v_pk_mul_f32 v[124:125], v[178:179], v[124:125] op_sel:[1,0]
	v_pk_fma_f32 v[112:113], v[112:113], s[52:53], v[202:203] op_sel_hi:[1,0,1]
	v_lshlrev_b32_e32 v196, 16, v197
	v_and_b32_e32 v197, 0xffff0000, v197
	v_pk_fma_f32 v[118:119], v[50:51], v[118:119], v[54:55]
	v_sub_f32_e32 v123, v123, v178
	v_sub_f32_e32 v122, v122, v178
	v_pk_fma_f32 v[120:121], v[120:121], s[52:53], v[180:181] op_sel_hi:[1,0,1]
	s_waitcnt vmcnt(24)
; DEVFI void ln_resid4(const float* ysrc, float* ydst, bfraw* fb, float* stats, const float* pw, const float* pb,
;                      const float* w, const float* b, int lane, bool fin) {
;     ...
;     float s = 0;
; #pragma unroll
;     for (int i = 0; i < 4; ++i) s += y[i][0] + y[i][1] + y[i][2] + y[i][3];
;     const float mean = red64(s) * (1.f / 1024.f);
;     float q = 0;
; #pragma unroll
;     for (int i = 0; i < 4; ++i) { const f32x4 d = y[i] - mean; q += d[0] * d[0] + d[1] * d[1] + d[2] * d[2] + d[3] * d[3]; }
;     const float rstd = 1.f / sqrtf(red64(q) * (1.f / 1024.f) + LN_EPS);
;     if (lane == 0) { stats[r * 2] = mean; stats[r * 2 + 1] = rstd; }
	v_lshlrev_b32_e32 v180, 16, v200
	v_and_b32_e32 v181, 0xffff0000, v200
	v_sub_f32_e32 v127, v127, v178
	v_sub_f32_e32 v126, v126, v178
	v_pk_fma_f32 v[124:125], v[32:33], v[124:125], v[36:37]
	v_pk_fma_f32 v[118:119], v[118:119], s[52:53], v[196:197] op_sel_hi:[1,0,1]
	v_pk_mul_f32 v[122:123], v[178:179], v[122:123] op_sel:[1,0]
	v_pk_mul_f32 v[126:127], v[178:179], v[126:127] op_sel:[1,0]
	v_pk_fma_f32 v[124:125], v[124:125], s[52:53], v[180:181] op_sel_hi:[1,0,1]
	v_mov_b32_e32 v178, v116
	v_mov_b32_e32 v179, v112
	v_mov_b32_e32 v180, v117
	v_mov_b32_e32 v181, v113
	v_pk_add_f32 v[178:179], v[178:179], v[180:181]
	v_mov_b32_e32 v180, v118
	v_mov_b32_e32 v181, v114
	v_pk_add_f32 v[178:179], v[180:181], v[178:179]
	v_mov_b32_e32 v180, v119
	v_mov_b32_e32 v181, v115
	v_lshlrev_b32_e32 v196, 16, v199
	v_and_b32_e32 v197, 0xffff0000, v199
	v_pk_fma_f32 v[122:123], v[58:59], v[122:123], v[62:63]
	v_pk_add_f32 v[178:179], v[180:181], v[178:179]
	v_pk_fma_f32 v[122:123], v[122:123], s[52:53], v[196:197] op_sel_hi:[1,0,1]
	v_lshlrev_b32_e32 v196, 16, v201
	v_and_b32_e32 v197, 0xffff0000, v201
	v_pk_fma_f32 v[126:127], v[34:35], v[126:127], v[38:39]
	v_add_f32_e32 v131, 0, v179
	v_pk_fma_f32 v[126:127], v[126:127], s[52:53], v[196:197] op_sel_hi:[1,0,1]
	v_add_f32_e32 v131, v178, v131
	v_mov_b32_e32 v178, v124
	v_mov_b32_e32 v179, v120
	v_mov_b32_e32 v180, v125
	v_mov_b32_e32 v181, v121
	v_pk_add_f32 v[178:179], v[178:179], v[180:181]
	v_mov_b32_e32 v180, v126
	v_mov_b32_e32 v181, v122
	v_pk_add_f32 v[178:179], v[180:181], v[178:179]
	v_mov_b32_e32 v180, v127
	v_mov_b32_e32 v181, v123
	v_pk_add_f32 v[178:179], v[180:181], v[178:179]
	s_nop 0
	v_add_f32_e32 v131, v179, v131
	v_add_f32_e32 v131, v178, v131
	ds_bpermute_b32 v143, v143, v131
	s_waitcnt lgkmcnt(0)
	v_add_f32_e32 v131, v131, v143
	v_xor_b32_e32 v143, 64, v141
	ds_bpermute_b32 v143, v143, v131
	s_waitcnt lgkmcnt(0)
	v_add_f32_e32 v131, v131, v143
	v_xor_b32_e32 v143, 32, v141
	ds_bpermute_b32 v143, v143, v131
	s_waitcnt lgkmcnt(0)
	v_add_f32_e32 v131, v131, v143
	v_xor_b32_e32 v143, 16, v141
	ds_bpermute_b32 v143, v143, v131
	s_waitcnt lgkmcnt(0)
	v_add_f32_e32 v131, v131, v143
	v_xor_b32_e32 v143, 8, v141
	ds_bpermute_b32 v143, v143, v131
	v_xor_b32_e32 v141, 4, v141
	s_waitcnt lgkmcnt(0)
	v_add_f32_e32 v131, v131, v143
	ds_bpermute_b32 v141, v141, v131
	s_waitcnt lgkmcnt(0)
	v_add_f32_e32 v131, v131, v141
	v_fmamk_f32 v211, v131, 0xba800000, v113
	v_fmamk_f32 v207, v131, 0xba800000, v117
	v_fmamk_f32 v210, v131, 0xba800000, v112
	v_mul_f32_e32 v141, v211, v211
	v_fmamk_f32 v206, v131, 0xba800000, v116
	v_mul_f32_e32 v143, v207, v207
	v_fmamk_f32 v208, v131, 0xba800000, v114
	v_fmac_f32_e32 v141, v210, v210
	v_fmamk_f32 v204, v131, 0xba800000, v118
	v_fmac_f32_e32 v143, v206, v206
	v_fmamk_f32 v209, v131, 0xba800000, v115
	v_fmac_f32_e32 v141, v208, v208
	v_fmamk_f32 v205, v131, 0xba800000, v119
	v_fmac_f32_e32 v143, v204, v204
	v_fmac_f32_e32 v141, v209, v209
	v_fmac_f32_e32 v143, v205, v205
	v_fmamk_f32 v203, v131, 0xba800000, v121
	v_add_f32_e32 v141, v141, v143
	v_fmamk_f32 v202, v131, 0xba800000, v120
	v_mul_f32_e32 v143, v203, v203
	v_fmamk_f32 v200, v131, 0xba800000, v122
	v_fmac_f32_e32 v143, v202, v202
	v_fmamk_f32 v201, v131, 0xba800000, v123
	v_fmac_f32_e32 v143, v200, v200
	v_fmac_f32_e32 v143, v201, v201
	v_fmamk_f32 v199, v131, 0xba800000, v125
	v_add_f32_e32 v141, v143, v141
	v_fmamk_f32 v198, v131, 0xba800000, v124
	v_mul_f32_e32 v143, v199, v199
	v_fmamk_f32 v196, v131, 0xba800000, v126
	v_fmac_f32_e32 v143, v198, v198
	v_fmamk_f32 v197, v131, 0xba800000, v127
	v_fmac_f32_e32 v143, v196, v196
	v_fmac_f32_e32 v143, v197, v197
	v_add_f32_e32 v141, v143, v141
	v_mbcnt_lo_u32_b32 v143, s2, 0
	v_mbcnt_hi_u32_b32 v143, s2, v143
	v_lshlrev_b32_e32 v143, 2, v143
	v_xor_b32_e32 v145, 0x80, v143
	ds_bpermute_b32 v145, v145, v141
	s_waitcnt lgkmcnt(0)
	v_add_f32_e32 v141, v141, v145
	v_xor_b32_e32 v145, 64, v143
	ds_bpermute_b32 v145, v145, v141
	s_waitcnt lgkmcnt(0)
	v_add_f32_e32 v141, v141, v145
	v_xor_b32_e32 v145, 32, v143
	ds_bpermute_b32 v145, v145, v141
	s_waitcnt lgkmcnt(0)
	v_add_f32_e32 v141, v141, v145
	v_xor_b32_e32 v145, 16, v143
	ds_bpermute_b32 v145, v145, v141
	s_waitcnt lgkmcnt(0)
	v_add_f32_e32 v141, v141, v145
	v_xor_b32_e32 v145, 8, v143
	ds_bpermute_b32 v145, v145, v141
	v_xor_b32_e32 v143, 4, v143
	s_waitcnt lgkmcnt(0)
	v_add_f32_e32 v141, v141, v145
	ds_bpermute_b32 v143, v143, v141
	s_waitcnt lgkmcnt(0)
	v_add_f32_e32 v141, v141, v143
	v_fmamk_f32 v141, v141, 0x3a800000, v183
	v_mul_f32_e32 v143, 0x4f800000, v141
	v_cmp_gt_f32_e32 vcc, s30, v141
	s_nop 1
	v_cndmask_b32_e32 v141, v141, v143, vcc
	v_sqrt_f32_e32 v143, v141
	s_nop 0
	v_add_u32_e32 v145, -1, v143
	v_fma_f32 v149, -v145, v143, v141
	v_cmp_ge_f32_e64 s[6:7], 0, v149
	v_add_u32_e32 v149, 1, v143
	s_nop 0
	v_cndmask_b32_e64 v145, v143, v145, s[6:7]
	v_fma_f32 v143, -v149, v143, v141
	v_cmp_lt_f32_e64 s[6:7], 0, v143
	s_nop 1
	v_cndmask_b32_e64 v143, v145, v149, s[6:7]
	v_mul_f32_e32 v145, 0x37800000, v143
	v_cndmask_b32_e32 v143, v143, v145, vcc
	v_cmp_class_f32_e32 vcc, v141, v222
	s_nop 1
	v_cndmask_b32_e32 v141, v143, v141, vcc
	s_nop 0
	v_rcp_f32_e32 v145, v141
	s_nop 0
	v_fma_f32 v143, -v141, v145, 1.0
	v_fma_f32 v143, v143, v145, v145
	v_div_fixup_f32 v212, v143, v141, 1.0
	s_and_saveexec_b64 s[2:3], s[4:5]
	s_cbranch_execz .LBB0_3164
	v_mul_f32_e32 v178, 0x3a800000, v131
	v_mov_b32_e32 v179, v212
	global_store_dwordx2 v[156:157], v[178:179], off
; DEVFI void ln_resid4(const float* ysrc, float* ydst, bfraw* fb, float* stats, const float* pw, const float* pb,
;                      const float* w, const float* b, int lane, bool fin) {
;     ...
;   for (int r = 0; r < 4; ++r) {
;     const float pmu = stats[r * 2], prs = stats[r * 2 + 1];
;     f32x4 y[4];
; #pragma unroll
;     for (int i = 0; i < 4; ++i) { const unsigned f0 = fv[r][i][0], f1 = fv[r][i][1];
;       const f32x4 f4 = {__uint_as_float(f0 << 16), __uint_as_float(f0 & 0xffff0000u), __uint_as_float(f1 << 16), __uint_as_float(f1 & 0xffff0000u)};
;       y[i] = ALPHA * ((v[r][i] - pmu) * prs * pwv[i] + pbv[i]) + f4; }
;     float s = 0;
; #pragma unroll
;     for (int i = 0; i < 4; ++i) s += y[i][0] + y[i][1] + y[i][2] + y[i][3];
;     const float mean = red64(s) * (1.f / 1024.f);
;     float q = 0;
; #pragma unroll
;     for (int i = 0; i < 4; ++i) { const f32x4 d = y[i] - mean; q += d[0] * d[0] + d[1] * d[1] + d[2] * d[2] + d[3] * d[3]; }
;     const float rstd = 1.f / sqrtf(red64(q) * (1.f / 1024.f) + LN_EPS);
;     if (lane == 0) { stats[r * 2] = mean; stats[r * 2 + 1] = rstd; }
; #pragma unroll
;     for (int i = 0; i < 4; ++i) { const int c4 = i * 64 + lane;
;       const f32x4 z = (y[i] - mean) * rstd * ww[i] + bb[i];
;       __builtin_nontemporal_store(fin ? z : y[i], (f32x4*)(ydst + r * 1024) + c4);
;       u32x2 pk = {cvtpk(z[0], z[1]), cvtpk(z[2], z[3])}; ((u32x2*)(fb + r * 1024))[c4] = pk; }
.LBB0_3164:
	s_or_b64 exec, exec, s[2:3]
	v_lshlrev_b64 v[168:169], 10, v[168:169]
	v_lshl_add_u64 v[168:169], v[168:169], 2, s[14:15]
	v_pk_mul_f32 v[178:179], v[208:209], v[212:213] op_sel_hi:[1,0]
	v_pk_mul_f32 v[180:181], v[210:211], v[212:213] op_sel_hi:[1,0]
	v_lshl_add_u64 v[208:209], v[168:169], 0, v[176:177]
	v_pk_fma_f32 v[178:179], v[26:27], v[178:179], v[30:31]
	v_pk_fma_f32 v[180:181], v[24:25], v[180:181], v[28:29]
	global_store_dwordx4 v[208:209], v[112:115], off nt
	s_mov_b32 s2, -1
	s_nop 0
	v_cvt_pk_bf16_f32 v112, v180, v181
	v_cvt_pk_bf16_f32 v113, v178, v179
	v_pk_mul_f32 v[114:115], v[206:207], v[212:213] op_sel_hi:[1,0]
	global_store_dwordx2 v[172:173], v[112:113], off
	v_pk_mul_f32 v[112:113], v[204:205], v[212:213] op_sel_hi:[1,0]
	v_pk_fma_f32 v[114:115], v[16:17], v[114:115], v[20:21]
	v_pk_fma_f32 v[112:113], v[18:19], v[112:113], v[22:23]
	global_store_dwordx4 v[208:209], v[116:119], off offset:1024 nt
	v_cvt_pk_bf16_f32 v114, v114, v115
	v_cvt_pk_bf16_f32 v115, v112, v113
	global_store_dwordx2 v[172:173], v[114:115], off offset:512
	v_pk_mul_f32 v[114:115], v[202:203], v[212:213] op_sel_hi:[1,0]
	v_pk_mul_f32 v[112:113], v[200:201], v[212:213] op_sel_hi:[1,0]
	v_pk_fma_f32 v[114:115], v[8:9], v[114:115], v[12:13]
	v_pk_fma_f32 v[112:113], v[10:11], v[112:113], v[14:15]
	global_store_dwordx4 v[208:209], v[120:123], off offset:2048 nt
	v_cvt_pk_bf16_f32 v114, v114, v115
	v_cvt_pk_bf16_f32 v115, v112, v113
	global_store_dwordx2 v[172:173], v[114:115], off offset:1024
	v_pk_mul_f32 v[114:115], v[198:199], v[212:213] op_sel_hi:[1,0]
	v_pk_mul_f32 v[112:113], v[196:197], v[212:213] op_sel_hi:[1,0]
	v_pk_fma_f32 v[114:115], v[0:1], v[114:115], v[4:5]
	v_pk_fma_f32 v[112:113], v[2:3], v[112:113], v[6:7]
	global_store_dwordx4 v[208:209], v[124:127], off offset:3072 nt
	v_cvt_pk_bf16_f32 v114, v114, v115
	v_cvt_pk_bf16_f32 v115, v112, v113
	global_store_dwordx2 v[172:173], v[114:115], off offset:1536
	global_load_dwordx2 v[112:113], v[156:157], off offset:8
	s_waitcnt vmcnt(32)
	v_lshlrev_b32_e32 v114, 16, v194
	v_and_b32_e32 v115, 0xffff0000, v194
	s_waitcnt vmcnt(31)
	v_lshlrev_b32_e32 v118, 16, v192
	v_and_b32_e32 v119, 0xffff0000, v192
	v_lshlrev_b32_e32 v116, 16, v195
	v_and_b32_e32 v117, 0xffff0000, v195
	v_lshlrev_b32_e32 v120, 16, v193
	v_and_b32_e32 v121, 0xffff0000, v193
	s_waitcnt vmcnt(30)
	v_lshlrev_b32_e32 v122, 16, v190
	v_and_b32_e32 v123, 0xffff0000, v190
	s_waitcnt vmcnt(29)
	v_lshlrev_b32_e32 v126, 16, v188
	v_and_b32_e32 v127, 0xffff0000, v188
	v_lshlrev_b32_e32 v124, 16, v191
	v_and_b32_e32 v125, 0xffff0000, v191
	v_lshlrev_b32_e32 v178, 16, v189
	v_and_b32_e32 v179, 0xffff0000, v189
	s_waitcnt vmcnt(0)
	v_sub_f32_e32 v109, v109, v112
	v_sub_f32_e32 v108, v108, v112
	v_sub_f32_e32 v105, v105, v112
	v_sub_f32_e32 v104, v104, v112
	v_sub_f32_e32 v111, v111, v112
	v_sub_f32_e32 v110, v110, v112
	v_sub_f32_e32 v107, v107, v112
	v_sub_f32_e32 v106, v106, v112
	v_pk_mul_f32 v[108:109], v[112:113], v[108:109] op_sel:[1,0]
	v_pk_mul_f32 v[104:105], v[112:113], v[104:105] op_sel:[1,0]
	v_pk_mul_f32 v[110:111], v[112:113], v[110:111] op_sel:[1,0]
	v_pk_mul_f32 v[106:107], v[112:113], v[106:107] op_sel:[1,0]
	v_pk_fma_f32 v[108:109], v[40:41], v[108:109], v[44:45]
	v_pk_fma_f32 v[104:105], v[48:49], v[104:105], v[52:53]
	v_sub_f32_e32 v101, v101, v112
	v_sub_f32_e32 v100, v100, v112
	v_sub_f32_e32 v103, v103, v112
	v_sub_f32_e32 v102, v102, v112
	v_sub_f32_e32 v97, v97, v112
	v_sub_f32_e32 v96, v96, v112
	v_sub_f32_e32 v99, v99, v112
	v_sub_f32_e32 v98, v98, v112
	v_pk_fma_f32 v[110:111], v[42:43], v[110:111], v[46:47]
	v_pk_fma_f32 v[106:107], v[50:51], v[106:107], v[54:55]
	v_pk_fma_f32 v[108:109], v[108:109], s[52:53], v[114:115] op_sel_hi:[1,0,1]
	v_pk_fma_f32 v[104:105], v[104:105], s[52:53], v[118:119] op_sel_hi:[1,0,1]
	v_pk_mul_f32 v[102:103], v[112:113], v[102:103] op_sel:[1,0]
	v_pk_mul_f32 v[100:101], v[112:113], v[100:101] op_sel:[1,0]
	v_pk_mul_f32 v[98:99], v[112:113], v[98:99] op_sel:[1,0]
	v_pk_mul_f32 v[96:97], v[112:113], v[96:97] op_sel:[1,0]
	v_pk_fma_f32 v[110:111], v[110:111], s[52:53], v[116:117] op_sel_hi:[1,0,1]
	v_pk_fma_f32 v[106:107], v[106:107], s[52:53], v[120:121] op_sel_hi:[1,0,1]
	v_mov_b32_e32 v112, v104
	v_mov_b32_e32 v113, v108
	v_mov_b32_e32 v114, v105
	v_mov_b32_e32 v115, v109
	v_pk_add_f32 v[112:113], v[112:113], v[114:115]
	v_mov_b32_e32 v114, v106
	v_mov_b32_e32 v115, v110
	v_pk_add_f32 v[112:113], v[114:115], v[112:113]
	v_mov_b32_e32 v114, v107
	v_mov_b32_e32 v115, v111
	v_pk_fma_f32 v[100:101], v[56:57], v[100:101], v[60:61]
	v_pk_fma_f32 v[96:97], v[32:33], v[96:97], v[36:37]
	v_pk_add_f32 v[112:113], v[114:115], v[112:113]
	v_pk_fma_f32 v[102:103], v[58:59], v[102:103], v[62:63]
	v_pk_fma_f32 v[98:99], v[34:35], v[98:99], v[38:39]
	v_pk_fma_f32 v[100:101], v[100:101], s[52:53], v[122:123] op_sel_hi:[1,0,1]
	v_pk_fma_f32 v[96:97], v[96:97], s[52:53], v[126:127] op_sel_hi:[1,0,1]
	v_add_f32_e32 v113, 0, v113
	v_pk_fma_f32 v[102:103], v[102:103], s[52:53], v[124:125] op_sel_hi:[1,0,1]
	v_pk_fma_f32 v[98:99], v[98:99], s[52:53], v[178:179] op_sel_hi:[1,0,1]
	v_add_f32_e32 v116, v112, v113
	v_mov_b32_e32 v112, v96
	v_mov_b32_e32 v113, v100
	v_mov_b32_e32 v114, v97
	v_mov_b32_e32 v115, v101
	v_pk_add_f32 v[112:113], v[112:113], v[114:115]
	v_mov_b32_e32 v114, v98
	v_mov_b32_e32 v115, v102
	v_pk_add_f32 v[112:113], v[114:115], v[112:113]
	v_mov_b32_e32 v114, v99
	v_mov_b32_e32 v115, v103
	v_pk_add_f32 v[112:113], v[114:115], v[112:113]
	s_nop 0
	v_add_f32_e32 v113, v113, v116
	v_add_f32_e32 v112, v112, v113
	v_mbcnt_lo_u32_b32 v113, s2, 0
	v_mbcnt_hi_u32_b32 v113, s2, v113
	v_lshlrev_b32_e32 v113, 2, v113
	v_xor_b32_e32 v114, 0x80, v113
	ds_bpermute_b32 v114, v114, v112
	s_mov_b32 s2, -1
	s_waitcnt lgkmcnt(0)
; DEVFI void ln_resid4(const float* ysrc, float* ydst, bfraw* fb, float* stats, const float* pw, const float* pb,
;                      const float* w, const float* b, int lane, bool fin) {
;     ...
;     const float mean = red64(s) * (1.f / 1024.f);
;     float q = 0;
; #pragma unroll
;     for (int i = 0; i < 4; ++i) { const f32x4 d = y[i] - mean; q += d[0] * d[0] + d[1] * d[1] + d[2] * d[2] + d[3] * d[3]; }
;     const float rstd = 1.f / sqrtf(red64(q) * (1.f / 1024.f) + LN_EPS);
;     if (lane == 0) { stats[r * 2] = mean; stats[r * 2 + 1] = rstd; }
; #pragma unroll
;     for (int i = 0; i < 4; ++i) { const int c4 = i * 64 + lane;
;       const f32x4 z = (y[i] - mean) * rstd * ww[i] + bb[i];
;       __builtin_nontemporal_store(fin ? z : y[i], (f32x4*)(ydst + r * 1024) + c4);
;       u32x2 pk = {cvtpk(z[0], z[1]), cvtpk(z[2], z[3])}; ((u32x2*)(fb + r * 1024))[c4] = pk; }
	v_add_f32_e32 v112, v112, v114
	v_xor_b32_e32 v114, 64, v113
	ds_bpermute_b32 v114, v114, v112
	s_waitcnt lgkmcnt(0)
	v_add_f32_e32 v112, v112, v114
	v_xor_b32_e32 v114, 32, v113
	ds_bpermute_b32 v114, v114, v112
	s_waitcnt lgkmcnt(0)
	v_add_f32_e32 v112, v112, v114
	v_xor_b32_e32 v114, 16, v113
	ds_bpermute_b32 v114, v114, v112
	s_waitcnt lgkmcnt(0)
	v_add_f32_e32 v112, v112, v114
	v_xor_b32_e32 v114, 8, v113
	ds_bpermute_b32 v114, v114, v112
	v_xor_b32_e32 v113, 4, v113
	s_waitcnt lgkmcnt(0)
	v_add_f32_e32 v112, v112, v114
	ds_bpermute_b32 v113, v113, v112
	s_waitcnt lgkmcnt(0)
	v_add_f32_e32 v131, v112, v113
	v_fmamk_f32 v127, v131, 0xba800000, v109
	v_fmamk_f32 v123, v131, 0xba800000, v105
	v_fmamk_f32 v126, v131, 0xba800000, v108
	v_mul_f32_e32 v112, v127, v127
	v_fmamk_f32 v122, v131, 0xba800000, v104
	v_mul_f32_e32 v113, v123, v123
	v_fmamk_f32 v124, v131, 0xba800000, v110
	v_fmac_f32_e32 v112, v126, v126
	v_fmamk_f32 v120, v131, 0xba800000, v106
	v_fmac_f32_e32 v113, v122, v122
	v_fmamk_f32 v125, v131, 0xba800000, v111
	v_fmac_f32_e32 v112, v124, v124
	v_fmamk_f32 v121, v131, 0xba800000, v107
	v_fmac_f32_e32 v113, v120, v120
	v_fmac_f32_e32 v112, v125, v125
	v_fmac_f32_e32 v113, v121, v121
	v_fmamk_f32 v119, v131, 0xba800000, v101
	v_add_f32_e32 v112, v112, v113
	v_fmamk_f32 v118, v131, 0xba800000, v100
	v_mul_f32_e32 v113, v119, v119
	v_fmamk_f32 v116, v131, 0xba800000, v102
	v_fmac_f32_e32 v113, v118, v118
	v_fmamk_f32 v117, v131, 0xba800000, v103
	v_fmac_f32_e32 v113, v116, v116
	v_fmamk_f32 v115, v131, 0xba800000, v97
	v_fmac_f32_e32 v113, v117, v117
	v_fmamk_f32 v114, v131, 0xba800000, v96
	v_mul_f32_e32 v143, v115, v115
	v_add_f32_e32 v141, v113, v112
	v_fmamk_f32 v112, v131, 0xba800000, v98
	v_fmac_f32_e32 v143, v114, v114
	v_fmamk_f32 v113, v131, 0xba800000, v99
	v_fmac_f32_e32 v143, v112, v112
	v_fmac_f32_e32 v143, v113, v113
	v_add_f32_e32 v141, v143, v141
	v_mbcnt_lo_u32_b32 v143, s2, 0
	v_mbcnt_hi_u32_b32 v143, s2, v143
	v_lshlrev_b32_e32 v143, 2, v143
	v_xor_b32_e32 v145, 0x80, v143
	ds_bpermute_b32 v145, v145, v141
	s_waitcnt lgkmcnt(0)
	v_add_f32_e32 v141, v141, v145
	v_xor_b32_e32 v145, 64, v143
	ds_bpermute_b32 v145, v145, v141
	s_waitcnt lgkmcnt(0)
	v_add_f32_e32 v141, v141, v145
	v_xor_b32_e32 v145, 32, v143
	ds_bpermute_b32 v145, v145, v141
	s_waitcnt lgkmcnt(0)
	v_add_f32_e32 v141, v141, v145
	v_xor_b32_e32 v145, 16, v143
	ds_bpermute_b32 v145, v145, v141
	s_waitcnt lgkmcnt(0)
	v_add_f32_e32 v141, v141, v145
	v_xor_b32_e32 v145, 8, v143
	ds_bpermute_b32 v145, v145, v141
	v_xor_b32_e32 v143, 4, v143
	s_waitcnt lgkmcnt(0)
	v_add_f32_e32 v141, v141, v145
	ds_bpermute_b32 v143, v143, v141
	s_waitcnt lgkmcnt(0)
	v_add_f32_e32 v141, v141, v143
	v_fmamk_f32 v141, v141, 0x3a800000, v183
	v_mul_f32_e32 v143, 0x4f800000, v141
	v_cmp_gt_f32_e32 vcc, s30, v141
	s_nop 1
	v_cndmask_b32_e32 v141, v141, v143, vcc
	v_sqrt_f32_e32 v143, v141
	s_nop 0
	v_add_u32_e32 v145, -1, v143
	v_fma_f32 v149, -v145, v143, v141
	v_cmp_ge_f32_e64 s[6:7], 0, v149
	v_add_u32_e32 v149, 1, v143
	s_nop 0
	v_cndmask_b32_e64 v145, v143, v145, s[6:7]
	v_fma_f32 v143, -v149, v143, v141
	v_cmp_lt_f32_e64 s[6:7], 0, v143
	s_nop 1
	v_cndmask_b32_e64 v143, v145, v149, s[6:7]
	v_mul_f32_e32 v145, 0x37800000, v143
	v_cndmask_b32_e32 v143, v143, v145, vcc
	v_cmp_class_f32_e32 vcc, v141, v222
	s_nop 1
	v_cndmask_b32_e32 v141, v143, v141, vcc
	s_nop 0
	v_rcp_f32_e32 v145, v141
	s_nop 0
	v_fma_f32 v143, -v141, v145, 1.0
	v_fma_f32 v143, v143, v145, v145
	v_div_fixup_f32 v188, v143, v141, 1.0
	s_and_saveexec_b64 s[2:3], s[4:5]
	s_cbranch_execz .LBB0_3166
	v_mul_f32_e32 v178, 0x3a800000, v131
	v_mov_b32_e32 v179, v188
	global_store_dwordx2 v[156:157], v[178:179], off offset:8
.LBB0_3166:
	s_or_b64 exec, exec, s[2:3]
	s_mov_b64 s[2:3], 0x1000
	v_lshl_add_u64 v[178:179], v[168:169], 0, s[2:3]
	v_pk_mul_f32 v[124:125], v[124:125], v[188:189] op_sel_hi:[1,0]
	v_pk_mul_f32 v[126:127], v[126:127], v[188:189] op_sel_hi:[1,0]
	v_lshl_add_u64 v[180:181], v[178:179], 0, v[176:177]
	v_pk_fma_f32 v[124:125], v[26:27], v[124:125], v[30:31]
	v_pk_fma_f32 v[126:127], v[24:25], v[126:127], v[28:29]
	global_store_dwordx4 v[180:181], v[108:111], off nt
	v_mov_b32_e32 v149, v177
	v_mov_b32_e32 v151, v177
	v_cvt_pk_bf16_f32 v108, v126, v127
	v_cvt_pk_bf16_f32 v109, v124, v125
	global_store_dwordx2 v[172:173], v[108:109], off offset:2048
	v_pk_mul_f32 v[108:109], v[120:121], v[188:189] op_sel_hi:[1,0]
	v_pk_mul_f32 v[110:111], v[122:123], v[188:189] op_sel_hi:[1,0]
	v_lshl_add_u64 v[120:121], v[178:179], 0, v[148:149]
	v_pk_fma_f32 v[108:109], v[18:19], v[108:109], v[22:23]
	v_pk_fma_f32 v[110:111], v[16:17], v[110:111], v[20:21]
	global_store_dwordx4 v[120:121], v[104:107], off nt
	v_mov_b32_e32 v153, v177
	s_mov_b32 s2, -1
	v_cvt_pk_bf16_f32 v104, v110, v111
	v_cvt_pk_bf16_f32 v105, v108, v109
	global_store_dwordx2 v[172:173], v[104:105], off offset:2560
	v_pk_mul_f32 v[104:105], v[116:117], v[188:189] op_sel_hi:[1,0]
	v_pk_mul_f32 v[106:107], v[118:119], v[188:189] op_sel_hi:[1,0]
	v_lshl_add_u64 v[108:109], v[178:179], 0, v[150:151]
	v_pk_fma_f32 v[104:105], v[10:11], v[104:105], v[14:15]
	v_pk_fma_f32 v[106:107], v[8:9], v[106:107], v[12:13]
	global_store_dwordx4 v[108:109], v[100:103], off nt
	v_lshlrev_b32_e32 v110, 16, v170
	v_and_b32_e32 v111, 0xffff0000, v170
	v_cvt_pk_bf16_f32 v100, v106, v107
	v_cvt_pk_bf16_f32 v101, v104, v105
	global_store_dwordx2 v[172:173], v[100:101], off offset:3072
	v_pk_mul_f32 v[100:101], v[112:113], v[188:189] op_sel_hi:[1,0]
	v_pk_mul_f32 v[102:103], v[114:115], v[188:189] op_sel_hi:[1,0]
	v_lshl_add_u64 v[104:105], v[178:179], 0, v[152:153]
	v_pk_fma_f32 v[100:101], v[2:3], v[100:101], v[6:7]
	v_pk_fma_f32 v[102:103], v[0:1], v[102:103], v[4:5]
	global_store_dwordx4 v[104:105], v[96:99], off nt
	v_lshlrev_b32_e32 v104, 16, v185
	v_and_b32_e32 v105, 0xffff0000, v185
	v_cvt_pk_bf16_f32 v96, v102, v103
	v_cvt_pk_bf16_f32 v97, v100, v101
	global_store_dwordx2 v[172:173], v[96:97], off offset:3584
	global_load_dwordx2 v[96:97], v[156:157], off offset:16
	v_lshlrev_b32_e32 v98, 16, v186
	v_and_b32_e32 v99, 0xffff0000, v186
	v_lshlrev_b32_e32 v102, 16, v184
	v_and_b32_e32 v103, 0xffff0000, v184
	v_lshlrev_b32_e32 v100, 16, v187
	v_and_b32_e32 v101, 0xffff0000, v187
	v_lshlrev_b32_e32 v106, 16, v174
	v_and_b32_e32 v107, 0xffff0000, v174
	v_lshlrev_b32_e32 v108, 16, v175
	v_and_b32_e32 v109, 0xffff0000, v175
	v_lshlrev_b32_e32 v112, 16, v171
	v_and_b32_e32 v113, 0xffff0000, v171
	s_waitcnt vmcnt(0)
; DEVFI void ln_resid4(const float* ysrc, float* ydst, bfraw* fb, float* stats, const float* pw, const float* pb,
;                      const float* w, const float* b, int lane, bool fin) {
;     ...
;   for (int r = 0; r < 4; ++r) {
;     const float pmu = stats[r * 2], prs = stats[r * 2 + 1];
;     f32x4 y[4];
; #pragma unroll
;     for (int i = 0; i < 4; ++i) { const unsigned f0 = fv[r][i][0], f1 = fv[r][i][1];
;       const f32x4 f4 = {__uint_as_float(f0 << 16), __uint_as_float(f0 & 0xffff0000u), __uint_as_float(f1 << 16), __uint_as_float(f1 & 0xffff0000u)};
;       y[i] = ALPHA * ((v[r][i] - pmu) * prs * pwv[i] + pbv[i]) + f4; }
;     float s = 0;
; #pragma unroll
;     for (int i = 0; i < 4; ++i) s += y[i][0] + y[i][1] + y[i][2] + y[i][3];
;     const float mean = red64(s) * (1.f / 1024.f);
;     float q = 0;
; #pragma unroll
;     for (int i = 0; i < 4; ++i) { const f32x4 d = y[i] - mean; q += d[0] * d[0] + d[1] * d[1] + d[2] * d[2] + d[3] * d[3]; }
;     const float rstd = 1.f / sqrtf(red64(q) * (1.f / 1024.f) + LN_EPS);
;     if (lane == 0) { stats[r * 2] = mean; stats[r * 2 + 1] = rstd; }
	v_sub_f32_e32 v93, v93, v96
	v_sub_f32_e32 v92, v92, v96
	v_sub_f32_e32 v89, v89, v96
	v_sub_f32_e32 v88, v88, v96
	v_sub_f32_e32 v95, v95, v96
	v_sub_f32_e32 v94, v94, v96
	v_sub_f32_e32 v91, v91, v96
	v_sub_f32_e32 v90, v90, v96
	v_pk_mul_f32 v[92:93], v[96:97], v[92:93] op_sel:[1,0]
	v_pk_mul_f32 v[88:89], v[96:97], v[88:89] op_sel:[1,0]
	v_pk_mul_f32 v[94:95], v[96:97], v[94:95] op_sel:[1,0]
	v_pk_mul_f32 v[90:91], v[96:97], v[90:91] op_sel:[1,0]
	v_pk_fma_f32 v[92:93], v[40:41], v[92:93], v[44:45]
	v_pk_fma_f32 v[88:89], v[48:49], v[88:89], v[52:53]
	v_sub_f32_e32 v85, v85, v96
	v_sub_f32_e32 v84, v84, v96
	v_sub_f32_e32 v87, v87, v96
	v_sub_f32_e32 v86, v86, v96
	v_sub_f32_e32 v81, v81, v96
	v_sub_f32_e32 v80, v80, v96
	v_sub_f32_e32 v83, v83, v96
	v_sub_f32_e32 v82, v82, v96
	v_pk_fma_f32 v[94:95], v[42:43], v[94:95], v[46:47]
	v_pk_fma_f32 v[90:91], v[50:51], v[90:91], v[54:55]
	v_pk_fma_f32 v[92:93], v[92:93], s[52:53], v[98:99] op_sel_hi:[1,0,1]
	v_pk_fma_f32 v[88:89], v[88:89], s[52:53], v[102:103] op_sel_hi:[1,0,1]
	v_pk_mul_f32 v[86:87], v[96:97], v[86:87] op_sel:[1,0]
	v_pk_mul_f32 v[84:85], v[96:97], v[84:85] op_sel:[1,0]
	v_pk_fma_f32 v[94:95], v[94:95], s[52:53], v[100:101] op_sel_hi:[1,0,1]
	v_pk_fma_f32 v[90:91], v[90:91], s[52:53], v[104:105] op_sel_hi:[1,0,1]
	v_pk_mul_f32 v[82:83], v[96:97], v[82:83] op_sel:[1,0]
	v_pk_mul_f32 v[80:81], v[96:97], v[80:81] op_sel:[1,0]
	v_mov_b32_e32 v96, v88
	v_mov_b32_e32 v97, v92
	v_mov_b32_e32 v98, v89
	v_mov_b32_e32 v99, v93
	v_pk_add_f32 v[96:97], v[96:97], v[98:99]
	v_mov_b32_e32 v98, v90
	v_mov_b32_e32 v99, v94
	v_pk_add_f32 v[96:97], v[98:99], v[96:97]
	v_mov_b32_e32 v98, v91
	v_mov_b32_e32 v99, v95
	v_pk_fma_f32 v[84:85], v[56:57], v[84:85], v[60:61]
	v_pk_fma_f32 v[80:81], v[32:33], v[80:81], v[36:37]
	v_pk_add_f32 v[96:97], v[98:99], v[96:97]
	v_pk_fma_f32 v[86:87], v[58:59], v[86:87], v[62:63]
	v_pk_fma_f32 v[84:85], v[84:85], s[52:53], v[106:107] op_sel_hi:[1,0,1]
	v_pk_fma_f32 v[82:83], v[34:35], v[82:83], v[38:39]
	v_pk_fma_f32 v[80:81], v[80:81], s[52:53], v[110:111] op_sel_hi:[1,0,1]
	v_add_f32_e32 v97, 0, v97
	v_pk_fma_f32 v[86:87], v[86:87], s[52:53], v[108:109] op_sel_hi:[1,0,1]
	v_pk_fma_f32 v[82:83], v[82:83], s[52:53], v[112:113] op_sel_hi:[1,0,1]
	v_add_f32_e32 v100, v96, v97
	v_mov_b32_e32 v96, v80
	v_mov_b32_e32 v97, v84
	v_mov_b32_e32 v98, v81
	v_mov_b32_e32 v99, v85
	v_pk_add_f32 v[96:97], v[96:97], v[98:99]
	v_mov_b32_e32 v98, v82
	v_mov_b32_e32 v99, v86
	v_pk_add_f32 v[96:97], v[98:99], v[96:97]
	v_mov_b32_e32 v98, v83
	v_mov_b32_e32 v99, v87
	v_pk_add_f32 v[96:97], v[98:99], v[96:97]
	s_nop 0
	v_add_f32_e32 v97, v97, v100
	v_add_f32_e32 v96, v96, v97
	v_mbcnt_lo_u32_b32 v97, s2, 0
	v_mbcnt_hi_u32_b32 v97, s2, v97
	v_lshlrev_b32_e32 v97, 2, v97
	v_xor_b32_e32 v98, 0x80, v97
	ds_bpermute_b32 v98, v98, v96
	s_mov_b32 s2, -1
	s_waitcnt lgkmcnt(0)
	v_add_f32_e32 v96, v96, v98
	v_xor_b32_e32 v98, 64, v97
	ds_bpermute_b32 v98, v98, v96
	s_waitcnt lgkmcnt(0)
	v_add_f32_e32 v96, v96, v98
	v_xor_b32_e32 v98, 32, v97
	ds_bpermute_b32 v98, v98, v96
	s_waitcnt lgkmcnt(0)
	v_add_f32_e32 v96, v96, v98
	v_xor_b32_e32 v98, 16, v97
	ds_bpermute_b32 v98, v98, v96
	s_waitcnt lgkmcnt(0)
	v_add_f32_e32 v96, v96, v98
	v_xor_b32_e32 v98, 8, v97
	ds_bpermute_b32 v98, v98, v96
	v_xor_b32_e32 v97, 4, v97
	s_waitcnt lgkmcnt(0)
	v_add_f32_e32 v96, v96, v98
	ds_bpermute_b32 v97, v97, v96
	s_waitcnt lgkmcnt(0)
	v_add_f32_e32 v113, v96, v97
	v_fmamk_f32 v111, v113, 0xba800000, v93
	v_fmamk_f32 v107, v113, 0xba800000, v89
	v_fmamk_f32 v110, v113, 0xba800000, v92
	v_mul_f32_e32 v96, v111, v111
	v_fmamk_f32 v106, v113, 0xba800000, v88
	v_mul_f32_e32 v97, v107, v107
	v_fmamk_f32 v108, v113, 0xba800000, v94
	v_fmac_f32_e32 v96, v110, v110
	v_fmamk_f32 v104, v113, 0xba800000, v90
	v_fmac_f32_e32 v97, v106, v106
	v_fmamk_f32 v109, v113, 0xba800000, v95
	v_fmac_f32_e32 v96, v108, v108
	v_fmamk_f32 v105, v113, 0xba800000, v91
	v_fmac_f32_e32 v97, v104, v104
	v_fmac_f32_e32 v96, v109, v109
	v_fmac_f32_e32 v97, v105, v105
	v_fmamk_f32 v103, v113, 0xba800000, v85
	v_add_f32_e32 v96, v96, v97
	v_fmamk_f32 v102, v113, 0xba800000, v84
	v_mul_f32_e32 v97, v103, v103
	v_fmamk_f32 v100, v113, 0xba800000, v86
	v_fmac_f32_e32 v97, v102, v102
	v_fmamk_f32 v101, v113, 0xba800000, v87
	v_fmac_f32_e32 v97, v100, v100
	v_fmamk_f32 v99, v113, 0xba800000, v81
	v_fmac_f32_e32 v97, v101, v101
	v_fmamk_f32 v98, v113, 0xba800000, v80
	v_mul_f32_e32 v114, v99, v99
	v_add_f32_e32 v112, v97, v96
	v_fmamk_f32 v96, v113, 0xba800000, v82
	v_fmac_f32_e32 v114, v98, v98
	v_fmamk_f32 v97, v113, 0xba800000, v83
	v_fmac_f32_e32 v114, v96, v96
	v_fmac_f32_e32 v114, v97, v97
	v_add_f32_e32 v112, v114, v112
	v_mbcnt_lo_u32_b32 v114, s2, 0
	v_mbcnt_hi_u32_b32 v114, s2, v114
	v_lshlrev_b32_e32 v114, 2, v114
	v_xor_b32_e32 v115, 0x80, v114
	ds_bpermute_b32 v115, v115, v112
	s_waitcnt lgkmcnt(0)
	v_add_f32_e32 v112, v112, v115
	v_xor_b32_e32 v115, 64, v114
	ds_bpermute_b32 v115, v115, v112
	s_waitcnt lgkmcnt(0)
	v_add_f32_e32 v112, v112, v115
	v_xor_b32_e32 v115, 32, v114
	ds_bpermute_b32 v115, v115, v112
	s_waitcnt lgkmcnt(0)
	v_add_f32_e32 v112, v112, v115
	v_xor_b32_e32 v115, 16, v114
	ds_bpermute_b32 v115, v115, v112
	s_waitcnt lgkmcnt(0)
	v_add_f32_e32 v112, v112, v115
	v_xor_b32_e32 v115, 8, v114
	ds_bpermute_b32 v115, v115, v112
	v_xor_b32_e32 v114, 4, v114
	s_waitcnt lgkmcnt(0)
	v_add_f32_e32 v112, v112, v115
	ds_bpermute_b32 v114, v114, v112
	s_waitcnt lgkmcnt(0)
	v_add_f32_e32 v112, v112, v114
	v_fmamk_f32 v112, v112, 0x3a800000, v183
	v_mul_f32_e32 v114, 0x4f800000, v112
	v_cmp_gt_f32_e32 vcc, s30, v112
	s_nop 1
	v_cndmask_b32_e32 v112, v112, v114, vcc
	v_sqrt_f32_e32 v114, v112
	s_nop 0
	v_add_u32_e32 v115, -1, v114
	v_fma_f32 v116, -v115, v114, v112
	v_cmp_ge_f32_e64 s[6:7], 0, v116
	v_add_u32_e32 v116, 1, v114
	s_nop 0
	v_cndmask_b32_e64 v115, v114, v115, s[6:7]
	v_fma_f32 v114, -v116, v114, v112
	v_cmp_lt_f32_e64 s[6:7], 0, v114
	s_nop 1
	v_cndmask_b32_e64 v114, v115, v116, s[6:7]
	v_mul_f32_e32 v115, 0x37800000, v114
	v_cndmask_b32_e32 v114, v114, v115, vcc
	v_cmp_class_f32_e32 vcc, v112, v222
	s_nop 1
	v_cndmask_b32_e32 v112, v114, v112, vcc
	s_nop 0
	v_rcp_f32_e32 v115, v112
	s_nop 0
	v_fma_f32 v114, -v112, v115, 1.0
	v_fma_f32 v114, v114, v115, v115
	v_div_fixup_f32 v112, v114, v112, 1.0
	s_and_saveexec_b64 s[2:3], s[4:5]
	s_cbranch_execz .LBB0_3168
	v_mul_f32_e32 v114, 0x3a800000, v113
	v_mov_b32_e32 v115, v112
	global_store_dwordx2 v[156:157], v[114:115], off offset:16
; DEVFI void ln_resid4(const float* ysrc, float* ydst, bfraw* fb, float* stats, const float* pw, const float* pb,
;                      const float* w, const float* b, int lane, bool fin) {
;     ...
;   for (int r = 0; r < 4; ++r) {
;     const float pmu = stats[r * 2], prs = stats[r * 2 + 1];
;     f32x4 y[4];
; #pragma unroll
;     for (int i = 0; i < 4; ++i) { const unsigned f0 = fv[r][i][0], f1 = fv[r][i][1];
;       const f32x4 f4 = {__uint_as_float(f0 << 16), __uint_as_float(f0 & 0xffff0000u), __uint_as_float(f1 << 16), __uint_as_float(f1 & 0xffff0000u)};
;       y[i] = ALPHA * ((v[r][i] - pmu) * prs * pwv[i] + pbv[i]) + f4; }
;     float s = 0;
; #pragma unroll
;     for (int i = 0; i < 4; ++i) s += y[i][0] + y[i][1] + y[i][2] + y[i][3];
;     const float mean = red64(s) * (1.f / 1024.f);
;     float q = 0;
; #pragma unroll
;     for (int i = 0; i < 4; ++i) { const f32x4 d = y[i] - mean; q += d[0] * d[0] + d[1] * d[1] + d[2] * d[2] + d[3] * d[3]; }
;     const float rstd = 1.f / sqrtf(red64(q) * (1.f / 1024.f) + LN_EPS);
;     if (lane == 0) { stats[r * 2] = mean; stats[r * 2 + 1] = rstd; }
; #pragma unroll
;     for (int i = 0; i < 4; ++i) { const int c4 = i * 64 + lane;
;       const f32x4 z = (y[i] - mean) * rstd * ww[i] + bb[i];
;       __builtin_nontemporal_store(fin ? z : y[i], (f32x4*)(ydst + r * 1024) + c4);
;       u32x2 pk = {cvtpk(z[0], z[1]), cvtpk(z[2], z[3])}; ((u32x2*)(fb + r * 1024))[c4] = pk; }
.LBB0_3168:
	s_or_b64 exec, exec, s[2:3]
	s_mov_b64 s[2:3], 0x2000
	v_lshl_add_u64 v[114:115], v[168:169], 0, s[2:3]
	s_mov_b64 s[2:3], 0x1000
	v_lshl_add_u64 v[116:117], v[154:155], 0, s[2:3]
	v_pk_mul_f32 v[108:109], v[108:109], v[112:113] op_sel_hi:[1,0]
	v_pk_mul_f32 v[110:111], v[110:111], v[112:113] op_sel_hi:[1,0]
	v_lshl_add_u64 v[118:119], v[114:115], 0, v[176:177]
	v_mov_b32_e32 v159, v177
	v_pk_fma_f32 v[108:109], v[26:27], v[108:109], v[30:31]
	v_pk_fma_f32 v[110:111], v[24:25], v[110:111], v[28:29]
	global_store_dwordx4 v[118:119], v[92:95], off nt
	s_mov_b32 s2, -1
	s_nop 0
	v_cvt_pk_bf16_f32 v92, v110, v111
	v_cvt_pk_bf16_f32 v93, v108, v109
	v_lshl_add_u64 v[94:95], v[116:117], 0, v[158:159]
	global_store_dwordx2 v[94:95], v[92:93], off
	v_pk_mul_f32 v[92:93], v[104:105], v[112:113] op_sel_hi:[1,0]
	v_lshl_add_u64 v[104:105], v[114:115], 0, v[148:149]
	v_pk_mul_f32 v[94:95], v[106:107], v[112:113] op_sel_hi:[1,0]
	v_pk_fma_f32 v[92:93], v[18:19], v[92:93], v[22:23]
	global_store_dwordx4 v[104:105], v[88:91], off nt
	v_pk_fma_f32 v[94:95], v[16:17], v[94:95], v[20:21]
	s_nop 0
	v_lshlrev_b32_e32 v88, 3, v140
	v_mov_b32_e32 v89, v177
	v_cvt_pk_bf16_f32 v90, v94, v95
	v_cvt_pk_bf16_f32 v91, v92, v93
	v_lshl_add_u64 v[92:93], v[116:117], 0, v[88:89]
	global_store_dwordx2 v[92:93], v[90:91], off
	v_pk_mul_f32 v[90:91], v[100:101], v[112:113] op_sel_hi:[1,0]
	v_lshl_add_u64 v[94:95], v[114:115], 0, v[150:151]
	v_pk_mul_f32 v[92:93], v[102:103], v[112:113] op_sel_hi:[1,0]
	v_pk_fma_f32 v[90:91], v[10:11], v[90:91], v[14:15]
	global_store_dwordx4 v[94:95], v[84:87], off nt
	v_pk_fma_f32 v[92:93], v[8:9], v[92:93], v[12:13]
	v_lshlrev_b32_e32 v94, 16, v165
	v_lshlrev_b32_e32 v84, 3, v142
	v_mov_b32_e32 v85, v177
	v_cvt_pk_bf16_f32 v86, v92, v93
	v_cvt_pk_bf16_f32 v87, v90, v91
	v_lshl_add_u64 v[90:91], v[116:117], 0, v[84:85]
	global_store_dwordx2 v[90:91], v[86:87], off
	v_pk_mul_f32 v[86:87], v[96:97], v[112:113] op_sel_hi:[1,0]
	v_lshl_add_u64 v[92:93], v[114:115], 0, v[152:153]
	v_pk_mul_f32 v[90:91], v[98:99], v[112:113] op_sel_hi:[1,0]
	v_pk_fma_f32 v[86:87], v[2:3], v[86:87], v[6:7]
	global_store_dwordx4 v[92:93], v[80:83], off nt
	v_pk_fma_f32 v[90:91], v[0:1], v[90:91], v[4:5]
	v_lshlrev_b32_e32 v92, 16, v164
	v_lshlrev_b32_e32 v80, 3, v144
	v_mov_b32_e32 v81, v177
	v_cvt_pk_bf16_f32 v82, v90, v91
	v_cvt_pk_bf16_f32 v83, v86, v87
	v_lshl_add_u64 v[86:87], v[116:117], 0, v[80:81]
	global_store_dwordx2 v[86:87], v[82:83], off
	global_load_dwordx2 v[82:83], v[156:157], off offset:24
	v_lshlrev_b32_e32 v86, 16, v166
	v_and_b32_e32 v87, 0xffff0000, v166
	v_and_b32_e32 v93, 0xffff0000, v164
	v_lshlrev_b32_e32 v90, 16, v167
	v_and_b32_e32 v91, 0xffff0000, v167
	v_and_b32_e32 v95, 0xffff0000, v165
	v_lshlrev_b32_e32 v96, 16, v162
	v_and_b32_e32 v97, 0xffff0000, v162
	v_lshlrev_b32_e32 v98, 16, v163
	v_and_b32_e32 v99, 0xffff0000, v163
	s_waitcnt vmcnt(0)
	v_sub_f32_e32 v77, v77, v82
	v_sub_f32_e32 v76, v76, v82
	v_sub_f32_e32 v79, v79, v82
	v_sub_f32_e32 v78, v78, v82
	v_sub_f32_e32 v73, v73, v82
	v_sub_f32_e32 v72, v72, v82
	v_sub_f32_e32 v75, v75, v82
	v_sub_f32_e32 v74, v74, v82
	v_sub_f32_e32 v69, v69, v82
	v_sub_f32_e32 v68, v68, v82
	v_sub_f32_e32 v71, v71, v82
	v_sub_f32_e32 v70, v70, v82
	v_pk_mul_f32 v[78:79], v[82:83], v[78:79] op_sel:[1,0]
	v_pk_mul_f32 v[76:77], v[82:83], v[76:77] op_sel:[1,0]
	v_pk_mul_f32 v[74:75], v[82:83], v[74:75] op_sel:[1,0]
	v_pk_mul_f32 v[72:73], v[82:83], v[72:73] op_sel:[1,0]
	v_pk_mul_f32 v[70:71], v[82:83], v[70:71] op_sel:[1,0]
	v_pk_mul_f32 v[68:69], v[82:83], v[68:69] op_sel:[1,0]
	v_pk_fma_f32 v[40:41], v[40:41], v[76:77], v[44:45]
	v_pk_fma_f32 v[42:43], v[42:43], v[78:79], v[46:47]
	v_pk_fma_f32 v[44:45], v[48:49], v[72:73], v[52:53]
	v_pk_fma_f32 v[46:47], v[50:51], v[74:75], v[54:55]
	v_pk_fma_f32 v[52:53], v[56:57], v[68:69], v[60:61]
	v_pk_fma_f32 v[54:55], v[58:59], v[70:71], v[62:63]
	v_sub_f32_e32 v57, v65, v82
	v_sub_f32_e32 v56, v64, v82
	v_sub_f32_e32 v59, v67, v82
	v_sub_f32_e32 v58, v66, v82
	v_pk_fma_f32 v[48:49], v[40:41], s[52:53], v[86:87] op_sel_hi:[1,0,1]
	v_pk_fma_f32 v[44:45], v[44:45], s[52:53], v[92:93] op_sel_hi:[1,0,1]
	v_pk_mul_f32 v[58:59], v[82:83], v[58:59] op_sel:[1,0]
	v_pk_mul_f32 v[56:57], v[82:83], v[56:57] op_sel:[1,0]
	v_pk_fma_f32 v[50:51], v[42:43], s[52:53], v[90:91] op_sel_hi:[1,0,1]
	v_pk_fma_f32 v[46:47], v[46:47], s[52:53], v[94:95] op_sel_hi:[1,0,1]
	v_pk_fma_f32 v[32:33], v[32:33], v[56:57], v[36:37]
	v_pk_fma_f32 v[34:35], v[34:35], v[58:59], v[38:39]
	v_mov_b32_e32 v36, v44
	v_mov_b32_e32 v37, v48
	v_mov_b32_e32 v38, v45
	v_mov_b32_e32 v39, v49
	v_pk_add_f32 v[36:37], v[36:37], v[38:39]
	v_mov_b32_e32 v38, v46
	v_mov_b32_e32 v39, v50
	v_pk_add_f32 v[36:37], v[38:39], v[36:37]
	v_mov_b32_e32 v38, v47
	v_mov_b32_e32 v39, v51
	v_pk_fma_f32 v[40:41], v[52:53], s[52:53], v[96:97] op_sel_hi:[1,0,1]
	v_lshlrev_b32_e32 v52, 16, v160
	v_and_b32_e32 v53, 0xffff0000, v160
	v_pk_add_f32 v[36:37], v[38:39], v[36:37]
	v_pk_fma_f32 v[42:43], v[54:55], s[52:53], v[98:99] op_sel_hi:[1,0,1]
	v_lshlrev_b32_e32 v54, 16, v161
	v_and_b32_e32 v55, 0xffff0000, v161
	v_pk_fma_f32 v[32:33], v[32:33], s[52:53], v[52:53] op_sel_hi:[1,0,1]
	v_add_f32_e32 v37, 0, v37
	v_pk_fma_f32 v[34:35], v[34:35], s[52:53], v[54:55] op_sel_hi:[1,0,1]
	v_add_f32_e32 v52, v36, v37
	v_mov_b32_e32 v36, v32
	v_mov_b32_e32 v37, v40
	v_mov_b32_e32 v38, v33
	v_mov_b32_e32 v39, v41
	v_pk_add_f32 v[36:37], v[36:37], v[38:39]
	v_mov_b32_e32 v38, v34
	v_mov_b32_e32 v39, v42
	v_pk_add_f32 v[36:37], v[38:39], v[36:37]
	v_mov_b32_e32 v38, v35
	v_mov_b32_e32 v39, v43
	v_pk_add_f32 v[36:37], v[38:39], v[36:37]
	s_nop 0
	v_add_f32_e32 v37, v37, v52
	v_add_f32_e32 v36, v36, v37
	v_mbcnt_lo_u32_b32 v37, s2, 0
	v_mbcnt_hi_u32_b32 v37, s2, v37
	v_lshlrev_b32_e32 v37, 2, v37
	v_xor_b32_e32 v38, 0x80, v37
	ds_bpermute_b32 v38, v38, v36
	s_mov_b32 s2, -1
	s_waitcnt lgkmcnt(0)
; DEVFI void ln_resid4(const float* ysrc, float* ydst, bfraw* fb, float* stats, const float* pw, const float* pb,
;                      const float* w, const float* b, int lane, bool fin) {
;     ...
;     const float mean = red64(s) * (1.f / 1024.f);
;     float q = 0;
; #pragma unroll
;     for (int i = 0; i < 4; ++i) { const f32x4 d = y[i] - mean; q += d[0] * d[0] + d[1] * d[1] + d[2] * d[2] + d[3] * d[3]; }
;     const float rstd = 1.f / sqrtf(red64(q) * (1.f / 1024.f) + LN_EPS);
;     if (lane == 0) { stats[r * 2] = mean; stats[r * 2 + 1] = rstd; }
	v_add_f32_e32 v36, v36, v38
	v_xor_b32_e32 v38, 64, v37
	ds_bpermute_b32 v38, v38, v36
	s_waitcnt lgkmcnt(0)
	v_add_f32_e32 v36, v36, v38
	v_xor_b32_e32 v38, 32, v37
	ds_bpermute_b32 v38, v38, v36
	s_waitcnt lgkmcnt(0)
	v_add_f32_e32 v36, v36, v38
	v_xor_b32_e32 v38, 16, v37
	ds_bpermute_b32 v38, v38, v36
	s_waitcnt lgkmcnt(0)
	v_add_f32_e32 v36, v36, v38
	v_xor_b32_e32 v38, 8, v37
	ds_bpermute_b32 v38, v38, v36
	v_xor_b32_e32 v37, 4, v37
	s_waitcnt lgkmcnt(0)
	v_add_f32_e32 v36, v36, v38
	ds_bpermute_b32 v37, v37, v36
	s_waitcnt lgkmcnt(0)
	v_add_f32_e32 v65, v36, v37
	v_fmamk_f32 v63, v65, 0xba800000, v49
	v_fmamk_f32 v59, v65, 0xba800000, v45
	v_fmamk_f32 v62, v65, 0xba800000, v48
	v_mul_f32_e32 v36, v63, v63
	v_fmamk_f32 v58, v65, 0xba800000, v44
	v_mul_f32_e32 v37, v59, v59
	v_fmamk_f32 v60, v65, 0xba800000, v50
	v_fmac_f32_e32 v36, v62, v62
	v_fmamk_f32 v56, v65, 0xba800000, v46
	v_fmac_f32_e32 v37, v58, v58
	v_fmamk_f32 v61, v65, 0xba800000, v51
	v_fmac_f32_e32 v36, v60, v60
	v_fmamk_f32 v57, v65, 0xba800000, v47
	v_fmac_f32_e32 v37, v56, v56
	v_fmac_f32_e32 v36, v61, v61
	v_fmac_f32_e32 v37, v57, v57
	v_fmamk_f32 v55, v65, 0xba800000, v41
	v_add_f32_e32 v36, v36, v37
	v_fmamk_f32 v54, v65, 0xba800000, v40
	v_mul_f32_e32 v37, v55, v55
	v_fmamk_f32 v52, v65, 0xba800000, v42
	v_fmac_f32_e32 v37, v54, v54
	v_fmamk_f32 v53, v65, 0xba800000, v43
	v_fmac_f32_e32 v37, v52, v52
	v_fmamk_f32 v39, v65, 0xba800000, v33
	v_fmac_f32_e32 v37, v53, v53
	v_fmamk_f32 v38, v65, 0xba800000, v32
	v_mul_f32_e32 v66, v39, v39
	v_add_f32_e32 v64, v37, v36
	v_fmamk_f32 v36, v65, 0xba800000, v34
	v_fmac_f32_e32 v66, v38, v38
	v_fmamk_f32 v37, v65, 0xba800000, v35
	v_fmac_f32_e32 v66, v36, v36
	v_fmac_f32_e32 v66, v37, v37
	v_add_f32_e32 v64, v66, v64
	v_mbcnt_lo_u32_b32 v66, s2, 0
	v_mbcnt_hi_u32_b32 v66, s2, v66
	v_lshlrev_b32_e32 v66, 2, v66
	v_xor_b32_e32 v67, 0x80, v66
	ds_bpermute_b32 v67, v67, v64
	s_waitcnt lgkmcnt(0)
	v_add_f32_e32 v64, v64, v67
	v_xor_b32_e32 v67, 64, v66
	ds_bpermute_b32 v67, v67, v64
	s_waitcnt lgkmcnt(0)
	v_add_f32_e32 v64, v64, v67
	v_xor_b32_e32 v67, 32, v66
	ds_bpermute_b32 v67, v67, v64
	s_waitcnt lgkmcnt(0)
	v_add_f32_e32 v64, v64, v67
	v_xor_b32_e32 v67, 16, v66
	ds_bpermute_b32 v67, v67, v64
	s_waitcnt lgkmcnt(0)
	v_add_f32_e32 v64, v64, v67
	v_xor_b32_e32 v67, 8, v66
	ds_bpermute_b32 v67, v67, v64
	v_xor_b32_e32 v66, 4, v66
	s_waitcnt lgkmcnt(0)
	v_add_f32_e32 v64, v64, v67
	ds_bpermute_b32 v66, v66, v64
	s_waitcnt lgkmcnt(0)
	v_add_f32_e32 v64, v64, v66
	v_fmamk_f32 v64, v64, 0x3a800000, v183
	v_mul_f32_e32 v66, 0x4f800000, v64
	v_cmp_gt_f32_e32 vcc, s30, v64
	s_nop 1
	v_cndmask_b32_e32 v64, v64, v66, vcc
	v_sqrt_f32_e32 v66, v64
	s_nop 0
	v_add_u32_e32 v67, -1, v66
	v_fma_f32 v68, -v67, v66, v64
	v_cmp_ge_f32_e64 s[6:7], 0, v68
	v_add_u32_e32 v68, 1, v66
	s_nop 0
	v_cndmask_b32_e64 v67, v66, v67, s[6:7]
	v_fma_f32 v66, -v68, v66, v64
	v_cmp_lt_f32_e64 s[6:7], 0, v66
	s_nop 1
	v_cndmask_b32_e64 v66, v67, v68, s[6:7]
	v_mul_f32_e32 v67, 0x37800000, v66
	v_cndmask_b32_e32 v66, v66, v67, vcc
	v_cmp_class_f32_e32 vcc, v64, v222
	s_nop 1
	v_cndmask_b32_e32 v64, v66, v64, vcc
	s_nop 0
	v_rcp_f32_e32 v67, v64
	s_nop 0
	v_fma_f32 v66, -v64, v67, 1.0
	v_fma_f32 v66, v66, v67, v67
	v_div_fixup_f32 v64, v66, v64, 1.0
	s_and_saveexec_b64 s[2:3], s[4:5]
	s_cbranch_execz .LBB0_3153
	v_mul_f32_e32 v66, 0x3a800000, v65
	v_mov_b32_e32 v67, v64
	global_store_dwordx2 v[156:157], v[66:67], off offset:24
	s_branch .LBB0_3153

; #define SBAR() __builtin_amdgcn_sched_barrier(0)
; DEVFI float dpp_xor1(float x) { return __int_as_float(__builtin_amdgcn_update_dpp(0, __float_as_int(x), 0xB1, 0xF, 0xF, true)); }
; #define QB ((bfraw*)(kargs()->ws + O_QB))
; DEVFI void store_nat_m(bfraw* base, long ld, f32x4 (&a)[8], int fr) {
;   const bool odd = fr & 1;
;   bfraw* p0 = base + (odd ? 15 + fr : fr);
; #pragma unroll
;   for (int j = 0; j < 4; ++j)
; #pragma unroll
;     for (int n0 = 0; n0 < 8; n0 += 2) { const float own0 = a[n0][j], own1 = a[n0 + 1][j];
;       const float recv = dpp_xor1(odd ? own0 : own1);
;       const unsigned pk = odd ? cvtpk(recv, own1) : cvtpk(own0, recv);
;       *reinterpret_cast<unsigned*>(p0 + (long)j * ld + n0 * 16) = pk; }
; }
; __global__ void __launch_bounds__(512) mega(Params p) {
;     ...
;             auto snorm = [&](f32x4 (&a)[8], const int m) {
; #pragma unroll
;               for (int j = 0; j < 4; ++j) { const int rr = rb + m * 16 + j; const float inv = 1.f / (red[512 + rr] + red[768 + rr]);
; #pragma unroll
;                 for (int n = 0; n < 8; ++n) a[n][j] *= inv; }
;               store_nat_m(QB + (long)(brow + rb + m * 16) * 1024 + hh * 256 + wc0, 1024, a, fr);
;               SBAR(); };
;             snorm(acc[0], 0); snorm(acc[1], 1); snorm(acc[2], 2); snorm(acc[3], 3);
.LBB0_3524:
	s_or_b64 exec, exec, s[2:3]
	s_waitcnt lgkmcnt(0)
	s_barrier
	ds_read_b128 v[0:3], v129 offset:2048
	ds_read_b128 v[4:7], v129 offset:3072
	s_waitcnt lgkmcnt(0)
	v_add_f32_e32 v0, v0, v4
	s_mov_b64 s[2:3], s[0:1]
	v_rcp_f32_e32 v8, v0
	s_nop 0
	v_fma_f32 v4, -v0, v8, 1.0
	v_fma_f32 v4, v4, v8, v8
	s_load_dwordx2 s[2:3], s[2:3], 0xe8
	v_div_fixup_f32 v0, v4, v0, 1.0
	v_and_b32_e32 v9, 1, v132
	v_mul_f32_e32 v8, v155, v0
	v_mul_f32_e32 v4, v156, v0
	v_cmp_eq_u32_e64 s[10:11], 0, v9
	v_cmp_eq_u32_e64 s[8:9], 1, v9
	s_nop 0
	v_cndmask_b32_e64 v9, v8, v4, s[10:11]
	s_nop 1
	v_mov_b32_dpp v9, v9 quad_perm:[1,0,3,2] row_mask:0xf bank_mask:0xf bound_ctrl:1
	s_and_saveexec_b64 s[20:21], s[8:9]
	s_xor_b64 s[20:21], exec, s[20:21]
	s_cbranch_execz .LBB0_3526
	v_cvt_pk_bf16_f32 v10, v9, v4

; #define SBAR() __builtin_amdgcn_sched_barrier(0)
; DEVFI float dpp_xor1(float x) { return __int_as_float(__builtin_amdgcn_update_dpp(0, __float_as_int(x), 0xB1, 0xF, 0xF, true)); }
; #define QB ((bfraw*)(kargs()->ws + O_QB))
; DEVFI void store_nat_m(bfraw* base, long ld, f32x4 (&a)[8], int fr) {
;   const bool odd = fr & 1;
;   bfraw* p0 = base + (odd ? 15 + fr : fr);
; #pragma unroll
;   for (int j = 0; j < 4; ++j)
; #pragma unroll
;     for (int n0 = 0; n0 < 8; n0 += 2) { const float own0 = a[n0][j], own1 = a[n0 + 1][j];
;       const float recv = dpp_xor1(odd ? own0 : own1);
;       const unsigned pk = odd ? cvtpk(recv, own1) : cvtpk(own0, recv);
;       *reinterpret_cast<unsigned*>(p0 + (long)j * ld + n0 * 16) = pk; }
; }
; __global__ void __launch_bounds__(512) mega(Params p) {
;     ...
;             auto snorm = [&](f32x4 (&a)[8], const int m) {
; #pragma unroll
;               for (int j = 0; j < 4; ++j) { const int rr = rb + m * 16 + j; const float inv = 1.f / (red[512 + rr] + red[768 + rr]);
; #pragma unroll
;                 for (int n = 0; n < 8; ++n) a[n][j] *= inv; }
;               store_nat_m(QB + (long)(brow + rb + m * 16) * 1024 + hh * 256 + wc0, 1024, a, fr);
;               SBAR(); };
;             snorm(acc[0], 0); snorm(acc[1], 1); snorm(acc[2], 2); snorm(acc[3], 3);
.LBB0_3536:
	s_or_b64 exec, exec, s[2:3]
	v_add_f32_e32 v1, v1, v5
	global_store_dword v[8:9], v11, off offset:128
	v_rcp_f32_e32 v10, v1
	s_nop 0
	v_fma_f32 v5, -v1, v10, 1.0
	v_fma_f32 v10, v5, v10, v10
	v_mov_b32_dpp v11, v23 quad_perm:[1,0,3,2] row_mask:0xf bank_mask:0xf bound_ctrl:1
	s_and_saveexec_b64 s[2:3], s[8:9]
	s_xor_b64 s[2:3], exec, s[2:3]
	s_cbranch_execz .LBB0_3538
	v_cvt_pk_bf16_f32 v5, v11, v0

; #define SBAR() __builtin_amdgcn_sched_barrier(0)
; DEVFI float dpp_xor1(float x) { return __int_as_float(__builtin_amdgcn_update_dpp(0, __float_as_int(x), 0xB1, 0xF, 0xF, true)); }
; #define QB ((bfraw*)(kargs()->ws + O_QB))
; DEVFI void store_nat_m(bfraw* base, long ld, f32x4 (&a)[8], int fr) {
;   const bool odd = fr & 1;
;   bfraw* p0 = base + (odd ? 15 + fr : fr);
; #pragma unroll
;   for (int j = 0; j < 4; ++j)
; #pragma unroll
;     for (int n0 = 0; n0 < 8; n0 += 2) { const float own0 = a[n0][j], own1 = a[n0 + 1][j];
;       const float recv = dpp_xor1(odd ? own0 : own1);
;       const unsigned pk = odd ? cvtpk(recv, own1) : cvtpk(own0, recv);
;       *reinterpret_cast<unsigned*>(p0 + (long)j * ld + n0 * 16) = pk; }
; }
; __global__ void __launch_bounds__(512) mega(Params p) {
;     ...
;             auto snorm = [&](f32x4 (&a)[8], const int m) {
; #pragma unroll
;               for (int j = 0; j < 4; ++j) { const int rr = rb + m * 16 + j; const float inv = 1.f / (red[512 + rr] + red[768 + rr]);
; #pragma unroll
;                 for (int n = 0; n < 8; ++n) a[n][j] *= inv; }
;               store_nat_m(QB + (long)(brow + rb + m * 16) * 1024 + hh * 256 + wc0, 1024, a, fr);
;               SBAR(); };
;             snorm(acc[0], 0); snorm(acc[1], 1); snorm(acc[2], 2); snorm(acc[3], 3);
.LBB0_3552:
	s_or_b64 exec, exec, s[2:3]
	v_add_f32_e32 v2, v2, v6
	global_store_dword v[8:9], v4, off offset:2176
	v_rcp_f32_e32 v6, v2
	s_nop 0
	v_fma_f32 v5, -v2, v6, 1.0
	v_fma_f32 v5, v5, v6, v6
	v_mov_b32_dpp v6, v10 quad_perm:[1,0,3,2] row_mask:0xf bank_mask:0xf bound_ctrl:1
	s_and_saveexec_b64 s[2:3], s[8:9]
	s_xor_b64 s[2:3], exec, s[2:3]
	s_cbranch_execz .LBB0_3554
	v_cvt_pk_bf16_f32 v4, v6, v0

; #define SBAR() __builtin_amdgcn_sched_barrier(0)
; DEVFI float dpp_xor1(float x) { return __int_as_float(__builtin_amdgcn_update_dpp(0, __float_as_int(x), 0xB1, 0xF, 0xF, true)); }
; #define QB ((bfraw*)(kargs()->ws + O_QB))
; DEVFI void store_nat_m(bfraw* base, long ld, f32x4 (&a)[8], int fr) {
;   const bool odd = fr & 1;
;   bfraw* p0 = base + (odd ? 15 + fr : fr);
; #pragma unroll
;   for (int j = 0; j < 4; ++j)
; #pragma unroll
;     for (int n0 = 0; n0 < 8; n0 += 2) { const float own0 = a[n0][j], own1 = a[n0 + 1][j];
;       const float recv = dpp_xor1(odd ? own0 : own1);
;       const unsigned pk = odd ? cvtpk(recv, own1) : cvtpk(own0, recv);
;       *reinterpret_cast<unsigned*>(p0 + (long)j * ld + n0 * 16) = pk; }
; }
; __global__ void __launch_bounds__(512) mega(Params p) {
;     ...
;             auto snorm = [&](f32x4 (&a)[8], const int m) {
; #pragma unroll
;               for (int j = 0; j < 4; ++j) { const int rr = rb + m * 16 + j; const float inv = 1.f / (red[512 + rr] + red[768 + rr]);
; #pragma unroll
;                 for (int n = 0; n < 8; ++n) a[n][j] *= inv; }
;               store_nat_m(QB + (long)(brow + rb + m * 16) * 1024 + hh * 256 + wc0, 1024, a, fr);
;               SBAR(); };
;             snorm(acc[0], 0); snorm(acc[1], 1); snorm(acc[2], 2); snorm(acc[3], 3);
.LBB0_3568:
	s_or_b64 exec, exec, s[2:3]
	v_add_f32_e32 v3, v3, v7
	v_rcp_f32_e32 v6, v3
	s_nop 0
	v_fma_f32 v4, -v3, v6, 1.0
	v_fma_f32 v6, v4, v6, v6
	v_add_co_u32_e32 v10, vcc, 0x1000, v8
	v_mov_b32_dpp v7, v5 quad_perm:[1,0,3,2] row_mask:0xf bank_mask:0xf bound_ctrl:1
	s_nop 0
	v_addc_co_u32_e32 v11, vcc, 0, v9, vcc
	global_store_dword v[10:11], v2, off offset:128
	s_and_saveexec_b64 s[2:3], s[8:9]
	s_xor_b64 s[2:3], exec, s[2:3]
	s_cbranch_execz .LBB0_3570
	v_cvt_pk_bf16_f32 v4, v7, v0

; #define SBAR() __builtin_amdgcn_sched_barrier(0)
; DEVFI float dpp_xor1(float x) { return __int_as_float(__builtin_amdgcn_update_dpp(0, __float_as_int(x), 0xB1, 0xF, 0xF, true)); }
; #define QB ((bfraw*)(kargs()->ws + O_QB))
; DEVFI void store_nat_m(bfraw* base, long ld, f32x4 (&a)[8], int fr) {
;   const bool odd = fr & 1;
;   bfraw* p0 = base + (odd ? 15 + fr : fr);
; #pragma unroll
;   for (int j = 0; j < 4; ++j)
; #pragma unroll
;     for (int n0 = 0; n0 < 8; n0 += 2) { const float own0 = a[n0][j], own1 = a[n0 + 1][j];
;       const float recv = dpp_xor1(odd ? own0 : own1);
;       const unsigned pk = odd ? cvtpk(recv, own1) : cvtpk(own0, recv);
;       *reinterpret_cast<unsigned*>(p0 + (long)j * ld + n0 * 16) = pk; }
; }
; __global__ void __launch_bounds__(512) mega(Params p) {
;     ...
;             auto snorm = [&](f32x4 (&a)[8], const int m) {
; #pragma unroll
;               for (int j = 0; j < 4; ++j) { const int rr = rb + m * 16 + j; const float inv = 1.f / (red[512 + rr] + red[768 + rr]);
; #pragma unroll
;                 for (int n = 0; n < 8; ++n) a[n][j] *= inv; }
;               store_nat_m(QB + (long)(brow + rb + m * 16) * 1024 + hh * 256 + wc0, 1024, a, fr);
;               SBAR(); };
;             snorm(acc[0], 0); snorm(acc[1], 1); snorm(acc[2], 2); snorm(acc[3], 3);
.LBB0_3584:
	s_or_b64 exec, exec, s[2:3]
	v_add_co_u32_e32 v6, vcc, 0x1000, v8
	s_nop 1
	v_addc_co_u32_e32 v7, vcc, 0, v9, vcc
	global_store_dword v[6:7], v3, off offset:2176
	v_mov_b32_dpp v3, v4 quad_perm:[1,0,3,2] row_mask:0xf bank_mask:0xf bound_ctrl:1
	v_cndmask_b32_e64 v2, v1, v3, s[8:9]
	v_cndmask_b32_e64 v3, v3, v0, s[8:9]
	v_cvt_pk_bf16_f32 v2, v2, v3
	v_add_co_u32_e32 v0, vcc, 0x1000, v8
	s_nop 1
	v_addc_co_u32_e32 v1, vcc, 0, v9, vcc
	global_store_dword v[0:1], v2, off offset:2240
	ds_read_b128 v[0:3], v129 offset:2112
	ds_read_b128 v[4:7], v129 offset:3136
	s_mov_b64 s[2:3], s[0:1]
	s_load_dwordx2 s[2:3], s[2:3], 0xe8
	s_waitcnt lgkmcnt(0)
	v_add_f32_e32 v0, v0, v4
	v_rcp_f32_e32 v8, v0
	s_nop 0
	v_fma_f32 v4, -v0, v8, 1.0
	v_fma_f32 v4, v4, v8, v8
	v_div_fixup_f32 v0, v4, v0, 1.0
	v_mul_f32_e32 v8, v115, v0
	v_mul_f32_e32 v4, v116, v0
	v_cndmask_b32_e64 v9, v8, v4, s[10:11]
	s_nop 1
	v_mov_b32_dpp v9, v9 quad_perm:[1,0,3,2] row_mask:0xf bank_mask:0xf bound_ctrl:1
	s_and_saveexec_b64 s[20:21], s[8:9]
	s_xor_b64 s[20:21], exec, s[20:21]
	s_cbranch_execz .LBB0_3590
	v_cvt_pk_bf16_f32 v19, v9, v4

; #define SBAR() __builtin_amdgcn_sched_barrier(0)
; DEVFI float dpp_xor1(float x) { return __int_as_float(__builtin_amdgcn_update_dpp(0, __float_as_int(x), 0xB1, 0xF, 0xF, true)); }
; #define QB ((bfraw*)(kargs()->ws + O_QB))
; DEVFI void store_nat_m(bfraw* base, long ld, f32x4 (&a)[8], int fr) {
;   const bool odd = fr & 1;
;   bfraw* p0 = base + (odd ? 15 + fr : fr);
; #pragma unroll
;   for (int j = 0; j < 4; ++j)
; #pragma unroll
;     for (int n0 = 0; n0 < 8; n0 += 2) { const float own0 = a[n0][j], own1 = a[n0 + 1][j];
;       const float recv = dpp_xor1(odd ? own0 : own1);
;       const unsigned pk = odd ? cvtpk(recv, own1) : cvtpk(own0, recv);
;       *reinterpret_cast<unsigned*>(p0 + (long)j * ld + n0 * 16) = pk; }
; }
; __global__ void __launch_bounds__(512) mega(Params p) {
;     ...
;             auto snorm = [&](f32x4 (&a)[8], const int m) {
; #pragma unroll
;               for (int j = 0; j < 4; ++j) { const int rr = rb + m * 16 + j; const float inv = 1.f / (red[512 + rr] + red[768 + rr]);
; #pragma unroll
;                 for (int n = 0; n < 8; ++n) a[n][j] *= inv; }
;               store_nat_m(QB + (long)(brow + rb + m * 16) * 1024 + hh * 256 + wc0, 1024, a, fr);
;               SBAR(); };
;             snorm(acc[0], 0); snorm(acc[1], 1); snorm(acc[2], 2); snorm(acc[3], 3);
.LBB0_3600:
	s_or_b64 exec, exec, s[2:3]
	v_add_f32_e32 v1, v1, v5
	global_store_dword v[10:11], v19, off offset:128
	v_rcp_f32_e32 v9, v1
	s_nop 0
	v_fma_f32 v5, -v1, v9, 1.0
	v_fma_f32 v9, v5, v9, v9
	v_mov_b32_dpp v19, v23 quad_perm:[1,0,3,2] row_mask:0xf bank_mask:0xf bound_ctrl:1
	s_and_saveexec_b64 s[2:3], s[8:9]
	s_xor_b64 s[2:3], exec, s[2:3]
	s_cbranch_execz .LBB0_3602
	v_cvt_pk_bf16_f32 v5, v19, v0

; #define SBAR() __builtin_amdgcn_sched_barrier(0)
; DEVFI float dpp_xor1(float x) { return __int_as_float(__builtin_amdgcn_update_dpp(0, __float_as_int(x), 0xB1, 0xF, 0xF, true)); }
; #define QB ((bfraw*)(kargs()->ws + O_QB))
; DEVFI void store_nat_m(bfraw* base, long ld, f32x4 (&a)[8], int fr) {
;   const bool odd = fr & 1;
;   bfraw* p0 = base + (odd ? 15 + fr : fr);
; #pragma unroll
;   for (int j = 0; j < 4; ++j)
; #pragma unroll
;     for (int n0 = 0; n0 < 8; n0 += 2) { const float own0 = a[n0][j], own1 = a[n0 + 1][j];
;       const float recv = dpp_xor1(odd ? own0 : own1);
;       const unsigned pk = odd ? cvtpk(recv, own1) : cvtpk(own0, recv);
;       *reinterpret_cast<unsigned*>(p0 + (long)j * ld + n0 * 16) = pk; }
; }
; __global__ void __launch_bounds__(512) mega(Params p) {
;     ...
;             auto snorm = [&](f32x4 (&a)[8], const int m) {
; #pragma unroll
;               for (int j = 0; j < 4; ++j) { const int rr = rb + m * 16 + j; const float inv = 1.f / (red[512 + rr] + red[768 + rr]);
; #pragma unroll
;                 for (int n = 0; n < 8; ++n) a[n][j] *= inv; }
;               store_nat_m(QB + (long)(brow + rb + m * 16) * 1024 + hh * 256 + wc0, 1024, a, fr);
;               SBAR(); };
;             snorm(acc[0], 0); snorm(acc[1], 1); snorm(acc[2], 2); snorm(acc[3], 3);
.LBB0_3616:
	s_or_b64 exec, exec, s[2:3]
	v_add_f32_e32 v2, v2, v6
	global_store_dword v[10:11], v4, off offset:2176
	v_rcp_f32_e32 v6, v2
	s_nop 0
	v_fma_f32 v5, -v2, v6, 1.0
	v_fma_f32 v5, v5, v6, v6
	v_mov_b32_dpp v6, v9 quad_perm:[1,0,3,2] row_mask:0xf bank_mask:0xf bound_ctrl:1
	s_and_saveexec_b64 s[2:3], s[8:9]
	s_xor_b64 s[2:3], exec, s[2:3]
	s_cbranch_execz .LBB0_3618
	v_cvt_pk_bf16_f32 v4, v6, v0

; #define SBAR() __builtin_amdgcn_sched_barrier(0)
; DEVFI float dpp_xor1(float x) { return __int_as_float(__builtin_amdgcn_update_dpp(0, __float_as_int(x), 0xB1, 0xF, 0xF, true)); }
; #define QB ((bfraw*)(kargs()->ws + O_QB))
; DEVFI void store_nat_m(bfraw* base, long ld, f32x4 (&a)[8], int fr) {
;   const bool odd = fr & 1;
;   bfraw* p0 = base + (odd ? 15 + fr : fr);
; #pragma unroll
;   for (int j = 0; j < 4; ++j)
; #pragma unroll
;     for (int n0 = 0; n0 < 8; n0 += 2) { const float own0 = a[n0][j], own1 = a[n0 + 1][j];
;       const float recv = dpp_xor1(odd ? own0 : own1);
;       const unsigned pk = odd ? cvtpk(recv, own1) : cvtpk(own0, recv);
;       *reinterpret_cast<unsigned*>(p0 + (long)j * ld + n0 * 16) = pk; }
; }
; __global__ void __launch_bounds__(512) mega(Params p) {
;     ...
;             auto snorm = [&](f32x4 (&a)[8], const int m) {
; #pragma unroll
;               for (int j = 0; j < 4; ++j) { const int rr = rb + m * 16 + j; const float inv = 1.f / (red[512 + rr] + red[768 + rr]);
; #pragma unroll
;                 for (int n = 0; n < 8; ++n) a[n][j] *= inv; }
;               store_nat_m(QB + (long)(brow + rb + m * 16) * 1024 + hh * 256 + wc0, 1024, a, fr);
;               SBAR(); };
;             snorm(acc[0], 0); snorm(acc[1], 1); snorm(acc[2], 2); snorm(acc[3], 3);
.LBB0_3632:
	s_or_b64 exec, exec, s[2:3]
	v_add_f32_e32 v3, v3, v7
	v_rcp_f32_e32 v6, v3
	s_nop 0
	v_fma_f32 v4, -v3, v6, 1.0
	v_fma_f32 v6, v4, v6, v6
	v_add_co_u32_e32 v92, vcc, 0x1000, v10
	v_mov_b32_dpp v7, v5 quad_perm:[1,0,3,2] row_mask:0xf bank_mask:0xf bound_ctrl:1
	s_nop 0
	v_addc_co_u32_e32 v93, vcc, 0, v11, vcc
	global_store_dword v[92:93], v2, off offset:128
	s_and_saveexec_b64 s[2:3], s[8:9]
	s_xor_b64 s[2:3], exec, s[2:3]
	s_cbranch_execz .LBB0_3634
	v_cvt_pk_bf16_f32 v4, v7, v0

; #define SBAR() __builtin_amdgcn_sched_barrier(0)
; DEVFI float dpp_xor1(float x) { return __int_as_float(__builtin_amdgcn_update_dpp(0, __float_as_int(x), 0xB1, 0xF, 0xF, true)); }
; #define QB ((bfraw*)(kargs()->ws + O_QB))
; DEVFI void store_nat_m(bfraw* base, long ld, f32x4 (&a)[8], int fr) {
;   const bool odd = fr & 1;
;   bfraw* p0 = base + (odd ? 15 + fr : fr);
; #pragma unroll
;   for (int j = 0; j < 4; ++j)
; #pragma unroll
;     for (int n0 = 0; n0 < 8; n0 += 2) { const float own0 = a[n0][j], own1 = a[n0 + 1][j];
;       const float recv = dpp_xor1(odd ? own0 : own1);
;       const unsigned pk = odd ? cvtpk(recv, own1) : cvtpk(own0, recv);
;       *reinterpret_cast<unsigned*>(p0 + (long)j * ld + n0 * 16) = pk; }
; }
; __global__ void __launch_bounds__(512) mega(Params p) {
;     ...
;             auto snorm = [&](f32x4 (&a)[8], const int m) {
; #pragma unroll
;               for (int j = 0; j < 4; ++j) { const int rr = rb + m * 16 + j; const float inv = 1.f / (red[512 + rr] + red[768 + rr]);
; #pragma unroll
;                 for (int n = 0; n < 8; ++n) a[n][j] *= inv; }
;               store_nat_m(QB + (long)(brow + rb + m * 16) * 1024 + hh * 256 + wc0, 1024, a, fr);
;               SBAR(); };
;             snorm(acc[0], 0); snorm(acc[1], 1); snorm(acc[2], 2); snorm(acc[3], 3);
.LBB0_3648:
	s_or_b64 exec, exec, s[2:3]
	v_add_co_u32_e32 v6, vcc, 0x1000, v10
	s_nop 1
	v_addc_co_u32_e32 v7, vcc, 0, v11, vcc
	global_store_dword v[6:7], v3, off offset:2176
	v_mov_b32_dpp v3, v4 quad_perm:[1,0,3,2] row_mask:0xf bank_mask:0xf bound_ctrl:1
	v_cndmask_b32_e64 v2, v1, v3, s[8:9]
	v_cndmask_b32_e64 v3, v3, v0, s[8:9]
	v_cvt_pk_bf16_f32 v2, v2, v3
	v_add_co_u32_e32 v0, vcc, 0x1000, v10
	s_nop 1
	v_addc_co_u32_e32 v1, vcc, 0, v11, vcc
	global_store_dword v[0:1], v2, off offset:2240
	ds_read_b128 v[0:3], v129 offset:2176
	ds_read_b128 v[4:7], v129 offset:3200
	s_mov_b64 s[2:3], s[0:1]
	s_load_dwordx2 s[2:3], s[2:3], 0xe8
	s_waitcnt lgkmcnt(0)
	v_add_f32_e32 v0, v0, v4
	v_rcp_f32_e32 v9, v0
	s_nop 0
	v_fma_f32 v4, -v0, v9, 1.0
	v_fma_f32 v4, v4, v9, v9
	v_div_fixup_f32 v0, v4, v0, 1.0
	v_mul_f32_e32 v9, v81, v0
	v_mul_f32_e32 v4, v82, v0
	v_cndmask_b32_e64 v10, v9, v4, s[10:11]
	s_nop 1
	v_mov_b32_dpp v10, v10 quad_perm:[1,0,3,2] row_mask:0xf bank_mask:0xf bound_ctrl:1
	s_and_saveexec_b64 s[20:21], s[8:9]
	s_xor_b64 s[20:21], exec, s[20:21]
	s_cbranch_execz .LBB0_3654
	v_cvt_pk_bf16_f32 v19, v10, v4

; #define SBAR() __builtin_amdgcn_sched_barrier(0)
; DEVFI float dpp_xor1(float x) { return __int_as_float(__builtin_amdgcn_update_dpp(0, __float_as_int(x), 0xB1, 0xF, 0xF, true)); }
; #define QB ((bfraw*)(kargs()->ws + O_QB))
; DEVFI void store_nat_m(bfraw* base, long ld, f32x4 (&a)[8], int fr) {
;   const bool odd = fr & 1;
;   bfraw* p0 = base + (odd ? 15 + fr : fr);
; #pragma unroll
;   for (int j = 0; j < 4; ++j)
; #pragma unroll
;     for (int n0 = 0; n0 < 8; n0 += 2) { const float own0 = a[n0][j], own1 = a[n0 + 1][j];
;       const float recv = dpp_xor1(odd ? own0 : own1);
;       const unsigned pk = odd ? cvtpk(recv, own1) : cvtpk(own0, recv);
;       *reinterpret_cast<unsigned*>(p0 + (long)j * ld + n0 * 16) = pk; }
; }
; __global__ void __launch_bounds__(512) mega(Params p) {
;     ...
;             auto snorm = [&](f32x4 (&a)[8], const int m) {
; #pragma unroll
;               for (int j = 0; j < 4; ++j) { const int rr = rb + m * 16 + j; const float inv = 1.f / (red[512 + rr] + red[768 + rr]);
; #pragma unroll
;                 for (int n = 0; n < 8; ++n) a[n][j] *= inv; }
;               store_nat_m(QB + (long)(brow + rb + m * 16) * 1024 + hh * 256 + wc0, 1024, a, fr);
;               SBAR(); };
;             snorm(acc[0], 0); snorm(acc[1], 1); snorm(acc[2], 2); snorm(acc[3], 3);
.LBB0_3696:
	s_or_b64 exec, exec, s[2:3]
	v_add_f32_e32 v3, v3, v7
	v_rcp_f32_e32 v6, v3
	s_nop 0
	v_fma_f32 v4, -v3, v6, 1.0
	v_fma_f32 v6, v4, v6, v6
	v_add_co_u32_e32 v58, vcc, 0x1000, v10
	v_mov_b32_dpp v7, v5 quad_perm:[1,0,3,2] row_mask:0xf bank_mask:0xf bound_ctrl:1
	s_nop 0
	v_addc_co_u32_e32 v59, vcc, 0, v11, vcc
	global_store_dword v[58:59], v2, off offset:128
	s_and_saveexec_b64 s[2:3], s[8:9]
	s_xor_b64 s[2:3], exec, s[2:3]
	s_cbranch_execz .LBB0_3698
	v_cvt_pk_bf16_f32 v4, v7, v0

; #define SBAR() __builtin_amdgcn_sched_barrier(0)
; DEVFI float dpp_xor1(float x) { return __int_as_float(__builtin_amdgcn_update_dpp(0, __float_as_int(x), 0xB1, 0xF, 0xF, true)); }
; #define QB ((bfraw*)(kargs()->ws + O_QB))
; DEVFI void store_nat_m(bfraw* base, long ld, f32x4 (&a)[8], int fr) {
;   const bool odd = fr & 1;
;   bfraw* p0 = base + (odd ? 15 + fr : fr);
; #pragma unroll
;   for (int j = 0; j < 4; ++j)
; #pragma unroll
;     for (int n0 = 0; n0 < 8; n0 += 2) { const float own0 = a[n0][j], own1 = a[n0 + 1][j];
;       const float recv = dpp_xor1(odd ? own0 : own1);
;       const unsigned pk = odd ? cvtpk(recv, own1) : cvtpk(own0, recv);
;       *reinterpret_cast<unsigned*>(p0 + (long)j * ld + n0 * 16) = pk; }
; }
; __global__ void __launch_bounds__(512) mega(Params p) {
;     ...
;             auto snorm = [&](f32x4 (&a)[8], const int m) {
; #pragma unroll
;               for (int j = 0; j < 4; ++j) { const int rr = rb + m * 16 + j; const float inv = 1.f / (red[512 + rr] + red[768 + rr]);
; #pragma unroll
;                 for (int n = 0; n < 8; ++n) a[n][j] *= inv; }
;               store_nat_m(QB + (long)(brow + rb + m * 16) * 1024 + hh * 256 + wc0, 1024, a, fr);
;               SBAR(); };
;             snorm(acc[0], 0); snorm(acc[1], 1); snorm(acc[2], 2); snorm(acc[3], 3);
.LBB0_3712:
	s_or_b64 exec, exec, s[2:3]
	v_add_co_u32_e32 v6, vcc, 0x1000, v10
	s_nop 1
	v_addc_co_u32_e32 v7, vcc, 0, v11, vcc
	global_store_dword v[6:7], v3, off offset:2176
	v_mov_b32_dpp v3, v4 quad_perm:[1,0,3,2] row_mask:0xf bank_mask:0xf bound_ctrl:1
	v_cndmask_b32_e64 v2, v1, v3, s[8:9]
	v_cndmask_b32_e64 v3, v3, v0, s[8:9]
	v_cvt_pk_bf16_f32 v2, v2, v3
	v_add_co_u32_e32 v0, vcc, 0x1000, v10
	s_nop 1
	v_addc_co_u32_e32 v1, vcc, 0, v11, vcc
	global_store_dword v[0:1], v2, off offset:2240
	ds_read_b128 v[0:3], v129 offset:2240
	ds_read_b128 v[4:7], v129 offset:3264
	s_mov_b64 s[2:3], s[0:1]
	s_load_dwordx2 s[2:3], s[2:3], 0xe8
	s_waitcnt lgkmcnt(0)
	v_add_f32_e32 v0, v0, v4
	v_rcp_f32_e32 v9, v0
	s_nop 0
	v_fma_f32 v4, -v0, v9, 1.0
	v_fma_f32 v4, v4, v9, v9
	v_div_fixup_f32 v0, v4, v0, 1.0
	v_mul_f32_e32 v9, v46, v0
	v_mul_f32_e32 v4, v47, v0
	v_cndmask_b32_e64 v10, v9, v4, s[10:11]
	s_nop 1
	v_mov_b32_dpp v23, v10 quad_perm:[1,0,3,2] row_mask:0xf bank_mask:0xf bound_ctrl:1
	s_and_saveexec_b64 s[10:11], s[8:9]
	s_xor_b64 s[10:11], exec, s[10:11]
	s_cbranch_execz .LBB0_3718
	v_cvt_pk_bf16_f32 v10, v23, v4

; DEVFI void ln_resid4(const float* ysrc, float* ydst, bfraw* fb, float* stats, const float* pw, const float* pb,
;                      const float* w, const float* b, int lane, bool fin) {
;   f32x4 v[4][4];
; #pragma unroll
;   for (int r = 0; r < 4; ++r)
; #pragma unroll
;     for (int i = 0; i < 4; ++i) v[r][i] = __builtin_nontemporal_load((const f32x4*)(ysrc + r * 1024) + i * 64 + lane);
;   u32x2 fv[4][4];
; #pragma unroll
;   for (int r = 0; r < 4; ++r)
; #pragma unroll
;     for (int i = 0; i < 4; ++i) fv[r][i] = __builtin_nontemporal_load((const u32x2*)(fb + r * 1024) + i * 64 + lane);
;   f32x4 pwv[4], pbv[4], ww[4], bb[4];
; #pragma unroll
;   for (int i = 0; i < 4; ++i) { pwv[i] = ((const f32x4*)pw)[i * 64 + lane]; pbv[i] = ((const f32x4*)pb)[i * 64 + lane];
;     ww[i] = ((const f32x4*)w)[i * 64 + lane]; bb[i] = ((const f32x4*)b)[i * 64 + lane]; }
; #pragma unroll
;   for (int r = 0; r < 4; ++r) {
;     const float pmu = stats[r * 2], prs = stats[r * 2 + 1];
;     f32x4 y[4];
; #pragma unroll
;     for (int i = 0; i < 4; ++i) { const unsigned f0 = fv[r][i][0], f1 = fv[r][i][1];
;       const f32x4 f4 = {__uint_as_float(f0 << 16), __uint_as_float(f0 & 0xffff0000u), __uint_as_float(f1 << 16), __uint_as_float(f1 & 0xffff0000u)};
;       y[i] = ALPHA * ((v[r][i] - pmu) * prs * pwv[i] + pbv[i]) + f4; }
;     float s = 0;
; #pragma unroll
;     for (int i = 0; i < 4; ++i) s += y[i][0] + y[i][1] + y[i][2] + y[i][3];
;     const float mean = red64(s) * (1.f / 1024.f);
.LBB0_4340:
	v_add_co_u32_e32 v0, vcc, 0x1000, v142
	global_load_dwordx4 v[124:127], v[142:143], off nt
	global_load_dwordx4 v[120:123], v[142:143], off offset:1024 nt
	global_load_dwordx4 v[116:119], v[142:143], off offset:2048 nt
	global_load_dwordx4 v[112:115], v[142:143], off offset:3072 nt
	v_addc_co_u32_e32 v1, vcc, 0, v143, vcc
	global_load_dwordx4 v[108:111], v[0:1], off nt
	global_load_dwordx4 v[104:107], v[0:1], off offset:1024 nt
	global_load_dwordx4 v[100:103], v[0:1], off offset:2048 nt
	global_load_dwordx4 v[96:99], v[0:1], off offset:3072 nt
	v_add_co_u32_e32 v0, vcc, s53, v142
	s_movk_i32 s2, 0x3000
	s_nop 0
	v_addc_co_u32_e32 v1, vcc, 0, v143, vcc
	v_add_co_u32_e32 v2, vcc, s2, v142
	s_mov_b32 s2, -1
	s_nop 0
	v_addc_co_u32_e32 v3, vcc, 0, v143, vcc
	global_load_dwordx4 v[92:95], v[2:3], off offset:-4096 nt
	global_load_dwordx4 v[88:91], v[0:1], off offset:1024 nt
	global_load_dwordx4 v[84:87], v[0:1], off offset:2048 nt
	global_load_dwordx4 v[80:83], v[0:1], off offset:3072 nt
	global_load_dwordx4 v[44:47], v[2:3], off nt
	global_load_dwordx4 v[40:43], v[2:3], off offset:1024 nt
	global_load_dwordx4 v[36:39], v[2:3], off offset:2048 nt
	global_load_dwordx4 v[32:35], v[2:3], off offset:3072 nt
	global_load_dwordx2 v[174:175], v[138:139], off nt
	global_load_dwordx2 v[172:173], v[138:139], off offset:512 nt
	global_load_dwordx2 v[170:171], v[138:139], off offset:1024 nt
	global_load_dwordx2 v[168:169], v[138:139], off offset:1536 nt
	global_load_dwordx2 v[166:167], v[138:139], off offset:2048 nt
	global_load_dwordx2 v[164:165], v[138:139], off offset:2560 nt
	global_load_dwordx2 v[162:163], v[138:139], off offset:3072 nt
	global_load_dwordx2 v[160:161], v[138:139], off offset:3584 nt
	v_add_co_u32_e32 v0, vcc, s56, v138
	v_mov_b32_e32 v192, 0x10000
	s_nop 0
	v_addc_co_u32_e32 v1, vcc, 0, v139, vcc
	global_load_dwordx2 v[158:159], v[0:1], off nt
	global_load_dwordx2 v[156:157], v[0:1], off offset:512 nt
	global_load_dwordx2 v[154:155], v[0:1], off offset:1024 nt
	global_load_dwordx2 v[152:153], v[0:1], off offset:1536 nt
	global_load_dwordx2 v[150:151], v[0:1], off offset:2048 nt
	global_load_dwordx2 v[148:149], v[0:1], off offset:2560 nt
	global_load_dwordx2 v[146:147], v[0:1], off offset:3072 nt
	global_load_dwordx2 v[144:145], v[0:1], off offset:3584 nt
	global_load_dwordx4 v[56:59], v[130:131], off
	global_load_dwordx4 v[60:63], v[132:133], off
	global_load_dwordx4 v[24:27], v[134:135], off
	global_load_dwordx4 v[28:31], v[136:137], off
	global_load_dwordx4 v[64:67], v[130:131], off offset:1024
	global_load_dwordx4 v[68:71], v[132:133], off offset:1024
	global_load_dwordx4 v[16:19], v[134:135], off offset:1024
	global_load_dwordx4 v[20:23], v[136:137], off offset:1024
	global_load_dwordx4 v[72:75], v[130:131], off offset:2048
	global_load_dwordx4 v[76:79], v[132:133], off offset:2048
	global_load_dwordx4 v[8:11], v[134:135], off offset:2048
	global_load_dwordx4 v[12:15], v[136:137], off offset:2048
	global_load_dwordx4 v[48:51], v[130:131], off offset:3072
	global_load_dwordx4 v[52:55], v[132:133], off offset:3072
	global_load_dwordx4 v[0:3], v[134:135], off offset:3072
	global_load_dwordx4 v[4:7], v[136:137], off offset:3072
	global_load_dwordx2 v[184:185], v[140:141], off
	s_waitcnt vmcnt(32)
	v_lshlrev_b32_e32 v178, 16, v174
	v_and_b32_e32 v179, 0xffff0000, v174
	v_lshlrev_b32_e32 v174, 16, v175
	v_and_b32_e32 v175, 0xffff0000, v175
	s_waitcnt vmcnt(0)
	v_sub_f32_e32 v127, v127, v184
	v_sub_f32_e32 v126, v126, v184
	v_pk_mul_f32 v[126:127], v[184:185], v[126:127] op_sel:[1,0]
	v_sub_f32_e32 v123, v123, v184
	v_sub_f32_e32 v122, v122, v184
	v_sub_f32_e32 v125, v125, v184
	v_sub_f32_e32 v124, v124, v184
	v_pk_fma_f32 v[126:127], v[58:59], v[126:127], v[62:63]
	v_sub_f32_e32 v121, v121, v184
	v_sub_f32_e32 v120, v120, v184
	v_pk_mul_f32 v[122:123], v[184:185], v[122:123] op_sel:[1,0]
	v_sub_f32_e32 v119, v119, v184
	v_sub_f32_e32 v118, v118, v184
	v_pk_mul_f32 v[124:125], v[184:185], v[124:125] op_sel:[1,0]
	v_pk_fma_f32 v[126:127], v[126:127], s[52:53], v[174:175] op_sel_hi:[1,0,1]
	v_lshlrev_b32_e32 v174, 16, v172
	v_and_b32_e32 v175, 0xffff0000, v172
	v_lshlrev_b32_e32 v172, 16, v173
	v_and_b32_e32 v173, 0xffff0000, v173
	v_pk_mul_f32 v[120:121], v[184:185], v[120:121] op_sel:[1,0]
	v_pk_fma_f32 v[122:123], v[66:67], v[122:123], v[70:71]
	v_pk_mul_f32 v[118:119], v[184:185], v[118:119] op_sel:[1,0]
	v_sub_f32_e32 v113, v113, v184
	v_sub_f32_e32 v112, v112, v184
	v_sub_f32_e32 v115, v115, v184
	v_sub_f32_e32 v114, v114, v184
	v_pk_fma_f32 v[124:125], v[56:57], v[124:125], v[60:61]
	v_pk_fma_f32 v[120:121], v[64:65], v[120:121], v[68:69]
	v_pk_fma_f32 v[122:123], v[122:123], s[52:53], v[172:173] op_sel_hi:[1,0,1]
	v_lshlrev_b32_e32 v172, 16, v170
	v_and_b32_e32 v173, 0xffff0000, v170
	v_lshlrev_b32_e32 v170, 16, v171
	v_and_b32_e32 v171, 0xffff0000, v171
	v_pk_fma_f32 v[118:119], v[74:75], v[118:119], v[78:79]
	v_pk_mul_f32 v[114:115], v[184:185], v[114:115] op_sel:[1,0]
	v_pk_mul_f32 v[112:113], v[184:185], v[112:113] op_sel:[1,0]
	v_pk_fma_f32 v[124:125], v[124:125], s[52:53], v[178:179] op_sel_hi:[1,0,1]
	v_pk_fma_f32 v[120:121], v[120:121], s[52:53], v[174:175] op_sel_hi:[1,0,1]
	v_pk_fma_f32 v[118:119], v[118:119], s[52:53], v[170:171] op_sel_hi:[1,0,1]
	v_lshlrev_b32_e32 v170, 16, v168
	v_and_b32_e32 v171, 0xffff0000, v168
	v_lshlrev_b32_e32 v168, 16, v169
	v_and_b32_e32 v169, 0xffff0000, v169
	v_pk_fma_f32 v[112:113], v[48:49], v[112:113], v[52:53]
	v_pk_fma_f32 v[114:115], v[50:51], v[114:115], v[54:55]
	v_pk_fma_f32 v[112:113], v[112:113], s[52:53], v[170:171] op_sel_hi:[1,0,1]
	v_pk_fma_f32 v[114:115], v[114:115], s[52:53], v[168:169] op_sel_hi:[1,0,1]
	v_mov_b32_e32 v168, v120
	v_mov_b32_e32 v169, v124
	v_mov_b32_e32 v170, v121
	v_mov_b32_e32 v171, v125
	v_sub_f32_e32 v117, v117, v184
	v_sub_f32_e32 v116, v116, v184
	v_pk_add_f32 v[168:169], v[168:169], v[170:171]
	v_mov_b32_e32 v170, v122
	v_mov_b32_e32 v171, v126
	v_pk_mul_f32 v[116:117], v[184:185], v[116:117] op_sel:[1,0]
	v_pk_add_f32 v[168:169], v[170:171], v[168:169]
	v_mov_b32_e32 v170, v123
	v_mov_b32_e32 v171, v127
	v_pk_fma_f32 v[116:117], v[72:73], v[116:117], v[76:77]
	v_pk_add_f32 v[168:169], v[170:171], v[168:169]
	v_pk_fma_f32 v[116:117], v[116:117], s[52:53], v[172:173] op_sel_hi:[1,0,1]
	v_add_f32_e32 v129, 0, v169
	v_add_f32_e32 v129, v168, v129
	v_mov_b32_e32 v168, v112
	v_mov_b32_e32 v169, v116
	v_mov_b32_e32 v170, v113
	v_mov_b32_e32 v171, v117
	v_pk_add_f32 v[168:169], v[168:169], v[170:171]
	v_mov_b32_e32 v170, v114
	v_mov_b32_e32 v171, v118
	v_pk_add_f32 v[168:169], v[170:171], v[168:169]
	v_mov_b32_e32 v170, v115
	v_mov_b32_e32 v171, v119
	v_pk_add_f32 v[168:169], v[170:171], v[168:169]
	s_nop 0
	v_add_f32_e32 v129, v169, v129
	v_add_f32_e32 v129, v168, v129
	v_mbcnt_lo_u32_b32 v168, s2, 0
	v_mbcnt_hi_u32_b32 v168, s2, v168
	v_lshlrev_b32_e32 v168, 2, v168
	v_xor_b32_e32 v169, 0x80, v168
	ds_bpermute_b32 v169, v169, v129
	s_mov_b32 s2, -1
	s_waitcnt lgkmcnt(0)
; DEVFI void ln_resid4(const float* ysrc, float* ydst, bfraw* fb, float* stats, const float* pw, const float* pb,
;                      const float* w, const float* b, int lane, bool fin) {
;     ...
;     float s = 0;
; #pragma unroll
;     for (int i = 0; i < 4; ++i) s += y[i][0] + y[i][1] + y[i][2] + y[i][3];
;     const float mean = red64(s) * (1.f / 1024.f);
;     float q = 0;
; #pragma unroll
;     for (int i = 0; i < 4; ++i) { const f32x4 d = y[i] - mean; q += d[0] * d[0] + d[1] * d[1] + d[2] * d[2] + d[3] * d[3]; }
;     const float rstd = 1.f / sqrtf(red64(q) * (1.f / 1024.f) + LN_EPS);
;     if (lane == 0) { stats[r * 2] = mean; stats[r * 2 + 1] = rstd; }
; #pragma unroll
;     for (int i = 0; i < 4; ++i) { const int c4 = i * 64 + lane;
;       const f32x4 z = (y[i] - mean) * rstd * ww[i] + bb[i];
;       __builtin_nontemporal_store(fin ? z : y[i], (f32x4*)(ydst + r * 1024) + c4);
;       u32x2 pk = {cvtpk(z[0], z[1]), cvtpk(z[2], z[3])}; ((u32x2*)(fb + r * 1024))[c4] = pk; }
	v_add_f32_e32 v129, v129, v169
	v_xor_b32_e32 v169, 64, v168
	ds_bpermute_b32 v169, v169, v129
	s_waitcnt lgkmcnt(0)
	v_add_f32_e32 v129, v129, v169
	v_xor_b32_e32 v169, 32, v168
	ds_bpermute_b32 v169, v169, v129
	s_waitcnt lgkmcnt(0)
	v_add_f32_e32 v129, v129, v169
	v_xor_b32_e32 v169, 16, v168
	ds_bpermute_b32 v169, v169, v129
	s_waitcnt lgkmcnt(0)
	v_add_f32_e32 v129, v129, v169
	v_xor_b32_e32 v169, 8, v168
	ds_bpermute_b32 v169, v169, v129
	v_xor_b32_e32 v168, 4, v168
	s_waitcnt lgkmcnt(0)
	v_add_f32_e32 v129, v129, v169
	ds_bpermute_b32 v168, v168, v129
	s_waitcnt lgkmcnt(0)
	v_add_f32_e32 v129, v129, v168
	v_fmamk_f32 v191, v129, 0xba800000, v125
	v_fmamk_f32 v187, v129, 0xba800000, v121
	v_fmamk_f32 v190, v129, 0xba800000, v124
	v_mul_f32_e32 v168, v191, v191
	v_fmamk_f32 v186, v129, 0xba800000, v120
	v_mul_f32_e32 v169, v187, v187
	v_fmamk_f32 v188, v129, 0xba800000, v126
	v_fmac_f32_e32 v168, v190, v190
	v_fmamk_f32 v184, v129, 0xba800000, v122
	v_fmac_f32_e32 v169, v186, v186
	v_fmamk_f32 v189, v129, 0xba800000, v127
	v_fmac_f32_e32 v168, v188, v188
	v_fmamk_f32 v185, v129, 0xba800000, v123
	v_fmac_f32_e32 v169, v184, v184
	v_fmac_f32_e32 v168, v189, v189
	v_fmac_f32_e32 v169, v185, v185
	v_fmamk_f32 v175, v129, 0xba800000, v117
	v_add_f32_e32 v168, v168, v169
	v_fmamk_f32 v174, v129, 0xba800000, v116
	v_mul_f32_e32 v169, v175, v175
	v_fmamk_f32 v172, v129, 0xba800000, v118
	v_fmac_f32_e32 v169, v174, v174
	v_fmamk_f32 v173, v129, 0xba800000, v119
	v_fmac_f32_e32 v169, v172, v172
	v_fmamk_f32 v171, v129, 0xba800000, v113
	v_fmac_f32_e32 v169, v173, v173
	v_fmamk_f32 v170, v129, 0xba800000, v112
	v_mul_f32_e32 v178, v171, v171
	v_add_f32_e32 v176, v169, v168
	v_fmamk_f32 v168, v129, 0xba800000, v114
	v_fmac_f32_e32 v178, v170, v170
	v_fmamk_f32 v169, v129, 0xba800000, v115
	v_fmac_f32_e32 v178, v168, v168
	v_fmac_f32_e32 v178, v169, v169
	v_add_f32_e32 v176, v178, v176
	v_mbcnt_lo_u32_b32 v178, s2, 0
	v_mbcnt_hi_u32_b32 v178, s2, v178
	v_lshlrev_b32_e32 v178, 2, v178
	v_xor_b32_e32 v179, 0x80, v178
	ds_bpermute_b32 v179, v179, v176
	s_waitcnt lgkmcnt(0)
	v_add_f32_e32 v176, v176, v179
	v_xor_b32_e32 v179, 64, v178
	ds_bpermute_b32 v179, v179, v176
	s_waitcnt lgkmcnt(0)
	v_add_f32_e32 v176, v176, v179
	v_xor_b32_e32 v179, 32, v178
	ds_bpermute_b32 v179, v179, v176
	s_waitcnt lgkmcnt(0)
	v_add_f32_e32 v176, v176, v179
	v_xor_b32_e32 v179, 16, v178
	ds_bpermute_b32 v179, v179, v176
	s_waitcnt lgkmcnt(0)
	v_add_f32_e32 v176, v176, v179
	v_xor_b32_e32 v179, 8, v178
	ds_bpermute_b32 v179, v179, v176
	v_xor_b32_e32 v178, 4, v178
	s_waitcnt lgkmcnt(0)
	v_add_f32_e32 v176, v176, v179
	ds_bpermute_b32 v178, v178, v176
	s_waitcnt lgkmcnt(0)
	v_add_f32_e32 v176, v176, v178
	v_fmamk_f32 v176, v176, 0x3a800000, v183
	v_cmp_gt_f32_e32 vcc, s30, v176
	v_mul_f32_e32 v178, 0x4f800000, v176
	s_nop 0
	v_cndmask_b32_e32 v176, v176, v178, vcc
	v_sqrt_f32_e32 v178, v176
	s_nop 0
	v_add_u32_e32 v179, -1, v178
	v_fma_f32 v180, -v179, v178, v176
	v_cmp_ge_f32_e64 s[8:9], 0, v180
	v_add_u32_e32 v180, 1, v178
	s_nop 0
	v_cndmask_b32_e64 v179, v178, v179, s[8:9]
	v_fma_f32 v178, -v180, v178, v176
	v_cmp_lt_f32_e64 s[8:9], 0, v178
	s_nop 1
	v_cndmask_b32_e64 v178, v179, v180, s[8:9]
	v_mul_f32_e32 v179, 0x37800000, v178
	v_cndmask_b32_e32 v178, v178, v179, vcc
	v_cmp_class_f32_e32 vcc, v176, v222
	s_nop 1
	v_cndmask_b32_e32 v176, v178, v176, vcc
	s_nop 0
	v_rcp_f32_e32 v179, v176
	s_nop 0
	v_fma_f32 v178, -v176, v179, 1.0
	v_fma_f32 v178, v178, v179, v179
	v_div_fixup_f32 v176, v178, v176, 1.0
	s_and_saveexec_b64 s[2:3], s[6:7]
	s_cbranch_execz .LBB0_4342
	v_mul_f32_e32 v178, 0x3a800000, v129
	v_mov_b32_e32 v179, v176
	global_store_dwordx2 v[140:141], v[178:179], off
.LBB0_4342:
	s_or_b64 exec, exec, s[2:3]
	v_pk_mul_f32 v[178:179], v[188:189], v[176:177] op_sel_hi:[1,0]
	v_pk_mul_f32 v[180:181], v[190:191], v[176:177] op_sel_hi:[1,0]
	v_pk_fma_f32 v[178:179], v[26:27], v[178:179], v[30:31]
	v_pk_fma_f32 v[180:181], v[24:25], v[180:181], v[28:29]
	global_store_dwordx4 v[142:143], v[124:127], off nt
	s_mov_b32 s2, -1
	s_nop 0
	v_cvt_pk_bf16_f32 v124, v180, v181
	v_cvt_pk_bf16_f32 v125, v178, v179
	global_store_dwordx2 v[138:139], v[124:125], off
	v_pk_mul_f32 v[124:125], v[184:185], v[176:177] op_sel_hi:[1,0]
	v_pk_mul_f32 v[126:127], v[186:187], v[176:177] op_sel_hi:[1,0]
	v_pk_fma_f32 v[124:125], v[18:19], v[124:125], v[22:23]
	v_pk_fma_f32 v[126:127], v[16:17], v[126:127], v[20:21]
	global_store_dwordx4 v[142:143], v[120:123], off offset:1024 nt
	s_nop 1
	v_cvt_pk_bf16_f32 v120, v126, v127
	v_cvt_pk_bf16_f32 v121, v124, v125
	global_store_dwordx2 v[138:139], v[120:121], off offset:512
	v_pk_mul_f32 v[120:121], v[172:173], v[176:177] op_sel_hi:[1,0]
	v_pk_mul_f32 v[122:123], v[174:175], v[176:177] op_sel_hi:[1,0]
	v_pk_fma_f32 v[120:121], v[10:11], v[120:121], v[14:15]
	v_pk_fma_f32 v[122:123], v[8:9], v[122:123], v[12:13]
	global_store_dwordx4 v[142:143], v[116:119], off offset:2048 nt
	v_lshlrev_b32_e32 v126, 16, v160
	v_and_b32_e32 v127, 0xffff0000, v160
	v_cvt_pk_bf16_f32 v116, v122, v123
	v_cvt_pk_bf16_f32 v117, v120, v121
	global_store_dwordx2 v[138:139], v[116:117], off offset:1024
	v_pk_mul_f32 v[116:117], v[168:169], v[176:177] op_sel_hi:[1,0]
	v_pk_mul_f32 v[118:119], v[170:171], v[176:177] op_sel_hi:[1,0]
	v_pk_fma_f32 v[116:117], v[2:3], v[116:117], v[6:7]
	v_pk_fma_f32 v[118:119], v[0:1], v[118:119], v[4:5]
	global_store_dwordx4 v[142:143], v[112:115], off offset:3072 nt
	v_lshlrev_b32_e32 v120, 16, v165
	v_and_b32_e32 v121, 0xffff0000, v165
	v_cvt_pk_bf16_f32 v112, v118, v119
	v_cvt_pk_bf16_f32 v113, v116, v117
	global_store_dwordx2 v[138:139], v[112:113], off offset:1536
	global_load_dwordx2 v[112:113], v[140:141], off offset:8
	v_lshlrev_b32_e32 v114, 16, v166
	v_and_b32_e32 v115, 0xffff0000, v166
	v_lshlrev_b32_e32 v118, 16, v164
	v_and_b32_e32 v119, 0xffff0000, v164
	v_lshlrev_b32_e32 v116, 16, v167
	v_and_b32_e32 v117, 0xffff0000, v167
	v_lshlrev_b32_e32 v122, 16, v162
	v_and_b32_e32 v123, 0xffff0000, v162
	v_lshlrev_b32_e32 v124, 16, v163
	v_and_b32_e32 v125, 0xffff0000, v163
	v_lshlrev_b32_e32 v160, 16, v161
	v_and_b32_e32 v161, 0xffff0000, v161
	s_waitcnt vmcnt(0)
; DEVFI void ln_resid4(const float* ysrc, float* ydst, bfraw* fb, float* stats, const float* pw, const float* pb,
;                      const float* w, const float* b, int lane, bool fin) {
;     ...
;   for (int r = 0; r < 4; ++r) {
;     const float pmu = stats[r * 2], prs = stats[r * 2 + 1];
;     f32x4 y[4];
; #pragma unroll
;     for (int i = 0; i < 4; ++i) { const unsigned f0 = fv[r][i][0], f1 = fv[r][i][1];
;       const f32x4 f4 = {__uint_as_float(f0 << 16), __uint_as_float(f0 & 0xffff0000u), __uint_as_float(f1 << 16), __uint_as_float(f1 & 0xffff0000u)};
;       y[i] = ALPHA * ((v[r][i] - pmu) * prs * pwv[i] + pbv[i]) + f4; }
;     float s = 0;
; #pragma unroll
;     for (int i = 0; i < 4; ++i) s += y[i][0] + y[i][1] + y[i][2] + y[i][3];
;     const float mean = red64(s) * (1.f / 1024.f);
;     float q = 0;
; #pragma unroll
;     for (int i = 0; i < 4; ++i) { const f32x4 d = y[i] - mean; q += d[0] * d[0] + d[1] * d[1] + d[2] * d[2] + d[3] * d[3]; }
;     const float rstd = 1.f / sqrtf(red64(q) * (1.f / 1024.f) + LN_EPS);
;     if (lane == 0) { stats[r * 2] = mean; stats[r * 2 + 1] = rstd; }
	v_sub_f32_e32 v109, v109, v112
	v_sub_f32_e32 v108, v108, v112
	v_sub_f32_e32 v105, v105, v112
	v_sub_f32_e32 v104, v104, v112
	v_sub_f32_e32 v111, v111, v112
	v_sub_f32_e32 v110, v110, v112
	v_sub_f32_e32 v107, v107, v112
	v_sub_f32_e32 v106, v106, v112
	v_pk_mul_f32 v[108:109], v[112:113], v[108:109] op_sel:[1,0]
	v_pk_mul_f32 v[104:105], v[112:113], v[104:105] op_sel:[1,0]
	v_pk_mul_f32 v[110:111], v[112:113], v[110:111] op_sel:[1,0]
	v_pk_mul_f32 v[106:107], v[112:113], v[106:107] op_sel:[1,0]
	v_pk_fma_f32 v[108:109], v[56:57], v[108:109], v[60:61]
	v_pk_fma_f32 v[104:105], v[64:65], v[104:105], v[68:69]
	v_sub_f32_e32 v101, v101, v112
	v_sub_f32_e32 v100, v100, v112
	v_sub_f32_e32 v103, v103, v112
	v_sub_f32_e32 v102, v102, v112
	v_sub_f32_e32 v97, v97, v112
	v_sub_f32_e32 v96, v96, v112
	v_sub_f32_e32 v99, v99, v112
	v_sub_f32_e32 v98, v98, v112
	v_pk_fma_f32 v[110:111], v[58:59], v[110:111], v[62:63]
	v_pk_fma_f32 v[106:107], v[66:67], v[106:107], v[70:71]
	v_pk_fma_f32 v[108:109], v[108:109], s[52:53], v[114:115] op_sel_hi:[1,0,1]
	v_pk_fma_f32 v[104:105], v[104:105], s[52:53], v[118:119] op_sel_hi:[1,0,1]
	v_pk_mul_f32 v[102:103], v[112:113], v[102:103] op_sel:[1,0]
	v_pk_mul_f32 v[100:101], v[112:113], v[100:101] op_sel:[1,0]
	v_pk_mul_f32 v[98:99], v[112:113], v[98:99] op_sel:[1,0]
	v_pk_mul_f32 v[96:97], v[112:113], v[96:97] op_sel:[1,0]
	v_pk_fma_f32 v[110:111], v[110:111], s[52:53], v[116:117] op_sel_hi:[1,0,1]
	v_pk_fma_f32 v[106:107], v[106:107], s[52:53], v[120:121] op_sel_hi:[1,0,1]
	v_mov_b32_e32 v112, v104
	v_mov_b32_e32 v113, v108
	v_mov_b32_e32 v114, v105
	v_mov_b32_e32 v115, v109
	v_pk_add_f32 v[112:113], v[112:113], v[114:115]
	v_mov_b32_e32 v114, v106
	v_mov_b32_e32 v115, v110
	v_pk_add_f32 v[112:113], v[114:115], v[112:113]
	v_mov_b32_e32 v114, v107
	v_mov_b32_e32 v115, v111
	v_pk_fma_f32 v[100:101], v[72:73], v[100:101], v[76:77]
	v_pk_fma_f32 v[96:97], v[48:49], v[96:97], v[52:53]
	v_pk_add_f32 v[112:113], v[114:115], v[112:113]
	v_pk_fma_f32 v[102:103], v[74:75], v[102:103], v[78:79]
	v_pk_fma_f32 v[98:99], v[50:51], v[98:99], v[54:55]
	v_pk_fma_f32 v[100:101], v[100:101], s[52:53], v[122:123] op_sel_hi:[1,0,1]
	v_pk_fma_f32 v[96:97], v[96:97], s[52:53], v[126:127] op_sel_hi:[1,0,1]
	v_add_f32_e32 v113, 0, v113
	v_pk_fma_f32 v[102:103], v[102:103], s[52:53], v[124:125] op_sel_hi:[1,0,1]
	v_pk_fma_f32 v[98:99], v[98:99], s[52:53], v[160:161] op_sel_hi:[1,0,1]
	v_add_f32_e32 v116, v112, v113
	v_mov_b32_e32 v112, v96
	v_mov_b32_e32 v113, v100
	v_mov_b32_e32 v114, v97
	v_mov_b32_e32 v115, v101
	v_pk_add_f32 v[112:113], v[112:113], v[114:115]
	v_mov_b32_e32 v114, v98
	v_mov_b32_e32 v115, v102
	v_pk_add_f32 v[112:113], v[114:115], v[112:113]
	v_mov_b32_e32 v114, v99
	v_mov_b32_e32 v115, v103
	v_pk_add_f32 v[112:113], v[114:115], v[112:113]
	s_nop 0
	v_add_f32_e32 v113, v113, v116
	v_add_f32_e32 v112, v112, v113
	v_mbcnt_lo_u32_b32 v113, s2, 0
	v_mbcnt_hi_u32_b32 v113, s2, v113
	v_lshlrev_b32_e32 v113, 2, v113
	v_xor_b32_e32 v114, 0x80, v113
	ds_bpermute_b32 v114, v114, v112
	s_mov_b32 s2, -1
	s_waitcnt lgkmcnt(0)
	v_add_f32_e32 v112, v112, v114
	v_xor_b32_e32 v114, 64, v113
	ds_bpermute_b32 v114, v114, v112
	s_waitcnt lgkmcnt(0)
	v_add_f32_e32 v112, v112, v114
	v_xor_b32_e32 v114, 32, v113
	ds_bpermute_b32 v114, v114, v112
	s_waitcnt lgkmcnt(0)
	v_add_f32_e32 v112, v112, v114
	v_xor_b32_e32 v114, 16, v113
	ds_bpermute_b32 v114, v114, v112
	s_waitcnt lgkmcnt(0)
	v_add_f32_e32 v112, v112, v114
	v_xor_b32_e32 v114, 8, v113
	ds_bpermute_b32 v114, v114, v112
	v_xor_b32_e32 v113, 4, v113
	s_waitcnt lgkmcnt(0)
	v_add_f32_e32 v112, v112, v114
	ds_bpermute_b32 v113, v113, v112
	s_waitcnt lgkmcnt(0)
	v_add_f32_e32 v129, v112, v113
	v_fmamk_f32 v127, v129, 0xba800000, v109
	v_fmamk_f32 v123, v129, 0xba800000, v105
	v_fmamk_f32 v126, v129, 0xba800000, v108
	v_mul_f32_e32 v112, v127, v127
	v_fmamk_f32 v122, v129, 0xba800000, v104
	v_mul_f32_e32 v113, v123, v123
	v_fmamk_f32 v124, v129, 0xba800000, v110
	v_fmac_f32_e32 v112, v126, v126
	v_fmamk_f32 v120, v129, 0xba800000, v106
	v_fmac_f32_e32 v113, v122, v122
	v_fmamk_f32 v125, v129, 0xba800000, v111
	v_fmac_f32_e32 v112, v124, v124
	v_fmamk_f32 v121, v129, 0xba800000, v107
	v_fmac_f32_e32 v113, v120, v120
	v_fmac_f32_e32 v112, v125, v125
	v_fmac_f32_e32 v113, v121, v121
	v_fmamk_f32 v119, v129, 0xba800000, v101
	v_add_f32_e32 v112, v112, v113
	v_fmamk_f32 v118, v129, 0xba800000, v100
	v_mul_f32_e32 v113, v119, v119
	v_fmamk_f32 v116, v129, 0xba800000, v102
	v_fmac_f32_e32 v113, v118, v118
	v_fmamk_f32 v117, v129, 0xba800000, v103
	v_fmac_f32_e32 v113, v116, v116
	v_fmamk_f32 v115, v129, 0xba800000, v97
	v_fmac_f32_e32 v113, v117, v117
	v_fmamk_f32 v114, v129, 0xba800000, v96
	v_mul_f32_e32 v161, v115, v115
	v_add_f32_e32 v160, v113, v112
	v_fmamk_f32 v112, v129, 0xba800000, v98
	v_fmac_f32_e32 v161, v114, v114
	v_fmamk_f32 v113, v129, 0xba800000, v99
	v_fmac_f32_e32 v161, v112, v112
	v_fmac_f32_e32 v161, v113, v113
	v_add_f32_e32 v160, v161, v160
	v_mbcnt_lo_u32_b32 v161, s2, 0
	v_mbcnt_hi_u32_b32 v161, s2, v161
	v_lshlrev_b32_e32 v161, 2, v161
	v_xor_b32_e32 v162, 0x80, v161
	ds_bpermute_b32 v162, v162, v160
	s_waitcnt lgkmcnt(0)
	v_add_f32_e32 v160, v160, v162
	v_xor_b32_e32 v162, 64, v161
	ds_bpermute_b32 v162, v162, v160
	s_waitcnt lgkmcnt(0)
	v_add_f32_e32 v160, v160, v162
	v_xor_b32_e32 v162, 32, v161
	ds_bpermute_b32 v162, v162, v160
	s_waitcnt lgkmcnt(0)
	v_add_f32_e32 v160, v160, v162
	v_xor_b32_e32 v162, 16, v161
	ds_bpermute_b32 v162, v162, v160
	s_waitcnt lgkmcnt(0)
	v_add_f32_e32 v160, v160, v162
	v_xor_b32_e32 v162, 8, v161
	ds_bpermute_b32 v162, v162, v160
	v_xor_b32_e32 v161, 4, v161
	s_waitcnt lgkmcnt(0)
	v_add_f32_e32 v160, v160, v162
	ds_bpermute_b32 v161, v161, v160
	s_waitcnt lgkmcnt(0)
	v_add_f32_e32 v160, v160, v161
	v_fmamk_f32 v160, v160, 0x3a800000, v183
	v_mul_f32_e32 v161, 0x4f800000, v160
	v_cmp_gt_f32_e32 vcc, s30, v160
	s_nop 1
	v_cndmask_b32_e32 v160, v160, v161, vcc
	v_sqrt_f32_e32 v161, v160
	s_nop 0
	v_add_u32_e32 v162, -1, v161
	v_fma_f32 v163, -v162, v161, v160
	v_cmp_ge_f32_e64 s[8:9], 0, v163
	v_add_u32_e32 v163, 1, v161
	s_nop 0
	v_cndmask_b32_e64 v162, v161, v162, s[8:9]
	v_fma_f32 v161, -v163, v161, v160
	v_cmp_lt_f32_e64 s[8:9], 0, v161
	s_nop 1
	v_cndmask_b32_e64 v161, v162, v163, s[8:9]
	v_mul_f32_e32 v162, 0x37800000, v161
	v_cndmask_b32_e32 v161, v161, v162, vcc
	v_cmp_class_f32_e32 vcc, v160, v222
	s_nop 1
	v_cndmask_b32_e32 v160, v161, v160, vcc
	s_nop 0
	v_rcp_f32_e32 v162, v160
	s_nop 0
	v_fma_f32 v161, -v160, v162, 1.0
	v_fma_f32 v161, v161, v162, v162
	v_div_fixup_f32 v160, v161, v160, 1.0
	s_and_saveexec_b64 s[2:3], s[6:7]
	s_cbranch_execz .LBB0_4344
	v_mul_f32_e32 v162, 0x3a800000, v129
	v_mov_b32_e32 v163, v160
	global_store_dwordx2 v[140:141], v[162:163], off offset:8
; DEVFI void ln_resid4(const float* ysrc, float* ydst, bfraw* fb, float* stats, const float* pw, const float* pb,
;                      const float* w, const float* b, int lane, bool fin) {
;     ...
;   for (int r = 0; r < 4; ++r) {
;     const float pmu = stats[r * 2], prs = stats[r * 2 + 1];
;     f32x4 y[4];
; #pragma unroll
;     for (int i = 0; i < 4; ++i) { const unsigned f0 = fv[r][i][0], f1 = fv[r][i][1];
;       const f32x4 f4 = {__uint_as_float(f0 << 16), __uint_as_float(f0 & 0xffff0000u), __uint_as_float(f1 << 16), __uint_as_float(f1 & 0xffff0000u)};
;       y[i] = ALPHA * ((v[r][i] - pmu) * prs * pwv[i] + pbv[i]) + f4; }
;     float s = 0;
; #pragma unroll
;     for (int i = 0; i < 4; ++i) s += y[i][0] + y[i][1] + y[i][2] + y[i][3];
;     const float mean = red64(s) * (1.f / 1024.f);
;     float q = 0;
; #pragma unroll
;     for (int i = 0; i < 4; ++i) { const f32x4 d = y[i] - mean; q += d[0] * d[0] + d[1] * d[1] + d[2] * d[2] + d[3] * d[3]; }
;     const float rstd = 1.f / sqrtf(red64(q) * (1.f / 1024.f) + LN_EPS);
;     if (lane == 0) { stats[r * 2] = mean; stats[r * 2 + 1] = rstd; }
; #pragma unroll
;     for (int i = 0; i < 4; ++i) { const int c4 = i * 64 + lane;
;       const f32x4 z = (y[i] - mean) * rstd * ww[i] + bb[i];
;       __builtin_nontemporal_store(fin ? z : y[i], (f32x4*)(ydst + r * 1024) + c4);
;       u32x2 pk = {cvtpk(z[0], z[1]), cvtpk(z[2], z[3])}; ((u32x2*)(fb + r * 1024))[c4] = pk; }
.LBB0_4344:
	s_or_b64 exec, exec, s[2:3]
	s_mov_b64 s[2:3], 0x1000
	v_lshl_add_u64 v[162:163], v[142:143], 0, s[2:3]
	v_pk_mul_f32 v[124:125], v[124:125], v[160:161] op_sel_hi:[1,0]
	v_pk_mul_f32 v[126:127], v[126:127], v[160:161] op_sel_hi:[1,0]
	s_mov_b64 s[2:3], 0x1400
	v_pk_fma_f32 v[124:125], v[26:27], v[124:125], v[30:31]
	v_pk_fma_f32 v[126:127], v[24:25], v[126:127], v[28:29]
	global_store_dwordx4 v[162:163], v[108:111], off nt
	v_lshl_add_u64 v[164:165], v[142:143], 0, s[2:3]
	s_mov_b64 s[2:3], 0x1800
	v_cvt_pk_bf16_f32 v108, v126, v127
	v_cvt_pk_bf16_f32 v109, v124, v125
	global_store_dwordx2 v[138:139], v[108:109], off offset:2048
	v_pk_mul_f32 v[108:109], v[120:121], v[160:161] op_sel_hi:[1,0]
	v_pk_mul_f32 v[110:111], v[122:123], v[160:161] op_sel_hi:[1,0]
	v_pk_fma_f32 v[108:109], v[18:19], v[108:109], v[22:23]
	v_pk_fma_f32 v[110:111], v[16:17], v[110:111], v[20:21]
	global_store_dwordx4 v[164:165], v[104:107], off nt
	v_lshl_add_u64 v[166:167], v[142:143], 0, s[2:3]
	s_mov_b64 s[2:3], 0x1c00
	v_cvt_pk_bf16_f32 v104, v110, v111
	v_cvt_pk_bf16_f32 v105, v108, v109
	global_store_dwordx2 v[138:139], v[104:105], off offset:2560
	v_pk_mul_f32 v[104:105], v[116:117], v[160:161] op_sel_hi:[1,0]
	v_pk_mul_f32 v[106:107], v[118:119], v[160:161] op_sel_hi:[1,0]
	v_pk_fma_f32 v[104:105], v[10:11], v[104:105], v[14:15]
	v_pk_fma_f32 v[106:107], v[8:9], v[106:107], v[12:13]
	global_store_dwordx4 v[166:167], v[100:103], off nt
	v_lshl_add_u64 v[168:169], v[142:143], 0, s[2:3]
	v_lshlrev_b32_e32 v110, 16, v152
	v_cvt_pk_bf16_f32 v100, v106, v107
	v_cvt_pk_bf16_f32 v101, v104, v105
	global_store_dwordx2 v[138:139], v[100:101], off offset:3072
	v_pk_mul_f32 v[100:101], v[112:113], v[160:161] op_sel_hi:[1,0]
	v_pk_mul_f32 v[102:103], v[114:115], v[160:161] op_sel_hi:[1,0]
	v_pk_fma_f32 v[100:101], v[2:3], v[100:101], v[6:7]
	v_pk_fma_f32 v[102:103], v[0:1], v[102:103], v[4:5]
	global_store_dwordx4 v[168:169], v[96:99], off nt
	v_lshlrev_b32_e32 v104, 16, v157
	v_and_b32_e32 v105, 0xffff0000, v157
	v_cvt_pk_bf16_f32 v96, v102, v103
	v_cvt_pk_bf16_f32 v97, v100, v101
	global_store_dwordx2 v[138:139], v[96:97], off offset:3584
	global_load_dwordx2 v[96:97], v[140:141], off offset:16
	v_lshlrev_b32_e32 v98, 16, v158
	v_and_b32_e32 v99, 0xffff0000, v158
	v_lshlrev_b32_e32 v102, 16, v156
	v_and_b32_e32 v103, 0xffff0000, v156
	v_lshlrev_b32_e32 v100, 16, v159
	v_and_b32_e32 v101, 0xffff0000, v159
	v_lshlrev_b32_e32 v106, 16, v154
	v_and_b32_e32 v107, 0xffff0000, v154
	v_and_b32_e32 v111, 0xffff0000, v152
	v_lshlrev_b32_e32 v108, 16, v155
	v_and_b32_e32 v109, 0xffff0000, v155
	v_lshlrev_b32_e32 v112, 16, v153
	v_and_b32_e32 v113, 0xffff0000, v153
	s_mov_b32 s2, -1
	s_waitcnt vmcnt(0)
	v_sub_f32_e32 v93, v93, v96
	v_sub_f32_e32 v92, v92, v96
	v_sub_f32_e32 v89, v89, v96
	v_sub_f32_e32 v88, v88, v96
	v_sub_f32_e32 v95, v95, v96
	v_sub_f32_e32 v94, v94, v96
	v_sub_f32_e32 v91, v91, v96
	v_sub_f32_e32 v90, v90, v96
	v_pk_mul_f32 v[92:93], v[96:97], v[92:93] op_sel:[1,0]
	v_pk_mul_f32 v[88:89], v[96:97], v[88:89] op_sel:[1,0]
	v_pk_mul_f32 v[94:95], v[96:97], v[94:95] op_sel:[1,0]
	v_pk_mul_f32 v[90:91], v[96:97], v[90:91] op_sel:[1,0]
	v_pk_fma_f32 v[92:93], v[56:57], v[92:93], v[60:61]
	v_pk_fma_f32 v[88:89], v[64:65], v[88:89], v[68:69]
	v_sub_f32_e32 v85, v85, v96
	v_sub_f32_e32 v84, v84, v96
	v_sub_f32_e32 v87, v87, v96
	v_sub_f32_e32 v86, v86, v96
	v_sub_f32_e32 v81, v81, v96
	v_sub_f32_e32 v80, v80, v96
	v_sub_f32_e32 v83, v83, v96
	v_sub_f32_e32 v82, v82, v96
	v_pk_fma_f32 v[94:95], v[58:59], v[94:95], v[62:63]
	v_pk_fma_f32 v[90:91], v[66:67], v[90:91], v[70:71]
	v_pk_fma_f32 v[92:93], v[92:93], s[52:53], v[98:99] op_sel_hi:[1,0,1]
	v_pk_fma_f32 v[88:89], v[88:89], s[52:53], v[102:103] op_sel_hi:[1,0,1]
	v_pk_mul_f32 v[86:87], v[96:97], v[86:87] op_sel:[1,0]
	v_pk_mul_f32 v[84:85], v[96:97], v[84:85] op_sel:[1,0]
	v_pk_mul_f32 v[82:83], v[96:97], v[82:83] op_sel:[1,0]
	v_pk_mul_f32 v[80:81], v[96:97], v[80:81] op_sel:[1,0]
	v_pk_fma_f32 v[94:95], v[94:95], s[52:53], v[100:101] op_sel_hi:[1,0,1]
	v_pk_fma_f32 v[90:91], v[90:91], s[52:53], v[104:105] op_sel_hi:[1,0,1]
	v_mov_b32_e32 v96, v88
	v_mov_b32_e32 v97, v92
	v_mov_b32_e32 v98, v89
	v_mov_b32_e32 v99, v93
	v_pk_add_f32 v[96:97], v[96:97], v[98:99]
	v_mov_b32_e32 v98, v90
	v_mov_b32_e32 v99, v94
	v_pk_add_f32 v[96:97], v[98:99], v[96:97]
	v_mov_b32_e32 v98, v91
	v_mov_b32_e32 v99, v95
	v_pk_fma_f32 v[84:85], v[72:73], v[84:85], v[76:77]
	v_pk_fma_f32 v[80:81], v[48:49], v[80:81], v[52:53]
	v_pk_add_f32 v[96:97], v[98:99], v[96:97]
	v_pk_fma_f32 v[86:87], v[74:75], v[86:87], v[78:79]
	v_pk_fma_f32 v[82:83], v[50:51], v[82:83], v[54:55]
	v_pk_fma_f32 v[84:85], v[84:85], s[52:53], v[106:107] op_sel_hi:[1,0,1]
	v_pk_fma_f32 v[80:81], v[80:81], s[52:53], v[110:111] op_sel_hi:[1,0,1]
	v_add_f32_e32 v97, 0, v97
	v_pk_fma_f32 v[86:87], v[86:87], s[52:53], v[108:109] op_sel_hi:[1,0,1]
	v_pk_fma_f32 v[82:83], v[82:83], s[52:53], v[112:113] op_sel_hi:[1,0,1]
	v_add_f32_e32 v100, v96, v97
	v_mov_b32_e32 v96, v80
	v_mov_b32_e32 v97, v84
	v_mov_b32_e32 v98, v81
	v_mov_b32_e32 v99, v85
	v_pk_add_f32 v[96:97], v[96:97], v[98:99]
	v_mov_b32_e32 v98, v82
	v_mov_b32_e32 v99, v86
	v_pk_add_f32 v[96:97], v[98:99], v[96:97]
	v_mov_b32_e32 v98, v83
	v_mov_b32_e32 v99, v87
	v_pk_add_f32 v[96:97], v[98:99], v[96:97]
	s_nop 0
	v_add_f32_e32 v97, v97, v100
	v_add_f32_e32 v96, v96, v97
	v_mbcnt_lo_u32_b32 v97, s2, 0
	v_mbcnt_hi_u32_b32 v97, s2, v97
	v_lshlrev_b32_e32 v97, 2, v97
	v_xor_b32_e32 v98, 0x80, v97
	ds_bpermute_b32 v98, v98, v96
	s_mov_b32 s2, -1
	s_waitcnt lgkmcnt(0)
; DEVFI void ln_resid4(const float* ysrc, float* ydst, bfraw* fb, float* stats, const float* pw, const float* pb,
;                      const float* w, const float* b, int lane, bool fin) {
;     ...
;     float s = 0;
; #pragma unroll
;     for (int i = 0; i < 4; ++i) s += y[i][0] + y[i][1] + y[i][2] + y[i][3];
;     const float mean = red64(s) * (1.f / 1024.f);
;     float q = 0;
; #pragma unroll
;     for (int i = 0; i < 4; ++i) { const f32x4 d = y[i] - mean; q += d[0] * d[0] + d[1] * d[1] + d[2] * d[2] + d[3] * d[3]; }
;     const float rstd = 1.f / sqrtf(red64(q) * (1.f / 1024.f) + LN_EPS);
;     if (lane == 0) { stats[r * 2] = mean; stats[r * 2 + 1] = rstd; }
; #pragma unroll
;     for (int i = 0; i < 4; ++i) { const int c4 = i * 64 + lane;
;       const f32x4 z = (y[i] - mean) * rstd * ww[i] + bb[i];
;       __builtin_nontemporal_store(fin ? z : y[i], (f32x4*)(ydst + r * 1024) + c4);
;       u32x2 pk = {cvtpk(z[0], z[1]), cvtpk(z[2], z[3])}; ((u32x2*)(fb + r * 1024))[c4] = pk; }
	v_add_f32_e32 v96, v96, v98
	v_xor_b32_e32 v98, 64, v97
	ds_bpermute_b32 v98, v98, v96
	s_waitcnt lgkmcnt(0)
	v_add_f32_e32 v96, v96, v98
	v_xor_b32_e32 v98, 32, v97
	ds_bpermute_b32 v98, v98, v96
	s_waitcnt lgkmcnt(0)
	v_add_f32_e32 v96, v96, v98
	v_xor_b32_e32 v98, 16, v97
	ds_bpermute_b32 v98, v98, v96
	s_waitcnt lgkmcnt(0)
	v_add_f32_e32 v96, v96, v98
	v_xor_b32_e32 v98, 8, v97
	ds_bpermute_b32 v98, v98, v96
	v_xor_b32_e32 v97, 4, v97
	s_waitcnt lgkmcnt(0)
	v_add_f32_e32 v96, v96, v98
	ds_bpermute_b32 v97, v97, v96
	s_waitcnt lgkmcnt(0)
	v_add_f32_e32 v113, v96, v97
	v_fmamk_f32 v111, v113, 0xba800000, v93
	v_fmamk_f32 v107, v113, 0xba800000, v89
	v_fmamk_f32 v110, v113, 0xba800000, v92
	v_mul_f32_e32 v96, v111, v111
	v_fmamk_f32 v106, v113, 0xba800000, v88
	v_mul_f32_e32 v97, v107, v107
	v_fmamk_f32 v108, v113, 0xba800000, v94
	v_fmac_f32_e32 v96, v110, v110
	v_fmamk_f32 v104, v113, 0xba800000, v90
	v_fmac_f32_e32 v97, v106, v106
	v_fmamk_f32 v109, v113, 0xba800000, v95
	v_fmac_f32_e32 v96, v108, v108
	v_fmamk_f32 v105, v113, 0xba800000, v91
	v_fmac_f32_e32 v97, v104, v104
	v_fmac_f32_e32 v96, v109, v109
	v_fmac_f32_e32 v97, v105, v105
	v_fmamk_f32 v103, v113, 0xba800000, v85
	v_add_f32_e32 v96, v96, v97
	v_fmamk_f32 v102, v113, 0xba800000, v84
	v_mul_f32_e32 v97, v103, v103
	v_fmamk_f32 v100, v113, 0xba800000, v86
	v_fmac_f32_e32 v97, v102, v102
	v_fmamk_f32 v101, v113, 0xba800000, v87
	v_fmac_f32_e32 v97, v100, v100
	v_fmamk_f32 v99, v113, 0xba800000, v81
	v_fmac_f32_e32 v97, v101, v101
	v_fmamk_f32 v98, v113, 0xba800000, v80
	v_mul_f32_e32 v114, v99, v99
	v_add_f32_e32 v112, v97, v96
	v_fmamk_f32 v96, v113, 0xba800000, v82
	v_fmac_f32_e32 v114, v98, v98
	v_fmamk_f32 v97, v113, 0xba800000, v83
	v_fmac_f32_e32 v114, v96, v96
	v_fmac_f32_e32 v114, v97, v97
	v_add_f32_e32 v112, v114, v112
	v_mbcnt_lo_u32_b32 v114, s2, 0
	v_mbcnt_hi_u32_b32 v114, s2, v114
	v_lshlrev_b32_e32 v114, 2, v114
	v_xor_b32_e32 v115, 0x80, v114
	ds_bpermute_b32 v115, v115, v112
	s_waitcnt lgkmcnt(0)
	v_add_f32_e32 v112, v112, v115
	v_xor_b32_e32 v115, 64, v114
	ds_bpermute_b32 v115, v115, v112
	s_waitcnt lgkmcnt(0)
	v_add_f32_e32 v112, v112, v115
	v_xor_b32_e32 v115, 32, v114
	ds_bpermute_b32 v115, v115, v112
	s_waitcnt lgkmcnt(0)
	v_add_f32_e32 v112, v112, v115
	v_xor_b32_e32 v115, 16, v114
	ds_bpermute_b32 v115, v115, v112
	s_waitcnt lgkmcnt(0)
	v_add_f32_e32 v112, v112, v115
	v_xor_b32_e32 v115, 8, v114
	ds_bpermute_b32 v115, v115, v112
	v_xor_b32_e32 v114, 4, v114
	s_waitcnt lgkmcnt(0)
	v_add_f32_e32 v112, v112, v115
	ds_bpermute_b32 v114, v114, v112
	s_waitcnt lgkmcnt(0)
	v_add_f32_e32 v112, v112, v114
	v_fmamk_f32 v112, v112, 0x3a800000, v183
	v_mul_f32_e32 v114, 0x4f800000, v112
	v_cmp_gt_f32_e32 vcc, s30, v112
	s_nop 1
	v_cndmask_b32_e32 v112, v112, v114, vcc
	v_sqrt_f32_e32 v114, v112
	s_nop 0
	v_add_u32_e32 v115, -1, v114
	v_fma_f32 v116, -v115, v114, v112
	v_cmp_ge_f32_e64 s[8:9], 0, v116
	v_add_u32_e32 v116, 1, v114
	s_nop 0
	v_cndmask_b32_e64 v115, v114, v115, s[8:9]
	v_fma_f32 v114, -v116, v114, v112
	v_cmp_lt_f32_e64 s[8:9], 0, v114
	s_nop 1
	v_cndmask_b32_e64 v114, v115, v116, s[8:9]
	v_mul_f32_e32 v115, 0x37800000, v114
	v_cndmask_b32_e32 v114, v114, v115, vcc
	v_cmp_class_f32_e32 vcc, v112, v222
	s_nop 1
	v_cndmask_b32_e32 v112, v114, v112, vcc
	s_nop 0
	v_rcp_f32_e32 v115, v112
	s_nop 0
	v_fma_f32 v114, -v112, v115, 1.0
	v_fma_f32 v114, v114, v115, v115
	v_div_fixup_f32 v112, v114, v112, 1.0
	s_mov_b64 s[2:3], exec
	s_and_b64 s[8:9], s[2:3], s[6:7]
	v_mov_b32_e32 v182, v192
	s_mov_b64 exec, s[8:9]
	s_cbranch_execz .LBB0_4346
	v_mul_f32_e32 v114, 0x3a800000, v113
	v_mov_b32_e32 v115, v112
	global_store_dwordx2 v[140:141], v[114:115], off offset:16
.LBB0_4346:
	s_or_b64 exec, exec, s[2:3]
	s_mov_b64 s[2:3], 0x2000
	v_lshl_add_u64 v[114:115], v[142:143], 0, s[2:3]
	s_mov_b64 s[2:3], 0x2400
	v_lshl_add_u64 v[116:117], v[142:143], 0, s[2:3]
	s_mov_b64 s[2:3], 0x2800
	v_lshl_add_u64 v[118:119], v[142:143], 0, s[2:3]
	s_mov_b64 s[2:3], 0x2c00
	v_lshl_add_u64 v[120:121], v[142:143], 0, s[2:3]
	s_mov_b64 s[2:3], 0x1000
	v_pk_mul_f32 v[108:109], v[108:109], v[112:113] op_sel_hi:[1,0]
	v_pk_mul_f32 v[110:111], v[110:111], v[112:113] op_sel_hi:[1,0]
	v_lshl_add_u64 v[122:123], v[138:139], 0, s[2:3]
	v_pk_fma_f32 v[108:109], v[26:27], v[108:109], v[30:31]
	v_pk_fma_f32 v[110:111], v[24:25], v[110:111], v[28:29]
	global_store_dwordx4 v[114:115], v[92:95], off nt
	s_mov_b64 s[2:3], 0x1200
	v_lshl_add_u64 v[124:125], v[138:139], 0, s[2:3]
	v_cvt_pk_bf16_f32 v92, v110, v111
	v_cvt_pk_bf16_f32 v93, v108, v109
	global_store_dwordx2 v[122:123], v[92:93], off
	v_pk_mul_f32 v[92:93], v[104:105], v[112:113] op_sel_hi:[1,0]
	v_pk_mul_f32 v[94:95], v[106:107], v[112:113] op_sel_hi:[1,0]
	v_pk_fma_f32 v[92:93], v[18:19], v[92:93], v[22:23]
	v_pk_fma_f32 v[94:95], v[16:17], v[94:95], v[20:21]
	global_store_dwordx4 v[116:117], v[88:91], off nt
	s_mov_b64 s[2:3], 0x1400
	v_lshl_add_u64 v[126:127], v[138:139], 0, s[2:3]
	v_cvt_pk_bf16_f32 v88, v94, v95
	v_cvt_pk_bf16_f32 v89, v92, v93
	global_store_dwordx2 v[124:125], v[88:89], off
	v_pk_mul_f32 v[88:89], v[100:101], v[112:113] op_sel_hi:[1,0]
	v_pk_mul_f32 v[90:91], v[102:103], v[112:113] op_sel_hi:[1,0]
	s_mov_b64 s[2:3], 0x1600
	v_pk_fma_f32 v[88:89], v[10:11], v[88:89], v[14:15]
	v_pk_fma_f32 v[90:91], v[8:9], v[90:91], v[12:13]
	global_store_dwordx4 v[118:119], v[84:87], off nt
	v_lshl_add_u64 v[152:153], v[138:139], 0, s[2:3]
	v_lshlrev_b32_e32 v94, 16, v144
	v_cvt_pk_bf16_f32 v84, v90, v91
	v_cvt_pk_bf16_f32 v85, v88, v89
	global_store_dwordx2 v[126:127], v[84:85], off
	v_pk_mul_f32 v[84:85], v[96:97], v[112:113] op_sel_hi:[1,0]
	v_pk_mul_f32 v[86:87], v[98:99], v[112:113] op_sel_hi:[1,0]
	v_pk_fma_f32 v[84:85], v[2:3], v[84:85], v[6:7]
	v_pk_fma_f32 v[86:87], v[0:1], v[86:87], v[4:5]
	global_store_dwordx4 v[120:121], v[80:83], off nt
	v_lshlrev_b32_e32 v88, 16, v149
	v_and_b32_e32 v89, 0xffff0000, v149
	v_cvt_pk_bf16_f32 v80, v86, v87
	v_cvt_pk_bf16_f32 v81, v84, v85
	global_store_dwordx2 v[152:153], v[80:81], off
	global_load_dwordx2 v[80:81], v[140:141], off offset:24
	v_lshlrev_b32_e32 v82, 16, v150
	v_and_b32_e32 v83, 0xffff0000, v150
	v_lshlrev_b32_e32 v86, 16, v148
	v_and_b32_e32 v87, 0xffff0000, v148
	v_lshlrev_b32_e32 v84, 16, v151
	v_and_b32_e32 v85, 0xffff0000, v151
	v_lshlrev_b32_e32 v90, 16, v146
	v_and_b32_e32 v91, 0xffff0000, v146
	v_and_b32_e32 v95, 0xffff0000, v144
	v_lshlrev_b32_e32 v92, 16, v147
	v_and_b32_e32 v93, 0xffff0000, v147
	v_lshlrev_b32_e32 v96, 16, v145
	v_and_b32_e32 v97, 0xffff0000, v145
	s_mov_b32 s2, -1
	s_waitcnt vmcnt(0)
; DEVFI void ln_resid4(const float* ysrc, float* ydst, bfraw* fb, float* stats, const float* pw, const float* pb,
;                      const float* w, const float* b, int lane, bool fin) {
;     ...
;   for (int r = 0; r < 4; ++r) {
;     const float pmu = stats[r * 2], prs = stats[r * 2 + 1];
;     f32x4 y[4];
; #pragma unroll
;     for (int i = 0; i < 4; ++i) { const unsigned f0 = fv[r][i][0], f1 = fv[r][i][1];
;       const f32x4 f4 = {__uint_as_float(f0 << 16), __uint_as_float(f0 & 0xffff0000u), __uint_as_float(f1 << 16), __uint_as_float(f1 & 0xffff0000u)};
;       y[i] = ALPHA * ((v[r][i] - pmu) * prs * pwv[i] + pbv[i]) + f4; }
;     float s = 0;
; #pragma unroll
;     for (int i = 0; i < 4; ++i) s += y[i][0] + y[i][1] + y[i][2] + y[i][3];
;     const float mean = red64(s) * (1.f / 1024.f);
;     float q = 0;
; #pragma unroll
;     for (int i = 0; i < 4; ++i) { const f32x4 d = y[i] - mean; q += d[0] * d[0] + d[1] * d[1] + d[2] * d[2] + d[3] * d[3]; }
;     const float rstd = 1.f / sqrtf(red64(q) * (1.f / 1024.f) + LN_EPS);
;     if (lane == 0) { stats[r * 2] = mean; stats[r * 2 + 1] = rstd; }
	v_sub_f32_e32 v45, v45, v80
	v_sub_f32_e32 v44, v44, v80
	v_sub_f32_e32 v41, v41, v80
	v_sub_f32_e32 v40, v40, v80
	v_sub_f32_e32 v47, v47, v80
	v_sub_f32_e32 v46, v46, v80
	v_sub_f32_e32 v43, v43, v80
	v_sub_f32_e32 v42, v42, v80
	v_pk_mul_f32 v[44:45], v[80:81], v[44:45] op_sel:[1,0]
	v_pk_mul_f32 v[40:41], v[80:81], v[40:41] op_sel:[1,0]
	v_sub_f32_e32 v33, v33, v80
	v_sub_f32_e32 v32, v32, v80
	v_sub_f32_e32 v35, v35, v80
	v_sub_f32_e32 v34, v34, v80
	v_pk_mul_f32 v[46:47], v[80:81], v[46:47] op_sel:[1,0]
	v_pk_mul_f32 v[42:43], v[80:81], v[42:43] op_sel:[1,0]
	v_pk_fma_f32 v[44:45], v[56:57], v[44:45], v[60:61]
	v_pk_fma_f32 v[40:41], v[64:65], v[40:41], v[68:69]
	v_pk_fma_f32 v[46:47], v[58:59], v[46:47], v[62:63]
	v_pk_fma_f32 v[42:43], v[66:67], v[42:43], v[70:71]
	v_pk_fma_f32 v[44:45], v[44:45], s[52:53], v[82:83] op_sel_hi:[1,0,1]
	v_pk_fma_f32 v[40:41], v[40:41], s[52:53], v[86:87] op_sel_hi:[1,0,1]
	v_pk_mul_f32 v[34:35], v[80:81], v[34:35] op_sel:[1,0]
	v_pk_mul_f32 v[32:33], v[80:81], v[32:33] op_sel:[1,0]
	v_pk_fma_f32 v[46:47], v[46:47], s[52:53], v[84:85] op_sel_hi:[1,0,1]
	v_pk_fma_f32 v[42:43], v[42:43], s[52:53], v[88:89] op_sel_hi:[1,0,1]
	v_pk_fma_f32 v[32:33], v[48:49], v[32:33], v[52:53]
	v_pk_fma_f32 v[34:35], v[50:51], v[34:35], v[54:55]
	v_mov_b32_e32 v48, v40
	v_mov_b32_e32 v49, v44
	v_mov_b32_e32 v50, v41
	v_mov_b32_e32 v51, v45
	v_sub_f32_e32 v37, v37, v80
	v_sub_f32_e32 v36, v36, v80
	v_pk_add_f32 v[48:49], v[48:49], v[50:51]
	v_mov_b32_e32 v50, v42
	v_mov_b32_e32 v51, v46
	v_sub_f32_e32 v39, v39, v80
	v_sub_f32_e32 v38, v38, v80
	v_pk_mul_f32 v[36:37], v[80:81], v[36:37] op_sel:[1,0]
	v_pk_add_f32 v[48:49], v[50:51], v[48:49]
	v_mov_b32_e32 v50, v43
	v_mov_b32_e32 v51, v47
	v_pk_mul_f32 v[38:39], v[80:81], v[38:39] op_sel:[1,0]
	v_pk_fma_f32 v[36:37], v[72:73], v[36:37], v[76:77]
	v_pk_add_f32 v[48:49], v[50:51], v[48:49]
	v_pk_fma_f32 v[38:39], v[74:75], v[38:39], v[78:79]
	v_pk_fma_f32 v[36:37], v[36:37], s[52:53], v[90:91] op_sel_hi:[1,0,1]
	v_pk_fma_f32 v[32:33], v[32:33], s[52:53], v[94:95] op_sel_hi:[1,0,1]
	v_add_f32_e32 v49, 0, v49
	v_pk_fma_f32 v[38:39], v[38:39], s[52:53], v[92:93] op_sel_hi:[1,0,1]
	v_pk_fma_f32 v[34:35], v[34:35], s[52:53], v[96:97] op_sel_hi:[1,0,1]
	v_add_f32_e32 v52, v48, v49
	v_mov_b32_e32 v48, v32
	v_mov_b32_e32 v49, v36
	v_mov_b32_e32 v50, v33
	v_mov_b32_e32 v51, v37
	v_pk_add_f32 v[48:49], v[48:49], v[50:51]
	v_mov_b32_e32 v50, v34
	v_mov_b32_e32 v51, v38
	v_pk_add_f32 v[48:49], v[50:51], v[48:49]
	v_mov_b32_e32 v50, v35
	v_mov_b32_e32 v51, v39
	v_pk_add_f32 v[48:49], v[50:51], v[48:49]
	s_nop 0
	v_add_f32_e32 v49, v49, v52
	v_add_f32_e32 v48, v48, v49
	v_mbcnt_lo_u32_b32 v49, s2, 0
	v_mbcnt_hi_u32_b32 v49, s2, v49
	v_lshlrev_b32_e32 v49, 2, v49
	v_xor_b32_e32 v50, 0x80, v49
	ds_bpermute_b32 v50, v50, v48
	s_mov_b32 s2, -1
	s_waitcnt lgkmcnt(0)
	v_add_f32_e32 v48, v48, v50
	v_xor_b32_e32 v50, 64, v49
	ds_bpermute_b32 v50, v50, v48
	s_waitcnt lgkmcnt(0)
	v_add_f32_e32 v48, v48, v50
	v_xor_b32_e32 v50, 32, v49
	ds_bpermute_b32 v50, v50, v48
	s_waitcnt lgkmcnt(0)
	v_add_f32_e32 v48, v48, v50
	v_xor_b32_e32 v50, 16, v49
	ds_bpermute_b32 v50, v50, v48
	s_waitcnt lgkmcnt(0)
	v_add_f32_e32 v48, v48, v50
	v_xor_b32_e32 v50, 8, v49
	ds_bpermute_b32 v50, v50, v48
	v_xor_b32_e32 v49, 4, v49
	s_waitcnt lgkmcnt(0)
	v_add_f32_e32 v48, v48, v50
	ds_bpermute_b32 v49, v49, v48
	s_waitcnt lgkmcnt(0)
	v_add_f32_e32 v65, v48, v49
	v_fmamk_f32 v63, v65, 0xba800000, v45
	v_fmamk_f32 v59, v65, 0xba800000, v41
	v_fmamk_f32 v62, v65, 0xba800000, v44
	v_mul_f32_e32 v48, v63, v63
	v_fmamk_f32 v58, v65, 0xba800000, v40
	v_mul_f32_e32 v49, v59, v59
	v_fmamk_f32 v60, v65, 0xba800000, v46
	v_fmac_f32_e32 v48, v62, v62
	v_fmamk_f32 v56, v65, 0xba800000, v42
	v_fmac_f32_e32 v49, v58, v58
	v_fmamk_f32 v61, v65, 0xba800000, v47
	v_fmac_f32_e32 v48, v60, v60
	v_fmamk_f32 v57, v65, 0xba800000, v43
	v_fmac_f32_e32 v49, v56, v56
	v_fmac_f32_e32 v48, v61, v61
	v_fmac_f32_e32 v49, v57, v57
	v_fmamk_f32 v55, v65, 0xba800000, v37
	v_add_f32_e32 v48, v48, v49
	v_fmamk_f32 v54, v65, 0xba800000, v36
	v_mul_f32_e32 v49, v55, v55
	v_fmamk_f32 v52, v65, 0xba800000, v38
	v_fmac_f32_e32 v49, v54, v54
	v_fmamk_f32 v53, v65, 0xba800000, v39
	v_fmac_f32_e32 v49, v52, v52
	v_fmamk_f32 v51, v65, 0xba800000, v33
	v_fmac_f32_e32 v49, v53, v53
	v_fmamk_f32 v50, v65, 0xba800000, v32
	v_mul_f32_e32 v66, v51, v51
	v_add_f32_e32 v64, v49, v48
	v_fmamk_f32 v48, v65, 0xba800000, v34
	v_fmac_f32_e32 v66, v50, v50
	v_fmamk_f32 v49, v65, 0xba800000, v35
	v_fmac_f32_e32 v66, v48, v48
	v_fmac_f32_e32 v66, v49, v49
	v_add_f32_e32 v64, v66, v64
	v_mbcnt_lo_u32_b32 v66, s2, 0
	v_mbcnt_hi_u32_b32 v66, s2, v66
	v_lshlrev_b32_e32 v66, 2, v66
	v_xor_b32_e32 v67, 0x80, v66
	ds_bpermute_b32 v67, v67, v64
	s_waitcnt lgkmcnt(0)
	v_add_f32_e32 v64, v64, v67
	v_xor_b32_e32 v67, 64, v66
	ds_bpermute_b32 v67, v67, v64
	s_waitcnt lgkmcnt(0)
	v_add_f32_e32 v64, v64, v67
	v_xor_b32_e32 v67, 32, v66
	ds_bpermute_b32 v67, v67, v64
	s_waitcnt lgkmcnt(0)
	v_add_f32_e32 v64, v64, v67
	v_xor_b32_e32 v67, 16, v66
	ds_bpermute_b32 v67, v67, v64
	s_waitcnt lgkmcnt(0)
	v_add_f32_e32 v64, v64, v67
	v_xor_b32_e32 v67, 8, v66
	ds_bpermute_b32 v67, v67, v64
	v_xor_b32_e32 v66, 4, v66
	s_waitcnt lgkmcnt(0)
	v_add_f32_e32 v64, v64, v67
	ds_bpermute_b32 v66, v66, v64
	s_waitcnt lgkmcnt(0)
	v_add_f32_e32 v64, v64, v66
	v_fmamk_f32 v64, v64, 0x3a800000, v183
	v_mul_f32_e32 v66, 0x4f800000, v64
	v_cmp_gt_f32_e32 vcc, s30, v64
	s_nop 1
	v_cndmask_b32_e32 v64, v64, v66, vcc
	v_sqrt_f32_e32 v66, v64
	s_nop 0
	v_add_u32_e32 v67, -1, v66
	v_fma_f32 v68, -v67, v66, v64
	v_cmp_ge_f32_e64 s[8:9], 0, v68
	v_add_u32_e32 v68, 1, v66
	s_nop 0
	v_cndmask_b32_e64 v67, v66, v67, s[8:9]
	v_fma_f32 v66, -v68, v66, v64
	v_cmp_lt_f32_e64 s[8:9], 0, v66
	s_nop 1
	v_cndmask_b32_e64 v66, v67, v68, s[8:9]
	v_mul_f32_e32 v67, 0x37800000, v66
	v_cndmask_b32_e32 v66, v66, v67, vcc
	v_cmp_class_f32_e32 vcc, v64, v222
	s_nop 1
	v_cndmask_b32_e32 v64, v66, v64, vcc
	s_nop 0
	v_rcp_f32_e32 v67, v64
	s_nop 0
	v_fma_f32 v66, -v64, v67, 1.0
	v_fma_f32 v66, v66, v67, v67
	v_div_fixup_f32 v64, v66, v64, 1.0
	s_and_saveexec_b64 s[2:3], s[6:7]
	s_cbranch_execz .LBB0_4339
	v_mul_f32_e32 v66, 0x3a800000, v65
	v_mov_b32_e32 v67, v64
	global_store_dwordx2 v[140:141], v[66:67], off offset:24
	s_branch .LBB0_4339

; #define SBAR() __builtin_amdgcn_sched_barrier(0)
; DEVFI float dpp_xor1(float x) { return __int_as_float(__builtin_amdgcn_update_dpp(0, __float_as_int(x), 0xB1, 0xF, 0xF, true)); }
; #define G ((bfraw*)(kargs()->ws + O_G))
; DEVFI float sigmoidf_(float x) { return 1.f / (1.f + __expf(-x)); }
; __global__ void __launch_bounds__(512) mega(Params p) {
;     ...
;             auto slab = [&](f32x4 (&a)[8], const int m) {
;               bfraw* p0 = G + (long)(brow + wr0 + m * 16 + fq * 4) * DFF + oc + (odd ? 15 + fr : fr);
; #pragma unroll
;               for (int j = 0; j < 4; ++j)
; #pragma unroll
;                 for (int n0 = 0; n0 < 4; n0 += 2) { const float a0 = a[n0][j], a1 = a[n0 + 1][j];
;                   const float g0 = a0 * sigmoidf_(a0) * a[n0 + 4][j], g1 = a1 * sigmoidf_(a1) * a[n0 + 5][j];
;                   const float recv = dpp_xor1(odd ? g0 : g1);
;                   *reinterpret_cast<unsigned*>(p0 + (long)j * DFF + n0 * 16) = odd ? cvtpk(recv, g1) : cvtpk(g0, recv); }
;               SBAR(); };
.LBB0_4366:
	v_mul_f32_e32 v128, 0xbfb8aa3b, v120
	v_exp_f32_e32 v128, v128
	v_and_b32_e32 v129, 1, v133
	v_add_f32_e32 v128, 1.0, v128
	s_mov_b64 s[2:3], s[0:1]
	s_load_dwordx2 s[2:3], s[2:3], 0xe8
	v_mul_f32_e32 v137, 0xbfb8aa3b, v112
	v_exp_f32_e32 v137, v137
	v_rcp_f32_e32 v131, v128
	s_nop 0
	v_fma_f32 v130, -v128, v131, 1.0
	v_fma_f32 v130, v130, v131, v131
	v_div_fixup_f32 v128, v130, v128, 1.0
	v_add_f32_e32 v131, 1.0, v137
	v_mul_f32_e32 v120, v120, v128
	v_mul_f32_e32 v120, v124, v120
	v_cmp_eq_u32_e64 s[6:7], 1, v129
	v_rcp_f32_e32 v136, v131
	s_nop 0
	v_fma_f32 v124, -v131, v136, 1.0
	v_fma_f32 v124, v124, v136, v136
	v_div_fixup_f32 v124, v124, v131, 1.0
	v_mul_f32_e32 v112, v112, v124
	v_mul_f32_e32 v124, v116, v112
	v_cndmask_b32_e64 v112, v124, v120, s[6:7]
	s_xor_b64 s[18:19], s[6:7], -1
	s_nop 0
	v_mov_b32_dpp v112, v112 quad_perm:[1,0,3,2] row_mask:0xf bank_mask:0xf bound_ctrl:1
	s_and_saveexec_b64 s[20:21], s[18:19]
	s_xor_b64 s[20:21], exec, s[20:21]
	s_cbranch_execz .LBB0_4368
	v_cvt_pk_bf16_f32 v116, v120, v112

; #define SBAR() __builtin_amdgcn_sched_barrier(0)
; DEVFI float dpp_xor1(float x) { return __int_as_float(__builtin_amdgcn_update_dpp(0, __float_as_int(x), 0xB1, 0xF, 0xF, true)); }
; DEVFI int xcd_remap(int bid, int nb) { return (nb % 8 == 0) ? (bid % 8) * (nb / 8) + bid / 8 : bid; }
; #define W_FFNIN ((bfraw*)(kargs()->ws + O_FFNIN))
; #define XBF ((bfraw*)(kargs()->ws + O_XBF))
; #define G ((bfraw*)(kargs()->ws + O_G))
; DEVFI float sigmoidf_(float x) { return 1.f / (1.f + __expf(-x)); }
; __global__ void __launch_bounds__(512) mega(Params p) {
;     ...
;         gemm_loop(wv, xcd_remap(bid, nb), 320 * 22, nb, 1024, shm,
;           [&](const int u) { MDEC(u); return mk_src(XBF + (long)brow * 1024, 1024, W_FFNIN + (long)bcol * 1024, 1024); },
;           [&](const int u, f32x4 (&acc)[4][8], int wr0, int wc0, int fr, int fq) { MDEC(u);
;             const int oc = ((bcol + wc0) >> 7) * 64; const bool odd = fr & 1;
;             auto slab = [&](f32x4 (&a)[8], const int m) {
;               bfraw* p0 = G + (long)(brow + wr0 + m * 16 + fq * 4) * DFF + oc + (odd ? 15 + fr : fr);
; #pragma unroll
;               for (int j = 0; j < 4; ++j)
; #pragma unroll
;                 for (int n0 = 0; n0 < 4; n0 += 2) { const float a0 = a[n0][j], a1 = a[n0 + 1][j];
;                   const float g0 = a0 * sigmoidf_(a0) * a[n0 + 4][j], g1 = a1 * sigmoidf_(a1) * a[n0 + 5][j];
;                   const float recv = dpp_xor1(odd ? g0 : g1);
;                   *reinterpret_cast<unsigned*>(p0 + (long)j * DFF + n0 * 16) = odd ? cvtpk(recv, g1) : cvtpk(g0, recv); }
;               SBAR(); };
.LBB0_4370:
	s_or_b64 exec, exec, s[20:21]
	s_mul_hi_i32 s20, s22, 0x2e8ba2e9
	s_lshr_b32 s21, s20, 31
	s_ashr_i32 s20, s20, 5
	s_add_i32 s20, s20, s21
	s_mul_i32 s21, s20, 0xb0
	s_sub_i32 s21, s22, s21
	s_lshl_b32 s22, s21, 8
	s_lshl_b32 s20, s20, 11
	s_and_b32 s22, s22, 0x700
	s_or_b32 s22, s22, s20
	s_lshl_b32 s20, s21, 5
	s_and_b32 s20, s20, 0xffffff00
	v_lshl_or_b32 v112, v134, 7, s20
	v_ashrrev_i32_e32 v128, 1, v112
	v_lshrrev_b32_e32 v112, 2, v133
	v_and_b32_e32 v112, 12, v112
	v_lshl_or_b32 v112, s23, 6, v112
	v_add_u32_e32 v120, s22, v112
	s_waitcnt lgkmcnt(0)
	v_mov_b64_e32 v[130:131], s[2:3]
	v_mad_i64_i32 v[130:131], s[2:3], v120, s38, v[130:131]
	v_add_u32_e32 v120, 15, v132
	v_ashrrev_i32_e32 v129, 31, v128
	v_cndmask_b32_e64 v120, v132, v120, s[6:7]
	v_lshl_add_u64 v[130:131], v[128:129], 1, v[130:131]
	v_lshlrev_b32_e32 v176, 1, v120
	v_lshl_add_u64 v[130:131], v[130:131], 0, v[176:177]
	v_add_co_u32_e32 v132, vcc, s84, v130
	s_nop 1
	v_addc_co_u32_e32 v133, vcc, 0, v131, vcc
	global_store_dword v[132:133], v116, off
	v_mul_f32_e32 v116, 0xbfb8aa3b, v104
	v_exp_f32_e32 v116, v116
	s_nop 0
	v_add_f32_e32 v116, 1.0, v116
	s_nop 0
	v_rcp_f32_e32 v124, v116
	s_nop 0
	v_fma_f32 v120, -v116, v124, 1.0
	v_fma_f32 v120, v120, v124, v124
	v_div_fixup_f32 v116, v120, v116, 1.0
	v_mul_f32_e32 v104, v104, v116
	v_mul_f32_e32 v104, v108, v104
	v_mul_f32_e32 v108, 0xbfb8aa3b, v96
	v_exp_f32_e32 v108, v108
	s_nop 0
	v_add_f32_e32 v108, 1.0, v108
	s_nop 0
	v_rcp_f32_e32 v120, v108
	s_nop 0
	v_fma_f32 v116, -v108, v120, 1.0
	v_fma_f32 v116, v116, v120, v120
	v_div_fixup_f32 v108, v116, v108, 1.0
	v_mul_f32_e32 v96, v96, v108
	v_mul_f32_e32 v108, v100, v96
	v_cndmask_b32_e64 v96, v108, v104, s[6:7]
	s_nop 1
	v_mov_b32_dpp v100, v96 quad_perm:[1,0,3,2] row_mask:0xf bank_mask:0xf bound_ctrl:1
	s_and_saveexec_b64 s[2:3], s[18:19]
	s_xor_b64 s[2:3], exec, s[2:3]
	s_cbranch_execz .LBB0_4372
	v_cvt_pk_bf16_f32 v96, v104, v100

; #define SBAR() __builtin_amdgcn_sched_barrier(0)
; DEVFI float dpp_xor1(float x) { return __int_as_float(__builtin_amdgcn_update_dpp(0, __float_as_int(x), 0xB1, 0xF, 0xF, true)); }
; #define G ((bfraw*)(kargs()->ws + O_G))
; DEVFI float sigmoidf_(float x) { return 1.f / (1.f + __expf(-x)); }
; __global__ void __launch_bounds__(512) mega(Params p) {
;     ...
;             auto slab = [&](f32x4 (&a)[8], const int m) {
;               bfraw* p0 = G + (long)(brow + wr0 + m * 16 + fq * 4) * DFF + oc + (odd ? 15 + fr : fr);
; #pragma unroll
;               for (int j = 0; j < 4; ++j)
; #pragma unroll
;                 for (int n0 = 0; n0 < 4; n0 += 2) { const float a0 = a[n0][j], a1 = a[n0 + 1][j];
;                   const float g0 = a0 * sigmoidf_(a0) * a[n0 + 4][j], g1 = a1 * sigmoidf_(a1) * a[n0 + 5][j];
;                   const float recv = dpp_xor1(odd ? g0 : g1);
;                   *reinterpret_cast<unsigned*>(p0 + (long)j * DFF + n0 * 16) = odd ? cvtpk(recv, g1) : cvtpk(g0, recv); }
;               SBAR(); };
.LBB0_4374:
	s_or_b64 exec, exec, s[2:3]
	v_lshl_add_u64 v[130:131], v[130:131], 0, s[62:63]
	global_store_dword v[130:131], v96, off offset:64
	v_mul_f32_e32 v96, 0xbfb8aa3b, v121
	v_exp_f32_e32 v96, v96
	s_nop 0
	v_add_f32_e32 v96, 1.0, v96
	s_nop 0
	v_rcp_f32_e32 v104, v96
	s_nop 0
	v_fma_f32 v100, -v96, v104, 1.0
	v_fma_f32 v100, v100, v104, v104
	v_div_fixup_f32 v96, v100, v96, 1.0
	v_mul_f32_e32 v100, 0xbfb8aa3b, v113
	v_exp_f32_e32 v100, v100
	v_mul_f32_e32 v96, v121, v96
	v_mul_f32_e32 v96, v125, v96
	v_add_f32_e32 v100, 1.0, v100
	s_nop 0
	v_rcp_f32_e32 v108, v100
	s_nop 0
	v_fma_f32 v104, -v100, v108, 1.0
	v_fma_f32 v104, v104, v108, v108
	v_div_fixup_f32 v100, v104, v100, 1.0
	v_mul_f32_e32 v100, v113, v100
	v_mul_f32_e32 v108, v117, v100
	v_cndmask_b32_e64 v100, v108, v96, s[6:7]
	s_nop 1
	v_mov_b32_dpp v104, v100 quad_perm:[1,0,3,2] row_mask:0xf bank_mask:0xf bound_ctrl:1
	s_and_saveexec_b64 s[2:3], s[18:19]
	s_xor_b64 s[2:3], exec, s[2:3]
	s_cbranch_execz .LBB0_4376
	v_cvt_pk_bf16_f32 v100, v96, v104

; #define SBAR() __builtin_amdgcn_sched_barrier(0)
; DEVFI float dpp_xor1(float x) { return __int_as_float(__builtin_amdgcn_update_dpp(0, __float_as_int(x), 0xB1, 0xF, 0xF, true)); }
; #define G ((bfraw*)(kargs()->ws + O_G))
; DEVFI float sigmoidf_(float x) { return 1.f / (1.f + __expf(-x)); }
; __global__ void __launch_bounds__(512) mega(Params p) {
;     ...
;             auto slab = [&](f32x4 (&a)[8], const int m) {
;               bfraw* p0 = G + (long)(brow + wr0 + m * 16 + fq * 4) * DFF + oc + (odd ? 15 + fr : fr);
; #pragma unroll
;               for (int j = 0; j < 4; ++j)
; #pragma unroll
;                 for (int n0 = 0; n0 < 4; n0 += 2) { const float a0 = a[n0][j], a1 = a[n0 + 1][j];
;                   const float g0 = a0 * sigmoidf_(a0) * a[n0 + 4][j], g1 = a1 * sigmoidf_(a1) * a[n0 + 5][j];
;                   const float recv = dpp_xor1(odd ? g0 : g1);
;                   *reinterpret_cast<unsigned*>(p0 + (long)j * DFF + n0 * 16) = odd ? cvtpk(recv, g1) : cvtpk(g0, recv); }
;               SBAR(); };
.LBB0_4378:
	s_or_b64 exec, exec, s[2:3]
	v_mul_f32_e32 v96, 0xbfb8aa3b, v105
	v_exp_f32_e32 v96, v96
	v_add_co_u32_e32 v116, vcc, 0x1000, v130
	v_add_f32_e32 v96, 1.0, v96
	s_nop 0
	v_addc_co_u32_e32 v117, vcc, 0, v131, vcc
	global_store_dword v[116:117], v100, off offset:1536
	s_nop 0
	v_rcp_f32_e32 v104, v96
	s_nop 0
	v_fma_f32 v100, -v96, v104, 1.0
	v_fma_f32 v100, v100, v104, v104
	v_div_fixup_f32 v96, v100, v96, 1.0
	v_mul_f32_e32 v100, 0xbfb8aa3b, v97
	v_exp_f32_e32 v100, v100
	v_mul_f32_e32 v96, v105, v96
	v_mul_f32_e32 v96, v109, v96
	v_add_f32_e32 v100, 1.0, v100
	s_nop 0
	v_rcp_f32_e32 v105, v100
	s_nop 0
	v_fma_f32 v104, -v100, v105, 1.0
	v_fma_f32 v104, v104, v105, v105
	v_div_fixup_f32 v100, v104, v100, 1.0
	v_mul_f32_e32 v97, v97, v100
	v_mul_f32_e32 v101, v101, v97
	v_cndmask_b32_e64 v97, v101, v96, s[6:7]
	s_nop 1
	v_mov_b32_dpp v100, v97 quad_perm:[1,0,3,2] row_mask:0xf bank_mask:0xf bound_ctrl:1
	s_and_saveexec_b64 s[2:3], s[18:19]
	s_xor_b64 s[2:3], exec, s[2:3]
	s_cbranch_execz .LBB0_4380
	v_cvt_pk_bf16_f32 v97, v96, v100

; #define SBAR() __builtin_amdgcn_sched_barrier(0)
; DEVFI float dpp_xor1(float x) { return __int_as_float(__builtin_amdgcn_update_dpp(0, __float_as_int(x), 0xB1, 0xF, 0xF, true)); }
; #define G ((bfraw*)(kargs()->ws + O_G))
; DEVFI float sigmoidf_(float x) { return 1.f / (1.f + __expf(-x)); }
; __global__ void __launch_bounds__(512) mega(Params p) {
;     ...
;             auto slab = [&](f32x4 (&a)[8], const int m) {
;               bfraw* p0 = G + (long)(brow + wr0 + m * 16 + fq * 4) * DFF + oc + (odd ? 15 + fr : fr);
; #pragma unroll
;               for (int j = 0; j < 4; ++j)
; #pragma unroll
;                 for (int n0 = 0; n0 < 4; n0 += 2) { const float a0 = a[n0][j], a1 = a[n0 + 1][j];
;                   const float g0 = a0 * sigmoidf_(a0) * a[n0 + 4][j], g1 = a1 * sigmoidf_(a1) * a[n0 + 5][j];
;                   const float recv = dpp_xor1(odd ? g0 : g1);
;                   *reinterpret_cast<unsigned*>(p0 + (long)j * DFF + n0 * 16) = odd ? cvtpk(recv, g1) : cvtpk(g0, recv); }
;               SBAR(); };
.LBB0_4382:
	s_or_b64 exec, exec, s[2:3]
	v_mul_f32_e32 v96, 0xbfb8aa3b, v122
	v_exp_f32_e32 v96, v96
	v_add_co_u32_e32 v100, vcc, 0x1000, v130
	v_add_f32_e32 v96, 1.0, v96
	s_nop 0
	v_addc_co_u32_e32 v101, vcc, 0, v131, vcc
	global_store_dword v[100:101], v97, off offset:1600
	s_nop 0
	v_rcp_f32_e32 v100, v96
	s_nop 0
	v_fma_f32 v97, -v96, v100, 1.0
	v_fma_f32 v97, v97, v100, v100
	v_div_fixup_f32 v96, v97, v96, 1.0
	v_mul_f32_e32 v97, 0xbfb8aa3b, v114
	v_exp_f32_e32 v97, v97
	v_mul_f32_e32 v96, v122, v96
	v_mul_f32_e32 v96, v126, v96
	v_add_f32_e32 v97, 1.0, v97
	s_nop 0
	v_rcp_f32_e32 v101, v97
	s_nop 0
	v_fma_f32 v100, -v97, v101, 1.0
	v_fma_f32 v100, v100, v101, v101
	v_div_fixup_f32 v97, v100, v97, 1.0
	v_mul_f32_e32 v97, v114, v97
	v_mul_f32_e32 v101, v118, v97
	v_cndmask_b32_e64 v97, v101, v96, s[6:7]
	s_nop 1
	v_mov_b32_dpp v100, v97 quad_perm:[1,0,3,2] row_mask:0xf bank_mask:0xf bound_ctrl:1
	s_and_saveexec_b64 s[2:3], s[18:19]
	s_xor_b64 s[2:3], exec, s[2:3]
	s_cbranch_execz .LBB0_4384
	v_cvt_pk_bf16_f32 v97, v96, v100

; #define SBAR() __builtin_amdgcn_sched_barrier(0)
; DEVFI float dpp_xor1(float x) { return __int_as_float(__builtin_amdgcn_update_dpp(0, __float_as_int(x), 0xB1, 0xF, 0xF, true)); }
; #define G ((bfraw*)(kargs()->ws + O_G))
; DEVFI float sigmoidf_(float x) { return 1.f / (1.f + __expf(-x)); }
; __global__ void __launch_bounds__(512) mega(Params p) {
;     ...
;             auto slab = [&](f32x4 (&a)[8], const int m) {
;               bfraw* p0 = G + (long)(brow + wr0 + m * 16 + fq * 4) * DFF + oc + (odd ? 15 + fr : fr);
; #pragma unroll
;               for (int j = 0; j < 4; ++j)
; #pragma unroll
;                 for (int n0 = 0; n0 < 4; n0 += 2) { const float a0 = a[n0][j], a1 = a[n0 + 1][j];
;                   const float g0 = a0 * sigmoidf_(a0) * a[n0 + 4][j], g1 = a1 * sigmoidf_(a1) * a[n0 + 5][j];
;                   const float recv = dpp_xor1(odd ? g0 : g1);
;                   *reinterpret_cast<unsigned*>(p0 + (long)j * DFF + n0 * 16) = odd ? cvtpk(recv, g1) : cvtpk(g0, recv); }
;               SBAR(); };
.LBB0_4386:
	s_or_b64 exec, exec, s[2:3]
	v_mul_f32_e32 v96, 0xbfb8aa3b, v106
	v_exp_f32_e32 v96, v96
	v_add_co_u32_e32 v100, vcc, 0x2000, v130
	v_add_f32_e32 v96, 1.0, v96
	s_nop 0
	v_addc_co_u32_e32 v101, vcc, 0, v131, vcc
	global_store_dword v[100:101], v97, off offset:3072
	s_nop 0
	v_rcp_f32_e32 v100, v96
	s_nop 0
	v_fma_f32 v97, -v96, v100, 1.0
	v_fma_f32 v97, v97, v100, v100
	v_div_fixup_f32 v96, v97, v96, 1.0
	v_mul_f32_e32 v97, 0xbfb8aa3b, v98
	v_exp_f32_e32 v97, v97
	v_mul_f32_e32 v96, v106, v96
	v_mul_f32_e32 v96, v110, v96
	v_add_f32_e32 v97, 1.0, v97
	s_nop 0
	v_rcp_f32_e32 v101, v97
	s_nop 0
	v_fma_f32 v100, -v97, v101, 1.0
	v_fma_f32 v100, v100, v101, v101
	v_div_fixup_f32 v97, v100, v97, 1.0
	v_mul_f32_e32 v97, v98, v97
	v_mul_f32_e32 v100, v102, v97
	v_cndmask_b32_e64 v97, v100, v96, s[6:7]
	s_nop 1
	v_mov_b32_dpp v98, v97 quad_perm:[1,0,3,2] row_mask:0xf bank_mask:0xf bound_ctrl:1
	s_and_saveexec_b64 s[2:3], s[18:19]
	s_xor_b64 s[2:3], exec, s[2:3]
	s_cbranch_execz .LBB0_4388
	v_cvt_pk_bf16_f32 v97, v96, v98

; #define SBAR() __builtin_amdgcn_sched_barrier(0)
; DEVFI float dpp_xor1(float x) { return __int_as_float(__builtin_amdgcn_update_dpp(0, __float_as_int(x), 0xB1, 0xF, 0xF, true)); }
; #define G ((bfraw*)(kargs()->ws + O_G))
; DEVFI float sigmoidf_(float x) { return 1.f / (1.f + __expf(-x)); }
; __global__ void __launch_bounds__(512) mega(Params p) {
;     ...
;             auto slab = [&](f32x4 (&a)[8], const int m) {
;               bfraw* p0 = G + (long)(brow + wr0 + m * 16 + fq * 4) * DFF + oc + (odd ? 15 + fr : fr);
; #pragma unroll
;               for (int j = 0; j < 4; ++j)
; #pragma unroll
;                 for (int n0 = 0; n0 < 4; n0 += 2) { const float a0 = a[n0][j], a1 = a[n0 + 1][j];
;                   const float g0 = a0 * sigmoidf_(a0) * a[n0 + 4][j], g1 = a1 * sigmoidf_(a1) * a[n0 + 5][j];
;                   const float recv = dpp_xor1(odd ? g0 : g1);
;                   *reinterpret_cast<unsigned*>(p0 + (long)j * DFF + n0 * 16) = odd ? cvtpk(recv, g1) : cvtpk(g0, recv); }
;               SBAR(); };
.LBB0_4390:
	s_or_b64 exec, exec, s[2:3]
	v_mul_f32_e32 v96, 0xbfb8aa3b, v123
	v_exp_f32_e32 v96, v96
	v_add_co_u32_e32 v100, vcc, 0x2000, v130
	v_add_f32_e32 v96, 1.0, v96
	s_nop 0
	v_addc_co_u32_e32 v101, vcc, 0, v131, vcc
	global_store_dword v[100:101], v97, off offset:3136
	s_nop 0
	v_rcp_f32_e32 v98, v96
	s_nop 0
	v_fma_f32 v97, -v96, v98, 1.0
	v_fma_f32 v97, v97, v98, v98
	v_div_fixup_f32 v96, v97, v96, 1.0
	v_mul_f32_e32 v97, 0xbfb8aa3b, v115
	v_exp_f32_e32 v97, v97
	v_mul_f32_e32 v96, v123, v96
	v_mul_f32_e32 v96, v127, v96
	v_add_f32_e32 v97, 1.0, v97
	s_nop 0
	v_rcp_f32_e32 v100, v97
	s_nop 0
	v_fma_f32 v98, -v97, v100, 1.0
	v_fma_f32 v98, v98, v100, v100
	v_div_fixup_f32 v97, v98, v97, 1.0
	v_mul_f32_e32 v97, v115, v97
	v_mul_f32_e32 v100, v119, v97
	v_cndmask_b32_e64 v97, v100, v96, s[6:7]
	s_nop 1
	v_mov_b32_dpp v98, v97 quad_perm:[1,0,3,2] row_mask:0xf bank_mask:0xf bound_ctrl:1
	s_and_saveexec_b64 s[2:3], s[18:19]
	s_xor_b64 s[2:3], exec, s[2:3]
	s_cbranch_execz .LBB0_4392
	v_cvt_pk_bf16_f32 v97, v96, v98

; #define SBAR() __builtin_amdgcn_sched_barrier(0)
; DEVFI float dpp_xor1(float x) { return __int_as_float(__builtin_amdgcn_update_dpp(0, __float_as_int(x), 0xB1, 0xF, 0xF, true)); }
; #define G ((bfraw*)(kargs()->ws + O_G))
; DEVFI float sigmoidf_(float x) { return 1.f / (1.f + __expf(-x)); }
; __global__ void __launch_bounds__(512) mega(Params p) {
;     ...
;             auto slab = [&](f32x4 (&a)[8], const int m) {
;               bfraw* p0 = G + (long)(brow + wr0 + m * 16 + fq * 4) * DFF + oc + (odd ? 15 + fr : fr);
; #pragma unroll
;               for (int j = 0; j < 4; ++j)
; #pragma unroll
;                 for (int n0 = 0; n0 < 4; n0 += 2) { const float a0 = a[n0][j], a1 = a[n0 + 1][j];
;                   const float g0 = a0 * sigmoidf_(a0) * a[n0 + 4][j], g1 = a1 * sigmoidf_(a1) * a[n0 + 5][j];
;                   const float recv = dpp_xor1(odd ? g0 : g1);
;                   *reinterpret_cast<unsigned*>(p0 + (long)j * DFF + n0 * 16) = odd ? cvtpk(recv, g1) : cvtpk(g0, recv); }
;               SBAR(); };
.LBB0_4394:
	s_or_b64 exec, exec, s[2:3]
	v_mul_f32_e32 v96, 0xbfb8aa3b, v107
	v_exp_f32_e32 v96, v96
	v_add_co_u32_e32 v100, vcc, 0x4000, v130
	v_add_f32_e32 v96, 1.0, v96
	s_nop 0
	v_addc_co_u32_e32 v101, vcc, 0, v131, vcc
	global_store_dword v[100:101], v97, off offset:512
	s_nop 0
	v_rcp_f32_e32 v98, v96
	s_nop 0
	v_fma_f32 v97, -v96, v98, 1.0
	v_fma_f32 v97, v97, v98, v98
	v_div_fixup_f32 v96, v97, v96, 1.0
	v_mul_f32_e32 v97, 0xbfb8aa3b, v99
	v_exp_f32_e32 v97, v97
	v_mul_f32_e32 v96, v107, v96
	v_mul_f32_e32 v96, v111, v96
	v_add_f32_e32 v97, 1.0, v97
	s_nop 0
	v_rcp_f32_e32 v100, v97
	s_nop 0
	v_fma_f32 v98, -v97, v100, 1.0
	v_fma_f32 v98, v98, v100, v100
	v_div_fixup_f32 v97, v98, v97, 1.0
	v_mul_f32_e32 v97, v99, v97
	v_mul_f32_e32 v99, v103, v97
	v_cndmask_b32_e64 v97, v99, v96, s[6:7]
	s_nop 1
	v_mov_b32_dpp v98, v97 quad_perm:[1,0,3,2] row_mask:0xf bank_mask:0xf bound_ctrl:1
	s_and_saveexec_b64 s[2:3], s[18:19]
	s_xor_b64 s[2:3], exec, s[2:3]
	s_cbranch_execz .LBB0_4396
	v_cvt_pk_bf16_f32 v97, v96, v98

; #define SBAR() __builtin_amdgcn_sched_barrier(0)
; DEVFI float dpp_xor1(float x) { return __int_as_float(__builtin_amdgcn_update_dpp(0, __float_as_int(x), 0xB1, 0xF, 0xF, true)); }
; #define G ((bfraw*)(kargs()->ws + O_G))
; DEVFI float sigmoidf_(float x) { return 1.f / (1.f + __expf(-x)); }
; __global__ void __launch_bounds__(512) mega(Params p) {
;     ...
;             auto slab = [&](f32x4 (&a)[8], const int m) {
;               bfraw* p0 = G + (long)(brow + wr0 + m * 16 + fq * 4) * DFF + oc + (odd ? 15 + fr : fr);
; #pragma unroll
;               for (int j = 0; j < 4; ++j)
; #pragma unroll
;                 for (int n0 = 0; n0 < 4; n0 += 2) { const float a0 = a[n0][j], a1 = a[n0 + 1][j];
;                   const float g0 = a0 * sigmoidf_(a0) * a[n0 + 4][j], g1 = a1 * sigmoidf_(a1) * a[n0 + 5][j];
;                   const float recv = dpp_xor1(odd ? g0 : g1);
;                   *reinterpret_cast<unsigned*>(p0 + (long)j * DFF + n0 * 16) = odd ? cvtpk(recv, g1) : cvtpk(g0, recv); }
;               SBAR(); };
.LBB0_4398:
	s_or_b64 exec, exec, s[2:3]
	v_add_co_u32_e32 v98, vcc, 0x4000, v130
	s_nop 1
	v_addc_co_u32_e32 v99, vcc, 0, v131, vcc
	global_store_dword v[98:99], v97, off offset:576
	v_mul_f32_e32 v96, 0xbfb8aa3b, v88
	v_exp_f32_e32 v96, v96
	s_mov_b64 s[2:3], s[0:1]
	s_load_dwordx2 s[2:3], s[2:3], 0xe8
	v_add_f32_e32 v96, 1.0, v96
	s_nop 0
	v_rcp_f32_e32 v98, v96
	s_nop 0
	v_fma_f32 v97, -v96, v98, 1.0
	v_fma_f32 v97, v97, v98, v98
	v_div_fixup_f32 v96, v97, v96, 1.0
	v_mul_f32_e32 v88, v88, v96
	v_mul_f32_e32 v88, v92, v88
	v_mul_f32_e32 v92, 0xbfb8aa3b, v80
	v_exp_f32_e32 v92, v92
	s_nop 0
	v_add_f32_e32 v92, 1.0, v92
	s_nop 0
	v_rcp_f32_e32 v97, v92
	s_nop 0
	v_fma_f32 v96, -v92, v97, 1.0
	v_fma_f32 v96, v96, v97, v97
	v_div_fixup_f32 v92, v96, v92, 1.0
	v_mul_f32_e32 v80, v80, v92
	v_mul_f32_e32 v92, v84, v80
	v_cndmask_b32_e64 v80, v92, v88, s[6:7]
	s_nop 1
	v_mov_b32_dpp v84, v80 quad_perm:[1,0,3,2] row_mask:0xf bank_mask:0xf bound_ctrl:1
	s_and_saveexec_b64 s[20:21], s[18:19]
	s_xor_b64 s[20:21], exec, s[20:21]
	s_cbranch_execz .LBB0_4400
	v_cvt_pk_bf16_f32 v80, v88, v84

; #define SBAR() __builtin_amdgcn_sched_barrier(0)
; DEVFI float dpp_xor1(float x) { return __int_as_float(__builtin_amdgcn_update_dpp(0, __float_as_int(x), 0xB1, 0xF, 0xF, true)); }
; #define G ((bfraw*)(kargs()->ws + O_G))
; DEVFI float sigmoidf_(float x) { return 1.f / (1.f + __expf(-x)); }
; __global__ void __launch_bounds__(512) mega(Params p) {
;     ...
;             auto slab = [&](f32x4 (&a)[8], const int m) {
;               bfraw* p0 = G + (long)(brow + wr0 + m * 16 + fq * 4) * DFF + oc + (odd ? 15 + fr : fr);
; #pragma unroll
;               for (int j = 0; j < 4; ++j)
; #pragma unroll
;                 for (int n0 = 0; n0 < 4; n0 += 2) { const float a0 = a[n0][j], a1 = a[n0 + 1][j];
;                   const float g0 = a0 * sigmoidf_(a0) * a[n0 + 4][j], g1 = a1 * sigmoidf_(a1) * a[n0 + 5][j];
;                   const float recv = dpp_xor1(odd ? g0 : g1);
;                   *reinterpret_cast<unsigned*>(p0 + (long)j * DFF + n0 * 16) = odd ? cvtpk(recv, g1) : cvtpk(g0, recv); }
;               SBAR(); };
.LBB0_4402:
	s_or_b64 exec, exec, s[20:21]
	v_add3_u32 v84, v112, s22, 16
	s_waitcnt lgkmcnt(0)
	v_mov_b64_e32 v[96:97], s[2:3]
	v_mad_i64_i32 v[96:97], s[2:3], v84, s38, v[96:97]
	v_lshl_add_u64 v[96:97], v[128:129], 1, v[96:97]
	v_lshl_add_u64 v[96:97], v[96:97], 0, v[176:177]
	v_add_co_u32_e32 v98, vcc, 0x11720000, v96
	s_nop 1
	v_addc_co_u32_e32 v99, vcc, 0, v97, vcc
	global_store_dword v[98:99], v80, off
	v_mul_f32_e32 v80, 0xbfb8aa3b, v72
	v_exp_f32_e32 v80, v80
	s_nop 0
	v_add_f32_e32 v80, 1.0, v80
	s_nop 0
	v_rcp_f32_e32 v88, v80
	s_nop 0
	v_fma_f32 v84, -v80, v88, 1.0
	v_fma_f32 v84, v84, v88, v88
	v_div_fixup_f32 v80, v84, v80, 1.0
	v_mul_f32_e32 v72, v72, v80
	v_mul_f32_e32 v72, v76, v72
	v_mul_f32_e32 v76, 0xbfb8aa3b, v64
	v_exp_f32_e32 v76, v76
	s_nop 0
	v_add_f32_e32 v76, 1.0, v76
	s_nop 0
	v_rcp_f32_e32 v84, v76
	s_nop 0
	v_fma_f32 v80, -v76, v84, 1.0
	v_fma_f32 v80, v80, v84, v84
	v_div_fixup_f32 v76, v80, v76, 1.0
	v_mul_f32_e32 v64, v64, v76
	v_mul_f32_e32 v76, v68, v64
	v_cndmask_b32_e64 v64, v76, v72, s[6:7]
	s_nop 1
	v_mov_b32_dpp v68, v64 quad_perm:[1,0,3,2] row_mask:0xf bank_mask:0xf bound_ctrl:1
	s_and_saveexec_b64 s[2:3], s[18:19]
	s_xor_b64 s[2:3], exec, s[2:3]
	s_cbranch_execz .LBB0_4404
	v_cvt_pk_bf16_f32 v64, v72, v68

; #define SBAR() __builtin_amdgcn_sched_barrier(0)
; DEVFI float dpp_xor1(float x) { return __int_as_float(__builtin_amdgcn_update_dpp(0, __float_as_int(x), 0xB1, 0xF, 0xF, true)); }
; #define G ((bfraw*)(kargs()->ws + O_G))
; DEVFI float sigmoidf_(float x) { return 1.f / (1.f + __expf(-x)); }
; __global__ void __launch_bounds__(512) mega(Params p) {
;     ...
;             auto slab = [&](f32x4 (&a)[8], const int m) {
;               bfraw* p0 = G + (long)(brow + wr0 + m * 16 + fq * 4) * DFF + oc + (odd ? 15 + fr : fr);
; #pragma unroll
;               for (int j = 0; j < 4; ++j)
; #pragma unroll
;                 for (int n0 = 0; n0 < 4; n0 += 2) { const float a0 = a[n0][j], a1 = a[n0 + 1][j];
;                   const float g0 = a0 * sigmoidf_(a0) * a[n0 + 4][j], g1 = a1 * sigmoidf_(a1) * a[n0 + 5][j];
;                   const float recv = dpp_xor1(odd ? g0 : g1);
;                   *reinterpret_cast<unsigned*>(p0 + (long)j * DFF + n0 * 16) = odd ? cvtpk(recv, g1) : cvtpk(g0, recv); }
;               SBAR(); };
.LBB0_4406:
	s_or_b64 exec, exec, s[2:3]
	v_lshl_add_u64 v[96:97], v[96:97], 0, s[62:63]
	global_store_dword v[96:97], v64, off offset:64
	v_mul_f32_e32 v64, 0xbfb8aa3b, v89
	v_exp_f32_e32 v64, v64
	s_nop 0
	v_add_f32_e32 v64, 1.0, v64
	s_nop 0
	v_rcp_f32_e32 v72, v64
	s_nop 0
	v_fma_f32 v68, -v64, v72, 1.0
	v_fma_f32 v68, v68, v72, v72
	v_div_fixup_f32 v64, v68, v64, 1.0
	v_mul_f32_e32 v68, 0xbfb8aa3b, v81
	v_exp_f32_e32 v68, v68
	v_mul_f32_e32 v64, v89, v64
	v_mul_f32_e32 v64, v93, v64
	v_add_f32_e32 v68, 1.0, v68
	s_nop 0
	v_rcp_f32_e32 v76, v68
	s_nop 0
	v_fma_f32 v72, -v68, v76, 1.0
	v_fma_f32 v72, v72, v76, v76
	v_div_fixup_f32 v68, v72, v68, 1.0
	v_mul_f32_e32 v68, v81, v68
	v_mul_f32_e32 v76, v85, v68
	v_cndmask_b32_e64 v68, v76, v64, s[6:7]
	s_nop 1
	v_mov_b32_dpp v72, v68 quad_perm:[1,0,3,2] row_mask:0xf bank_mask:0xf bound_ctrl:1
	s_and_saveexec_b64 s[2:3], s[18:19]
	s_xor_b64 s[2:3], exec, s[2:3]
	s_cbranch_execz .LBB0_4408
	v_cvt_pk_bf16_f32 v68, v64, v72

; #define SBAR() __builtin_amdgcn_sched_barrier(0)
; DEVFI float dpp_xor1(float x) { return __int_as_float(__builtin_amdgcn_update_dpp(0, __float_as_int(x), 0xB1, 0xF, 0xF, true)); }
; #define G ((bfraw*)(kargs()->ws + O_G))
; DEVFI float sigmoidf_(float x) { return 1.f / (1.f + __expf(-x)); }
; __global__ void __launch_bounds__(512) mega(Params p) {
;     ...
;             auto slab = [&](f32x4 (&a)[8], const int m) {
;               bfraw* p0 = G + (long)(brow + wr0 + m * 16 + fq * 4) * DFF + oc + (odd ? 15 + fr : fr);
; #pragma unroll
;               for (int j = 0; j < 4; ++j)
; #pragma unroll
;                 for (int n0 = 0; n0 < 4; n0 += 2) { const float a0 = a[n0][j], a1 = a[n0 + 1][j];
;                   const float g0 = a0 * sigmoidf_(a0) * a[n0 + 4][j], g1 = a1 * sigmoidf_(a1) * a[n0 + 5][j];
;                   const float recv = dpp_xor1(odd ? g0 : g1);
;                   *reinterpret_cast<unsigned*>(p0 + (long)j * DFF + n0 * 16) = odd ? cvtpk(recv, g1) : cvtpk(g0, recv); }
;               SBAR(); };
.LBB0_4410:
	s_or_b64 exec, exec, s[2:3]
	v_mul_f32_e32 v64, 0xbfb8aa3b, v73
	v_exp_f32_e32 v64, v64
	v_add_co_u32_e32 v80, vcc, 0x1000, v96
	v_add_f32_e32 v64, 1.0, v64
	s_nop 0
	v_addc_co_u32_e32 v81, vcc, 0, v97, vcc
	global_store_dword v[80:81], v68, off offset:1536
	s_nop 0
	v_rcp_f32_e32 v72, v64
	s_nop 0
	v_fma_f32 v68, -v64, v72, 1.0
	v_fma_f32 v68, v68, v72, v72
	v_div_fixup_f32 v64, v68, v64, 1.0
	v_mul_f32_e32 v68, 0xbfb8aa3b, v65
	v_exp_f32_e32 v68, v68
	v_mul_f32_e32 v64, v73, v64
	v_mul_f32_e32 v64, v77, v64
	v_add_f32_e32 v68, 1.0, v68
	s_nop 0
	v_rcp_f32_e32 v73, v68
	s_nop 0
	v_fma_f32 v72, -v68, v73, 1.0
	v_fma_f32 v72, v72, v73, v73
	v_div_fixup_f32 v68, v72, v68, 1.0
	v_mul_f32_e32 v65, v65, v68
	v_mul_f32_e32 v69, v69, v65
	v_cndmask_b32_e64 v65, v69, v64, s[6:7]
	s_nop 1
	v_mov_b32_dpp v68, v65 quad_perm:[1,0,3,2] row_mask:0xf bank_mask:0xf bound_ctrl:1
	s_and_saveexec_b64 s[2:3], s[18:19]
	s_xor_b64 s[2:3], exec, s[2:3]
	s_cbranch_execz .LBB0_4412
	v_cvt_pk_bf16_f32 v65, v64, v68

; #define SBAR() __builtin_amdgcn_sched_barrier(0)
; DEVFI float dpp_xor1(float x) { return __int_as_float(__builtin_amdgcn_update_dpp(0, __float_as_int(x), 0xB1, 0xF, 0xF, true)); }
; #define G ((bfraw*)(kargs()->ws + O_G))
; DEVFI float sigmoidf_(float x) { return 1.f / (1.f + __expf(-x)); }
; __global__ void __launch_bounds__(512) mega(Params p) {
;     ...
;             auto slab = [&](f32x4 (&a)[8], const int m) {
;               bfraw* p0 = G + (long)(brow + wr0 + m * 16 + fq * 4) * DFF + oc + (odd ? 15 + fr : fr);
; #pragma unroll
;               for (int j = 0; j < 4; ++j)
; #pragma unroll
;                 for (int n0 = 0; n0 < 4; n0 += 2) { const float a0 = a[n0][j], a1 = a[n0 + 1][j];
;                   const float g0 = a0 * sigmoidf_(a0) * a[n0 + 4][j], g1 = a1 * sigmoidf_(a1) * a[n0 + 5][j];
;                   const float recv = dpp_xor1(odd ? g0 : g1);
;                   *reinterpret_cast<unsigned*>(p0 + (long)j * DFF + n0 * 16) = odd ? cvtpk(recv, g1) : cvtpk(g0, recv); }
;               SBAR(); };
.LBB0_4414:
	s_or_b64 exec, exec, s[2:3]
	v_mul_f32_e32 v64, 0xbfb8aa3b, v90
	v_exp_f32_e32 v64, v64
	v_add_co_u32_e32 v68, vcc, 0x1000, v96
	v_add_f32_e32 v64, 1.0, v64
	s_nop 0
	v_addc_co_u32_e32 v69, vcc, 0, v97, vcc
	global_store_dword v[68:69], v65, off offset:1600
	s_nop 0
	v_rcp_f32_e32 v68, v64
	s_nop 0
	v_fma_f32 v65, -v64, v68, 1.0
	v_fma_f32 v65, v65, v68, v68
	v_div_fixup_f32 v64, v65, v64, 1.0
	v_mul_f32_e32 v65, 0xbfb8aa3b, v82
	v_exp_f32_e32 v65, v65
	v_mul_f32_e32 v64, v90, v64
	v_mul_f32_e32 v64, v94, v64
	v_add_f32_e32 v65, 1.0, v65
	s_nop 0
	v_rcp_f32_e32 v69, v65
	s_nop 0
	v_fma_f32 v68, -v65, v69, 1.0
	v_fma_f32 v68, v68, v69, v69
	v_div_fixup_f32 v65, v68, v65, 1.0
	v_mul_f32_e32 v65, v82, v65
	v_mul_f32_e32 v69, v86, v65
	v_cndmask_b32_e64 v65, v69, v64, s[6:7]
	s_nop 1
	v_mov_b32_dpp v68, v65 quad_perm:[1,0,3,2] row_mask:0xf bank_mask:0xf bound_ctrl:1
	s_and_saveexec_b64 s[2:3], s[18:19]
	s_xor_b64 s[2:3], exec, s[2:3]
	s_cbranch_execz .LBB0_4416
	v_cvt_pk_bf16_f32 v65, v64, v68

; #define SBAR() __builtin_amdgcn_sched_barrier(0)
; DEVFI float dpp_xor1(float x) { return __int_as_float(__builtin_amdgcn_update_dpp(0, __float_as_int(x), 0xB1, 0xF, 0xF, true)); }
; #define G ((bfraw*)(kargs()->ws + O_G))
; DEVFI float sigmoidf_(float x) { return 1.f / (1.f + __expf(-x)); }
; __global__ void __launch_bounds__(512) mega(Params p) {
;     ...
;             auto slab = [&](f32x4 (&a)[8], const int m) {
;               bfraw* p0 = G + (long)(brow + wr0 + m * 16 + fq * 4) * DFF + oc + (odd ? 15 + fr : fr);
; #pragma unroll
;               for (int j = 0; j < 4; ++j)
; #pragma unroll
;                 for (int n0 = 0; n0 < 4; n0 += 2) { const float a0 = a[n0][j], a1 = a[n0 + 1][j];
;                   const float g0 = a0 * sigmoidf_(a0) * a[n0 + 4][j], g1 = a1 * sigmoidf_(a1) * a[n0 + 5][j];
;                   const float recv = dpp_xor1(odd ? g0 : g1);
;                   *reinterpret_cast<unsigned*>(p0 + (long)j * DFF + n0 * 16) = odd ? cvtpk(recv, g1) : cvtpk(g0, recv); }
;               SBAR(); };
.LBB0_4418:
	s_or_b64 exec, exec, s[2:3]
	v_mul_f32_e32 v64, 0xbfb8aa3b, v74
	v_exp_f32_e32 v64, v64
	v_add_co_u32_e32 v68, vcc, 0x2000, v96
	v_add_f32_e32 v64, 1.0, v64
	s_nop 0
	v_addc_co_u32_e32 v69, vcc, 0, v97, vcc
	global_store_dword v[68:69], v65, off offset:3072
	s_nop 0
	v_rcp_f32_e32 v68, v64
	s_nop 0
	v_fma_f32 v65, -v64, v68, 1.0
	v_fma_f32 v65, v65, v68, v68
	v_div_fixup_f32 v64, v65, v64, 1.0
	v_mul_f32_e32 v65, 0xbfb8aa3b, v66
	v_exp_f32_e32 v65, v65
	v_mul_f32_e32 v64, v74, v64
	v_mul_f32_e32 v64, v78, v64
	v_add_f32_e32 v65, 1.0, v65
	s_nop 0
	v_rcp_f32_e32 v69, v65
	s_nop 0
	v_fma_f32 v68, -v65, v69, 1.0
	v_fma_f32 v68, v68, v69, v69
	v_div_fixup_f32 v65, v68, v65, 1.0
	v_mul_f32_e32 v65, v66, v65
	v_mul_f32_e32 v68, v70, v65
	v_cndmask_b32_e64 v65, v68, v64, s[6:7]
	s_nop 1
	v_mov_b32_dpp v66, v65 quad_perm:[1,0,3,2] row_mask:0xf bank_mask:0xf bound_ctrl:1
	s_and_saveexec_b64 s[2:3], s[18:19]
	s_xor_b64 s[2:3], exec, s[2:3]
	s_cbranch_execz .LBB0_4420
	v_cvt_pk_bf16_f32 v65, v64, v66

; #define SBAR() __builtin_amdgcn_sched_barrier(0)
; DEVFI float dpp_xor1(float x) { return __int_as_float(__builtin_amdgcn_update_dpp(0, __float_as_int(x), 0xB1, 0xF, 0xF, true)); }
; #define G ((bfraw*)(kargs()->ws + O_G))
; DEVFI float sigmoidf_(float x) { return 1.f / (1.f + __expf(-x)); }
; __global__ void __launch_bounds__(512) mega(Params p) {
;     ...
;             auto slab = [&](f32x4 (&a)[8], const int m) {
;               bfraw* p0 = G + (long)(brow + wr0 + m * 16 + fq * 4) * DFF + oc + (odd ? 15 + fr : fr);
; #pragma unroll
;               for (int j = 0; j < 4; ++j)
; #pragma unroll
;                 for (int n0 = 0; n0 < 4; n0 += 2) { const float a0 = a[n0][j], a1 = a[n0 + 1][j];
;                   const float g0 = a0 * sigmoidf_(a0) * a[n0 + 4][j], g1 = a1 * sigmoidf_(a1) * a[n0 + 5][j];
;                   const float recv = dpp_xor1(odd ? g0 : g1);
;                   *reinterpret_cast<unsigned*>(p0 + (long)j * DFF + n0 * 16) = odd ? cvtpk(recv, g1) : cvtpk(g0, recv); }
;               SBAR(); };
.LBB0_4422:
	s_or_b64 exec, exec, s[2:3]
	v_mul_f32_e32 v64, 0xbfb8aa3b, v91
	v_exp_f32_e32 v64, v64
	v_add_co_u32_e32 v68, vcc, 0x2000, v96
	v_add_f32_e32 v64, 1.0, v64
	s_nop 0
	v_addc_co_u32_e32 v69, vcc, 0, v97, vcc
	global_store_dword v[68:69], v65, off offset:3136
	s_nop 0
	v_rcp_f32_e32 v66, v64
	s_nop 0
	v_fma_f32 v65, -v64, v66, 1.0
	v_fma_f32 v65, v65, v66, v66
	v_div_fixup_f32 v64, v65, v64, 1.0
	v_mul_f32_e32 v65, 0xbfb8aa3b, v83
	v_exp_f32_e32 v65, v65
	v_mul_f32_e32 v64, v91, v64
	v_mul_f32_e32 v64, v95, v64
	v_add_f32_e32 v65, 1.0, v65
	s_nop 0
	v_rcp_f32_e32 v68, v65
	s_nop 0
	v_fma_f32 v66, -v65, v68, 1.0
	v_fma_f32 v66, v66, v68, v68
	v_div_fixup_f32 v65, v66, v65, 1.0
	v_mul_f32_e32 v65, v83, v65
	v_mul_f32_e32 v68, v87, v65
	v_cndmask_b32_e64 v65, v68, v64, s[6:7]
	s_nop 1
	v_mov_b32_dpp v66, v65 quad_perm:[1,0,3,2] row_mask:0xf bank_mask:0xf bound_ctrl:1
	s_and_saveexec_b64 s[2:3], s[18:19]
	s_xor_b64 s[2:3], exec, s[2:3]
	s_cbranch_execz .LBB0_4424
	v_cvt_pk_bf16_f32 v65, v64, v66

; #define SBAR() __builtin_amdgcn_sched_barrier(0)
; DEVFI float dpp_xor1(float x) { return __int_as_float(__builtin_amdgcn_update_dpp(0, __float_as_int(x), 0xB1, 0xF, 0xF, true)); }
; #define G ((bfraw*)(kargs()->ws + O_G))
; DEVFI float sigmoidf_(float x) { return 1.f / (1.f + __expf(-x)); }
; __global__ void __launch_bounds__(512) mega(Params p) {
;     ...
;             auto slab = [&](f32x4 (&a)[8], const int m) {
;               bfraw* p0 = G + (long)(brow + wr0 + m * 16 + fq * 4) * DFF + oc + (odd ? 15 + fr : fr);
; #pragma unroll
;               for (int j = 0; j < 4; ++j)
; #pragma unroll
;                 for (int n0 = 0; n0 < 4; n0 += 2) { const float a0 = a[n0][j], a1 = a[n0 + 1][j];
;                   const float g0 = a0 * sigmoidf_(a0) * a[n0 + 4][j], g1 = a1 * sigmoidf_(a1) * a[n0 + 5][j];
;                   const float recv = dpp_xor1(odd ? g0 : g1);
;                   *reinterpret_cast<unsigned*>(p0 + (long)j * DFF + n0 * 16) = odd ? cvtpk(recv, g1) : cvtpk(g0, recv); }
;               SBAR(); };
.LBB0_4426:
	s_or_b64 exec, exec, s[2:3]
	v_mul_f32_e32 v64, 0xbfb8aa3b, v75
	v_exp_f32_e32 v64, v64
	v_add_co_u32_e32 v68, vcc, 0x4000, v96
	v_add_f32_e32 v64, 1.0, v64
	s_nop 0
	v_addc_co_u32_e32 v69, vcc, 0, v97, vcc
	global_store_dword v[68:69], v65, off offset:512
	s_nop 0
	v_rcp_f32_e32 v66, v64
	s_nop 0
	v_fma_f32 v65, -v64, v66, 1.0
	v_fma_f32 v65, v65, v66, v66
	v_div_fixup_f32 v64, v65, v64, 1.0
	v_mul_f32_e32 v65, 0xbfb8aa3b, v67
	v_exp_f32_e32 v65, v65
	v_mul_f32_e32 v64, v75, v64
	v_mul_f32_e32 v64, v79, v64
	v_add_f32_e32 v65, 1.0, v65
	s_nop 0
	v_rcp_f32_e32 v68, v65
	s_nop 0
	v_fma_f32 v66, -v65, v68, 1.0
	v_fma_f32 v66, v66, v68, v68
	v_div_fixup_f32 v65, v66, v65, 1.0
	v_mul_f32_e32 v65, v67, v65
	v_mul_f32_e32 v67, v71, v65
	v_cndmask_b32_e64 v65, v67, v64, s[6:7]
	s_nop 1
	v_mov_b32_dpp v66, v65 quad_perm:[1,0,3,2] row_mask:0xf bank_mask:0xf bound_ctrl:1
	s_and_saveexec_b64 s[2:3], s[18:19]
	s_xor_b64 s[2:3], exec, s[2:3]
	s_cbranch_execz .LBB0_4428
	v_cvt_pk_bf16_f32 v65, v64, v66

; #define SBAR() __builtin_amdgcn_sched_barrier(0)
; DEVFI float dpp_xor1(float x) { return __int_as_float(__builtin_amdgcn_update_dpp(0, __float_as_int(x), 0xB1, 0xF, 0xF, true)); }
; #define G ((bfraw*)(kargs()->ws + O_G))
; DEVFI float sigmoidf_(float x) { return 1.f / (1.f + __expf(-x)); }
; __global__ void __launch_bounds__(512) mega(Params p) {
;     ...
;             auto slab = [&](f32x4 (&a)[8], const int m) {
;               bfraw* p0 = G + (long)(brow + wr0 + m * 16 + fq * 4) * DFF + oc + (odd ? 15 + fr : fr);
; #pragma unroll
;               for (int j = 0; j < 4; ++j)
; #pragma unroll
;                 for (int n0 = 0; n0 < 4; n0 += 2) { const float a0 = a[n0][j], a1 = a[n0 + 1][j];
;                   const float g0 = a0 * sigmoidf_(a0) * a[n0 + 4][j], g1 = a1 * sigmoidf_(a1) * a[n0 + 5][j];
;                   const float recv = dpp_xor1(odd ? g0 : g1);
;                   *reinterpret_cast<unsigned*>(p0 + (long)j * DFF + n0 * 16) = odd ? cvtpk(recv, g1) : cvtpk(g0, recv); }
;               SBAR(); };
.LBB0_4430:
	s_or_b64 exec, exec, s[2:3]
	v_add_co_u32_e32 v66, vcc, 0x4000, v96
	s_nop 1
	v_addc_co_u32_e32 v67, vcc, 0, v97, vcc
	global_store_dword v[66:67], v65, off offset:576
	v_mul_f32_e32 v64, 0xbfb8aa3b, v56
	v_exp_f32_e32 v64, v64
	s_mov_b64 s[2:3], s[0:1]
	s_load_dwordx2 s[2:3], s[2:3], 0xe8
	v_add_f32_e32 v64, 1.0, v64
	s_nop 0
	v_rcp_f32_e32 v66, v64
	s_nop 0
	v_fma_f32 v65, -v64, v66, 1.0
	v_fma_f32 v65, v65, v66, v66
	v_div_fixup_f32 v64, v65, v64, 1.0
	v_mul_f32_e32 v56, v56, v64
	v_mul_f32_e32 v56, v60, v56
	v_mul_f32_e32 v60, 0xbfb8aa3b, v48
	v_exp_f32_e32 v60, v60
	s_nop 0
	v_add_f32_e32 v60, 1.0, v60
	s_nop 0
	v_rcp_f32_e32 v65, v60
	s_nop 0
	v_fma_f32 v64, -v60, v65, 1.0
	v_fma_f32 v64, v64, v65, v65
	v_div_fixup_f32 v60, v64, v60, 1.0
	v_mul_f32_e32 v48, v48, v60
	v_mul_f32_e32 v60, v52, v48
	v_cndmask_b32_e64 v48, v60, v56, s[6:7]
	s_nop 1
	v_mov_b32_dpp v52, v48 quad_perm:[1,0,3,2] row_mask:0xf bank_mask:0xf bound_ctrl:1
	s_and_saveexec_b64 s[20:21], s[18:19]
	s_xor_b64 s[20:21], exec, s[20:21]
	s_cbranch_execz .LBB0_4432
	v_cvt_pk_bf16_f32 v48, v56, v52

; #define SBAR() __builtin_amdgcn_sched_barrier(0)
; DEVFI float dpp_xor1(float x) { return __int_as_float(__builtin_amdgcn_update_dpp(0, __float_as_int(x), 0xB1, 0xF, 0xF, true)); }
; #define G ((bfraw*)(kargs()->ws + O_G))
; DEVFI float sigmoidf_(float x) { return 1.f / (1.f + __expf(-x)); }
; __global__ void __launch_bounds__(512) mega(Params p) {
;     ...
;             auto slab = [&](f32x4 (&a)[8], const int m) {
;               bfraw* p0 = G + (long)(brow + wr0 + m * 16 + fq * 4) * DFF + oc + (odd ? 15 + fr : fr);
; #pragma unroll
;               for (int j = 0; j < 4; ++j)
; #pragma unroll
;                 for (int n0 = 0; n0 < 4; n0 += 2) { const float a0 = a[n0][j], a1 = a[n0 + 1][j];
;                   const float g0 = a0 * sigmoidf_(a0) * a[n0 + 4][j], g1 = a1 * sigmoidf_(a1) * a[n0 + 5][j];
;                   const float recv = dpp_xor1(odd ? g0 : g1);
;                   *reinterpret_cast<unsigned*>(p0 + (long)j * DFF + n0 * 16) = odd ? cvtpk(recv, g1) : cvtpk(g0, recv); }
;               SBAR(); };
.LBB0_4434:
	s_or_b64 exec, exec, s[20:21]
	v_add3_u32 v52, v112, s22, 32
	s_waitcnt lgkmcnt(0)
	v_mov_b64_e32 v[64:65], s[2:3]
	v_mad_i64_i32 v[64:65], s[2:3], v52, s38, v[64:65]
	v_lshl_add_u64 v[64:65], v[128:129], 1, v[64:65]
	v_lshl_add_u64 v[64:65], v[64:65], 0, v[176:177]
	v_add_co_u32_e32 v66, vcc, 0x11720000, v64
	s_nop 1
	v_addc_co_u32_e32 v67, vcc, 0, v65, vcc
	global_store_dword v[66:67], v48, off
	v_mul_f32_e32 v48, 0xbfb8aa3b, v40
	v_exp_f32_e32 v48, v48
	s_nop 0
	v_add_f32_e32 v48, 1.0, v48
	s_nop 0
	v_rcp_f32_e32 v56, v48
	s_nop 0
	v_fma_f32 v52, -v48, v56, 1.0
	v_fma_f32 v52, v52, v56, v56
	v_div_fixup_f32 v48, v52, v48, 1.0
	v_mul_f32_e32 v40, v40, v48
	v_mul_f32_e32 v40, v44, v40
	v_mul_f32_e32 v44, 0xbfb8aa3b, v32
	v_exp_f32_e32 v44, v44
	s_nop 0
	v_add_f32_e32 v44, 1.0, v44
	s_nop 0
	v_rcp_f32_e32 v52, v44
	s_nop 0
	v_fma_f32 v48, -v44, v52, 1.0
	v_fma_f32 v48, v48, v52, v52
	v_div_fixup_f32 v44, v48, v44, 1.0
	v_mul_f32_e32 v32, v32, v44
	v_mul_f32_e32 v44, v36, v32
	v_cndmask_b32_e64 v32, v44, v40, s[6:7]
	s_nop 1
	v_mov_b32_dpp v36, v32 quad_perm:[1,0,3,2] row_mask:0xf bank_mask:0xf bound_ctrl:1
	s_and_saveexec_b64 s[2:3], s[18:19]
	s_xor_b64 s[2:3], exec, s[2:3]
	s_cbranch_execz .LBB0_4436
	v_cvt_pk_bf16_f32 v32, v40, v36

; #define SBAR() __builtin_amdgcn_sched_barrier(0)
; DEVFI float dpp_xor1(float x) { return __int_as_float(__builtin_amdgcn_update_dpp(0, __float_as_int(x), 0xB1, 0xF, 0xF, true)); }
; #define G ((bfraw*)(kargs()->ws + O_G))
; DEVFI float sigmoidf_(float x) { return 1.f / (1.f + __expf(-x)); }
; __global__ void __launch_bounds__(512) mega(Params p) {
;     ...
;             auto slab = [&](f32x4 (&a)[8], const int m) {
;               bfraw* p0 = G + (long)(brow + wr0 + m * 16 + fq * 4) * DFF + oc + (odd ? 15 + fr : fr);
; #pragma unroll
;               for (int j = 0; j < 4; ++j)
; #pragma unroll
;                 for (int n0 = 0; n0 < 4; n0 += 2) { const float a0 = a[n0][j], a1 = a[n0 + 1][j];
;                   const float g0 = a0 * sigmoidf_(a0) * a[n0 + 4][j], g1 = a1 * sigmoidf_(a1) * a[n0 + 5][j];
;                   const float recv = dpp_xor1(odd ? g0 : g1);
;                   *reinterpret_cast<unsigned*>(p0 + (long)j * DFF + n0 * 16) = odd ? cvtpk(recv, g1) : cvtpk(g0, recv); }
;               SBAR(); };
.LBB0_4438:
	s_or_b64 exec, exec, s[2:3]
	v_lshl_add_u64 v[64:65], v[64:65], 0, s[62:63]
	global_store_dword v[64:65], v32, off offset:64
	v_mul_f32_e32 v32, 0xbfb8aa3b, v57
	v_exp_f32_e32 v32, v32
	s_nop 0
	v_add_f32_e32 v32, 1.0, v32
	s_nop 0
	v_rcp_f32_e32 v40, v32
	s_nop 0
	v_fma_f32 v36, -v32, v40, 1.0
	v_fma_f32 v36, v36, v40, v40
	v_div_fixup_f32 v32, v36, v32, 1.0
	v_mul_f32_e32 v36, 0xbfb8aa3b, v49
	v_exp_f32_e32 v36, v36
	v_mul_f32_e32 v32, v57, v32
	v_mul_f32_e32 v32, v61, v32
	v_add_f32_e32 v36, 1.0, v36
	s_nop 0
	v_rcp_f32_e32 v44, v36
	s_nop 0
	v_fma_f32 v40, -v36, v44, 1.0
	v_fma_f32 v40, v40, v44, v44
	v_div_fixup_f32 v36, v40, v36, 1.0
	v_mul_f32_e32 v36, v49, v36
	v_mul_f32_e32 v44, v53, v36
	v_cndmask_b32_e64 v36, v44, v32, s[6:7]
	s_nop 1
	v_mov_b32_dpp v40, v36 quad_perm:[1,0,3,2] row_mask:0xf bank_mask:0xf bound_ctrl:1
	s_and_saveexec_b64 s[2:3], s[18:19]
	s_xor_b64 s[2:3], exec, s[2:3]
	s_cbranch_execz .LBB0_4440
	v_cvt_pk_bf16_f32 v36, v32, v40

; #define SBAR() __builtin_amdgcn_sched_barrier(0)
; DEVFI float dpp_xor1(float x) { return __int_as_float(__builtin_amdgcn_update_dpp(0, __float_as_int(x), 0xB1, 0xF, 0xF, true)); }
; #define G ((bfraw*)(kargs()->ws + O_G))
; DEVFI float sigmoidf_(float x) { return 1.f / (1.f + __expf(-x)); }
; __global__ void __launch_bounds__(512) mega(Params p) {
;     ...
;             auto slab = [&](f32x4 (&a)[8], const int m) {
;               bfraw* p0 = G + (long)(brow + wr0 + m * 16 + fq * 4) * DFF + oc + (odd ? 15 + fr : fr);
; #pragma unroll
;               for (int j = 0; j < 4; ++j)
; #pragma unroll
;                 for (int n0 = 0; n0 < 4; n0 += 2) { const float a0 = a[n0][j], a1 = a[n0 + 1][j];
;                   const float g0 = a0 * sigmoidf_(a0) * a[n0 + 4][j], g1 = a1 * sigmoidf_(a1) * a[n0 + 5][j];
;                   const float recv = dpp_xor1(odd ? g0 : g1);
;                   *reinterpret_cast<unsigned*>(p0 + (long)j * DFF + n0 * 16) = odd ? cvtpk(recv, g1) : cvtpk(g0, recv); }
;               SBAR(); };
.LBB0_4442:
	s_or_b64 exec, exec, s[2:3]
	v_mul_f32_e32 v32, 0xbfb8aa3b, v41
	v_exp_f32_e32 v32, v32
	v_add_co_u32_e32 v48, vcc, 0x1000, v64
	v_add_f32_e32 v32, 1.0, v32
	s_nop 0
	v_addc_co_u32_e32 v49, vcc, 0, v65, vcc
	global_store_dword v[48:49], v36, off offset:1536
	s_nop 0
	v_rcp_f32_e32 v40, v32
	s_nop 0
	v_fma_f32 v36, -v32, v40, 1.0
	v_fma_f32 v36, v36, v40, v40
	v_div_fixup_f32 v32, v36, v32, 1.0
	v_mul_f32_e32 v36, 0xbfb8aa3b, v33
	v_exp_f32_e32 v36, v36
	v_mul_f32_e32 v32, v41, v32
	v_mul_f32_e32 v32, v45, v32
	v_add_f32_e32 v36, 1.0, v36
	s_nop 0
	v_rcp_f32_e32 v41, v36
	s_nop 0
	v_fma_f32 v40, -v36, v41, 1.0
	v_fma_f32 v40, v40, v41, v41
	v_div_fixup_f32 v36, v40, v36, 1.0
	v_mul_f32_e32 v33, v33, v36
	v_mul_f32_e32 v37, v37, v33
	v_cndmask_b32_e64 v33, v37, v32, s[6:7]
	s_nop 1
	v_mov_b32_dpp v36, v33 quad_perm:[1,0,3,2] row_mask:0xf bank_mask:0xf bound_ctrl:1
	s_and_saveexec_b64 s[2:3], s[18:19]
	s_xor_b64 s[2:3], exec, s[2:3]
	s_cbranch_execz .LBB0_4444
	v_cvt_pk_bf16_f32 v33, v32, v36

; #define SBAR() __builtin_amdgcn_sched_barrier(0)
; DEVFI float dpp_xor1(float x) { return __int_as_float(__builtin_amdgcn_update_dpp(0, __float_as_int(x), 0xB1, 0xF, 0xF, true)); }
; #define G ((bfraw*)(kargs()->ws + O_G))
; DEVFI float sigmoidf_(float x) { return 1.f / (1.f + __expf(-x)); }
; __global__ void __launch_bounds__(512) mega(Params p) {
;     ...
;             auto slab = [&](f32x4 (&a)[8], const int m) {
;               bfraw* p0 = G + (long)(brow + wr0 + m * 16 + fq * 4) * DFF + oc + (odd ? 15 + fr : fr);
; #pragma unroll
;               for (int j = 0; j < 4; ++j)
; #pragma unroll
;                 for (int n0 = 0; n0 < 4; n0 += 2) { const float a0 = a[n0][j], a1 = a[n0 + 1][j];
;                   const float g0 = a0 * sigmoidf_(a0) * a[n0 + 4][j], g1 = a1 * sigmoidf_(a1) * a[n0 + 5][j];
;                   const float recv = dpp_xor1(odd ? g0 : g1);
;                   *reinterpret_cast<unsigned*>(p0 + (long)j * DFF + n0 * 16) = odd ? cvtpk(recv, g1) : cvtpk(g0, recv); }
;               SBAR(); };
.LBB0_4446:
	s_or_b64 exec, exec, s[2:3]
	v_mul_f32_e32 v32, 0xbfb8aa3b, v58
	v_exp_f32_e32 v32, v32
	v_add_co_u32_e32 v36, vcc, 0x1000, v64
	v_add_f32_e32 v32, 1.0, v32
	s_nop 0
	v_addc_co_u32_e32 v37, vcc, 0, v65, vcc
	global_store_dword v[36:37], v33, off offset:1600
	s_nop 0
	v_rcp_f32_e32 v36, v32
	s_nop 0
	v_fma_f32 v33, -v32, v36, 1.0
	v_fma_f32 v33, v33, v36, v36
	v_div_fixup_f32 v32, v33, v32, 1.0
	v_mul_f32_e32 v33, 0xbfb8aa3b, v50
	v_exp_f32_e32 v33, v33
	v_mul_f32_e32 v32, v58, v32
	v_mul_f32_e32 v32, v62, v32
	v_add_f32_e32 v33, 1.0, v33
	s_nop 0
	v_rcp_f32_e32 v37, v33
	s_nop 0
	v_fma_f32 v36, -v33, v37, 1.0
	v_fma_f32 v36, v36, v37, v37
	v_div_fixup_f32 v33, v36, v33, 1.0
	v_mul_f32_e32 v33, v50, v33
	v_mul_f32_e32 v37, v54, v33
	v_cndmask_b32_e64 v33, v37, v32, s[6:7]
	s_nop 1
	v_mov_b32_dpp v36, v33 quad_perm:[1,0,3,2] row_mask:0xf bank_mask:0xf bound_ctrl:1
	s_and_saveexec_b64 s[2:3], s[18:19]
	s_xor_b64 s[2:3], exec, s[2:3]
	s_cbranch_execz .LBB0_4448
	v_cvt_pk_bf16_f32 v33, v32, v36

; #define SBAR() __builtin_amdgcn_sched_barrier(0)
; DEVFI float dpp_xor1(float x) { return __int_as_float(__builtin_amdgcn_update_dpp(0, __float_as_int(x), 0xB1, 0xF, 0xF, true)); }
; #define G ((bfraw*)(kargs()->ws + O_G))
; DEVFI float sigmoidf_(float x) { return 1.f / (1.f + __expf(-x)); }
; __global__ void __launch_bounds__(512) mega(Params p) {
;     ...
;             auto slab = [&](f32x4 (&a)[8], const int m) {
;               bfraw* p0 = G + (long)(brow + wr0 + m * 16 + fq * 4) * DFF + oc + (odd ? 15 + fr : fr);
; #pragma unroll
;               for (int j = 0; j < 4; ++j)
; #pragma unroll
;                 for (int n0 = 0; n0 < 4; n0 += 2) { const float a0 = a[n0][j], a1 = a[n0 + 1][j];
;                   const float g0 = a0 * sigmoidf_(a0) * a[n0 + 4][j], g1 = a1 * sigmoidf_(a1) * a[n0 + 5][j];
;                   const float recv = dpp_xor1(odd ? g0 : g1);
;                   *reinterpret_cast<unsigned*>(p0 + (long)j * DFF + n0 * 16) = odd ? cvtpk(recv, g1) : cvtpk(g0, recv); }
;               SBAR(); };
.LBB0_4450:
	s_or_b64 exec, exec, s[2:3]
	v_mul_f32_e32 v32, 0xbfb8aa3b, v42
	v_exp_f32_e32 v32, v32
	v_add_co_u32_e32 v36, vcc, 0x2000, v64
	v_add_f32_e32 v32, 1.0, v32
	s_nop 0
	v_addc_co_u32_e32 v37, vcc, 0, v65, vcc
	global_store_dword v[36:37], v33, off offset:3072
	s_nop 0
	v_rcp_f32_e32 v36, v32
	s_nop 0
	v_fma_f32 v33, -v32, v36, 1.0
	v_fma_f32 v33, v33, v36, v36
	v_div_fixup_f32 v32, v33, v32, 1.0
	v_mul_f32_e32 v33, 0xbfb8aa3b, v34
	v_exp_f32_e32 v33, v33
	v_mul_f32_e32 v32, v42, v32
	v_mul_f32_e32 v32, v46, v32
	v_add_f32_e32 v33, 1.0, v33
	s_nop 0
	v_rcp_f32_e32 v37, v33
	s_nop 0
	v_fma_f32 v36, -v33, v37, 1.0
	v_fma_f32 v36, v36, v37, v37
	v_div_fixup_f32 v33, v36, v33, 1.0
	v_mul_f32_e32 v33, v34, v33
	v_mul_f32_e32 v36, v38, v33
	v_cndmask_b32_e64 v33, v36, v32, s[6:7]
	s_nop 1
	v_mov_b32_dpp v34, v33 quad_perm:[1,0,3,2] row_mask:0xf bank_mask:0xf bound_ctrl:1
	s_and_saveexec_b64 s[2:3], s[18:19]
	s_xor_b64 s[2:3], exec, s[2:3]
	s_cbranch_execz .LBB0_4452
	v_cvt_pk_bf16_f32 v33, v32, v34

; #define SBAR() __builtin_amdgcn_sched_barrier(0)
; DEVFI float dpp_xor1(float x) { return __int_as_float(__builtin_amdgcn_update_dpp(0, __float_as_int(x), 0xB1, 0xF, 0xF, true)); }
; #define G ((bfraw*)(kargs()->ws + O_G))
; DEVFI float sigmoidf_(float x) { return 1.f / (1.f + __expf(-x)); }
; __global__ void __launch_bounds__(512) mega(Params p) {
;     ...
;             auto slab = [&](f32x4 (&a)[8], const int m) {
;               bfraw* p0 = G + (long)(brow + wr0 + m * 16 + fq * 4) * DFF + oc + (odd ? 15 + fr : fr);
; #pragma unroll
;               for (int j = 0; j < 4; ++j)
; #pragma unroll
;                 for (int n0 = 0; n0 < 4; n0 += 2) { const float a0 = a[n0][j], a1 = a[n0 + 1][j];
;                   const float g0 = a0 * sigmoidf_(a0) * a[n0 + 4][j], g1 = a1 * sigmoidf_(a1) * a[n0 + 5][j];
;                   const float recv = dpp_xor1(odd ? g0 : g1);
;                   *reinterpret_cast<unsigned*>(p0 + (long)j * DFF + n0 * 16) = odd ? cvtpk(recv, g1) : cvtpk(g0, recv); }
;               SBAR(); };
.LBB0_4454:
	s_or_b64 exec, exec, s[2:3]
	v_mul_f32_e32 v32, 0xbfb8aa3b, v59
	v_exp_f32_e32 v32, v32
	v_add_co_u32_e32 v36, vcc, 0x2000, v64
	v_add_f32_e32 v32, 1.0, v32
	s_nop 0
	v_addc_co_u32_e32 v37, vcc, 0, v65, vcc
	global_store_dword v[36:37], v33, off offset:3136
	s_nop 0
	v_rcp_f32_e32 v34, v32
	s_nop 0
	v_fma_f32 v33, -v32, v34, 1.0
	v_fma_f32 v33, v33, v34, v34
	v_div_fixup_f32 v32, v33, v32, 1.0
	v_mul_f32_e32 v33, 0xbfb8aa3b, v51
	v_exp_f32_e32 v33, v33
	v_mul_f32_e32 v32, v59, v32
	v_mul_f32_e32 v32, v63, v32
	v_add_f32_e32 v33, 1.0, v33
	s_nop 0
	v_rcp_f32_e32 v36, v33
	s_nop 0
	v_fma_f32 v34, -v33, v36, 1.0
	v_fma_f32 v34, v34, v36, v36
	v_div_fixup_f32 v33, v34, v33, 1.0
	v_mul_f32_e32 v33, v51, v33
	v_mul_f32_e32 v36, v55, v33
	v_cndmask_b32_e64 v33, v36, v32, s[6:7]
	s_nop 1
	v_mov_b32_dpp v34, v33 quad_perm:[1,0,3,2] row_mask:0xf bank_mask:0xf bound_ctrl:1
	s_and_saveexec_b64 s[2:3], s[18:19]
	s_xor_b64 s[2:3], exec, s[2:3]
	s_cbranch_execz .LBB0_4456
	v_cvt_pk_bf16_f32 v33, v32, v34

; #define SBAR() __builtin_amdgcn_sched_barrier(0)
; DEVFI float dpp_xor1(float x) { return __int_as_float(__builtin_amdgcn_update_dpp(0, __float_as_int(x), 0xB1, 0xF, 0xF, true)); }
; #define G ((bfraw*)(kargs()->ws + O_G))
; DEVFI float sigmoidf_(float x) { return 1.f / (1.f + __expf(-x)); }
; __global__ void __launch_bounds__(512) mega(Params p) {
;     ...
;             auto slab = [&](f32x4 (&a)[8], const int m) {
;               bfraw* p0 = G + (long)(brow + wr0 + m * 16 + fq * 4) * DFF + oc + (odd ? 15 + fr : fr);
; #pragma unroll
;               for (int j = 0; j < 4; ++j)
; #pragma unroll
;                 for (int n0 = 0; n0 < 4; n0 += 2) { const float a0 = a[n0][j], a1 = a[n0 + 1][j];
;                   const float g0 = a0 * sigmoidf_(a0) * a[n0 + 4][j], g1 = a1 * sigmoidf_(a1) * a[n0 + 5][j];
;                   const float recv = dpp_xor1(odd ? g0 : g1);
;                   *reinterpret_cast<unsigned*>(p0 + (long)j * DFF + n0 * 16) = odd ? cvtpk(recv, g1) : cvtpk(g0, recv); }
;               SBAR(); };
.LBB0_4458:
	s_or_b64 exec, exec, s[2:3]
	v_mul_f32_e32 v32, 0xbfb8aa3b, v43
	v_exp_f32_e32 v32, v32
	v_add_co_u32_e32 v36, vcc, 0x4000, v64
	v_add_f32_e32 v32, 1.0, v32
	s_nop 0
	v_addc_co_u32_e32 v37, vcc, 0, v65, vcc
	global_store_dword v[36:37], v33, off offset:512
	s_nop 0
	v_rcp_f32_e32 v34, v32
	s_nop 0
	v_fma_f32 v33, -v32, v34, 1.0
	v_fma_f32 v33, v33, v34, v34
	v_div_fixup_f32 v32, v33, v32, 1.0
	v_mul_f32_e32 v33, 0xbfb8aa3b, v35
	v_exp_f32_e32 v33, v33
	v_mul_f32_e32 v32, v43, v32
	v_mul_f32_e32 v32, v47, v32
	v_add_f32_e32 v33, 1.0, v33
	s_nop 0
	v_rcp_f32_e32 v36, v33
	s_nop 0
	v_fma_f32 v34, -v33, v36, 1.0
	v_fma_f32 v34, v34, v36, v36
	v_div_fixup_f32 v33, v34, v33, 1.0
	v_mul_f32_e32 v33, v35, v33
	v_mul_f32_e32 v35, v39, v33
	v_cndmask_b32_e64 v33, v35, v32, s[6:7]
	s_nop 1
	v_mov_b32_dpp v34, v33 quad_perm:[1,0,3,2] row_mask:0xf bank_mask:0xf bound_ctrl:1
	s_and_saveexec_b64 s[2:3], s[18:19]
	s_xor_b64 s[2:3], exec, s[2:3]
	s_cbranch_execz .LBB0_4460
	v_cvt_pk_bf16_f32 v33, v32, v34

; #define SBAR() __builtin_amdgcn_sched_barrier(0)
; DEVFI float dpp_xor1(float x) { return __int_as_float(__builtin_amdgcn_update_dpp(0, __float_as_int(x), 0xB1, 0xF, 0xF, true)); }
; #define G ((bfraw*)(kargs()->ws + O_G))
; DEVFI float sigmoidf_(float x) { return 1.f / (1.f + __expf(-x)); }
; __global__ void __launch_bounds__(512) mega(Params p) {
;     ...
;             auto slab = [&](f32x4 (&a)[8], const int m) {
;               bfraw* p0 = G + (long)(brow + wr0 + m * 16 + fq * 4) * DFF + oc + (odd ? 15 + fr : fr);
; #pragma unroll
;               for (int j = 0; j < 4; ++j)
; #pragma unroll
;                 for (int n0 = 0; n0 < 4; n0 += 2) { const float a0 = a[n0][j], a1 = a[n0 + 1][j];
;                   const float g0 = a0 * sigmoidf_(a0) * a[n0 + 4][j], g1 = a1 * sigmoidf_(a1) * a[n0 + 5][j];
;                   const float recv = dpp_xor1(odd ? g0 : g1);
;                   *reinterpret_cast<unsigned*>(p0 + (long)j * DFF + n0 * 16) = odd ? cvtpk(recv, g1) : cvtpk(g0, recv); }
;               SBAR(); };
.LBB0_4462:
	s_or_b64 exec, exec, s[2:3]
	v_add_co_u32_e32 v34, vcc, 0x4000, v64
	s_nop 1
	v_addc_co_u32_e32 v35, vcc, 0, v65, vcc
	global_store_dword v[34:35], v33, off offset:576
	v_mul_f32_e32 v32, 0xbfb8aa3b, v24
	v_exp_f32_e32 v32, v32
	s_mov_b64 s[2:3], s[0:1]
	s_load_dwordx2 s[2:3], s[2:3], 0xe8
	v_add_f32_e32 v32, 1.0, v32
	s_nop 0
	v_rcp_f32_e32 v34, v32
	s_nop 0
	v_fma_f32 v33, -v32, v34, 1.0
	v_fma_f32 v33, v33, v34, v34
	v_div_fixup_f32 v32, v33, v32, 1.0
	v_mul_f32_e32 v24, v24, v32
	v_mul_f32_e32 v24, v28, v24
	v_mul_f32_e32 v28, 0xbfb8aa3b, v16
	v_exp_f32_e32 v28, v28
	s_nop 0
	v_add_f32_e32 v28, 1.0, v28
	s_nop 0
	v_rcp_f32_e32 v33, v28
	s_nop 0
	v_fma_f32 v32, -v28, v33, 1.0
	v_fma_f32 v32, v32, v33, v33
	v_div_fixup_f32 v28, v32, v28, 1.0
	v_mul_f32_e32 v16, v16, v28
	v_mul_f32_e32 v28, v20, v16
	v_cndmask_b32_e64 v16, v28, v24, s[6:7]
	s_nop 1
	v_mov_b32_dpp v20, v16 quad_perm:[1,0,3,2] row_mask:0xf bank_mask:0xf bound_ctrl:1
	s_and_saveexec_b64 s[20:21], s[18:19]
	s_xor_b64 s[20:21], exec, s[20:21]
	s_cbranch_execz .LBB0_4464
	v_cvt_pk_bf16_f32 v16, v24, v20

; #define SBAR() __builtin_amdgcn_sched_barrier(0)
; DEVFI float dpp_xor1(float x) { return __int_as_float(__builtin_amdgcn_update_dpp(0, __float_as_int(x), 0xB1, 0xF, 0xF, true)); }
; #define G ((bfraw*)(kargs()->ws + O_G))
; DEVFI float sigmoidf_(float x) { return 1.f / (1.f + __expf(-x)); }
; __global__ void __launch_bounds__(512) mega(Params p) {
;     ...
;             auto slab = [&](f32x4 (&a)[8], const int m) {
;               bfraw* p0 = G + (long)(brow + wr0 + m * 16 + fq * 4) * DFF + oc + (odd ? 15 + fr : fr);
; #pragma unroll
;               for (int j = 0; j < 4; ++j)
; #pragma unroll
;                 for (int n0 = 0; n0 < 4; n0 += 2) { const float a0 = a[n0][j], a1 = a[n0 + 1][j];
;                   const float g0 = a0 * sigmoidf_(a0) * a[n0 + 4][j], g1 = a1 * sigmoidf_(a1) * a[n0 + 5][j];
;                   const float recv = dpp_xor1(odd ? g0 : g1);
;                   *reinterpret_cast<unsigned*>(p0 + (long)j * DFF + n0 * 16) = odd ? cvtpk(recv, g1) : cvtpk(g0, recv); }
;               SBAR(); };
.LBB0_4466:
	s_or_b64 exec, exec, s[20:21]
	v_add3_u32 v20, v112, s22, 48
	s_waitcnt lgkmcnt(0)
	v_mov_b64_e32 v[32:33], s[2:3]
	v_mad_i64_i32 v[32:33], s[2:3], v20, s38, v[32:33]
	v_mul_f32_e32 v20, 0xbfb8aa3b, v8
	v_exp_f32_e32 v20, v20
	v_lshl_add_u64 v[32:33], v[128:129], 1, v[32:33]
	v_lshl_add_u64 v[32:33], v[32:33], 0, v[176:177]
	v_add_co_u32_e32 v34, vcc, 0x11720000, v32
	v_add_f32_e32 v20, 1.0, v20
	s_nop 0
	v_addc_co_u32_e32 v35, vcc, 0, v33, vcc
	global_store_dword v[34:35], v16, off
	v_mul_f32_e32 v35, 0xbfb8aa3b, v0
	v_exp_f32_e32 v35, v35
	v_rcp_f32_e32 v28, v20
	s_nop 0
	v_fma_f32 v16, -v20, v28, 1.0
	v_fma_f32 v16, v16, v28, v28
	v_div_fixup_f32 v16, v16, v20, 1.0
	v_add_f32_e32 v24, 1.0, v35
	v_mul_f32_e32 v8, v8, v16
	v_mul_f32_e32 v8, v12, v8
	v_rcp_f32_e32 v34, v24
	s_nop 0
	v_fma_f32 v12, -v24, v34, 1.0
	v_fma_f32 v12, v12, v34, v34
	v_div_fixup_f32 v12, v12, v24, 1.0
	v_mul_f32_e32 v0, v0, v12
	v_mul_f32_e32 v12, v4, v0
	v_cndmask_b32_e64 v0, v12, v8, s[6:7]
	s_nop 1
	v_mov_b32_dpp v4, v0 quad_perm:[1,0,3,2] row_mask:0xf bank_mask:0xf bound_ctrl:1
	s_and_saveexec_b64 s[2:3], s[18:19]
	s_xor_b64 s[2:3], exec, s[2:3]
	s_cbranch_execz .LBB0_4468
	v_cvt_pk_bf16_f32 v0, v8, v4

; #define SBAR() __builtin_amdgcn_sched_barrier(0)
; DEVFI float dpp_xor1(float x) { return __int_as_float(__builtin_amdgcn_update_dpp(0, __float_as_int(x), 0xB1, 0xF, 0xF, true)); }
; #define G ((bfraw*)(kargs()->ws + O_G))
; DEVFI float sigmoidf_(float x) { return 1.f / (1.f + __expf(-x)); }
; __global__ void __launch_bounds__(512) mega(Params p) {
;     ...
;             auto slab = [&](f32x4 (&a)[8], const int m) {
;               bfraw* p0 = G + (long)(brow + wr0 + m * 16 + fq * 4) * DFF + oc + (odd ? 15 + fr : fr);
; #pragma unroll
;               for (int j = 0; j < 4; ++j)
; #pragma unroll
;                 for (int n0 = 0; n0 < 4; n0 += 2) { const float a0 = a[n0][j], a1 = a[n0 + 1][j];
;                   const float g0 = a0 * sigmoidf_(a0) * a[n0 + 4][j], g1 = a1 * sigmoidf_(a1) * a[n0 + 5][j];
;                   const float recv = dpp_xor1(odd ? g0 : g1);
;                   *reinterpret_cast<unsigned*>(p0 + (long)j * DFF + n0 * 16) = odd ? cvtpk(recv, g1) : cvtpk(g0, recv); }
;               SBAR(); };
.LBB0_4470:
	s_or_b64 exec, exec, s[2:3]
	v_lshl_add_u64 v[32:33], v[32:33], 0, s[62:63]
	global_store_dword v[32:33], v0, off offset:64
	v_mul_f32_e32 v0, 0xbfb8aa3b, v25
	v_exp_f32_e32 v0, v0
	s_nop 0
	v_add_f32_e32 v0, 1.0, v0
	s_nop 0
	v_rcp_f32_e32 v8, v0
	s_nop 0
	v_fma_f32 v4, -v0, v8, 1.0
	v_fma_f32 v4, v4, v8, v8
	v_div_fixup_f32 v0, v4, v0, 1.0
	v_mul_f32_e32 v4, 0xbfb8aa3b, v17
	v_exp_f32_e32 v4, v4
	v_mul_f32_e32 v0, v25, v0
	v_mul_f32_e32 v0, v29, v0
	v_add_f32_e32 v4, 1.0, v4
	s_nop 0
	v_rcp_f32_e32 v12, v4
	s_nop 0
	v_fma_f32 v8, -v4, v12, 1.0
	v_fma_f32 v8, v8, v12, v12
	v_div_fixup_f32 v4, v8, v4, 1.0
	v_mul_f32_e32 v4, v17, v4
	v_mul_f32_e32 v12, v21, v4
	v_cndmask_b32_e64 v4, v12, v0, s[6:7]
	s_nop 1
	v_mov_b32_dpp v8, v4 quad_perm:[1,0,3,2] row_mask:0xf bank_mask:0xf bound_ctrl:1
	s_and_saveexec_b64 s[2:3], s[18:19]
	s_xor_b64 s[2:3], exec, s[2:3]
	s_cbranch_execz .LBB0_4472
	v_cvt_pk_bf16_f32 v4, v0, v8

; #define SBAR() __builtin_amdgcn_sched_barrier(0)
; DEVFI float dpp_xor1(float x) { return __int_as_float(__builtin_amdgcn_update_dpp(0, __float_as_int(x), 0xB1, 0xF, 0xF, true)); }
; #define G ((bfraw*)(kargs()->ws + O_G))
; DEVFI float sigmoidf_(float x) { return 1.f / (1.f + __expf(-x)); }
; __global__ void __launch_bounds__(512) mega(Params p) {
;     ...
;             auto slab = [&](f32x4 (&a)[8], const int m) {
;               bfraw* p0 = G + (long)(brow + wr0 + m * 16 + fq * 4) * DFF + oc + (odd ? 15 + fr : fr);
; #pragma unroll
;               for (int j = 0; j < 4; ++j)
; #pragma unroll
;                 for (int n0 = 0; n0 < 4; n0 += 2) { const float a0 = a[n0][j], a1 = a[n0 + 1][j];
;                   const float g0 = a0 * sigmoidf_(a0) * a[n0 + 4][j], g1 = a1 * sigmoidf_(a1) * a[n0 + 5][j];
;                   const float recv = dpp_xor1(odd ? g0 : g1);
;                   *reinterpret_cast<unsigned*>(p0 + (long)j * DFF + n0 * 16) = odd ? cvtpk(recv, g1) : cvtpk(g0, recv); }
;               SBAR(); };
.LBB0_4474:
	s_or_b64 exec, exec, s[2:3]
	v_mul_f32_e32 v0, 0xbfb8aa3b, v9
	v_exp_f32_e32 v0, v0
	v_add_co_u32_e32 v16, vcc, 0x1000, v32
	v_add_f32_e32 v0, 1.0, v0
	s_nop 0
	v_addc_co_u32_e32 v17, vcc, 0, v33, vcc
	global_store_dword v[16:17], v4, off offset:1536
	s_nop 0
	v_rcp_f32_e32 v8, v0
	s_nop 0
	v_fma_f32 v4, -v0, v8, 1.0
	v_fma_f32 v4, v4, v8, v8
	v_div_fixup_f32 v0, v4, v0, 1.0
	v_mul_f32_e32 v4, 0xbfb8aa3b, v1
	v_exp_f32_e32 v4, v4
	v_mul_f32_e32 v0, v9, v0
	v_mul_f32_e32 v0, v13, v0
	v_add_f32_e32 v4, 1.0, v4
	s_nop 0
	v_rcp_f32_e32 v9, v4
	s_nop 0
	v_fma_f32 v8, -v4, v9, 1.0
	v_fma_f32 v8, v8, v9, v9
	v_div_fixup_f32 v4, v8, v4, 1.0
	v_mul_f32_e32 v1, v1, v4
	v_mul_f32_e32 v5, v5, v1
	v_cndmask_b32_e64 v1, v5, v0, s[6:7]
	s_nop 1
	v_mov_b32_dpp v4, v1 quad_perm:[1,0,3,2] row_mask:0xf bank_mask:0xf bound_ctrl:1
	s_and_saveexec_b64 s[2:3], s[18:19]
	s_xor_b64 s[2:3], exec, s[2:3]
	s_cbranch_execz .LBB0_4476
	v_cvt_pk_bf16_f32 v1, v0, v4

; #define SBAR() __builtin_amdgcn_sched_barrier(0)
; DEVFI float dpp_xor1(float x) { return __int_as_float(__builtin_amdgcn_update_dpp(0, __float_as_int(x), 0xB1, 0xF, 0xF, true)); }
; #define G ((bfraw*)(kargs()->ws + O_G))
; DEVFI float sigmoidf_(float x) { return 1.f / (1.f + __expf(-x)); }
; __global__ void __launch_bounds__(512) mega(Params p) {
;     ...
;             auto slab = [&](f32x4 (&a)[8], const int m) {
;               bfraw* p0 = G + (long)(brow + wr0 + m * 16 + fq * 4) * DFF + oc + (odd ? 15 + fr : fr);
; #pragma unroll
;               for (int j = 0; j < 4; ++j)
; #pragma unroll
;                 for (int n0 = 0; n0 < 4; n0 += 2) { const float a0 = a[n0][j], a1 = a[n0 + 1][j];
;                   const float g0 = a0 * sigmoidf_(a0) * a[n0 + 4][j], g1 = a1 * sigmoidf_(a1) * a[n0 + 5][j];
;                   const float recv = dpp_xor1(odd ? g0 : g1);
;                   *reinterpret_cast<unsigned*>(p0 + (long)j * DFF + n0 * 16) = odd ? cvtpk(recv, g1) : cvtpk(g0, recv); }
;               SBAR(); };
.LBB0_4478:
	s_or_b64 exec, exec, s[2:3]
	v_mul_f32_e32 v0, 0xbfb8aa3b, v26
	v_exp_f32_e32 v0, v0
	v_add_co_u32_e32 v4, vcc, 0x1000, v32
	v_add_f32_e32 v0, 1.0, v0
	s_nop 0
	v_addc_co_u32_e32 v5, vcc, 0, v33, vcc
	global_store_dword v[4:5], v1, off offset:1600
	s_nop 0
	v_rcp_f32_e32 v4, v0
	s_nop 0
	v_fma_f32 v1, -v0, v4, 1.0
	v_fma_f32 v1, v1, v4, v4
	v_div_fixup_f32 v0, v1, v0, 1.0
	v_mul_f32_e32 v1, 0xbfb8aa3b, v18
	v_exp_f32_e32 v1, v1
	v_mul_f32_e32 v0, v26, v0
	v_mul_f32_e32 v0, v30, v0
	v_add_f32_e32 v1, 1.0, v1
	s_nop 0
	v_rcp_f32_e32 v5, v1
	s_nop 0
	v_fma_f32 v4, -v1, v5, 1.0
	v_fma_f32 v4, v4, v5, v5
	v_div_fixup_f32 v1, v4, v1, 1.0
	v_mul_f32_e32 v1, v18, v1
	v_mul_f32_e32 v5, v22, v1
	v_cndmask_b32_e64 v1, v5, v0, s[6:7]
	s_nop 1
	v_mov_b32_dpp v4, v1 quad_perm:[1,0,3,2] row_mask:0xf bank_mask:0xf bound_ctrl:1
	s_and_saveexec_b64 s[2:3], s[18:19]
	s_xor_b64 s[2:3], exec, s[2:3]
	s_cbranch_execz .LBB0_4480
	v_cvt_pk_bf16_f32 v1, v0, v4

; #define SBAR() __builtin_amdgcn_sched_barrier(0)
; DEVFI float dpp_xor1(float x) { return __int_as_float(__builtin_amdgcn_update_dpp(0, __float_as_int(x), 0xB1, 0xF, 0xF, true)); }
; #define G ((bfraw*)(kargs()->ws + O_G))
; DEVFI float sigmoidf_(float x) { return 1.f / (1.f + __expf(-x)); }
; __global__ void __launch_bounds__(512) mega(Params p) {
;     ...
;             auto slab = [&](f32x4 (&a)[8], const int m) {
;               bfraw* p0 = G + (long)(brow + wr0 + m * 16 + fq * 4) * DFF + oc + (odd ? 15 + fr : fr);
; #pragma unroll
;               for (int j = 0; j < 4; ++j)
; #pragma unroll
;                 for (int n0 = 0; n0 < 4; n0 += 2) { const float a0 = a[n0][j], a1 = a[n0 + 1][j];
;                   const float g0 = a0 * sigmoidf_(a0) * a[n0 + 4][j], g1 = a1 * sigmoidf_(a1) * a[n0 + 5][j];
;                   const float recv = dpp_xor1(odd ? g0 : g1);
;                   *reinterpret_cast<unsigned*>(p0 + (long)j * DFF + n0 * 16) = odd ? cvtpk(recv, g1) : cvtpk(g0, recv); }
;               SBAR(); };
.LBB0_4482:
	s_or_b64 exec, exec, s[2:3]
	v_mul_f32_e32 v0, 0xbfb8aa3b, v10
	v_exp_f32_e32 v0, v0
	v_add_co_u32_e32 v4, vcc, 0x2000, v32
	v_add_f32_e32 v0, 1.0, v0
	s_nop 0
	v_addc_co_u32_e32 v5, vcc, 0, v33, vcc
	global_store_dword v[4:5], v1, off offset:3072
	s_nop 0
	v_rcp_f32_e32 v4, v0
	s_nop 0
	v_fma_f32 v1, -v0, v4, 1.0
	v_fma_f32 v1, v1, v4, v4
	v_div_fixup_f32 v0, v1, v0, 1.0
	v_mul_f32_e32 v1, 0xbfb8aa3b, v2
	v_exp_f32_e32 v1, v1
	v_mul_f32_e32 v0, v10, v0
	v_mul_f32_e32 v0, v14, v0
	v_add_f32_e32 v1, 1.0, v1
	s_nop 0
	v_rcp_f32_e32 v5, v1
	s_nop 0
	v_fma_f32 v4, -v1, v5, 1.0
	v_fma_f32 v4, v4, v5, v5
	v_div_fixup_f32 v1, v4, v1, 1.0
	v_mul_f32_e32 v1, v2, v1
	v_mul_f32_e32 v4, v6, v1
	v_cndmask_b32_e64 v1, v4, v0, s[6:7]
	s_nop 1
	v_mov_b32_dpp v2, v1 quad_perm:[1,0,3,2] row_mask:0xf bank_mask:0xf bound_ctrl:1
	s_and_saveexec_b64 s[2:3], s[18:19]
	s_xor_b64 s[2:3], exec, s[2:3]
	s_cbranch_execz .LBB0_4484
	v_cvt_pk_bf16_f32 v1, v0, v2

; #define SBAR() __builtin_amdgcn_sched_barrier(0)
; DEVFI float dpp_xor1(float x) { return __int_as_float(__builtin_amdgcn_update_dpp(0, __float_as_int(x), 0xB1, 0xF, 0xF, true)); }
; #define G ((bfraw*)(kargs()->ws + O_G))
; DEVFI float sigmoidf_(float x) { return 1.f / (1.f + __expf(-x)); }
; __global__ void __launch_bounds__(512) mega(Params p) {
;     ...
;             auto slab = [&](f32x4 (&a)[8], const int m) {
;               bfraw* p0 = G + (long)(brow + wr0 + m * 16 + fq * 4) * DFF + oc + (odd ? 15 + fr : fr);
; #pragma unroll
;               for (int j = 0; j < 4; ++j)
; #pragma unroll
;                 for (int n0 = 0; n0 < 4; n0 += 2) { const float a0 = a[n0][j], a1 = a[n0 + 1][j];
;                   const float g0 = a0 * sigmoidf_(a0) * a[n0 + 4][j], g1 = a1 * sigmoidf_(a1) * a[n0 + 5][j];
;                   const float recv = dpp_xor1(odd ? g0 : g1);
;                   *reinterpret_cast<unsigned*>(p0 + (long)j * DFF + n0 * 16) = odd ? cvtpk(recv, g1) : cvtpk(g0, recv); }
;               SBAR(); };
.LBB0_4486:
	s_or_b64 exec, exec, s[2:3]
	v_mul_f32_e32 v0, 0xbfb8aa3b, v27
	v_exp_f32_e32 v0, v0
	v_add_co_u32_e32 v4, vcc, 0x2000, v32
	v_add_f32_e32 v0, 1.0, v0
	s_nop 0
	v_addc_co_u32_e32 v5, vcc, 0, v33, vcc
	global_store_dword v[4:5], v1, off offset:3136
	s_nop 0
	v_rcp_f32_e32 v2, v0
	s_nop 0
	v_fma_f32 v1, -v0, v2, 1.0
	v_fma_f32 v1, v1, v2, v2
	v_div_fixup_f32 v0, v1, v0, 1.0
	v_mul_f32_e32 v1, 0xbfb8aa3b, v19
	v_exp_f32_e32 v1, v1
	v_mul_f32_e32 v0, v27, v0
	v_mul_f32_e32 v0, v31, v0
	v_add_f32_e32 v1, 1.0, v1
	s_nop 0
	v_rcp_f32_e32 v4, v1
	s_nop 0
	v_fma_f32 v2, -v1, v4, 1.0
	v_fma_f32 v2, v2, v4, v4
	v_div_fixup_f32 v1, v2, v1, 1.0
	v_mul_f32_e32 v1, v19, v1
	v_mul_f32_e32 v4, v23, v1
	v_cndmask_b32_e64 v1, v4, v0, s[6:7]
	s_nop 1
	v_mov_b32_dpp v2, v1 quad_perm:[1,0,3,2] row_mask:0xf bank_mask:0xf bound_ctrl:1
	s_and_saveexec_b64 s[2:3], s[18:19]
	s_xor_b64 s[2:3], exec, s[2:3]
	s_cbranch_execz .LBB0_4488
	v_cvt_pk_bf16_f32 v1, v0, v2

; #define SBAR() __builtin_amdgcn_sched_barrier(0)
; DEVFI float dpp_xor1(float x) { return __int_as_float(__builtin_amdgcn_update_dpp(0, __float_as_int(x), 0xB1, 0xF, 0xF, true)); }
; #define G ((bfraw*)(kargs()->ws + O_G))
; DEVFI float sigmoidf_(float x) { return 1.f / (1.f + __expf(-x)); }
; __global__ void __launch_bounds__(512) mega(Params p) {
;     ...
;             auto slab = [&](f32x4 (&a)[8], const int m) {
;               bfraw* p0 = G + (long)(brow + wr0 + m * 16 + fq * 4) * DFF + oc + (odd ? 15 + fr : fr);
; #pragma unroll
;               for (int j = 0; j < 4; ++j)
; #pragma unroll
;                 for (int n0 = 0; n0 < 4; n0 += 2) { const float a0 = a[n0][j], a1 = a[n0 + 1][j];
;                   const float g0 = a0 * sigmoidf_(a0) * a[n0 + 4][j], g1 = a1 * sigmoidf_(a1) * a[n0 + 5][j];
;                   const float recv = dpp_xor1(odd ? g0 : g1);
;                   *reinterpret_cast<unsigned*>(p0 + (long)j * DFF + n0 * 16) = odd ? cvtpk(recv, g1) : cvtpk(g0, recv); }
;               SBAR(); };
.LBB0_4490:
	s_or_b64 exec, exec, s[2:3]
	v_mul_f32_e32 v0, 0xbfb8aa3b, v11
	v_exp_f32_e32 v0, v0
	v_add_co_u32_e32 v4, vcc, 0x4000, v32
	v_add_f32_e32 v0, 1.0, v0
	s_nop 0
	v_addc_co_u32_e32 v5, vcc, 0, v33, vcc
	global_store_dword v[4:5], v1, off offset:512
	s_nop 0
	v_rcp_f32_e32 v2, v0
	s_nop 0
	v_fma_f32 v1, -v0, v2, 1.0
	v_fma_f32 v1, v1, v2, v2
	v_div_fixup_f32 v0, v1, v0, 1.0
	v_mul_f32_e32 v1, 0xbfb8aa3b, v3
	v_exp_f32_e32 v1, v1
	v_mul_f32_e32 v0, v11, v0
	v_mul_f32_e32 v0, v15, v0
	v_add_f32_e32 v1, 1.0, v1
	s_nop 0
	v_rcp_f32_e32 v4, v1
	s_nop 0
	v_fma_f32 v2, -v1, v4, 1.0
	v_fma_f32 v2, v2, v4, v4
	v_div_fixup_f32 v1, v2, v1, 1.0
	v_mul_f32_e32 v1, v3, v1
	v_mul_f32_e32 v3, v7, v1
	v_cndmask_b32_e64 v1, v3, v0, s[6:7]
	s_nop 1
	v_mov_b32_dpp v2, v1 quad_perm:[1,0,3,2] row_mask:0xf bank_mask:0xf bound_ctrl:1
	s_and_saveexec_b64 s[2:3], s[18:19]
	s_xor_b64 s[2:3], exec, s[2:3]
	s_cbranch_execz .LBB0_4492
	v_cvt_pk_bf16_f32 v1, v0, v2

; DEVFI void ln_resid4(const float* ysrc, float* ydst, bfraw* fb, float* stats, const float* pw, const float* pb,
;                      const float* w, const float* b, int lane, bool fin) {
;   f32x4 v[4][4];
; #pragma unroll
;   for (int r = 0; r < 4; ++r)
; #pragma unroll
;     for (int i = 0; i < 4; ++i) v[r][i] = __builtin_nontemporal_load((const f32x4*)(ysrc + r * 1024) + i * 64 + lane);
;   u32x2 fv[4][4];
; #pragma unroll
;   for (int r = 0; r < 4; ++r)
; #pragma unroll
;     for (int i = 0; i < 4; ++i) fv[r][i] = __builtin_nontemporal_load((const u32x2*)(fb + r * 1024) + i * 64 + lane);
;   f32x4 pwv[4], pbv[4], ww[4], bb[4];
; #pragma unroll
;   for (int i = 0; i < 4; ++i) { pwv[i] = ((const f32x4*)pw)[i * 64 + lane]; pbv[i] = ((const f32x4*)pb)[i * 64 + lane];
;     ww[i] = ((const f32x4*)w)[i * 64 + lane]; bb[i] = ((const f32x4*)b)[i * 64 + lane]; }
; #pragma unroll
;   for (int r = 0; r < 4; ++r) {
;     const float pmu = stats[r * 2], prs = stats[r * 2 + 1];
;     f32x4 y[4];
; #pragma unroll
;     for (int i = 0; i < 4; ++i) { const unsigned f0 = fv[r][i][0], f1 = fv[r][i][1];
;       const f32x4 f4 = {__uint_as_float(f0 << 16), __uint_as_float(f0 & 0xffff0000u), __uint_as_float(f1 << 16), __uint_as_float(f1 & 0xffff0000u)};
;       y[i] = ALPHA * ((v[r][i] - pmu) * prs * pwv[i] + pbv[i]) + f4; }
;     float s = 0;
; #pragma unroll
;     for (int i = 0; i < 4; ++i) s += y[i][0] + y[i][1] + y[i][2] + y[i][3];
.LBB0_4780:
	v_add_co_u32_e32 v0, vcc, 0x1000, v142
	global_load_dwordx4 v[124:127], v[142:143], off nt
	global_load_dwordx4 v[120:123], v[142:143], off offset:1024 nt
	global_load_dwordx4 v[116:119], v[142:143], off offset:2048 nt
	global_load_dwordx4 v[112:115], v[142:143], off offset:3072 nt
	v_addc_co_u32_e32 v1, vcc, 0, v143, vcc
	global_load_dwordx4 v[108:111], v[0:1], off nt
	global_load_dwordx4 v[104:107], v[0:1], off offset:1024 nt
	global_load_dwordx4 v[100:103], v[0:1], off offset:2048 nt
	global_load_dwordx4 v[96:99], v[0:1], off offset:3072 nt
	v_add_co_u32_e32 v0, vcc, s53, v142
	s_movk_i32 s2, 0x3000
	s_nop 0
	v_addc_co_u32_e32 v1, vcc, 0, v143, vcc
	v_add_co_u32_e32 v2, vcc, s2, v142
	s_mov_b32 s2, -1
	s_nop 0
	v_addc_co_u32_e32 v3, vcc, 0, v143, vcc
	global_load_dwordx4 v[92:95], v[2:3], off offset:-4096 nt
	global_load_dwordx4 v[88:91], v[0:1], off offset:1024 nt
	global_load_dwordx4 v[84:87], v[0:1], off offset:2048 nt
	global_load_dwordx4 v[80:83], v[0:1], off offset:3072 nt
	global_load_dwordx4 v[44:47], v[2:3], off nt
	global_load_dwordx4 v[40:43], v[2:3], off offset:1024 nt
	global_load_dwordx4 v[36:39], v[2:3], off offset:2048 nt
	global_load_dwordx4 v[32:35], v[2:3], off offset:3072 nt
	global_load_dwordx2 v[174:175], v[138:139], off nt
	global_load_dwordx2 v[172:173], v[138:139], off offset:512 nt
	global_load_dwordx2 v[170:171], v[138:139], off offset:1024 nt
	global_load_dwordx2 v[168:169], v[138:139], off offset:1536 nt
	global_load_dwordx2 v[166:167], v[138:139], off offset:2048 nt
	global_load_dwordx2 v[164:165], v[138:139], off offset:2560 nt
	global_load_dwordx2 v[162:163], v[138:139], off offset:3072 nt
	global_load_dwordx2 v[160:161], v[138:139], off offset:3584 nt
	v_add_co_u32_e32 v0, vcc, s56, v138
	v_mov_b32_e32 v192, 0x10000
	s_nop 0
	v_addc_co_u32_e32 v1, vcc, 0, v139, vcc
	global_load_dwordx2 v[158:159], v[0:1], off nt
	global_load_dwordx2 v[156:157], v[0:1], off offset:512 nt
	global_load_dwordx2 v[154:155], v[0:1], off offset:1024 nt
	global_load_dwordx2 v[152:153], v[0:1], off offset:1536 nt
	global_load_dwordx2 v[150:151], v[0:1], off offset:2048 nt
	global_load_dwordx2 v[148:149], v[0:1], off offset:2560 nt
	global_load_dwordx2 v[146:147], v[0:1], off offset:3072 nt
	global_load_dwordx2 v[144:145], v[0:1], off offset:3584 nt
	global_load_dwordx4 v[64:67], v[130:131], off
	global_load_dwordx4 v[68:71], v[132:133], off
	global_load_dwordx4 v[24:27], v[134:135], off
	global_load_dwordx4 v[28:31], v[136:137], off
	global_load_dwordx4 v[72:75], v[130:131], off offset:1024
	global_load_dwordx4 v[76:79], v[132:133], off offset:1024
	global_load_dwordx4 v[16:19], v[134:135], off offset:1024
	global_load_dwordx4 v[20:23], v[136:137], off offset:1024
	global_load_dwordx4 v[56:59], v[130:131], off offset:2048
	global_load_dwordx4 v[60:63], v[132:133], off offset:2048
	global_load_dwordx4 v[8:11], v[134:135], off offset:2048
	global_load_dwordx4 v[12:15], v[136:137], off offset:2048
	global_load_dwordx4 v[48:51], v[130:131], off offset:3072
	global_load_dwordx4 v[52:55], v[132:133], off offset:3072
	global_load_dwordx4 v[0:3], v[134:135], off offset:3072
	global_load_dwordx4 v[4:7], v[136:137], off offset:3072
	global_load_dwordx2 v[184:185], v[140:141], off
	s_waitcnt vmcnt(32)
	v_lshlrev_b32_e32 v178, 16, v174
	v_and_b32_e32 v179, 0xffff0000, v174
	v_lshlrev_b32_e32 v174, 16, v175
	v_and_b32_e32 v175, 0xffff0000, v175
	s_waitcnt vmcnt(0)
	v_sub_f32_e32 v127, v127, v184
	v_sub_f32_e32 v126, v126, v184
	v_pk_mul_f32 v[126:127], v[184:185], v[126:127] op_sel:[1,0]
	v_sub_f32_e32 v123, v123, v184
	v_sub_f32_e32 v122, v122, v184
	v_sub_f32_e32 v125, v125, v184
	v_sub_f32_e32 v124, v124, v184
	v_pk_fma_f32 v[126:127], v[66:67], v[126:127], v[70:71]
	v_sub_f32_e32 v121, v121, v184
	v_sub_f32_e32 v120, v120, v184
	v_pk_mul_f32 v[122:123], v[184:185], v[122:123] op_sel:[1,0]
	v_sub_f32_e32 v119, v119, v184
	v_sub_f32_e32 v118, v118, v184
	v_pk_mul_f32 v[124:125], v[184:185], v[124:125] op_sel:[1,0]
	v_pk_fma_f32 v[126:127], v[126:127], s[52:53], v[174:175] op_sel_hi:[1,0,1]
	v_lshlrev_b32_e32 v174, 16, v172
	v_and_b32_e32 v175, 0xffff0000, v172
	v_lshlrev_b32_e32 v172, 16, v173
	v_and_b32_e32 v173, 0xffff0000, v173
	v_pk_mul_f32 v[120:121], v[184:185], v[120:121] op_sel:[1,0]
	v_pk_fma_f32 v[122:123], v[74:75], v[122:123], v[78:79]
	v_pk_mul_f32 v[118:119], v[184:185], v[118:119] op_sel:[1,0]
	v_sub_f32_e32 v113, v113, v184
	v_sub_f32_e32 v112, v112, v184
	v_sub_f32_e32 v115, v115, v184
	v_sub_f32_e32 v114, v114, v184
	v_pk_fma_f32 v[124:125], v[64:65], v[124:125], v[68:69]
	v_pk_fma_f32 v[120:121], v[72:73], v[120:121], v[76:77]
	v_pk_fma_f32 v[122:123], v[122:123], s[52:53], v[172:173] op_sel_hi:[1,0,1]
	v_lshlrev_b32_e32 v172, 16, v170
	v_and_b32_e32 v173, 0xffff0000, v170
	v_lshlrev_b32_e32 v170, 16, v171
	v_and_b32_e32 v171, 0xffff0000, v171
	v_pk_fma_f32 v[118:119], v[58:59], v[118:119], v[62:63]
	v_pk_mul_f32 v[114:115], v[184:185], v[114:115] op_sel:[1,0]
	v_pk_mul_f32 v[112:113], v[184:185], v[112:113] op_sel:[1,0]
	v_pk_fma_f32 v[124:125], v[124:125], s[52:53], v[178:179] op_sel_hi:[1,0,1]
	v_pk_fma_f32 v[120:121], v[120:121], s[52:53], v[174:175] op_sel_hi:[1,0,1]
	v_pk_fma_f32 v[118:119], v[118:119], s[52:53], v[170:171] op_sel_hi:[1,0,1]
	v_lshlrev_b32_e32 v170, 16, v168
	v_and_b32_e32 v171, 0xffff0000, v168
	v_lshlrev_b32_e32 v168, 16, v169
	v_and_b32_e32 v169, 0xffff0000, v169
	v_pk_fma_f32 v[112:113], v[48:49], v[112:113], v[52:53]
	v_pk_fma_f32 v[114:115], v[50:51], v[114:115], v[54:55]
	v_pk_fma_f32 v[112:113], v[112:113], s[52:53], v[170:171] op_sel_hi:[1,0,1]
	v_pk_fma_f32 v[114:115], v[114:115], s[52:53], v[168:169] op_sel_hi:[1,0,1]
	v_mov_b32_e32 v168, v120
	v_mov_b32_e32 v169, v124
	v_mov_b32_e32 v170, v121
	v_mov_b32_e32 v171, v125
	v_sub_f32_e32 v117, v117, v184
	v_sub_f32_e32 v116, v116, v184
	v_pk_add_f32 v[168:169], v[168:169], v[170:171]
	v_mov_b32_e32 v170, v122
	v_mov_b32_e32 v171, v126
	v_pk_mul_f32 v[116:117], v[184:185], v[116:117] op_sel:[1,0]
	v_pk_add_f32 v[168:169], v[170:171], v[168:169]
	v_mov_b32_e32 v170, v123
	v_mov_b32_e32 v171, v127
	v_pk_fma_f32 v[116:117], v[56:57], v[116:117], v[60:61]
	v_pk_add_f32 v[168:169], v[170:171], v[168:169]
	v_pk_fma_f32 v[116:117], v[116:117], s[52:53], v[172:173] op_sel_hi:[1,0,1]
	v_add_f32_e32 v129, 0, v169
	v_add_f32_e32 v129, v168, v129
	v_mov_b32_e32 v168, v112
	v_mov_b32_e32 v169, v116
	v_mov_b32_e32 v170, v113
	v_mov_b32_e32 v171, v117
	v_pk_add_f32 v[168:169], v[168:169], v[170:171]
	v_mov_b32_e32 v170, v114
	v_mov_b32_e32 v171, v118
	v_pk_add_f32 v[168:169], v[170:171], v[168:169]
	v_mov_b32_e32 v170, v115
	v_mov_b32_e32 v171, v119
	v_pk_add_f32 v[168:169], v[170:171], v[168:169]
	s_nop 0
	v_add_f32_e32 v129, v169, v129
	v_add_f32_e32 v129, v168, v129
	v_mbcnt_lo_u32_b32 v168, s2, 0
	v_mbcnt_hi_u32_b32 v168, s2, v168
	v_lshlrev_b32_e32 v168, 2, v168
	v_xor_b32_e32 v169, 0x80, v168
	ds_bpermute_b32 v169, v169, v129
	s_mov_b32 s2, -1
	s_waitcnt lgkmcnt(0)
; DEVFI void ln_resid4(const float* ysrc, float* ydst, bfraw* fb, float* stats, const float* pw, const float* pb,
;                      const float* w, const float* b, int lane, bool fin) {
;     ...
;     const float mean = red64(s) * (1.f / 1024.f);
;     float q = 0;
; #pragma unroll
;     for (int i = 0; i < 4; ++i) { const f32x4 d = y[i] - mean; q += d[0] * d[0] + d[1] * d[1] + d[2] * d[2] + d[3] * d[3]; }
;     const float rstd = 1.f / sqrtf(red64(q) * (1.f / 1024.f) + LN_EPS);
;     if (lane == 0) { stats[r * 2] = mean; stats[r * 2 + 1] = rstd; }
; #pragma unroll
;     for (int i = 0; i < 4; ++i) { const int c4 = i * 64 + lane;
;       const f32x4 z = (y[i] - mean) * rstd * ww[i] + bb[i];
;       __builtin_nontemporal_store(fin ? z : y[i], (f32x4*)(ydst + r * 1024) + c4);
;       u32x2 pk = {cvtpk(z[0], z[1]), cvtpk(z[2], z[3])}; ((u32x2*)(fb + r * 1024))[c4] = pk; }
	v_add_f32_e32 v129, v129, v169
	v_xor_b32_e32 v169, 64, v168
	ds_bpermute_b32 v169, v169, v129
	s_waitcnt lgkmcnt(0)
	v_add_f32_e32 v129, v129, v169
	v_xor_b32_e32 v169, 32, v168
	ds_bpermute_b32 v169, v169, v129
	s_waitcnt lgkmcnt(0)
	v_add_f32_e32 v129, v129, v169
	v_xor_b32_e32 v169, 16, v168
	ds_bpermute_b32 v169, v169, v129
	s_waitcnt lgkmcnt(0)
	v_add_f32_e32 v129, v129, v169
	v_xor_b32_e32 v169, 8, v168
	ds_bpermute_b32 v169, v169, v129
	v_xor_b32_e32 v168, 4, v168
	s_waitcnt lgkmcnt(0)
	v_add_f32_e32 v129, v129, v169
	ds_bpermute_b32 v168, v168, v129
	s_waitcnt lgkmcnt(0)
	v_add_f32_e32 v129, v129, v168
	v_fmamk_f32 v191, v129, 0xba800000, v125
	v_fmamk_f32 v187, v129, 0xba800000, v121
	v_fmamk_f32 v190, v129, 0xba800000, v124
	v_mul_f32_e32 v168, v191, v191
	v_fmamk_f32 v186, v129, 0xba800000, v120
	v_mul_f32_e32 v169, v187, v187
	v_fmamk_f32 v188, v129, 0xba800000, v126
	v_fmac_f32_e32 v168, v190, v190
	v_fmamk_f32 v184, v129, 0xba800000, v122
	v_fmac_f32_e32 v169, v186, v186
	v_fmamk_f32 v189, v129, 0xba800000, v127
	v_fmac_f32_e32 v168, v188, v188
	v_fmamk_f32 v185, v129, 0xba800000, v123
	v_fmac_f32_e32 v169, v184, v184
	v_fmac_f32_e32 v168, v189, v189
	v_fmac_f32_e32 v169, v185, v185
	v_fmamk_f32 v175, v129, 0xba800000, v117
	v_add_f32_e32 v168, v168, v169
	v_fmamk_f32 v174, v129, 0xba800000, v116
	v_mul_f32_e32 v169, v175, v175
	v_fmamk_f32 v172, v129, 0xba800000, v118
	v_fmac_f32_e32 v169, v174, v174
	v_fmamk_f32 v173, v129, 0xba800000, v119
	v_fmac_f32_e32 v169, v172, v172
	v_fmamk_f32 v171, v129, 0xba800000, v113
	v_fmac_f32_e32 v169, v173, v173
	v_fmamk_f32 v170, v129, 0xba800000, v112
	v_mul_f32_e32 v178, v171, v171
	v_add_f32_e32 v176, v169, v168
	v_fmamk_f32 v168, v129, 0xba800000, v114
	v_fmac_f32_e32 v178, v170, v170
	v_fmamk_f32 v169, v129, 0xba800000, v115
	v_fmac_f32_e32 v178, v168, v168
	v_fmac_f32_e32 v178, v169, v169
	v_add_f32_e32 v176, v178, v176
	v_mbcnt_lo_u32_b32 v178, s2, 0
	v_mbcnt_hi_u32_b32 v178, s2, v178
	v_lshlrev_b32_e32 v178, 2, v178
	v_xor_b32_e32 v179, 0x80, v178
	ds_bpermute_b32 v179, v179, v176
	s_waitcnt lgkmcnt(0)
	v_add_f32_e32 v176, v176, v179
	v_xor_b32_e32 v179, 64, v178
	ds_bpermute_b32 v179, v179, v176
	s_waitcnt lgkmcnt(0)
	v_add_f32_e32 v176, v176, v179
	v_xor_b32_e32 v179, 32, v178
	ds_bpermute_b32 v179, v179, v176
	s_waitcnt lgkmcnt(0)
	v_add_f32_e32 v176, v176, v179
	v_xor_b32_e32 v179, 16, v178
	ds_bpermute_b32 v179, v179, v176
	s_waitcnt lgkmcnt(0)
	v_add_f32_e32 v176, v176, v179
	v_xor_b32_e32 v179, 8, v178
	ds_bpermute_b32 v179, v179, v176
	v_xor_b32_e32 v178, 4, v178
	s_waitcnt lgkmcnt(0)
	v_add_f32_e32 v176, v176, v179
	ds_bpermute_b32 v178, v178, v176
	s_waitcnt lgkmcnt(0)
	v_add_f32_e32 v176, v176, v178
	v_fmamk_f32 v176, v176, 0x3a800000, v183
	v_cmp_gt_f32_e32 vcc, s30, v176
	v_mul_f32_e32 v178, 0x4f800000, v176
	s_nop 0
	v_cndmask_b32_e32 v176, v176, v178, vcc
	v_sqrt_f32_e32 v178, v176
	s_nop 0
	v_add_u32_e32 v179, -1, v178
	v_fma_f32 v180, -v179, v178, v176
	v_cmp_ge_f32_e64 s[8:9], 0, v180
	v_add_u32_e32 v180, 1, v178
	s_nop 0
	v_cndmask_b32_e64 v179, v178, v179, s[8:9]
	v_fma_f32 v178, -v180, v178, v176
	v_cmp_lt_f32_e64 s[8:9], 0, v178
	s_nop 1
	v_cndmask_b32_e64 v178, v179, v180, s[8:9]
	v_mul_f32_e32 v179, 0x37800000, v178
	v_cndmask_b32_e32 v178, v178, v179, vcc
	v_cmp_class_f32_e32 vcc, v176, v222
	s_nop 1
	v_cndmask_b32_e32 v176, v178, v176, vcc
	s_nop 0
	v_rcp_f32_e32 v179, v176
	s_nop 0
	v_fma_f32 v178, -v176, v179, 1.0
	v_fma_f32 v178, v178, v179, v179
	v_div_fixup_f32 v176, v178, v176, 1.0
	s_and_saveexec_b64 s[2:3], s[6:7]
	s_cbranch_execz .LBB0_4782
	v_mul_f32_e32 v178, 0x3a800000, v129
	v_mov_b32_e32 v179, v176
	global_store_dwordx2 v[140:141], v[178:179], off
.LBB0_4782:
	s_or_b64 exec, exec, s[2:3]
	v_pk_mul_f32 v[178:179], v[188:189], v[176:177] op_sel_hi:[1,0]
	v_pk_mul_f32 v[180:181], v[190:191], v[176:177] op_sel_hi:[1,0]
	v_pk_fma_f32 v[178:179], v[26:27], v[178:179], v[30:31]
	v_pk_fma_f32 v[180:181], v[24:25], v[180:181], v[28:29]
	v_cndmask_b32_e64 v127, v127, v179, s[4:5]
	v_cndmask_b32_e64 v126, v126, v178, s[4:5]
	v_cndmask_b32_e64 v125, v125, v181, s[4:5]
	v_cndmask_b32_e64 v124, v124, v180, s[4:5]
	global_store_dwordx4 v[142:143], v[124:127], off nt
	s_mov_b32 s2, -1
	s_nop 0
	v_cvt_pk_bf16_f32 v124, v180, v181
	v_cvt_pk_bf16_f32 v125, v178, v179
	global_store_dwordx2 v[138:139], v[124:125], off
	v_pk_mul_f32 v[124:125], v[184:185], v[176:177] op_sel_hi:[1,0]
	v_pk_mul_f32 v[126:127], v[186:187], v[176:177] op_sel_hi:[1,0]
	v_pk_fma_f32 v[124:125], v[18:19], v[124:125], v[22:23]
	v_pk_fma_f32 v[126:127], v[16:17], v[126:127], v[20:21]
	v_cndmask_b32_e64 v123, v123, v125, s[4:5]
	v_cndmask_b32_e64 v122, v122, v124, s[4:5]
	v_cndmask_b32_e64 v121, v121, v127, s[4:5]
	v_cndmask_b32_e64 v120, v120, v126, s[4:5]
	global_store_dwordx4 v[142:143], v[120:123], off offset:1024 nt
	s_nop 1
	v_cvt_pk_bf16_f32 v120, v126, v127
	v_cvt_pk_bf16_f32 v121, v124, v125
	global_store_dwordx2 v[138:139], v[120:121], off offset:512
	v_pk_mul_f32 v[120:121], v[172:173], v[176:177] op_sel_hi:[1,0]
	v_pk_mul_f32 v[122:123], v[174:175], v[176:177] op_sel_hi:[1,0]
	v_pk_fma_f32 v[120:121], v[10:11], v[120:121], v[14:15]
	v_pk_fma_f32 v[122:123], v[8:9], v[122:123], v[12:13]
	v_cndmask_b32_e64 v119, v119, v121, s[4:5]
	v_cndmask_b32_e64 v118, v118, v120, s[4:5]
	v_cndmask_b32_e64 v117, v117, v123, s[4:5]
	v_cndmask_b32_e64 v116, v116, v122, s[4:5]
	global_store_dwordx4 v[142:143], v[116:119], off offset:2048 nt
	v_lshlrev_b32_e32 v126, 16, v160
	v_and_b32_e32 v127, 0xffff0000, v160
	v_cvt_pk_bf16_f32 v116, v122, v123
	v_cvt_pk_bf16_f32 v117, v120, v121
	global_store_dwordx2 v[138:139], v[116:117], off offset:1024
	v_pk_mul_f32 v[116:117], v[168:169], v[176:177] op_sel_hi:[1,0]
	v_pk_mul_f32 v[118:119], v[170:171], v[176:177] op_sel_hi:[1,0]
	v_pk_fma_f32 v[116:117], v[2:3], v[116:117], v[6:7]
	v_pk_fma_f32 v[118:119], v[0:1], v[118:119], v[4:5]
	v_cndmask_b32_e64 v115, v115, v117, s[4:5]
	v_cndmask_b32_e64 v114, v114, v116, s[4:5]
	v_cndmask_b32_e64 v113, v113, v119, s[4:5]
	v_cndmask_b32_e64 v112, v112, v118, s[4:5]
	global_store_dwordx4 v[142:143], v[112:115], off offset:3072 nt
	v_lshlrev_b32_e32 v120, 16, v165
	v_and_b32_e32 v121, 0xffff0000, v165
	v_cvt_pk_bf16_f32 v112, v118, v119
	v_cvt_pk_bf16_f32 v113, v116, v117
	global_store_dwordx2 v[138:139], v[112:113], off offset:1536
	global_load_dwordx2 v[112:113], v[140:141], off offset:8
	v_lshlrev_b32_e32 v114, 16, v166
	v_and_b32_e32 v115, 0xffff0000, v166
	v_lshlrev_b32_e32 v118, 16, v164
	v_and_b32_e32 v119, 0xffff0000, v164
	v_lshlrev_b32_e32 v116, 16, v167
	v_and_b32_e32 v117, 0xffff0000, v167
	v_lshlrev_b32_e32 v122, 16, v162
	v_and_b32_e32 v123, 0xffff0000, v162
	v_lshlrev_b32_e32 v124, 16, v163
	v_and_b32_e32 v125, 0xffff0000, v163
	s_waitcnt vmcnt(0)
; DEVFI void ln_resid4(const float* ysrc, float* ydst, bfraw* fb, float* stats, const float* pw, const float* pb,
;                      const float* w, const float* b, int lane, bool fin) {
;     ...
;   for (int r = 0; r < 4; ++r) {
;     const float pmu = stats[r * 2], prs = stats[r * 2 + 1];
;     f32x4 y[4];
; #pragma unroll
;     for (int i = 0; i < 4; ++i) { const unsigned f0 = fv[r][i][0], f1 = fv[r][i][1];
;       const f32x4 f4 = {__uint_as_float(f0 << 16), __uint_as_float(f0 & 0xffff0000u), __uint_as_float(f1 << 16), __uint_as_float(f1 & 0xffff0000u)};
;       y[i] = ALPHA * ((v[r][i] - pmu) * prs * pwv[i] + pbv[i]) + f4; }
;     float s = 0;
; #pragma unroll
;     for (int i = 0; i < 4; ++i) s += y[i][0] + y[i][1] + y[i][2] + y[i][3];
;     const float mean = red64(s) * (1.f / 1024.f);
;     float q = 0;
; #pragma unroll
;     for (int i = 0; i < 4; ++i) { const f32x4 d = y[i] - mean; q += d[0] * d[0] + d[1] * d[1] + d[2] * d[2] + d[3] * d[3]; }
;     const float rstd = 1.f / sqrtf(red64(q) * (1.f / 1024.f) + LN_EPS);
;     if (lane == 0) { stats[r * 2] = mean; stats[r * 2 + 1] = rstd; }
	v_sub_f32_e32 v109, v109, v112
	v_sub_f32_e32 v108, v108, v112
	v_sub_f32_e32 v105, v105, v112
	v_sub_f32_e32 v104, v104, v112
	v_sub_f32_e32 v111, v111, v112
	v_sub_f32_e32 v110, v110, v112
	v_sub_f32_e32 v107, v107, v112
	v_sub_f32_e32 v106, v106, v112
	v_pk_mul_f32 v[108:109], v[112:113], v[108:109] op_sel:[1,0]
	v_pk_mul_f32 v[104:105], v[112:113], v[104:105] op_sel:[1,0]
	v_sub_f32_e32 v99, v99, v112
	v_sub_f32_e32 v98, v98, v112
	v_pk_mul_f32 v[110:111], v[112:113], v[110:111] op_sel:[1,0]
	v_pk_mul_f32 v[106:107], v[112:113], v[106:107] op_sel:[1,0]
	v_pk_fma_f32 v[108:109], v[64:65], v[108:109], v[68:69]
	v_pk_fma_f32 v[104:105], v[72:73], v[104:105], v[76:77]
	v_pk_mul_f32 v[98:99], v[112:113], v[98:99] op_sel:[1,0]
	v_sub_f32_e32 v101, v101, v112
	v_sub_f32_e32 v100, v100, v112
	v_sub_f32_e32 v103, v103, v112
	v_sub_f32_e32 v102, v102, v112
	v_pk_fma_f32 v[110:111], v[66:67], v[110:111], v[70:71]
	v_pk_fma_f32 v[106:107], v[74:75], v[106:107], v[78:79]
	v_pk_fma_f32 v[108:109], v[108:109], s[52:53], v[114:115] op_sel_hi:[1,0,1]
	v_pk_fma_f32 v[104:105], v[104:105], s[52:53], v[118:119] op_sel_hi:[1,0,1]
	v_lshlrev_b32_e32 v114, 16, v161
	v_and_b32_e32 v115, 0xffff0000, v161
	v_sub_f32_e32 v97, v97, v112
	v_sub_f32_e32 v96, v96, v112
	v_pk_fma_f32 v[98:99], v[50:51], v[98:99], v[54:55]
	v_pk_mul_f32 v[102:103], v[112:113], v[102:103] op_sel:[1,0]
	v_pk_mul_f32 v[100:101], v[112:113], v[100:101] op_sel:[1,0]
	v_pk_fma_f32 v[110:111], v[110:111], s[52:53], v[116:117] op_sel_hi:[1,0,1]
	v_pk_fma_f32 v[106:107], v[106:107], s[52:53], v[120:121] op_sel_hi:[1,0,1]
	v_pk_mul_f32 v[96:97], v[112:113], v[96:97] op_sel:[1,0]
	v_pk_fma_f32 v[98:99], v[98:99], s[52:53], v[114:115] op_sel_hi:[1,0,1]
	v_mov_b32_e32 v112, v104
	v_mov_b32_e32 v113, v108
	v_mov_b32_e32 v114, v105
	v_mov_b32_e32 v115, v109
	v_pk_add_f32 v[112:113], v[112:113], v[114:115]
	v_mov_b32_e32 v114, v106
	v_mov_b32_e32 v115, v110
	v_pk_add_f32 v[112:113], v[114:115], v[112:113]
	v_mov_b32_e32 v114, v107
	v_mov_b32_e32 v115, v111
	v_pk_fma_f32 v[100:101], v[56:57], v[100:101], v[60:61]
	v_pk_fma_f32 v[96:97], v[48:49], v[96:97], v[52:53]
	v_pk_add_f32 v[112:113], v[114:115], v[112:113]
	v_pk_fma_f32 v[102:103], v[58:59], v[102:103], v[62:63]
	v_pk_fma_f32 v[100:101], v[100:101], s[52:53], v[122:123] op_sel_hi:[1,0,1]
	v_pk_fma_f32 v[96:97], v[96:97], s[52:53], v[126:127] op_sel_hi:[1,0,1]
	v_add_f32_e32 v113, 0, v113
	v_pk_fma_f32 v[102:103], v[102:103], s[52:53], v[124:125] op_sel_hi:[1,0,1]
	v_add_f32_e32 v116, v112, v113
	v_mov_b32_e32 v112, v96
	v_mov_b32_e32 v113, v100
	v_mov_b32_e32 v114, v97
	v_mov_b32_e32 v115, v101
	v_pk_add_f32 v[112:113], v[112:113], v[114:115]
	v_mov_b32_e32 v114, v98
	v_mov_b32_e32 v115, v102
	v_pk_add_f32 v[112:113], v[114:115], v[112:113]
	v_mov_b32_e32 v114, v99
	v_mov_b32_e32 v115, v103
	v_pk_add_f32 v[112:113], v[114:115], v[112:113]
	s_nop 0
	v_add_f32_e32 v113, v113, v116
	v_add_f32_e32 v112, v112, v113
	v_mbcnt_lo_u32_b32 v113, s2, 0
	v_mbcnt_hi_u32_b32 v113, s2, v113
	v_lshlrev_b32_e32 v113, 2, v113
	v_xor_b32_e32 v114, 0x80, v113
	ds_bpermute_b32 v114, v114, v112
	s_mov_b32 s2, -1
	s_waitcnt lgkmcnt(0)
	v_add_f32_e32 v112, v112, v114
	v_xor_b32_e32 v114, 64, v113
	ds_bpermute_b32 v114, v114, v112
	s_waitcnt lgkmcnt(0)
	v_add_f32_e32 v112, v112, v114
	v_xor_b32_e32 v114, 32, v113
	ds_bpermute_b32 v114, v114, v112
	s_waitcnt lgkmcnt(0)
	v_add_f32_e32 v112, v112, v114
	v_xor_b32_e32 v114, 16, v113
	ds_bpermute_b32 v114, v114, v112
	s_waitcnt lgkmcnt(0)
	v_add_f32_e32 v112, v112, v114
	v_xor_b32_e32 v114, 8, v113
	ds_bpermute_b32 v114, v114, v112
	v_xor_b32_e32 v113, 4, v113
	s_waitcnt lgkmcnt(0)
	v_add_f32_e32 v112, v112, v114
	ds_bpermute_b32 v113, v113, v112
	s_waitcnt lgkmcnt(0)
	v_add_f32_e32 v129, v112, v113
	v_fmamk_f32 v127, v129, 0xba800000, v109
	v_fmamk_f32 v123, v129, 0xba800000, v105
	v_fmamk_f32 v126, v129, 0xba800000, v108
	v_mul_f32_e32 v112, v127, v127
	v_fmamk_f32 v122, v129, 0xba800000, v104
	v_mul_f32_e32 v113, v123, v123
	v_fmamk_f32 v124, v129, 0xba800000, v110
	v_fmac_f32_e32 v112, v126, v126
	v_fmamk_f32 v120, v129, 0xba800000, v106
	v_fmac_f32_e32 v113, v122, v122
	v_fmamk_f32 v125, v129, 0xba800000, v111
	v_fmac_f32_e32 v112, v124, v124
	v_fmamk_f32 v121, v129, 0xba800000, v107
	v_fmac_f32_e32 v113, v120, v120
	v_fmac_f32_e32 v112, v125, v125
	v_fmac_f32_e32 v113, v121, v121
	v_fmamk_f32 v119, v129, 0xba800000, v101
	v_add_f32_e32 v112, v112, v113
	v_fmamk_f32 v118, v129, 0xba800000, v100
	v_mul_f32_e32 v113, v119, v119
	v_fmamk_f32 v116, v129, 0xba800000, v102
	v_fmac_f32_e32 v113, v118, v118
	v_fmamk_f32 v117, v129, 0xba800000, v103
	v_fmac_f32_e32 v113, v116, v116
	v_fmamk_f32 v115, v129, 0xba800000, v97
	v_fmac_f32_e32 v113, v117, v117
	v_fmamk_f32 v114, v129, 0xba800000, v96
	v_mul_f32_e32 v161, v115, v115
	v_add_f32_e32 v160, v113, v112
	v_fmamk_f32 v112, v129, 0xba800000, v98
	v_fmac_f32_e32 v161, v114, v114
	v_fmamk_f32 v113, v129, 0xba800000, v99
	v_fmac_f32_e32 v161, v112, v112
	v_fmac_f32_e32 v161, v113, v113
	v_add_f32_e32 v160, v161, v160
	v_mbcnt_lo_u32_b32 v161, s2, 0
	v_mbcnt_hi_u32_b32 v161, s2, v161
	v_lshlrev_b32_e32 v161, 2, v161
	v_xor_b32_e32 v162, 0x80, v161
	ds_bpermute_b32 v162, v162, v160
	s_waitcnt lgkmcnt(0)
	v_add_f32_e32 v160, v160, v162
	v_xor_b32_e32 v162, 64, v161
	ds_bpermute_b32 v162, v162, v160
	s_waitcnt lgkmcnt(0)
	v_add_f32_e32 v160, v160, v162
	v_xor_b32_e32 v162, 32, v161
	ds_bpermute_b32 v162, v162, v160
	s_waitcnt lgkmcnt(0)
	v_add_f32_e32 v160, v160, v162
	v_xor_b32_e32 v162, 16, v161
	ds_bpermute_b32 v162, v162, v160
	s_waitcnt lgkmcnt(0)
	v_add_f32_e32 v160, v160, v162
	v_xor_b32_e32 v162, 8, v161
	ds_bpermute_b32 v162, v162, v160
	v_xor_b32_e32 v161, 4, v161
	s_waitcnt lgkmcnt(0)
	v_add_f32_e32 v160, v160, v162
	ds_bpermute_b32 v161, v161, v160
	s_waitcnt lgkmcnt(0)
	v_add_f32_e32 v160, v160, v161
	v_fmamk_f32 v160, v160, 0x3a800000, v183
	v_mul_f32_e32 v161, 0x4f800000, v160
	v_cmp_gt_f32_e32 vcc, s30, v160
	s_nop 1
	v_cndmask_b32_e32 v160, v160, v161, vcc
	v_sqrt_f32_e32 v161, v160
	s_nop 0
	v_add_u32_e32 v162, -1, v161
	v_fma_f32 v163, -v162, v161, v160
	v_cmp_ge_f32_e64 s[8:9], 0, v163
	v_add_u32_e32 v163, 1, v161
	s_nop 0
	v_cndmask_b32_e64 v162, v161, v162, s[8:9]
	v_fma_f32 v161, -v163, v161, v160
	v_cmp_lt_f32_e64 s[8:9], 0, v161
	s_nop 1
	v_cndmask_b32_e64 v161, v162, v163, s[8:9]
	v_mul_f32_e32 v162, 0x37800000, v161
	v_cndmask_b32_e32 v161, v161, v162, vcc
	v_cmp_class_f32_e32 vcc, v160, v222
	s_nop 1
	v_cndmask_b32_e32 v160, v161, v160, vcc
	s_nop 0
	v_rcp_f32_e32 v162, v160
	s_nop 0
	v_fma_f32 v161, -v160, v162, 1.0
	v_fma_f32 v161, v161, v162, v162
	v_div_fixup_f32 v160, v161, v160, 1.0
	s_and_saveexec_b64 s[2:3], s[6:7]
	s_cbranch_execz .LBB0_4784
	v_mul_f32_e32 v162, 0x3a800000, v129
	v_mov_b32_e32 v163, v160
	global_store_dwordx2 v[140:141], v[162:163], off offset:8
; DEVFI void ln_resid4(const float* ysrc, float* ydst, bfraw* fb, float* stats, const float* pw, const float* pb,
;                      const float* w, const float* b, int lane, bool fin) {
;     ...
;   for (int r = 0; r < 4; ++r) {
;     const float pmu = stats[r * 2], prs = stats[r * 2 + 1];
;     f32x4 y[4];
; #pragma unroll
;     for (int i = 0; i < 4; ++i) { const unsigned f0 = fv[r][i][0], f1 = fv[r][i][1];
;       const f32x4 f4 = {__uint_as_float(f0 << 16), __uint_as_float(f0 & 0xffff0000u), __uint_as_float(f1 << 16), __uint_as_float(f1 & 0xffff0000u)};
;       y[i] = ALPHA * ((v[r][i] - pmu) * prs * pwv[i] + pbv[i]) + f4; }
;     float s = 0;
; #pragma unroll
;     for (int i = 0; i < 4; ++i) s += y[i][0] + y[i][1] + y[i][2] + y[i][3];
;     const float mean = red64(s) * (1.f / 1024.f);
;     float q = 0;
; #pragma unroll
;     for (int i = 0; i < 4; ++i) { const f32x4 d = y[i] - mean; q += d[0] * d[0] + d[1] * d[1] + d[2] * d[2] + d[3] * d[3]; }
;     const float rstd = 1.f / sqrtf(red64(q) * (1.f / 1024.f) + LN_EPS);
;     if (lane == 0) { stats[r * 2] = mean; stats[r * 2 + 1] = rstd; }
; #pragma unroll
;     for (int i = 0; i < 4; ++i) { const int c4 = i * 64 + lane;
;       const f32x4 z = (y[i] - mean) * rstd * ww[i] + bb[i];
;       __builtin_nontemporal_store(fin ? z : y[i], (f32x4*)(ydst + r * 1024) + c4);
;       u32x2 pk = {cvtpk(z[0], z[1]), cvtpk(z[2], z[3])}; ((u32x2*)(fb + r * 1024))[c4] = pk; }
.LBB0_4784:
	s_or_b64 exec, exec, s[2:3]
	v_pk_mul_f32 v[124:125], v[124:125], v[160:161] op_sel_hi:[1,0]
	v_pk_mul_f32 v[126:127], v[126:127], v[160:161] op_sel_hi:[1,0]
	s_mov_b64 s[2:3], 0x1000
	v_pk_fma_f32 v[124:125], v[26:27], v[124:125], v[30:31]
	v_pk_fma_f32 v[126:127], v[24:25], v[126:127], v[28:29]
	v_lshl_add_u64 v[162:163], v[142:143], 0, s[2:3]
	v_cndmask_b32_e64 v111, v111, v125, s[4:5]
	v_cndmask_b32_e64 v110, v110, v124, s[4:5]
	v_cndmask_b32_e64 v109, v109, v127, s[4:5]
	v_cndmask_b32_e64 v108, v108, v126, s[4:5]
	global_store_dwordx4 v[162:163], v[108:111], off nt
	s_mov_b64 s[2:3], 0x1400
	v_lshl_add_u64 v[164:165], v[142:143], 0, s[2:3]
	v_cvt_pk_bf16_f32 v108, v126, v127
	v_cvt_pk_bf16_f32 v109, v124, v125
	global_store_dwordx2 v[138:139], v[108:109], off offset:2048
	v_pk_mul_f32 v[108:109], v[120:121], v[160:161] op_sel_hi:[1,0]
	v_pk_mul_f32 v[110:111], v[122:123], v[160:161] op_sel_hi:[1,0]
	v_pk_fma_f32 v[108:109], v[18:19], v[108:109], v[22:23]
	v_pk_fma_f32 v[110:111], v[16:17], v[110:111], v[20:21]
	v_cndmask_b32_e64 v107, v107, v109, s[4:5]
	v_cndmask_b32_e64 v106, v106, v108, s[4:5]
	v_cndmask_b32_e64 v105, v105, v111, s[4:5]
	v_cndmask_b32_e64 v104, v104, v110, s[4:5]
	global_store_dwordx4 v[164:165], v[104:107], off nt
	s_mov_b64 s[2:3], 0x1800
	v_lshl_add_u64 v[166:167], v[142:143], 0, s[2:3]
	v_cvt_pk_bf16_f32 v104, v110, v111
	v_cvt_pk_bf16_f32 v105, v108, v109
	global_store_dwordx2 v[138:139], v[104:105], off offset:2560
	v_pk_mul_f32 v[104:105], v[116:117], v[160:161] op_sel_hi:[1,0]
	v_pk_mul_f32 v[106:107], v[118:119], v[160:161] op_sel_hi:[1,0]
	v_pk_fma_f32 v[104:105], v[10:11], v[104:105], v[14:15]
	v_pk_fma_f32 v[106:107], v[8:9], v[106:107], v[12:13]
	v_cndmask_b32_e64 v103, v103, v105, s[4:5]
	v_cndmask_b32_e64 v102, v102, v104, s[4:5]
	v_cndmask_b32_e64 v101, v101, v107, s[4:5]
	v_cndmask_b32_e64 v100, v100, v106, s[4:5]
	global_store_dwordx4 v[166:167], v[100:103], off nt
	s_mov_b64 s[2:3], 0x1c00
	v_lshl_add_u64 v[168:169], v[142:143], 0, s[2:3]
	v_cvt_pk_bf16_f32 v100, v106, v107
	v_cvt_pk_bf16_f32 v101, v104, v105
	global_store_dwordx2 v[138:139], v[100:101], off offset:3072
	v_pk_mul_f32 v[100:101], v[112:113], v[160:161] op_sel_hi:[1,0]
	v_pk_mul_f32 v[102:103], v[114:115], v[160:161] op_sel_hi:[1,0]
	v_pk_fma_f32 v[100:101], v[2:3], v[100:101], v[6:7]
	v_pk_fma_f32 v[102:103], v[0:1], v[102:103], v[4:5]
	v_cndmask_b32_e64 v99, v99, v101, s[4:5]
	v_cndmask_b32_e64 v98, v98, v100, s[4:5]
	v_cndmask_b32_e64 v97, v97, v103, s[4:5]
	v_cndmask_b32_e64 v96, v96, v102, s[4:5]
	global_store_dwordx4 v[168:169], v[96:99], off nt
	v_lshlrev_b32_e32 v104, 16, v157
	v_and_b32_e32 v105, 0xffff0000, v157
	v_cvt_pk_bf16_f32 v96, v102, v103
	v_cvt_pk_bf16_f32 v97, v100, v101
	global_store_dwordx2 v[138:139], v[96:97], off offset:3584
	global_load_dwordx2 v[96:97], v[140:141], off offset:16
	v_lshlrev_b32_e32 v98, 16, v158
	v_and_b32_e32 v99, 0xffff0000, v158
	v_lshlrev_b32_e32 v102, 16, v156
	v_and_b32_e32 v103, 0xffff0000, v156
	v_lshlrev_b32_e32 v100, 16, v159
	v_and_b32_e32 v101, 0xffff0000, v159
	v_lshlrev_b32_e32 v106, 16, v154
	v_and_b32_e32 v107, 0xffff0000, v154
	v_lshlrev_b32_e32 v108, 16, v155
	v_and_b32_e32 v109, 0xffff0000, v155
	s_mov_b32 s2, -1
	s_waitcnt vmcnt(0)
	v_sub_f32_e32 v93, v93, v96
	v_sub_f32_e32 v92, v92, v96
	v_sub_f32_e32 v89, v89, v96
	v_sub_f32_e32 v88, v88, v96
	v_sub_f32_e32 v95, v95, v96
	v_sub_f32_e32 v94, v94, v96
	v_sub_f32_e32 v91, v91, v96
	v_sub_f32_e32 v90, v90, v96
	v_pk_mul_f32 v[92:93], v[96:97], v[92:93] op_sel:[1,0]
	v_pk_mul_f32 v[88:89], v[96:97], v[88:89] op_sel:[1,0]
	v_sub_f32_e32 v81, v81, v96
	v_sub_f32_e32 v80, v80, v96
	v_pk_mul_f32 v[94:95], v[96:97], v[94:95] op_sel:[1,0]
	v_pk_mul_f32 v[90:91], v[96:97], v[90:91] op_sel:[1,0]
	v_pk_fma_f32 v[92:93], v[64:65], v[92:93], v[68:69]
	v_pk_fma_f32 v[88:89], v[72:73], v[88:89], v[76:77]
	v_pk_mul_f32 v[80:81], v[96:97], v[80:81] op_sel:[1,0]
	v_sub_f32_e32 v85, v85, v96
	v_sub_f32_e32 v84, v84, v96
	v_sub_f32_e32 v87, v87, v96
	v_sub_f32_e32 v86, v86, v96
	v_pk_fma_f32 v[94:95], v[66:67], v[94:95], v[70:71]
	v_pk_fma_f32 v[90:91], v[74:75], v[90:91], v[78:79]
	v_pk_fma_f32 v[92:93], v[92:93], s[52:53], v[98:99] op_sel_hi:[1,0,1]
	v_pk_fma_f32 v[88:89], v[88:89], s[52:53], v[102:103] op_sel_hi:[1,0,1]
	v_lshlrev_b32_e32 v98, 16, v152
	v_and_b32_e32 v99, 0xffff0000, v152
	v_sub_f32_e32 v83, v83, v96
	v_sub_f32_e32 v82, v82, v96
	v_pk_fma_f32 v[80:81], v[48:49], v[80:81], v[52:53]
	v_pk_mul_f32 v[86:87], v[96:97], v[86:87] op_sel:[1,0]
	v_pk_mul_f32 v[84:85], v[96:97], v[84:85] op_sel:[1,0]
	v_pk_fma_f32 v[94:95], v[94:95], s[52:53], v[100:101] op_sel_hi:[1,0,1]
	v_pk_fma_f32 v[90:91], v[90:91], s[52:53], v[104:105] op_sel_hi:[1,0,1]
	v_pk_mul_f32 v[82:83], v[96:97], v[82:83] op_sel:[1,0]
	v_pk_fma_f32 v[80:81], v[80:81], s[52:53], v[98:99] op_sel_hi:[1,0,1]
	v_mov_b32_e32 v96, v88
	v_mov_b32_e32 v97, v92
	v_mov_b32_e32 v98, v89
	v_mov_b32_e32 v99, v93
	v_pk_add_f32 v[96:97], v[96:97], v[98:99]
	v_mov_b32_e32 v98, v90
	v_mov_b32_e32 v99, v94
	v_pk_add_f32 v[96:97], v[98:99], v[96:97]
	v_mov_b32_e32 v98, v91
	v_mov_b32_e32 v99, v95
	v_pk_fma_f32 v[84:85], v[56:57], v[84:85], v[60:61]
	v_pk_add_f32 v[96:97], v[98:99], v[96:97]
	v_pk_fma_f32 v[86:87], v[58:59], v[86:87], v[62:63]
	v_pk_fma_f32 v[84:85], v[84:85], s[52:53], v[106:107] op_sel_hi:[1,0,1]
	v_lshlrev_b32_e32 v100, 16, v153
	v_and_b32_e32 v101, 0xffff0000, v153
	v_pk_fma_f32 v[82:83], v[50:51], v[82:83], v[54:55]
	v_add_f32_e32 v97, 0, v97
	v_pk_fma_f32 v[86:87], v[86:87], s[52:53], v[108:109] op_sel_hi:[1,0,1]
	v_pk_fma_f32 v[82:83], v[82:83], s[52:53], v[100:101] op_sel_hi:[1,0,1]
	v_add_f32_e32 v100, v96, v97
	v_mov_b32_e32 v96, v80
	v_mov_b32_e32 v97, v84
	v_mov_b32_e32 v98, v81
	v_mov_b32_e32 v99, v85
	v_pk_add_f32 v[96:97], v[96:97], v[98:99]
	v_mov_b32_e32 v98, v82
	v_mov_b32_e32 v99, v86
	v_pk_add_f32 v[96:97], v[98:99], v[96:97]
	v_mov_b32_e32 v98, v83
	v_mov_b32_e32 v99, v87
	v_pk_add_f32 v[96:97], v[98:99], v[96:97]
	s_nop 0
	v_add_f32_e32 v97, v97, v100
	v_add_f32_e32 v96, v96, v97
	v_mbcnt_lo_u32_b32 v97, s2, 0
	v_mbcnt_hi_u32_b32 v97, s2, v97
	v_lshlrev_b32_e32 v97, 2, v97
	v_xor_b32_e32 v98, 0x80, v97
	ds_bpermute_b32 v98, v98, v96
	s_mov_b32 s2, -1
	s_waitcnt lgkmcnt(0)
; DEVFI void ln_resid4(const float* ysrc, float* ydst, bfraw* fb, float* stats, const float* pw, const float* pb,
;                      const float* w, const float* b, int lane, bool fin) {
;     ...
;     const float mean = red64(s) * (1.f / 1024.f);
;     float q = 0;
; #pragma unroll
;     for (int i = 0; i < 4; ++i) { const f32x4 d = y[i] - mean; q += d[0] * d[0] + d[1] * d[1] + d[2] * d[2] + d[3] * d[3]; }
;     const float rstd = 1.f / sqrtf(red64(q) * (1.f / 1024.f) + LN_EPS);
;     if (lane == 0) { stats[r * 2] = mean; stats[r * 2 + 1] = rstd; }
; #pragma unroll
;     for (int i = 0; i < 4; ++i) { const int c4 = i * 64 + lane;
;       const f32x4 z = (y[i] - mean) * rstd * ww[i] + bb[i];
;       __builtin_nontemporal_store(fin ? z : y[i], (f32x4*)(ydst + r * 1024) + c4);
;       u32x2 pk = {cvtpk(z[0], z[1]), cvtpk(z[2], z[3])}; ((u32x2*)(fb + r * 1024))[c4] = pk; }
	v_add_f32_e32 v96, v96, v98
	v_xor_b32_e32 v98, 64, v97
	ds_bpermute_b32 v98, v98, v96
	s_waitcnt lgkmcnt(0)
	v_add_f32_e32 v96, v96, v98
	v_xor_b32_e32 v98, 32, v97
	ds_bpermute_b32 v98, v98, v96
	s_waitcnt lgkmcnt(0)
	v_add_f32_e32 v96, v96, v98
	v_xor_b32_e32 v98, 16, v97
	ds_bpermute_b32 v98, v98, v96
	s_waitcnt lgkmcnt(0)
	v_add_f32_e32 v96, v96, v98
	v_xor_b32_e32 v98, 8, v97
	ds_bpermute_b32 v98, v98, v96
	v_xor_b32_e32 v97, 4, v97
	s_waitcnt lgkmcnt(0)
	v_add_f32_e32 v96, v96, v98
	ds_bpermute_b32 v97, v97, v96
	s_waitcnt lgkmcnt(0)
	v_add_f32_e32 v113, v96, v97
	v_fmamk_f32 v111, v113, 0xba800000, v93
	v_fmamk_f32 v107, v113, 0xba800000, v89
	v_fmamk_f32 v110, v113, 0xba800000, v92
	v_mul_f32_e32 v96, v111, v111
	v_fmamk_f32 v106, v113, 0xba800000, v88
	v_mul_f32_e32 v97, v107, v107
	v_fmamk_f32 v108, v113, 0xba800000, v94
	v_fmac_f32_e32 v96, v110, v110
	v_fmamk_f32 v104, v113, 0xba800000, v90
	v_fmac_f32_e32 v97, v106, v106
	v_fmamk_f32 v109, v113, 0xba800000, v95
	v_fmac_f32_e32 v96, v108, v108
	v_fmamk_f32 v105, v113, 0xba800000, v91
	v_fmac_f32_e32 v97, v104, v104
	v_fmac_f32_e32 v96, v109, v109
	v_fmac_f32_e32 v97, v105, v105
	v_fmamk_f32 v103, v113, 0xba800000, v85
	v_add_f32_e32 v96, v96, v97
	v_fmamk_f32 v102, v113, 0xba800000, v84
	v_mul_f32_e32 v97, v103, v103
	v_fmamk_f32 v100, v113, 0xba800000, v86
	v_fmac_f32_e32 v97, v102, v102
	v_fmamk_f32 v101, v113, 0xba800000, v87
	v_fmac_f32_e32 v97, v100, v100
	v_fmamk_f32 v99, v113, 0xba800000, v81
	v_fmac_f32_e32 v97, v101, v101
	v_fmamk_f32 v98, v113, 0xba800000, v80
	v_mul_f32_e32 v114, v99, v99
	v_add_f32_e32 v112, v97, v96
	v_fmamk_f32 v96, v113, 0xba800000, v82
	v_fmac_f32_e32 v114, v98, v98
	v_fmamk_f32 v97, v113, 0xba800000, v83
	v_fmac_f32_e32 v114, v96, v96
	v_fmac_f32_e32 v114, v97, v97
	v_add_f32_e32 v112, v114, v112
	v_mbcnt_lo_u32_b32 v114, s2, 0
	v_mbcnt_hi_u32_b32 v114, s2, v114
	v_lshlrev_b32_e32 v114, 2, v114
	v_xor_b32_e32 v115, 0x80, v114
	ds_bpermute_b32 v115, v115, v112
	s_waitcnt lgkmcnt(0)
	v_add_f32_e32 v112, v112, v115
	v_xor_b32_e32 v115, 64, v114
	ds_bpermute_b32 v115, v115, v112
	s_waitcnt lgkmcnt(0)
	v_add_f32_e32 v112, v112, v115
	v_xor_b32_e32 v115, 32, v114
	ds_bpermute_b32 v115, v115, v112
	s_waitcnt lgkmcnt(0)
	v_add_f32_e32 v112, v112, v115
	v_xor_b32_e32 v115, 16, v114
	ds_bpermute_b32 v115, v115, v112
	s_waitcnt lgkmcnt(0)
	v_add_f32_e32 v112, v112, v115
	v_xor_b32_e32 v115, 8, v114
	ds_bpermute_b32 v115, v115, v112
	v_xor_b32_e32 v114, 4, v114
	s_waitcnt lgkmcnt(0)
	v_add_f32_e32 v112, v112, v115
	ds_bpermute_b32 v114, v114, v112
	s_waitcnt lgkmcnt(0)
	v_add_f32_e32 v112, v112, v114
	v_fmamk_f32 v112, v112, 0x3a800000, v183
	v_mul_f32_e32 v114, 0x4f800000, v112
	v_cmp_gt_f32_e32 vcc, s30, v112
	s_nop 1
	v_cndmask_b32_e32 v112, v112, v114, vcc
	v_sqrt_f32_e32 v114, v112
	s_nop 0
	v_add_u32_e32 v115, -1, v114
	v_fma_f32 v116, -v115, v114, v112
	v_cmp_ge_f32_e64 s[8:9], 0, v116
	v_add_u32_e32 v116, 1, v114
	s_nop 0
	v_cndmask_b32_e64 v115, v114, v115, s[8:9]
	v_fma_f32 v114, -v116, v114, v112
	v_cmp_lt_f32_e64 s[8:9], 0, v114
	s_nop 1
	v_cndmask_b32_e64 v114, v115, v116, s[8:9]
	v_mul_f32_e32 v115, 0x37800000, v114
	v_cndmask_b32_e32 v114, v114, v115, vcc
	v_cmp_class_f32_e32 vcc, v112, v222
	s_nop 1
	v_cndmask_b32_e32 v112, v114, v112, vcc
	s_nop 0
	v_rcp_f32_e32 v115, v112
	s_nop 0
	v_fma_f32 v114, -v112, v115, 1.0
	v_fma_f32 v114, v114, v115, v115
	v_div_fixup_f32 v112, v114, v112, 1.0
	s_mov_b64 s[2:3], exec
	s_and_b64 s[8:9], s[2:3], s[6:7]
	v_mov_b32_e32 v182, v192
	s_mov_b64 exec, s[8:9]
	s_cbranch_execz .LBB0_4786
	v_mul_f32_e32 v114, 0x3a800000, v113
	v_mov_b32_e32 v115, v112
	global_store_dwordx2 v[140:141], v[114:115], off offset:16
.LBB0_4786:
	s_or_b64 exec, exec, s[2:3]
	s_mov_b64 s[2:3], 0x2000
	v_lshl_add_u64 v[114:115], v[142:143], 0, s[2:3]
	s_mov_b64 s[2:3], 0x2400
	v_lshl_add_u64 v[116:117], v[142:143], 0, s[2:3]
	s_mov_b64 s[2:3], 0x2800
	v_pk_mul_f32 v[108:109], v[108:109], v[112:113] op_sel_hi:[1,0]
	v_pk_mul_f32 v[110:111], v[110:111], v[112:113] op_sel_hi:[1,0]
	v_lshl_add_u64 v[118:119], v[142:143], 0, s[2:3]
	s_mov_b64 s[2:3], 0x2c00
	v_pk_fma_f32 v[108:109], v[26:27], v[108:109], v[30:31]
	v_pk_fma_f32 v[110:111], v[24:25], v[110:111], v[28:29]
	v_lshl_add_u64 v[120:121], v[142:143], 0, s[2:3]
	s_mov_b64 s[2:3], 0x1000
	v_cndmask_b32_e64 v95, v95, v109, s[4:5]
	v_cndmask_b32_e64 v94, v94, v108, s[4:5]
	v_cndmask_b32_e64 v93, v93, v111, s[4:5]
	v_cndmask_b32_e64 v92, v92, v110, s[4:5]
	v_lshl_add_u64 v[122:123], v[138:139], 0, s[2:3]
	global_store_dwordx4 v[114:115], v[92:95], off nt
	s_mov_b64 s[2:3], 0x1200
	v_lshl_add_u64 v[124:125], v[138:139], 0, s[2:3]
	v_cvt_pk_bf16_f32 v92, v110, v111
	v_cvt_pk_bf16_f32 v93, v108, v109
	global_store_dwordx2 v[122:123], v[92:93], off
	v_pk_mul_f32 v[92:93], v[104:105], v[112:113] op_sel_hi:[1,0]
	v_pk_mul_f32 v[94:95], v[106:107], v[112:113] op_sel_hi:[1,0]
	v_pk_fma_f32 v[92:93], v[18:19], v[92:93], v[22:23]
	v_pk_fma_f32 v[94:95], v[16:17], v[94:95], v[20:21]
	v_cndmask_b32_e64 v91, v91, v93, s[4:5]
	v_cndmask_b32_e64 v90, v90, v92, s[4:5]
	v_cndmask_b32_e64 v89, v89, v95, s[4:5]
	v_cndmask_b32_e64 v88, v88, v94, s[4:5]
	global_store_dwordx4 v[116:117], v[88:91], off nt
	s_mov_b64 s[2:3], 0x1400
	v_lshl_add_u64 v[126:127], v[138:139], 0, s[2:3]
	v_cvt_pk_bf16_f32 v88, v94, v95
	v_cvt_pk_bf16_f32 v89, v92, v93
	global_store_dwordx2 v[124:125], v[88:89], off
	v_pk_mul_f32 v[88:89], v[100:101], v[112:113] op_sel_hi:[1,0]
	v_pk_mul_f32 v[90:91], v[102:103], v[112:113] op_sel_hi:[1,0]
	v_pk_fma_f32 v[88:89], v[10:11], v[88:89], v[14:15]
	v_pk_fma_f32 v[90:91], v[8:9], v[90:91], v[12:13]
; DEVFI void ln_resid4(const float* ysrc, float* ydst, bfraw* fb, float* stats, const float* pw, const float* pb,
;                      const float* w, const float* b, int lane, bool fin) {
;     ...
;     const float pmu = stats[r * 2], prs = stats[r * 2 + 1];
;     f32x4 y[4];
; #pragma unroll
;     for (int i = 0; i < 4; ++i) { const unsigned f0 = fv[r][i][0], f1 = fv[r][i][1];
;       const f32x4 f4 = {__uint_as_float(f0 << 16), __uint_as_float(f0 & 0xffff0000u), __uint_as_float(f1 << 16), __uint_as_float(f1 & 0xffff0000u)};
;       y[i] = ALPHA * ((v[r][i] - pmu) * prs * pwv[i] + pbv[i]) + f4; }
;     float s = 0;
; #pragma unroll
;     for (int i = 0; i < 4; ++i) s += y[i][0] + y[i][1] + y[i][2] + y[i][3];
;     const float mean = red64(s) * (1.f / 1024.f);
;     float q = 0;
; #pragma unroll
;     for (int i = 0; i < 4; ++i) { const f32x4 d = y[i] - mean; q += d[0] * d[0] + d[1] * d[1] + d[2] * d[2] + d[3] * d[3]; }
;     const float rstd = 1.f / sqrtf(red64(q) * (1.f / 1024.f) + LN_EPS);
;     if (lane == 0) { stats[r * 2] = mean; stats[r * 2 + 1] = rstd; }
; #pragma unroll
;     for (int i = 0; i < 4; ++i) { const int c4 = i * 64 + lane;
;       const f32x4 z = (y[i] - mean) * rstd * ww[i] + bb[i];
;       __builtin_nontemporal_store(fin ? z : y[i], (f32x4*)(ydst + r * 1024) + c4);
;       u32x2 pk = {cvtpk(z[0], z[1]), cvtpk(z[2], z[3])}; ((u32x2*)(fb + r * 1024))[c4] = pk; }
	v_cndmask_b32_e64 v87, v87, v89, s[4:5]
	v_cndmask_b32_e64 v86, v86, v88, s[4:5]
	v_cndmask_b32_e64 v85, v85, v91, s[4:5]
	v_cndmask_b32_e64 v84, v84, v90, s[4:5]
	global_store_dwordx4 v[118:119], v[84:87], off nt
	s_mov_b64 s[2:3], 0x1600
	v_lshl_add_u64 v[152:153], v[138:139], 0, s[2:3]
	v_cvt_pk_bf16_f32 v84, v90, v91
	v_cvt_pk_bf16_f32 v85, v88, v89
	global_store_dwordx2 v[126:127], v[84:85], off
	v_pk_mul_f32 v[84:85], v[96:97], v[112:113] op_sel_hi:[1,0]
	v_pk_mul_f32 v[86:87], v[98:99], v[112:113] op_sel_hi:[1,0]
	v_pk_fma_f32 v[84:85], v[2:3], v[84:85], v[6:7]
	v_pk_fma_f32 v[86:87], v[0:1], v[86:87], v[4:5]
	v_cndmask_b32_e64 v83, v83, v85, s[4:5]
	v_cndmask_b32_e64 v82, v82, v84, s[4:5]
	v_cndmask_b32_e64 v81, v81, v87, s[4:5]
	v_cndmask_b32_e64 v80, v80, v86, s[4:5]
	global_store_dwordx4 v[120:121], v[80:83], off nt
	v_lshlrev_b32_e32 v88, 16, v149
	v_and_b32_e32 v89, 0xffff0000, v149
	v_cvt_pk_bf16_f32 v80, v86, v87
	v_cvt_pk_bf16_f32 v81, v84, v85
	global_store_dwordx2 v[152:153], v[80:81], off
	global_load_dwordx2 v[80:81], v[140:141], off offset:24
	v_lshlrev_b32_e32 v82, 16, v150
	v_and_b32_e32 v83, 0xffff0000, v150
	v_lshlrev_b32_e32 v86, 16, v148
	v_and_b32_e32 v87, 0xffff0000, v148
	v_lshlrev_b32_e32 v84, 16, v151
	v_and_b32_e32 v85, 0xffff0000, v151
	v_lshlrev_b32_e32 v90, 16, v146
	v_and_b32_e32 v91, 0xffff0000, v146
	v_lshlrev_b32_e32 v92, 16, v147
	v_and_b32_e32 v93, 0xffff0000, v147
	s_mov_b32 s2, -1
	s_waitcnt vmcnt(0)
	v_sub_f32_e32 v45, v45, v80
	v_sub_f32_e32 v44, v44, v80
	v_sub_f32_e32 v41, v41, v80
	v_sub_f32_e32 v40, v40, v80
	v_sub_f32_e32 v47, v47, v80
	v_sub_f32_e32 v46, v46, v80
	v_sub_f32_e32 v43, v43, v80
	v_sub_f32_e32 v42, v42, v80
	v_pk_mul_f32 v[44:45], v[80:81], v[44:45] op_sel:[1,0]
	v_pk_mul_f32 v[40:41], v[80:81], v[40:41] op_sel:[1,0]
	v_pk_mul_f32 v[46:47], v[80:81], v[46:47] op_sel:[1,0]
	v_pk_mul_f32 v[42:43], v[80:81], v[42:43] op_sel:[1,0]
	v_pk_fma_f32 v[44:45], v[64:65], v[44:45], v[68:69]
	v_pk_fma_f32 v[40:41], v[72:73], v[40:41], v[76:77]
	v_sub_f32_e32 v33, v33, v80
	v_sub_f32_e32 v32, v32, v80
	v_sub_f32_e32 v35, v35, v80
	v_sub_f32_e32 v34, v34, v80
	v_pk_fma_f32 v[46:47], v[66:67], v[46:47], v[70:71]
	v_pk_fma_f32 v[42:43], v[74:75], v[42:43], v[78:79]
	v_pk_fma_f32 v[44:45], v[44:45], s[52:53], v[82:83] op_sel_hi:[1,0,1]
	v_pk_fma_f32 v[40:41], v[40:41], s[52:53], v[86:87] op_sel_hi:[1,0,1]
	v_pk_mul_f32 v[34:35], v[80:81], v[34:35] op_sel:[1,0]
	v_pk_mul_f32 v[32:33], v[80:81], v[32:33] op_sel:[1,0]
	v_pk_fma_f32 v[46:47], v[46:47], s[52:53], v[84:85] op_sel_hi:[1,0,1]
	v_pk_fma_f32 v[42:43], v[42:43], s[52:53], v[88:89] op_sel_hi:[1,0,1]
	v_pk_fma_f32 v[32:33], v[48:49], v[32:33], v[52:53]
	v_pk_fma_f32 v[34:35], v[50:51], v[34:35], v[54:55]
	v_mov_b32_e32 v48, v40
	v_mov_b32_e32 v49, v44
	v_mov_b32_e32 v50, v41
	v_mov_b32_e32 v51, v45
	v_sub_f32_e32 v37, v37, v80
	v_sub_f32_e32 v36, v36, v80
	v_pk_add_f32 v[48:49], v[48:49], v[50:51]
	v_mov_b32_e32 v50, v42
	v_mov_b32_e32 v51, v46
	v_sub_f32_e32 v39, v39, v80
	v_sub_f32_e32 v38, v38, v80
	v_pk_mul_f32 v[36:37], v[80:81], v[36:37] op_sel:[1,0]
	v_pk_add_f32 v[48:49], v[50:51], v[48:49]
	v_mov_b32_e32 v50, v43
	v_mov_b32_e32 v51, v47
	v_pk_mul_f32 v[38:39], v[80:81], v[38:39] op_sel:[1,0]
	v_pk_fma_f32 v[36:37], v[56:57], v[36:37], v[60:61]
	v_lshlrev_b32_e32 v56, 16, v144
	v_and_b32_e32 v57, 0xffff0000, v144
	v_pk_add_f32 v[48:49], v[50:51], v[48:49]
	v_pk_fma_f32 v[38:39], v[58:59], v[38:39], v[62:63]
	v_pk_fma_f32 v[36:37], v[36:37], s[52:53], v[90:91] op_sel_hi:[1,0,1]
	v_lshlrev_b32_e32 v58, 16, v145
	v_and_b32_e32 v59, 0xffff0000, v145
	v_pk_fma_f32 v[32:33], v[32:33], s[52:53], v[56:57] op_sel_hi:[1,0,1]
	v_add_f32_e32 v49, 0, v49
	v_pk_fma_f32 v[38:39], v[38:39], s[52:53], v[92:93] op_sel_hi:[1,0,1]
	v_pk_fma_f32 v[34:35], v[34:35], s[52:53], v[58:59] op_sel_hi:[1,0,1]
	v_add_f32_e32 v52, v48, v49
	v_mov_b32_e32 v48, v32
	v_mov_b32_e32 v49, v36
	v_mov_b32_e32 v50, v33
	v_mov_b32_e32 v51, v37
	v_pk_add_f32 v[48:49], v[48:49], v[50:51]
	v_mov_b32_e32 v50, v34
	v_mov_b32_e32 v51, v38
	v_pk_add_f32 v[48:49], v[50:51], v[48:49]
	v_mov_b32_e32 v50, v35
	v_mov_b32_e32 v51, v39
	v_pk_add_f32 v[48:49], v[50:51], v[48:49]
	s_nop 0
	v_add_f32_e32 v49, v49, v52
	v_add_f32_e32 v48, v48, v49
	v_mbcnt_lo_u32_b32 v49, s2, 0
	v_mbcnt_hi_u32_b32 v49, s2, v49
	v_lshlrev_b32_e32 v49, 2, v49
	v_xor_b32_e32 v50, 0x80, v49
	ds_bpermute_b32 v50, v50, v48
	s_mov_b32 s2, -1
	s_waitcnt lgkmcnt(0)
; DEVFI int opaque_tid(const int wv) { return (wv << 6) | lane_opaque(); }
; DEVFI void ln_resid4(const float* ysrc, float* ydst, bfraw* fb, float* stats, const float* pw, const float* pb,
;                      const float* w, const float* b, int lane, bool fin) {
;     ...
;     const float mean = red64(s) * (1.f / 1024.f);
;     float q = 0;
; #pragma unroll
;     for (int i = 0; i < 4; ++i) { const f32x4 d = y[i] - mean; q += d[0] * d[0] + d[1] * d[1] + d[2] * d[2] + d[3] * d[3]; }
;     const float rstd = 1.f / sqrtf(red64(q) * (1.f / 1024.f) + LN_EPS);
;     if (lane == 0) { stats[r * 2] = mean; stats[r * 2 + 1] = rstd; }
; DEVFI void gbar(unsigned* bar, unsigned& gen, const unsigned nb, const unsigned bid, const int wv) {
;   __syncthreads();
;   gen += 1;
;   if (opaque_tid(wv) == 0) {
;     const unsigned groups = (nb % 8 == 0) ? 8u : 1u, gsz = nb / groups;
;     unsigned* grp = bar + (bid % groups) * 32; unsigned* glob = bar + 8 * 32;
	v_add_f32_e32 v48, v48, v50
	v_xor_b32_e32 v50, 64, v49
	ds_bpermute_b32 v50, v50, v48
	s_waitcnt lgkmcnt(0)
	v_add_f32_e32 v48, v48, v50
	v_xor_b32_e32 v50, 32, v49
	ds_bpermute_b32 v50, v50, v48
	s_waitcnt lgkmcnt(0)
	v_add_f32_e32 v48, v48, v50
	v_xor_b32_e32 v50, 16, v49
	ds_bpermute_b32 v50, v50, v48
	s_waitcnt lgkmcnt(0)
	v_add_f32_e32 v48, v48, v50
	v_xor_b32_e32 v50, 8, v49
	ds_bpermute_b32 v50, v50, v48
	v_xor_b32_e32 v49, 4, v49
	s_waitcnt lgkmcnt(0)
	v_add_f32_e32 v48, v48, v50
	ds_bpermute_b32 v49, v49, v48
	s_waitcnt lgkmcnt(0)
	v_add_f32_e32 v65, v48, v49
	v_fmamk_f32 v63, v65, 0xba800000, v45
	v_fmamk_f32 v59, v65, 0xba800000, v41
	v_fmamk_f32 v62, v65, 0xba800000, v44
	v_mul_f32_e32 v48, v63, v63
	v_fmamk_f32 v58, v65, 0xba800000, v40
	v_mul_f32_e32 v49, v59, v59
	v_fmamk_f32 v60, v65, 0xba800000, v46
	v_fmac_f32_e32 v48, v62, v62
	v_fmamk_f32 v56, v65, 0xba800000, v42
	v_fmac_f32_e32 v49, v58, v58
	v_fmamk_f32 v61, v65, 0xba800000, v47
	v_fmac_f32_e32 v48, v60, v60
	v_fmamk_f32 v57, v65, 0xba800000, v43
	v_fmac_f32_e32 v49, v56, v56
	v_fmac_f32_e32 v48, v61, v61
	v_fmac_f32_e32 v49, v57, v57
	v_fmamk_f32 v55, v65, 0xba800000, v37
	v_add_f32_e32 v48, v48, v49
	v_fmamk_f32 v54, v65, 0xba800000, v36
	v_mul_f32_e32 v49, v55, v55
	v_fmamk_f32 v52, v65, 0xba800000, v38
	v_fmac_f32_e32 v49, v54, v54
	v_fmamk_f32 v53, v65, 0xba800000, v39
	v_fmac_f32_e32 v49, v52, v52
	v_fmamk_f32 v51, v65, 0xba800000, v33
	v_fmac_f32_e32 v49, v53, v53
	v_fmamk_f32 v50, v65, 0xba800000, v32
	v_mul_f32_e32 v66, v51, v51
	v_add_f32_e32 v64, v49, v48
	v_fmamk_f32 v48, v65, 0xba800000, v34
	v_fmac_f32_e32 v66, v50, v50
	v_fmamk_f32 v49, v65, 0xba800000, v35
	v_fmac_f32_e32 v66, v48, v48
	v_fmac_f32_e32 v66, v49, v49
	v_add_f32_e32 v64, v66, v64
	v_mbcnt_lo_u32_b32 v66, s2, 0
	v_mbcnt_hi_u32_b32 v66, s2, v66
	v_lshlrev_b32_e32 v66, 2, v66
	v_xor_b32_e32 v67, 0x80, v66
	ds_bpermute_b32 v67, v67, v64
	s_waitcnt lgkmcnt(0)
	v_add_f32_e32 v64, v64, v67
	v_xor_b32_e32 v67, 64, v66
	ds_bpermute_b32 v67, v67, v64
	s_waitcnt lgkmcnt(0)
	v_add_f32_e32 v64, v64, v67
	v_xor_b32_e32 v67, 32, v66
	ds_bpermute_b32 v67, v67, v64
	s_waitcnt lgkmcnt(0)
	v_add_f32_e32 v64, v64, v67
	v_xor_b32_e32 v67, 16, v66
	ds_bpermute_b32 v67, v67, v64
	s_waitcnt lgkmcnt(0)
	v_add_f32_e32 v64, v64, v67
	v_xor_b32_e32 v67, 8, v66
	ds_bpermute_b32 v67, v67, v64
	v_xor_b32_e32 v66, 4, v66
	s_waitcnt lgkmcnt(0)
	v_add_f32_e32 v64, v64, v67
	ds_bpermute_b32 v66, v66, v64
	s_waitcnt lgkmcnt(0)
	v_add_f32_e32 v64, v64, v66
	v_fmamk_f32 v64, v64, 0x3a800000, v183
	v_mul_f32_e32 v66, 0x4f800000, v64
	v_cmp_gt_f32_e32 vcc, s30, v64
	s_nop 1
	v_cndmask_b32_e32 v64, v64, v66, vcc
	v_sqrt_f32_e32 v66, v64
	s_nop 0
	v_add_u32_e32 v67, -1, v66
	v_fma_f32 v68, -v67, v66, v64
	v_cmp_ge_f32_e64 s[8:9], 0, v68
	v_add_u32_e32 v68, 1, v66
	s_nop 0
	v_cndmask_b32_e64 v67, v66, v67, s[8:9]
	v_fma_f32 v66, -v68, v66, v64
	v_cmp_lt_f32_e64 s[8:9], 0, v66
	s_nop 1
	v_cndmask_b32_e64 v66, v67, v68, s[8:9]
	v_mul_f32_e32 v67, 0x37800000, v66
	v_cndmask_b32_e32 v66, v66, v67, vcc
	v_cmp_class_f32_e32 vcc, v64, v222
	s_nop 1
	v_cndmask_b32_e32 v64, v66, v64, vcc
	s_nop 0
	v_rcp_f32_e32 v67, v64
	s_nop 0
	v_fma_f32 v66, -v64, v67, 1.0
	v_fma_f32 v66, v66, v67, v67
	v_div_fixup_f32 v64, v66, v64, 1.0
	s_and_saveexec_b64 s[2:3], s[6:7]
	s_cbranch_execz .LBB0_4779
	v_mul_f32_e32 v66, 0x3a800000, v65
	v_mov_b32_e32 v67, v64
	global_store_dwordx2 v[140:141], v[66:67], off offset:24
	s_branch .LBB0_4779
.LBB0_4788:
	s_or_b64 exec, exec, s[14:15]
	v_readlane_b32 s2, v255, 3
	s_add_i32 s2, s2, 36
	s_mov_b64 s[4:5], s[0:1]
	s_nop 1
	v_writelane_b32 v255, s2, 3
	s_mov_b32 s2, -1
	s_barrier
	s_nop 0
	v_mbcnt_lo_u32_b32 v0, s2, 0
	v_mbcnt_hi_u32_b32 v0, s2, v0
	v_or_b32_e32 v0, s33, v0
	v_cmp_eq_u32_e32 vcc, 0, v0
	s_and_saveexec_b64 s[2:3], vcc
	v_readlane_b32 s22, v255, 17
	s_cbranch_execnz .LBB0_4789
	s_getpc_b64 s[98:99]
